# GEMM K-loops: per-phase s_setprio flips deleted, one static s_setprio 1 for the younger wave half (waves 4-7) per K-loop
# speedup vs baseline: 1.0066x; 1.0066x over previous
; #define PG8_STAGE(bufoff, gbase, voff) do { _Pragma("unroll") for (int _i = 0; _i < 2; ++_i) \
;         __builtin_amdgcn_global_load_lds((const unsigned*)((const char*)(gbase) + (voff)[_i]), (PG8_LAS unsigned*)(lds + (bufoff) + ldsw + _i * 8192), 16, 0, 0); } while (0)
; #define PG8_LDA(dst, b, h) do { _Pragma("unroll") for (int m = 0; m < 4; ++m) _Pragma("unroll") for (int k = 0; k < 2; ++k) dst[m][k] = *(const PG8_LAS bf16x8*)(lds + PG8_SA(b, h) + aoff + m * 2048 + k * 1024); } while (0)
; #define PG8_LDB(dst, b, h) do { _Pragma("unroll") for (int n = 0; n < 2; ++n) _Pragma("unroll") for (int k = 0; k < 2; ++k) dst[n][k] = *(const PG8_LAS bf16x8*)(lds + PG8_SB(b, h) + boff + n * 2048 + k * 1024); } while (0)
; #define PG8_SCHED __builtin_amdgcn_sched_barrier(0)
;     __device__ __forceinline__ bool next(int i, pg8::Unit& u) const { if (c < 128 || i >= 2) return false; const int idx = (c - 128) * 2 + i; u.pm = idx >> 2; u.pn = idx & 3; return true; }
; template <class Epi, class Sched, bool ALIGN_EPI = false, bool SP2 = false, bool F16 = false>
; __device__ __forceinline__ void gemm_phase(PG8_LAS unsigned char* lds, const Gemm g, const Sched& S, const Epi& E, const int wid_in) {
;     ...
;         const bool has_next = S.next(ui + 1, nxt);
;         const char* nA = has_next ? (const char*)g.A + (size_t)nxt.pm * tstep : cA; const char* nB = has_next ? (const char*)g.Bt + (size_t)nxt.pn * tstep : cB;
;         for (int t = 0; t < nt; t += 2) {
;             const bool last = (t == nt - 2);
;             const char* a1 = cA + (size_t)(t + 1) * kstep;
;             const char* a2 = last ? nA : cA + (size_t)(t + 2) * kstep; const char* b2 = last ? nB : cB + (size_t)(t + 2) * kstep;
;             const char* a3 = a2 + kstep; const char* b3 = b2 + kstep;
;             if (last && has_next) S.a_ready(nxt);
;             if constexpr (SP2) {
;             PG8_LDB(B0, 0, 0); PG8_LDB(B1, 0, 1); PG8_SCHED; PG8_LDA(At, 0, 0); PG8_STAGE(PG8_SA(1, 1), a1 + hstep, voffA);
;     ...
;         for (int a = 0; a < 2; ++a)
; #pragma unroll
;             for (int b = 0; b < 2; ++b)
; #pragma unroll
;                 for (int m = 0; m < 4; ++m)
; #pragma unroll
;                     for (int n = 0; n < 2; ++n) acc[a][b][m][n] = (f32x4){0.f, 0.f, 0.f, 0.f};
.LBB0_223:
	s_ashr_i32 s51, s50, 31
	s_lshl_b64 s[42:43], s[50:51], 19
	s_add_u32 s52, s79, s42
	s_addc_u32 s53, s80, s43
	s_and_b64 s[42:43], s[6:7], exec
	s_cselect_b32 s9, s53, s57
	s_cselect_b32 s21, s52, s56
	s_ashr_i32 s49, s48, 31
	s_lshl_b64 s[42:43], s[48:49], 19
	s_add_u32 s54, s81, s42
	s_addc_u32 s55, s82, s43
	s_and_b64 s[42:43], s[6:7], exec
	s_cselect_b32 s42, s55, s59
	s_cselect_b32 s43, s54, s58
	s_add_u32 s56, s56, 0x40080
	s_addc_u32 s57, s57, 0
	s_add_u32 s49, s58, 0x100
	v_mov_b32_e32 v0, 0
	s_addc_u32 s51, s59, 0
	s_mov_b32 s62, -2
	s_waitcnt lgkmcnt(0)
	v_mov_b32_e32 v1, v0
	v_mov_b32_e32 v2, v0
	v_mov_b32_e32 v3, v0
	v_mov_b32_e32 v4, v0
	v_mov_b32_e32 v5, v0
	v_mov_b32_e32 v6, v0
	v_mov_b32_e32 v7, v0
	v_mov_b32_e32 v16, v0
	v_mov_b32_e32 v17, v0
	v_mov_b32_e32 v18, v0
	v_mov_b32_e32 v19, v0
	v_mov_b32_e32 v20, v0
	v_mov_b32_e32 v21, v0
	v_mov_b32_e32 v22, v0
	v_mov_b32_e32 v23, v0
	v_mov_b32_e32 v32, v0
	v_mov_b32_e32 v33, v0
	v_mov_b32_e32 v34, v0
	v_mov_b32_e32 v35, v0
	v_mov_b32_e32 v36, v0
	v_mov_b32_e32 v37, v0
	v_mov_b32_e32 v38, v0
	v_mov_b32_e32 v39, v0
	v_mov_b32_e32 v48, v0
	v_mov_b32_e32 v49, v0
	v_mov_b32_e32 v50, v0
	v_mov_b32_e32 v51, v0
	v_mov_b32_e32 v52, v0
	v_mov_b32_e32 v53, v0
	v_mov_b32_e32 v54, v0
	v_mov_b32_e32 v55, v0
	v_mov_b32_e32 v8, v0
	v_mov_b32_e32 v9, v0
	v_mov_b32_e32 v10, v0
	v_mov_b32_e32 v11, v0
	v_mov_b32_e32 v12, v0
	v_mov_b32_e32 v13, v0
	v_mov_b32_e32 v14, v0
	v_mov_b32_e32 v15, v0
	v_mov_b32_e32 v24, v0
	v_mov_b32_e32 v25, v0
	v_mov_b32_e32 v26, v0
	v_mov_b32_e32 v27, v0
	v_mov_b32_e32 v28, v0
	v_mov_b32_e32 v29, v0
	v_mov_b32_e32 v30, v0
	v_mov_b32_e32 v31, v0
	v_mov_b32_e32 v40, v0
	v_mov_b32_e32 v41, v0
	v_mov_b32_e32 v42, v0
	v_mov_b32_e32 v43, v0
	v_mov_b32_e32 v44, v0
	v_mov_b32_e32 v45, v0
	v_mov_b32_e32 v46, v0
	v_mov_b32_e32 v47, v0
	v_mov_b32_e32 v56, v0
	v_mov_b32_e32 v57, v0
	v_mov_b32_e32 v58, v0
	v_mov_b32_e32 v59, v0
	v_mov_b32_e32 v60, v0
	v_mov_b32_e32 v61, v0
	v_mov_b32_e32 v62, v0
	v_mov_b32_e32 v63, v0
	v_mov_b32_e32 v64, v0
	v_mov_b32_e32 v65, v0
	v_mov_b32_e32 v66, v0
	v_mov_b32_e32 v67, v0
	v_mov_b32_e32 v68, v0
	v_mov_b32_e32 v69, v0
	v_mov_b32_e32 v70, v0
	v_mov_b32_e32 v71, v0
	v_mov_b32_e32 v80, v0
	v_mov_b32_e32 v81, v0
	v_mov_b32_e32 v82, v0
	v_mov_b32_e32 v83, v0
	v_mov_b32_e32 v84, v0
	v_mov_b32_e32 v85, v0
	v_mov_b32_e32 v86, v0
	v_mov_b32_e32 v87, v0
	v_mov_b32_e32 v96, v0
	v_mov_b32_e32 v97, v0
	v_mov_b32_e32 v98, v0
	v_mov_b32_e32 v99, v0
	v_mov_b32_e32 v100, v0
	v_mov_b32_e32 v101, v0
	v_mov_b32_e32 v102, v0
	v_mov_b32_e32 v103, v0
	v_mov_b32_e32 v112, v0
	v_mov_b32_e32 v113, v0
	v_mov_b32_e32 v114, v0
	v_mov_b32_e32 v115, v0
	v_mov_b32_e32 v116, v0
	v_mov_b32_e32 v117, v0
	v_mov_b32_e32 v118, v0
	v_mov_b32_e32 v119, v0
	v_mov_b32_e32 v72, v0
	v_mov_b32_e32 v73, v0
	v_mov_b32_e32 v74, v0
	v_mov_b32_e32 v75, v0
	v_mov_b32_e32 v76, v0
	v_mov_b32_e32 v77, v0
	v_mov_b32_e32 v78, v0
	v_mov_b32_e32 v79, v0
	v_mov_b32_e32 v88, v0
	v_mov_b32_e32 v89, v0
	v_mov_b32_e32 v90, v0
	v_mov_b32_e32 v91, v0
	v_mov_b32_e32 v92, v0
	v_mov_b32_e32 v93, v0
	v_mov_b32_e32 v94, v0
	v_mov_b32_e32 v95, v0
	v_mov_b32_e32 v104, v0
	v_mov_b32_e32 v105, v0
	v_mov_b32_e32 v106, v0
	v_mov_b32_e32 v107, v0
	v_mov_b32_e32 v108, v0
	v_mov_b32_e32 v109, v0
	v_mov_b32_e32 v110, v0
	v_mov_b32_e32 v111, v0
	v_mov_b32_e32 v120, v0
	v_mov_b32_e32 v121, v0
	v_mov_b32_e32 v122, v0
	v_mov_b32_e32 v123, v0
	v_mov_b32_e32 v124, v0
	v_mov_b32_e32 v125, v0
	v_mov_b32_e32 v126, v0
	v_mov_b32_e32 v127, v0
	s_cmp_ge_u32 s3, 4
	s_cbranch_scc0 .Lgsp_0
	s_setprio 1
.Lgsp_0:
.LBB0_224:
	ds_read_b128 v[128:131], v184
	ds_read_b128 v[132:135], v184 offset:1024
	ds_read_b128 v[136:139], v184 offset:2048
	ds_read_b128 v[140:143], v184 offset:3072
	ds_read_b128 v[144:147], v185
	ds_read_b128 v[148:151], v185 offset:1024
	ds_read_b128 v[152:155], v185 offset:2048
	ds_read_b128 v[174:177], v185 offset:3072
	s_add_u32 s58, s56, 0xfffc0080
	s_addc_u32 s59, s57, -1
	s_cmp_eq_u32 s62, 12
	s_cselect_b32 s61, s9, s59
	s_cselect_b32 s60, s21, s58
	s_cselect_b32 s59, s42, s51
	s_cselect_b32 s58, s43, s49
	v_lshl_add_u64 v[178:179], s[56:57], 0, v[166:167]
	s_add_i32 m0, s83, 0xc000
	ds_read_b128 v[190:193], v186
	ds_read_b128 v[194:197], v186 offset:1024
	ds_read_b128 v[198:201], v186 offset:2048
	ds_read_b128 v[202:205], v186 offset:3072
	ds_read_b128 v[206:209], v186 offset:4096
	ds_read_b128 v[210:213], v186 offset:5120
	ds_read_b128 v[214:217], v186 offset:6144
	ds_read_b128 v[218:221], v186 offset:7168
	global_load_lds_dwordx4 v[178:179], off
	v_lshl_add_u64 v[178:179], s[56:57], 0, v[168:169]
	s_add_i32 m0, s83, 0xe000
	s_nop 0
	global_load_lds_dwordx4 v[178:179], off
	s_waitcnt vmcnt(8)
	s_waitcnt lgkmcnt(0)
	s_barrier
; #define PG8_STAGE(bufoff, gbase, voff) do { _Pragma("unroll") for (int _i = 0; _i < 2; ++_i) \
;         __builtin_amdgcn_global_load_lds((const unsigned*)((const char*)(gbase) + (voff)[_i]), (PG8_LAS unsigned*)(lds + (bufoff) + ldsw + _i * 8192), 16, 0, 0); } while (0)
; #define PG8_LDA(dst, b, h) do { _Pragma("unroll") for (int m = 0; m < 4; ++m) _Pragma("unroll") for (int k = 0; k < 2; ++k) dst[m][k] = *(const PG8_LAS bf16x8*)(lds + PG8_SA(b, h) + aoff + m * 2048 + k * 1024); } while (0)
; #define PG8_LDB(dst, b, h) do { _Pragma("unroll") for (int n = 0; n < 2; ++n) _Pragma("unroll") for (int k = 0; k < 2; ++k) dst[n][k] = *(const PG8_LAS bf16x8*)(lds + PG8_SB(b, h) + boff + n * 2048 + k * 1024); } while (0)
; #define PG8_MMA(ai, bj, At, Bt) do { __builtin_amdgcn_s_setprio(1); _Pragma("unroll") for (int m = 0; m < 4; ++m) _Pragma("unroll") for (int n = 0; n < 2; ++n) _Pragma("unroll") for (int k = 0; k < 2; ++k) \
;         acc[ai][bj][m][n] = mma16<F16>(Bt[n][k], At[m][k], acc[ai][bj][m][n]); __builtin_amdgcn_s_setprio(0); } while (0)
; #define PG8_WAIT_V(n) asm volatile("s_waitcnt vmcnt(" #n ")" ::: "memory")
; #define PG8_WAIT_L(n) asm volatile("s_waitcnt lgkmcnt(" #n ")" ::: "memory")
; #define PG8_BAR __builtin_amdgcn_s_barrier()
; #define PG8_SCHED __builtin_amdgcn_sched_barrier(0)
; template <class Epi, class Sched, bool ALIGN_EPI = false, bool SP2 = false, bool F16 = false>
; __device__ __forceinline__ void gemm_phase(PG8_LAS unsigned char* lds, const Gemm g, const Sched& S, const Epi& E, const int wid_in) {
;     ...
;             PG8_LDB(B0, 0, 0); PG8_LDB(B1, 0, 1); PG8_SCHED; PG8_LDA(At, 0, 0); PG8_STAGE(PG8_SA(1, 1), a1 + hstep, voffA);
;             PG8_WAIT_V(8); PG8_WAIT_L(0); PG8_BAR; PG8_MMA(0, 0, At, B0); PG8_MMA(0, 1, At, B1); PG8_BAR; PG8_SCHED;
;             PG8_LDA(At, 0, 1); PG8_STAGE(PG8_SB(0, 0), b2, voffB); PG8_STAGE(PG8_SB(0, 1), b2 + hstep, voffB); PG8_STAGE(PG8_SA(0, 0), a2, voffA);
;             PG8_WAIT_V(8); PG8_WAIT_L(0); PG8_BAR; PG8_MMA(1, 0, At, B0); PG8_MMA(1, 1, At, B1); PG8_BAR; PG8_SCHED;
	s_waitcnt lgkmcnt(0)
	v_mfma_f32_16x16x32_f16 v[124:127], v[128:131], v[190:193], v[124:127]
	v_mfma_f32_16x16x32_f16 v[120:123], v[136:139], v[190:193], v[120:123]
	v_mfma_f32_16x16x32_f16 v[108:111], v[128:131], v[198:201], v[108:111]
	v_mfma_f32_16x16x32_f16 v[104:107], v[136:139], v[198:201], v[104:107]
	v_mfma_f32_16x16x32_f16 v[92:95], v[128:131], v[206:209], v[92:95]
	v_mfma_f32_16x16x32_f16 v[88:91], v[136:139], v[206:209], v[88:91]
	v_mfma_f32_16x16x32_f16 v[76:79], v[128:131], v[214:217], v[76:79]
	v_mfma_f32_16x16x32_f16 v[72:75], v[136:139], v[214:217], v[72:75]
	v_mfma_f32_16x16x32_f16 v[124:127], v[132:135], v[194:197], v[124:127]
	v_mfma_f32_16x16x32_f16 v[120:123], v[140:143], v[194:197], v[120:123]
	v_mfma_f32_16x16x32_f16 v[108:111], v[132:135], v[202:205], v[108:111]
	v_mfma_f32_16x16x32_f16 v[104:107], v[140:143], v[202:205], v[104:107]
	v_mfma_f32_16x16x32_f16 v[92:95], v[132:135], v[210:213], v[92:95]
	v_mfma_f32_16x16x32_f16 v[88:91], v[140:143], v[210:213], v[88:91]
	v_mfma_f32_16x16x32_f16 v[76:79], v[132:135], v[218:221], v[76:79]
	v_mfma_f32_16x16x32_f16 v[72:75], v[140:143], v[218:221], v[72:75]
	v_mfma_f32_16x16x32_f16 v[116:119], v[144:147], v[190:193], v[116:119]
	v_mfma_f32_16x16x32_f16 v[112:115], v[152:155], v[190:193], v[112:115]
	v_mfma_f32_16x16x32_f16 v[100:103], v[144:147], v[198:201], v[100:103]
	v_mfma_f32_16x16x32_f16 v[96:99], v[152:155], v[198:201], v[96:99]
	v_mfma_f32_16x16x32_f16 v[84:87], v[144:147], v[206:209], v[84:87]
	v_mfma_f32_16x16x32_f16 v[80:83], v[152:155], v[206:209], v[80:83]
	v_mfma_f32_16x16x32_f16 v[68:71], v[144:147], v[214:217], v[68:71]
	v_mfma_f32_16x16x32_f16 v[64:67], v[152:155], v[214:217], v[64:67]
	v_mfma_f32_16x16x32_f16 v[116:119], v[148:151], v[194:197], v[116:119]
	v_mfma_f32_16x16x32_f16 v[112:115], v[174:177], v[194:197], v[112:115]
	v_mfma_f32_16x16x32_f16 v[100:103], v[148:151], v[202:205], v[100:103]
	v_mfma_f32_16x16x32_f16 v[96:99], v[174:177], v[202:205], v[96:99]
	v_mfma_f32_16x16x32_f16 v[84:87], v[148:151], v[210:213], v[84:87]
	v_mfma_f32_16x16x32_f16 v[80:83], v[174:177], v[210:213], v[80:83]
	v_mfma_f32_16x16x32_f16 v[68:71], v[148:151], v[218:221], v[68:71]
	v_mfma_f32_16x16x32_f16 v[64:67], v[174:177], v[218:221], v[64:67]
	s_barrier
	s_add_i32 s63, s40, s68
	v_lshl_add_u64 v[178:179], s[58:59], 0, v[158:159]
	s_mov_b32 m0, s63
	ds_read_b128 v[190:193], v186 offset:16384
	ds_read_b128 v[194:197], v186 offset:17408
	ds_read_b128 v[198:201], v186 offset:18432
	ds_read_b128 v[202:205], v186 offset:19456
	ds_read_b128 v[206:209], v186 offset:20480
	ds_read_b128 v[210:213], v186 offset:21504
	ds_read_b128 v[214:217], v186 offset:22528
	ds_read_b128 v[218:221], v186 offset:23552
	global_load_lds_dwordx4 v[178:179], off
	s_add_i32 m0, s63, 0x2000
	s_add_u32 s64, s58, 0x40000
	v_lshl_add_u64 v[222:223], s[58:59], 0, v[162:163]
	s_addc_u32 s65, s59, 0
	s_add_i32 s63, s41, s68
	global_load_lds_dwordx4 v[222:223], off
	v_lshl_add_u64 v[224:225], s[64:65], 0, v[158:159]
	s_mov_b32 m0, s63
	v_lshl_add_u64 v[226:227], s[60:61], 0, v[160:161]
	global_load_lds_dwordx4 v[224:225], off
	v_lshl_add_u64 v[224:225], s[64:65], 0, v[162:163]
	s_add_i32 m0, s63, 0x2000
	s_nop 0
	global_load_lds_dwordx4 v[224:225], off
	v_lshl_add_u64 v[224:225], s[60:61], 0, v[156:157]
	s_mov_b32 m0, s83
	s_nop 0
	global_load_lds_dwordx4 v[224:225], off
	s_mov_b32 m0, s84
	s_nop 0
	global_load_lds_dwordx4 v[226:227], off
	s_waitcnt vmcnt(8)
	s_waitcnt lgkmcnt(0)
	s_barrier
	s_waitcnt lgkmcnt(0)
	v_mfma_f32_16x16x32_f16 v[60:63], v[128:131], v[190:193], v[60:63]
	v_mfma_f32_16x16x32_f16 v[56:59], v[136:139], v[190:193], v[56:59]
	v_mfma_f32_16x16x32_f16 v[44:47], v[128:131], v[198:201], v[44:47]
	v_mfma_f32_16x16x32_f16 v[40:43], v[136:139], v[198:201], v[40:43]
	v_mfma_f32_16x16x32_f16 v[28:31], v[128:131], v[206:209], v[28:31]
	v_mfma_f32_16x16x32_f16 v[24:27], v[136:139], v[206:209], v[24:27]
	v_mfma_f32_16x16x32_f16 v[12:15], v[128:131], v[214:217], v[12:15]
	v_mfma_f32_16x16x32_f16 v[8:11], v[136:139], v[214:217], v[8:11]
	v_mfma_f32_16x16x32_f16 v[60:63], v[132:135], v[194:197], v[60:63]
	v_mfma_f32_16x16x32_f16 v[56:59], v[140:143], v[194:197], v[56:59]
	v_mfma_f32_16x16x32_f16 v[44:47], v[132:135], v[202:205], v[44:47]
	v_mfma_f32_16x16x32_f16 v[40:43], v[140:143], v[202:205], v[40:43]
	v_mfma_f32_16x16x32_f16 v[28:31], v[132:135], v[210:213], v[28:31]
	v_mfma_f32_16x16x32_f16 v[24:27], v[140:143], v[210:213], v[24:27]
	v_mfma_f32_16x16x32_f16 v[12:15], v[132:135], v[218:221], v[12:15]
	v_mfma_f32_16x16x32_f16 v[8:11], v[140:143], v[218:221], v[8:11]
	v_mfma_f32_16x16x32_f16 v[52:55], v[144:147], v[190:193], v[52:55]
	v_mfma_f32_16x16x32_f16 v[48:51], v[152:155], v[190:193], v[48:51]
	v_mfma_f32_16x16x32_f16 v[36:39], v[144:147], v[198:201], v[36:39]
	v_mfma_f32_16x16x32_f16 v[32:35], v[152:155], v[198:201], v[32:35]
	v_mfma_f32_16x16x32_f16 v[20:23], v[144:147], v[206:209], v[20:23]
	v_mfma_f32_16x16x32_f16 v[16:19], v[152:155], v[206:209], v[16:19]
	v_mfma_f32_16x16x32_f16 v[4:7], v[144:147], v[214:217], v[4:7]
	v_mfma_f32_16x16x32_f16 v[0:3], v[152:155], v[214:217], v[0:3]
	v_mfma_f32_16x16x32_f16 v[52:55], v[148:151], v[194:197], v[52:55]
	v_mfma_f32_16x16x32_f16 v[48:51], v[174:177], v[194:197], v[48:51]
	v_mfma_f32_16x16x32_f16 v[36:39], v[148:151], v[202:205], v[36:39]
	v_mfma_f32_16x16x32_f16 v[32:35], v[174:177], v[202:205], v[32:35]
	v_mfma_f32_16x16x32_f16 v[20:23], v[148:151], v[210:213], v[20:23]
	v_mfma_f32_16x16x32_f16 v[16:19], v[174:177], v[210:213], v[16:19]
	v_mfma_f32_16x16x32_f16 v[4:7], v[148:151], v[218:221], v[4:7]
	v_mfma_f32_16x16x32_f16 v[0:3], v[174:177], v[218:221], v[0:3]
	s_barrier
; #define PG8_STAGE(bufoff, gbase, voff) do { _Pragma("unroll") for (int _i = 0; _i < 2; ++_i) \
;         __builtin_amdgcn_global_load_lds((const unsigned*)((const char*)(gbase) + (voff)[_i]), (PG8_LAS unsigned*)(lds + (bufoff) + ldsw + _i * 8192), 16, 0, 0); } while (0)
; #define PG8_LDA(dst, b, h) do { _Pragma("unroll") for (int m = 0; m < 4; ++m) _Pragma("unroll") for (int k = 0; k < 2; ++k) dst[m][k] = *(const PG8_LAS bf16x8*)(lds + PG8_SA(b, h) + aoff + m * 2048 + k * 1024); } while (0)
; #define PG8_LDB(dst, b, h) do { _Pragma("unroll") for (int n = 0; n < 2; ++n) _Pragma("unroll") for (int k = 0; k < 2; ++k) dst[n][k] = *(const PG8_LAS bf16x8*)(lds + PG8_SB(b, h) + boff + n * 2048 + k * 1024); } while (0)
; #define PG8_MMA(ai, bj, At, Bt) do { __builtin_amdgcn_s_setprio(1); _Pragma("unroll") for (int m = 0; m < 4; ++m) _Pragma("unroll") for (int n = 0; n < 2; ++n) _Pragma("unroll") for (int k = 0; k < 2; ++k) \
;         acc[ai][bj][m][n] = mma16<F16>(Bt[n][k], At[m][k], acc[ai][bj][m][n]); __builtin_amdgcn_s_setprio(0); } while (0)
; #define PG8_WAIT_V(n) asm volatile("s_waitcnt vmcnt(" #n ")" ::: "memory")
; #define PG8_WAIT_L(n) asm volatile("s_waitcnt lgkmcnt(" #n ")" ::: "memory")
; #define PG8_BAR __builtin_amdgcn_s_barrier()
; #define PG8_SCHED __builtin_amdgcn_sched_barrier(0)
; template <class Epi, class Sched, bool ALIGN_EPI = false, bool SP2 = false, bool F16 = false>
; __device__ __forceinline__ void gemm_phase(PG8_LAS unsigned char* lds, const Gemm g, const Sched& S, const Epi& E, const int wid_in) {
;     ...
;             PG8_LDB(B0, 1, 0); PG8_LDB(B1, 1, 1); PG8_SCHED; PG8_LDA(At, 1, 0); PG8_STAGE(PG8_SA(0, 1), a2 + hstep, voffA);
;             PG8_WAIT_V(8); PG8_WAIT_L(0); PG8_BAR; PG8_MMA(0, 0, At, B0); PG8_MMA(0, 1, At, B1); PG8_BAR; PG8_SCHED;
	s_add_i32 s63, 0, 0x18000
	s_add_i32 s64, 0, 0x1c000
	v_add_u32_e32 v140, s63, v183
	v_add_u32_e32 v165, s64, v183
	ds_read_b128 v[128:131], v140
	ds_read_b128 v[132:135], v140 offset:1024
	ds_read_b128 v[136:139], v140 offset:2048
	ds_read_b128 v[140:143], v140 offset:3072
	ds_read_b128 v[144:147], v165
	ds_read_b128 v[148:151], v165 offset:1024
	ds_read_b128 v[152:155], v165 offset:2048
	ds_read_b128 v[174:177], v165 offset:3072
	s_add_u32 s60, s60, 0x40000
	s_addc_u32 s61, s61, 0
	s_mov_b32 m0, s85
	v_lshl_add_u64 v[228:229], s[60:61], 0, v[156:157]
	ds_read_b128 v[190:193], v186 offset:32768
	ds_read_b128 v[194:197], v186 offset:33792
	ds_read_b128 v[198:201], v186 offset:34816
	ds_read_b128 v[202:205], v186 offset:35840
	ds_read_b128 v[206:209], v186 offset:36864
	ds_read_b128 v[210:213], v186 offset:37888
	ds_read_b128 v[214:217], v186 offset:38912
	ds_read_b128 v[218:221], v186 offset:39936
	global_load_lds_dwordx4 v[228:229], off
	v_lshl_add_u64 v[228:229], s[60:61], 0, v[160:161]
	s_mov_b32 m0, s86
	s_nop 0
	global_load_lds_dwordx4 v[228:229], off
	s_waitcnt vmcnt(8)
	s_waitcnt lgkmcnt(0)
	s_barrier
	s_waitcnt lgkmcnt(0)
	v_mfma_f32_16x16x32_f16 v[124:127], v[128:131], v[190:193], v[124:127]
	v_mfma_f32_16x16x32_f16 v[120:123], v[136:139], v[190:193], v[120:123]
	v_mfma_f32_16x16x32_f16 v[108:111], v[128:131], v[198:201], v[108:111]
	v_mfma_f32_16x16x32_f16 v[104:107], v[136:139], v[198:201], v[104:107]
	v_mfma_f32_16x16x32_f16 v[92:95], v[128:131], v[206:209], v[92:95]
	v_mfma_f32_16x16x32_f16 v[88:91], v[136:139], v[206:209], v[88:91]
	v_mfma_f32_16x16x32_f16 v[76:79], v[128:131], v[214:217], v[76:79]
	v_mfma_f32_16x16x32_f16 v[72:75], v[136:139], v[214:217], v[72:75]
	v_mfma_f32_16x16x32_f16 v[124:127], v[132:135], v[194:197], v[124:127]
	v_mfma_f32_16x16x32_f16 v[120:123], v[140:143], v[194:197], v[120:123]
	v_mfma_f32_16x16x32_f16 v[108:111], v[132:135], v[202:205], v[108:111]
	v_mfma_f32_16x16x32_f16 v[104:107], v[140:143], v[202:205], v[104:107]
	v_mfma_f32_16x16x32_f16 v[92:95], v[132:135], v[210:213], v[92:95]
	v_mfma_f32_16x16x32_f16 v[88:91], v[140:143], v[210:213], v[88:91]
	v_mfma_f32_16x16x32_f16 v[76:79], v[132:135], v[218:221], v[76:79]
	v_mfma_f32_16x16x32_f16 v[72:75], v[140:143], v[218:221], v[72:75]
	v_mfma_f32_16x16x32_f16 v[116:119], v[144:147], v[190:193], v[116:119]
	v_mfma_f32_16x16x32_f16 v[112:115], v[152:155], v[190:193], v[112:115]
	v_mfma_f32_16x16x32_f16 v[100:103], v[144:147], v[198:201], v[100:103]
	v_mfma_f32_16x16x32_f16 v[96:99], v[152:155], v[198:201], v[96:99]
	v_mfma_f32_16x16x32_f16 v[84:87], v[144:147], v[206:209], v[84:87]
	v_mfma_f32_16x16x32_f16 v[80:83], v[152:155], v[206:209], v[80:83]
	v_mfma_f32_16x16x32_f16 v[68:71], v[144:147], v[214:217], v[68:71]
	v_mfma_f32_16x16x32_f16 v[64:67], v[152:155], v[214:217], v[64:67]
	v_mfma_f32_16x16x32_f16 v[116:119], v[148:151], v[194:197], v[116:119]
	v_mfma_f32_16x16x32_f16 v[112:115], v[174:177], v[194:197], v[112:115]
	v_mfma_f32_16x16x32_f16 v[100:103], v[148:151], v[202:205], v[100:103]
	v_mfma_f32_16x16x32_f16 v[96:99], v[174:177], v[202:205], v[96:99]
	v_mfma_f32_16x16x32_f16 v[84:87], v[148:151], v[210:213], v[84:87]
	v_mfma_f32_16x16x32_f16 v[80:83], v[174:177], v[210:213], v[80:83]
	v_mfma_f32_16x16x32_f16 v[68:71], v[148:151], v[218:221], v[68:71]
	v_mfma_f32_16x16x32_f16 v[64:67], v[174:177], v[218:221], v[64:67]
	s_barrier
; #define PG8_STAGE(bufoff, gbase, voff) do { _Pragma("unroll") for (int _i = 0; _i < 2; ++_i) \
;         __builtin_amdgcn_global_load_lds((const unsigned*)((const char*)(gbase) + (voff)[_i]), (PG8_LAS unsigned*)(lds + (bufoff) + ldsw + _i * 8192), 16, 0, 0); } while (0)
; #define PG8_LDA(dst, b, h) do { _Pragma("unroll") for (int m = 0; m < 4; ++m) _Pragma("unroll") for (int k = 0; k < 2; ++k) dst[m][k] = *(const PG8_LAS bf16x8*)(lds + PG8_SA(b, h) + aoff + m * 2048 + k * 1024); } while (0)
; #define PG8_MMA(ai, bj, At, Bt) do { __builtin_amdgcn_s_setprio(1); _Pragma("unroll") for (int m = 0; m < 4; ++m) _Pragma("unroll") for (int n = 0; n < 2; ++n) _Pragma("unroll") for (int k = 0; k < 2; ++k) \
;         acc[ai][bj][m][n] = mma16<F16>(Bt[n][k], At[m][k], acc[ai][bj][m][n]); __builtin_amdgcn_s_setprio(0); } while (0)
; #define PG8_WAIT_V(n) asm volatile("s_waitcnt vmcnt(" #n ")" ::: "memory")
; #define PG8_WAIT_L(n) asm volatile("s_waitcnt lgkmcnt(" #n ")" ::: "memory")
; #define PG8_BAR __builtin_amdgcn_s_barrier()
; #define PG8_SCHED __builtin_amdgcn_sched_barrier(0)
; template <class Epi, class Sched, bool ALIGN_EPI = false, bool SP2 = false, bool F16 = false>
; __device__ __forceinline__ void gemm_phase(PG8_LAS unsigned char* lds, const Gemm g, const Sched& S, const Epi& E, const int wid_in) {
;     ...
;         for (int t = 0; t < nt; t += 2) {
;             const bool last = (t == nt - 2);
;             const char* a1 = cA + (size_t)(t + 1) * kstep;
;             const char* a2 = last ? nA : cA + (size_t)(t + 2) * kstep; const char* b2 = last ? nB : cB + (size_t)(t + 2) * kstep;
;     ...
;             PG8_LDA(At, 1, 1); PG8_STAGE(PG8_SB(1, 0), b3, voffB); PG8_STAGE(PG8_SB(1, 1), b3 + hstep, voffB); PG8_STAGE(PG8_SA(1, 0), a3, voffA);
;             PG8_WAIT_V(8); PG8_WAIT_L(0); PG8_BAR; PG8_MMA(1, 0, At, B0); PG8_MMA(1, 1, At, B1); PG8_BAR; PG8_SCHED;
	s_add_i32 s60, s63, s68
	v_lshl_add_u64 v[178:179], v[178:179], 0, s[24:25]
	s_mov_b32 m0, s60
	ds_read_b128 v[190:193], v186 offset:49152
	ds_read_b128 v[194:197], v186 offset:50176
	ds_read_b128 v[198:201], v186 offset:51200
	ds_read_b128 v[202:205], v186 offset:52224
	ds_read_b128 v[206:209], v186 offset:53248
	ds_read_b128 v[210:213], v186 offset:54272
	ds_read_b128 v[214:217], v186 offset:55296
	ds_read_b128 v[218:221], v186 offset:56320
	global_load_lds_dwordx4 v[178:179], off
	s_add_i32 m0, s60, 0x2000
	s_add_u32 s58, s58, 0x40080
	v_lshl_add_u64 v[178:179], v[222:223], 0, s[24:25]
	s_addc_u32 s59, s59, 0
	s_add_i32 s60, s64, s68
	global_load_lds_dwordx4 v[178:179], off
	v_lshl_add_u64 v[178:179], s[58:59], 0, v[158:159]
	s_mov_b32 m0, s60
	s_nop 0
	global_load_lds_dwordx4 v[178:179], off
	v_lshl_add_u64 v[178:179], s[58:59], 0, v[162:163]
	s_add_i32 m0, s60, 0x2000
	s_nop 0
	global_load_lds_dwordx4 v[178:179], off
	v_lshl_add_u64 v[178:179], v[224:225], 0, s[24:25]
	s_mov_b32 m0, s90
	s_nop 0
	global_load_lds_dwordx4 v[178:179], off
	v_lshl_add_u64 v[178:179], v[226:227], 0, s[24:25]
	s_mov_b32 m0, s91
	s_nop 0
	global_load_lds_dwordx4 v[178:179], off
	s_waitcnt vmcnt(8)
	s_waitcnt lgkmcnt(0)
	s_barrier
	s_waitcnt lgkmcnt(0)
	v_mfma_f32_16x16x32_f16 v[60:63], v[128:131], v[190:193], v[60:63]
	v_mfma_f32_16x16x32_f16 v[56:59], v[136:139], v[190:193], v[56:59]
	v_mfma_f32_16x16x32_f16 v[44:47], v[128:131], v[198:201], v[44:47]
	v_mfma_f32_16x16x32_f16 v[40:43], v[136:139], v[198:201], v[40:43]
	v_mfma_f32_16x16x32_f16 v[28:31], v[128:131], v[206:209], v[28:31]
	v_mfma_f32_16x16x32_f16 v[24:27], v[136:139], v[206:209], v[24:27]
	v_mfma_f32_16x16x32_f16 v[12:15], v[128:131], v[214:217], v[12:15]
	v_mfma_f32_16x16x32_f16 v[8:11], v[136:139], v[214:217], v[8:11]
	v_mfma_f32_16x16x32_f16 v[60:63], v[132:135], v[194:197], v[60:63]
	v_mfma_f32_16x16x32_f16 v[56:59], v[140:143], v[194:197], v[56:59]
	v_mfma_f32_16x16x32_f16 v[44:47], v[132:135], v[202:205], v[44:47]
	v_mfma_f32_16x16x32_f16 v[40:43], v[140:143], v[202:205], v[40:43]
	v_mfma_f32_16x16x32_f16 v[28:31], v[132:135], v[210:213], v[28:31]
	v_mfma_f32_16x16x32_f16 v[24:27], v[140:143], v[210:213], v[24:27]
	v_mfma_f32_16x16x32_f16 v[12:15], v[132:135], v[218:221], v[12:15]
	v_mfma_f32_16x16x32_f16 v[8:11], v[140:143], v[218:221], v[8:11]
	v_mfma_f32_16x16x32_f16 v[52:55], v[144:147], v[190:193], v[52:55]
	v_mfma_f32_16x16x32_f16 v[48:51], v[152:155], v[190:193], v[48:51]
	v_mfma_f32_16x16x32_f16 v[36:39], v[144:147], v[198:201], v[36:39]
	v_mfma_f32_16x16x32_f16 v[32:35], v[152:155], v[198:201], v[32:35]
	v_mfma_f32_16x16x32_f16 v[20:23], v[144:147], v[206:209], v[20:23]
	v_mfma_f32_16x16x32_f16 v[16:19], v[152:155], v[206:209], v[16:19]
	v_mfma_f32_16x16x32_f16 v[4:7], v[144:147], v[214:217], v[4:7]
	v_mfma_f32_16x16x32_f16 v[0:3], v[152:155], v[214:217], v[0:3]
	v_mfma_f32_16x16x32_f16 v[52:55], v[148:151], v[194:197], v[52:55]
	v_mfma_f32_16x16x32_f16 v[48:51], v[174:177], v[194:197], v[48:51]
	v_mfma_f32_16x16x32_f16 v[36:39], v[148:151], v[202:205], v[36:39]
	v_mfma_f32_16x16x32_f16 v[32:35], v[174:177], v[202:205], v[32:35]
	v_mfma_f32_16x16x32_f16 v[20:23], v[148:151], v[210:213], v[20:23]
	v_mfma_f32_16x16x32_f16 v[16:19], v[174:177], v[210:213], v[16:19]
	v_mfma_f32_16x16x32_f16 v[4:7], v[148:151], v[218:221], v[4:7]
	v_mfma_f32_16x16x32_f16 v[0:3], v[174:177], v[218:221], v[0:3]
	s_barrier
	s_add_i32 s62, s62, 2
	s_add_u32 s56, s56, 0x100
	s_addc_u32 s57, s57, 0
	s_add_u32 s49, s49, 0x100
	s_addc_u32 s51, s51, 0
	s_cmp_gt_u32 s62, 13
	s_cbranch_scc0 .LBB0_224
	s_setprio 0
	s_and_b64 vcc, exec, s[26:27]
	s_cbranch_vccz .LBB0_227
	s_barrier

; #define PG8_STAGE(bufoff, gbase, voff) do { _Pragma("unroll") for (int _i = 0; _i < 2; ++_i) \
;         __builtin_amdgcn_global_load_lds((const unsigned*)((const char*)(gbase) + (voff)[_i]), (PG8_LAS unsigned*)(lds + (bufoff) + ldsw + _i * 8192), 16, 0, 0); } while (0)
; #define PG8_LDA(dst, b, h) do { _Pragma("unroll") for (int m = 0; m < 4; ++m) _Pragma("unroll") for (int k = 0; k < 2; ++k) dst[m][k] = *(const PG8_LAS bf16x8*)(lds + PG8_SA(b, h) + aoff + m * 2048 + k * 1024); } while (0)
; #define PG8_LDB(dst, b, h) do { _Pragma("unroll") for (int n = 0; n < 2; ++n) _Pragma("unroll") for (int k = 0; k < 2; ++k) dst[n][k] = *(const PG8_LAS bf16x8*)(lds + PG8_SB(b, h) + boff + n * 2048 + k * 1024); } while (0)
; #define PG8_WAIT_V(n) asm volatile("s_waitcnt vmcnt(" #n ")" ::: "memory")
; #define PG8_WAIT_L(n) asm volatile("s_waitcnt lgkmcnt(" #n ")" ::: "memory")
; #define PG8_BAR __builtin_amdgcn_s_barrier()
; template <class Epi, class Sched, bool ALIGN_EPI = false, bool SP2 = false, bool F16 = false>
; __device__ __forceinline__ void gemm_phase(PG8_LAS unsigned char* lds, const Gemm g, const Sched& S, const Epi& E, const int wid_in) {
;     ...
;         const bool has_next = S.next(ui + 1, nxt);
;         const char* nA = has_next ? (const char*)g.A + (size_t)nxt.pm * tstep : cA; const char* nB = has_next ? (const char*)g.Bt + (size_t)nxt.pn * tstep : cB;
;         for (int t = 0; t < nt; t += 2) {
;             const bool last = (t == nt - 2);
;             const char* a1 = cA + (size_t)(t + 1) * kstep;
;             const char* a2 = last ? nA : cA + (size_t)(t + 2) * kstep; const char* b2 = last ? nB : cB + (size_t)(t + 2) * kstep;
;             const char* a3 = a2 + kstep; const char* b3 = b2 + kstep;
;             if (last && has_next) S.a_ready(nxt);
;             if constexpr (SP2) {
;             PG8_LDB(B0, 0, 0); PG8_LDB(B1, 0, 1); PG8_SCHED; PG8_LDA(At, 0, 0); PG8_STAGE(PG8_SA(1, 1), a1 + hstep, voffA);
;             PG8_WAIT_V(8); PG8_WAIT_L(0); PG8_BAR; PG8_MMA(0, 0, At, B0); PG8_MMA(0, 1, At, B1); PG8_BAR; PG8_SCHED;
;     ...
;         for (int a = 0; a < 2; ++a)
; #pragma unroll
;             for (int b = 0; b < 2; ++b)
; #pragma unroll
;                 for (int m = 0; m < 4; ++m)
; #pragma unroll
;                     for (int n = 0; n < 2; ++n) acc[a][b][m][n] = (f32x4){0.f, 0.f, 0.f, 0.f};
;         cur = nxt; cA = nA; cB = nB; ++ui;
.LBB0_507:
	s_ashr_i32 s27, s26, 31
	s_lshl_b64 s[28:29], s[26:27], 19
	s_add_u32 s28, s15, s28
	s_addc_u32 s29, s40, s29
	s_and_b64 s[30:31], s[8:9], exec
	s_cselect_b32 s10, s29, s45
	s_cselect_b32 s27, s28, s44
	s_ashr_i32 s25, s24, 31
	s_lshl_b64 s[30:31], s[24:25], 19
	s_add_u32 s30, s41, s30
	s_addc_u32 s31, s50, s31
	s_and_b64 s[42:43], s[8:9], exec
	s_cselect_b32 s25, s31, s47
	s_cselect_b32 s35, s30, s46
	s_add_u32 s44, s44, 0x40080
	s_addc_u32 s45, s45, 0
	s_add_u32 s37, s46, 0x100
	v_mov_b32_e32 v0, 0
	s_addc_u32 s42, s47, 0
	s_mov_b32 s43, -2
	v_mov_b32_e32 v1, v0
	v_mov_b32_e32 v2, v0
	v_mov_b32_e32 v3, v0
	v_mov_b32_e32 v4, v0
	v_mov_b32_e32 v5, v0
	v_mov_b32_e32 v6, v0
	v_mov_b32_e32 v7, v0
	v_mov_b32_e32 v16, v0
	v_mov_b32_e32 v17, v0
	v_mov_b32_e32 v18, v0
	v_mov_b32_e32 v19, v0
	v_mov_b32_e32 v20, v0
	v_mov_b32_e32 v21, v0
	v_mov_b32_e32 v22, v0
	v_mov_b32_e32 v23, v0
	v_mov_b32_e32 v32, v0
	v_mov_b32_e32 v33, v0
	v_mov_b32_e32 v34, v0
	v_mov_b32_e32 v35, v0
	v_mov_b32_e32 v36, v0
	v_mov_b32_e32 v37, v0
	v_mov_b32_e32 v38, v0
	v_mov_b32_e32 v39, v0
	v_mov_b32_e32 v48, v0
	v_mov_b32_e32 v49, v0
	v_mov_b32_e32 v50, v0
	v_mov_b32_e32 v51, v0
	v_mov_b32_e32 v52, v0
	v_mov_b32_e32 v53, v0
	v_mov_b32_e32 v54, v0
	v_mov_b32_e32 v55, v0
	v_mov_b32_e32 v8, v0
	v_mov_b32_e32 v9, v0
	v_mov_b32_e32 v10, v0
	v_mov_b32_e32 v11, v0
	v_mov_b32_e32 v12, v0
	v_mov_b32_e32 v13, v0
	v_mov_b32_e32 v14, v0
	v_mov_b32_e32 v15, v0
	v_mov_b32_e32 v24, v0
	v_mov_b32_e32 v25, v0
	v_mov_b32_e32 v26, v0
	v_mov_b32_e32 v27, v0
	v_mov_b32_e32 v28, v0
	v_mov_b32_e32 v29, v0
	v_mov_b32_e32 v30, v0
	v_mov_b32_e32 v31, v0
	v_mov_b32_e32 v40, v0
	v_mov_b32_e32 v41, v0
	v_mov_b32_e32 v42, v0
	v_mov_b32_e32 v43, v0
	v_mov_b32_e32 v44, v0
	v_mov_b32_e32 v45, v0
	v_mov_b32_e32 v46, v0
	v_mov_b32_e32 v47, v0
	v_mov_b32_e32 v56, v0
	v_mov_b32_e32 v57, v0
	v_mov_b32_e32 v58, v0
	v_mov_b32_e32 v59, v0
	v_mov_b32_e32 v60, v0
	v_mov_b32_e32 v61, v0
	v_mov_b32_e32 v62, v0
	v_mov_b32_e32 v63, v0
	v_mov_b32_e32 v64, v0
	v_mov_b32_e32 v65, v0
	v_mov_b32_e32 v66, v0
	v_mov_b32_e32 v67, v0
	v_mov_b32_e32 v68, v0
	v_mov_b32_e32 v69, v0
	v_mov_b32_e32 v70, v0
	v_mov_b32_e32 v71, v0
	v_mov_b32_e32 v80, v0
	v_mov_b32_e32 v81, v0
	v_mov_b32_e32 v82, v0
	v_mov_b32_e32 v83, v0
	v_mov_b32_e32 v84, v0
	v_mov_b32_e32 v85, v0
	v_mov_b32_e32 v86, v0
	v_mov_b32_e32 v87, v0
	v_mov_b32_e32 v96, v0
	v_mov_b32_e32 v97, v0
	v_mov_b32_e32 v98, v0
	v_mov_b32_e32 v99, v0
	v_mov_b32_e32 v100, v0
	v_mov_b32_e32 v101, v0
	v_mov_b32_e32 v102, v0
	v_mov_b32_e32 v103, v0
	v_mov_b32_e32 v112, v0
	v_mov_b32_e32 v113, v0
	v_mov_b32_e32 v114, v0
	v_mov_b32_e32 v115, v0
	v_mov_b32_e32 v116, v0
	v_mov_b32_e32 v117, v0
	v_mov_b32_e32 v118, v0
	v_mov_b32_e32 v119, v0
	v_mov_b32_e32 v72, v0
	v_mov_b32_e32 v73, v0
	v_mov_b32_e32 v74, v0
	v_mov_b32_e32 v75, v0
	v_mov_b32_e32 v76, v0
	v_mov_b32_e32 v77, v0
	v_mov_b32_e32 v78, v0
	v_mov_b32_e32 v79, v0
	v_mov_b32_e32 v88, v0
	v_mov_b32_e32 v89, v0
	v_mov_b32_e32 v90, v0
	v_mov_b32_e32 v91, v0
	v_mov_b32_e32 v92, v0
	v_mov_b32_e32 v93, v0
	v_mov_b32_e32 v94, v0
	v_mov_b32_e32 v95, v0
	v_mov_b32_e32 v104, v0
	v_mov_b32_e32 v105, v0
	v_mov_b32_e32 v106, v0
	v_mov_b32_e32 v107, v0
	v_mov_b32_e32 v108, v0
	v_mov_b32_e32 v109, v0
	v_mov_b32_e32 v110, v0
	v_mov_b32_e32 v111, v0
	v_mov_b32_e32 v120, v0
	v_mov_b32_e32 v121, v0
	v_mov_b32_e32 v122, v0
	v_mov_b32_e32 v123, v0
	v_mov_b32_e32 v124, v0
	v_mov_b32_e32 v125, v0
	v_mov_b32_e32 v126, v0
	v_mov_b32_e32 v127, v0
	s_cmp_ge_u32 s3, 4
	s_cbranch_scc0 .Lgsp_1
	s_setprio 1
.Lgsp_1:
.LBB0_508:
	ds_read_b128 v[128:131], v189
	ds_read_b128 v[132:135], v189 offset:1024
	ds_read_b128 v[136:139], v189 offset:2048
	ds_read_b128 v[140:143], v189 offset:3072
	ds_read_b128 v[144:147], v190
	ds_read_b128 v[148:151], v190 offset:1024
	ds_read_b128 v[168:171], v190 offset:2048
	ds_read_b128 v[172:175], v190 offset:3072
	s_add_u32 s46, s44, 0xfffc0080
	s_addc_u32 s47, s45, -1
	s_cmp_eq_u32 s43, 12
	s_cselect_b32 s49, s10, s47
	s_cselect_b32 s48, s27, s46
	s_cselect_b32 s47, s25, s42
	s_cselect_b32 s46, s35, s37
	v_lshl_add_u64 v[184:185], s[44:45], 0, v[160:161]
	s_add_i32 m0, s74, 0xc000
	ds_read_b128 v[176:179], v191
	ds_read_b128 v[180:183], v191 offset:1024
	ds_read_b128 v[192:195], v191 offset:2048
	ds_read_b128 v[196:199], v191 offset:3072
	ds_read_b128 v[200:203], v191 offset:4096
	ds_read_b128 v[204:207], v191 offset:5120
	ds_read_b128 v[208:211], v191 offset:6144
	ds_read_b128 v[212:215], v191 offset:7168
	global_load_lds_dwordx4 v[184:185], off
	v_lshl_add_u64 v[184:185], s[44:45], 0, v[162:163]
	s_add_i32 m0, s74, 0xe000
	s_nop 0
	global_load_lds_dwordx4 v[184:185], off
	s_waitcnt vmcnt(8)
	s_waitcnt lgkmcnt(0)
	s_barrier
; #define PG8_STAGE(bufoff, gbase, voff) do { _Pragma("unroll") for (int _i = 0; _i < 2; ++_i) \
;         __builtin_amdgcn_global_load_lds((const unsigned*)((const char*)(gbase) + (voff)[_i]), (PG8_LAS unsigned*)(lds + (bufoff) + ldsw + _i * 8192), 16, 0, 0); } while (0)
; #define PG8_LDA(dst, b, h) do { _Pragma("unroll") for (int m = 0; m < 4; ++m) _Pragma("unroll") for (int k = 0; k < 2; ++k) dst[m][k] = *(const PG8_LAS bf16x8*)(lds + PG8_SA(b, h) + aoff + m * 2048 + k * 1024); } while (0)
; #define PG8_MMA(ai, bj, At, Bt) do { __builtin_amdgcn_s_setprio(1); _Pragma("unroll") for (int m = 0; m < 4; ++m) _Pragma("unroll") for (int n = 0; n < 2; ++n) _Pragma("unroll") for (int k = 0; k < 2; ++k) \
;         acc[ai][bj][m][n] = mma16<F16>(Bt[n][k], At[m][k], acc[ai][bj][m][n]); __builtin_amdgcn_s_setprio(0); } while (0)
; #define PG8_WAIT_V(n) asm volatile("s_waitcnt vmcnt(" #n ")" ::: "memory")
; #define PG8_WAIT_L(n) asm volatile("s_waitcnt lgkmcnt(" #n ")" ::: "memory")
; #define PG8_BAR __builtin_amdgcn_s_barrier()
; #define PG8_SCHED __builtin_amdgcn_sched_barrier(0)
; template <class Epi, class Sched, bool ALIGN_EPI = false, bool SP2 = false, bool F16 = false>
; __device__ __forceinline__ void gemm_phase(PG8_LAS unsigned char* lds, const Gemm g, const Sched& S, const Epi& E, const int wid_in) {
;     ...
;             PG8_WAIT_V(8); PG8_WAIT_L(0); PG8_BAR; PG8_MMA(0, 0, At, B0); PG8_MMA(0, 1, At, B1); PG8_BAR; PG8_SCHED;
;             PG8_LDA(At, 0, 1); PG8_STAGE(PG8_SB(0, 0), b2, voffB); PG8_STAGE(PG8_SB(0, 1), b2 + hstep, voffB); PG8_STAGE(PG8_SA(0, 0), a2, voffA);
;             PG8_WAIT_V(8); PG8_WAIT_L(0); PG8_BAR; PG8_MMA(1, 0, At, B0); PG8_MMA(1, 1, At, B1); PG8_BAR; PG8_SCHED;
	s_waitcnt lgkmcnt(0)
	v_mfma_f32_16x16x32_bf16 v[124:127], v[128:131], v[176:179], v[124:127]
	v_mfma_f32_16x16x32_bf16 v[120:123], v[136:139], v[176:179], v[120:123]
	v_mfma_f32_16x16x32_bf16 v[108:111], v[128:131], v[192:195], v[108:111]
	v_mfma_f32_16x16x32_bf16 v[104:107], v[136:139], v[192:195], v[104:107]
	v_mfma_f32_16x16x32_bf16 v[92:95], v[128:131], v[200:203], v[92:95]
	v_mfma_f32_16x16x32_bf16 v[88:91], v[136:139], v[200:203], v[88:91]
	v_mfma_f32_16x16x32_bf16 v[76:79], v[128:131], v[208:211], v[76:79]
	v_mfma_f32_16x16x32_bf16 v[72:75], v[136:139], v[208:211], v[72:75]
	v_mfma_f32_16x16x32_bf16 v[124:127], v[132:135], v[180:183], v[124:127]
	v_mfma_f32_16x16x32_bf16 v[120:123], v[140:143], v[180:183], v[120:123]
	v_mfma_f32_16x16x32_bf16 v[108:111], v[132:135], v[196:199], v[108:111]
	v_mfma_f32_16x16x32_bf16 v[104:107], v[140:143], v[196:199], v[104:107]
	v_mfma_f32_16x16x32_bf16 v[92:95], v[132:135], v[204:207], v[92:95]
	v_mfma_f32_16x16x32_bf16 v[88:91], v[140:143], v[204:207], v[88:91]
	v_mfma_f32_16x16x32_bf16 v[76:79], v[132:135], v[212:215], v[76:79]
	v_mfma_f32_16x16x32_bf16 v[72:75], v[140:143], v[212:215], v[72:75]
	v_mfma_f32_16x16x32_bf16 v[116:119], v[144:147], v[176:179], v[116:119]
	v_mfma_f32_16x16x32_bf16 v[112:115], v[168:171], v[176:179], v[112:115]
	v_mfma_f32_16x16x32_bf16 v[100:103], v[144:147], v[192:195], v[100:103]
	v_mfma_f32_16x16x32_bf16 v[96:99], v[168:171], v[192:195], v[96:99]
	v_mfma_f32_16x16x32_bf16 v[84:87], v[144:147], v[200:203], v[84:87]
	v_mfma_f32_16x16x32_bf16 v[80:83], v[168:171], v[200:203], v[80:83]
	v_mfma_f32_16x16x32_bf16 v[68:71], v[144:147], v[208:211], v[68:71]
	v_mfma_f32_16x16x32_bf16 v[64:67], v[168:171], v[208:211], v[64:67]
	v_mfma_f32_16x16x32_bf16 v[116:119], v[148:151], v[180:183], v[116:119]
	v_mfma_f32_16x16x32_bf16 v[112:115], v[172:175], v[180:183], v[112:115]
	v_mfma_f32_16x16x32_bf16 v[100:103], v[148:151], v[196:199], v[100:103]
	v_mfma_f32_16x16x32_bf16 v[96:99], v[172:175], v[196:199], v[96:99]
	v_mfma_f32_16x16x32_bf16 v[84:87], v[148:151], v[204:207], v[84:87]
	v_mfma_f32_16x16x32_bf16 v[80:83], v[172:175], v[204:207], v[80:83]
	v_mfma_f32_16x16x32_bf16 v[68:71], v[148:151], v[212:215], v[68:71]
	v_mfma_f32_16x16x32_bf16 v[64:67], v[172:175], v[212:215], v[64:67]
	s_barrier
	s_add_i32 s63, s60, s68
	v_lshl_add_u64 v[184:185], s[46:47], 0, v[154:155]
	s_mov_b32 m0, s63
	ds_read_b128 v[176:179], v191 offset:16384
	ds_read_b128 v[180:183], v191 offset:17408
	ds_read_b128 v[192:195], v191 offset:18432
	ds_read_b128 v[196:199], v191 offset:19456
	ds_read_b128 v[200:203], v191 offset:20480
	ds_read_b128 v[204:207], v191 offset:21504
	ds_read_b128 v[208:211], v191 offset:22528
	ds_read_b128 v[212:215], v191 offset:23552
	global_load_lds_dwordx4 v[184:185], off
	s_add_i32 m0, s63, 0x2000
	s_add_u32 s64, s46, 0x40000
	v_lshl_add_u64 v[216:217], s[46:47], 0, v[158:159]
	s_addc_u32 s65, s47, 0
	s_add_i32 s63, s61, s68
	global_load_lds_dwordx4 v[216:217], off
	v_lshl_add_u64 v[218:219], s[64:65], 0, v[154:155]
	s_mov_b32 m0, s63
	v_lshl_add_u64 v[220:221], s[48:49], 0, v[156:157]
	global_load_lds_dwordx4 v[218:219], off
	v_lshl_add_u64 v[218:219], s[64:65], 0, v[158:159]
	s_add_i32 m0, s63, 0x2000
	s_nop 0
	global_load_lds_dwordx4 v[218:219], off
	v_lshl_add_u64 v[218:219], s[48:49], 0, v[152:153]
	s_mov_b32 m0, s74
	s_nop 0
	global_load_lds_dwordx4 v[218:219], off
	s_mov_b32 m0, s51
	s_nop 0
	global_load_lds_dwordx4 v[220:221], off
	s_waitcnt vmcnt(8)
	s_waitcnt lgkmcnt(0)
	s_barrier
	s_waitcnt lgkmcnt(0)
	v_mfma_f32_16x16x32_bf16 v[60:63], v[128:131], v[176:179], v[60:63]
	v_mfma_f32_16x16x32_bf16 v[56:59], v[136:139], v[176:179], v[56:59]
	v_mfma_f32_16x16x32_bf16 v[44:47], v[128:131], v[192:195], v[44:47]
	v_mfma_f32_16x16x32_bf16 v[40:43], v[136:139], v[192:195], v[40:43]
	v_mfma_f32_16x16x32_bf16 v[28:31], v[128:131], v[200:203], v[28:31]
	v_mfma_f32_16x16x32_bf16 v[24:27], v[136:139], v[200:203], v[24:27]
	v_mfma_f32_16x16x32_bf16 v[12:15], v[128:131], v[208:211], v[12:15]
	v_mfma_f32_16x16x32_bf16 v[8:11], v[136:139], v[208:211], v[8:11]
	v_mfma_f32_16x16x32_bf16 v[60:63], v[132:135], v[180:183], v[60:63]
	v_mfma_f32_16x16x32_bf16 v[56:59], v[140:143], v[180:183], v[56:59]
	v_mfma_f32_16x16x32_bf16 v[44:47], v[132:135], v[196:199], v[44:47]
	v_mfma_f32_16x16x32_bf16 v[40:43], v[140:143], v[196:199], v[40:43]
	v_mfma_f32_16x16x32_bf16 v[28:31], v[132:135], v[204:207], v[28:31]
	v_mfma_f32_16x16x32_bf16 v[24:27], v[140:143], v[204:207], v[24:27]
	v_mfma_f32_16x16x32_bf16 v[12:15], v[132:135], v[212:215], v[12:15]
	v_mfma_f32_16x16x32_bf16 v[8:11], v[140:143], v[212:215], v[8:11]
	v_mfma_f32_16x16x32_bf16 v[52:55], v[144:147], v[176:179], v[52:55]
	v_mfma_f32_16x16x32_bf16 v[48:51], v[168:171], v[176:179], v[48:51]
	v_mfma_f32_16x16x32_bf16 v[36:39], v[144:147], v[192:195], v[36:39]
	v_mfma_f32_16x16x32_bf16 v[32:35], v[168:171], v[192:195], v[32:35]
	v_mfma_f32_16x16x32_bf16 v[20:23], v[144:147], v[200:203], v[20:23]
	v_mfma_f32_16x16x32_bf16 v[16:19], v[168:171], v[200:203], v[16:19]
	v_mfma_f32_16x16x32_bf16 v[4:7], v[144:147], v[208:211], v[4:7]
	v_mfma_f32_16x16x32_bf16 v[0:3], v[168:171], v[208:211], v[0:3]
	v_mfma_f32_16x16x32_bf16 v[52:55], v[148:151], v[180:183], v[52:55]
	v_mfma_f32_16x16x32_bf16 v[48:51], v[172:175], v[180:183], v[48:51]
	v_mfma_f32_16x16x32_bf16 v[36:39], v[148:151], v[196:199], v[36:39]
	v_mfma_f32_16x16x32_bf16 v[32:35], v[172:175], v[196:199], v[32:35]
	v_mfma_f32_16x16x32_bf16 v[20:23], v[148:151], v[204:207], v[20:23]
	v_mfma_f32_16x16x32_bf16 v[16:19], v[172:175], v[204:207], v[16:19]
	v_mfma_f32_16x16x32_bf16 v[4:7], v[148:151], v[212:215], v[4:7]
	v_mfma_f32_16x16x32_bf16 v[0:3], v[172:175], v[212:215], v[0:3]
	s_barrier
; #define PG8_STAGE(bufoff, gbase, voff) do { _Pragma("unroll") for (int _i = 0; _i < 2; ++_i) \
;         __builtin_amdgcn_global_load_lds((const unsigned*)((const char*)(gbase) + (voff)[_i]), (PG8_LAS unsigned*)(lds + (bufoff) + ldsw + _i * 8192), 16, 0, 0); } while (0)
; #define PG8_LDA(dst, b, h) do { _Pragma("unroll") for (int m = 0; m < 4; ++m) _Pragma("unroll") for (int k = 0; k < 2; ++k) dst[m][k] = *(const PG8_LAS bf16x8*)(lds + PG8_SA(b, h) + aoff + m * 2048 + k * 1024); } while (0)
; #define PG8_LDB(dst, b, h) do { _Pragma("unroll") for (int n = 0; n < 2; ++n) _Pragma("unroll") for (int k = 0; k < 2; ++k) dst[n][k] = *(const PG8_LAS bf16x8*)(lds + PG8_SB(b, h) + boff + n * 2048 + k * 1024); } while (0)
; #define PG8_MMA(ai, bj, At, Bt) do { __builtin_amdgcn_s_setprio(1); _Pragma("unroll") for (int m = 0; m < 4; ++m) _Pragma("unroll") for (int n = 0; n < 2; ++n) _Pragma("unroll") for (int k = 0; k < 2; ++k) \
;         acc[ai][bj][m][n] = mma16<F16>(Bt[n][k], At[m][k], acc[ai][bj][m][n]); __builtin_amdgcn_s_setprio(0); } while (0)
; #define PG8_WAIT_V(n) asm volatile("s_waitcnt vmcnt(" #n ")" ::: "memory")
; #define PG8_WAIT_L(n) asm volatile("s_waitcnt lgkmcnt(" #n ")" ::: "memory")
; #define PG8_BAR __builtin_amdgcn_s_barrier()
; #define PG8_SCHED __builtin_amdgcn_sched_barrier(0)
; template <class Epi, class Sched, bool ALIGN_EPI = false, bool SP2 = false, bool F16 = false>
; __device__ __forceinline__ void gemm_phase(PG8_LAS unsigned char* lds, const Gemm g, const Sched& S, const Epi& E, const int wid_in) {
;     ...
;             PG8_LDB(B0, 1, 0); PG8_LDB(B1, 1, 1); PG8_SCHED; PG8_LDA(At, 1, 0); PG8_STAGE(PG8_SA(0, 1), a2 + hstep, voffA);
;             PG8_WAIT_V(8); PG8_WAIT_L(0); PG8_BAR; PG8_MMA(0, 0, At, B0); PG8_MMA(0, 1, At, B1); PG8_BAR; PG8_SCHED;
	s_add_i32 s63, 0, 0x18000
	s_add_i32 s64, 0, 0x1c000
	v_add_u32_e32 v140, s63, v188
	v_add_u32_e32 v172, s64, v188
	ds_read_b128 v[128:131], v140
	ds_read_b128 v[132:135], v140 offset:1024
	ds_read_b128 v[136:139], v140 offset:2048
	ds_read_b128 v[140:143], v140 offset:3072
	ds_read_b128 v[144:147], v172
	ds_read_b128 v[148:151], v172 offset:1024
	ds_read_b128 v[168:171], v172 offset:2048
	ds_read_b128 v[172:175], v172 offset:3072
	s_add_u32 s48, s48, 0x40000
	s_addc_u32 s49, s49, 0
	s_mov_b32 m0, s52
	v_lshl_add_u64 v[222:223], s[48:49], 0, v[152:153]
	ds_read_b128 v[176:179], v191 offset:32768
	ds_read_b128 v[180:183], v191 offset:33792
	ds_read_b128 v[192:195], v191 offset:34816
	ds_read_b128 v[196:199], v191 offset:35840
	ds_read_b128 v[200:203], v191 offset:36864
	ds_read_b128 v[204:207], v191 offset:37888
	ds_read_b128 v[208:211], v191 offset:38912
	ds_read_b128 v[212:215], v191 offset:39936
	global_load_lds_dwordx4 v[222:223], off
	v_lshl_add_u64 v[222:223], s[48:49], 0, v[156:157]
	s_mov_b32 m0, s53
	s_nop 0
	global_load_lds_dwordx4 v[222:223], off
	s_waitcnt vmcnt(8)
	s_waitcnt lgkmcnt(0)
	s_barrier
	s_waitcnt lgkmcnt(0)
	v_mfma_f32_16x16x32_bf16 v[124:127], v[128:131], v[176:179], v[124:127]
	v_mfma_f32_16x16x32_bf16 v[120:123], v[136:139], v[176:179], v[120:123]
	v_mfma_f32_16x16x32_bf16 v[108:111], v[128:131], v[192:195], v[108:111]
	v_mfma_f32_16x16x32_bf16 v[104:107], v[136:139], v[192:195], v[104:107]
	v_mfma_f32_16x16x32_bf16 v[92:95], v[128:131], v[200:203], v[92:95]
	v_mfma_f32_16x16x32_bf16 v[88:91], v[136:139], v[200:203], v[88:91]
	v_mfma_f32_16x16x32_bf16 v[76:79], v[128:131], v[208:211], v[76:79]
	v_mfma_f32_16x16x32_bf16 v[72:75], v[136:139], v[208:211], v[72:75]
	v_mfma_f32_16x16x32_bf16 v[124:127], v[132:135], v[180:183], v[124:127]
	v_mfma_f32_16x16x32_bf16 v[120:123], v[140:143], v[180:183], v[120:123]
	v_mfma_f32_16x16x32_bf16 v[108:111], v[132:135], v[196:199], v[108:111]
	v_mfma_f32_16x16x32_bf16 v[104:107], v[140:143], v[196:199], v[104:107]
	v_mfma_f32_16x16x32_bf16 v[92:95], v[132:135], v[204:207], v[92:95]
	v_mfma_f32_16x16x32_bf16 v[88:91], v[140:143], v[204:207], v[88:91]
	v_mfma_f32_16x16x32_bf16 v[76:79], v[132:135], v[212:215], v[76:79]
	v_mfma_f32_16x16x32_bf16 v[72:75], v[140:143], v[212:215], v[72:75]
	v_mfma_f32_16x16x32_bf16 v[116:119], v[144:147], v[176:179], v[116:119]
	v_mfma_f32_16x16x32_bf16 v[112:115], v[168:171], v[176:179], v[112:115]
	v_mfma_f32_16x16x32_bf16 v[100:103], v[144:147], v[192:195], v[100:103]
	v_mfma_f32_16x16x32_bf16 v[96:99], v[168:171], v[192:195], v[96:99]
	v_mfma_f32_16x16x32_bf16 v[84:87], v[144:147], v[200:203], v[84:87]
	v_mfma_f32_16x16x32_bf16 v[80:83], v[168:171], v[200:203], v[80:83]
	v_mfma_f32_16x16x32_bf16 v[68:71], v[144:147], v[208:211], v[68:71]
	v_mfma_f32_16x16x32_bf16 v[64:67], v[168:171], v[208:211], v[64:67]
	v_mfma_f32_16x16x32_bf16 v[116:119], v[148:151], v[180:183], v[116:119]
	v_mfma_f32_16x16x32_bf16 v[112:115], v[172:175], v[180:183], v[112:115]
	v_mfma_f32_16x16x32_bf16 v[100:103], v[148:151], v[196:199], v[100:103]
	v_mfma_f32_16x16x32_bf16 v[96:99], v[172:175], v[196:199], v[96:99]
	v_mfma_f32_16x16x32_bf16 v[84:87], v[148:151], v[204:207], v[84:87]
	v_mfma_f32_16x16x32_bf16 v[80:83], v[172:175], v[204:207], v[80:83]
	v_mfma_f32_16x16x32_bf16 v[68:71], v[148:151], v[212:215], v[68:71]
	v_mfma_f32_16x16x32_bf16 v[64:67], v[172:175], v[212:215], v[64:67]
	s_barrier
; #define PG8_STAGE(bufoff, gbase, voff) do { _Pragma("unroll") for (int _i = 0; _i < 2; ++_i) \
;         __builtin_amdgcn_global_load_lds((const unsigned*)((const char*)(gbase) + (voff)[_i]), (PG8_LAS unsigned*)(lds + (bufoff) + ldsw + _i * 8192), 16, 0, 0); } while (0)
; #define PG8_LDA(dst, b, h) do { _Pragma("unroll") for (int m = 0; m < 4; ++m) _Pragma("unroll") for (int k = 0; k < 2; ++k) dst[m][k] = *(const PG8_LAS bf16x8*)(lds + PG8_SA(b, h) + aoff + m * 2048 + k * 1024); } while (0)
; #define PG8_MMA(ai, bj, At, Bt) do { __builtin_amdgcn_s_setprio(1); _Pragma("unroll") for (int m = 0; m < 4; ++m) _Pragma("unroll") for (int n = 0; n < 2; ++n) _Pragma("unroll") for (int k = 0; k < 2; ++k) \
;         acc[ai][bj][m][n] = mma16<F16>(Bt[n][k], At[m][k], acc[ai][bj][m][n]); __builtin_amdgcn_s_setprio(0); } while (0)
; #define PG8_WAIT_V(n) asm volatile("s_waitcnt vmcnt(" #n ")" ::: "memory")
; #define PG8_WAIT_L(n) asm volatile("s_waitcnt lgkmcnt(" #n ")" ::: "memory")
; #define PG8_BAR __builtin_amdgcn_s_barrier()
; #define PG8_SCHED __builtin_amdgcn_sched_barrier(0)
; template <class Epi, class Sched, bool ALIGN_EPI = false, bool SP2 = false, bool F16 = false>
; __device__ __forceinline__ void gemm_phase(PG8_LAS unsigned char* lds, const Gemm g, const Sched& S, const Epi& E, const int wid_in) {
;     ...
;         for (int t = 0; t < nt; t += 2) {
;             const bool last = (t == nt - 2);
;             const char* a1 = cA + (size_t)(t + 1) * kstep;
;             const char* a2 = last ? nA : cA + (size_t)(t + 2) * kstep; const char* b2 = last ? nB : cB + (size_t)(t + 2) * kstep;
;     ...
;             PG8_LDA(At, 1, 1); PG8_STAGE(PG8_SB(1, 0), b3, voffB); PG8_STAGE(PG8_SB(1, 1), b3 + hstep, voffB); PG8_STAGE(PG8_SA(1, 0), a3, voffA);
;             PG8_WAIT_V(8); PG8_WAIT_L(0); PG8_BAR; PG8_MMA(1, 0, At, B0); PG8_MMA(1, 1, At, B1); PG8_BAR; PG8_SCHED;
	s_add_i32 s48, s63, s68
	v_lshl_add_u64 v[184:185], v[184:185], 0, s[22:23]
	s_mov_b32 m0, s48
	ds_read_b128 v[176:179], v191 offset:49152
	ds_read_b128 v[180:183], v191 offset:50176
	ds_read_b128 v[192:195], v191 offset:51200
	ds_read_b128 v[196:199], v191 offset:52224
	ds_read_b128 v[200:203], v191 offset:53248
	ds_read_b128 v[204:207], v191 offset:54272
	ds_read_b128 v[208:211], v191 offset:55296
	ds_read_b128 v[212:215], v191 offset:56320
	global_load_lds_dwordx4 v[184:185], off
	s_add_i32 m0, s48, 0x2000
	s_add_u32 s46, s46, 0x40080
	v_lshl_add_u64 v[184:185], v[216:217], 0, s[22:23]
	s_addc_u32 s47, s47, 0
	s_add_i32 s48, s64, s68
	global_load_lds_dwordx4 v[184:185], off
	v_lshl_add_u64 v[184:185], s[46:47], 0, v[154:155]
	s_mov_b32 m0, s48
	s_nop 0
	global_load_lds_dwordx4 v[184:185], off
	v_lshl_add_u64 v[184:185], s[46:47], 0, v[158:159]
	s_add_i32 m0, s48, 0x2000
	s_nop 0
	global_load_lds_dwordx4 v[184:185], off
	v_lshl_add_u64 v[184:185], v[218:219], 0, s[22:23]
	s_mov_b32 m0, s75
	s_nop 0
	global_load_lds_dwordx4 v[184:185], off
	v_lshl_add_u64 v[184:185], v[220:221], 0, s[22:23]
	s_mov_b32 m0, s54
	s_nop 0
	global_load_lds_dwordx4 v[184:185], off
	s_waitcnt vmcnt(8)
	s_waitcnt lgkmcnt(0)
	s_barrier
	s_waitcnt lgkmcnt(0)
	v_mfma_f32_16x16x32_bf16 v[60:63], v[128:131], v[176:179], v[60:63]
	v_mfma_f32_16x16x32_bf16 v[56:59], v[136:139], v[176:179], v[56:59]
	v_mfma_f32_16x16x32_bf16 v[44:47], v[128:131], v[192:195], v[44:47]
	v_mfma_f32_16x16x32_bf16 v[40:43], v[136:139], v[192:195], v[40:43]
	v_mfma_f32_16x16x32_bf16 v[28:31], v[128:131], v[200:203], v[28:31]
	v_mfma_f32_16x16x32_bf16 v[24:27], v[136:139], v[200:203], v[24:27]
	v_mfma_f32_16x16x32_bf16 v[12:15], v[128:131], v[208:211], v[12:15]
	v_mfma_f32_16x16x32_bf16 v[8:11], v[136:139], v[208:211], v[8:11]
	v_mfma_f32_16x16x32_bf16 v[60:63], v[132:135], v[180:183], v[60:63]
	v_mfma_f32_16x16x32_bf16 v[56:59], v[140:143], v[180:183], v[56:59]
	v_mfma_f32_16x16x32_bf16 v[44:47], v[132:135], v[196:199], v[44:47]
	v_mfma_f32_16x16x32_bf16 v[40:43], v[140:143], v[196:199], v[40:43]
	v_mfma_f32_16x16x32_bf16 v[28:31], v[132:135], v[204:207], v[28:31]
	v_mfma_f32_16x16x32_bf16 v[24:27], v[140:143], v[204:207], v[24:27]
	v_mfma_f32_16x16x32_bf16 v[12:15], v[132:135], v[212:215], v[12:15]
	v_mfma_f32_16x16x32_bf16 v[8:11], v[140:143], v[212:215], v[8:11]
	v_mfma_f32_16x16x32_bf16 v[52:55], v[144:147], v[176:179], v[52:55]
	v_mfma_f32_16x16x32_bf16 v[48:51], v[168:171], v[176:179], v[48:51]
	v_mfma_f32_16x16x32_bf16 v[36:39], v[144:147], v[192:195], v[36:39]
	v_mfma_f32_16x16x32_bf16 v[32:35], v[168:171], v[192:195], v[32:35]
	v_mfma_f32_16x16x32_bf16 v[20:23], v[144:147], v[200:203], v[20:23]
	v_mfma_f32_16x16x32_bf16 v[16:19], v[168:171], v[200:203], v[16:19]
	v_mfma_f32_16x16x32_bf16 v[4:7], v[144:147], v[208:211], v[4:7]
	v_mfma_f32_16x16x32_bf16 v[0:3], v[168:171], v[208:211], v[0:3]
	v_mfma_f32_16x16x32_bf16 v[52:55], v[148:151], v[180:183], v[52:55]
	v_mfma_f32_16x16x32_bf16 v[48:51], v[172:175], v[180:183], v[48:51]
	v_mfma_f32_16x16x32_bf16 v[36:39], v[148:151], v[196:199], v[36:39]
	v_mfma_f32_16x16x32_bf16 v[32:35], v[172:175], v[196:199], v[32:35]
	v_mfma_f32_16x16x32_bf16 v[20:23], v[148:151], v[204:207], v[20:23]
	v_mfma_f32_16x16x32_bf16 v[16:19], v[172:175], v[204:207], v[16:19]
	v_mfma_f32_16x16x32_bf16 v[4:7], v[148:151], v[212:215], v[4:7]
	v_mfma_f32_16x16x32_bf16 v[0:3], v[172:175], v[212:215], v[0:3]
	s_barrier
	s_add_i32 s43, s43, 2
	s_add_u32 s44, s44, 0x100
	s_addc_u32 s45, s45, 0
	s_add_u32 s37, s37, 0x100
	s_addc_u32 s42, s42, 0
	s_cmp_gt_u32 s43, 13
	s_cbranch_scc0 .LBB0_508
	s_setprio 0
	s_and_b64 vcc, exec, s[16:17]
	s_cbranch_vccz .LBB0_511
	s_barrier

; #define PG8_STAGE(bufoff, gbase, voff) do { _Pragma("unroll") for (int _i = 0; _i < 2; ++_i) \
;         __builtin_amdgcn_global_load_lds((const unsigned*)((const char*)(gbase) + (voff)[_i]), (PG8_LAS unsigned*)(lds + (bufoff) + ldsw + _i * 8192), 16, 0, 0); } while (0)
; #define PG8_LDA(dst, b, h) do { _Pragma("unroll") for (int m = 0; m < 4; ++m) _Pragma("unroll") for (int k = 0; k < 2; ++k) dst[m][k] = *(const PG8_LAS bf16x8*)(lds + PG8_SA(b, h) + aoff + m * 2048 + k * 1024); } while (0)
; #define PG8_LDB(dst, b, h) do { _Pragma("unroll") for (int n = 0; n < 2; ++n) _Pragma("unroll") for (int k = 0; k < 2; ++k) dst[n][k] = *(const PG8_LAS bf16x8*)(lds + PG8_SB(b, h) + boff + n * 2048 + k * 1024); } while (0)
; #define PG8_WAIT_V(n) asm volatile("s_waitcnt vmcnt(" #n ")" ::: "memory")
; #define PG8_WAIT_L(n) asm volatile("s_waitcnt lgkmcnt(" #n ")" ::: "memory")
; #define PG8_BAR __builtin_amdgcn_s_barrier()
; template <class Epi, class Sched, bool ALIGN_EPI = false, bool SP2 = false, bool F16 = false>
; __device__ __forceinline__ void gemm_phase(PG8_LAS unsigned char* lds, const Gemm g, const Sched& S, const Epi& E, const int wid_in) {
;     ...
;         const bool has_next = S.next(ui + 1, nxt);
;         const char* nA = has_next ? (const char*)g.A + (size_t)nxt.pm * tstep : cA; const char* nB = has_next ? (const char*)g.Bt + (size_t)nxt.pn * tstep : cB;
;         for (int t = 0; t < nt; t += 2) {
;             const bool last = (t == nt - 2);
;             const char* a1 = cA + (size_t)(t + 1) * kstep;
;             const char* a2 = last ? nA : cA + (size_t)(t + 2) * kstep; const char* b2 = last ? nB : cB + (size_t)(t + 2) * kstep;
;             const char* a3 = a2 + kstep; const char* b3 = b2 + kstep;
;             if (last && has_next) S.a_ready(nxt);
;             if constexpr (SP2) {
;             PG8_LDB(B0, 0, 0); PG8_LDB(B1, 0, 1); PG8_SCHED; PG8_LDA(At, 0, 0); PG8_STAGE(PG8_SA(1, 1), a1 + hstep, voffA);
;             PG8_WAIT_V(8); PG8_WAIT_L(0); PG8_BAR; PG8_MMA(0, 0, At, B0); PG8_MMA(0, 1, At, B1); PG8_BAR; PG8_SCHED;
;     ...
;         for (int a = 0; a < 2; ++a)
; #pragma unroll
;             for (int b = 0; b < 2; ++b)
; #pragma unroll
;                 for (int m = 0; m < 4; ++m)
; #pragma unroll
;                     for (int n = 0; n < 2; ++n) acc[a][b][m][n] = (f32x4){0.f, 0.f, 0.f, 0.f};
;         cur = nxt; cA = nA; cB = nB; ++ui;
.LBB0_584:
	s_ashr_i32 s23, s22, 31
	s_lshl_b64 s[24:25], s[22:23], 19
	s_add_u32 s24, s41, s24
	s_addc_u32 s25, s46, s25
	s_and_b64 s[26:27], s[8:9], exec
	s_cselect_b32 s23, s25, s35
	s_cselect_b32 s31, s24, s34
	s_ashr_i32 s21, s20, 31
	s_lshl_b64 s[26:27], s[20:21], 19
	s_add_u32 s26, s47, s26
	s_addc_u32 s27, s48, s27
	s_and_b64 s[42:43], s[8:9], exec
	s_cselect_b32 s21, s27, s37
	s_cselect_b32 s42, s26, s36
	s_add_u32 s34, s34, 0x40080
	s_addc_u32 s35, s35, 0
	s_add_u32 s43, s36, 0x100
	v_mov_b32_e32 v8, 0
	s_addc_u32 s64, s37, 0
	s_mov_b32 s65, -2
	v_mov_b32_e32 v9, v8
	v_mov_b32_e32 v10, v8
	v_mov_b32_e32 v11, v8
	v_mov_b32_e32 v12, v8
	v_mov_b32_e32 v13, v8
	v_mov_b32_e32 v14, v8
	v_mov_b32_e32 v15, v8
	v_mov_b32_e32 v24, v8
	v_mov_b32_e32 v25, v8
	v_mov_b32_e32 v26, v8
	v_mov_b32_e32 v27, v8
	v_mov_b32_e32 v28, v8
	v_mov_b32_e32 v29, v8
	v_mov_b32_e32 v30, v8
	v_mov_b32_e32 v31, v8
	v_mov_b32_e32 v40, v8
	v_mov_b32_e32 v41, v8
	v_mov_b32_e32 v42, v8
	v_mov_b32_e32 v43, v8
	v_mov_b32_e32 v44, v8
	v_mov_b32_e32 v45, v8
	v_mov_b32_e32 v46, v8
	v_mov_b32_e32 v47, v8
	v_mov_b32_e32 v56, v8
	v_mov_b32_e32 v57, v8
	v_mov_b32_e32 v58, v8
	v_mov_b32_e32 v59, v8
	v_mov_b32_e32 v60, v8
	v_mov_b32_e32 v61, v8
	v_mov_b32_e32 v62, v8
	v_mov_b32_e32 v63, v8
	v_mov_b32_e32 v16, v8
	v_mov_b32_e32 v17, v8
	v_mov_b32_e32 v18, v8
	v_mov_b32_e32 v19, v8
	v_mov_b32_e32 v20, v8
	v_mov_b32_e32 v21, v8
	v_mov_b32_e32 v22, v8
	v_mov_b32_e32 v23, v8
	v_mov_b32_e32 v32, v8
	v_mov_b32_e32 v33, v8
	v_mov_b32_e32 v34, v8
	v_mov_b32_e32 v35, v8
	v_mov_b32_e32 v36, v8
	v_mov_b32_e32 v37, v8
	v_mov_b32_e32 v38, v8
	v_mov_b32_e32 v39, v8
	v_mov_b32_e32 v48, v8
	v_mov_b32_e32 v49, v8
	v_mov_b32_e32 v50, v8
	v_mov_b32_e32 v51, v8
	v_mov_b32_e32 v52, v8
	v_mov_b32_e32 v53, v8
	v_mov_b32_e32 v54, v8
	v_mov_b32_e32 v55, v8
	v_mov_b32_e32 v64, v8
	v_mov_b32_e32 v65, v8
	v_mov_b32_e32 v66, v8
	v_mov_b32_e32 v67, v8
	v_mov_b32_e32 v68, v8
	v_mov_b32_e32 v69, v8
	v_mov_b32_e32 v70, v8
	v_mov_b32_e32 v71, v8
	v_mov_b32_e32 v72, v8
	v_mov_b32_e32 v73, v8
	v_mov_b32_e32 v74, v8
	v_mov_b32_e32 v75, v8
	v_mov_b32_e32 v76, v8
	v_mov_b32_e32 v77, v8
	v_mov_b32_e32 v78, v8
	v_mov_b32_e32 v79, v8
	v_mov_b32_e32 v88, v8
	v_mov_b32_e32 v89, v8
	v_mov_b32_e32 v90, v8
	v_mov_b32_e32 v91, v8
	v_mov_b32_e32 v92, v8
	v_mov_b32_e32 v93, v8
	v_mov_b32_e32 v94, v8
	v_mov_b32_e32 v95, v8
	v_mov_b32_e32 v104, v8
	v_mov_b32_e32 v105, v8
	v_mov_b32_e32 v106, v8
	v_mov_b32_e32 v107, v8
	v_mov_b32_e32 v108, v8
	v_mov_b32_e32 v109, v8
	v_mov_b32_e32 v110, v8
	v_mov_b32_e32 v111, v8
	v_mov_b32_e32 v120, v8
	v_mov_b32_e32 v121, v8
	v_mov_b32_e32 v122, v8
	v_mov_b32_e32 v123, v8
	v_mov_b32_e32 v124, v8
	v_mov_b32_e32 v125, v8
	v_mov_b32_e32 v126, v8
	v_mov_b32_e32 v127, v8
	v_mov_b32_e32 v80, v8
	v_mov_b32_e32 v81, v8
	v_mov_b32_e32 v82, v8
	v_mov_b32_e32 v83, v8
	v_mov_b32_e32 v84, v8
	v_mov_b32_e32 v85, v8
	v_mov_b32_e32 v86, v8
	v_mov_b32_e32 v87, v8
	v_mov_b32_e32 v96, v8
	v_mov_b32_e32 v97, v8
	v_mov_b32_e32 v98, v8
	v_mov_b32_e32 v99, v8
	v_mov_b32_e32 v100, v8
	v_mov_b32_e32 v101, v8
	v_mov_b32_e32 v102, v8
	v_mov_b32_e32 v103, v8
	v_mov_b32_e32 v112, v8
	v_mov_b32_e32 v113, v8
	v_mov_b32_e32 v114, v8
	v_mov_b32_e32 v115, v8
	v_mov_b32_e32 v116, v8
	v_mov_b32_e32 v117, v8
	v_mov_b32_e32 v118, v8
	v_mov_b32_e32 v119, v8
	v_mov_b32_e32 v128, v8
	v_mov_b32_e32 v129, v8
	v_mov_b32_e32 v130, v8
	v_mov_b32_e32 v131, v8
	v_mov_b32_e32 v132, v8
	v_mov_b32_e32 v133, v8
	v_mov_b32_e32 v134, v8
	v_mov_b32_e32 v135, v8
	s_cmp_ge_u32 s3, 4
	s_cbranch_scc0 .Lgsp_2
	s_setprio 1
.Lgsp_2:
.LBB0_585:
	ds_read_b128 v[0:3], v193
	ds_read_b128 v[4:7], v193 offset:1024
	ds_read_b128 v[136:139], v193 offset:2048
	ds_read_b128 v[140:143], v193 offset:3072
	ds_read_b128 v[144:147], v194
	ds_read_b128 v[148:151], v194 offset:1024
	ds_read_b128 v[152:155], v194 offset:2048
	ds_read_b128 v[156:159], v194 offset:3072
	s_add_u32 s36, s34, 0xfffc0080
	s_addc_u32 s37, s35, -1
	s_cmp_eq_u32 s65, 12
	s_cselect_b32 s45, s23, s37
	s_cselect_b32 s44, s31, s36
	s_cselect_b32 s37, s21, s64
	s_cselect_b32 s36, s42, s43
	v_lshl_add_u64 v[188:189], s[34:35], 0, v[168:169]
	s_add_i32 m0, s74, 0xc000
	ds_read_b128 v[176:179], v195
	ds_read_b128 v[180:183], v195 offset:1024
	ds_read_b128 v[184:187], v195 offset:2048
	ds_read_b128 v[198:201], v195 offset:3072
	ds_read_b128 v[202:205], v195 offset:4096
	ds_read_b128 v[206:209], v195 offset:5120
	ds_read_b128 v[210:213], v195 offset:6144
	ds_read_b128 v[214:217], v195 offset:7168
	global_load_lds_dwordx4 v[188:189], off
	v_lshl_add_u64 v[188:189], s[34:35], 0, v[170:171]
	s_add_i32 m0, s74, 0xe000
	s_nop 0
	global_load_lds_dwordx4 v[188:189], off
	s_waitcnt vmcnt(8)
	s_waitcnt lgkmcnt(0)
	s_barrier
; #define PG8_STAGE(bufoff, gbase, voff) do { _Pragma("unroll") for (int _i = 0; _i < 2; ++_i) \
;         __builtin_amdgcn_global_load_lds((const unsigned*)((const char*)(gbase) + (voff)[_i]), (PG8_LAS unsigned*)(lds + (bufoff) + ldsw + _i * 8192), 16, 0, 0); } while (0)
; #define PG8_LDA(dst, b, h) do { _Pragma("unroll") for (int m = 0; m < 4; ++m) _Pragma("unroll") for (int k = 0; k < 2; ++k) dst[m][k] = *(const PG8_LAS bf16x8*)(lds + PG8_SA(b, h) + aoff + m * 2048 + k * 1024); } while (0)
; #define PG8_MMA(ai, bj, At, Bt) do { __builtin_amdgcn_s_setprio(1); _Pragma("unroll") for (int m = 0; m < 4; ++m) _Pragma("unroll") for (int n = 0; n < 2; ++n) _Pragma("unroll") for (int k = 0; k < 2; ++k) \
;         acc[ai][bj][m][n] = mma16<F16>(Bt[n][k], At[m][k], acc[ai][bj][m][n]); __builtin_amdgcn_s_setprio(0); } while (0)
; #define PG8_WAIT_V(n) asm volatile("s_waitcnt vmcnt(" #n ")" ::: "memory")
; #define PG8_WAIT_L(n) asm volatile("s_waitcnt lgkmcnt(" #n ")" ::: "memory")
; #define PG8_BAR __builtin_amdgcn_s_barrier()
; #define PG8_SCHED __builtin_amdgcn_sched_barrier(0)
; template <class Epi, class Sched, bool ALIGN_EPI = false, bool SP2 = false, bool F16 = false>
; __device__ __forceinline__ void gemm_phase(PG8_LAS unsigned char* lds, const Gemm g, const Sched& S, const Epi& E, const int wid_in) {
;     ...
;             PG8_WAIT_V(8); PG8_WAIT_L(0); PG8_BAR; PG8_MMA(0, 0, At, B0); PG8_MMA(0, 1, At, B1); PG8_BAR; PG8_SCHED;
;             PG8_LDA(At, 0, 1); PG8_STAGE(PG8_SB(0, 0), b2, voffB); PG8_STAGE(PG8_SB(0, 1), b2 + hstep, voffB); PG8_STAGE(PG8_SA(0, 0), a2, voffA);
;             PG8_WAIT_V(8); PG8_WAIT_L(0); PG8_BAR; PG8_MMA(1, 0, At, B0); PG8_MMA(1, 1, At, B1); PG8_BAR; PG8_SCHED;
	s_waitcnt lgkmcnt(0)
	v_mfma_f32_16x16x32_f16 v[132:135], v[0:3], v[176:179], v[132:135]
	v_mfma_f32_16x16x32_f16 v[128:131], v[136:139], v[176:179], v[128:131]
	v_mfma_f32_16x16x32_f16 v[116:119], v[0:3], v[184:187], v[116:119]
	v_mfma_f32_16x16x32_f16 v[112:115], v[136:139], v[184:187], v[112:115]
	v_mfma_f32_16x16x32_f16 v[100:103], v[0:3], v[202:205], v[100:103]
	v_mfma_f32_16x16x32_f16 v[96:99], v[136:139], v[202:205], v[96:99]
	v_mfma_f32_16x16x32_f16 v[84:87], v[0:3], v[210:213], v[84:87]
	v_mfma_f32_16x16x32_f16 v[80:83], v[136:139], v[210:213], v[80:83]
	v_mfma_f32_16x16x32_f16 v[132:135], v[4:7], v[180:183], v[132:135]
	v_mfma_f32_16x16x32_f16 v[128:131], v[140:143], v[180:183], v[128:131]
	v_mfma_f32_16x16x32_f16 v[116:119], v[4:7], v[198:201], v[116:119]
	v_mfma_f32_16x16x32_f16 v[112:115], v[140:143], v[198:201], v[112:115]
	v_mfma_f32_16x16x32_f16 v[100:103], v[4:7], v[206:209], v[100:103]
	v_mfma_f32_16x16x32_f16 v[96:99], v[140:143], v[206:209], v[96:99]
	v_mfma_f32_16x16x32_f16 v[84:87], v[4:7], v[214:217], v[84:87]
	v_mfma_f32_16x16x32_f16 v[80:83], v[140:143], v[214:217], v[80:83]
	v_mfma_f32_16x16x32_f16 v[124:127], v[144:147], v[176:179], v[124:127]
	v_mfma_f32_16x16x32_f16 v[120:123], v[152:155], v[176:179], v[120:123]
	v_mfma_f32_16x16x32_f16 v[108:111], v[144:147], v[184:187], v[108:111]
	v_mfma_f32_16x16x32_f16 v[104:107], v[152:155], v[184:187], v[104:107]
	v_mfma_f32_16x16x32_f16 v[92:95], v[144:147], v[202:205], v[92:95]
	v_mfma_f32_16x16x32_f16 v[88:91], v[152:155], v[202:205], v[88:91]
	v_mfma_f32_16x16x32_f16 v[76:79], v[144:147], v[210:213], v[76:79]
	v_mfma_f32_16x16x32_f16 v[72:75], v[152:155], v[210:213], v[72:75]
	v_mfma_f32_16x16x32_f16 v[124:127], v[148:151], v[180:183], v[124:127]
	v_mfma_f32_16x16x32_f16 v[120:123], v[156:159], v[180:183], v[120:123]
	v_mfma_f32_16x16x32_f16 v[108:111], v[148:151], v[198:201], v[108:111]
	v_mfma_f32_16x16x32_f16 v[104:107], v[156:159], v[198:201], v[104:107]
	v_mfma_f32_16x16x32_f16 v[92:95], v[148:151], v[206:209], v[92:95]
	v_mfma_f32_16x16x32_f16 v[88:91], v[156:159], v[206:209], v[88:91]
	v_mfma_f32_16x16x32_f16 v[76:79], v[148:151], v[214:217], v[76:79]
	v_mfma_f32_16x16x32_f16 v[72:75], v[156:159], v[214:217], v[72:75]
	s_barrier
	s_add_i32 s66, s61, s68
	v_lshl_add_u64 v[188:189], s[36:37], 0, v[162:163]
	s_mov_b32 m0, s66
	ds_read_b128 v[176:179], v195 offset:16384
	ds_read_b128 v[180:183], v195 offset:17408
	ds_read_b128 v[184:187], v195 offset:18432
	ds_read_b128 v[198:201], v195 offset:19456
	ds_read_b128 v[202:205], v195 offset:20480
	ds_read_b128 v[206:209], v195 offset:21504
	ds_read_b128 v[210:213], v195 offset:22528
	ds_read_b128 v[214:217], v195 offset:23552
	global_load_lds_dwordx4 v[188:189], off
	s_add_i32 m0, s66, 0x2000
	s_add_u32 s66, s36, 0x40000
	v_lshl_add_u64 v[218:219], s[36:37], 0, v[166:167]
	s_addc_u32 s67, s37, 0
	s_add_i32 s76, s62, s68
	global_load_lds_dwordx4 v[218:219], off
	v_lshl_add_u64 v[220:221], s[66:67], 0, v[162:163]
	s_mov_b32 m0, s76
	v_lshl_add_u64 v[222:223], s[44:45], 0, v[164:165]
	global_load_lds_dwordx4 v[220:221], off
	v_lshl_add_u64 v[220:221], s[66:67], 0, v[166:167]
	s_add_i32 m0, s76, 0x2000
	s_nop 0
	global_load_lds_dwordx4 v[220:221], off
	v_lshl_add_u64 v[220:221], s[44:45], 0, v[160:161]
	s_mov_b32 m0, s74
	s_nop 0
	global_load_lds_dwordx4 v[220:221], off
	s_mov_b32 m0, s29
	s_nop 0
	global_load_lds_dwordx4 v[222:223], off
	s_waitcnt vmcnt(8)
	s_waitcnt lgkmcnt(0)
	s_barrier
	s_waitcnt lgkmcnt(0)
	v_mfma_f32_16x16x32_f16 v[68:71], v[0:3], v[176:179], v[68:71]
	v_mfma_f32_16x16x32_f16 v[64:67], v[136:139], v[176:179], v[64:67]
	v_mfma_f32_16x16x32_f16 v[52:55], v[0:3], v[184:187], v[52:55]
	v_mfma_f32_16x16x32_f16 v[48:51], v[136:139], v[184:187], v[48:51]
	v_mfma_f32_16x16x32_f16 v[36:39], v[0:3], v[202:205], v[36:39]
	v_mfma_f32_16x16x32_f16 v[32:35], v[136:139], v[202:205], v[32:35]
	v_mfma_f32_16x16x32_f16 v[0:3], v[0:3], v[210:213], v[20:23]
	v_mfma_f32_16x16x32_f16 v[68:71], v[4:7], v[180:183], v[68:71]
	v_mfma_f32_16x16x32_f16 v[64:67], v[140:143], v[180:183], v[64:67]
	v_mfma_f32_16x16x32_f16 v[52:55], v[4:7], v[198:201], v[52:55]
	v_mfma_f32_16x16x32_f16 v[48:51], v[140:143], v[198:201], v[48:51]
	v_mfma_f32_16x16x32_f16 v[36:39], v[4:7], v[206:209], v[36:39]
	v_mfma_f32_16x16x32_f16 v[32:35], v[140:143], v[206:209], v[32:35]
	v_mfma_f32_16x16x32_f16 v[0:3], v[4:7], v[214:217], v[0:3]
	v_mfma_f32_16x16x32_f16 v[4:7], v[136:139], v[210:213], v[16:19]
	v_mfma_f32_16x16x32_f16 v[4:7], v[140:143], v[214:217], v[4:7]
	v_mfma_f32_16x16x32_f16 v[16:19], v[144:147], v[176:179], v[60:63]
	v_mfma_f32_16x16x32_f16 v[60:63], v[148:151], v[180:183], v[16:19]
	v_mfma_f32_16x16x32_f16 v[16:19], v[152:155], v[176:179], v[56:59]
	v_mfma_f32_16x16x32_f16 v[56:59], v[156:159], v[180:183], v[16:19]
	v_mfma_f32_16x16x32_f16 v[16:19], v[144:147], v[184:187], v[44:47]
	v_mfma_f32_16x16x32_f16 v[44:47], v[148:151], v[198:201], v[16:19]
	v_mfma_f32_16x16x32_f16 v[16:19], v[152:155], v[184:187], v[40:43]
	v_mfma_f32_16x16x32_f16 v[40:43], v[156:159], v[198:201], v[16:19]
	v_mfma_f32_16x16x32_f16 v[16:19], v[144:147], v[202:205], v[28:31]
	v_mfma_f32_16x16x32_f16 v[28:31], v[148:151], v[206:209], v[16:19]
	v_mfma_f32_16x16x32_f16 v[16:19], v[152:155], v[202:205], v[24:27]
	v_mfma_f32_16x16x32_f16 v[12:15], v[144:147], v[210:213], v[12:15]
	v_mfma_f32_16x16x32_f16 v[8:11], v[152:155], v[210:213], v[8:11]
	v_mfma_f32_16x16x32_f16 v[24:27], v[156:159], v[206:209], v[16:19]
	v_mfma_f32_16x16x32_f16 v[12:15], v[148:151], v[214:217], v[12:15]
	v_mfma_f32_16x16x32_f16 v[8:11], v[156:159], v[214:217], v[8:11]
	s_barrier
; #define PG8_STAGE(bufoff, gbase, voff) do { _Pragma("unroll") for (int _i = 0; _i < 2; ++_i) \
;         __builtin_amdgcn_global_load_lds((const unsigned*)((const char*)(gbase) + (voff)[_i]), (PG8_LAS unsigned*)(lds + (bufoff) + ldsw + _i * 8192), 16, 0, 0); } while (0)
; #define PG8_LDA(dst, b, h) do { _Pragma("unroll") for (int m = 0; m < 4; ++m) _Pragma("unroll") for (int k = 0; k < 2; ++k) dst[m][k] = *(const PG8_LAS bf16x8*)(lds + PG8_SA(b, h) + aoff + m * 2048 + k * 1024); } while (0)
; #define PG8_LDB(dst, b, h) do { _Pragma("unroll") for (int n = 0; n < 2; ++n) _Pragma("unroll") for (int k = 0; k < 2; ++k) dst[n][k] = *(const PG8_LAS bf16x8*)(lds + PG8_SB(b, h) + boff + n * 2048 + k * 1024); } while (0)
; #define PG8_MMA(ai, bj, At, Bt) do { __builtin_amdgcn_s_setprio(1); _Pragma("unroll") for (int m = 0; m < 4; ++m) _Pragma("unroll") for (int n = 0; n < 2; ++n) _Pragma("unroll") for (int k = 0; k < 2; ++k) \
;         acc[ai][bj][m][n] = mma16<F16>(Bt[n][k], At[m][k], acc[ai][bj][m][n]); __builtin_amdgcn_s_setprio(0); } while (0)
; #define PG8_WAIT_V(n) asm volatile("s_waitcnt vmcnt(" #n ")" ::: "memory")
; #define PG8_WAIT_L(n) asm volatile("s_waitcnt lgkmcnt(" #n ")" ::: "memory")
; #define PG8_BAR __builtin_amdgcn_s_barrier()
; #define PG8_SCHED __builtin_amdgcn_sched_barrier(0)
; template <class Epi, class Sched, bool ALIGN_EPI = false, bool SP2 = false, bool F16 = false>
; __device__ __forceinline__ void gemm_phase(PG8_LAS unsigned char* lds, const Gemm g, const Sched& S, const Epi& E, const int wid_in) {
;     ...
;         for (int t = 0; t < nt; t += 2) {
;             const bool last = (t == nt - 2);
;             const char* a1 = cA + (size_t)(t + 1) * kstep;
;             const char* a2 = last ? nA : cA + (size_t)(t + 2) * kstep; const char* b2 = last ? nB : cB + (size_t)(t + 2) * kstep;
;     ...
;             PG8_LDB(B0, 1, 0); PG8_LDB(B1, 1, 1); PG8_SCHED; PG8_LDA(At, 1, 0); PG8_STAGE(PG8_SA(0, 1), a2 + hstep, voffA);
;             PG8_WAIT_V(8); PG8_WAIT_L(0); PG8_BAR; PG8_MMA(0, 0, At, B0); PG8_MMA(0, 1, At, B1); PG8_BAR; PG8_SCHED;
;             PG8_LDA(At, 1, 1); PG8_STAGE(PG8_SB(1, 0), b3, voffB); PG8_STAGE(PG8_SB(1, 1), b3 + hstep, voffB); PG8_STAGE(PG8_SA(1, 0), a3, voffA);
;             PG8_WAIT_V(8); PG8_WAIT_L(0); PG8_BAR; PG8_MMA(1, 0, At, B0); PG8_MMA(1, 1, At, B1); PG8_BAR; PG8_SCHED;
	s_add_i32 s66, 0, 0x18000
	s_add_i32 s67, 0, 0x1c000
	v_add_u32_e32 v140, s66, v192
	v_add_u32_e32 v156, s67, v192
	ds_read_b128 v[16:19], v140
	ds_read_b128 v[20:23], v140 offset:1024
	ds_read_b128 v[136:139], v140 offset:2048
	ds_read_b128 v[140:143], v140 offset:3072
	ds_read_b128 v[144:147], v156
	ds_read_b128 v[148:151], v156 offset:1024
	ds_read_b128 v[152:155], v156 offset:2048
	ds_read_b128 v[156:159], v156 offset:3072
	s_add_u32 s44, s44, 0x40000
	s_addc_u32 s45, s45, 0
	s_mov_b32 m0, s49
	v_lshl_add_u64 v[224:225], s[44:45], 0, v[160:161]
	ds_read_b128 v[176:179], v195 offset:32768
	ds_read_b128 v[180:183], v195 offset:33792
	ds_read_b128 v[184:187], v195 offset:34816
	ds_read_b128 v[198:201], v195 offset:35840
	ds_read_b128 v[202:205], v195 offset:36864
	ds_read_b128 v[206:209], v195 offset:37888
	ds_read_b128 v[210:213], v195 offset:38912
	ds_read_b128 v[214:217], v195 offset:39936
	global_load_lds_dwordx4 v[224:225], off
	v_lshl_add_u64 v[224:225], s[44:45], 0, v[164:165]
	s_mov_b32 m0, s50
	s_nop 0
	global_load_lds_dwordx4 v[224:225], off
	s_waitcnt vmcnt(8)
	s_waitcnt lgkmcnt(0)
	s_barrier
	s_waitcnt lgkmcnt(0)
	v_mfma_f32_16x16x32_f16 v[132:135], v[16:19], v[176:179], v[132:135]
	v_mfma_f32_16x16x32_f16 v[128:131], v[136:139], v[176:179], v[128:131]
	v_mfma_f32_16x16x32_f16 v[116:119], v[16:19], v[184:187], v[116:119]
	v_mfma_f32_16x16x32_f16 v[112:115], v[136:139], v[184:187], v[112:115]
	v_mfma_f32_16x16x32_f16 v[100:103], v[16:19], v[202:205], v[100:103]
	v_mfma_f32_16x16x32_f16 v[96:99], v[136:139], v[202:205], v[96:99]
	v_mfma_f32_16x16x32_f16 v[84:87], v[16:19], v[210:213], v[84:87]
	v_mfma_f32_16x16x32_f16 v[80:83], v[136:139], v[210:213], v[80:83]
	v_mfma_f32_16x16x32_f16 v[132:135], v[20:23], v[180:183], v[132:135]
	v_mfma_f32_16x16x32_f16 v[128:131], v[140:143], v[180:183], v[128:131]
	v_mfma_f32_16x16x32_f16 v[116:119], v[20:23], v[198:201], v[116:119]
	v_mfma_f32_16x16x32_f16 v[112:115], v[140:143], v[198:201], v[112:115]
	v_mfma_f32_16x16x32_f16 v[100:103], v[20:23], v[206:209], v[100:103]
	v_mfma_f32_16x16x32_f16 v[96:99], v[140:143], v[206:209], v[96:99]
	v_mfma_f32_16x16x32_f16 v[84:87], v[20:23], v[214:217], v[84:87]
	v_mfma_f32_16x16x32_f16 v[80:83], v[140:143], v[214:217], v[80:83]
	v_mfma_f32_16x16x32_f16 v[124:127], v[144:147], v[176:179], v[124:127]
	v_mfma_f32_16x16x32_f16 v[120:123], v[152:155], v[176:179], v[120:123]
	v_mfma_f32_16x16x32_f16 v[108:111], v[144:147], v[184:187], v[108:111]
	v_mfma_f32_16x16x32_f16 v[104:107], v[152:155], v[184:187], v[104:107]
	v_mfma_f32_16x16x32_f16 v[92:95], v[144:147], v[202:205], v[92:95]
	v_mfma_f32_16x16x32_f16 v[88:91], v[152:155], v[202:205], v[88:91]
	v_mfma_f32_16x16x32_f16 v[76:79], v[144:147], v[210:213], v[76:79]
	v_mfma_f32_16x16x32_f16 v[72:75], v[152:155], v[210:213], v[72:75]
	v_mfma_f32_16x16x32_f16 v[124:127], v[148:151], v[180:183], v[124:127]
	v_mfma_f32_16x16x32_f16 v[120:123], v[156:159], v[180:183], v[120:123]
	v_mfma_f32_16x16x32_f16 v[108:111], v[148:151], v[198:201], v[108:111]
	v_mfma_f32_16x16x32_f16 v[104:107], v[156:159], v[198:201], v[104:107]
	v_mfma_f32_16x16x32_f16 v[92:95], v[148:151], v[206:209], v[92:95]
	v_mfma_f32_16x16x32_f16 v[88:91], v[156:159], v[206:209], v[88:91]
	v_mfma_f32_16x16x32_f16 v[76:79], v[148:151], v[214:217], v[76:79]
	v_mfma_f32_16x16x32_f16 v[72:75], v[156:159], v[214:217], v[72:75]
	s_barrier
	s_add_i32 s44, s66, s68
	v_lshl_add_u64 v[188:189], v[188:189], 0, s[18:19]
	s_mov_b32 m0, s44
	ds_read_b128 v[176:179], v195 offset:49152
	ds_read_b128 v[180:183], v195 offset:50176
	ds_read_b128 v[184:187], v195 offset:51200
	ds_read_b128 v[198:201], v195 offset:52224
	ds_read_b128 v[202:205], v195 offset:53248
	ds_read_b128 v[206:209], v195 offset:54272
	ds_read_b128 v[210:213], v195 offset:55296
	ds_read_b128 v[214:217], v195 offset:56320
	global_load_lds_dwordx4 v[188:189], off
	s_add_i32 m0, s44, 0x2000
	s_add_u32 s36, s36, 0x40080
	v_lshl_add_u64 v[188:189], v[218:219], 0, s[18:19]
	s_addc_u32 s37, s37, 0
	s_add_i32 s44, s67, s68
	global_load_lds_dwordx4 v[188:189], off
	v_lshl_add_u64 v[188:189], s[36:37], 0, v[162:163]
	s_mov_b32 m0, s44
	s_nop 0
	global_load_lds_dwordx4 v[188:189], off
	v_lshl_add_u64 v[188:189], s[36:37], 0, v[166:167]
	s_add_i32 m0, s44, 0x2000
	s_nop 0
	global_load_lds_dwordx4 v[188:189], off
	v_lshl_add_u64 v[188:189], v[220:221], 0, s[18:19]
	s_mov_b32 m0, s75
	s_nop 0
	global_load_lds_dwordx4 v[188:189], off
	v_lshl_add_u64 v[188:189], v[222:223], 0, s[18:19]
	s_mov_b32 m0, s53
	s_nop 0
	global_load_lds_dwordx4 v[188:189], off
	s_waitcnt vmcnt(8)
	s_waitcnt lgkmcnt(0)
	s_barrier
	s_waitcnt lgkmcnt(0)
	v_mfma_f32_16x16x32_f16 v[68:71], v[16:19], v[176:179], v[68:71]
	v_mfma_f32_16x16x32_f16 v[52:55], v[16:19], v[184:187], v[52:55]
	v_mfma_f32_16x16x32_f16 v[36:39], v[16:19], v[202:205], v[36:39]
	v_mfma_f32_16x16x32_f16 v[0:3], v[16:19], v[210:213], v[0:3]
	v_mfma_f32_16x16x32_f16 v[68:71], v[20:23], v[180:183], v[68:71]
	v_mfma_f32_16x16x32_f16 v[64:67], v[136:139], v[176:179], v[64:67]
	v_mfma_f32_16x16x32_f16 v[52:55], v[20:23], v[198:201], v[52:55]
	v_mfma_f32_16x16x32_f16 v[48:51], v[136:139], v[184:187], v[48:51]
	v_mfma_f32_16x16x32_f16 v[36:39], v[20:23], v[206:209], v[36:39]
	v_mfma_f32_16x16x32_f16 v[32:35], v[136:139], v[202:205], v[32:35]
	v_mfma_f32_16x16x32_f16 v[20:23], v[20:23], v[214:217], v[0:3]
	v_mfma_f32_16x16x32_f16 v[0:3], v[136:139], v[210:213], v[4:7]
	v_mfma_f32_16x16x32_f16 v[64:67], v[140:143], v[180:183], v[64:67]
	v_mfma_f32_16x16x32_f16 v[48:51], v[140:143], v[198:201], v[48:51]
	v_mfma_f32_16x16x32_f16 v[32:35], v[140:143], v[206:209], v[32:35]
	v_mfma_f32_16x16x32_f16 v[16:19], v[140:143], v[214:217], v[0:3]
	v_mfma_f32_16x16x32_f16 v[0:3], v[144:147], v[176:179], v[60:63]
	v_mfma_f32_16x16x32_f16 v[60:63], v[148:151], v[180:183], v[0:3]
	v_mfma_f32_16x16x32_f16 v[0:3], v[152:155], v[176:179], v[56:59]
	v_mfma_f32_16x16x32_f16 v[56:59], v[156:159], v[180:183], v[0:3]
	v_mfma_f32_16x16x32_f16 v[0:3], v[144:147], v[184:187], v[44:47]
	v_mfma_f32_16x16x32_f16 v[44:47], v[148:151], v[198:201], v[0:3]
	v_mfma_f32_16x16x32_f16 v[0:3], v[152:155], v[184:187], v[40:43]
	v_mfma_f32_16x16x32_f16 v[40:43], v[156:159], v[198:201], v[0:3]
	v_mfma_f32_16x16x32_f16 v[0:3], v[144:147], v[202:205], v[28:31]
	v_mfma_f32_16x16x32_f16 v[28:31], v[148:151], v[206:209], v[0:3]
	v_mfma_f32_16x16x32_f16 v[0:3], v[152:155], v[202:205], v[24:27]
	v_mfma_f32_16x16x32_f16 v[24:27], v[156:159], v[206:209], v[0:3]
	v_mfma_f32_16x16x32_f16 v[0:3], v[144:147], v[210:213], v[12:15]
	v_mfma_f32_16x16x32_f16 v[12:15], v[148:151], v[214:217], v[0:3]
	v_mfma_f32_16x16x32_f16 v[0:3], v[152:155], v[210:213], v[8:11]
	v_mfma_f32_16x16x32_f16 v[8:11], v[156:159], v[214:217], v[0:3]
	s_barrier
	s_add_i32 s65, s65, 2
	s_add_u32 s34, s34, 0x100
	s_addc_u32 s35, s35, 0
	s_add_u32 s43, s43, 0x100
	s_addc_u32 s64, s64, 0
	s_cmp_gt_u32 s65, 13
	s_cbranch_scc0 .LBB0_585
	s_setprio 0
	s_and_b64 vcc, exec, s[16:17]
	s_cbranch_vccz .LBB0_588
	s_barrier

; #define PG8_STAGE(bufoff, gbase, voff) do { _Pragma("unroll") for (int _i = 0; _i < 2; ++_i) \
;         __builtin_amdgcn_global_load_lds((const unsigned*)((const char*)(gbase) + (voff)[_i]), (PG8_LAS unsigned*)(lds + (bufoff) + ldsw + _i * 8192), 16, 0, 0); } while (0)
; #define PG8_LDA(dst, b, h) do { _Pragma("unroll") for (int m = 0; m < 4; ++m) _Pragma("unroll") for (int k = 0; k < 2; ++k) dst[m][k] = *(const PG8_LAS bf16x8*)(lds + PG8_SA(b, h) + aoff + m * 2048 + k * 1024); } while (0)
; #define PG8_LDB(dst, b, h) do { _Pragma("unroll") for (int n = 0; n < 2; ++n) _Pragma("unroll") for (int k = 0; k < 2; ++k) dst[n][k] = *(const PG8_LAS bf16x8*)(lds + PG8_SB(b, h) + boff + n * 2048 + k * 1024); } while (0)
; #define PG8_WAIT_V(n) asm volatile("s_waitcnt vmcnt(" #n ")" ::: "memory")
; #define PG8_WAIT_L(n) asm volatile("s_waitcnt lgkmcnt(" #n ")" ::: "memory")
; #define PG8_BAR __builtin_amdgcn_s_barrier()
; #define PG8_SCHED __builtin_amdgcn_sched_barrier(0)
; template <class Epi, class Sched, bool ALIGN_EPI = false, bool SP2 = false, bool F16 = false>
; __device__ __forceinline__ void gemm_phase(PG8_LAS unsigned char* lds, const Gemm g, const Sched& S, const Epi& E, const int wid_in) {
;     ...
;         const bool has_next = S.next(ui + 1, nxt);
;         const char* nA = has_next ? (const char*)g.A + (size_t)nxt.pm * tstep : cA; const char* nB = has_next ? (const char*)g.Bt + (size_t)nxt.pn * tstep : cB;
;         for (int t = 0; t < nt; t += 2) {
;             const bool last = (t == nt - 2);
;             const char* a1 = cA + (size_t)(t + 1) * kstep;
;             const char* a2 = last ? nA : cA + (size_t)(t + 2) * kstep; const char* b2 = last ? nB : cB + (size_t)(t + 2) * kstep;
;             const char* a3 = a2 + kstep; const char* b3 = b2 + kstep;
;             if (last && has_next) S.a_ready(nxt);
;             if constexpr (SP2) {
;             PG8_LDB(B0, 0, 0); PG8_LDB(B1, 0, 1); PG8_SCHED; PG8_LDA(At, 0, 0); PG8_STAGE(PG8_SA(1, 1), a1 + hstep, voffA);
;             PG8_WAIT_V(8); PG8_WAIT_L(0); PG8_BAR; PG8_MMA(0, 0, At, B0); PG8_MMA(0, 1, At, B1); PG8_BAR; PG8_SCHED;
;             PG8_LDA(At, 0, 1); PG8_STAGE(PG8_SB(0, 0), b2, voffB); PG8_STAGE(PG8_SB(0, 1), b2 + hstep, voffB); PG8_STAGE(PG8_SA(0, 0), a2, voffA);
;             PG8_WAIT_V(8); PG8_WAIT_L(0); PG8_BAR; PG8_MMA(1, 0, At, B0); PG8_MMA(1, 1, At, B1); PG8_BAR; PG8_SCHED;
.LBB0_618:
	s_mov_b64 s[28:29], 0
	s_cmp_ge_u32 s3, 4
	s_cbranch_scc0 .Lgsp_3
	s_setprio 1
.Lgsp_3:
.LBB0_619:
	s_mov_b32 s30, 2
	s_mov_b64 s[26:27], 0
	s_andn2_b64 vcc, exec, s[28:29]
	s_mov_b32 s63, s61
	s_mov_b32 s28, s62
	s_cbranch_vccz .LBB0_625
.LBB0_620:
	s_mov_b64 s[44:45], s[10:11]
	s_add_i32 s10, s30, s40
	s_mov_b64 s[36:37], s[12:13]
	s_mov_b32 s12, s62
	s_mov_b32 s13, s61
	s_and_b32 s61, s10, 3
	s_ashr_i32 s62, s10, 2
	s_and_b64 s[10:11], s[26:27], exec
	s_cselect_b32 s12, s62, s12
	ds_read_b128 v[0:3], v134
	ds_read_b128 v[4:7], v134 offset:1024
	ds_read_b128 v[8:11], v134 offset:2048
	ds_read_b128 v[12:15], v134 offset:3072
	ds_read_b128 v[16:19], v135
	ds_read_b128 v[20:23], v135 offset:1024
	ds_read_b128 v[24:27], v135 offset:2048
	ds_read_b128 v[28:31], v135 offset:3072
	s_cselect_b32 s10, s61, s13
	s_ashr_i32 s13, s12, 31
	s_lshl_b64 s[12:13], s[12:13], 17
	s_add_u32 s12, s43, s12
	s_addc_u32 s13, s46, s13
	s_and_b64 s[30:31], s[26:27], exec
	s_cselect_b32 s35, s13, s37
	s_cselect_b32 s34, s12, s36
	s_ashr_i32 s11, s10, 31
	s_lshl_b64 s[10:11], s[10:11], 17
	s_add_u32 s10, s41, s10
	s_addc_u32 s11, s42, s11
	s_and_b64 s[30:31], s[26:27], exec
	s_cselect_b32 s31, s11, s45
	s_cselect_b32 s30, s10, s44
	s_add_u32 s64, s36, 0x10080
	s_addc_u32 s65, s37, 0
	s_mov_b32 m0, s15
	v_lshl_add_u64 v[64:65], s[64:65], 0, v[130:131]
	ds_read_b128 v[32:35], v136
	ds_read_b128 v[36:39], v136 offset:1024
	ds_read_b128 v[40:43], v136 offset:2048
	ds_read_b128 v[44:47], v136 offset:3072
	ds_read_b128 v[48:51], v136 offset:4096
	ds_read_b128 v[52:55], v136 offset:5120
	ds_read_b128 v[56:59], v136 offset:6144
	ds_read_b128 v[60:63], v136 offset:7168
	global_load_lds_dwordx4 v[64:65], off
	v_lshl_add_u64 v[64:65], s[64:65], 0, v[128:129]
	s_mov_b32 m0, s50
	s_nop 0
	global_load_lds_dwordx4 v[64:65], off
	s_waitcnt vmcnt(8)
	s_waitcnt lgkmcnt(0)
	s_barrier
	s_waitcnt lgkmcnt(0)
	v_mfma_f32_16x16x32_bf16 v[64:67], v[0:3], v[32:35], 0
	v_mfma_f32_16x16x32_bf16 v[68:71], v[8:11], v[32:35], 0
	v_mfma_f32_16x16x32_bf16 v[72:75], v[0:3], v[40:43], 0
	v_mfma_f32_16x16x32_bf16 v[76:79], v[8:11], v[40:43], 0
	v_mfma_f32_16x16x32_bf16 v[80:83], v[0:3], v[48:51], 0
	v_mfma_f32_16x16x32_bf16 v[84:87], v[8:11], v[48:51], 0
	v_mfma_f32_16x16x32_bf16 v[88:91], v[0:3], v[56:59], 0
	v_mfma_f32_16x16x32_bf16 v[92:95], v[8:11], v[56:59], 0
	v_mfma_f32_16x16x32_bf16 v[64:67], v[4:7], v[36:39], v[64:67]
	v_mfma_f32_16x16x32_bf16 v[68:71], v[12:15], v[36:39], v[68:71]
	v_mfma_f32_16x16x32_bf16 v[72:75], v[4:7], v[44:47], v[72:75]
	v_mfma_f32_16x16x32_bf16 v[76:79], v[12:15], v[44:47], v[76:79]
	v_mfma_f32_16x16x32_bf16 v[80:83], v[4:7], v[52:55], v[80:83]
	v_mfma_f32_16x16x32_bf16 v[84:87], v[12:15], v[52:55], v[84:87]
	v_mfma_f32_16x16x32_bf16 v[88:91], v[4:7], v[60:63], v[88:91]
	v_mfma_f32_16x16x32_bf16 v[92:95], v[12:15], v[60:63], v[92:95]
	v_mfma_f32_16x16x32_bf16 v[96:99], v[16:19], v[32:35], 0
	v_mfma_f32_16x16x32_bf16 v[32:35], v[24:27], v[32:35], 0
	v_mfma_f32_16x16x32_bf16 v[96:99], v[20:23], v[36:39], v[96:99]
	v_mfma_f32_16x16x32_bf16 v[32:35], v[28:31], v[36:39], v[32:35]
	v_mfma_f32_16x16x32_bf16 v[36:39], v[16:19], v[40:43], 0
	v_mfma_f32_16x16x32_bf16 v[40:43], v[24:27], v[40:43], 0
	v_mfma_f32_16x16x32_bf16 v[36:39], v[20:23], v[44:47], v[36:39]
	v_mfma_f32_16x16x32_bf16 v[40:43], v[28:31], v[44:47], v[40:43]
	v_mfma_f32_16x16x32_bf16 v[44:47], v[16:19], v[48:51], 0
	v_mfma_f32_16x16x32_bf16 v[48:51], v[24:27], v[48:51], 0
	v_mfma_f32_16x16x32_bf16 v[44:47], v[20:23], v[52:55], v[44:47]
	v_mfma_f32_16x16x32_bf16 v[48:51], v[28:31], v[52:55], v[48:51]
	v_mfma_f32_16x16x32_bf16 v[52:55], v[16:19], v[56:59], 0
	v_mfma_f32_16x16x32_bf16 v[56:59], v[24:27], v[56:59], 0
	v_mfma_f32_16x16x32_bf16 v[52:55], v[20:23], v[60:63], v[52:55]
	v_mfma_f32_16x16x32_bf16 v[56:59], v[28:31], v[60:63], v[56:59]
	s_barrier
	v_lshl_add_u64 v[204:205], s[44:45], 0, v[130:131]
	s_mov_b32 m0, s51
	v_lshl_add_u64 v[140:141], v[204:205], 0, s[22:23]
	v_lshl_add_u64 v[206:207], s[44:45], 0, v[128:129]
	s_add_u32 s64, s44, 0x10100
	ds_read_b128 v[60:63], v136 offset:16384
	ds_read_b128 v[100:103], v136 offset:17408
	ds_read_b128 v[104:107], v136 offset:18432
	ds_read_b128 v[108:111], v136 offset:19456
	ds_read_b128 v[112:115], v136 offset:20480
	ds_read_b128 v[116:119], v136 offset:21504
	ds_read_b128 v[120:123], v136 offset:22528
	ds_read_b128 v[124:127], v136 offset:23552
	global_load_lds_dwordx4 v[140:141], off
	v_lshl_add_u64 v[140:141], v[206:207], 0, s[22:23]
	s_mov_b32 m0, s52
	s_addc_u32 s65, s45, 0
	global_load_lds_dwordx4 v[140:141], off
	v_lshl_add_u64 v[140:141], s[64:65], 0, v[130:131]
	s_mov_b32 m0, s53
	v_lshl_add_u64 v[208:209], s[36:37], 0, v[130:131]
	global_load_lds_dwordx4 v[140:141], off
	v_lshl_add_u64 v[140:141], s[64:65], 0, v[128:129]
	s_mov_b32 m0, s54
	v_lshl_add_u64 v[210:211], s[36:37], 0, v[128:129]
	global_load_lds_dwordx4 v[140:141], off
	v_lshl_add_u64 v[140:141], v[208:209], 0, s[22:23]
	s_mov_b32 m0, s74
	s_nop 0
	global_load_lds_dwordx4 v[140:141], off
	v_lshl_add_u64 v[140:141], v[210:211], 0, s[22:23]
	s_mov_b32 m0, s47
	s_nop 0
	global_load_lds_dwordx4 v[140:141], off
	s_waitcnt vmcnt(8)
	s_waitcnt lgkmcnt(0)
	s_barrier
; #define PG8_STAGE(bufoff, gbase, voff) do { _Pragma("unroll") for (int _i = 0; _i < 2; ++_i) \
;         __builtin_amdgcn_global_load_lds((const unsigned*)((const char*)(gbase) + (voff)[_i]), (PG8_LAS unsigned*)(lds + (bufoff) + ldsw + _i * 8192), 16, 0, 0); } while (0)
; #define PG8_LDA(dst, b, h) do { _Pragma("unroll") for (int m = 0; m < 4; ++m) _Pragma("unroll") for (int k = 0; k < 2; ++k) dst[m][k] = *(const PG8_LAS bf16x8*)(lds + PG8_SA(b, h) + aoff + m * 2048 + k * 1024); } while (0)
; #define PG8_LDB(dst, b, h) do { _Pragma("unroll") for (int n = 0; n < 2; ++n) _Pragma("unroll") for (int k = 0; k < 2; ++k) dst[n][k] = *(const PG8_LAS bf16x8*)(lds + PG8_SB(b, h) + boff + n * 2048 + k * 1024); } while (0)
; #define PG8_MMA(ai, bj, At, Bt) do { __builtin_amdgcn_s_setprio(1); _Pragma("unroll") for (int m = 0; m < 4; ++m) _Pragma("unroll") for (int n = 0; n < 2; ++n) _Pragma("unroll") for (int k = 0; k < 2; ++k) \
;         acc[ai][bj][m][n] = mma16<F16>(Bt[n][k], At[m][k], acc[ai][bj][m][n]); __builtin_amdgcn_s_setprio(0); } while (0)
; #define PG8_WAIT_V(n) asm volatile("s_waitcnt vmcnt(" #n ")" ::: "memory")
; #define PG8_WAIT_L(n) asm volatile("s_waitcnt lgkmcnt(" #n ")" ::: "memory")
; #define PG8_BAR __builtin_amdgcn_s_barrier()
; #define PG8_SCHED __builtin_amdgcn_sched_barrier(0)
; template <class Epi, class Sched, bool ALIGN_EPI = false, bool SP2 = false, bool F16 = false>
; __device__ __forceinline__ void gemm_phase(PG8_LAS unsigned char* lds, const Gemm g, const Sched& S, const Epi& E, const int wid_in) {
;     ...
;             PG8_WAIT_V(8); PG8_WAIT_L(0); PG8_BAR; PG8_MMA(1, 0, At, B0); PG8_MMA(1, 1, At, B1); PG8_BAR; PG8_SCHED;
;             PG8_LDB(B0, 1, 0); PG8_LDB(B1, 1, 1); PG8_SCHED; PG8_LDA(At, 1, 0); PG8_STAGE(PG8_SA(0, 1), a2 + hstep, voffA);
;             PG8_WAIT_V(8); PG8_WAIT_L(0); PG8_BAR; PG8_MMA(0, 0, At, B0); PG8_MMA(0, 1, At, B1); PG8_BAR; PG8_SCHED;
	s_waitcnt lgkmcnt(0)
	v_mfma_f32_16x16x32_bf16 v[140:143], v[0:3], v[60:63], 0
	v_mfma_f32_16x16x32_bf16 v[148:151], v[0:3], v[104:107], 0
	v_mfma_f32_16x16x32_bf16 v[156:159], v[0:3], v[112:115], 0
	v_mfma_f32_16x16x32_bf16 v[0:3], v[0:3], v[120:123], 0
	v_mfma_f32_16x16x32_bf16 v[140:143], v[4:7], v[100:103], v[140:143]
	v_mfma_f32_16x16x32_bf16 v[148:151], v[4:7], v[108:111], v[148:151]
	v_mfma_f32_16x16x32_bf16 v[156:159], v[4:7], v[116:119], v[156:159]
	v_mfma_f32_16x16x32_bf16 v[0:3], v[4:7], v[124:127], v[0:3]
	v_mfma_f32_16x16x32_bf16 v[4:7], v[8:11], v[120:123], 0
	v_mfma_f32_16x16x32_bf16 v[144:147], v[8:11], v[60:63], 0
	v_mfma_f32_16x16x32_bf16 v[152:155], v[8:11], v[104:107], 0
	v_mfma_f32_16x16x32_bf16 v[160:163], v[8:11], v[112:115], 0
	v_mfma_f32_16x16x32_bf16 v[4:7], v[12:15], v[124:127], v[4:7]
	v_mfma_f32_16x16x32_bf16 v[144:147], v[12:15], v[100:103], v[144:147]
	v_mfma_f32_16x16x32_bf16 v[152:155], v[12:15], v[108:111], v[152:155]
	v_mfma_f32_16x16x32_bf16 v[160:163], v[12:15], v[116:119], v[160:163]
	v_mfma_f32_16x16x32_bf16 v[8:11], v[16:19], v[60:63], 0
	v_mfma_f32_16x16x32_bf16 v[12:15], v[24:27], v[60:63], 0
	v_mfma_f32_16x16x32_bf16 v[8:11], v[20:23], v[100:103], v[8:11]
	v_mfma_f32_16x16x32_bf16 v[12:15], v[28:31], v[100:103], v[12:15]
	v_mfma_f32_16x16x32_bf16 v[60:63], v[16:19], v[104:107], 0
	v_mfma_f32_16x16x32_bf16 v[100:103], v[24:27], v[104:107], 0
	v_mfma_f32_16x16x32_bf16 v[104:107], v[16:19], v[112:115], 0
	v_mfma_f32_16x16x32_bf16 v[16:19], v[16:19], v[120:123], 0
	v_mfma_f32_16x16x32_bf16 v[60:63], v[20:23], v[108:111], v[60:63]
	v_mfma_f32_16x16x32_bf16 v[100:103], v[28:31], v[108:111], v[100:103]
	v_mfma_f32_16x16x32_bf16 v[104:107], v[20:23], v[116:119], v[104:107]
	v_mfma_f32_16x16x32_bf16 v[108:111], v[24:27], v[112:115], 0
	v_mfma_f32_16x16x32_bf16 v[16:19], v[20:23], v[124:127], v[16:19]
	v_mfma_f32_16x16x32_bf16 v[20:23], v[24:27], v[120:123], 0
	v_mfma_f32_16x16x32_bf16 v[108:111], v[28:31], v[116:119], v[108:111]
	v_mfma_f32_16x16x32_bf16 v[20:23], v[28:31], v[124:127], v[20:23]
	s_barrier
	ds_read_b128 v[24:27], v137
	ds_read_b128 v[28:31], v137 offset:1024
	ds_read_b128 v[112:115], v137 offset:2048
	ds_read_b128 v[116:119], v137 offset:3072
	ds_read_b128 v[120:123], v138
	ds_read_b128 v[124:127], v138 offset:1024
	ds_read_b128 v[164:167], v138 offset:2048
	ds_read_b128 v[168:171], v138 offset:3072
	s_add_u32 s64, s36, 0x10100
	s_addc_u32 s65, s37, 0
	s_mov_b32 m0, s48
	v_lshl_add_u64 v[212:213], s[64:65], 0, v[130:131]
	ds_read_b128 v[172:175], v136 offset:32768
	ds_read_b128 v[176:179], v136 offset:33792
	ds_read_b128 v[180:183], v136 offset:34816
	ds_read_b128 v[184:187], v136 offset:35840
	ds_read_b128 v[188:191], v136 offset:36864
	ds_read_b128 v[192:195], v136 offset:37888
	ds_read_b128 v[196:199], v136 offset:38912
	ds_read_b128 v[200:203], v136 offset:39936
	global_load_lds_dwordx4 v[212:213], off
	v_lshl_add_u64 v[212:213], s[64:65], 0, v[128:129]
	s_mov_b32 m0, s49
	s_nop 0
	global_load_lds_dwordx4 v[212:213], off
	s_waitcnt vmcnt(8)
	s_waitcnt lgkmcnt(0)
	s_barrier
	s_waitcnt lgkmcnt(0)
	v_mfma_f32_16x16x32_bf16 v[64:67], v[24:27], v[172:175], v[64:67]
	v_mfma_f32_16x16x32_bf16 v[68:71], v[112:115], v[172:175], v[68:71]
	v_mfma_f32_16x16x32_bf16 v[72:75], v[24:27], v[180:183], v[72:75]
	v_mfma_f32_16x16x32_bf16 v[76:79], v[112:115], v[180:183], v[76:79]
	v_mfma_f32_16x16x32_bf16 v[80:83], v[24:27], v[188:191], v[80:83]
	v_mfma_f32_16x16x32_bf16 v[84:87], v[112:115], v[188:191], v[84:87]
	v_mfma_f32_16x16x32_bf16 v[88:91], v[24:27], v[196:199], v[88:91]
	v_mfma_f32_16x16x32_bf16 v[92:95], v[112:115], v[196:199], v[92:95]
	v_mfma_f32_16x16x32_bf16 v[64:67], v[28:31], v[176:179], v[64:67]
	v_mfma_f32_16x16x32_bf16 v[68:71], v[116:119], v[176:179], v[68:71]
	v_mfma_f32_16x16x32_bf16 v[72:75], v[28:31], v[184:187], v[72:75]
	v_mfma_f32_16x16x32_bf16 v[76:79], v[116:119], v[184:187], v[76:79]
	v_mfma_f32_16x16x32_bf16 v[80:83], v[28:31], v[192:195], v[80:83]
	v_mfma_f32_16x16x32_bf16 v[84:87], v[116:119], v[192:195], v[84:87]
	v_mfma_f32_16x16x32_bf16 v[88:91], v[28:31], v[200:203], v[88:91]
	v_mfma_f32_16x16x32_bf16 v[92:95], v[116:119], v[200:203], v[92:95]
	v_mfma_f32_16x16x32_bf16 v[96:99], v[120:123], v[172:175], v[96:99]
	v_mfma_f32_16x16x32_bf16 v[32:35], v[164:167], v[172:175], v[32:35]
	v_mfma_f32_16x16x32_bf16 v[36:39], v[120:123], v[180:183], v[36:39]
	v_mfma_f32_16x16x32_bf16 v[40:43], v[164:167], v[180:183], v[40:43]
	v_mfma_f32_16x16x32_bf16 v[44:47], v[120:123], v[188:191], v[44:47]
	v_mfma_f32_16x16x32_bf16 v[48:51], v[164:167], v[188:191], v[48:51]
	v_mfma_f32_16x16x32_bf16 v[52:55], v[120:123], v[196:199], v[52:55]
	v_mfma_f32_16x16x32_bf16 v[56:59], v[164:167], v[196:199], v[56:59]
	v_mfma_f32_16x16x32_bf16 v[96:99], v[124:127], v[176:179], v[96:99]
	v_mfma_f32_16x16x32_bf16 v[32:35], v[168:171], v[176:179], v[32:35]
	v_mfma_f32_16x16x32_bf16 v[36:39], v[124:127], v[184:187], v[36:39]
	v_mfma_f32_16x16x32_bf16 v[40:43], v[168:171], v[184:187], v[40:43]
	v_mfma_f32_16x16x32_bf16 v[44:47], v[124:127], v[192:195], v[44:47]
	v_mfma_f32_16x16x32_bf16 v[48:51], v[168:171], v[192:195], v[48:51]
	v_mfma_f32_16x16x32_bf16 v[52:55], v[124:127], v[200:203], v[52:55]
	v_mfma_f32_16x16x32_bf16 v[56:59], v[168:171], v[200:203], v[56:59]
	s_barrier
; #define PG8_STAGE(bufoff, gbase, voff) do { _Pragma("unroll") for (int _i = 0; _i < 2; ++_i) \
;         __builtin_amdgcn_global_load_lds((const unsigned*)((const char*)(gbase) + (voff)[_i]), (PG8_LAS unsigned*)(lds + (bufoff) + ldsw + _i * 8192), 16, 0, 0); } while (0)
; #define PG8_LDA(dst, b, h) do { _Pragma("unroll") for (int m = 0; m < 4; ++m) _Pragma("unroll") for (int k = 0; k < 2; ++k) dst[m][k] = *(const PG8_LAS bf16x8*)(lds + PG8_SA(b, h) + aoff + m * 2048 + k * 1024); } while (0)
; #define PG8_LDB(dst, b, h) do { _Pragma("unroll") for (int n = 0; n < 2; ++n) _Pragma("unroll") for (int k = 0; k < 2; ++k) dst[n][k] = *(const PG8_LAS bf16x8*)(lds + PG8_SB(b, h) + boff + n * 2048 + k * 1024); } while (0)
; #define PG8_MMA(ai, bj, At, Bt) do { __builtin_amdgcn_s_setprio(1); _Pragma("unroll") for (int m = 0; m < 4; ++m) _Pragma("unroll") for (int n = 0; n < 2; ++n) _Pragma("unroll") for (int k = 0; k < 2; ++k) \
;         acc[ai][bj][m][n] = mma16<F16>(Bt[n][k], At[m][k], acc[ai][bj][m][n]); __builtin_amdgcn_s_setprio(0); } while (0)
; #define PG8_WAIT_V(n) asm volatile("s_waitcnt vmcnt(" #n ")" ::: "memory")
; #define PG8_WAIT_L(n) asm volatile("s_waitcnt lgkmcnt(" #n ")" ::: "memory")
; #define PG8_BAR __builtin_amdgcn_s_barrier()
; #define PG8_SCHED __builtin_amdgcn_sched_barrier(0)
; template <class Epi, class Sched, bool ALIGN_EPI = false, bool SP2 = false, bool F16 = false>
; __device__ __forceinline__ void gemm_phase(PG8_LAS unsigned char* lds, const Gemm g, const Sched& S, const Epi& E, const int wid_in) {
;     ...
;             PG8_LDB(B0, 0, 0); PG8_LDB(B1, 0, 1); PG8_SCHED; PG8_LDA(At, 0, 0); PG8_STAGE(PG8_SA(1, 1), a1 + hstep, voffA);
;             PG8_WAIT_V(8); PG8_WAIT_L(0); PG8_BAR; PG8_MMA(0, 0, At, B0); PG8_MMA(0, 1, At, B1); PG8_BAR; PG8_SCHED;
;     ...
;             PG8_LDA(At, 1, 1); PG8_STAGE(PG8_SB(1, 0), b3, voffB); PG8_STAGE(PG8_SB(1, 1), b3 + hstep, voffB); PG8_STAGE(PG8_SA(1, 0), a3, voffA);
;             PG8_WAIT_V(8); PG8_WAIT_L(0); PG8_BAR; PG8_MMA(1, 0, At, B0); PG8_MMA(1, 1, At, B1); PG8_BAR; PG8_SCHED;
	s_mov_b32 m0, s55
	v_lshl_add_u64 v[204:205], v[204:205], 0, s[24:25]
	s_add_u32 s44, s44, 0x10180
	ds_read_b128 v[172:175], v136 offset:49152
	ds_read_b128 v[176:179], v136 offset:50176
	ds_read_b128 v[180:183], v136 offset:51200
	ds_read_b128 v[184:187], v136 offset:52224
	ds_read_b128 v[188:191], v136 offset:53248
	ds_read_b128 v[192:195], v136 offset:54272
	ds_read_b128 v[196:199], v136 offset:55296
	ds_read_b128 v[200:203], v136 offset:56320
	global_load_lds_dwordx4 v[204:205], off
	v_lshl_add_u64 v[204:205], v[206:207], 0, s[24:25]
	s_mov_b32 m0, s58
	s_addc_u32 s45, s45, 0
	global_load_lds_dwordx4 v[204:205], off
	v_lshl_add_u64 v[204:205], s[44:45], 0, v[130:131]
	s_mov_b32 m0, s59
	s_nop 0
	global_load_lds_dwordx4 v[204:205], off
	v_lshl_add_u64 v[204:205], s[44:45], 0, v[128:129]
	s_mov_b32 m0, s60
	s_nop 0
	global_load_lds_dwordx4 v[204:205], off
	v_lshl_add_u64 v[204:205], v[208:209], 0, s[24:25]
	s_mov_b32 m0, s75
	s_nop 0
	global_load_lds_dwordx4 v[204:205], off
	v_lshl_add_u64 v[204:205], v[210:211], 0, s[24:25]
	s_mov_b32 m0, s14
	s_nop 0
	global_load_lds_dwordx4 v[204:205], off
	s_waitcnt vmcnt(8)
	s_waitcnt lgkmcnt(0)
	s_barrier
	s_waitcnt lgkmcnt(0)
	v_mfma_f32_16x16x32_bf16 v[0:3], v[24:27], v[196:199], v[0:3]
	v_mfma_f32_16x16x32_bf16 v[4:7], v[112:115], v[196:199], v[4:7]
	v_mfma_f32_16x16x32_bf16 v[140:143], v[24:27], v[172:175], v[140:143]
	v_mfma_f32_16x16x32_bf16 v[144:147], v[112:115], v[172:175], v[144:147]
	v_mfma_f32_16x16x32_bf16 v[148:151], v[24:27], v[180:183], v[148:151]
	v_mfma_f32_16x16x32_bf16 v[152:155], v[112:115], v[180:183], v[152:155]
	v_mfma_f32_16x16x32_bf16 v[156:159], v[24:27], v[188:191], v[156:159]
	v_mfma_f32_16x16x32_bf16 v[160:163], v[112:115], v[188:191], v[160:163]
	v_mfma_f32_16x16x32_bf16 v[0:3], v[28:31], v[200:203], v[0:3]
	v_mfma_f32_16x16x32_bf16 v[4:7], v[116:119], v[200:203], v[4:7]
	v_mfma_f32_16x16x32_bf16 v[140:143], v[28:31], v[176:179], v[140:143]
	v_mfma_f32_16x16x32_bf16 v[144:147], v[116:119], v[176:179], v[144:147]
	v_mfma_f32_16x16x32_bf16 v[148:151], v[28:31], v[184:187], v[148:151]
	v_mfma_f32_16x16x32_bf16 v[152:155], v[116:119], v[184:187], v[152:155]
	v_mfma_f32_16x16x32_bf16 v[156:159], v[28:31], v[192:195], v[156:159]
	v_mfma_f32_16x16x32_bf16 v[160:163], v[116:119], v[192:195], v[160:163]
	v_mfma_f32_16x16x32_bf16 v[8:11], v[120:123], v[172:175], v[8:11]
	v_mfma_f32_16x16x32_bf16 v[12:15], v[164:167], v[172:175], v[12:15]
	v_mfma_f32_16x16x32_bf16 v[24:27], v[120:123], v[180:183], v[60:63]
	v_mfma_f32_16x16x32_bf16 v[28:31], v[164:167], v[180:183], v[100:103]
	v_mfma_f32_16x16x32_bf16 v[60:63], v[120:123], v[188:191], v[104:107]
	v_mfma_f32_16x16x32_bf16 v[100:103], v[164:167], v[188:191], v[108:111]
	v_mfma_f32_16x16x32_bf16 v[16:19], v[120:123], v[196:199], v[16:19]
	v_mfma_f32_16x16x32_bf16 v[20:23], v[164:167], v[196:199], v[20:23]
	v_mfma_f32_16x16x32_bf16 v[8:11], v[124:127], v[176:179], v[8:11]
	v_mfma_f32_16x16x32_bf16 v[12:15], v[168:171], v[176:179], v[12:15]
	v_mfma_f32_16x16x32_bf16 v[24:27], v[124:127], v[184:187], v[24:27]
	v_mfma_f32_16x16x32_bf16 v[28:31], v[168:171], v[184:187], v[28:31]
	v_mfma_f32_16x16x32_bf16 v[60:63], v[124:127], v[192:195], v[60:63]
	v_mfma_f32_16x16x32_bf16 v[100:103], v[168:171], v[192:195], v[100:103]
	v_mfma_f32_16x16x32_bf16 v[16:19], v[124:127], v[200:203], v[16:19]
	v_mfma_f32_16x16x32_bf16 v[20:23], v[168:171], v[200:203], v[20:23]
	s_barrier
	ds_read_b128 v[104:107], v134
	ds_read_b128 v[108:111], v134 offset:1024
	ds_read_b128 v[112:115], v134 offset:2048
	ds_read_b128 v[116:119], v134 offset:3072
	ds_read_b128 v[120:123], v135
	ds_read_b128 v[124:127], v135 offset:1024
	ds_read_b128 v[164:167], v135 offset:2048
	ds_read_b128 v[168:171], v135 offset:3072
	s_add_u32 s36, s36, 0x10180
	s_addc_u32 s37, s37, 0
	s_mov_b32 m0, s15
	v_lshl_add_u64 v[204:205], s[36:37], 0, v[130:131]
	ds_read_b128 v[172:175], v136
	ds_read_b128 v[176:179], v136 offset:1024
	ds_read_b128 v[180:183], v136 offset:2048
	ds_read_b128 v[184:187], v136 offset:3072
	ds_read_b128 v[188:191], v136 offset:4096
	ds_read_b128 v[192:195], v136 offset:5120
	ds_read_b128 v[196:199], v136 offset:6144
	ds_read_b128 v[200:203], v136 offset:7168
	global_load_lds_dwordx4 v[204:205], off
	v_lshl_add_u64 v[204:205], s[36:37], 0, v[128:129]
	s_mov_b32 m0, s50
	s_nop 0
	global_load_lds_dwordx4 v[204:205], off
	s_waitcnt vmcnt(8)
	s_waitcnt lgkmcnt(0)
	s_barrier
	s_waitcnt lgkmcnt(0)
	v_mfma_f32_16x16x32_bf16 v[64:67], v[104:107], v[172:175], v[64:67]
	v_mfma_f32_16x16x32_bf16 v[68:71], v[112:115], v[172:175], v[68:71]
	v_mfma_f32_16x16x32_bf16 v[72:75], v[104:107], v[180:183], v[72:75]
	v_mfma_f32_16x16x32_bf16 v[76:79], v[112:115], v[180:183], v[76:79]
	v_mfma_f32_16x16x32_bf16 v[80:83], v[104:107], v[188:191], v[80:83]
	v_mfma_f32_16x16x32_bf16 v[84:87], v[112:115], v[188:191], v[84:87]
	v_mfma_f32_16x16x32_bf16 v[88:91], v[104:107], v[196:199], v[88:91]
	v_mfma_f32_16x16x32_bf16 v[92:95], v[112:115], v[196:199], v[92:95]
	v_mfma_f32_16x16x32_bf16 v[64:67], v[108:111], v[176:179], v[64:67]
	v_mfma_f32_16x16x32_bf16 v[68:71], v[116:119], v[176:179], v[68:71]
	v_mfma_f32_16x16x32_bf16 v[72:75], v[108:111], v[184:187], v[72:75]
	v_mfma_f32_16x16x32_bf16 v[76:79], v[116:119], v[184:187], v[76:79]
	v_mfma_f32_16x16x32_bf16 v[80:83], v[108:111], v[192:195], v[80:83]
	v_mfma_f32_16x16x32_bf16 v[84:87], v[116:119], v[192:195], v[84:87]
	v_mfma_f32_16x16x32_bf16 v[88:91], v[108:111], v[200:203], v[88:91]
	v_mfma_f32_16x16x32_bf16 v[92:95], v[116:119], v[200:203], v[92:95]
	v_mfma_f32_16x16x32_bf16 v[32:35], v[164:167], v[172:175], v[32:35]
	v_mfma_f32_16x16x32_bf16 v[96:99], v[120:123], v[172:175], v[96:99]
	v_mfma_f32_16x16x32_bf16 v[172:175], v[168:171], v[176:179], v[32:35]
	v_mfma_f32_16x16x32_bf16 v[32:35], v[120:123], v[180:183], v[36:39]
	v_mfma_f32_16x16x32_bf16 v[204:207], v[124:127], v[176:179], v[96:99]
	v_mfma_f32_16x16x32_bf16 v[176:179], v[124:127], v[184:187], v[32:35]
	v_mfma_f32_16x16x32_bf16 v[32:35], v[164:167], v[180:183], v[40:43]
	v_mfma_f32_16x16x32_bf16 v[40:43], v[168:171], v[184:187], v[32:35]
	v_mfma_f32_16x16x32_bf16 v[32:35], v[120:123], v[188:191], v[44:47]
	v_mfma_f32_16x16x32_bf16 v[44:47], v[124:127], v[192:195], v[32:35]
	v_mfma_f32_16x16x32_bf16 v[32:35], v[164:167], v[188:191], v[48:51]
	v_mfma_f32_16x16x32_bf16 v[48:51], v[168:171], v[192:195], v[32:35]
	v_mfma_f32_16x16x32_bf16 v[32:35], v[120:123], v[196:199], v[52:55]
	v_mfma_f32_16x16x32_bf16 v[52:55], v[124:127], v[200:203], v[32:35]
	v_mfma_f32_16x16x32_bf16 v[32:35], v[164:167], v[196:199], v[56:59]
	v_mfma_f32_16x16x32_bf16 v[56:59], v[168:171], v[200:203], v[32:35]
	s_barrier
; #define PG8_STAGE(bufoff, gbase, voff) do { _Pragma("unroll") for (int _i = 0; _i < 2; ++_i) \
;         __builtin_amdgcn_global_load_lds((const unsigned*)((const char*)(gbase) + (voff)[_i]), (PG8_LAS unsigned*)(lds + (bufoff) + ldsw + _i * 8192), 16, 0, 0); } while (0)
; #define PG8_LDA(dst, b, h) do { _Pragma("unroll") for (int m = 0; m < 4; ++m) _Pragma("unroll") for (int k = 0; k < 2; ++k) dst[m][k] = *(const PG8_LAS bf16x8*)(lds + PG8_SA(b, h) + aoff + m * 2048 + k * 1024); } while (0)
; #define PG8_LDB(dst, b, h) do { _Pragma("unroll") for (int n = 0; n < 2; ++n) _Pragma("unroll") for (int k = 0; k < 2; ++k) dst[n][k] = *(const PG8_LAS bf16x8*)(lds + PG8_SB(b, h) + boff + n * 2048 + k * 1024); } while (0)
; #define PG8_MMA(ai, bj, At, Bt) do { __builtin_amdgcn_s_setprio(1); _Pragma("unroll") for (int m = 0; m < 4; ++m) _Pragma("unroll") for (int n = 0; n < 2; ++n) _Pragma("unroll") for (int k = 0; k < 2; ++k) \
;         acc[ai][bj][m][n] = mma16<F16>(Bt[n][k], At[m][k], acc[ai][bj][m][n]); __builtin_amdgcn_s_setprio(0); } while (0)
; #define PG8_WAIT_V(n) asm volatile("s_waitcnt vmcnt(" #n ")" ::: "memory")
; #define PG8_WAIT_L(n) asm volatile("s_waitcnt lgkmcnt(" #n ")" ::: "memory")
; #define PG8_BAR __builtin_amdgcn_s_barrier()
; #define PG8_SCHED __builtin_amdgcn_sched_barrier(0)
; template <class Epi, class Sched, bool ALIGN_EPI = false, bool SP2 = false, bool F16 = false>
; __device__ __forceinline__ void gemm_phase(PG8_LAS unsigned char* lds, const Gemm g, const Sched& S, const Epi& E, const int wid_in) {
;     ...
;             PG8_LDA(At, 0, 1); PG8_STAGE(PG8_SB(0, 0), b2, voffB); PG8_STAGE(PG8_SB(0, 1), b2 + hstep, voffB); PG8_STAGE(PG8_SA(0, 0), a2, voffA);
;             PG8_WAIT_V(8); PG8_WAIT_L(0); PG8_BAR; PG8_MMA(1, 0, At, B0); PG8_MMA(1, 1, At, B1); PG8_BAR; PG8_SCHED;
;             PG8_LDB(B0, 1, 0); PG8_LDB(B1, 1, 1); PG8_SCHED; PG8_LDA(At, 1, 0); PG8_STAGE(PG8_SA(0, 1), a2 + hstep, voffA);
;             PG8_WAIT_V(8); PG8_WAIT_L(0); PG8_BAR; PG8_MMA(0, 0, At, B0); PG8_MMA(0, 1, At, B1); PG8_BAR; PG8_SCHED;
	s_mov_b32 m0, s51
	v_lshl_add_u64 v[240:241], s[30:31], 0, v[130:131]
	s_add_u32 s36, s30, 0x10000
	s_nop 1
	ds_read_b128 v[32:35], v136 offset:16384
	ds_read_b128 v[36:39], v136 offset:17408
	ds_read_b128 v[96:99], v136 offset:18432
	ds_read_b128 v[180:183], v136 offset:19456
	ds_read_b128 v[184:187], v136 offset:20480
	ds_read_b128 v[188:191], v136 offset:21504
	ds_read_b128 v[192:195], v136 offset:22528
	ds_read_b128 v[196:199], v136 offset:23552
	global_load_lds_dwordx4 v[240:241], off
	v_lshl_add_u64 v[242:243], s[30:31], 0, v[128:129]
	s_mov_b32 m0, s52
	s_addc_u32 s37, s31, 0
	global_load_lds_dwordx4 v[242:243], off
	v_lshl_add_u64 v[200:201], s[36:37], 0, v[130:131]
	s_mov_b32 m0, s53
	v_lshl_add_u64 v[244:245], s[34:35], 0, v[130:131]
	global_load_lds_dwordx4 v[200:201], off
	v_lshl_add_u64 v[200:201], s[36:37], 0, v[128:129]
	s_mov_b32 m0, s54
	v_lshl_add_u64 v[246:247], s[34:35], 0, v[128:129]
	global_load_lds_dwordx4 v[200:201], off
	s_mov_b32 m0, s74
	s_nop 0
	global_load_lds_dwordx4 v[244:245], off
	s_mov_b32 m0, s47
	s_nop 0
	global_load_lds_dwordx4 v[246:247], off
	s_waitcnt vmcnt(8)
	s_waitcnt lgkmcnt(0)
	s_barrier
	s_waitcnt lgkmcnt(0)
	v_mfma_f32_16x16x32_bf16 v[0:3], v[104:107], v[192:195], v[0:3]
	v_mfma_f32_16x16x32_bf16 v[140:143], v[104:107], v[32:35], v[140:143]
	v_mfma_f32_16x16x32_bf16 v[144:147], v[112:115], v[32:35], v[144:147]
	v_mfma_f32_16x16x32_bf16 v[148:151], v[104:107], v[96:99], v[148:151]
	v_mfma_f32_16x16x32_bf16 v[152:155], v[112:115], v[96:99], v[152:155]
	v_mfma_f32_16x16x32_bf16 v[156:159], v[104:107], v[184:187], v[156:159]
	v_mfma_f32_16x16x32_bf16 v[160:163], v[112:115], v[184:187], v[160:163]
	v_mfma_f32_16x16x32_bf16 v[0:3], v[108:111], v[196:199], v[0:3]
	v_mfma_f32_16x16x32_bf16 v[4:7], v[112:115], v[192:195], v[4:7]
	v_mfma_f32_16x16x32_bf16 v[140:143], v[108:111], v[36:39], v[140:143]
	v_mfma_f32_16x16x32_bf16 v[144:147], v[116:119], v[36:39], v[144:147]
	v_mfma_f32_16x16x32_bf16 v[148:151], v[108:111], v[180:183], v[148:151]
	v_mfma_f32_16x16x32_bf16 v[152:155], v[116:119], v[180:183], v[152:155]
	v_mfma_f32_16x16x32_bf16 v[156:159], v[108:111], v[188:191], v[156:159]
	v_mfma_f32_16x16x32_bf16 v[160:163], v[116:119], v[188:191], v[160:163]
	v_mfma_f32_16x16x32_bf16 v[200:203], v[116:119], v[196:199], v[4:7]
	v_mfma_f32_16x16x32_bf16 v[4:7], v[120:123], v[32:35], v[8:11]
	v_mfma_f32_16x16x32_bf16 v[8:11], v[124:127], v[36:39], v[4:7]
	v_mfma_f32_16x16x32_bf16 v[4:7], v[164:167], v[32:35], v[12:15]
	v_mfma_f32_16x16x32_bf16 v[12:15], v[168:171], v[36:39], v[4:7]
	v_mfma_f32_16x16x32_bf16 v[4:7], v[120:123], v[96:99], v[24:27]
	v_mfma_f32_16x16x32_bf16 v[24:27], v[124:127], v[180:183], v[4:7]
	v_mfma_f32_16x16x32_bf16 v[4:7], v[164:167], v[96:99], v[28:31]
	v_mfma_f32_16x16x32_bf16 v[28:31], v[168:171], v[180:183], v[4:7]
	v_mfma_f32_16x16x32_bf16 v[4:7], v[120:123], v[184:187], v[60:63]
	v_mfma_f32_16x16x32_bf16 v[180:183], v[124:127], v[188:191], v[4:7]
	v_mfma_f32_16x16x32_bf16 v[4:7], v[164:167], v[184:187], v[100:103]
	v_mfma_f32_16x16x32_bf16 v[184:187], v[168:171], v[188:191], v[4:7]
	v_mfma_f32_16x16x32_bf16 v[4:7], v[120:123], v[192:195], v[16:19]
	v_mfma_f32_16x16x32_bf16 v[188:191], v[124:127], v[196:199], v[4:7]
	v_mfma_f32_16x16x32_bf16 v[4:7], v[164:167], v[192:195], v[20:23]
	v_mfma_f32_16x16x32_bf16 v[164:167], v[168:171], v[196:199], v[4:7]
	s_barrier
	s_nop 4
	ds_read_b128 v[4:7], v137
	ds_read_b128 v[60:63], v137 offset:1024
	ds_read_b128 v[168:171], v137 offset:2048
	ds_read_b128 v[192:195], v137 offset:3072
	ds_read_b128 v[196:199], v138
	ds_read_b128 v[208:211], v138 offset:1024
	ds_read_b128 v[212:215], v138 offset:2048
	ds_read_b128 v[216:219], v138 offset:3072
	s_add_u32 s34, s34, 0x10000
	s_addc_u32 s35, s35, 0
	s_mov_b32 m0, s48
	v_lshl_add_u64 v[32:33], s[34:35], 0, v[130:131]
	ds_read_b128 v[16:19], v136 offset:32768
	ds_read_b128 v[20:23], v136 offset:33792
	ds_read_b128 v[104:107], v136 offset:34816
	ds_read_b128 v[220:223], v136 offset:35840
	ds_read_b128 v[224:227], v136 offset:36864
	ds_read_b128 v[228:231], v136 offset:37888
	ds_read_b128 v[232:235], v136 offset:38912
	ds_read_b128 v[236:239], v136 offset:39936
	global_load_lds_dwordx4 v[32:33], off
	v_lshl_add_u64 v[32:33], s[34:35], 0, v[128:129]
	s_mov_b32 m0, s49
	s_nop 0
	global_load_lds_dwordx4 v[32:33], off
	s_waitcnt vmcnt(8)
	s_waitcnt lgkmcnt(0)
	s_barrier
	s_waitcnt lgkmcnt(0)
	v_mfma_f32_16x16x32_bf16 v[32:35], v[4:7], v[16:19], v[64:67]
	v_mfma_f32_16x16x32_bf16 v[116:119], v[60:63], v[20:23], v[32:35]
	v_mfma_f32_16x16x32_bf16 v[32:35], v[168:171], v[16:19], v[68:71]
	v_mfma_f32_16x16x32_bf16 v[112:115], v[192:195], v[20:23], v[32:35]
	v_mfma_f32_16x16x32_bf16 v[32:35], v[4:7], v[104:107], v[72:75]
	v_mfma_f32_16x16x32_bf16 v[100:103], v[60:63], v[220:223], v[32:35]
	v_mfma_f32_16x16x32_bf16 v[32:35], v[168:171], v[104:107], v[76:79]
	v_mfma_f32_16x16x32_bf16 v[96:99], v[192:195], v[220:223], v[32:35]
	v_mfma_f32_16x16x32_bf16 v[32:35], v[4:7], v[224:227], v[80:83]
	v_mfma_f32_16x16x32_bf16 v[68:71], v[60:63], v[228:231], v[32:35]
	v_mfma_f32_16x16x32_bf16 v[32:35], v[168:171], v[224:227], v[84:87]
	v_mfma_f32_16x16x32_bf16 v[64:67], v[192:195], v[228:231], v[32:35]
	v_mfma_f32_16x16x32_bf16 v[32:35], v[4:7], v[232:235], v[88:91]
	v_mfma_f32_16x16x32_bf16 v[36:39], v[60:63], v[236:239], v[32:35]
	v_mfma_f32_16x16x32_bf16 v[32:35], v[168:171], v[232:235], v[92:95]
	v_mfma_f32_16x16x32_bf16 v[32:35], v[192:195], v[236:239], v[32:35]
	v_mfma_f32_16x16x32_bf16 v[72:75], v[196:199], v[16:19], v[204:207]
	v_mfma_f32_16x16x32_bf16 v[16:19], v[212:215], v[16:19], v[172:175]
	v_mfma_f32_16x16x32_bf16 v[120:123], v[216:219], v[20:23], v[16:19]
	v_mfma_f32_16x16x32_bf16 v[16:19], v[196:199], v[104:107], v[176:179]
	v_mfma_f32_16x16x32_bf16 v[108:111], v[208:211], v[220:223], v[16:19]
	v_mfma_f32_16x16x32_bf16 v[16:19], v[212:215], v[104:107], v[40:43]
	v_mfma_f32_16x16x32_bf16 v[104:107], v[216:219], v[220:223], v[16:19]
	v_mfma_f32_16x16x32_bf16 v[16:19], v[196:199], v[224:227], v[44:47]
	v_mfma_f32_16x16x32_bf16 v[80:83], v[208:211], v[228:231], v[16:19]
	v_mfma_f32_16x16x32_bf16 v[16:19], v[212:215], v[224:227], v[48:51]
	v_mfma_f32_16x16x32_bf16 v[124:127], v[208:211], v[20:23], v[72:75]
	v_mfma_f32_16x16x32_bf16 v[72:75], v[216:219], v[228:231], v[16:19]
	v_mfma_f32_16x16x32_bf16 v[16:19], v[196:199], v[232:235], v[52:55]
	v_mfma_f32_16x16x32_bf16 v[48:51], v[208:211], v[236:239], v[16:19]
	v_mfma_f32_16x16x32_bf16 v[16:19], v[212:215], v[232:235], v[56:59]
	v_mfma_f32_16x16x32_bf16 v[40:43], v[216:219], v[236:239], v[16:19]
	s_barrier
; #define PG8_STAGE(bufoff, gbase, voff) do { _Pragma("unroll") for (int _i = 0; _i < 2; ++_i) \
;         __builtin_amdgcn_global_load_lds((const unsigned*)((const char*)(gbase) + (voff)[_i]), (PG8_LAS unsigned*)(lds + (bufoff) + ldsw + _i * 8192), 16, 0, 0); } while (0)
; #define PG8_LDA(dst, b, h) do { _Pragma("unroll") for (int m = 0; m < 4; ++m) _Pragma("unroll") for (int k = 0; k < 2; ++k) dst[m][k] = *(const PG8_LAS bf16x8*)(lds + PG8_SA(b, h) + aoff + m * 2048 + k * 1024); } while (0)
; #define PG8_MMA(ai, bj, At, Bt) do { __builtin_amdgcn_s_setprio(1); _Pragma("unroll") for (int m = 0; m < 4; ++m) _Pragma("unroll") for (int n = 0; n < 2; ++n) _Pragma("unroll") for (int k = 0; k < 2; ++k) \
;         acc[ai][bj][m][n] = mma16<F16>(Bt[n][k], At[m][k], acc[ai][bj][m][n]); __builtin_amdgcn_s_setprio(0); } while (0)
; #define PG8_WAIT_V(n) asm volatile("s_waitcnt vmcnt(" #n ")" ::: "memory")
; #define PG8_WAIT_L(n) asm volatile("s_waitcnt lgkmcnt(" #n ")" ::: "memory")
; #define PG8_BAR __builtin_amdgcn_s_barrier()
; #define PG8_SCHED __builtin_amdgcn_sched_barrier(0)
; template <class Epi, class Sched, bool ALIGN_EPI = false, bool SP2 = false, bool F16 = false>
; __device__ __forceinline__ void gemm_phase(PG8_LAS unsigned char* lds, const Gemm g, const Sched& S, const Epi& E, const int wid_in) {
;     ...
;             PG8_LDA(At, 1, 1); PG8_STAGE(PG8_SB(1, 0), b3, voffB); PG8_STAGE(PG8_SB(1, 1), b3 + hstep, voffB); PG8_STAGE(PG8_SA(1, 0), a3, voffA);
;             PG8_WAIT_V(8); PG8_WAIT_L(0); PG8_BAR; PG8_MMA(1, 0, At, B0); PG8_MMA(1, 1, At, B1); PG8_BAR; PG8_SCHED;
;     ...
;         if constexpr (ALIGN_EPI) { if (wr == 0) PG8_BAR; }
	s_mov_b32 m0, s55
	s_nop 3
	v_lshl_add_u64 v[16:17], v[240:241], 0, s[20:21]
	s_add_u32 s30, s30, 0x10080
	ds_read_b128 v[56:59], v136 offset:49152
	ds_read_b128 v[88:91], v136 offset:50176
	ds_read_b128 v[172:175], v136 offset:51200
	ds_read_b128 v[176:179], v136 offset:52224
	ds_read_b128 v[204:207], v136 offset:53248
	ds_read_b128 v[220:223], v136 offset:54272
	ds_read_b128 v[224:227], v136 offset:55296
	ds_read_b128 v[228:231], v136 offset:56320
	global_load_lds_dwordx4 v[16:17], off
	v_lshl_add_u64 v[16:17], v[242:243], 0, s[20:21]
	s_mov_b32 m0, s58
	s_addc_u32 s31, s31, 0
	global_load_lds_dwordx4 v[16:17], off
	v_lshl_add_u64 v[16:17], s[30:31], 0, v[130:131]
	s_mov_b32 m0, s59
	s_nop 0
	global_load_lds_dwordx4 v[16:17], off
	v_lshl_add_u64 v[16:17], s[30:31], 0, v[128:129]
	s_mov_b32 m0, s60
	s_nop 0
	global_load_lds_dwordx4 v[16:17], off
	v_lshl_add_u64 v[16:17], v[244:245], 0, s[20:21]
	s_mov_b32 m0, s75
	s_nop 0
	global_load_lds_dwordx4 v[16:17], off
	v_lshl_add_u64 v[16:17], v[246:247], 0, s[20:21]
	s_mov_b32 m0, s14
	s_nop 0
	global_load_lds_dwordx4 v[16:17], off
	s_waitcnt vmcnt(8)
	s_waitcnt lgkmcnt(0)
	s_barrier
	s_waitcnt lgkmcnt(0)
	v_mfma_f32_16x16x32_bf16 v[16:19], v[4:7], v[56:59], v[140:143]
	v_mfma_f32_16x16x32_bf16 v[84:87], v[60:63], v[88:91], v[16:19]
	v_mfma_f32_16x16x32_bf16 v[16:19], v[168:171], v[56:59], v[144:147]
	v_mfma_f32_16x16x32_bf16 v[76:79], v[192:195], v[88:91], v[16:19]
	v_mfma_f32_16x16x32_bf16 v[16:19], v[4:7], v[172:175], v[148:151]
	v_mfma_f32_16x16x32_bf16 v[52:55], v[60:63], v[176:179], v[16:19]
	v_mfma_f32_16x16x32_bf16 v[16:19], v[168:171], v[172:175], v[152:155]
	v_mfma_f32_16x16x32_bf16 v[44:47], v[192:195], v[176:179], v[16:19]
	v_mfma_f32_16x16x32_bf16 v[16:19], v[4:7], v[204:207], v[156:159]
	v_mfma_f32_16x16x32_bf16 v[0:3], v[4:7], v[224:227], v[0:3]
	v_mfma_f32_16x16x32_bf16 v[20:23], v[60:63], v[220:223], v[16:19]
	v_mfma_f32_16x16x32_bf16 v[16:19], v[168:171], v[204:207], v[160:163]
	v_mfma_f32_16x16x32_bf16 v[4:7], v[60:63], v[228:231], v[0:3]
	v_mfma_f32_16x16x32_bf16 v[0:3], v[168:171], v[224:227], v[200:203]
	v_mfma_f32_16x16x32_bf16 v[16:19], v[192:195], v[220:223], v[16:19]
	v_mfma_f32_16x16x32_bf16 v[0:3], v[192:195], v[228:231], v[0:3]
	v_mfma_f32_16x16x32_bf16 v[8:11], v[196:199], v[56:59], v[8:11]
	v_mfma_f32_16x16x32_bf16 v[92:95], v[208:211], v[88:91], v[8:11]
	v_mfma_f32_16x16x32_bf16 v[8:11], v[212:215], v[56:59], v[12:15]
	v_mfma_f32_16x16x32_bf16 v[88:91], v[216:219], v[88:91], v[8:11]
	v_mfma_f32_16x16x32_bf16 v[8:11], v[196:199], v[172:175], v[24:27]
	v_mfma_f32_16x16x32_bf16 v[60:63], v[208:211], v[176:179], v[8:11]
	v_mfma_f32_16x16x32_bf16 v[8:11], v[212:215], v[172:175], v[28:31]
	v_mfma_f32_16x16x32_bf16 v[56:59], v[216:219], v[176:179], v[8:11]
	v_mfma_f32_16x16x32_bf16 v[8:11], v[196:199], v[204:207], v[180:183]
	v_mfma_f32_16x16x32_bf16 v[28:31], v[208:211], v[220:223], v[8:11]
	v_mfma_f32_16x16x32_bf16 v[8:11], v[212:215], v[204:207], v[184:187]
	v_mfma_f32_16x16x32_bf16 v[24:27], v[216:219], v[220:223], v[8:11]
	v_mfma_f32_16x16x32_bf16 v[8:11], v[196:199], v[224:227], v[188:191]
	v_mfma_f32_16x16x32_bf16 v[12:15], v[208:211], v[228:231], v[8:11]
	v_mfma_f32_16x16x32_bf16 v[8:11], v[212:215], v[224:227], v[164:167]
	v_mfma_f32_16x16x32_bf16 v[8:11], v[216:219], v[228:231], v[8:11]
	s_barrier
	s_and_b64 vcc, exec, s[8:9]
	s_cbranch_vccnz .LBB0_622
	s_barrier
; __device__ __forceinline__ unsigned cvt_pk_bf16(float lo, float hi) { const f32x2cv v = {lo, hi}; const bf16x2cv b = __builtin_convertvector(v, bf16x2cv); return __builtin_bit_cast(unsigned, b); }
;     __device__ __forceinline__ void operator()(const f32x4 (&acc)[2][2][4][2], const Unit& u, int wr, int wc, int fr, int fq) const {
;         asm volatile("" : "+v"(fr), "+v"(fq));
;         const int col0 = u.pn * BM + wc * 32 + 4 * fq;
; #pragma unroll
;         for (int ai = 0; ai < 2; ++ai)
; #pragma unroll
;             for (int m = 0; m < 4; ++m) { const int row = u.pm * BM + ai * HALF + wr * 64 + m * 16 + fr; const size_t off = (size_t)row * 1024 + col0;
; #pragma unroll
;                 for (int bj = 0; bj < 2; ++bj)
; #pragma unroll
;                     for (int n = 0; n < 2; ++n) { const f32x4 a = acc[ai][bj][m][n]; u32x2 w; w.x = cvt_pk_bf16(a[0], a[1]); w.y = cvt_pk_bf16(a[2], a[3]); *(u32x2*)(hb_ptr(off + bj * HALF + n * 16)) = w; } }
;     }
.LBB0_622:
	v_mov_b32_e32 v139, v133
	v_mov_b32_e32 v142, v132
	s_lshl_b32 s28, s28, 8
	s_lshl_b32 s29, s63, 8
	s_add_i32 s28, s28, s70
	s_or_b32 s29, s29, s82
	v_add_u32_e32 v142, s28, v142
	v_lshl_add_u32 v140, v139, 2, s29
	v_ashrrev_i32_e32 v143, 31, v142
	v_ashrrev_i32_e32 v141, 31, v140
	v_lshlrev_b64 v[144:145], 11, v[142:143]
	v_cvt_pk_bf16_f32 v116, v116, v117
	v_cvt_pk_bf16_f32 v117, v118, v119
	v_lshl_add_u64 v[118:119], s[18:19], 0, v[144:145]
	v_lshlrev_b64 v[140:141], 1, v[140:141]
	v_lshl_add_u64 v[118:119], v[118:119], 0, v[140:141]
	v_cvt_pk_bf16_f32 v112, v112, v113
	v_cvt_pk_bf16_f32 v113, v114, v115
	global_store_dwordx2 v[118:119], v[112:113], off offset:32
	v_cvt_pk_bf16_f32 v112, v124, v125
	v_cvt_pk_bf16_f32 v113, v126, v127
	global_store_dwordx2 v[118:119], v[112:113], off offset:256
	v_cvt_pk_bf16_f32 v112, v120, v121
	v_cvt_pk_bf16_f32 v113, v122, v123
	global_store_dwordx2 v[118:119], v[112:113], off offset:288
	v_add_u32_e32 v112, 16, v142
	v_ashrrev_i32_e32 v113, 31, v112
	v_lshlrev_b64 v[112:113], 11, v[112:113]
	v_cvt_pk_bf16_f32 v100, v100, v101
	v_cvt_pk_bf16_f32 v101, v102, v103
	v_lshl_add_u64 v[102:103], s[18:19], 0, v[112:113]
	v_lshl_add_u64 v[102:103], v[102:103], 0, v[140:141]
	v_cvt_pk_bf16_f32 v96, v96, v97
	v_cvt_pk_bf16_f32 v97, v98, v99
	global_store_dwordx2 v[102:103], v[96:97], off offset:32
	v_cvt_pk_bf16_f32 v96, v108, v109
	v_cvt_pk_bf16_f32 v97, v110, v111
	global_store_dwordx2 v[102:103], v[96:97], off offset:256
	v_cvt_pk_bf16_f32 v96, v104, v105
	v_cvt_pk_bf16_f32 v97, v106, v107
	global_store_dwordx2 v[102:103], v[96:97], off offset:288
	v_add_u32_e32 v96, 32, v142
	v_ashrrev_i32_e32 v97, 31, v96
	v_lshlrev_b64 v[96:97], 11, v[96:97]
	v_cvt_pk_bf16_f32 v68, v68, v69
	v_cvt_pk_bf16_f32 v69, v70, v71
	v_lshl_add_u64 v[70:71], s[18:19], 0, v[96:97]
	v_lshl_add_u64 v[70:71], v[70:71], 0, v[140:141]
	v_cvt_pk_bf16_f32 v64, v64, v65
	v_cvt_pk_bf16_f32 v65, v66, v67
	global_store_dwordx2 v[70:71], v[64:65], off offset:32
	v_cvt_pk_bf16_f32 v64, v80, v81
	v_cvt_pk_bf16_f32 v65, v82, v83
	global_store_dwordx2 v[70:71], v[64:65], off offset:256
	v_cvt_pk_bf16_f32 v64, v72, v73
	v_cvt_pk_bf16_f32 v65, v74, v75
	global_store_dwordx2 v[70:71], v[64:65], off offset:288
	v_add_u32_e32 v64, 48, v142
	v_ashrrev_i32_e32 v65, 31, v64
	v_lshlrev_b64 v[64:65], 11, v[64:65]
	v_cvt_pk_bf16_f32 v36, v36, v37
	v_cvt_pk_bf16_f32 v37, v38, v39
	v_lshl_add_u64 v[38:39], s[18:19], 0, v[64:65]
	v_lshl_add_u64 v[38:39], v[38:39], 0, v[140:141]
	v_cvt_pk_bf16_f32 v32, v32, v33
	v_cvt_pk_bf16_f32 v33, v34, v35
	global_store_dwordx2 v[38:39], v[32:33], off offset:32
	v_cvt_pk_bf16_f32 v32, v48, v49
	v_cvt_pk_bf16_f32 v33, v50, v51
	global_store_dwordx2 v[38:39], v[32:33], off offset:256
	v_cvt_pk_bf16_f32 v32, v40, v41
	v_cvt_pk_bf16_f32 v33, v42, v43
	global_store_dwordx2 v[38:39], v[32:33], off offset:288
	v_add_u32_e32 v32, 0x80, v142
	v_ashrrev_i32_e32 v33, 31, v32
	v_lshlrev_b64 v[32:33], 11, v[32:33]
	v_lshl_add_u64 v[32:33], s[18:19], 0, v[32:33]
	v_cvt_pk_bf16_f32 v34, v84, v85
	v_cvt_pk_bf16_f32 v35, v86, v87
	v_lshl_add_u64 v[32:33], v[32:33], 0, v[140:141]
	global_store_dwordx2 v[32:33], v[34:35], off
	v_cvt_pk_bf16_f32 v34, v76, v77
	v_cvt_pk_bf16_f32 v35, v78, v79
	global_store_dwordx2 v[32:33], v[34:35], off offset:32
	v_cvt_pk_bf16_f32 v34, v92, v93
	v_cvt_pk_bf16_f32 v35, v94, v95
	global_store_dwordx2 v[32:33], v[34:35], off offset:256
	v_cvt_pk_bf16_f32 v34, v88, v89
	v_cvt_pk_bf16_f32 v35, v90, v91
	global_store_dwordx2 v[32:33], v[34:35], off offset:288
	v_add_u32_e32 v32, 0x90, v142
	v_ashrrev_i32_e32 v33, 31, v32
	v_lshlrev_b64 v[32:33], 11, v[32:33]
	v_lshl_add_u64 v[32:33], s[18:19], 0, v[32:33]
	v_cvt_pk_bf16_f32 v34, v52, v53
	v_cvt_pk_bf16_f32 v35, v54, v55
	v_lshl_add_u64 v[32:33], v[32:33], 0, v[140:141]
	global_store_dwordx2 v[32:33], v[34:35], off
	v_cvt_pk_bf16_f32 v34, v44, v45
	v_cvt_pk_bf16_f32 v35, v46, v47
	global_store_dwordx2 v[32:33], v[34:35], off offset:32
	v_cvt_pk_bf16_f32 v34, v60, v61
	v_cvt_pk_bf16_f32 v35, v62, v63
	global_store_dwordx2 v[32:33], v[34:35], off offset:256
	v_cvt_pk_bf16_f32 v34, v56, v57
	v_cvt_pk_bf16_f32 v35, v58, v59
	global_store_dwordx2 v[32:33], v[34:35], off offset:288
	v_add_u32_e32 v32, 0xa0, v142
	v_ashrrev_i32_e32 v33, 31, v32
	v_lshlrev_b64 v[32:33], 11, v[32:33]
	v_cvt_pk_bf16_f32 v20, v20, v21
	v_cvt_pk_bf16_f32 v21, v22, v23
	v_lshl_add_u64 v[22:23], s[18:19], 0, v[32:33]
	v_lshl_add_u64 v[22:23], v[22:23], 0, v[140:141]
	v_cvt_pk_bf16_f32 v16, v16, v17
	v_cvt_pk_bf16_f32 v17, v18, v19
	global_store_dwordx2 v[22:23], v[16:17], off offset:32
	v_cvt_pk_bf16_f32 v16, v28, v29
	v_cvt_pk_bf16_f32 v17, v30, v31
	global_store_dwordx2 v[22:23], v[16:17], off offset:256
	v_cvt_pk_bf16_f32 v16, v24, v25
	v_cvt_pk_bf16_f32 v17, v26, v27
	global_store_dwordx2 v[22:23], v[16:17], off offset:288
	v_add_u32_e32 v16, 0xb0, v142
	v_ashrrev_i32_e32 v17, 31, v16
	v_lshlrev_b64 v[16:17], 11, v[16:17]
	v_cvt_pk_bf16_f32 v4, v4, v5
	v_cvt_pk_bf16_f32 v5, v6, v7
	v_lshl_add_u64 v[6:7], s[18:19], 0, v[16:17]
	v_lshl_add_u64 v[6:7], v[6:7], 0, v[140:141]
	v_cvt_pk_bf16_f32 v0, v0, v1
	v_cvt_pk_bf16_f32 v1, v2, v3
	global_store_dwordx2 v[6:7], v[0:1], off offset:32
	v_cvt_pk_bf16_f32 v0, v12, v13
	v_cvt_pk_bf16_f32 v1, v14, v15
	global_store_dwordx2 v[6:7], v[0:1], off offset:256
	v_cvt_pk_bf16_f32 v0, v8, v9
	v_cvt_pk_bf16_f32 v1, v10, v11
	s_andn2_b64 vcc, exec, s[26:27]
	s_mov_b64 s[28:29], -1
	global_store_dwordx2 v[118:119], v[116:117], off
	global_store_dwordx2 v[102:103], v[100:101], off
	global_store_dwordx2 v[70:71], v[68:69], off
	global_store_dwordx2 v[38:39], v[36:37], off
	global_store_dwordx2 v[22:23], v[20:21], off
	global_store_dwordx2 v[6:7], v[4:5], off
	global_store_dwordx2 v[6:7], v[0:1], off offset:288
	s_cbranch_vccnz .LBB0_619
	s_setprio 0
	s_and_b64 vcc, exec, s[6:7]
	s_cbranch_vccnz .LBB0_618
	s_barrier
	s_branch .LBB0_618

; #define PG8_STAGE(bufoff, gbase, voff) do { _Pragma("unroll") for (int _i = 0; _i < 2; ++_i) \
;         __builtin_amdgcn_global_load_lds((const unsigned*)((const char*)(gbase) + (voff)[_i]), (PG8_LAS unsigned*)(lds + (bufoff) + ldsw + _i * 8192), 16, 0, 0); } while (0)
; #define PG8_LDA(dst, b, h) do { _Pragma("unroll") for (int m = 0; m < 4; ++m) _Pragma("unroll") for (int k = 0; k < 2; ++k) dst[m][k] = *(const PG8_LAS bf16x8*)(lds + PG8_SA(b, h) + aoff + m * 2048 + k * 1024); } while (0)
; #define PG8_LDB(dst, b, h) do { _Pragma("unroll") for (int n = 0; n < 2; ++n) _Pragma("unroll") for (int k = 0; k < 2; ++k) dst[n][k] = *(const PG8_LAS bf16x8*)(lds + PG8_SB(b, h) + boff + n * 2048 + k * 1024); } while (0)
; #define PG8_MMA(ai, bj, At, Bt) do { __builtin_amdgcn_s_setprio(1); _Pragma("unroll") for (int m = 0; m < 4; ++m) _Pragma("unroll") for (int n = 0; n < 2; ++n) _Pragma("unroll") for (int k = 0; k < 2; ++k) \
;         acc[ai][bj][m][n] = mma16<F16>(Bt[n][k], At[m][k], acc[ai][bj][m][n]); __builtin_amdgcn_s_setprio(0); } while (0)
; #define PG8_WAIT_V(n) asm volatile("s_waitcnt vmcnt(" #n ")" ::: "memory")
; #define PG8_WAIT_L(n) asm volatile("s_waitcnt lgkmcnt(" #n ")" ::: "memory")
; #define PG8_BAR __builtin_amdgcn_s_barrier()
; #define PG8_SCHED __builtin_amdgcn_sched_barrier(0)
; template <class Epi, class Sched, bool ALIGN_EPI = false, bool SP2 = false, bool F16 = false>
; __device__ __forceinline__ void gemm_phase(PG8_LAS unsigned char* lds, const Gemm g, const Sched& S, const Epi& E, const int wid_in) {
;     ...
;             PG8_LDB(B0, 0, 0); PG8_LDB(B1, 0, 1); PG8_SCHED; PG8_LDA(At, 0, 0); PG8_STAGE(PG8_SA(1, 1), a1 + hstep, voffA);
;             PG8_WAIT_V(8); PG8_WAIT_L(0); PG8_BAR; PG8_MMA(0, 0, At, B0); PG8_MMA(0, 1, At, B1); PG8_BAR; PG8_SCHED;
;     ...
;         for (int a = 0; a < 2; ++a)
; #pragma unroll
;             for (int b = 0; b < 2; ++b)
; #pragma unroll
;                 for (int m = 0; m < 4; ++m)
; #pragma unroll
;                     for (int n = 0; n < 2; ++n) acc[a][b][m][n] = (f32x4){0.f, 0.f, 0.f, 0.f};
.LBB0_715:
	s_add_u32 s43, s30, 0x100
	v_mov_b32_e32 v0, 0
	s_addc_u32 s59, s31, 0
	s_mov_b32 s60, -2
	v_mov_b32_e32 v1, v0
	v_mov_b32_e32 v2, v0
	v_mov_b32_e32 v3, v0
	v_mov_b32_e32 v4, v0
	v_mov_b32_e32 v5, v0
	v_mov_b32_e32 v6, v0
	v_mov_b32_e32 v7, v0
	v_mov_b32_e32 v16, v0
	v_mov_b32_e32 v17, v0
	v_mov_b32_e32 v18, v0
	v_mov_b32_e32 v19, v0
	v_mov_b32_e32 v20, v0
	v_mov_b32_e32 v21, v0
	v_mov_b32_e32 v22, v0
	v_mov_b32_e32 v23, v0
	v_mov_b32_e32 v32, v0
	v_mov_b32_e32 v33, v0
	v_mov_b32_e32 v34, v0
	v_mov_b32_e32 v35, v0
	v_mov_b32_e32 v36, v0
	v_mov_b32_e32 v37, v0
	v_mov_b32_e32 v38, v0
	v_mov_b32_e32 v39, v0
	v_mov_b32_e32 v48, v0
	v_mov_b32_e32 v49, v0
	v_mov_b32_e32 v50, v0
	v_mov_b32_e32 v51, v0
	v_mov_b32_e32 v52, v0
	v_mov_b32_e32 v53, v0
	v_mov_b32_e32 v54, v0
	v_mov_b32_e32 v55, v0
	v_mov_b32_e32 v8, v0
	v_mov_b32_e32 v9, v0
	v_mov_b32_e32 v10, v0
	v_mov_b32_e32 v11, v0
	v_mov_b32_e32 v12, v0
	v_mov_b32_e32 v13, v0
	v_mov_b32_e32 v14, v0
	v_mov_b32_e32 v15, v0
	v_mov_b32_e32 v24, v0
	v_mov_b32_e32 v25, v0
	v_mov_b32_e32 v26, v0
	v_mov_b32_e32 v27, v0
	v_mov_b32_e32 v28, v0
	v_mov_b32_e32 v29, v0
	v_mov_b32_e32 v30, v0
	v_mov_b32_e32 v31, v0
	v_mov_b32_e32 v40, v0
	v_mov_b32_e32 v41, v0
	v_mov_b32_e32 v42, v0
	v_mov_b32_e32 v43, v0
	v_mov_b32_e32 v44, v0
	v_mov_b32_e32 v45, v0
	v_mov_b32_e32 v46, v0
	v_mov_b32_e32 v47, v0
	v_mov_b32_e32 v56, v0
	v_mov_b32_e32 v57, v0
	v_mov_b32_e32 v58, v0
	v_mov_b32_e32 v59, v0
	v_mov_b32_e32 v60, v0
	v_mov_b32_e32 v61, v0
	v_mov_b32_e32 v62, v0
	v_mov_b32_e32 v63, v0
	v_mov_b32_e32 v64, v0
	v_mov_b32_e32 v65, v0
	v_mov_b32_e32 v66, v0
	v_mov_b32_e32 v67, v0
	v_mov_b32_e32 v68, v0
	v_mov_b32_e32 v69, v0
	v_mov_b32_e32 v70, v0
	v_mov_b32_e32 v71, v0
	v_mov_b32_e32 v80, v0
	v_mov_b32_e32 v81, v0
	v_mov_b32_e32 v82, v0
	v_mov_b32_e32 v83, v0
	v_mov_b32_e32 v84, v0
	v_mov_b32_e32 v85, v0
	v_mov_b32_e32 v86, v0
	v_mov_b32_e32 v87, v0
	v_mov_b32_e32 v96, v0
	v_mov_b32_e32 v97, v0
	v_mov_b32_e32 v98, v0
	v_mov_b32_e32 v99, v0
	v_mov_b32_e32 v100, v0
	v_mov_b32_e32 v101, v0
	v_mov_b32_e32 v102, v0
	v_mov_b32_e32 v103, v0
	v_mov_b32_e32 v112, v0
	v_mov_b32_e32 v113, v0
	v_mov_b32_e32 v114, v0
	v_mov_b32_e32 v115, v0
	v_mov_b32_e32 v116, v0
	v_mov_b32_e32 v117, v0
	v_mov_b32_e32 v118, v0
	v_mov_b32_e32 v119, v0
	v_mov_b32_e32 v72, v0
	v_mov_b32_e32 v73, v0
	v_mov_b32_e32 v74, v0
	v_mov_b32_e32 v75, v0
	v_mov_b32_e32 v76, v0
	v_mov_b32_e32 v77, v0
	v_mov_b32_e32 v78, v0
	v_mov_b32_e32 v79, v0
	v_mov_b32_e32 v88, v0
	v_mov_b32_e32 v89, v0
	v_mov_b32_e32 v90, v0
	v_mov_b32_e32 v91, v0
	v_mov_b32_e32 v92, v0
	v_mov_b32_e32 v93, v0
	v_mov_b32_e32 v94, v0
	v_mov_b32_e32 v95, v0
	v_mov_b32_e32 v104, v0
	v_mov_b32_e32 v105, v0
	v_mov_b32_e32 v106, v0
	v_mov_b32_e32 v107, v0
	v_mov_b32_e32 v108, v0
	v_mov_b32_e32 v109, v0
	v_mov_b32_e32 v110, v0
	v_mov_b32_e32 v111, v0
	v_mov_b32_e32 v120, v0
	v_mov_b32_e32 v121, v0
	v_mov_b32_e32 v122, v0
	v_mov_b32_e32 v123, v0
	v_mov_b32_e32 v124, v0
	v_mov_b32_e32 v125, v0
	v_mov_b32_e32 v126, v0
	v_mov_b32_e32 v127, v0
	s_cmp_ge_u32 s3, 4
	s_cbranch_scc0 .Lgsp_4
	s_setprio 1
.Lgsp_4:
.LBB0_716:
	ds_read_b128 v[128:131], v189
	ds_read_b128 v[132:135], v189 offset:1024
	ds_read_b128 v[136:139], v189 offset:2048
	ds_read_b128 v[140:143], v189 offset:3072
	ds_read_b128 v[144:147], v190
	ds_read_b128 v[148:151], v190 offset:1024
	ds_read_b128 v[168:171], v190 offset:2048
	ds_read_b128 v[172:175], v190 offset:3072
	s_add_u32 s30, s28, 0x100
	s_addc_u32 s31, s29, 0
	s_cmp_eq_u32 s60, 40
	s_cselect_b32 s37, s11, s31
	s_cselect_b32 s36, s10, s30
	s_cselect_b32 s35, s27, s59
	s_cselect_b32 s34, s26, s43
	v_lshl_add_u64 v[184:185], s[28:29], 0, v[160:161]
	s_add_i32 m0, s74, 0xc000
	ds_read_b128 v[176:179], v191
	ds_read_b128 v[180:183], v191 offset:1024
	ds_read_b128 v[192:195], v191 offset:2048
	ds_read_b128 v[196:199], v191 offset:3072
	ds_read_b128 v[200:203], v191 offset:4096
	ds_read_b128 v[204:207], v191 offset:5120
	ds_read_b128 v[208:211], v191 offset:6144
	ds_read_b128 v[212:215], v191 offset:7168
	global_load_lds_dwordx4 v[184:185], off
	v_lshl_add_u64 v[184:185], s[28:29], 0, v[162:163]
	s_add_i32 m0, s74, 0xe000
	s_nop 0
	global_load_lds_dwordx4 v[184:185], off
	s_waitcnt vmcnt(8)
	s_waitcnt lgkmcnt(0)
	s_barrier
	s_waitcnt lgkmcnt(0)
	v_mfma_f32_16x16x32_bf16 v[124:127], v[128:131], v[176:179], v[124:127]
	v_mfma_f32_16x16x32_bf16 v[120:123], v[136:139], v[176:179], v[120:123]
	v_mfma_f32_16x16x32_bf16 v[108:111], v[128:131], v[192:195], v[108:111]
	v_mfma_f32_16x16x32_bf16 v[104:107], v[136:139], v[192:195], v[104:107]
	v_mfma_f32_16x16x32_bf16 v[92:95], v[128:131], v[200:203], v[92:95]
	v_mfma_f32_16x16x32_bf16 v[88:91], v[136:139], v[200:203], v[88:91]
	v_mfma_f32_16x16x32_bf16 v[76:79], v[128:131], v[208:211], v[76:79]
	v_mfma_f32_16x16x32_bf16 v[72:75], v[136:139], v[208:211], v[72:75]
	v_mfma_f32_16x16x32_bf16 v[124:127], v[132:135], v[180:183], v[124:127]
	v_mfma_f32_16x16x32_bf16 v[120:123], v[140:143], v[180:183], v[120:123]
	v_mfma_f32_16x16x32_bf16 v[108:111], v[132:135], v[196:199], v[108:111]
	v_mfma_f32_16x16x32_bf16 v[104:107], v[140:143], v[196:199], v[104:107]
	v_mfma_f32_16x16x32_bf16 v[92:95], v[132:135], v[204:207], v[92:95]
	v_mfma_f32_16x16x32_bf16 v[88:91], v[140:143], v[204:207], v[88:91]
	v_mfma_f32_16x16x32_bf16 v[76:79], v[132:135], v[212:215], v[76:79]
	v_mfma_f32_16x16x32_bf16 v[72:75], v[140:143], v[212:215], v[72:75]
	v_mfma_f32_16x16x32_bf16 v[116:119], v[144:147], v[176:179], v[116:119]
	v_mfma_f32_16x16x32_bf16 v[112:115], v[168:171], v[176:179], v[112:115]
	v_mfma_f32_16x16x32_bf16 v[100:103], v[144:147], v[192:195], v[100:103]
	v_mfma_f32_16x16x32_bf16 v[96:99], v[168:171], v[192:195], v[96:99]
	v_mfma_f32_16x16x32_bf16 v[84:87], v[144:147], v[200:203], v[84:87]
	v_mfma_f32_16x16x32_bf16 v[80:83], v[168:171], v[200:203], v[80:83]
	v_mfma_f32_16x16x32_bf16 v[68:71], v[144:147], v[208:211], v[68:71]
	v_mfma_f32_16x16x32_bf16 v[64:67], v[168:171], v[208:211], v[64:67]
	v_mfma_f32_16x16x32_bf16 v[116:119], v[148:151], v[180:183], v[116:119]
	v_mfma_f32_16x16x32_bf16 v[112:115], v[172:175], v[180:183], v[112:115]
	v_mfma_f32_16x16x32_bf16 v[100:103], v[148:151], v[196:199], v[100:103]
	v_mfma_f32_16x16x32_bf16 v[96:99], v[172:175], v[196:199], v[96:99]
	v_mfma_f32_16x16x32_bf16 v[84:87], v[148:151], v[204:207], v[84:87]
	v_mfma_f32_16x16x32_bf16 v[80:83], v[172:175], v[204:207], v[80:83]
	v_mfma_f32_16x16x32_bf16 v[68:71], v[148:151], v[212:215], v[68:71]
	v_mfma_f32_16x16x32_bf16 v[64:67], v[172:175], v[212:215], v[64:67]
	s_barrier
; #define PG8_STAGE(bufoff, gbase, voff) do { _Pragma("unroll") for (int _i = 0; _i < 2; ++_i) \
;         __builtin_amdgcn_global_load_lds((const unsigned*)((const char*)(gbase) + (voff)[_i]), (PG8_LAS unsigned*)(lds + (bufoff) + ldsw + _i * 8192), 16, 0, 0); } while (0)
; #define PG8_LDA(dst, b, h) do { _Pragma("unroll") for (int m = 0; m < 4; ++m) _Pragma("unroll") for (int k = 0; k < 2; ++k) dst[m][k] = *(const PG8_LAS bf16x8*)(lds + PG8_SA(b, h) + aoff + m * 2048 + k * 1024); } while (0)
; #define PG8_LDB(dst, b, h) do { _Pragma("unroll") for (int n = 0; n < 2; ++n) _Pragma("unroll") for (int k = 0; k < 2; ++k) dst[n][k] = *(const PG8_LAS bf16x8*)(lds + PG8_SB(b, h) + boff + n * 2048 + k * 1024); } while (0)
; #define PG8_MMA(ai, bj, At, Bt) do { __builtin_amdgcn_s_setprio(1); _Pragma("unroll") for (int m = 0; m < 4; ++m) _Pragma("unroll") for (int n = 0; n < 2; ++n) _Pragma("unroll") for (int k = 0; k < 2; ++k) \
;         acc[ai][bj][m][n] = mma16<F16>(Bt[n][k], At[m][k], acc[ai][bj][m][n]); __builtin_amdgcn_s_setprio(0); } while (0)
; #define PG8_WAIT_V(n) asm volatile("s_waitcnt vmcnt(" #n ")" ::: "memory")
; #define PG8_WAIT_L(n) asm volatile("s_waitcnt lgkmcnt(" #n ")" ::: "memory")
; #define PG8_BAR __builtin_amdgcn_s_barrier()
; #define PG8_SCHED __builtin_amdgcn_sched_barrier(0)
; template <class Epi, class Sched, bool ALIGN_EPI = false, bool SP2 = false, bool F16 = false>
; __device__ __forceinline__ void gemm_phase(PG8_LAS unsigned char* lds, const Gemm g, const Sched& S, const Epi& E, const int wid_in) {
;     ...
;             PG8_LDA(At, 0, 1); PG8_STAGE(PG8_SB(0, 0), b2, voffB); PG8_STAGE(PG8_SB(0, 1), b2 + hstep, voffB); PG8_STAGE(PG8_SA(0, 0), a2, voffA);
;             PG8_WAIT_V(8); PG8_WAIT_L(0); PG8_BAR; PG8_MMA(1, 0, At, B0); PG8_MMA(1, 1, At, B1); PG8_BAR; PG8_SCHED;
;             PG8_LDB(B0, 1, 0); PG8_LDB(B1, 1, 1); PG8_SCHED; PG8_LDA(At, 1, 0); PG8_STAGE(PG8_SA(0, 1), a2 + hstep, voffA);
;             PG8_WAIT_V(8); PG8_WAIT_L(0); PG8_BAR; PG8_MMA(0, 0, At, B0); PG8_MMA(0, 1, At, B1); PG8_BAR; PG8_SCHED;
	s_add_i32 s28, s52, s68
	v_lshl_add_u64 v[184:185], s[34:35], 0, v[154:155]
	s_mov_b32 m0, s28
	ds_read_b128 v[176:179], v191 offset:16384
	ds_read_b128 v[180:183], v191 offset:17408
	ds_read_b128 v[192:195], v191 offset:18432
	ds_read_b128 v[196:199], v191 offset:19456
	ds_read_b128 v[200:203], v191 offset:20480
	ds_read_b128 v[204:207], v191 offset:21504
	ds_read_b128 v[208:211], v191 offset:22528
	ds_read_b128 v[212:215], v191 offset:23552
	global_load_lds_dwordx4 v[184:185], off
	s_add_i32 m0, s28, 0x2000
	s_add_u32 s28, s34, 0xb0000
	v_lshl_add_u64 v[216:217], s[34:35], 0, v[158:159]
	s_addc_u32 s29, s35, 0
	s_add_i32 s61, s53, s68
	global_load_lds_dwordx4 v[216:217], off
	v_lshl_add_u64 v[218:219], s[28:29], 0, v[154:155]
	s_mov_b32 m0, s61
	v_lshl_add_u64 v[220:221], s[36:37], 0, v[156:157]
	global_load_lds_dwordx4 v[218:219], off
	v_lshl_add_u64 v[218:219], s[28:29], 0, v[158:159]
	s_add_i32 m0, s61, 0x2000
	s_nop 0
	global_load_lds_dwordx4 v[218:219], off
	v_lshl_add_u64 v[218:219], s[36:37], 0, v[152:153]
	s_mov_b32 m0, s74
	s_nop 0
	global_load_lds_dwordx4 v[218:219], off
	s_mov_b32 m0, s45
	s_nop 0
	global_load_lds_dwordx4 v[220:221], off
	s_waitcnt vmcnt(8)
	s_waitcnt lgkmcnt(0)
	s_barrier
	s_waitcnt lgkmcnt(0)
	v_mfma_f32_16x16x32_bf16 v[60:63], v[128:131], v[176:179], v[60:63]
	v_mfma_f32_16x16x32_bf16 v[56:59], v[136:139], v[176:179], v[56:59]
	v_mfma_f32_16x16x32_bf16 v[44:47], v[128:131], v[192:195], v[44:47]
	v_mfma_f32_16x16x32_bf16 v[40:43], v[136:139], v[192:195], v[40:43]
	v_mfma_f32_16x16x32_bf16 v[28:31], v[128:131], v[200:203], v[28:31]
	v_mfma_f32_16x16x32_bf16 v[24:27], v[136:139], v[200:203], v[24:27]
	v_mfma_f32_16x16x32_bf16 v[12:15], v[128:131], v[208:211], v[12:15]
	v_mfma_f32_16x16x32_bf16 v[8:11], v[136:139], v[208:211], v[8:11]
	v_mfma_f32_16x16x32_bf16 v[60:63], v[132:135], v[180:183], v[60:63]
	v_mfma_f32_16x16x32_bf16 v[56:59], v[140:143], v[180:183], v[56:59]
	v_mfma_f32_16x16x32_bf16 v[44:47], v[132:135], v[196:199], v[44:47]
	v_mfma_f32_16x16x32_bf16 v[40:43], v[140:143], v[196:199], v[40:43]
	v_mfma_f32_16x16x32_bf16 v[28:31], v[132:135], v[204:207], v[28:31]
	v_mfma_f32_16x16x32_bf16 v[24:27], v[140:143], v[204:207], v[24:27]
	v_mfma_f32_16x16x32_bf16 v[12:15], v[132:135], v[212:215], v[12:15]
	v_mfma_f32_16x16x32_bf16 v[8:11], v[140:143], v[212:215], v[8:11]
	v_mfma_f32_16x16x32_bf16 v[52:55], v[144:147], v[176:179], v[52:55]
	v_mfma_f32_16x16x32_bf16 v[48:51], v[168:171], v[176:179], v[48:51]
	v_mfma_f32_16x16x32_bf16 v[36:39], v[144:147], v[192:195], v[36:39]
	v_mfma_f32_16x16x32_bf16 v[32:35], v[168:171], v[192:195], v[32:35]
	v_mfma_f32_16x16x32_bf16 v[20:23], v[144:147], v[200:203], v[20:23]
	v_mfma_f32_16x16x32_bf16 v[16:19], v[168:171], v[200:203], v[16:19]
	v_mfma_f32_16x16x32_bf16 v[4:7], v[144:147], v[208:211], v[4:7]
	v_mfma_f32_16x16x32_bf16 v[0:3], v[168:171], v[208:211], v[0:3]
	v_mfma_f32_16x16x32_bf16 v[52:55], v[148:151], v[180:183], v[52:55]
	v_mfma_f32_16x16x32_bf16 v[48:51], v[172:175], v[180:183], v[48:51]
	v_mfma_f32_16x16x32_bf16 v[36:39], v[148:151], v[196:199], v[36:39]
	v_mfma_f32_16x16x32_bf16 v[32:35], v[172:175], v[196:199], v[32:35]
	v_mfma_f32_16x16x32_bf16 v[20:23], v[148:151], v[204:207], v[20:23]
	v_mfma_f32_16x16x32_bf16 v[16:19], v[172:175], v[204:207], v[16:19]
	v_mfma_f32_16x16x32_bf16 v[4:7], v[148:151], v[212:215], v[4:7]
	v_mfma_f32_16x16x32_bf16 v[0:3], v[172:175], v[212:215], v[0:3]
	s_barrier
	s_add_i32 s61, 0, 0x18000
	s_add_i32 s62, 0, 0x1c000
	v_add_u32_e32 v140, s61, v188
	v_add_u32_e32 v172, s62, v188
	ds_read_b128 v[128:131], v140
	ds_read_b128 v[132:135], v140 offset:1024
	ds_read_b128 v[136:139], v140 offset:2048
	ds_read_b128 v[140:143], v140 offset:3072
	ds_read_b128 v[144:147], v172
	ds_read_b128 v[148:151], v172 offset:1024
	ds_read_b128 v[168:171], v172 offset:2048
	ds_read_b128 v[172:175], v172 offset:3072
	s_add_u32 s28, s36, 0xb0000
	s_addc_u32 s29, s37, 0
	s_mov_b32 m0, s46
	v_lshl_add_u64 v[222:223], s[28:29], 0, v[152:153]
	ds_read_b128 v[176:179], v191 offset:32768
	ds_read_b128 v[180:183], v191 offset:33792
	ds_read_b128 v[192:195], v191 offset:34816
	ds_read_b128 v[196:199], v191 offset:35840
	ds_read_b128 v[200:203], v191 offset:36864
	ds_read_b128 v[204:207], v191 offset:37888
	ds_read_b128 v[208:211], v191 offset:38912
	ds_read_b128 v[212:215], v191 offset:39936
	global_load_lds_dwordx4 v[222:223], off
	v_lshl_add_u64 v[222:223], s[28:29], 0, v[156:157]
	s_mov_b32 m0, s47
	s_nop 0
	global_load_lds_dwordx4 v[222:223], off
	s_waitcnt vmcnt(8)
	s_waitcnt lgkmcnt(0)
	s_barrier
; #define PG8_STAGE(bufoff, gbase, voff) do { _Pragma("unroll") for (int _i = 0; _i < 2; ++_i) \
;         __builtin_amdgcn_global_load_lds((const unsigned*)((const char*)(gbase) + (voff)[_i]), (PG8_LAS unsigned*)(lds + (bufoff) + ldsw + _i * 8192), 16, 0, 0); } while (0)
; #define PG8_LDA(dst, b, h) do { _Pragma("unroll") for (int m = 0; m < 4; ++m) _Pragma("unroll") for (int k = 0; k < 2; ++k) dst[m][k] = *(const PG8_LAS bf16x8*)(lds + PG8_SA(b, h) + aoff + m * 2048 + k * 1024); } while (0)
; #define PG8_MMA(ai, bj, At, Bt) do { __builtin_amdgcn_s_setprio(1); _Pragma("unroll") for (int m = 0; m < 4; ++m) _Pragma("unroll") for (int n = 0; n < 2; ++n) _Pragma("unroll") for (int k = 0; k < 2; ++k) \
;         acc[ai][bj][m][n] = mma16<F16>(Bt[n][k], At[m][k], acc[ai][bj][m][n]); __builtin_amdgcn_s_setprio(0); } while (0)
; #define PG8_WAIT_V(n) asm volatile("s_waitcnt vmcnt(" #n ")" ::: "memory")
; #define PG8_WAIT_L(n) asm volatile("s_waitcnt lgkmcnt(" #n ")" ::: "memory")
; #define PG8_BAR __builtin_amdgcn_s_barrier()
; #define PG8_SCHED __builtin_amdgcn_sched_barrier(0)
; template <class Epi, class Sched, bool ALIGN_EPI = false, bool SP2 = false, bool F16 = false>
; __device__ __forceinline__ void gemm_phase(PG8_LAS unsigned char* lds, const Gemm g, const Sched& S, const Epi& E, const int wid_in) {
;     ...
;         for (int t = 0; t < nt; t += 2) {
;             const bool last = (t == nt - 2);
;             const char* a1 = cA + (size_t)(t + 1) * kstep;
;             const char* a2 = last ? nA : cA + (size_t)(t + 2) * kstep; const char* b2 = last ? nB : cB + (size_t)(t + 2) * kstep;
;     ...
;             PG8_WAIT_V(8); PG8_WAIT_L(0); PG8_BAR; PG8_MMA(0, 0, At, B0); PG8_MMA(0, 1, At, B1); PG8_BAR; PG8_SCHED;
;             PG8_LDA(At, 1, 1); PG8_STAGE(PG8_SB(1, 0), b3, voffB); PG8_STAGE(PG8_SB(1, 1), b3 + hstep, voffB); PG8_STAGE(PG8_SA(1, 0), a3, voffA);
;             PG8_WAIT_V(8); PG8_WAIT_L(0); PG8_BAR; PG8_MMA(1, 0, At, B0); PG8_MMA(1, 1, At, B1); PG8_BAR; PG8_SCHED;
	s_waitcnt lgkmcnt(0)
	v_mfma_f32_16x16x32_bf16 v[124:127], v[128:131], v[176:179], v[124:127]
	v_mfma_f32_16x16x32_bf16 v[120:123], v[136:139], v[176:179], v[120:123]
	v_mfma_f32_16x16x32_bf16 v[108:111], v[128:131], v[192:195], v[108:111]
	v_mfma_f32_16x16x32_bf16 v[104:107], v[136:139], v[192:195], v[104:107]
	v_mfma_f32_16x16x32_bf16 v[92:95], v[128:131], v[200:203], v[92:95]
	v_mfma_f32_16x16x32_bf16 v[88:91], v[136:139], v[200:203], v[88:91]
	v_mfma_f32_16x16x32_bf16 v[76:79], v[128:131], v[208:211], v[76:79]
	v_mfma_f32_16x16x32_bf16 v[72:75], v[136:139], v[208:211], v[72:75]
	v_mfma_f32_16x16x32_bf16 v[124:127], v[132:135], v[180:183], v[124:127]
	v_mfma_f32_16x16x32_bf16 v[120:123], v[140:143], v[180:183], v[120:123]
	v_mfma_f32_16x16x32_bf16 v[108:111], v[132:135], v[196:199], v[108:111]
	v_mfma_f32_16x16x32_bf16 v[104:107], v[140:143], v[196:199], v[104:107]
	v_mfma_f32_16x16x32_bf16 v[92:95], v[132:135], v[204:207], v[92:95]
	v_mfma_f32_16x16x32_bf16 v[88:91], v[140:143], v[204:207], v[88:91]
	v_mfma_f32_16x16x32_bf16 v[76:79], v[132:135], v[212:215], v[76:79]
	v_mfma_f32_16x16x32_bf16 v[72:75], v[140:143], v[212:215], v[72:75]
	v_mfma_f32_16x16x32_bf16 v[116:119], v[144:147], v[176:179], v[116:119]
	v_mfma_f32_16x16x32_bf16 v[112:115], v[168:171], v[176:179], v[112:115]
	v_mfma_f32_16x16x32_bf16 v[100:103], v[144:147], v[192:195], v[100:103]
	v_mfma_f32_16x16x32_bf16 v[96:99], v[168:171], v[192:195], v[96:99]
	v_mfma_f32_16x16x32_bf16 v[84:87], v[144:147], v[200:203], v[84:87]
	v_mfma_f32_16x16x32_bf16 v[80:83], v[168:171], v[200:203], v[80:83]
	v_mfma_f32_16x16x32_bf16 v[68:71], v[144:147], v[208:211], v[68:71]
	v_mfma_f32_16x16x32_bf16 v[64:67], v[168:171], v[208:211], v[64:67]
	v_mfma_f32_16x16x32_bf16 v[116:119], v[148:151], v[180:183], v[116:119]
	v_mfma_f32_16x16x32_bf16 v[112:115], v[172:175], v[180:183], v[112:115]
	v_mfma_f32_16x16x32_bf16 v[100:103], v[148:151], v[196:199], v[100:103]
	v_mfma_f32_16x16x32_bf16 v[96:99], v[172:175], v[196:199], v[96:99]
	v_mfma_f32_16x16x32_bf16 v[84:87], v[148:151], v[204:207], v[84:87]
	v_mfma_f32_16x16x32_bf16 v[80:83], v[172:175], v[204:207], v[80:83]
	v_mfma_f32_16x16x32_bf16 v[68:71], v[148:151], v[212:215], v[68:71]
	v_mfma_f32_16x16x32_bf16 v[64:67], v[172:175], v[212:215], v[64:67]
	s_barrier
	s_add_i32 s28, s61, s68
	v_lshl_add_u64 v[184:185], v[184:185], 0, s[24:25]
	s_mov_b32 m0, s28
	ds_read_b128 v[176:179], v191 offset:49152
	ds_read_b128 v[180:183], v191 offset:50176
	ds_read_b128 v[192:195], v191 offset:51200
	ds_read_b128 v[196:199], v191 offset:52224
	ds_read_b128 v[200:203], v191 offset:53248
	ds_read_b128 v[204:207], v191 offset:54272
	ds_read_b128 v[208:211], v191 offset:55296
	ds_read_b128 v[212:215], v191 offset:56320
	global_load_lds_dwordx4 v[184:185], off
	s_add_i32 m0, s28, 0x2000
	s_add_u32 s28, s34, 0xb0080
	v_lshl_add_u64 v[184:185], v[216:217], 0, s[24:25]
	s_addc_u32 s29, s35, 0
	s_add_i32 s34, s62, s68
	global_load_lds_dwordx4 v[184:185], off
	v_lshl_add_u64 v[184:185], s[28:29], 0, v[154:155]
	s_mov_b32 m0, s34
	s_nop 0
	global_load_lds_dwordx4 v[184:185], off
	v_lshl_add_u64 v[184:185], s[28:29], 0, v[158:159]
	s_add_i32 m0, s34, 0x2000
	s_nop 0
	global_load_lds_dwordx4 v[184:185], off
	v_lshl_add_u64 v[184:185], v[218:219], 0, s[24:25]
	s_mov_b32 m0, s75
	s_nop 0
	global_load_lds_dwordx4 v[184:185], off
	v_lshl_add_u64 v[184:185], v[220:221], 0, s[24:25]
	s_mov_b32 m0, s48
	s_nop 0
	global_load_lds_dwordx4 v[184:185], off
	s_waitcnt vmcnt(8)
	s_waitcnt lgkmcnt(0)
	s_barrier
	s_waitcnt lgkmcnt(0)
	v_mfma_f32_16x16x32_bf16 v[60:63], v[128:131], v[176:179], v[60:63]
	v_mfma_f32_16x16x32_bf16 v[56:59], v[136:139], v[176:179], v[56:59]
	v_mfma_f32_16x16x32_bf16 v[44:47], v[128:131], v[192:195], v[44:47]
	v_mfma_f32_16x16x32_bf16 v[40:43], v[136:139], v[192:195], v[40:43]
	v_mfma_f32_16x16x32_bf16 v[28:31], v[128:131], v[200:203], v[28:31]
	v_mfma_f32_16x16x32_bf16 v[24:27], v[136:139], v[200:203], v[24:27]
	v_mfma_f32_16x16x32_bf16 v[12:15], v[128:131], v[208:211], v[12:15]
	v_mfma_f32_16x16x32_bf16 v[8:11], v[136:139], v[208:211], v[8:11]
	v_mfma_f32_16x16x32_bf16 v[60:63], v[132:135], v[180:183], v[60:63]
	v_mfma_f32_16x16x32_bf16 v[56:59], v[140:143], v[180:183], v[56:59]
	v_mfma_f32_16x16x32_bf16 v[44:47], v[132:135], v[196:199], v[44:47]
	v_mfma_f32_16x16x32_bf16 v[40:43], v[140:143], v[196:199], v[40:43]
	v_mfma_f32_16x16x32_bf16 v[28:31], v[132:135], v[204:207], v[28:31]
	v_mfma_f32_16x16x32_bf16 v[24:27], v[140:143], v[204:207], v[24:27]
	v_mfma_f32_16x16x32_bf16 v[12:15], v[132:135], v[212:215], v[12:15]
	v_mfma_f32_16x16x32_bf16 v[8:11], v[140:143], v[212:215], v[8:11]
	v_mfma_f32_16x16x32_bf16 v[52:55], v[144:147], v[176:179], v[52:55]
	v_mfma_f32_16x16x32_bf16 v[48:51], v[168:171], v[176:179], v[48:51]
	v_mfma_f32_16x16x32_bf16 v[36:39], v[144:147], v[192:195], v[36:39]
	v_mfma_f32_16x16x32_bf16 v[32:35], v[168:171], v[192:195], v[32:35]
	v_mfma_f32_16x16x32_bf16 v[20:23], v[144:147], v[200:203], v[20:23]
	v_mfma_f32_16x16x32_bf16 v[16:19], v[168:171], v[200:203], v[16:19]
	v_mfma_f32_16x16x32_bf16 v[4:7], v[144:147], v[208:211], v[4:7]
	v_mfma_f32_16x16x32_bf16 v[0:3], v[168:171], v[208:211], v[0:3]
	v_mfma_f32_16x16x32_bf16 v[52:55], v[148:151], v[180:183], v[52:55]
	v_mfma_f32_16x16x32_bf16 v[48:51], v[172:175], v[180:183], v[48:51]
	v_mfma_f32_16x16x32_bf16 v[36:39], v[148:151], v[196:199], v[36:39]
	v_mfma_f32_16x16x32_bf16 v[32:35], v[172:175], v[196:199], v[32:35]
	v_mfma_f32_16x16x32_bf16 v[20:23], v[148:151], v[204:207], v[20:23]
	v_mfma_f32_16x16x32_bf16 v[16:19], v[172:175], v[204:207], v[16:19]
	v_mfma_f32_16x16x32_bf16 v[4:7], v[148:151], v[212:215], v[4:7]
	v_mfma_f32_16x16x32_bf16 v[0:3], v[172:175], v[212:215], v[0:3]
	s_barrier
	s_add_i32 s60, s60, 2
	s_add_u32 s43, s43, 0x100
	s_addc_u32 s59, s59, 0
	s_cmp_gt_u32 s60, 41
	s_mov_b64 s[28:29], s[30:31]
	s_cbranch_scc0 .LBB0_716
	s_setprio 0
	s_and_b64 vcc, exec, s[16:17]
	s_cbranch_vccz .LBB0_719
	s_barrier

; #define PG8_STAGE(bufoff, gbase, voff) do { _Pragma("unroll") for (int _i = 0; _i < 2; ++_i) \
;         __builtin_amdgcn_global_load_lds((const unsigned*)((const char*)(gbase) + (voff)[_i]), (PG8_LAS unsigned*)(lds + (bufoff) + ldsw + _i * 8192), 16, 0, 0); } while (0)
; #define PG8_LDA(dst, b, h) do { _Pragma("unroll") for (int m = 0; m < 4; ++m) _Pragma("unroll") for (int k = 0; k < 2; ++k) dst[m][k] = *(const PG8_LAS bf16x8*)(lds + PG8_SA(b, h) + aoff + m * 2048 + k * 1024); } while (0)
; #define PG8_LDB(dst, b, h) do { _Pragma("unroll") for (int n = 0; n < 2; ++n) _Pragma("unroll") for (int k = 0; k < 2; ++k) dst[n][k] = *(const PG8_LAS bf16x8*)(lds + PG8_SB(b, h) + boff + n * 2048 + k * 1024); } while (0)
; #define PG8_WAIT_V(n) asm volatile("s_waitcnt vmcnt(" #n ")" ::: "memory")
; #define PG8_WAIT_L(n) asm volatile("s_waitcnt lgkmcnt(" #n ")" ::: "memory")
; #define PG8_BAR __builtin_amdgcn_s_barrier()
; template <class Epi, class Sched, bool ALIGN_EPI = false, bool SP2 = false, bool F16 = false>
; __device__ __forceinline__ void gemm_phase(PG8_LAS unsigned char* lds, const Gemm g, const Sched& S, const Epi& E, const int wid_in) {
;     ...
;         const bool has_next = S.next(ui + 1, nxt);
;         const char* nA = has_next ? (const char*)g.A + (size_t)nxt.pm * tstep : cA; const char* nB = has_next ? (const char*)g.Bt + (size_t)nxt.pn * tstep : cB;
;         for (int t = 0; t < nt; t += 2) {
;             const bool last = (t == nt - 2);
;             const char* a1 = cA + (size_t)(t + 1) * kstep;
;             const char* a2 = last ? nA : cA + (size_t)(t + 2) * kstep; const char* b2 = last ? nB : cB + (size_t)(t + 2) * kstep;
;             const char* a3 = a2 + kstep; const char* b3 = b2 + kstep;
;             if (last && has_next) S.a_ready(nxt);
;             if constexpr (SP2) {
;             PG8_LDB(B0, 0, 0); PG8_LDB(B1, 0, 1); PG8_SCHED; PG8_LDA(At, 0, 0); PG8_STAGE(PG8_SA(1, 1), a1 + hstep, voffA);
;             PG8_WAIT_V(8); PG8_WAIT_L(0); PG8_BAR; PG8_MMA(0, 0, At, B0); PG8_MMA(0, 1, At, B1); PG8_BAR; PG8_SCHED;
;     ...
;         for (int a = 0; a < 2; ++a)
; #pragma unroll
;             for (int b = 0; b < 2; ++b)
; #pragma unroll
;                 for (int m = 0; m < 4; ++m)
; #pragma unroll
;                     for (int n = 0; n < 2; ++n) acc[a][b][m][n] = (f32x4){0.f, 0.f, 0.f, 0.f};
;         cur = nxt; cA = nA; cB = nB; ++ui;
.LBB0_811:
	s_ashr_i32 s31, s30, 31
	s_lshl_b64 s[14:15], s[30:31], 19
	s_add_u32 s34, s10, s14
	s_addc_u32 s35, s11, s15
	s_and_b64 s[14:15], s[8:9], exec
	s_cselect_b32 s14, s35, s47
	s_cselect_b32 s15, s34, s46
	s_ashr_i32 s29, s28, 31
	s_lshl_b64 s[36:37], s[28:29], 19
	s_add_u32 s36, s53, s36
	s_addc_u32 s37, s54, s37
	s_and_b64 s[40:41], s[8:9], exec
	s_cselect_b32 s29, s37, s49
	s_cselect_b32 s31, s36, s48
	s_add_u32 s46, s46, 0x40080
	s_addc_u32 s47, s47, 0
	s_add_u32 s40, s48, 0x100
	v_mov_b32_e32 v0, 0
	s_addc_u32 s41, s49, 0
	s_mov_b32 s42, -2
	v_mov_b32_e32 v1, v0
	v_mov_b32_e32 v2, v0
	v_mov_b32_e32 v3, v0
	v_mov_b32_e32 v4, v0
	v_mov_b32_e32 v5, v0
	v_mov_b32_e32 v6, v0
	v_mov_b32_e32 v7, v0
	v_mov_b32_e32 v16, v0
	v_mov_b32_e32 v17, v0
	v_mov_b32_e32 v18, v0
	v_mov_b32_e32 v19, v0
	v_mov_b32_e32 v20, v0
	v_mov_b32_e32 v21, v0
	v_mov_b32_e32 v22, v0
	v_mov_b32_e32 v23, v0
	v_mov_b32_e32 v32, v0
	v_mov_b32_e32 v33, v0
	v_mov_b32_e32 v34, v0
	v_mov_b32_e32 v35, v0
	v_mov_b32_e32 v36, v0
	v_mov_b32_e32 v37, v0
	v_mov_b32_e32 v38, v0
	v_mov_b32_e32 v39, v0
	v_mov_b32_e32 v48, v0
	v_mov_b32_e32 v49, v0
	v_mov_b32_e32 v50, v0
	v_mov_b32_e32 v51, v0
	v_mov_b32_e32 v52, v0
	v_mov_b32_e32 v53, v0
	v_mov_b32_e32 v54, v0
	v_mov_b32_e32 v55, v0
	v_mov_b32_e32 v8, v0
	v_mov_b32_e32 v9, v0
	v_mov_b32_e32 v10, v0
	v_mov_b32_e32 v11, v0
	v_mov_b32_e32 v12, v0
	v_mov_b32_e32 v13, v0
	v_mov_b32_e32 v14, v0
	v_mov_b32_e32 v15, v0
	v_mov_b32_e32 v24, v0
	v_mov_b32_e32 v25, v0
	v_mov_b32_e32 v26, v0
	v_mov_b32_e32 v27, v0
	v_mov_b32_e32 v28, v0
	v_mov_b32_e32 v29, v0
	v_mov_b32_e32 v30, v0
	v_mov_b32_e32 v31, v0
	v_mov_b32_e32 v40, v0
	v_mov_b32_e32 v41, v0
	v_mov_b32_e32 v42, v0
	v_mov_b32_e32 v43, v0
	v_mov_b32_e32 v44, v0
	v_mov_b32_e32 v45, v0
	v_mov_b32_e32 v46, v0
	v_mov_b32_e32 v47, v0
	v_mov_b32_e32 v56, v0
	v_mov_b32_e32 v57, v0
	v_mov_b32_e32 v58, v0
	v_mov_b32_e32 v59, v0
	v_mov_b32_e32 v60, v0
	v_mov_b32_e32 v61, v0
	v_mov_b32_e32 v62, v0
	v_mov_b32_e32 v63, v0
	v_mov_b32_e32 v64, v0
	v_mov_b32_e32 v65, v0
	v_mov_b32_e32 v66, v0
	v_mov_b32_e32 v67, v0
	v_mov_b32_e32 v68, v0
	v_mov_b32_e32 v69, v0
	v_mov_b32_e32 v70, v0
	v_mov_b32_e32 v71, v0
	v_mov_b32_e32 v80, v0
	v_mov_b32_e32 v81, v0
	v_mov_b32_e32 v82, v0
	v_mov_b32_e32 v83, v0
	v_mov_b32_e32 v84, v0
	v_mov_b32_e32 v85, v0
	v_mov_b32_e32 v86, v0
	v_mov_b32_e32 v87, v0
	v_mov_b32_e32 v96, v0
	v_mov_b32_e32 v97, v0
	v_mov_b32_e32 v98, v0
	v_mov_b32_e32 v99, v0
	v_mov_b32_e32 v100, v0
	v_mov_b32_e32 v101, v0
	v_mov_b32_e32 v102, v0
	v_mov_b32_e32 v103, v0
	v_mov_b32_e32 v120, v0
	v_mov_b32_e32 v121, v0
	v_mov_b32_e32 v122, v0
	v_mov_b32_e32 v123, v0
	v_mov_b32_e32 v124, v0
	v_mov_b32_e32 v125, v0
	v_mov_b32_e32 v126, v0
	v_mov_b32_e32 v127, v0
	v_mov_b32_e32 v72, v0
	v_mov_b32_e32 v73, v0
	v_mov_b32_e32 v74, v0
	v_mov_b32_e32 v75, v0
	v_mov_b32_e32 v76, v0
	v_mov_b32_e32 v77, v0
	v_mov_b32_e32 v78, v0
	v_mov_b32_e32 v79, v0
	v_mov_b32_e32 v88, v0
	v_mov_b32_e32 v89, v0
	v_mov_b32_e32 v90, v0
	v_mov_b32_e32 v91, v0
	v_mov_b32_e32 v92, v0
	v_mov_b32_e32 v93, v0
	v_mov_b32_e32 v94, v0
	v_mov_b32_e32 v95, v0
	v_mov_b32_e32 v104, v0
	v_mov_b32_e32 v105, v0
	v_mov_b32_e32 v106, v0
	v_mov_b32_e32 v107, v0
	v_mov_b32_e32 v108, v0
	v_mov_b32_e32 v109, v0
	v_mov_b32_e32 v110, v0
	v_mov_b32_e32 v111, v0
	v_mov_b32_e32 v136, v0
	v_mov_b32_e32 v137, v0
	v_mov_b32_e32 v138, v0
	v_mov_b32_e32 v139, v0
	v_mov_b32_e32 v140, v0
	v_mov_b32_e32 v141, v0
	v_mov_b32_e32 v142, v0
	v_mov_b32_e32 v143, v0
	s_cmp_ge_u32 s3, 4
	s_cbranch_scc0 .Lgsp_5
	s_setprio 1
.Lgsp_5:
.LBB0_812:
	ds_read_b128 v[112:115], v235
	ds_read_b128 v[116:119], v235 offset:1024
	ds_read_b128 v[128:131], v235 offset:2048
	ds_read_b128 v[132:135], v235 offset:3072
	ds_read_b128 v[144:147], v236
	ds_read_b128 v[148:151], v236 offset:1024
	ds_read_b128 v[152:155], v236 offset:2048
	ds_read_b128 v[156:159], v236 offset:3072
	s_add_u32 s43, s46, 0xfffc0080
	s_addc_u32 s45, s47, -1
	s_cmp_eq_u32 s42, 12
	s_cselect_b32 s51, s14, s45
	s_cselect_b32 s50, s15, s43
	s_cselect_b32 s49, s29, s41
	s_cselect_b32 s48, s31, s40
	v_lshl_add_u64 v[192:193], s[46:47], 0, v[204:205]
	s_add_i32 m0, s74, 0xc000
	ds_read_b128 v[160:163], v237
	ds_read_b128 v[164:167], v237 offset:1024
	ds_read_b128 v[168:171], v237 offset:2048
	ds_read_b128 v[172:175], v237 offset:3072
	ds_read_b128 v[176:179], v237 offset:4096
	ds_read_b128 v[180:183], v237 offset:5120
	ds_read_b128 v[184:187], v237 offset:6144
	ds_read_b128 v[188:191], v237 offset:7168
	global_load_lds_dwordx4 v[192:193], off
	v_lshl_add_u64 v[192:193], s[46:47], 0, v[206:207]
	s_add_i32 m0, s74, 0xe000
	s_nop 0
	global_load_lds_dwordx4 v[192:193], off
	s_waitcnt vmcnt(8)
	s_waitcnt lgkmcnt(0)
	s_barrier
; #define PG8_STAGE(bufoff, gbase, voff) do { _Pragma("unroll") for (int _i = 0; _i < 2; ++_i) \
;         __builtin_amdgcn_global_load_lds((const unsigned*)((const char*)(gbase) + (voff)[_i]), (PG8_LAS unsigned*)(lds + (bufoff) + ldsw + _i * 8192), 16, 0, 0); } while (0)
; #define PG8_LDA(dst, b, h) do { _Pragma("unroll") for (int m = 0; m < 4; ++m) _Pragma("unroll") for (int k = 0; k < 2; ++k) dst[m][k] = *(const PG8_LAS bf16x8*)(lds + PG8_SA(b, h) + aoff + m * 2048 + k * 1024); } while (0)
; #define PG8_MMA(ai, bj, At, Bt) do { __builtin_amdgcn_s_setprio(1); _Pragma("unroll") for (int m = 0; m < 4; ++m) _Pragma("unroll") for (int n = 0; n < 2; ++n) _Pragma("unroll") for (int k = 0; k < 2; ++k) \
;         acc[ai][bj][m][n] = mma16<F16>(Bt[n][k], At[m][k], acc[ai][bj][m][n]); __builtin_amdgcn_s_setprio(0); } while (0)
; #define PG8_WAIT_V(n) asm volatile("s_waitcnt vmcnt(" #n ")" ::: "memory")
; #define PG8_WAIT_L(n) asm volatile("s_waitcnt lgkmcnt(" #n ")" ::: "memory")
; #define PG8_BAR __builtin_amdgcn_s_barrier()
; #define PG8_SCHED __builtin_amdgcn_sched_barrier(0)
; template <class Epi, class Sched, bool ALIGN_EPI = false, bool SP2 = false, bool F16 = false>
; __device__ __forceinline__ void gemm_phase(PG8_LAS unsigned char* lds, const Gemm g, const Sched& S, const Epi& E, const int wid_in) {
;     ...
;             PG8_WAIT_V(8); PG8_WAIT_L(0); PG8_BAR; PG8_MMA(0, 0, At, B0); PG8_MMA(0, 1, At, B1); PG8_BAR; PG8_SCHED;
;             PG8_LDA(At, 0, 1); PG8_STAGE(PG8_SB(0, 0), b2, voffB); PG8_STAGE(PG8_SB(0, 1), b2 + hstep, voffB); PG8_STAGE(PG8_SA(0, 0), a2, voffA);
;             PG8_WAIT_V(8); PG8_WAIT_L(0); PG8_BAR; PG8_MMA(1, 0, At, B0); PG8_MMA(1, 1, At, B1); PG8_BAR; PG8_SCHED;
	s_waitcnt lgkmcnt(0)
	v_mfma_f32_16x16x32_f16 v[140:143], v[112:115], v[160:163], v[140:143]
	v_mfma_f32_16x16x32_f16 v[136:139], v[128:131], v[160:163], v[136:139]
	v_mfma_f32_16x16x32_f16 v[108:111], v[112:115], v[168:171], v[108:111]
	v_mfma_f32_16x16x32_f16 v[104:107], v[128:131], v[168:171], v[104:107]
	v_mfma_f32_16x16x32_f16 v[92:95], v[112:115], v[176:179], v[92:95]
	v_mfma_f32_16x16x32_f16 v[88:91], v[128:131], v[176:179], v[88:91]
	v_mfma_f32_16x16x32_f16 v[76:79], v[112:115], v[184:187], v[76:79]
	v_mfma_f32_16x16x32_f16 v[72:75], v[128:131], v[184:187], v[72:75]
	v_mfma_f32_16x16x32_f16 v[140:143], v[116:119], v[164:167], v[140:143]
	v_mfma_f32_16x16x32_f16 v[136:139], v[132:135], v[164:167], v[136:139]
	v_mfma_f32_16x16x32_f16 v[108:111], v[116:119], v[172:175], v[108:111]
	v_mfma_f32_16x16x32_f16 v[104:107], v[132:135], v[172:175], v[104:107]
	v_mfma_f32_16x16x32_f16 v[92:95], v[116:119], v[180:183], v[92:95]
	v_mfma_f32_16x16x32_f16 v[88:91], v[132:135], v[180:183], v[88:91]
	v_mfma_f32_16x16x32_f16 v[76:79], v[116:119], v[188:191], v[76:79]
	v_mfma_f32_16x16x32_f16 v[72:75], v[132:135], v[188:191], v[72:75]
	v_mfma_f32_16x16x32_f16 v[124:127], v[144:147], v[160:163], v[124:127]
	v_mfma_f32_16x16x32_f16 v[120:123], v[152:155], v[160:163], v[120:123]
	v_mfma_f32_16x16x32_f16 v[100:103], v[144:147], v[168:171], v[100:103]
	v_mfma_f32_16x16x32_f16 v[96:99], v[152:155], v[168:171], v[96:99]
	v_mfma_f32_16x16x32_f16 v[84:87], v[144:147], v[176:179], v[84:87]
	v_mfma_f32_16x16x32_f16 v[80:83], v[152:155], v[176:179], v[80:83]
	v_mfma_f32_16x16x32_f16 v[68:71], v[144:147], v[184:187], v[68:71]
	v_mfma_f32_16x16x32_f16 v[64:67], v[152:155], v[184:187], v[64:67]
	v_mfma_f32_16x16x32_f16 v[124:127], v[148:151], v[164:167], v[124:127]
	v_mfma_f32_16x16x32_f16 v[120:123], v[156:159], v[164:167], v[120:123]
	v_mfma_f32_16x16x32_f16 v[100:103], v[148:151], v[172:175], v[100:103]
	v_mfma_f32_16x16x32_f16 v[96:99], v[156:159], v[172:175], v[96:99]
	v_mfma_f32_16x16x32_f16 v[84:87], v[148:151], v[180:183], v[84:87]
	v_mfma_f32_16x16x32_f16 v[80:83], v[156:159], v[180:183], v[80:83]
	v_mfma_f32_16x16x32_f16 v[68:71], v[148:151], v[188:191], v[68:71]
	v_mfma_f32_16x16x32_f16 v[64:67], v[156:159], v[188:191], v[64:67]
	s_barrier
	s_add_i32 s43, s64, s68
	v_lshl_add_u64 v[192:193], s[48:49], 0, v[198:199]
	s_mov_b32 m0, s43
	ds_read_b128 v[160:163], v237 offset:16384
	ds_read_b128 v[164:167], v237 offset:17408
	ds_read_b128 v[168:171], v237 offset:18432
	ds_read_b128 v[172:175], v237 offset:19456
	ds_read_b128 v[176:179], v237 offset:20480
	ds_read_b128 v[180:183], v237 offset:21504
	ds_read_b128 v[184:187], v237 offset:22528
	ds_read_b128 v[188:191], v237 offset:23552
	global_load_lds_dwordx4 v[192:193], off
	s_add_i32 m0, s43, 0x2000
	s_add_u32 s86, s48, 0x40000
	v_lshl_add_u64 v[194:195], s[48:49], 0, v[202:203]
	s_addc_u32 s87, s49, 0
	s_add_i32 s43, s65, s68
	global_load_lds_dwordx4 v[194:195], off
	v_lshl_add_u64 v[212:213], s[86:87], 0, v[198:199]
	s_mov_b32 m0, s43
	v_lshl_add_u64 v[214:215], s[50:51], 0, v[200:201]
	global_load_lds_dwordx4 v[212:213], off
	v_lshl_add_u64 v[212:213], s[86:87], 0, v[202:203]
	s_add_i32 m0, s43, 0x2000
	s_nop 0
	global_load_lds_dwordx4 v[212:213], off
	v_lshl_add_u64 v[212:213], s[50:51], 0, v[196:197]
	s_mov_b32 m0, s74
	s_nop 0
	global_load_lds_dwordx4 v[212:213], off
	s_mov_b32 m0, s55
	s_nop 0
	global_load_lds_dwordx4 v[214:215], off
	s_waitcnt vmcnt(8)
	s_waitcnt lgkmcnt(0)
	s_barrier
	s_waitcnt lgkmcnt(0)
	v_mfma_f32_16x16x32_f16 v[60:63], v[112:115], v[160:163], v[60:63]
	v_mfma_f32_16x16x32_f16 v[56:59], v[128:131], v[160:163], v[56:59]
	v_mfma_f32_16x16x32_f16 v[44:47], v[112:115], v[168:171], v[44:47]
	v_mfma_f32_16x16x32_f16 v[40:43], v[128:131], v[168:171], v[40:43]
	v_mfma_f32_16x16x32_f16 v[28:31], v[112:115], v[176:179], v[28:31]
	v_mfma_f32_16x16x32_f16 v[24:27], v[128:131], v[176:179], v[24:27]
	v_mfma_f32_16x16x32_f16 v[12:15], v[112:115], v[184:187], v[12:15]
	v_mfma_f32_16x16x32_f16 v[8:11], v[128:131], v[184:187], v[8:11]
	v_mfma_f32_16x16x32_f16 v[60:63], v[116:119], v[164:167], v[60:63]
	v_mfma_f32_16x16x32_f16 v[56:59], v[132:135], v[164:167], v[56:59]
	v_mfma_f32_16x16x32_f16 v[44:47], v[116:119], v[172:175], v[44:47]
	v_mfma_f32_16x16x32_f16 v[40:43], v[132:135], v[172:175], v[40:43]
	v_mfma_f32_16x16x32_f16 v[28:31], v[116:119], v[180:183], v[28:31]
	v_mfma_f32_16x16x32_f16 v[24:27], v[132:135], v[180:183], v[24:27]
	v_mfma_f32_16x16x32_f16 v[12:15], v[116:119], v[188:191], v[12:15]
	v_mfma_f32_16x16x32_f16 v[8:11], v[132:135], v[188:191], v[8:11]
	v_mfma_f32_16x16x32_f16 v[52:55], v[144:147], v[160:163], v[52:55]
	v_mfma_f32_16x16x32_f16 v[48:51], v[152:155], v[160:163], v[48:51]
	v_mfma_f32_16x16x32_f16 v[36:39], v[144:147], v[168:171], v[36:39]
	v_mfma_f32_16x16x32_f16 v[32:35], v[152:155], v[168:171], v[32:35]
	v_mfma_f32_16x16x32_f16 v[20:23], v[144:147], v[176:179], v[20:23]
	v_mfma_f32_16x16x32_f16 v[16:19], v[152:155], v[176:179], v[16:19]
	v_mfma_f32_16x16x32_f16 v[4:7], v[144:147], v[184:187], v[4:7]
	v_mfma_f32_16x16x32_f16 v[0:3], v[152:155], v[184:187], v[0:3]
	v_mfma_f32_16x16x32_f16 v[52:55], v[148:151], v[164:167], v[52:55]
	v_mfma_f32_16x16x32_f16 v[48:51], v[156:159], v[164:167], v[48:51]
	v_mfma_f32_16x16x32_f16 v[36:39], v[148:151], v[172:175], v[36:39]
	v_mfma_f32_16x16x32_f16 v[32:35], v[156:159], v[172:175], v[32:35]
	v_mfma_f32_16x16x32_f16 v[20:23], v[148:151], v[180:183], v[20:23]
	v_mfma_f32_16x16x32_f16 v[16:19], v[156:159], v[180:183], v[16:19]
	v_mfma_f32_16x16x32_f16 v[4:7], v[148:151], v[188:191], v[4:7]
	v_mfma_f32_16x16x32_f16 v[0:3], v[156:159], v[188:191], v[0:3]
	s_barrier
; #define PG8_STAGE(bufoff, gbase, voff) do { _Pragma("unroll") for (int _i = 0; _i < 2; ++_i) \
;         __builtin_amdgcn_global_load_lds((const unsigned*)((const char*)(gbase) + (voff)[_i]), (PG8_LAS unsigned*)(lds + (bufoff) + ldsw + _i * 8192), 16, 0, 0); } while (0)
; #define PG8_LDA(dst, b, h) do { _Pragma("unroll") for (int m = 0; m < 4; ++m) _Pragma("unroll") for (int k = 0; k < 2; ++k) dst[m][k] = *(const PG8_LAS bf16x8*)(lds + PG8_SA(b, h) + aoff + m * 2048 + k * 1024); } while (0)
; #define PG8_LDB(dst, b, h) do { _Pragma("unroll") for (int n = 0; n < 2; ++n) _Pragma("unroll") for (int k = 0; k < 2; ++k) dst[n][k] = *(const PG8_LAS bf16x8*)(lds + PG8_SB(b, h) + boff + n * 2048 + k * 1024); } while (0)
; #define PG8_MMA(ai, bj, At, Bt) do { __builtin_amdgcn_s_setprio(1); _Pragma("unroll") for (int m = 0; m < 4; ++m) _Pragma("unroll") for (int n = 0; n < 2; ++n) _Pragma("unroll") for (int k = 0; k < 2; ++k) \
;         acc[ai][bj][m][n] = mma16<F16>(Bt[n][k], At[m][k], acc[ai][bj][m][n]); __builtin_amdgcn_s_setprio(0); } while (0)
; #define PG8_WAIT_V(n) asm volatile("s_waitcnt vmcnt(" #n ")" ::: "memory")
; #define PG8_WAIT_L(n) asm volatile("s_waitcnt lgkmcnt(" #n ")" ::: "memory")
; #define PG8_BAR __builtin_amdgcn_s_barrier()
; #define PG8_SCHED __builtin_amdgcn_sched_barrier(0)
; template <class Epi, class Sched, bool ALIGN_EPI = false, bool SP2 = false, bool F16 = false>
; __device__ __forceinline__ void gemm_phase(PG8_LAS unsigned char* lds, const Gemm g, const Sched& S, const Epi& E, const int wid_in) {
;     ...
;             PG8_LDB(B0, 1, 0); PG8_LDB(B1, 1, 1); PG8_SCHED; PG8_LDA(At, 1, 0); PG8_STAGE(PG8_SA(0, 1), a2 + hstep, voffA);
;             PG8_WAIT_V(8); PG8_WAIT_L(0); PG8_BAR; PG8_MMA(0, 0, At, B0); PG8_MMA(0, 1, At, B1); PG8_BAR; PG8_SCHED;
	s_add_i32 s43, 0, 0x18000
	s_add_i32 s45, 0, 0x1c000
	v_add_u32_e32 v132, s43, v234
	v_add_u32_e32 v156, s45, v234
	ds_read_b128 v[112:115], v132
	ds_read_b128 v[116:119], v132 offset:1024
	ds_read_b128 v[128:131], v132 offset:2048
	ds_read_b128 v[132:135], v132 offset:3072
	ds_read_b128 v[144:147], v156
	ds_read_b128 v[148:151], v156 offset:1024
	ds_read_b128 v[152:155], v156 offset:2048
	ds_read_b128 v[156:159], v156 offset:3072
	s_add_u32 s50, s50, 0x40000
	s_addc_u32 s51, s51, 0
	s_mov_b32 m0, s58
	v_lshl_add_u64 v[216:217], s[50:51], 0, v[196:197]
	ds_read_b128 v[160:163], v237 offset:32768
	ds_read_b128 v[164:167], v237 offset:33792
	ds_read_b128 v[168:171], v237 offset:34816
	ds_read_b128 v[172:175], v237 offset:35840
	ds_read_b128 v[176:179], v237 offset:36864
	ds_read_b128 v[180:183], v237 offset:37888
	ds_read_b128 v[184:187], v237 offset:38912
	ds_read_b128 v[188:191], v237 offset:39936
	global_load_lds_dwordx4 v[216:217], off
	v_lshl_add_u64 v[216:217], s[50:51], 0, v[200:201]
	s_mov_b32 m0, s59
	s_nop 0
	global_load_lds_dwordx4 v[216:217], off
	s_waitcnt vmcnt(8)
	s_waitcnt lgkmcnt(0)
	s_barrier
	s_waitcnt lgkmcnt(0)
	v_mfma_f32_16x16x32_f16 v[140:143], v[112:115], v[160:163], v[140:143]
	v_mfma_f32_16x16x32_f16 v[136:139], v[128:131], v[160:163], v[136:139]
	v_mfma_f32_16x16x32_f16 v[108:111], v[112:115], v[168:171], v[108:111]
	v_mfma_f32_16x16x32_f16 v[104:107], v[128:131], v[168:171], v[104:107]
	v_mfma_f32_16x16x32_f16 v[92:95], v[112:115], v[176:179], v[92:95]
	v_mfma_f32_16x16x32_f16 v[88:91], v[128:131], v[176:179], v[88:91]
	v_mfma_f32_16x16x32_f16 v[76:79], v[112:115], v[184:187], v[76:79]
	v_mfma_f32_16x16x32_f16 v[72:75], v[128:131], v[184:187], v[72:75]
	v_mfma_f32_16x16x32_f16 v[140:143], v[116:119], v[164:167], v[140:143]
	v_mfma_f32_16x16x32_f16 v[136:139], v[132:135], v[164:167], v[136:139]
	v_mfma_f32_16x16x32_f16 v[108:111], v[116:119], v[172:175], v[108:111]
	v_mfma_f32_16x16x32_f16 v[104:107], v[132:135], v[172:175], v[104:107]
	v_mfma_f32_16x16x32_f16 v[92:95], v[116:119], v[180:183], v[92:95]
	v_mfma_f32_16x16x32_f16 v[88:91], v[132:135], v[180:183], v[88:91]
	v_mfma_f32_16x16x32_f16 v[76:79], v[116:119], v[188:191], v[76:79]
	v_mfma_f32_16x16x32_f16 v[72:75], v[132:135], v[188:191], v[72:75]
	v_mfma_f32_16x16x32_f16 v[124:127], v[144:147], v[160:163], v[124:127]
	v_mfma_f32_16x16x32_f16 v[120:123], v[152:155], v[160:163], v[120:123]
	v_mfma_f32_16x16x32_f16 v[100:103], v[144:147], v[168:171], v[100:103]
	v_mfma_f32_16x16x32_f16 v[96:99], v[152:155], v[168:171], v[96:99]
	v_mfma_f32_16x16x32_f16 v[84:87], v[144:147], v[176:179], v[84:87]
	v_mfma_f32_16x16x32_f16 v[80:83], v[152:155], v[176:179], v[80:83]
	v_mfma_f32_16x16x32_f16 v[68:71], v[144:147], v[184:187], v[68:71]
	v_mfma_f32_16x16x32_f16 v[64:67], v[152:155], v[184:187], v[64:67]
	v_mfma_f32_16x16x32_f16 v[124:127], v[148:151], v[164:167], v[124:127]
	v_mfma_f32_16x16x32_f16 v[120:123], v[156:159], v[164:167], v[120:123]
	v_mfma_f32_16x16x32_f16 v[100:103], v[148:151], v[172:175], v[100:103]
	v_mfma_f32_16x16x32_f16 v[96:99], v[156:159], v[172:175], v[96:99]
	v_mfma_f32_16x16x32_f16 v[84:87], v[148:151], v[180:183], v[84:87]
	v_mfma_f32_16x16x32_f16 v[80:83], v[156:159], v[180:183], v[80:83]
	v_mfma_f32_16x16x32_f16 v[68:71], v[148:151], v[188:191], v[68:71]
	v_mfma_f32_16x16x32_f16 v[64:67], v[156:159], v[188:191], v[64:67]
	s_barrier
; #define PG8_STAGE(bufoff, gbase, voff) do { _Pragma("unroll") for (int _i = 0; _i < 2; ++_i) \
;         __builtin_amdgcn_global_load_lds((const unsigned*)((const char*)(gbase) + (voff)[_i]), (PG8_LAS unsigned*)(lds + (bufoff) + ldsw + _i * 8192), 16, 0, 0); } while (0)
; #define PG8_LDA(dst, b, h) do { _Pragma("unroll") for (int m = 0; m < 4; ++m) _Pragma("unroll") for (int k = 0; k < 2; ++k) dst[m][k] = *(const PG8_LAS bf16x8*)(lds + PG8_SA(b, h) + aoff + m * 2048 + k * 1024); } while (0)
; #define PG8_MMA(ai, bj, At, Bt) do { __builtin_amdgcn_s_setprio(1); _Pragma("unroll") for (int m = 0; m < 4; ++m) _Pragma("unroll") for (int n = 0; n < 2; ++n) _Pragma("unroll") for (int k = 0; k < 2; ++k) \
;         acc[ai][bj][m][n] = mma16<F16>(Bt[n][k], At[m][k], acc[ai][bj][m][n]); __builtin_amdgcn_s_setprio(0); } while (0)
; #define PG8_WAIT_V(n) asm volatile("s_waitcnt vmcnt(" #n ")" ::: "memory")
; #define PG8_WAIT_L(n) asm volatile("s_waitcnt lgkmcnt(" #n ")" ::: "memory")
; #define PG8_BAR __builtin_amdgcn_s_barrier()
; #define PG8_SCHED __builtin_amdgcn_sched_barrier(0)
; template <class Epi, class Sched, bool ALIGN_EPI = false, bool SP2 = false, bool F16 = false>
; __device__ __forceinline__ void gemm_phase(PG8_LAS unsigned char* lds, const Gemm g, const Sched& S, const Epi& E, const int wid_in) {
;     ...
;         for (int t = 0; t < nt; t += 2) {
;             const bool last = (t == nt - 2);
;             const char* a1 = cA + (size_t)(t + 1) * kstep;
;             const char* a2 = last ? nA : cA + (size_t)(t + 2) * kstep; const char* b2 = last ? nB : cB + (size_t)(t + 2) * kstep;
;     ...
;             PG8_LDA(At, 1, 1); PG8_STAGE(PG8_SB(1, 0), b3, voffB); PG8_STAGE(PG8_SB(1, 1), b3 + hstep, voffB); PG8_STAGE(PG8_SA(1, 0), a3, voffA);
;             PG8_WAIT_V(8); PG8_WAIT_L(0); PG8_BAR; PG8_MMA(1, 0, At, B0); PG8_MMA(1, 1, At, B1); PG8_BAR; PG8_SCHED;
	s_add_i32 s43, s43, s68
	v_lshl_add_u64 v[192:193], v[192:193], 0, s[26:27]
	s_mov_b32 m0, s43
	ds_read_b128 v[160:163], v237 offset:49152
	ds_read_b128 v[164:167], v237 offset:50176
	ds_read_b128 v[168:171], v237 offset:51200
	ds_read_b128 v[172:175], v237 offset:52224
	ds_read_b128 v[176:179], v237 offset:53248
	ds_read_b128 v[180:183], v237 offset:54272
	ds_read_b128 v[184:187], v237 offset:55296
	ds_read_b128 v[188:191], v237 offset:56320
	global_load_lds_dwordx4 v[192:193], off
	s_add_i32 m0, s43, 0x2000
	s_add_u32 s48, s48, 0x40080
	v_lshl_add_u64 v[192:193], v[194:195], 0, s[26:27]
	s_addc_u32 s49, s49, 0
	s_add_i32 s43, s45, s68
	global_load_lds_dwordx4 v[192:193], off
	v_lshl_add_u64 v[192:193], s[48:49], 0, v[198:199]
	s_mov_b32 m0, s43
	s_nop 0
	global_load_lds_dwordx4 v[192:193], off
	v_lshl_add_u64 v[192:193], s[48:49], 0, v[202:203]
	s_add_i32 m0, s43, 0x2000
	s_nop 0
	global_load_lds_dwordx4 v[192:193], off
	v_lshl_add_u64 v[192:193], v[212:213], 0, s[26:27]
	s_mov_b32 m0, s75
	s_nop 0
	global_load_lds_dwordx4 v[192:193], off
	v_lshl_add_u64 v[192:193], v[214:215], 0, s[26:27]
	s_mov_b32 m0, s60
	s_nop 0
	global_load_lds_dwordx4 v[192:193], off
	s_waitcnt vmcnt(8)
	s_waitcnt lgkmcnt(0)
	s_barrier
	s_waitcnt lgkmcnt(0)
	v_mfma_f32_16x16x32_f16 v[60:63], v[112:115], v[160:163], v[60:63]
	v_mfma_f32_16x16x32_f16 v[56:59], v[128:131], v[160:163], v[56:59]
	v_mfma_f32_16x16x32_f16 v[44:47], v[112:115], v[168:171], v[44:47]
	v_mfma_f32_16x16x32_f16 v[40:43], v[128:131], v[168:171], v[40:43]
	v_mfma_f32_16x16x32_f16 v[28:31], v[112:115], v[176:179], v[28:31]
	v_mfma_f32_16x16x32_f16 v[24:27], v[128:131], v[176:179], v[24:27]
	v_mfma_f32_16x16x32_f16 v[12:15], v[112:115], v[184:187], v[12:15]
	v_mfma_f32_16x16x32_f16 v[8:11], v[128:131], v[184:187], v[8:11]
	v_mfma_f32_16x16x32_f16 v[60:63], v[116:119], v[164:167], v[60:63]
	v_mfma_f32_16x16x32_f16 v[56:59], v[132:135], v[164:167], v[56:59]
	v_mfma_f32_16x16x32_f16 v[44:47], v[116:119], v[172:175], v[44:47]
	v_mfma_f32_16x16x32_f16 v[40:43], v[132:135], v[172:175], v[40:43]
	v_mfma_f32_16x16x32_f16 v[28:31], v[116:119], v[180:183], v[28:31]
	v_mfma_f32_16x16x32_f16 v[24:27], v[132:135], v[180:183], v[24:27]
	v_mfma_f32_16x16x32_f16 v[12:15], v[116:119], v[188:191], v[12:15]
	v_mfma_f32_16x16x32_f16 v[8:11], v[132:135], v[188:191], v[8:11]
	v_mfma_f32_16x16x32_f16 v[52:55], v[144:147], v[160:163], v[52:55]
	v_mfma_f32_16x16x32_f16 v[48:51], v[152:155], v[160:163], v[48:51]
	v_mfma_f32_16x16x32_f16 v[36:39], v[144:147], v[168:171], v[36:39]
	v_mfma_f32_16x16x32_f16 v[32:35], v[152:155], v[168:171], v[32:35]
	v_mfma_f32_16x16x32_f16 v[20:23], v[144:147], v[176:179], v[20:23]
	v_mfma_f32_16x16x32_f16 v[16:19], v[152:155], v[176:179], v[16:19]
	v_mfma_f32_16x16x32_f16 v[4:7], v[144:147], v[184:187], v[4:7]
	v_mfma_f32_16x16x32_f16 v[0:3], v[152:155], v[184:187], v[0:3]
	v_mfma_f32_16x16x32_f16 v[52:55], v[148:151], v[164:167], v[52:55]
	v_mfma_f32_16x16x32_f16 v[48:51], v[156:159], v[164:167], v[48:51]
	v_mfma_f32_16x16x32_f16 v[36:39], v[148:151], v[172:175], v[36:39]
	v_mfma_f32_16x16x32_f16 v[32:35], v[156:159], v[172:175], v[32:35]
	v_mfma_f32_16x16x32_f16 v[20:23], v[148:151], v[180:183], v[20:23]
	v_mfma_f32_16x16x32_f16 v[16:19], v[156:159], v[180:183], v[16:19]
	v_mfma_f32_16x16x32_f16 v[4:7], v[148:151], v[188:191], v[4:7]
	v_mfma_f32_16x16x32_f16 v[0:3], v[156:159], v[188:191], v[0:3]
	s_barrier
	s_add_i32 s42, s42, 2
	s_add_u32 s46, s46, 0x100
	s_addc_u32 s47, s47, 0
	s_add_u32 s40, s40, 0x100
	s_addc_u32 s41, s41, 0
	s_cmp_gt_u32 s42, 13
	s_cbranch_scc0 .LBB0_812
	s_setprio 0
	s_and_b64 vcc, exec, s[16:17]
	s_cbranch_vccz .LBB0_815
	s_barrier

; #define PG8_STAGE(bufoff, gbase, voff) do { _Pragma("unroll") for (int _i = 0; _i < 2; ++_i) \
;         __builtin_amdgcn_global_load_lds((const unsigned*)((const char*)(gbase) + (voff)[_i]), (PG8_LAS unsigned*)(lds + (bufoff) + ldsw + _i * 8192), 16, 0, 0); } while (0)
; #define PG8_LDA(dst, b, h) do { _Pragma("unroll") for (int m = 0; m < 4; ++m) _Pragma("unroll") for (int k = 0; k < 2; ++k) dst[m][k] = *(const PG8_LAS bf16x8*)(lds + PG8_SA(b, h) + aoff + m * 2048 + k * 1024); } while (0)
; #define PG8_LDB(dst, b, h) do { _Pragma("unroll") for (int n = 0; n < 2; ++n) _Pragma("unroll") for (int k = 0; k < 2; ++k) dst[n][k] = *(const PG8_LAS bf16x8*)(lds + PG8_SB(b, h) + boff + n * 2048 + k * 1024); } while (0)
; #define PG8_WAIT_V(n) asm volatile("s_waitcnt vmcnt(" #n ")" ::: "memory")
; #define PG8_WAIT_L(n) asm volatile("s_waitcnt lgkmcnt(" #n ")" ::: "memory")
; #define PG8_BAR __builtin_amdgcn_s_barrier()
; template <class Epi, class Sched, bool ALIGN_EPI = false, bool SP2 = false, bool F16 = false>
; __device__ __forceinline__ void gemm_phase(PG8_LAS unsigned char* lds, const Gemm g, const Sched& S, const Epi& E, const int wid_in) {
;     ...
;         const bool has_next = S.next(ui + 1, nxt);
;         const char* nA = has_next ? (const char*)g.A + (size_t)nxt.pm * tstep : cA; const char* nB = has_next ? (const char*)g.Bt + (size_t)nxt.pn * tstep : cB;
;         for (int t = 0; t < nt; t += 2) {
;             const bool last = (t == nt - 2);
;             const char* a1 = cA + (size_t)(t + 1) * kstep;
;             const char* a2 = last ? nA : cA + (size_t)(t + 2) * kstep; const char* b2 = last ? nB : cB + (size_t)(t + 2) * kstep;
;             const char* a3 = a2 + kstep; const char* b3 = b2 + kstep;
;             if (last && has_next) S.a_ready(nxt);
;             if constexpr (SP2) {
;             PG8_LDB(B0, 0, 0); PG8_LDB(B1, 0, 1); PG8_SCHED; PG8_LDA(At, 0, 0); PG8_STAGE(PG8_SA(1, 1), a1 + hstep, voffA);
;             PG8_WAIT_V(8); PG8_WAIT_L(0); PG8_BAR; PG8_MMA(0, 0, At, B0); PG8_MMA(0, 1, At, B1); PG8_BAR; PG8_SCHED;
;     ...
;         for (int a = 0; a < 2; ++a)
; #pragma unroll
;             for (int b = 0; b < 2; ++b)
; #pragma unroll
;                 for (int m = 0; m < 4; ++m)
; #pragma unroll
;                     for (int n = 0; n < 2; ++n) acc[a][b][m][n] = (f32x4){0.f, 0.f, 0.f, 0.f};
;         cur = nxt; cA = nA; cB = nB; ++ui;
.LBB0_901:
	s_ashr_i32 s35, s34, 31
	s_lshl_b64 s[36:37], s[34:35], 19
	s_add_u32 s36, s61, s36
	s_addc_u32 s37, s62, s37
	s_and_b64 s[42:43], s[8:9], exec
	s_cselect_b32 s11, s37, s47
	s_cselect_b32 s13, s36, s46
	s_ashr_i32 s31, s30, 31
	s_lshl_b64 s[42:43], s[30:31], 19
	s_add_u32 s44, s63, s42
	s_addc_u32 s45, s64, s43
	s_and_b64 s[42:43], s[8:9], exec
	s_cselect_b32 s31, s45, s49
	s_cselect_b32 s35, s44, s48
	s_add_u32 s46, s46, 0x40080
	s_addc_u32 s47, s47, 0
	s_add_u32 s42, s48, 0x100
	v_mov_b32_e32 v0, 0
	s_addc_u32 s43, s49, 0
	s_mov_b32 s52, -2
	s_waitcnt lgkmcnt(0)
	v_mov_b32_e32 v1, v0
	v_mov_b32_e32 v2, v0
	v_mov_b32_e32 v3, v0
	v_mov_b32_e32 v4, v0
	v_mov_b32_e32 v5, v0
	v_mov_b32_e32 v6, v0
	v_mov_b32_e32 v7, v0
	v_mov_b32_e32 v16, v0
	v_mov_b32_e32 v17, v0
	v_mov_b32_e32 v18, v0
	v_mov_b32_e32 v19, v0
	v_mov_b32_e32 v20, v0
	v_mov_b32_e32 v21, v0
	v_mov_b32_e32 v22, v0
	v_mov_b32_e32 v23, v0
	v_mov_b32_e32 v32, v0
	v_mov_b32_e32 v33, v0
	v_mov_b32_e32 v34, v0
	v_mov_b32_e32 v35, v0
	v_mov_b32_e32 v36, v0
	v_mov_b32_e32 v37, v0
	v_mov_b32_e32 v38, v0
	v_mov_b32_e32 v39, v0
	v_mov_b32_e32 v48, v0
	v_mov_b32_e32 v49, v0
	v_mov_b32_e32 v50, v0
	v_mov_b32_e32 v51, v0
	v_mov_b32_e32 v52, v0
	v_mov_b32_e32 v53, v0
	v_mov_b32_e32 v54, v0
	v_mov_b32_e32 v55, v0
	v_mov_b32_e32 v8, v0
	v_mov_b32_e32 v9, v0
	v_mov_b32_e32 v10, v0
	v_mov_b32_e32 v11, v0
	v_mov_b32_e32 v12, v0
	v_mov_b32_e32 v13, v0
	v_mov_b32_e32 v14, v0
	v_mov_b32_e32 v15, v0
	v_mov_b32_e32 v24, v0
	v_mov_b32_e32 v25, v0
	v_mov_b32_e32 v26, v0
	v_mov_b32_e32 v27, v0
	v_mov_b32_e32 v28, v0
	v_mov_b32_e32 v29, v0
	v_mov_b32_e32 v30, v0
	v_mov_b32_e32 v31, v0
	v_mov_b32_e32 v40, v0
	v_mov_b32_e32 v41, v0
	v_mov_b32_e32 v42, v0
	v_mov_b32_e32 v43, v0
	v_mov_b32_e32 v44, v0
	v_mov_b32_e32 v45, v0
	v_mov_b32_e32 v46, v0
	v_mov_b32_e32 v47, v0
	v_mov_b32_e32 v56, v0
	v_mov_b32_e32 v57, v0
	v_mov_b32_e32 v58, v0
	v_mov_b32_e32 v59, v0
	v_mov_b32_e32 v60, v0
	v_mov_b32_e32 v61, v0
	v_mov_b32_e32 v62, v0
	v_mov_b32_e32 v63, v0
	v_mov_b32_e32 v64, v0
	v_mov_b32_e32 v65, v0
	v_mov_b32_e32 v66, v0
	v_mov_b32_e32 v67, v0
	v_mov_b32_e32 v68, v0
	v_mov_b32_e32 v69, v0
	v_mov_b32_e32 v70, v0
	v_mov_b32_e32 v71, v0
	v_mov_b32_e32 v80, v0
	v_mov_b32_e32 v81, v0
	v_mov_b32_e32 v82, v0
	v_mov_b32_e32 v83, v0
	v_mov_b32_e32 v84, v0
	v_mov_b32_e32 v85, v0
	v_mov_b32_e32 v86, v0
	v_mov_b32_e32 v87, v0
	v_mov_b32_e32 v96, v0
	v_mov_b32_e32 v97, v0
	v_mov_b32_e32 v98, v0
	v_mov_b32_e32 v99, v0
	v_mov_b32_e32 v100, v0
	v_mov_b32_e32 v101, v0
	v_mov_b32_e32 v102, v0
	v_mov_b32_e32 v103, v0
	v_mov_b32_e32 v112, v0
	v_mov_b32_e32 v113, v0
	v_mov_b32_e32 v114, v0
	v_mov_b32_e32 v115, v0
	v_mov_b32_e32 v116, v0
	v_mov_b32_e32 v117, v0
	v_mov_b32_e32 v118, v0
	v_mov_b32_e32 v119, v0
	v_mov_b32_e32 v72, v0
	v_mov_b32_e32 v73, v0
	v_mov_b32_e32 v74, v0
	v_mov_b32_e32 v75, v0
	v_mov_b32_e32 v76, v0
	v_mov_b32_e32 v77, v0
	v_mov_b32_e32 v78, v0
	v_mov_b32_e32 v79, v0
	v_mov_b32_e32 v88, v0
	v_mov_b32_e32 v89, v0
	v_mov_b32_e32 v90, v0
	v_mov_b32_e32 v91, v0
	v_mov_b32_e32 v92, v0
	v_mov_b32_e32 v93, v0
	v_mov_b32_e32 v94, v0
	v_mov_b32_e32 v95, v0
	v_mov_b32_e32 v104, v0
	v_mov_b32_e32 v105, v0
	v_mov_b32_e32 v106, v0
	v_mov_b32_e32 v107, v0
	v_mov_b32_e32 v108, v0
	v_mov_b32_e32 v109, v0
	v_mov_b32_e32 v110, v0
	v_mov_b32_e32 v111, v0
	v_mov_b32_e32 v120, v0
	v_mov_b32_e32 v121, v0
	v_mov_b32_e32 v122, v0
	v_mov_b32_e32 v123, v0
	v_mov_b32_e32 v124, v0
	v_mov_b32_e32 v125, v0
	v_mov_b32_e32 v126, v0
	v_mov_b32_e32 v127, v0
	s_cmp_ge_u32 s3, 4
	s_cbranch_scc0 .Lgsp_6
	s_setprio 1
.Lgsp_6:
.LBB0_902:
	ds_read_b128 v[128:131], v183
	ds_read_b128 v[132:135], v183 offset:1024
	ds_read_b128 v[136:139], v183 offset:2048
	ds_read_b128 v[140:143], v183 offset:3072
	ds_read_b128 v[144:147], v184
	ds_read_b128 v[148:151], v184 offset:1024
	ds_read_b128 v[152:155], v184 offset:2048
	ds_read_b128 v[174:177], v184 offset:3072
	s_add_u32 s48, s46, 0xfffc0080
	s_addc_u32 s49, s47, -1
	s_cmp_eq_u32 s52, 12
	s_cselect_b32 s51, s11, s49
	s_cselect_b32 s50, s13, s48
	s_cselect_b32 s49, s31, s43
	s_cselect_b32 s48, s35, s42
	v_lshl_add_u64 v[178:179], s[46:47], 0, v[166:167]
	s_add_i32 m0, s74, 0xc000
	ds_read_b128 v[188:191], v185
	ds_read_b128 v[192:195], v185 offset:1024
	ds_read_b128 v[196:199], v185 offset:2048
	ds_read_b128 v[200:203], v185 offset:3072
	ds_read_b128 v[204:207], v185 offset:4096
	ds_read_b128 v[208:211], v185 offset:5120
	ds_read_b128 v[212:215], v185 offset:6144
	ds_read_b128 v[216:219], v185 offset:7168
	global_load_lds_dwordx4 v[178:179], off
	v_lshl_add_u64 v[178:179], s[46:47], 0, v[168:169]
	s_add_i32 m0, s74, 0xe000
	s_nop 0
	global_load_lds_dwordx4 v[178:179], off
	s_waitcnt vmcnt(8)
	s_waitcnt lgkmcnt(0)
	s_barrier
; #define PG8_STAGE(bufoff, gbase, voff) do { _Pragma("unroll") for (int _i = 0; _i < 2; ++_i) \
;         __builtin_amdgcn_global_load_lds((const unsigned*)((const char*)(gbase) + (voff)[_i]), (PG8_LAS unsigned*)(lds + (bufoff) + ldsw + _i * 8192), 16, 0, 0); } while (0)
; #define PG8_LDA(dst, b, h) do { _Pragma("unroll") for (int m = 0; m < 4; ++m) _Pragma("unroll") for (int k = 0; k < 2; ++k) dst[m][k] = *(const PG8_LAS bf16x8*)(lds + PG8_SA(b, h) + aoff + m * 2048 + k * 1024); } while (0)
; #define PG8_MMA(ai, bj, At, Bt) do { __builtin_amdgcn_s_setprio(1); _Pragma("unroll") for (int m = 0; m < 4; ++m) _Pragma("unroll") for (int n = 0; n < 2; ++n) _Pragma("unroll") for (int k = 0; k < 2; ++k) \
;         acc[ai][bj][m][n] = mma16<F16>(Bt[n][k], At[m][k], acc[ai][bj][m][n]); __builtin_amdgcn_s_setprio(0); } while (0)
; #define PG8_WAIT_V(n) asm volatile("s_waitcnt vmcnt(" #n ")" ::: "memory")
; #define PG8_WAIT_L(n) asm volatile("s_waitcnt lgkmcnt(" #n ")" ::: "memory")
; #define PG8_BAR __builtin_amdgcn_s_barrier()
; #define PG8_SCHED __builtin_amdgcn_sched_barrier(0)
; template <class Epi, class Sched, bool ALIGN_EPI = false, bool SP2 = false, bool F16 = false>
; __device__ __forceinline__ void gemm_phase(PG8_LAS unsigned char* lds, const Gemm g, const Sched& S, const Epi& E, const int wid_in) {
;     ...
;             PG8_WAIT_V(8); PG8_WAIT_L(0); PG8_BAR; PG8_MMA(0, 0, At, B0); PG8_MMA(0, 1, At, B1); PG8_BAR; PG8_SCHED;
;             PG8_LDA(At, 0, 1); PG8_STAGE(PG8_SB(0, 0), b2, voffB); PG8_STAGE(PG8_SB(0, 1), b2 + hstep, voffB); PG8_STAGE(PG8_SA(0, 0), a2, voffA);
;             PG8_WAIT_V(8); PG8_WAIT_L(0); PG8_BAR; PG8_MMA(1, 0, At, B0); PG8_MMA(1, 1, At, B1); PG8_BAR; PG8_SCHED;
	s_waitcnt lgkmcnt(0)
	v_mfma_f32_16x16x32_f16 v[124:127], v[128:131], v[188:191], v[124:127]
	v_mfma_f32_16x16x32_f16 v[120:123], v[136:139], v[188:191], v[120:123]
	v_mfma_f32_16x16x32_f16 v[108:111], v[128:131], v[196:199], v[108:111]
	v_mfma_f32_16x16x32_f16 v[104:107], v[136:139], v[196:199], v[104:107]
	v_mfma_f32_16x16x32_f16 v[92:95], v[128:131], v[204:207], v[92:95]
	v_mfma_f32_16x16x32_f16 v[88:91], v[136:139], v[204:207], v[88:91]
	v_mfma_f32_16x16x32_f16 v[76:79], v[128:131], v[212:215], v[76:79]
	v_mfma_f32_16x16x32_f16 v[72:75], v[136:139], v[212:215], v[72:75]
	v_mfma_f32_16x16x32_f16 v[124:127], v[132:135], v[192:195], v[124:127]
	v_mfma_f32_16x16x32_f16 v[120:123], v[140:143], v[192:195], v[120:123]
	v_mfma_f32_16x16x32_f16 v[108:111], v[132:135], v[200:203], v[108:111]
	v_mfma_f32_16x16x32_f16 v[104:107], v[140:143], v[200:203], v[104:107]
	v_mfma_f32_16x16x32_f16 v[92:95], v[132:135], v[208:211], v[92:95]
	v_mfma_f32_16x16x32_f16 v[88:91], v[140:143], v[208:211], v[88:91]
	v_mfma_f32_16x16x32_f16 v[76:79], v[132:135], v[216:219], v[76:79]
	v_mfma_f32_16x16x32_f16 v[72:75], v[140:143], v[216:219], v[72:75]
	v_mfma_f32_16x16x32_f16 v[116:119], v[144:147], v[188:191], v[116:119]
	v_mfma_f32_16x16x32_f16 v[112:115], v[152:155], v[188:191], v[112:115]
	v_mfma_f32_16x16x32_f16 v[100:103], v[144:147], v[196:199], v[100:103]
	v_mfma_f32_16x16x32_f16 v[96:99], v[152:155], v[196:199], v[96:99]
	v_mfma_f32_16x16x32_f16 v[84:87], v[144:147], v[204:207], v[84:87]
	v_mfma_f32_16x16x32_f16 v[80:83], v[152:155], v[204:207], v[80:83]
	v_mfma_f32_16x16x32_f16 v[68:71], v[144:147], v[212:215], v[68:71]
	v_mfma_f32_16x16x32_f16 v[64:67], v[152:155], v[212:215], v[64:67]
	v_mfma_f32_16x16x32_f16 v[116:119], v[148:151], v[192:195], v[116:119]
	v_mfma_f32_16x16x32_f16 v[112:115], v[174:177], v[192:195], v[112:115]
	v_mfma_f32_16x16x32_f16 v[100:103], v[148:151], v[200:203], v[100:103]
	v_mfma_f32_16x16x32_f16 v[96:99], v[174:177], v[200:203], v[96:99]
	v_mfma_f32_16x16x32_f16 v[84:87], v[148:151], v[208:211], v[84:87]
	v_mfma_f32_16x16x32_f16 v[80:83], v[174:177], v[208:211], v[80:83]
	v_mfma_f32_16x16x32_f16 v[68:71], v[148:151], v[216:219], v[68:71]
	v_mfma_f32_16x16x32_f16 v[64:67], v[174:177], v[216:219], v[64:67]
	s_barrier
	s_add_i32 s53, s40, s68
	v_lshl_add_u64 v[178:179], s[48:49], 0, v[158:159]
	s_mov_b32 m0, s53
	ds_read_b128 v[188:191], v185 offset:16384
	ds_read_b128 v[192:195], v185 offset:17408
	ds_read_b128 v[196:199], v185 offset:18432
	ds_read_b128 v[200:203], v185 offset:19456
	ds_read_b128 v[204:207], v185 offset:20480
	ds_read_b128 v[208:211], v185 offset:21504
	ds_read_b128 v[212:215], v185 offset:22528
	ds_read_b128 v[216:219], v185 offset:23552
	global_load_lds_dwordx4 v[178:179], off
	s_add_i32 m0, s53, 0x2000
	s_add_u32 s54, s48, 0x40000
	v_lshl_add_u64 v[220:221], s[48:49], 0, v[162:163]
	s_addc_u32 s55, s49, 0
	s_add_i32 s53, s41, s68
	global_load_lds_dwordx4 v[220:221], off
	v_lshl_add_u64 v[222:223], s[54:55], 0, v[158:159]
	s_mov_b32 m0, s53
	v_lshl_add_u64 v[224:225], s[50:51], 0, v[160:161]
	global_load_lds_dwordx4 v[222:223], off
	v_lshl_add_u64 v[222:223], s[54:55], 0, v[162:163]
	s_add_i32 m0, s53, 0x2000
	s_nop 0
	global_load_lds_dwordx4 v[222:223], off
	v_lshl_add_u64 v[222:223], s[50:51], 0, v[156:157]
	s_mov_b32 m0, s74
	s_nop 0
	global_load_lds_dwordx4 v[222:223], off
	s_mov_b32 m0, s65
	s_nop 0
	global_load_lds_dwordx4 v[224:225], off
	s_waitcnt vmcnt(8)
	s_waitcnt lgkmcnt(0)
	s_barrier
	s_waitcnt lgkmcnt(0)
	v_mfma_f32_16x16x32_f16 v[60:63], v[128:131], v[188:191], v[60:63]
	v_mfma_f32_16x16x32_f16 v[56:59], v[136:139], v[188:191], v[56:59]
	v_mfma_f32_16x16x32_f16 v[44:47], v[128:131], v[196:199], v[44:47]
	v_mfma_f32_16x16x32_f16 v[40:43], v[136:139], v[196:199], v[40:43]
	v_mfma_f32_16x16x32_f16 v[28:31], v[128:131], v[204:207], v[28:31]
	v_mfma_f32_16x16x32_f16 v[24:27], v[136:139], v[204:207], v[24:27]
	v_mfma_f32_16x16x32_f16 v[12:15], v[128:131], v[212:215], v[12:15]
	v_mfma_f32_16x16x32_f16 v[8:11], v[136:139], v[212:215], v[8:11]
	v_mfma_f32_16x16x32_f16 v[60:63], v[132:135], v[192:195], v[60:63]
	v_mfma_f32_16x16x32_f16 v[56:59], v[140:143], v[192:195], v[56:59]
	v_mfma_f32_16x16x32_f16 v[44:47], v[132:135], v[200:203], v[44:47]
	v_mfma_f32_16x16x32_f16 v[40:43], v[140:143], v[200:203], v[40:43]
	v_mfma_f32_16x16x32_f16 v[28:31], v[132:135], v[208:211], v[28:31]
	v_mfma_f32_16x16x32_f16 v[24:27], v[140:143], v[208:211], v[24:27]
	v_mfma_f32_16x16x32_f16 v[12:15], v[132:135], v[216:219], v[12:15]
	v_mfma_f32_16x16x32_f16 v[8:11], v[140:143], v[216:219], v[8:11]
	v_mfma_f32_16x16x32_f16 v[52:55], v[144:147], v[188:191], v[52:55]
	v_mfma_f32_16x16x32_f16 v[48:51], v[152:155], v[188:191], v[48:51]
	v_mfma_f32_16x16x32_f16 v[36:39], v[144:147], v[196:199], v[36:39]
	v_mfma_f32_16x16x32_f16 v[32:35], v[152:155], v[196:199], v[32:35]
	v_mfma_f32_16x16x32_f16 v[20:23], v[144:147], v[204:207], v[20:23]
	v_mfma_f32_16x16x32_f16 v[16:19], v[152:155], v[204:207], v[16:19]
	v_mfma_f32_16x16x32_f16 v[4:7], v[144:147], v[212:215], v[4:7]
	v_mfma_f32_16x16x32_f16 v[0:3], v[152:155], v[212:215], v[0:3]
	v_mfma_f32_16x16x32_f16 v[52:55], v[148:151], v[192:195], v[52:55]
	v_mfma_f32_16x16x32_f16 v[48:51], v[174:177], v[192:195], v[48:51]
	v_mfma_f32_16x16x32_f16 v[36:39], v[148:151], v[200:203], v[36:39]
	v_mfma_f32_16x16x32_f16 v[32:35], v[174:177], v[200:203], v[32:35]
	v_mfma_f32_16x16x32_f16 v[20:23], v[148:151], v[208:211], v[20:23]
	v_mfma_f32_16x16x32_f16 v[16:19], v[174:177], v[208:211], v[16:19]
	v_mfma_f32_16x16x32_f16 v[4:7], v[148:151], v[216:219], v[4:7]
	v_mfma_f32_16x16x32_f16 v[0:3], v[174:177], v[216:219], v[0:3]
	s_barrier
; #define PG8_STAGE(bufoff, gbase, voff) do { _Pragma("unroll") for (int _i = 0; _i < 2; ++_i) \
;         __builtin_amdgcn_global_load_lds((const unsigned*)((const char*)(gbase) + (voff)[_i]), (PG8_LAS unsigned*)(lds + (bufoff) + ldsw + _i * 8192), 16, 0, 0); } while (0)
; #define PG8_LDA(dst, b, h) do { _Pragma("unroll") for (int m = 0; m < 4; ++m) _Pragma("unroll") for (int k = 0; k < 2; ++k) dst[m][k] = *(const PG8_LAS bf16x8*)(lds + PG8_SA(b, h) + aoff + m * 2048 + k * 1024); } while (0)
; #define PG8_LDB(dst, b, h) do { _Pragma("unroll") for (int n = 0; n < 2; ++n) _Pragma("unroll") for (int k = 0; k < 2; ++k) dst[n][k] = *(const PG8_LAS bf16x8*)(lds + PG8_SB(b, h) + boff + n * 2048 + k * 1024); } while (0)
; #define PG8_MMA(ai, bj, At, Bt) do { __builtin_amdgcn_s_setprio(1); _Pragma("unroll") for (int m = 0; m < 4; ++m) _Pragma("unroll") for (int n = 0; n < 2; ++n) _Pragma("unroll") for (int k = 0; k < 2; ++k) \
;         acc[ai][bj][m][n] = mma16<F16>(Bt[n][k], At[m][k], acc[ai][bj][m][n]); __builtin_amdgcn_s_setprio(0); } while (0)
; #define PG8_WAIT_V(n) asm volatile("s_waitcnt vmcnt(" #n ")" ::: "memory")
; #define PG8_WAIT_L(n) asm volatile("s_waitcnt lgkmcnt(" #n ")" ::: "memory")
; #define PG8_BAR __builtin_amdgcn_s_barrier()
; #define PG8_SCHED __builtin_amdgcn_sched_barrier(0)
; template <class Epi, class Sched, bool ALIGN_EPI = false, bool SP2 = false, bool F16 = false>
; __device__ __forceinline__ void gemm_phase(PG8_LAS unsigned char* lds, const Gemm g, const Sched& S, const Epi& E, const int wid_in) {
;     ...
;             PG8_LDB(B0, 1, 0); PG8_LDB(B1, 1, 1); PG8_SCHED; PG8_LDA(At, 1, 0); PG8_STAGE(PG8_SA(0, 1), a2 + hstep, voffA);
;             PG8_WAIT_V(8); PG8_WAIT_L(0); PG8_BAR; PG8_MMA(0, 0, At, B0); PG8_MMA(0, 1, At, B1); PG8_BAR; PG8_SCHED;
	s_add_i32 s53, 0, 0x18000
	s_add_i32 s54, 0, 0x1c000
	v_add_u32_e32 v140, s53, v182
	v_add_u32_e32 v165, s54, v182
	ds_read_b128 v[128:131], v140
	ds_read_b128 v[132:135], v140 offset:1024
	ds_read_b128 v[136:139], v140 offset:2048
	ds_read_b128 v[140:143], v140 offset:3072
	ds_read_b128 v[144:147], v165
	ds_read_b128 v[148:151], v165 offset:1024
	ds_read_b128 v[152:155], v165 offset:2048
	ds_read_b128 v[174:177], v165 offset:3072
	s_add_u32 s50, s50, 0x40000
	s_addc_u32 s51, s51, 0
	s_mov_b32 m0, s66
	v_lshl_add_u64 v[226:227], s[50:51], 0, v[156:157]
	ds_read_b128 v[188:191], v185 offset:32768
	ds_read_b128 v[192:195], v185 offset:33792
	ds_read_b128 v[196:199], v185 offset:34816
	ds_read_b128 v[200:203], v185 offset:35840
	ds_read_b128 v[204:207], v185 offset:36864
	ds_read_b128 v[208:211], v185 offset:37888
	ds_read_b128 v[212:215], v185 offset:38912
	ds_read_b128 v[216:219], v185 offset:39936
	global_load_lds_dwordx4 v[226:227], off
	v_lshl_add_u64 v[226:227], s[50:51], 0, v[160:161]
	s_mov_b32 m0, s67
	s_nop 0
	global_load_lds_dwordx4 v[226:227], off
	s_waitcnt vmcnt(8)
	s_waitcnt lgkmcnt(0)
	s_barrier
	s_waitcnt lgkmcnt(0)
	v_mfma_f32_16x16x32_f16 v[124:127], v[128:131], v[188:191], v[124:127]
	v_mfma_f32_16x16x32_f16 v[120:123], v[136:139], v[188:191], v[120:123]
	v_mfma_f32_16x16x32_f16 v[108:111], v[128:131], v[196:199], v[108:111]
	v_mfma_f32_16x16x32_f16 v[104:107], v[136:139], v[196:199], v[104:107]
	v_mfma_f32_16x16x32_f16 v[92:95], v[128:131], v[204:207], v[92:95]
	v_mfma_f32_16x16x32_f16 v[88:91], v[136:139], v[204:207], v[88:91]
	v_mfma_f32_16x16x32_f16 v[76:79], v[128:131], v[212:215], v[76:79]
	v_mfma_f32_16x16x32_f16 v[72:75], v[136:139], v[212:215], v[72:75]
	v_mfma_f32_16x16x32_f16 v[124:127], v[132:135], v[192:195], v[124:127]
	v_mfma_f32_16x16x32_f16 v[120:123], v[140:143], v[192:195], v[120:123]
	v_mfma_f32_16x16x32_f16 v[108:111], v[132:135], v[200:203], v[108:111]
	v_mfma_f32_16x16x32_f16 v[104:107], v[140:143], v[200:203], v[104:107]
	v_mfma_f32_16x16x32_f16 v[92:95], v[132:135], v[208:211], v[92:95]
	v_mfma_f32_16x16x32_f16 v[88:91], v[140:143], v[208:211], v[88:91]
	v_mfma_f32_16x16x32_f16 v[76:79], v[132:135], v[216:219], v[76:79]
	v_mfma_f32_16x16x32_f16 v[72:75], v[140:143], v[216:219], v[72:75]
	v_mfma_f32_16x16x32_f16 v[116:119], v[144:147], v[188:191], v[116:119]
	v_mfma_f32_16x16x32_f16 v[112:115], v[152:155], v[188:191], v[112:115]
	v_mfma_f32_16x16x32_f16 v[100:103], v[144:147], v[196:199], v[100:103]
	v_mfma_f32_16x16x32_f16 v[96:99], v[152:155], v[196:199], v[96:99]
	v_mfma_f32_16x16x32_f16 v[84:87], v[144:147], v[204:207], v[84:87]
	v_mfma_f32_16x16x32_f16 v[80:83], v[152:155], v[204:207], v[80:83]
	v_mfma_f32_16x16x32_f16 v[68:71], v[144:147], v[212:215], v[68:71]
	v_mfma_f32_16x16x32_f16 v[64:67], v[152:155], v[212:215], v[64:67]
	v_mfma_f32_16x16x32_f16 v[116:119], v[148:151], v[192:195], v[116:119]
	v_mfma_f32_16x16x32_f16 v[112:115], v[174:177], v[192:195], v[112:115]
	v_mfma_f32_16x16x32_f16 v[100:103], v[148:151], v[200:203], v[100:103]
	v_mfma_f32_16x16x32_f16 v[96:99], v[174:177], v[200:203], v[96:99]
	v_mfma_f32_16x16x32_f16 v[84:87], v[148:151], v[208:211], v[84:87]
	v_mfma_f32_16x16x32_f16 v[80:83], v[174:177], v[208:211], v[80:83]
	v_mfma_f32_16x16x32_f16 v[68:71], v[148:151], v[216:219], v[68:71]
	v_mfma_f32_16x16x32_f16 v[64:67], v[174:177], v[216:219], v[64:67]
	s_barrier
; #define PG8_STAGE(bufoff, gbase, voff) do { _Pragma("unroll") for (int _i = 0; _i < 2; ++_i) \
;         __builtin_amdgcn_global_load_lds((const unsigned*)((const char*)(gbase) + (voff)[_i]), (PG8_LAS unsigned*)(lds + (bufoff) + ldsw + _i * 8192), 16, 0, 0); } while (0)
; #define PG8_LDA(dst, b, h) do { _Pragma("unroll") for (int m = 0; m < 4; ++m) _Pragma("unroll") for (int k = 0; k < 2; ++k) dst[m][k] = *(const PG8_LAS bf16x8*)(lds + PG8_SA(b, h) + aoff + m * 2048 + k * 1024); } while (0)
; #define PG8_MMA(ai, bj, At, Bt) do { __builtin_amdgcn_s_setprio(1); _Pragma("unroll") for (int m = 0; m < 4; ++m) _Pragma("unroll") for (int n = 0; n < 2; ++n) _Pragma("unroll") for (int k = 0; k < 2; ++k) \
;         acc[ai][bj][m][n] = mma16<F16>(Bt[n][k], At[m][k], acc[ai][bj][m][n]); __builtin_amdgcn_s_setprio(0); } while (0)
; #define PG8_WAIT_V(n) asm volatile("s_waitcnt vmcnt(" #n ")" ::: "memory")
; #define PG8_WAIT_L(n) asm volatile("s_waitcnt lgkmcnt(" #n ")" ::: "memory")
; #define PG8_BAR __builtin_amdgcn_s_barrier()
; #define PG8_SCHED __builtin_amdgcn_sched_barrier(0)
; template <class Epi, class Sched, bool ALIGN_EPI = false, bool SP2 = false, bool F16 = false>
; __device__ __forceinline__ void gemm_phase(PG8_LAS unsigned char* lds, const Gemm g, const Sched& S, const Epi& E, const int wid_in) {
;     ...
;         for (int t = 0; t < nt; t += 2) {
;             const bool last = (t == nt - 2);
;     ...
;             PG8_LDA(At, 1, 1); PG8_STAGE(PG8_SB(1, 0), b3, voffB); PG8_STAGE(PG8_SB(1, 1), b3 + hstep, voffB); PG8_STAGE(PG8_SA(1, 0), a3, voffA);
;             PG8_WAIT_V(8); PG8_WAIT_L(0); PG8_BAR; PG8_MMA(1, 0, At, B0); PG8_MMA(1, 1, At, B1); PG8_BAR; PG8_SCHED;
	s_add_i32 s50, s53, s68
	v_lshl_add_u64 v[178:179], v[178:179], 0, s[20:21]
	s_mov_b32 m0, s50
	ds_read_b128 v[188:191], v185 offset:49152
	ds_read_b128 v[192:195], v185 offset:50176
	ds_read_b128 v[196:199], v185 offset:51200
	ds_read_b128 v[200:203], v185 offset:52224
	ds_read_b128 v[204:207], v185 offset:53248
	ds_read_b128 v[208:211], v185 offset:54272
	ds_read_b128 v[212:215], v185 offset:55296
	ds_read_b128 v[216:219], v185 offset:56320
	global_load_lds_dwordx4 v[178:179], off
	s_add_i32 m0, s50, 0x2000
	s_add_u32 s48, s48, 0x40080
	v_lshl_add_u64 v[178:179], v[220:221], 0, s[20:21]
	s_addc_u32 s49, s49, 0
	s_add_i32 s50, s54, s68
	global_load_lds_dwordx4 v[178:179], off
	v_lshl_add_u64 v[178:179], s[48:49], 0, v[158:159]
	s_mov_b32 m0, s50
	s_nop 0
	global_load_lds_dwordx4 v[178:179], off
	v_lshl_add_u64 v[178:179], s[48:49], 0, v[162:163]
	s_add_i32 m0, s50, 0x2000
	s_nop 0
	global_load_lds_dwordx4 v[178:179], off
	v_lshl_add_u64 v[178:179], v[222:223], 0, s[20:21]
	s_mov_b32 m0, s75
	s_nop 0
	global_load_lds_dwordx4 v[178:179], off
	v_lshl_add_u64 v[178:179], v[224:225], 0, s[20:21]
	s_mov_b32 m0, s89
	s_nop 0
	global_load_lds_dwordx4 v[178:179], off
	s_waitcnt vmcnt(8)
	s_waitcnt lgkmcnt(0)
	s_barrier
	s_waitcnt lgkmcnt(0)
	v_mfma_f32_16x16x32_f16 v[60:63], v[128:131], v[188:191], v[60:63]
	v_mfma_f32_16x16x32_f16 v[56:59], v[136:139], v[188:191], v[56:59]
	v_mfma_f32_16x16x32_f16 v[44:47], v[128:131], v[196:199], v[44:47]
	v_mfma_f32_16x16x32_f16 v[40:43], v[136:139], v[196:199], v[40:43]
	v_mfma_f32_16x16x32_f16 v[28:31], v[128:131], v[204:207], v[28:31]
	v_mfma_f32_16x16x32_f16 v[24:27], v[136:139], v[204:207], v[24:27]
	v_mfma_f32_16x16x32_f16 v[12:15], v[128:131], v[212:215], v[12:15]
	v_mfma_f32_16x16x32_f16 v[8:11], v[136:139], v[212:215], v[8:11]
	v_mfma_f32_16x16x32_f16 v[60:63], v[132:135], v[192:195], v[60:63]
	v_mfma_f32_16x16x32_f16 v[56:59], v[140:143], v[192:195], v[56:59]
	v_mfma_f32_16x16x32_f16 v[44:47], v[132:135], v[200:203], v[44:47]
	v_mfma_f32_16x16x32_f16 v[40:43], v[140:143], v[200:203], v[40:43]
	v_mfma_f32_16x16x32_f16 v[28:31], v[132:135], v[208:211], v[28:31]
	v_mfma_f32_16x16x32_f16 v[24:27], v[140:143], v[208:211], v[24:27]
	v_mfma_f32_16x16x32_f16 v[12:15], v[132:135], v[216:219], v[12:15]
	v_mfma_f32_16x16x32_f16 v[8:11], v[140:143], v[216:219], v[8:11]
	v_mfma_f32_16x16x32_f16 v[52:55], v[144:147], v[188:191], v[52:55]
	v_mfma_f32_16x16x32_f16 v[48:51], v[152:155], v[188:191], v[48:51]
	v_mfma_f32_16x16x32_f16 v[36:39], v[144:147], v[196:199], v[36:39]
	v_mfma_f32_16x16x32_f16 v[32:35], v[152:155], v[196:199], v[32:35]
	v_mfma_f32_16x16x32_f16 v[20:23], v[144:147], v[204:207], v[20:23]
	v_mfma_f32_16x16x32_f16 v[16:19], v[152:155], v[204:207], v[16:19]
	v_mfma_f32_16x16x32_f16 v[4:7], v[144:147], v[212:215], v[4:7]
	v_mfma_f32_16x16x32_f16 v[0:3], v[152:155], v[212:215], v[0:3]
	v_mfma_f32_16x16x32_f16 v[52:55], v[148:151], v[192:195], v[52:55]
	v_mfma_f32_16x16x32_f16 v[48:51], v[174:177], v[192:195], v[48:51]
	v_mfma_f32_16x16x32_f16 v[36:39], v[148:151], v[200:203], v[36:39]
	v_mfma_f32_16x16x32_f16 v[32:35], v[174:177], v[200:203], v[32:35]
	v_mfma_f32_16x16x32_f16 v[20:23], v[148:151], v[208:211], v[20:23]
	v_mfma_f32_16x16x32_f16 v[16:19], v[174:177], v[208:211], v[16:19]
	v_mfma_f32_16x16x32_f16 v[4:7], v[148:151], v[216:219], v[4:7]
	v_mfma_f32_16x16x32_f16 v[0:3], v[174:177], v[216:219], v[0:3]
	s_barrier
	s_add_i32 s52, s52, 2
	s_add_u32 s46, s46, 0x100
	s_addc_u32 s47, s47, 0
	s_add_u32 s42, s42, 0x100
	s_addc_u32 s43, s43, 0
	s_cmp_gt_u32 s52, 13
	s_cbranch_scc0 .LBB0_902
	s_setprio 0
	s_and_b64 vcc, exec, s[16:17]
	s_cbranch_vccz .LBB0_905
	s_barrier

; #define PG8_STAGE(bufoff, gbase, voff) do { _Pragma("unroll") for (int _i = 0; _i < 2; ++_i) \
;         __builtin_amdgcn_global_load_lds((const unsigned*)((const char*)(gbase) + (voff)[_i]), (PG8_LAS unsigned*)(lds + (bufoff) + ldsw + _i * 8192), 16, 0, 0); } while (0)
; #define PG8_LDA(dst, b, h) do { _Pragma("unroll") for (int m = 0; m < 4; ++m) _Pragma("unroll") for (int k = 0; k < 2; ++k) dst[m][k] = *(const PG8_LAS bf16x8*)(lds + PG8_SA(b, h) + aoff + m * 2048 + k * 1024); } while (0)
; #define PG8_LDB(dst, b, h) do { _Pragma("unroll") for (int n = 0; n < 2; ++n) _Pragma("unroll") for (int k = 0; k < 2; ++k) dst[n][k] = *(const PG8_LAS bf16x8*)(lds + PG8_SB(b, h) + boff + n * 2048 + k * 1024); } while (0)
; #define PG8_WAIT_V(n) asm volatile("s_waitcnt vmcnt(" #n ")" ::: "memory")
; #define PG8_WAIT_L(n) asm volatile("s_waitcnt lgkmcnt(" #n ")" ::: "memory")
; #define PG8_BAR __builtin_amdgcn_s_barrier()
; #define PG8_SCHED __builtin_amdgcn_sched_barrier(0)
; template <class Epi, class Sched, bool ALIGN_EPI = false, bool SP2 = false, bool F16 = false>
; __device__ __forceinline__ void gemm_phase(PG8_LAS unsigned char* lds, const Gemm g, const Sched& S, const Epi& E, const int wid_in) {
;     ...
;         const char* nA = has_next ? (const char*)g.A + (size_t)nxt.pm * tstep : cA; const char* nB = has_next ? (const char*)g.Bt + (size_t)nxt.pn * tstep : cB;
;         for (int t = 0; t < nt; t += 2) {
;             const bool last = (t == nt - 2);
;             const char* a1 = cA + (size_t)(t + 1) * kstep;
;             const char* a2 = last ? nA : cA + (size_t)(t + 2) * kstep; const char* b2 = last ? nB : cB + (size_t)(t + 2) * kstep;
;             const char* a3 = a2 + kstep; const char* b3 = b2 + kstep;
;             if (last && has_next) S.a_ready(nxt);
;             if constexpr (SP2) {
;             PG8_LDB(B0, 0, 0); PG8_LDB(B1, 0, 1); PG8_SCHED; PG8_LDA(At, 0, 0); PG8_STAGE(PG8_SA(1, 1), a1 + hstep, voffA);
;             PG8_WAIT_V(8); PG8_WAIT_L(0); PG8_BAR; PG8_MMA(0, 0, At, B0); PG8_MMA(0, 1, At, B1); PG8_BAR; PG8_SCHED;
;     ...
; #pragma unroll
;         for (int a = 0; a < 2; ++a)
; #pragma unroll
;             for (int b = 0; b < 2; ++b)
; #pragma unroll
;                 for (int m = 0; m < 4; ++m)
; #pragma unroll
;                     for (int n = 0; n < 2; ++n) acc[a][b][m][n] = (f32x4){0.f, 0.f, 0.f, 0.f};
.LBB0_1164:
	s_ashr_i32 s35, s34, 31
	s_lshl_b64 s[36:37], s[34:35], 19
	s_add_u32 s36, s15, s36
	s_addc_u32 s37, s19, s37
	s_and_b64 s[42:43], s[10:11], exec
	s_cselect_b32 s35, s37, s49
	s_cselect_b32 s42, s36, s48
	s_ashr_i32 s31, s30, 31
	s_lshl_b64 s[44:45], s[30:31], 19
	s_add_u32 s44, s21, s44
	s_addc_u32 s45, s40, s45
	s_and_b64 s[52:53], s[10:11], exec
	s_cselect_b32 s31, s45, s51
	s_cselect_b32 s43, s44, s50
	s_add_u32 s48, s48, 0x40080
	s_addc_u32 s49, s49, 0
	s_add_u32 s47, s50, 0x100
	v_mov_b32_e32 v0, 0
	s_addc_u32 s63, s51, 0
	s_mov_b32 s64, -2
	v_mov_b32_e32 v1, v0
	v_mov_b32_e32 v2, v0
	v_mov_b32_e32 v3, v0
	v_mov_b32_e32 v4, v0
	v_mov_b32_e32 v5, v0
	v_mov_b32_e32 v6, v0
	v_mov_b32_e32 v7, v0
	v_mov_b32_e32 v16, v0
	v_mov_b32_e32 v17, v0
	v_mov_b32_e32 v18, v0
	v_mov_b32_e32 v19, v0
	v_mov_b32_e32 v20, v0
	v_mov_b32_e32 v21, v0
	v_mov_b32_e32 v22, v0
	v_mov_b32_e32 v23, v0
	v_mov_b32_e32 v32, v0
	v_mov_b32_e32 v33, v0
	v_mov_b32_e32 v34, v0
	v_mov_b32_e32 v35, v0
	v_mov_b32_e32 v36, v0
	v_mov_b32_e32 v37, v0
	v_mov_b32_e32 v38, v0
	v_mov_b32_e32 v39, v0
	v_mov_b32_e32 v48, v0
	v_mov_b32_e32 v49, v0
	v_mov_b32_e32 v50, v0
	v_mov_b32_e32 v51, v0
	v_mov_b32_e32 v52, v0
	v_mov_b32_e32 v53, v0
	v_mov_b32_e32 v54, v0
	v_mov_b32_e32 v55, v0
	v_mov_b32_e32 v8, v0
	v_mov_b32_e32 v9, v0
	v_mov_b32_e32 v10, v0
	v_mov_b32_e32 v11, v0
	v_mov_b32_e32 v12, v0
	v_mov_b32_e32 v13, v0
	v_mov_b32_e32 v14, v0
	v_mov_b32_e32 v15, v0
	v_mov_b32_e32 v24, v0
	v_mov_b32_e32 v25, v0
	v_mov_b32_e32 v26, v0
	v_mov_b32_e32 v27, v0
	v_mov_b32_e32 v28, v0
	v_mov_b32_e32 v29, v0
	v_mov_b32_e32 v30, v0
	v_mov_b32_e32 v31, v0
	v_mov_b32_e32 v40, v0
	v_mov_b32_e32 v41, v0
	v_mov_b32_e32 v42, v0
	v_mov_b32_e32 v43, v0
	v_mov_b32_e32 v44, v0
	v_mov_b32_e32 v45, v0
	v_mov_b32_e32 v46, v0
	v_mov_b32_e32 v47, v0
	v_mov_b32_e32 v56, v0
	v_mov_b32_e32 v57, v0
	v_mov_b32_e32 v58, v0
	v_mov_b32_e32 v59, v0
	v_mov_b32_e32 v60, v0
	v_mov_b32_e32 v61, v0
	v_mov_b32_e32 v62, v0
	v_mov_b32_e32 v63, v0
	v_mov_b32_e32 v64, v0
	v_mov_b32_e32 v65, v0
	v_mov_b32_e32 v66, v0
	v_mov_b32_e32 v67, v0
	v_mov_b32_e32 v68, v0
	v_mov_b32_e32 v69, v0
	v_mov_b32_e32 v70, v0
	v_mov_b32_e32 v71, v0
	v_mov_b32_e32 v80, v0
	v_mov_b32_e32 v81, v0
	v_mov_b32_e32 v82, v0
	v_mov_b32_e32 v83, v0
	v_mov_b32_e32 v84, v0
	v_mov_b32_e32 v85, v0
	v_mov_b32_e32 v86, v0
	v_mov_b32_e32 v87, v0
	v_mov_b32_e32 v96, v0
	v_mov_b32_e32 v97, v0
	v_mov_b32_e32 v98, v0
	v_mov_b32_e32 v99, v0
	v_mov_b32_e32 v100, v0
	v_mov_b32_e32 v101, v0
	v_mov_b32_e32 v102, v0
	v_mov_b32_e32 v103, v0
	v_mov_b32_e32 v112, v0
	v_mov_b32_e32 v113, v0
	v_mov_b32_e32 v114, v0
	v_mov_b32_e32 v115, v0
	v_mov_b32_e32 v116, v0
	v_mov_b32_e32 v117, v0
	v_mov_b32_e32 v118, v0
	v_mov_b32_e32 v119, v0
	v_mov_b32_e32 v72, v0
	v_mov_b32_e32 v73, v0
	v_mov_b32_e32 v74, v0
	v_mov_b32_e32 v75, v0
	v_mov_b32_e32 v76, v0
	v_mov_b32_e32 v77, v0
	v_mov_b32_e32 v78, v0
	v_mov_b32_e32 v79, v0
	v_mov_b32_e32 v88, v0
	v_mov_b32_e32 v89, v0
	v_mov_b32_e32 v90, v0
	v_mov_b32_e32 v91, v0
	v_mov_b32_e32 v92, v0
	v_mov_b32_e32 v93, v0
	v_mov_b32_e32 v94, v0
	v_mov_b32_e32 v95, v0
	v_mov_b32_e32 v104, v0
	v_mov_b32_e32 v105, v0
	v_mov_b32_e32 v106, v0
	v_mov_b32_e32 v107, v0
	v_mov_b32_e32 v108, v0
	v_mov_b32_e32 v109, v0
	v_mov_b32_e32 v110, v0
	v_mov_b32_e32 v111, v0
	v_mov_b32_e32 v120, v0
	v_mov_b32_e32 v121, v0
	v_mov_b32_e32 v122, v0
	v_mov_b32_e32 v123, v0
	v_mov_b32_e32 v124, v0
	v_mov_b32_e32 v125, v0
	v_mov_b32_e32 v126, v0
	v_mov_b32_e32 v127, v0
	s_cmp_ge_u32 s3, 4
	s_cbranch_scc0 .Lgsp_7
	s_setprio 1
.Lgsp_7:
.LBB0_1165:
	ds_read_b128 v[128:131], v189
	ds_read_b128 v[132:135], v189 offset:1024
	ds_read_b128 v[136:139], v189 offset:2048
	ds_read_b128 v[140:143], v189 offset:3072
	ds_read_b128 v[144:147], v190
	ds_read_b128 v[148:151], v190 offset:1024
	ds_read_b128 v[168:171], v190 offset:2048
	ds_read_b128 v[172:175], v190 offset:3072
	s_add_u32 s50, s48, 0xfffc0080
	s_addc_u32 s51, s49, -1
	s_cmp_eq_u32 s64, 12
	s_cselect_b32 s53, s35, s51
	s_cselect_b32 s52, s42, s50
	s_cselect_b32 s51, s31, s63
	s_cselect_b32 s50, s43, s47
	v_lshl_add_u64 v[184:185], s[48:49], 0, v[160:161]
	s_add_i32 m0, s74, 0xc000
	ds_read_b128 v[176:179], v191
	ds_read_b128 v[180:183], v191 offset:1024
	ds_read_b128 v[192:195], v191 offset:2048
	ds_read_b128 v[196:199], v191 offset:3072
	ds_read_b128 v[200:203], v191 offset:4096
	ds_read_b128 v[204:207], v191 offset:5120
	ds_read_b128 v[208:211], v191 offset:6144
	ds_read_b128 v[212:215], v191 offset:7168
	global_load_lds_dwordx4 v[184:185], off
	v_lshl_add_u64 v[184:185], s[48:49], 0, v[162:163]
	s_add_i32 m0, s74, 0xe000
	s_nop 0
	global_load_lds_dwordx4 v[184:185], off
	s_waitcnt vmcnt(8)
	s_waitcnt lgkmcnt(0)
	s_barrier
; #define PG8_STAGE(bufoff, gbase, voff) do { _Pragma("unroll") for (int _i = 0; _i < 2; ++_i) \
;         __builtin_amdgcn_global_load_lds((const unsigned*)((const char*)(gbase) + (voff)[_i]), (PG8_LAS unsigned*)(lds + (bufoff) + ldsw + _i * 8192), 16, 0, 0); } while (0)
; #define PG8_LDA(dst, b, h) do { _Pragma("unroll") for (int m = 0; m < 4; ++m) _Pragma("unroll") for (int k = 0; k < 2; ++k) dst[m][k] = *(const PG8_LAS bf16x8*)(lds + PG8_SA(b, h) + aoff + m * 2048 + k * 1024); } while (0)
; #define PG8_MMA(ai, bj, At, Bt) do { __builtin_amdgcn_s_setprio(1); _Pragma("unroll") for (int m = 0; m < 4; ++m) _Pragma("unroll") for (int n = 0; n < 2; ++n) _Pragma("unroll") for (int k = 0; k < 2; ++k) \
;         acc[ai][bj][m][n] = mma16<F16>(Bt[n][k], At[m][k], acc[ai][bj][m][n]); __builtin_amdgcn_s_setprio(0); } while (0)
; #define PG8_WAIT_V(n) asm volatile("s_waitcnt vmcnt(" #n ")" ::: "memory")
; #define PG8_WAIT_L(n) asm volatile("s_waitcnt lgkmcnt(" #n ")" ::: "memory")
; #define PG8_BAR __builtin_amdgcn_s_barrier()
; #define PG8_SCHED __builtin_amdgcn_sched_barrier(0)
; template <class Epi, class Sched, bool ALIGN_EPI = false, bool SP2 = false, bool F16 = false>
; __device__ __forceinline__ void gemm_phase(PG8_LAS unsigned char* lds, const Gemm g, const Sched& S, const Epi& E, const int wid_in) {
;     ...
;             PG8_WAIT_V(8); PG8_WAIT_L(0); PG8_BAR; PG8_MMA(0, 0, At, B0); PG8_MMA(0, 1, At, B1); PG8_BAR; PG8_SCHED;
;             PG8_LDA(At, 0, 1); PG8_STAGE(PG8_SB(0, 0), b2, voffB); PG8_STAGE(PG8_SB(0, 1), b2 + hstep, voffB); PG8_STAGE(PG8_SA(0, 0), a2, voffA);
;             PG8_WAIT_V(8); PG8_WAIT_L(0); PG8_BAR; PG8_MMA(1, 0, At, B0); PG8_MMA(1, 1, At, B1); PG8_BAR; PG8_SCHED;
	s_waitcnt lgkmcnt(0)
	v_mfma_f32_16x16x32_bf16 v[124:127], v[128:131], v[176:179], v[124:127]
	v_mfma_f32_16x16x32_bf16 v[120:123], v[136:139], v[176:179], v[120:123]
	v_mfma_f32_16x16x32_bf16 v[108:111], v[128:131], v[192:195], v[108:111]
	v_mfma_f32_16x16x32_bf16 v[104:107], v[136:139], v[192:195], v[104:107]
	v_mfma_f32_16x16x32_bf16 v[92:95], v[128:131], v[200:203], v[92:95]
	v_mfma_f32_16x16x32_bf16 v[88:91], v[136:139], v[200:203], v[88:91]
	v_mfma_f32_16x16x32_bf16 v[76:79], v[128:131], v[208:211], v[76:79]
	v_mfma_f32_16x16x32_bf16 v[72:75], v[136:139], v[208:211], v[72:75]
	v_mfma_f32_16x16x32_bf16 v[124:127], v[132:135], v[180:183], v[124:127]
	v_mfma_f32_16x16x32_bf16 v[120:123], v[140:143], v[180:183], v[120:123]
	v_mfma_f32_16x16x32_bf16 v[108:111], v[132:135], v[196:199], v[108:111]
	v_mfma_f32_16x16x32_bf16 v[104:107], v[140:143], v[196:199], v[104:107]
	v_mfma_f32_16x16x32_bf16 v[92:95], v[132:135], v[204:207], v[92:95]
	v_mfma_f32_16x16x32_bf16 v[88:91], v[140:143], v[204:207], v[88:91]
	v_mfma_f32_16x16x32_bf16 v[76:79], v[132:135], v[212:215], v[76:79]
	v_mfma_f32_16x16x32_bf16 v[72:75], v[140:143], v[212:215], v[72:75]
	v_mfma_f32_16x16x32_bf16 v[116:119], v[144:147], v[176:179], v[116:119]
	v_mfma_f32_16x16x32_bf16 v[112:115], v[168:171], v[176:179], v[112:115]
	v_mfma_f32_16x16x32_bf16 v[100:103], v[144:147], v[192:195], v[100:103]
	v_mfma_f32_16x16x32_bf16 v[96:99], v[168:171], v[192:195], v[96:99]
	v_mfma_f32_16x16x32_bf16 v[84:87], v[144:147], v[200:203], v[84:87]
	v_mfma_f32_16x16x32_bf16 v[80:83], v[168:171], v[200:203], v[80:83]
	v_mfma_f32_16x16x32_bf16 v[68:71], v[144:147], v[208:211], v[68:71]
	v_mfma_f32_16x16x32_bf16 v[64:67], v[168:171], v[208:211], v[64:67]
	v_mfma_f32_16x16x32_bf16 v[116:119], v[148:151], v[180:183], v[116:119]
	v_mfma_f32_16x16x32_bf16 v[112:115], v[172:175], v[180:183], v[112:115]
	v_mfma_f32_16x16x32_bf16 v[100:103], v[148:151], v[196:199], v[100:103]
	v_mfma_f32_16x16x32_bf16 v[96:99], v[172:175], v[196:199], v[96:99]
	v_mfma_f32_16x16x32_bf16 v[84:87], v[148:151], v[204:207], v[84:87]
	v_mfma_f32_16x16x32_bf16 v[80:83], v[172:175], v[204:207], v[80:83]
	v_mfma_f32_16x16x32_bf16 v[68:71], v[148:151], v[212:215], v[68:71]
	v_mfma_f32_16x16x32_bf16 v[64:67], v[172:175], v[212:215], v[64:67]
	s_barrier
	s_add_i32 s65, s60, s68
	v_lshl_add_u64 v[184:185], s[50:51], 0, v[154:155]
	s_mov_b32 m0, s65
	ds_read_b128 v[176:179], v191 offset:16384
	ds_read_b128 v[180:183], v191 offset:17408
	ds_read_b128 v[192:195], v191 offset:18432
	ds_read_b128 v[196:199], v191 offset:19456
	ds_read_b128 v[200:203], v191 offset:20480
	ds_read_b128 v[204:207], v191 offset:21504
	ds_read_b128 v[208:211], v191 offset:22528
	ds_read_b128 v[212:215], v191 offset:23552
	global_load_lds_dwordx4 v[184:185], off
	s_add_i32 m0, s65, 0x2000
	s_add_u32 s66, s50, 0x40000
	v_lshl_add_u64 v[216:217], s[50:51], 0, v[158:159]
	s_addc_u32 s67, s51, 0
	s_add_i32 s65, s61, s68
	global_load_lds_dwordx4 v[216:217], off
	v_lshl_add_u64 v[218:219], s[66:67], 0, v[154:155]
	s_mov_b32 m0, s65
	v_lshl_add_u64 v[220:221], s[52:53], 0, v[156:157]
	global_load_lds_dwordx4 v[218:219], off
	v_lshl_add_u64 v[218:219], s[66:67], 0, v[158:159]
	s_add_i32 m0, s65, 0x2000
	s_nop 0
	global_load_lds_dwordx4 v[218:219], off
	v_lshl_add_u64 v[218:219], s[52:53], 0, v[152:153]
	s_mov_b32 m0, s74
	s_nop 0
	global_load_lds_dwordx4 v[218:219], off
	s_mov_b32 m0, s41
	s_nop 0
	global_load_lds_dwordx4 v[220:221], off
	s_waitcnt vmcnt(8)
	s_waitcnt lgkmcnt(0)
	s_barrier
	s_waitcnt lgkmcnt(0)
	v_mfma_f32_16x16x32_bf16 v[60:63], v[128:131], v[176:179], v[60:63]
	v_mfma_f32_16x16x32_bf16 v[56:59], v[136:139], v[176:179], v[56:59]
	v_mfma_f32_16x16x32_bf16 v[44:47], v[128:131], v[192:195], v[44:47]
	v_mfma_f32_16x16x32_bf16 v[40:43], v[136:139], v[192:195], v[40:43]
	v_mfma_f32_16x16x32_bf16 v[28:31], v[128:131], v[200:203], v[28:31]
	v_mfma_f32_16x16x32_bf16 v[24:27], v[136:139], v[200:203], v[24:27]
	v_mfma_f32_16x16x32_bf16 v[12:15], v[128:131], v[208:211], v[12:15]
	v_mfma_f32_16x16x32_bf16 v[8:11], v[136:139], v[208:211], v[8:11]
	v_mfma_f32_16x16x32_bf16 v[60:63], v[132:135], v[180:183], v[60:63]
	v_mfma_f32_16x16x32_bf16 v[56:59], v[140:143], v[180:183], v[56:59]
	v_mfma_f32_16x16x32_bf16 v[44:47], v[132:135], v[196:199], v[44:47]
	v_mfma_f32_16x16x32_bf16 v[40:43], v[140:143], v[196:199], v[40:43]
	v_mfma_f32_16x16x32_bf16 v[28:31], v[132:135], v[204:207], v[28:31]
	v_mfma_f32_16x16x32_bf16 v[24:27], v[140:143], v[204:207], v[24:27]
	v_mfma_f32_16x16x32_bf16 v[12:15], v[132:135], v[212:215], v[12:15]
	v_mfma_f32_16x16x32_bf16 v[8:11], v[140:143], v[212:215], v[8:11]
	v_mfma_f32_16x16x32_bf16 v[52:55], v[144:147], v[176:179], v[52:55]
	v_mfma_f32_16x16x32_bf16 v[48:51], v[168:171], v[176:179], v[48:51]
	v_mfma_f32_16x16x32_bf16 v[36:39], v[144:147], v[192:195], v[36:39]
	v_mfma_f32_16x16x32_bf16 v[32:35], v[168:171], v[192:195], v[32:35]
	v_mfma_f32_16x16x32_bf16 v[20:23], v[144:147], v[200:203], v[20:23]
	v_mfma_f32_16x16x32_bf16 v[16:19], v[168:171], v[200:203], v[16:19]
	v_mfma_f32_16x16x32_bf16 v[4:7], v[144:147], v[208:211], v[4:7]
	v_mfma_f32_16x16x32_bf16 v[0:3], v[168:171], v[208:211], v[0:3]
	v_mfma_f32_16x16x32_bf16 v[52:55], v[148:151], v[180:183], v[52:55]
	v_mfma_f32_16x16x32_bf16 v[48:51], v[172:175], v[180:183], v[48:51]
	v_mfma_f32_16x16x32_bf16 v[36:39], v[148:151], v[196:199], v[36:39]
	v_mfma_f32_16x16x32_bf16 v[32:35], v[172:175], v[196:199], v[32:35]
	v_mfma_f32_16x16x32_bf16 v[20:23], v[148:151], v[204:207], v[20:23]
	v_mfma_f32_16x16x32_bf16 v[16:19], v[172:175], v[204:207], v[16:19]
	v_mfma_f32_16x16x32_bf16 v[4:7], v[148:151], v[212:215], v[4:7]
	v_mfma_f32_16x16x32_bf16 v[0:3], v[172:175], v[212:215], v[0:3]
	s_barrier
; #define PG8_STAGE(bufoff, gbase, voff) do { _Pragma("unroll") for (int _i = 0; _i < 2; ++_i) \
;         __builtin_amdgcn_global_load_lds((const unsigned*)((const char*)(gbase) + (voff)[_i]), (PG8_LAS unsigned*)(lds + (bufoff) + ldsw + _i * 8192), 16, 0, 0); } while (0)
; #define PG8_LDA(dst, b, h) do { _Pragma("unroll") for (int m = 0; m < 4; ++m) _Pragma("unroll") for (int k = 0; k < 2; ++k) dst[m][k] = *(const PG8_LAS bf16x8*)(lds + PG8_SA(b, h) + aoff + m * 2048 + k * 1024); } while (0)
; #define PG8_LDB(dst, b, h) do { _Pragma("unroll") for (int n = 0; n < 2; ++n) _Pragma("unroll") for (int k = 0; k < 2; ++k) dst[n][k] = *(const PG8_LAS bf16x8*)(lds + PG8_SB(b, h) + boff + n * 2048 + k * 1024); } while (0)
; #define PG8_MMA(ai, bj, At, Bt) do { __builtin_amdgcn_s_setprio(1); _Pragma("unroll") for (int m = 0; m < 4; ++m) _Pragma("unroll") for (int n = 0; n < 2; ++n) _Pragma("unroll") for (int k = 0; k < 2; ++k) \
;         acc[ai][bj][m][n] = mma16<F16>(Bt[n][k], At[m][k], acc[ai][bj][m][n]); __builtin_amdgcn_s_setprio(0); } while (0)
; #define PG8_WAIT_V(n) asm volatile("s_waitcnt vmcnt(" #n ")" ::: "memory")
; #define PG8_WAIT_L(n) asm volatile("s_waitcnt lgkmcnt(" #n ")" ::: "memory")
; #define PG8_BAR __builtin_amdgcn_s_barrier()
; #define PG8_SCHED __builtin_amdgcn_sched_barrier(0)
; template <class Epi, class Sched, bool ALIGN_EPI = false, bool SP2 = false, bool F16 = false>
; __device__ __forceinline__ void gemm_phase(PG8_LAS unsigned char* lds, const Gemm g, const Sched& S, const Epi& E, const int wid_in) {
;     ...
;             PG8_LDB(B0, 1, 0); PG8_LDB(B1, 1, 1); PG8_SCHED; PG8_LDA(At, 1, 0); PG8_STAGE(PG8_SA(0, 1), a2 + hstep, voffA);
;             PG8_WAIT_V(8); PG8_WAIT_L(0); PG8_BAR; PG8_MMA(0, 0, At, B0); PG8_MMA(0, 1, At, B1); PG8_BAR; PG8_SCHED;
	s_add_i32 s65, 0, 0x18000
	s_add_i32 s66, 0, 0x1c000
	v_add_u32_e32 v140, s65, v188
	v_add_u32_e32 v172, s66, v188
	ds_read_b128 v[128:131], v140
	ds_read_b128 v[132:135], v140 offset:1024
	ds_read_b128 v[136:139], v140 offset:2048
	ds_read_b128 v[140:143], v140 offset:3072
	ds_read_b128 v[144:147], v172
	ds_read_b128 v[148:151], v172 offset:1024
	ds_read_b128 v[168:171], v172 offset:2048
	ds_read_b128 v[172:175], v172 offset:3072
	s_add_u32 s52, s52, 0x40000
	s_addc_u32 s53, s53, 0
	s_mov_b32 m0, s54
	v_lshl_add_u64 v[222:223], s[52:53], 0, v[152:153]
	ds_read_b128 v[176:179], v191 offset:32768
	ds_read_b128 v[180:183], v191 offset:33792
	ds_read_b128 v[192:195], v191 offset:34816
	ds_read_b128 v[196:199], v191 offset:35840
	ds_read_b128 v[200:203], v191 offset:36864
	ds_read_b128 v[204:207], v191 offset:37888
	ds_read_b128 v[208:211], v191 offset:38912
	ds_read_b128 v[212:215], v191 offset:39936
	global_load_lds_dwordx4 v[222:223], off
	v_lshl_add_u64 v[222:223], s[52:53], 0, v[156:157]
	s_mov_b32 m0, s55
	s_nop 0
	global_load_lds_dwordx4 v[222:223], off
	s_waitcnt vmcnt(8)
	s_waitcnt lgkmcnt(0)
	s_barrier
	s_waitcnt lgkmcnt(0)
	v_mfma_f32_16x16x32_bf16 v[124:127], v[128:131], v[176:179], v[124:127]
	v_mfma_f32_16x16x32_bf16 v[120:123], v[136:139], v[176:179], v[120:123]
	v_mfma_f32_16x16x32_bf16 v[108:111], v[128:131], v[192:195], v[108:111]
	v_mfma_f32_16x16x32_bf16 v[104:107], v[136:139], v[192:195], v[104:107]
	v_mfma_f32_16x16x32_bf16 v[92:95], v[128:131], v[200:203], v[92:95]
	v_mfma_f32_16x16x32_bf16 v[88:91], v[136:139], v[200:203], v[88:91]
	v_mfma_f32_16x16x32_bf16 v[76:79], v[128:131], v[208:211], v[76:79]
	v_mfma_f32_16x16x32_bf16 v[72:75], v[136:139], v[208:211], v[72:75]
	v_mfma_f32_16x16x32_bf16 v[124:127], v[132:135], v[180:183], v[124:127]
	v_mfma_f32_16x16x32_bf16 v[120:123], v[140:143], v[180:183], v[120:123]
	v_mfma_f32_16x16x32_bf16 v[108:111], v[132:135], v[196:199], v[108:111]
	v_mfma_f32_16x16x32_bf16 v[104:107], v[140:143], v[196:199], v[104:107]
	v_mfma_f32_16x16x32_bf16 v[92:95], v[132:135], v[204:207], v[92:95]
	v_mfma_f32_16x16x32_bf16 v[88:91], v[140:143], v[204:207], v[88:91]
	v_mfma_f32_16x16x32_bf16 v[76:79], v[132:135], v[212:215], v[76:79]
	v_mfma_f32_16x16x32_bf16 v[72:75], v[140:143], v[212:215], v[72:75]
	v_mfma_f32_16x16x32_bf16 v[116:119], v[144:147], v[176:179], v[116:119]
	v_mfma_f32_16x16x32_bf16 v[112:115], v[168:171], v[176:179], v[112:115]
	v_mfma_f32_16x16x32_bf16 v[100:103], v[144:147], v[192:195], v[100:103]
	v_mfma_f32_16x16x32_bf16 v[96:99], v[168:171], v[192:195], v[96:99]
	v_mfma_f32_16x16x32_bf16 v[84:87], v[144:147], v[200:203], v[84:87]
	v_mfma_f32_16x16x32_bf16 v[80:83], v[168:171], v[200:203], v[80:83]
	v_mfma_f32_16x16x32_bf16 v[68:71], v[144:147], v[208:211], v[68:71]
	v_mfma_f32_16x16x32_bf16 v[64:67], v[168:171], v[208:211], v[64:67]
	v_mfma_f32_16x16x32_bf16 v[116:119], v[148:151], v[180:183], v[116:119]
	v_mfma_f32_16x16x32_bf16 v[112:115], v[172:175], v[180:183], v[112:115]
	v_mfma_f32_16x16x32_bf16 v[100:103], v[148:151], v[196:199], v[100:103]
	v_mfma_f32_16x16x32_bf16 v[96:99], v[172:175], v[196:199], v[96:99]
	v_mfma_f32_16x16x32_bf16 v[84:87], v[148:151], v[204:207], v[84:87]
	v_mfma_f32_16x16x32_bf16 v[80:83], v[172:175], v[204:207], v[80:83]
	v_mfma_f32_16x16x32_bf16 v[68:71], v[148:151], v[212:215], v[68:71]
	v_mfma_f32_16x16x32_bf16 v[64:67], v[172:175], v[212:215], v[64:67]
	s_barrier
; #define PG8_STAGE(bufoff, gbase, voff) do { _Pragma("unroll") for (int _i = 0; _i < 2; ++_i) \
;         __builtin_amdgcn_global_load_lds((const unsigned*)((const char*)(gbase) + (voff)[_i]), (PG8_LAS unsigned*)(lds + (bufoff) + ldsw + _i * 8192), 16, 0, 0); } while (0)
; #define PG8_LDA(dst, b, h) do { _Pragma("unroll") for (int m = 0; m < 4; ++m) _Pragma("unroll") for (int k = 0; k < 2; ++k) dst[m][k] = *(const PG8_LAS bf16x8*)(lds + PG8_SA(b, h) + aoff + m * 2048 + k * 1024); } while (0)
; #define PG8_MMA(ai, bj, At, Bt) do { __builtin_amdgcn_s_setprio(1); _Pragma("unroll") for (int m = 0; m < 4; ++m) _Pragma("unroll") for (int n = 0; n < 2; ++n) _Pragma("unroll") for (int k = 0; k < 2; ++k) \
;         acc[ai][bj][m][n] = mma16<F16>(Bt[n][k], At[m][k], acc[ai][bj][m][n]); __builtin_amdgcn_s_setprio(0); } while (0)
; #define PG8_WAIT_V(n) asm volatile("s_waitcnt vmcnt(" #n ")" ::: "memory")
; #define PG8_WAIT_L(n) asm volatile("s_waitcnt lgkmcnt(" #n ")" ::: "memory")
; #define PG8_BAR __builtin_amdgcn_s_barrier()
; #define PG8_SCHED __builtin_amdgcn_sched_barrier(0)
; template <class Epi, class Sched, bool ALIGN_EPI = false, bool SP2 = false, bool F16 = false>
; __device__ __forceinline__ void gemm_phase(PG8_LAS unsigned char* lds, const Gemm g, const Sched& S, const Epi& E, const int wid_in) {
;     ...
;             PG8_LDA(At, 1, 1); PG8_STAGE(PG8_SB(1, 0), b3, voffB); PG8_STAGE(PG8_SB(1, 1), b3 + hstep, voffB); PG8_STAGE(PG8_SA(1, 0), a3, voffA);
;             PG8_WAIT_V(8); PG8_WAIT_L(0); PG8_BAR; PG8_MMA(1, 0, At, B0); PG8_MMA(1, 1, At, B1); PG8_BAR; PG8_SCHED;
	s_add_i32 s52, s65, s68
	v_lshl_add_u64 v[184:185], v[184:185], 0, s[28:29]
	s_mov_b32 m0, s52
	ds_read_b128 v[176:179], v191 offset:49152
	ds_read_b128 v[180:183], v191 offset:50176
	ds_read_b128 v[192:195], v191 offset:51200
	ds_read_b128 v[196:199], v191 offset:52224
	ds_read_b128 v[200:203], v191 offset:53248
	ds_read_b128 v[204:207], v191 offset:54272
	ds_read_b128 v[208:211], v191 offset:55296
	ds_read_b128 v[212:215], v191 offset:56320
	global_load_lds_dwordx4 v[184:185], off
	s_add_i32 m0, s52, 0x2000
	s_add_u32 s50, s50, 0x40080
	v_lshl_add_u64 v[184:185], v[216:217], 0, s[28:29]
	s_addc_u32 s51, s51, 0
	s_add_i32 s52, s66, s68
	global_load_lds_dwordx4 v[184:185], off
	v_lshl_add_u64 v[184:185], s[50:51], 0, v[154:155]
	s_mov_b32 m0, s52
	s_nop 0
	global_load_lds_dwordx4 v[184:185], off
	v_lshl_add_u64 v[184:185], s[50:51], 0, v[158:159]
	s_add_i32 m0, s52, 0x2000
	s_nop 0
	global_load_lds_dwordx4 v[184:185], off
	v_lshl_add_u64 v[184:185], v[218:219], 0, s[28:29]
	s_mov_b32 m0, s75
	s_nop 0
	global_load_lds_dwordx4 v[184:185], off
	v_lshl_add_u64 v[184:185], v[220:221], 0, s[28:29]
	s_mov_b32 m0, s56
	s_nop 0
	global_load_lds_dwordx4 v[184:185], off
	s_waitcnt vmcnt(8)
	s_waitcnt lgkmcnt(0)
	s_barrier
	s_waitcnt lgkmcnt(0)
	v_mfma_f32_16x16x32_bf16 v[60:63], v[128:131], v[176:179], v[60:63]
	v_mfma_f32_16x16x32_bf16 v[56:59], v[136:139], v[176:179], v[56:59]
	v_mfma_f32_16x16x32_bf16 v[44:47], v[128:131], v[192:195], v[44:47]
	v_mfma_f32_16x16x32_bf16 v[40:43], v[136:139], v[192:195], v[40:43]
	v_mfma_f32_16x16x32_bf16 v[28:31], v[128:131], v[200:203], v[28:31]
	v_mfma_f32_16x16x32_bf16 v[24:27], v[136:139], v[200:203], v[24:27]
	v_mfma_f32_16x16x32_bf16 v[12:15], v[128:131], v[208:211], v[12:15]
	v_mfma_f32_16x16x32_bf16 v[8:11], v[136:139], v[208:211], v[8:11]
	v_mfma_f32_16x16x32_bf16 v[60:63], v[132:135], v[180:183], v[60:63]
	v_mfma_f32_16x16x32_bf16 v[56:59], v[140:143], v[180:183], v[56:59]
	v_mfma_f32_16x16x32_bf16 v[44:47], v[132:135], v[196:199], v[44:47]
	v_mfma_f32_16x16x32_bf16 v[40:43], v[140:143], v[196:199], v[40:43]
	v_mfma_f32_16x16x32_bf16 v[28:31], v[132:135], v[204:207], v[28:31]
	v_mfma_f32_16x16x32_bf16 v[24:27], v[140:143], v[204:207], v[24:27]
	v_mfma_f32_16x16x32_bf16 v[12:15], v[132:135], v[212:215], v[12:15]
	v_mfma_f32_16x16x32_bf16 v[8:11], v[140:143], v[212:215], v[8:11]
	v_mfma_f32_16x16x32_bf16 v[52:55], v[144:147], v[176:179], v[52:55]
	v_mfma_f32_16x16x32_bf16 v[48:51], v[168:171], v[176:179], v[48:51]
	v_mfma_f32_16x16x32_bf16 v[36:39], v[144:147], v[192:195], v[36:39]
	v_mfma_f32_16x16x32_bf16 v[32:35], v[168:171], v[192:195], v[32:35]
	v_mfma_f32_16x16x32_bf16 v[20:23], v[144:147], v[200:203], v[20:23]
	v_mfma_f32_16x16x32_bf16 v[16:19], v[168:171], v[200:203], v[16:19]
	v_mfma_f32_16x16x32_bf16 v[4:7], v[144:147], v[208:211], v[4:7]
	v_mfma_f32_16x16x32_bf16 v[0:3], v[168:171], v[208:211], v[0:3]
	v_mfma_f32_16x16x32_bf16 v[52:55], v[148:151], v[180:183], v[52:55]
	v_mfma_f32_16x16x32_bf16 v[48:51], v[172:175], v[180:183], v[48:51]
	v_mfma_f32_16x16x32_bf16 v[36:39], v[148:151], v[196:199], v[36:39]
	v_mfma_f32_16x16x32_bf16 v[32:35], v[172:175], v[196:199], v[32:35]
	v_mfma_f32_16x16x32_bf16 v[20:23], v[148:151], v[204:207], v[20:23]
	v_mfma_f32_16x16x32_bf16 v[16:19], v[172:175], v[204:207], v[16:19]
	v_mfma_f32_16x16x32_bf16 v[4:7], v[148:151], v[212:215], v[4:7]
	v_mfma_f32_16x16x32_bf16 v[0:3], v[172:175], v[212:215], v[0:3]
	s_barrier
	s_add_i32 s64, s64, 2
	s_add_u32 s48, s48, 0x100
	s_addc_u32 s49, s49, 0
	s_add_u32 s47, s47, 0x100
	s_addc_u32 s63, s63, 0
	s_cmp_gt_u32 s64, 13
	s_cbranch_scc0 .LBB0_1165
	s_setprio 0
	s_and_b64 vcc, exec, s[16:17]
	s_cbranch_vccz .LBB0_1168
	s_barrier

; #define PG8_STAGE(bufoff, gbase, voff) do { _Pragma("unroll") for (int _i = 0; _i < 2; ++_i) \
;         __builtin_amdgcn_global_load_lds((const unsigned*)((const char*)(gbase) + (voff)[_i]), (PG8_LAS unsigned*)(lds + (bufoff) + ldsw + _i * 8192), 16, 0, 0); } while (0)
; #define PG8_LDA(dst, b, h) do { _Pragma("unroll") for (int m = 0; m < 4; ++m) _Pragma("unroll") for (int k = 0; k < 2; ++k) dst[m][k] = *(const PG8_LAS bf16x8*)(lds + PG8_SA(b, h) + aoff + m * 2048 + k * 1024); } while (0)
; #define PG8_LDB(dst, b, h) do { _Pragma("unroll") for (int n = 0; n < 2; ++n) _Pragma("unroll") for (int k = 0; k < 2; ++k) dst[n][k] = *(const PG8_LAS bf16x8*)(lds + PG8_SB(b, h) + boff + n * 2048 + k * 1024); } while (0)
; #define PG8_WAIT_V(n) asm volatile("s_waitcnt vmcnt(" #n ")" ::: "memory")
; #define PG8_WAIT_L(n) asm volatile("s_waitcnt lgkmcnt(" #n ")" ::: "memory")
; #define PG8_BAR __builtin_amdgcn_s_barrier()
; #define PG8_SCHED __builtin_amdgcn_sched_barrier(0)
; template <class Epi, class Sched, bool ALIGN_EPI = false, bool SP2 = false, bool F16 = false>
; __device__ __forceinline__ void gemm_phase(PG8_LAS unsigned char* lds, const Gemm g, const Sched& S, const Epi& E, const int wid_in) {
;     ...
;         const char* nA = has_next ? (const char*)g.A + (size_t)nxt.pm * tstep : cA; const char* nB = has_next ? (const char*)g.Bt + (size_t)nxt.pn * tstep : cB;
;         for (int t = 0; t < nt; t += 2) {
;             const bool last = (t == nt - 2);
;             const char* a1 = cA + (size_t)(t + 1) * kstep;
;             const char* a2 = last ? nA : cA + (size_t)(t + 2) * kstep; const char* b2 = last ? nB : cB + (size_t)(t + 2) * kstep;
;             const char* a3 = a2 + kstep; const char* b3 = b2 + kstep;
;             if (last && has_next) S.a_ready(nxt);
;             if constexpr (SP2) {
;             PG8_LDB(B0, 0, 0); PG8_LDB(B1, 0, 1); PG8_SCHED; PG8_LDA(At, 0, 0); PG8_STAGE(PG8_SA(1, 1), a1 + hstep, voffA);
;             PG8_WAIT_V(8); PG8_WAIT_L(0); PG8_BAR; PG8_MMA(0, 0, At, B0); PG8_MMA(0, 1, At, B1); PG8_BAR; PG8_SCHED;
;     ...
; #pragma unroll
;         for (int a = 0; a < 2; ++a)
; #pragma unroll
;             for (int b = 0; b < 2; ++b)
; #pragma unroll
;                 for (int m = 0; m < 4; ++m)
; #pragma unroll
;                     for (int n = 0; n < 2; ++n) acc[a][b][m][n] = (f32x4){0.f, 0.f, 0.f, 0.f};
.LBB0_1241:
	s_ashr_i32 s29, s28, 31
	s_lshl_b64 s[30:31], s[28:29], 19
	s_add_u32 s30, s21, s30
	s_addc_u32 s31, s40, s31
	s_and_b64 s[34:35], s[10:11], exec
	s_cselect_b32 s29, s31, s47
	s_cselect_b32 s42, s30, s46
	s_ashr_i32 s27, s26, 31
	s_lshl_b64 s[34:35], s[26:27], 19
	s_add_u32 s34, s41, s34
	s_addc_u32 s35, s52, s35
	s_and_b64 s[50:51], s[10:11], exec
	s_cselect_b32 s27, s35, s49
	s_cselect_b32 s43, s34, s48
	s_add_u32 s46, s46, 0x40080
	s_addc_u32 s47, s47, 0
	s_add_u32 s45, s48, 0x100
	v_mov_b32_e32 v8, 0
	s_addc_u32 s66, s49, 0
	s_mov_b32 s67, -2
	v_mov_b32_e32 v9, v8
	v_mov_b32_e32 v10, v8
	v_mov_b32_e32 v11, v8
	v_mov_b32_e32 v12, v8
	v_mov_b32_e32 v13, v8
	v_mov_b32_e32 v14, v8
	v_mov_b32_e32 v15, v8
	v_mov_b32_e32 v24, v8
	v_mov_b32_e32 v25, v8
	v_mov_b32_e32 v26, v8
	v_mov_b32_e32 v27, v8
	v_mov_b32_e32 v28, v8
	v_mov_b32_e32 v29, v8
	v_mov_b32_e32 v30, v8
	v_mov_b32_e32 v31, v8
	v_mov_b32_e32 v40, v8
	v_mov_b32_e32 v41, v8
	v_mov_b32_e32 v42, v8
	v_mov_b32_e32 v43, v8
	v_mov_b32_e32 v44, v8
	v_mov_b32_e32 v45, v8
	v_mov_b32_e32 v46, v8
	v_mov_b32_e32 v47, v8
	v_mov_b32_e32 v56, v8
	v_mov_b32_e32 v57, v8
	v_mov_b32_e32 v58, v8
	v_mov_b32_e32 v59, v8
	v_mov_b32_e32 v60, v8
	v_mov_b32_e32 v61, v8
	v_mov_b32_e32 v62, v8
	v_mov_b32_e32 v63, v8
	v_mov_b32_e32 v16, v8
	v_mov_b32_e32 v17, v8
	v_mov_b32_e32 v18, v8
	v_mov_b32_e32 v19, v8
	v_mov_b32_e32 v20, v8
	v_mov_b32_e32 v21, v8
	v_mov_b32_e32 v22, v8
	v_mov_b32_e32 v23, v8
	v_mov_b32_e32 v32, v8
	v_mov_b32_e32 v33, v8
	v_mov_b32_e32 v34, v8
	v_mov_b32_e32 v35, v8
	v_mov_b32_e32 v36, v8
	v_mov_b32_e32 v37, v8
	v_mov_b32_e32 v38, v8
	v_mov_b32_e32 v39, v8
	v_mov_b32_e32 v48, v8
	v_mov_b32_e32 v49, v8
	v_mov_b32_e32 v50, v8
	v_mov_b32_e32 v51, v8
	v_mov_b32_e32 v52, v8
	v_mov_b32_e32 v53, v8
	v_mov_b32_e32 v54, v8
	v_mov_b32_e32 v55, v8
	v_mov_b32_e32 v64, v8
	v_mov_b32_e32 v65, v8
	v_mov_b32_e32 v66, v8
	v_mov_b32_e32 v67, v8
	v_mov_b32_e32 v68, v8
	v_mov_b32_e32 v69, v8
	v_mov_b32_e32 v70, v8
	v_mov_b32_e32 v71, v8
	v_mov_b32_e32 v72, v8
	v_mov_b32_e32 v73, v8
	v_mov_b32_e32 v74, v8
	v_mov_b32_e32 v75, v8
	v_mov_b32_e32 v76, v8
	v_mov_b32_e32 v77, v8
	v_mov_b32_e32 v78, v8
	v_mov_b32_e32 v79, v8
	v_mov_b32_e32 v88, v8
	v_mov_b32_e32 v89, v8
	v_mov_b32_e32 v90, v8
	v_mov_b32_e32 v91, v8
	v_mov_b32_e32 v92, v8
	v_mov_b32_e32 v93, v8
	v_mov_b32_e32 v94, v8
	v_mov_b32_e32 v95, v8
	v_mov_b32_e32 v104, v8
	v_mov_b32_e32 v105, v8
	v_mov_b32_e32 v106, v8
	v_mov_b32_e32 v107, v8
	v_mov_b32_e32 v108, v8
	v_mov_b32_e32 v109, v8
	v_mov_b32_e32 v110, v8
	v_mov_b32_e32 v111, v8
	v_mov_b32_e32 v120, v8
	v_mov_b32_e32 v121, v8
	v_mov_b32_e32 v122, v8
	v_mov_b32_e32 v123, v8
	v_mov_b32_e32 v124, v8
	v_mov_b32_e32 v125, v8
	v_mov_b32_e32 v126, v8
	v_mov_b32_e32 v127, v8
	v_mov_b32_e32 v80, v8
	v_mov_b32_e32 v81, v8
	v_mov_b32_e32 v82, v8
	v_mov_b32_e32 v83, v8
	v_mov_b32_e32 v84, v8
	v_mov_b32_e32 v85, v8
	v_mov_b32_e32 v86, v8
	v_mov_b32_e32 v87, v8
	v_mov_b32_e32 v96, v8
	v_mov_b32_e32 v97, v8
	v_mov_b32_e32 v98, v8
	v_mov_b32_e32 v99, v8
	v_mov_b32_e32 v100, v8
	v_mov_b32_e32 v101, v8
	v_mov_b32_e32 v102, v8
	v_mov_b32_e32 v103, v8
	v_mov_b32_e32 v112, v8
	v_mov_b32_e32 v113, v8
	v_mov_b32_e32 v114, v8
	v_mov_b32_e32 v115, v8
	v_mov_b32_e32 v116, v8
	v_mov_b32_e32 v117, v8
	v_mov_b32_e32 v118, v8
	v_mov_b32_e32 v119, v8
	v_mov_b32_e32 v128, v8
	v_mov_b32_e32 v129, v8
	v_mov_b32_e32 v130, v8
	v_mov_b32_e32 v131, v8
	v_mov_b32_e32 v132, v8
	v_mov_b32_e32 v133, v8
	v_mov_b32_e32 v134, v8
	v_mov_b32_e32 v135, v8
	s_cmp_ge_u32 s3, 4
	s_cbranch_scc0 .Lgsp_8
	s_setprio 1
.Lgsp_8:
.LBB0_1242:
	ds_read_b128 v[0:3], v193
	ds_read_b128 v[4:7], v193 offset:1024
	ds_read_b128 v[136:139], v193 offset:2048
	ds_read_b128 v[140:143], v193 offset:3072
	ds_read_b128 v[144:147], v194
	ds_read_b128 v[148:151], v194 offset:1024
	ds_read_b128 v[152:155], v194 offset:2048
	ds_read_b128 v[156:159], v194 offset:3072
	s_add_u32 s48, s46, 0xfffc0080
	s_addc_u32 s49, s47, -1
	s_cmp_eq_u32 s67, 12
	s_cselect_b32 s51, s29, s49
	s_cselect_b32 s50, s42, s48
	s_cselect_b32 s49, s27, s66
	s_cselect_b32 s48, s43, s45
	v_lshl_add_u64 v[188:189], s[46:47], 0, v[168:169]
	s_add_i32 m0, s74, 0xc000
	ds_read_b128 v[176:179], v195
	ds_read_b128 v[180:183], v195 offset:1024
	ds_read_b128 v[184:187], v195 offset:2048
	ds_read_b128 v[198:201], v195 offset:3072
	ds_read_b128 v[202:205], v195 offset:4096
	ds_read_b128 v[206:209], v195 offset:5120
	ds_read_b128 v[210:213], v195 offset:6144
	ds_read_b128 v[214:217], v195 offset:7168
	global_load_lds_dwordx4 v[188:189], off
	v_lshl_add_u64 v[188:189], s[46:47], 0, v[170:171]
	s_add_i32 m0, s74, 0xe000
	s_nop 0
	global_load_lds_dwordx4 v[188:189], off
	s_waitcnt vmcnt(8)
	s_waitcnt lgkmcnt(0)
	s_barrier
; #define PG8_STAGE(bufoff, gbase, voff) do { _Pragma("unroll") for (int _i = 0; _i < 2; ++_i) \
;         __builtin_amdgcn_global_load_lds((const unsigned*)((const char*)(gbase) + (voff)[_i]), (PG8_LAS unsigned*)(lds + (bufoff) + ldsw + _i * 8192), 16, 0, 0); } while (0)
; #define PG8_LDA(dst, b, h) do { _Pragma("unroll") for (int m = 0; m < 4; ++m) _Pragma("unroll") for (int k = 0; k < 2; ++k) dst[m][k] = *(const PG8_LAS bf16x8*)(lds + PG8_SA(b, h) + aoff + m * 2048 + k * 1024); } while (0)
; #define PG8_MMA(ai, bj, At, Bt) do { __builtin_amdgcn_s_setprio(1); _Pragma("unroll") for (int m = 0; m < 4; ++m) _Pragma("unroll") for (int n = 0; n < 2; ++n) _Pragma("unroll") for (int k = 0; k < 2; ++k) \
;         acc[ai][bj][m][n] = mma16<F16>(Bt[n][k], At[m][k], acc[ai][bj][m][n]); __builtin_amdgcn_s_setprio(0); } while (0)
; #define PG8_WAIT_V(n) asm volatile("s_waitcnt vmcnt(" #n ")" ::: "memory")
; #define PG8_WAIT_L(n) asm volatile("s_waitcnt lgkmcnt(" #n ")" ::: "memory")
; #define PG8_BAR __builtin_amdgcn_s_barrier()
; #define PG8_SCHED __builtin_amdgcn_sched_barrier(0)
; template <class Epi, class Sched, bool ALIGN_EPI = false, bool SP2 = false, bool F16 = false>
; __device__ __forceinline__ void gemm_phase(PG8_LAS unsigned char* lds, const Gemm g, const Sched& S, const Epi& E, const int wid_in) {
;     ...
;             PG8_WAIT_V(8); PG8_WAIT_L(0); PG8_BAR; PG8_MMA(0, 0, At, B0); PG8_MMA(0, 1, At, B1); PG8_BAR; PG8_SCHED;
;             PG8_LDA(At, 0, 1); PG8_STAGE(PG8_SB(0, 0), b2, voffB); PG8_STAGE(PG8_SB(0, 1), b2 + hstep, voffB); PG8_STAGE(PG8_SA(0, 0), a2, voffA);
;             PG8_WAIT_V(8); PG8_WAIT_L(0); PG8_BAR; PG8_MMA(1, 0, At, B0); PG8_MMA(1, 1, At, B1); PG8_BAR; PG8_SCHED;
	s_waitcnt lgkmcnt(0)
	v_mfma_f32_16x16x32_f16 v[132:135], v[0:3], v[176:179], v[132:135]
	v_mfma_f32_16x16x32_f16 v[128:131], v[136:139], v[176:179], v[128:131]
	v_mfma_f32_16x16x32_f16 v[116:119], v[0:3], v[184:187], v[116:119]
	v_mfma_f32_16x16x32_f16 v[112:115], v[136:139], v[184:187], v[112:115]
	v_mfma_f32_16x16x32_f16 v[100:103], v[0:3], v[202:205], v[100:103]
	v_mfma_f32_16x16x32_f16 v[96:99], v[136:139], v[202:205], v[96:99]
	v_mfma_f32_16x16x32_f16 v[84:87], v[0:3], v[210:213], v[84:87]
	v_mfma_f32_16x16x32_f16 v[80:83], v[136:139], v[210:213], v[80:83]
	v_mfma_f32_16x16x32_f16 v[132:135], v[4:7], v[180:183], v[132:135]
	v_mfma_f32_16x16x32_f16 v[128:131], v[140:143], v[180:183], v[128:131]
	v_mfma_f32_16x16x32_f16 v[116:119], v[4:7], v[198:201], v[116:119]
	v_mfma_f32_16x16x32_f16 v[112:115], v[140:143], v[198:201], v[112:115]
	v_mfma_f32_16x16x32_f16 v[100:103], v[4:7], v[206:209], v[100:103]
	v_mfma_f32_16x16x32_f16 v[96:99], v[140:143], v[206:209], v[96:99]
	v_mfma_f32_16x16x32_f16 v[84:87], v[4:7], v[214:217], v[84:87]
	v_mfma_f32_16x16x32_f16 v[80:83], v[140:143], v[214:217], v[80:83]
	v_mfma_f32_16x16x32_f16 v[124:127], v[144:147], v[176:179], v[124:127]
	v_mfma_f32_16x16x32_f16 v[120:123], v[152:155], v[176:179], v[120:123]
	v_mfma_f32_16x16x32_f16 v[108:111], v[144:147], v[184:187], v[108:111]
	v_mfma_f32_16x16x32_f16 v[104:107], v[152:155], v[184:187], v[104:107]
	v_mfma_f32_16x16x32_f16 v[92:95], v[144:147], v[202:205], v[92:95]
	v_mfma_f32_16x16x32_f16 v[88:91], v[152:155], v[202:205], v[88:91]
	v_mfma_f32_16x16x32_f16 v[76:79], v[144:147], v[210:213], v[76:79]
	v_mfma_f32_16x16x32_f16 v[72:75], v[152:155], v[210:213], v[72:75]
	v_mfma_f32_16x16x32_f16 v[124:127], v[148:151], v[180:183], v[124:127]
	v_mfma_f32_16x16x32_f16 v[120:123], v[156:159], v[180:183], v[120:123]
	v_mfma_f32_16x16x32_f16 v[108:111], v[148:151], v[198:201], v[108:111]
	v_mfma_f32_16x16x32_f16 v[104:107], v[156:159], v[198:201], v[104:107]
	v_mfma_f32_16x16x32_f16 v[92:95], v[148:151], v[206:209], v[92:95]
	v_mfma_f32_16x16x32_f16 v[88:91], v[156:159], v[206:209], v[88:91]
	v_mfma_f32_16x16x32_f16 v[76:79], v[148:151], v[214:217], v[76:79]
	v_mfma_f32_16x16x32_f16 v[72:75], v[156:159], v[214:217], v[72:75]
	s_barrier
	s_add_i32 s76, s63, s68
	v_lshl_add_u64 v[188:189], s[48:49], 0, v[162:163]
	s_mov_b32 m0, s76
	ds_read_b128 v[176:179], v195 offset:16384
	ds_read_b128 v[180:183], v195 offset:17408
	ds_read_b128 v[184:187], v195 offset:18432
	ds_read_b128 v[198:201], v195 offset:19456
	ds_read_b128 v[202:205], v195 offset:20480
	ds_read_b128 v[206:209], v195 offset:21504
	ds_read_b128 v[210:213], v195 offset:22528
	ds_read_b128 v[214:217], v195 offset:23552
	global_load_lds_dwordx4 v[188:189], off
	s_add_i32 m0, s76, 0x2000
	s_add_u32 s90, s48, 0x40000
	v_lshl_add_u64 v[218:219], s[48:49], 0, v[166:167]
	s_addc_u32 s91, s49, 0
	s_add_i32 s76, s64, s68
	global_load_lds_dwordx4 v[218:219], off
	v_lshl_add_u64 v[220:221], s[90:91], 0, v[162:163]
	s_mov_b32 m0, s76
	v_lshl_add_u64 v[222:223], s[50:51], 0, v[164:165]
	global_load_lds_dwordx4 v[220:221], off
	v_lshl_add_u64 v[220:221], s[90:91], 0, v[166:167]
	s_add_i32 m0, s76, 0x2000
	s_nop 0
	global_load_lds_dwordx4 v[220:221], off
	v_lshl_add_u64 v[220:221], s[50:51], 0, v[160:161]
	s_mov_b32 m0, s74
	s_nop 0
	global_load_lds_dwordx4 v[220:221], off
	s_mov_b32 m0, s37
	s_nop 0
	global_load_lds_dwordx4 v[222:223], off
	s_waitcnt vmcnt(8)
	s_waitcnt lgkmcnt(0)
	s_barrier
	s_waitcnt lgkmcnt(0)
	v_mfma_f32_16x16x32_f16 v[68:71], v[0:3], v[176:179], v[68:71]
	v_mfma_f32_16x16x32_f16 v[64:67], v[136:139], v[176:179], v[64:67]
	v_mfma_f32_16x16x32_f16 v[52:55], v[0:3], v[184:187], v[52:55]
	v_mfma_f32_16x16x32_f16 v[48:51], v[136:139], v[184:187], v[48:51]
	v_mfma_f32_16x16x32_f16 v[36:39], v[0:3], v[202:205], v[36:39]
	v_mfma_f32_16x16x32_f16 v[32:35], v[136:139], v[202:205], v[32:35]
	v_mfma_f32_16x16x32_f16 v[0:3], v[0:3], v[210:213], v[20:23]
	v_mfma_f32_16x16x32_f16 v[68:71], v[4:7], v[180:183], v[68:71]
	v_mfma_f32_16x16x32_f16 v[64:67], v[140:143], v[180:183], v[64:67]
	v_mfma_f32_16x16x32_f16 v[52:55], v[4:7], v[198:201], v[52:55]
	v_mfma_f32_16x16x32_f16 v[48:51], v[140:143], v[198:201], v[48:51]
	v_mfma_f32_16x16x32_f16 v[36:39], v[4:7], v[206:209], v[36:39]
	v_mfma_f32_16x16x32_f16 v[32:35], v[140:143], v[206:209], v[32:35]
	v_mfma_f32_16x16x32_f16 v[0:3], v[4:7], v[214:217], v[0:3]
	v_mfma_f32_16x16x32_f16 v[4:7], v[136:139], v[210:213], v[16:19]
	v_mfma_f32_16x16x32_f16 v[4:7], v[140:143], v[214:217], v[4:7]
	v_mfma_f32_16x16x32_f16 v[16:19], v[144:147], v[176:179], v[60:63]
	v_mfma_f32_16x16x32_f16 v[60:63], v[148:151], v[180:183], v[16:19]
	v_mfma_f32_16x16x32_f16 v[16:19], v[152:155], v[176:179], v[56:59]
	v_mfma_f32_16x16x32_f16 v[56:59], v[156:159], v[180:183], v[16:19]
	v_mfma_f32_16x16x32_f16 v[16:19], v[144:147], v[184:187], v[44:47]
	v_mfma_f32_16x16x32_f16 v[44:47], v[148:151], v[198:201], v[16:19]
	v_mfma_f32_16x16x32_f16 v[16:19], v[152:155], v[184:187], v[40:43]
	v_mfma_f32_16x16x32_f16 v[40:43], v[156:159], v[198:201], v[16:19]
	v_mfma_f32_16x16x32_f16 v[16:19], v[144:147], v[202:205], v[28:31]
	v_mfma_f32_16x16x32_f16 v[28:31], v[148:151], v[206:209], v[16:19]
	v_mfma_f32_16x16x32_f16 v[16:19], v[152:155], v[202:205], v[24:27]
	v_mfma_f32_16x16x32_f16 v[12:15], v[144:147], v[210:213], v[12:15]
	v_mfma_f32_16x16x32_f16 v[8:11], v[152:155], v[210:213], v[8:11]
	v_mfma_f32_16x16x32_f16 v[24:27], v[156:159], v[206:209], v[16:19]
	v_mfma_f32_16x16x32_f16 v[12:15], v[148:151], v[214:217], v[12:15]
	v_mfma_f32_16x16x32_f16 v[8:11], v[156:159], v[214:217], v[8:11]
	s_barrier
; #define PG8_STAGE(bufoff, gbase, voff) do { _Pragma("unroll") for (int _i = 0; _i < 2; ++_i) \
;         __builtin_amdgcn_global_load_lds((const unsigned*)((const char*)(gbase) + (voff)[_i]), (PG8_LAS unsigned*)(lds + (bufoff) + ldsw + _i * 8192), 16, 0, 0); } while (0)
; #define PG8_LDA(dst, b, h) do { _Pragma("unroll") for (int m = 0; m < 4; ++m) _Pragma("unroll") for (int k = 0; k < 2; ++k) dst[m][k] = *(const PG8_LAS bf16x8*)(lds + PG8_SA(b, h) + aoff + m * 2048 + k * 1024); } while (0)
; #define PG8_LDB(dst, b, h) do { _Pragma("unroll") for (int n = 0; n < 2; ++n) _Pragma("unroll") for (int k = 0; k < 2; ++k) dst[n][k] = *(const PG8_LAS bf16x8*)(lds + PG8_SB(b, h) + boff + n * 2048 + k * 1024); } while (0)
; #define PG8_MMA(ai, bj, At, Bt) do { __builtin_amdgcn_s_setprio(1); _Pragma("unroll") for (int m = 0; m < 4; ++m) _Pragma("unroll") for (int n = 0; n < 2; ++n) _Pragma("unroll") for (int k = 0; k < 2; ++k) \
;         acc[ai][bj][m][n] = mma16<F16>(Bt[n][k], At[m][k], acc[ai][bj][m][n]); __builtin_amdgcn_s_setprio(0); } while (0)
; #define PG8_WAIT_V(n) asm volatile("s_waitcnt vmcnt(" #n ")" ::: "memory")
; #define PG8_WAIT_L(n) asm volatile("s_waitcnt lgkmcnt(" #n ")" ::: "memory")
; #define PG8_BAR __builtin_amdgcn_s_barrier()
; #define PG8_SCHED __builtin_amdgcn_sched_barrier(0)
; template <class Epi, class Sched, bool ALIGN_EPI = false, bool SP2 = false, bool F16 = false>
; __device__ __forceinline__ void gemm_phase(PG8_LAS unsigned char* lds, const Gemm g, const Sched& S, const Epi& E, const int wid_in) {
;     ...
;             PG8_LDB(B0, 1, 0); PG8_LDB(B1, 1, 1); PG8_SCHED; PG8_LDA(At, 1, 0); PG8_STAGE(PG8_SA(0, 1), a2 + hstep, voffA);
;             PG8_WAIT_V(8); PG8_WAIT_L(0); PG8_BAR; PG8_MMA(0, 0, At, B0); PG8_MMA(0, 1, At, B1); PG8_BAR; PG8_SCHED;
;             PG8_LDA(At, 1, 1); PG8_STAGE(PG8_SB(1, 0), b3, voffB); PG8_STAGE(PG8_SB(1, 1), b3 + hstep, voffB); PG8_STAGE(PG8_SA(1, 0), a3, voffA);
;             PG8_WAIT_V(8); PG8_WAIT_L(0); PG8_BAR; PG8_MMA(1, 0, At, B0); PG8_MMA(1, 1, At, B1); PG8_BAR; PG8_SCHED;
	s_add_i32 s76, 0, 0x18000
	s_add_i32 s83, 0, 0x1c000
	v_add_u32_e32 v140, s76, v192
	v_add_u32_e32 v156, s83, v192
	ds_read_b128 v[16:19], v140
	ds_read_b128 v[20:23], v140 offset:1024
	ds_read_b128 v[136:139], v140 offset:2048
	ds_read_b128 v[140:143], v140 offset:3072
	ds_read_b128 v[144:147], v156
	ds_read_b128 v[148:151], v156 offset:1024
	ds_read_b128 v[152:155], v156 offset:2048
	ds_read_b128 v[156:159], v156 offset:3072
	s_add_u32 s50, s50, 0x40000
	s_addc_u32 s51, s51, 0
	s_mov_b32 m0, s53
	v_lshl_add_u64 v[224:225], s[50:51], 0, v[160:161]
	ds_read_b128 v[176:179], v195 offset:32768
	ds_read_b128 v[180:183], v195 offset:33792
	ds_read_b128 v[184:187], v195 offset:34816
	ds_read_b128 v[198:201], v195 offset:35840
	ds_read_b128 v[202:205], v195 offset:36864
	ds_read_b128 v[206:209], v195 offset:37888
	ds_read_b128 v[210:213], v195 offset:38912
	ds_read_b128 v[214:217], v195 offset:39936
	global_load_lds_dwordx4 v[224:225], off
	v_lshl_add_u64 v[224:225], s[50:51], 0, v[164:165]
	s_mov_b32 m0, s54
	s_nop 0
	global_load_lds_dwordx4 v[224:225], off
	s_waitcnt vmcnt(8)
	s_waitcnt lgkmcnt(0)
	s_barrier
	s_waitcnt lgkmcnt(0)
	v_mfma_f32_16x16x32_f16 v[132:135], v[16:19], v[176:179], v[132:135]
	v_mfma_f32_16x16x32_f16 v[128:131], v[136:139], v[176:179], v[128:131]
	v_mfma_f32_16x16x32_f16 v[116:119], v[16:19], v[184:187], v[116:119]
	v_mfma_f32_16x16x32_f16 v[112:115], v[136:139], v[184:187], v[112:115]
	v_mfma_f32_16x16x32_f16 v[100:103], v[16:19], v[202:205], v[100:103]
	v_mfma_f32_16x16x32_f16 v[96:99], v[136:139], v[202:205], v[96:99]
	v_mfma_f32_16x16x32_f16 v[84:87], v[16:19], v[210:213], v[84:87]
	v_mfma_f32_16x16x32_f16 v[80:83], v[136:139], v[210:213], v[80:83]
	v_mfma_f32_16x16x32_f16 v[132:135], v[20:23], v[180:183], v[132:135]
	v_mfma_f32_16x16x32_f16 v[128:131], v[140:143], v[180:183], v[128:131]
	v_mfma_f32_16x16x32_f16 v[116:119], v[20:23], v[198:201], v[116:119]
	v_mfma_f32_16x16x32_f16 v[112:115], v[140:143], v[198:201], v[112:115]
	v_mfma_f32_16x16x32_f16 v[100:103], v[20:23], v[206:209], v[100:103]
	v_mfma_f32_16x16x32_f16 v[96:99], v[140:143], v[206:209], v[96:99]
	v_mfma_f32_16x16x32_f16 v[84:87], v[20:23], v[214:217], v[84:87]
	v_mfma_f32_16x16x32_f16 v[80:83], v[140:143], v[214:217], v[80:83]
	v_mfma_f32_16x16x32_f16 v[124:127], v[144:147], v[176:179], v[124:127]
	v_mfma_f32_16x16x32_f16 v[120:123], v[152:155], v[176:179], v[120:123]
	v_mfma_f32_16x16x32_f16 v[108:111], v[144:147], v[184:187], v[108:111]
	v_mfma_f32_16x16x32_f16 v[104:107], v[152:155], v[184:187], v[104:107]
	v_mfma_f32_16x16x32_f16 v[92:95], v[144:147], v[202:205], v[92:95]
	v_mfma_f32_16x16x32_f16 v[88:91], v[152:155], v[202:205], v[88:91]
	v_mfma_f32_16x16x32_f16 v[76:79], v[144:147], v[210:213], v[76:79]
	v_mfma_f32_16x16x32_f16 v[72:75], v[152:155], v[210:213], v[72:75]
	v_mfma_f32_16x16x32_f16 v[124:127], v[148:151], v[180:183], v[124:127]
	v_mfma_f32_16x16x32_f16 v[120:123], v[156:159], v[180:183], v[120:123]
	v_mfma_f32_16x16x32_f16 v[108:111], v[148:151], v[198:201], v[108:111]
	v_mfma_f32_16x16x32_f16 v[104:107], v[156:159], v[198:201], v[104:107]
	v_mfma_f32_16x16x32_f16 v[92:95], v[148:151], v[206:209], v[92:95]
	v_mfma_f32_16x16x32_f16 v[88:91], v[156:159], v[206:209], v[88:91]
	v_mfma_f32_16x16x32_f16 v[76:79], v[148:151], v[214:217], v[76:79]
	v_mfma_f32_16x16x32_f16 v[72:75], v[156:159], v[214:217], v[72:75]
	s_barrier
	s_add_i32 s50, s76, s68
	v_lshl_add_u64 v[188:189], v[188:189], 0, s[24:25]
	s_mov_b32 m0, s50
	ds_read_b128 v[176:179], v195 offset:49152
	ds_read_b128 v[180:183], v195 offset:50176
	ds_read_b128 v[184:187], v195 offset:51200
	ds_read_b128 v[198:201], v195 offset:52224
	ds_read_b128 v[202:205], v195 offset:53248
	ds_read_b128 v[206:209], v195 offset:54272
	ds_read_b128 v[210:213], v195 offset:55296
	ds_read_b128 v[214:217], v195 offset:56320
	global_load_lds_dwordx4 v[188:189], off
	s_add_i32 m0, s50, 0x2000
	s_add_u32 s48, s48, 0x40080
	v_lshl_add_u64 v[188:189], v[218:219], 0, s[24:25]
	s_addc_u32 s49, s49, 0
	s_add_i32 s50, s83, s68
	global_load_lds_dwordx4 v[188:189], off
	v_lshl_add_u64 v[188:189], s[48:49], 0, v[162:163]
	s_mov_b32 m0, s50
	s_nop 0
	global_load_lds_dwordx4 v[188:189], off
	v_lshl_add_u64 v[188:189], s[48:49], 0, v[166:167]
	s_add_i32 m0, s50, 0x2000
	s_nop 0
	global_load_lds_dwordx4 v[188:189], off
	v_lshl_add_u64 v[188:189], v[220:221], 0, s[24:25]
	s_mov_b32 m0, s75
	s_nop 0
	global_load_lds_dwordx4 v[188:189], off
	v_lshl_add_u64 v[188:189], v[222:223], 0, s[24:25]
	s_mov_b32 m0, s57
	s_nop 0
	global_load_lds_dwordx4 v[188:189], off
	s_waitcnt vmcnt(8)
	s_waitcnt lgkmcnt(0)
	s_barrier
	s_waitcnt lgkmcnt(0)
	v_mfma_f32_16x16x32_f16 v[68:71], v[16:19], v[176:179], v[68:71]
	v_mfma_f32_16x16x32_f16 v[52:55], v[16:19], v[184:187], v[52:55]
	v_mfma_f32_16x16x32_f16 v[36:39], v[16:19], v[202:205], v[36:39]
	v_mfma_f32_16x16x32_f16 v[0:3], v[16:19], v[210:213], v[0:3]
	v_mfma_f32_16x16x32_f16 v[68:71], v[20:23], v[180:183], v[68:71]
	v_mfma_f32_16x16x32_f16 v[64:67], v[136:139], v[176:179], v[64:67]
	v_mfma_f32_16x16x32_f16 v[52:55], v[20:23], v[198:201], v[52:55]
	v_mfma_f32_16x16x32_f16 v[48:51], v[136:139], v[184:187], v[48:51]
	v_mfma_f32_16x16x32_f16 v[36:39], v[20:23], v[206:209], v[36:39]
	v_mfma_f32_16x16x32_f16 v[32:35], v[136:139], v[202:205], v[32:35]
	v_mfma_f32_16x16x32_f16 v[20:23], v[20:23], v[214:217], v[0:3]
	v_mfma_f32_16x16x32_f16 v[0:3], v[136:139], v[210:213], v[4:7]
	v_mfma_f32_16x16x32_f16 v[64:67], v[140:143], v[180:183], v[64:67]
	v_mfma_f32_16x16x32_f16 v[48:51], v[140:143], v[198:201], v[48:51]
	v_mfma_f32_16x16x32_f16 v[32:35], v[140:143], v[206:209], v[32:35]
	v_mfma_f32_16x16x32_f16 v[16:19], v[140:143], v[214:217], v[0:3]
	v_mfma_f32_16x16x32_f16 v[0:3], v[144:147], v[176:179], v[60:63]
	v_mfma_f32_16x16x32_f16 v[60:63], v[148:151], v[180:183], v[0:3]
	v_mfma_f32_16x16x32_f16 v[0:3], v[152:155], v[176:179], v[56:59]
	v_mfma_f32_16x16x32_f16 v[56:59], v[156:159], v[180:183], v[0:3]
	v_mfma_f32_16x16x32_f16 v[0:3], v[144:147], v[184:187], v[44:47]
	v_mfma_f32_16x16x32_f16 v[44:47], v[148:151], v[198:201], v[0:3]
	v_mfma_f32_16x16x32_f16 v[0:3], v[152:155], v[184:187], v[40:43]
	v_mfma_f32_16x16x32_f16 v[40:43], v[156:159], v[198:201], v[0:3]
	v_mfma_f32_16x16x32_f16 v[0:3], v[144:147], v[202:205], v[28:31]
	v_mfma_f32_16x16x32_f16 v[28:31], v[148:151], v[206:209], v[0:3]
	v_mfma_f32_16x16x32_f16 v[0:3], v[152:155], v[202:205], v[24:27]
	v_mfma_f32_16x16x32_f16 v[24:27], v[156:159], v[206:209], v[0:3]
	v_mfma_f32_16x16x32_f16 v[0:3], v[144:147], v[210:213], v[12:15]
	v_mfma_f32_16x16x32_f16 v[12:15], v[148:151], v[214:217], v[0:3]
	v_mfma_f32_16x16x32_f16 v[0:3], v[152:155], v[210:213], v[8:11]
	v_mfma_f32_16x16x32_f16 v[8:11], v[156:159], v[214:217], v[0:3]
	s_barrier
	s_add_i32 s67, s67, 2
	s_add_u32 s46, s46, 0x100
	s_addc_u32 s47, s47, 0
	s_add_u32 s45, s45, 0x100
	s_addc_u32 s66, s66, 0
	s_cmp_gt_u32 s67, 13
	s_cbranch_scc0 .LBB0_1242
	s_setprio 0
	s_and_b64 vcc, exec, s[16:17]
	s_cbranch_vccz .LBB0_1245
	s_barrier

; #define PG8_STAGE(bufoff, gbase, voff) do { _Pragma("unroll") for (int _i = 0; _i < 2; ++_i) \
;         __builtin_amdgcn_global_load_lds((const unsigned*)((const char*)(gbase) + (voff)[_i]), (PG8_LAS unsigned*)(lds + (bufoff) + ldsw + _i * 8192), 16, 0, 0); } while (0)
; #define PG8_LDA(dst, b, h) do { _Pragma("unroll") for (int m = 0; m < 4; ++m) _Pragma("unroll") for (int k = 0; k < 2; ++k) dst[m][k] = *(const PG8_LAS bf16x8*)(lds + PG8_SA(b, h) + aoff + m * 2048 + k * 1024); } while (0)
; #define PG8_LDB(dst, b, h) do { _Pragma("unroll") for (int n = 0; n < 2; ++n) _Pragma("unroll") for (int k = 0; k < 2; ++k) dst[n][k] = *(const PG8_LAS bf16x8*)(lds + PG8_SB(b, h) + boff + n * 2048 + k * 1024); } while (0)
; #define PG8_MMA(ai, bj, At, Bt) do { __builtin_amdgcn_s_setprio(1); _Pragma("unroll") for (int m = 0; m < 4; ++m) _Pragma("unroll") for (int n = 0; n < 2; ++n) _Pragma("unroll") for (int k = 0; k < 2; ++k) \
;         acc[ai][bj][m][n] = mma16<F16>(Bt[n][k], At[m][k], acc[ai][bj][m][n]); __builtin_amdgcn_s_setprio(0); } while (0)
; #define PG8_BAR __builtin_amdgcn_s_barrier()
; template <class Epi, class Sched, bool ALIGN_EPI = false, bool SP2 = false, bool F16 = false>
; __device__ __forceinline__ void gemm_phase(PG8_LAS unsigned char* lds, const Gemm g, const Sched& S, const Epi& E, const int wid_in) {
;     ...
;         const bool has_next = S.next(ui + 1, nxt);
;         const char* nA = has_next ? (const char*)g.A + (size_t)nxt.pm * tstep : cA; const char* nB = has_next ? (const char*)g.Bt + (size_t)nxt.pn * tstep : cB;
;         for (int t = 0; t < nt; t += 2) {
;             const bool last = (t == nt - 2);
;             const char* a1 = cA + (size_t)(t + 1) * kstep;
;             const char* a2 = last ? nA : cA + (size_t)(t + 2) * kstep; const char* b2 = last ? nB : cB + (size_t)(t + 2) * kstep;
;             const char* a3 = a2 + kstep; const char* b3 = b2 + kstep;
;             if (last && has_next) S.a_ready(nxt);
;             if constexpr (SP2) {
;             PG8_LDB(B0, 0, 0); PG8_LDB(B1, 0, 1); PG8_SCHED; PG8_LDA(At, 0, 0); PG8_STAGE(PG8_SA(1, 1), a1 + hstep, voffA);
;             PG8_WAIT_V(8); PG8_WAIT_L(0); PG8_BAR; PG8_MMA(0, 0, At, B0); PG8_MMA(0, 1, At, B1); PG8_BAR; PG8_SCHED;
;             PG8_LDA(At, 0, 1); PG8_STAGE(PG8_SB(0, 0), b2, voffB); PG8_STAGE(PG8_SB(0, 1), b2 + hstep, voffB); PG8_STAGE(PG8_SA(0, 0), a2, voffA);
.LBB0_1275:
	s_mov_b64 s[34:35], 0
	s_cmp_ge_u32 s3, 4
	s_cbranch_scc0 .Lgsp_9
	s_setprio 1
.Lgsp_9:
.LBB0_1276:
	s_mov_b32 s36, 2
	s_mov_b64 s[30:31], 0
	s_andn2_b64 vcc, exec, s[34:35]
	s_mov_b32 s63, s61
	s_mov_b32 s34, s62
	s_cbranch_vccz .LBB0_1282
.LBB0_1277:
	s_mov_b64 s[48:49], s[10:11]
	s_add_i32 s10, s36, s19
	s_mov_b64 s[46:47], s[12:13]
	s_mov_b32 s12, s62
	s_mov_b32 s13, s61
	s_and_b32 s61, s10, 3
	s_ashr_i32 s62, s10, 2
	s_and_b64 s[10:11], s[30:31], exec
	s_cselect_b32 s12, s62, s12
	ds_read_b128 v[0:3], v134
	ds_read_b128 v[4:7], v134 offset:1024
	ds_read_b128 v[8:11], v134 offset:2048
	ds_read_b128 v[12:15], v134 offset:3072
	ds_read_b128 v[16:19], v135
	ds_read_b128 v[20:23], v135 offset:1024
	ds_read_b128 v[24:27], v135 offset:2048
	ds_read_b128 v[28:31], v135 offset:3072
	s_cselect_b32 s10, s61, s13
	s_ashr_i32 s13, s12, 31
	s_lshl_b64 s[12:13], s[12:13], 17
	s_add_u32 s12, s21, s12
	s_addc_u32 s13, s40, s13
	s_and_b64 s[36:37], s[30:31], exec
	s_cselect_b32 s45, s13, s47
	s_cselect_b32 s44, s12, s46
	s_ashr_i32 s11, s10, 31
	s_lshl_b64 s[10:11], s[10:11], 17
	s_add_u32 s10, s41, s10
	s_addc_u32 s11, s42, s11
	s_and_b64 s[36:37], s[30:31], exec
	s_cselect_b32 s37, s11, s49
	s_cselect_b32 s36, s10, s48
	s_add_u32 s64, s46, 0x10080
	s_addc_u32 s65, s47, 0
	s_mov_b32 m0, s15
	v_lshl_add_u64 v[64:65], s[64:65], 0, v[130:131]
	ds_read_b128 v[32:35], v136
	ds_read_b128 v[36:39], v136 offset:1024
	ds_read_b128 v[40:43], v136 offset:2048
	ds_read_b128 v[44:47], v136 offset:3072
	ds_read_b128 v[48:51], v136 offset:4096
	ds_read_b128 v[52:55], v136 offset:5120
	ds_read_b128 v[56:59], v136 offset:6144
	ds_read_b128 v[60:63], v136 offset:7168
	global_load_lds_dwordx4 v[64:65], off
	v_lshl_add_u64 v[64:65], s[64:65], 0, v[128:129]
	s_mov_b32 m0, s52
	s_nop 0
	global_load_lds_dwordx4 v[64:65], off
	s_waitcnt vmcnt(8)
	s_waitcnt lgkmcnt(0)
	s_barrier
	s_waitcnt lgkmcnt(0)
	v_mfma_f32_16x16x32_bf16 v[64:67], v[0:3], v[32:35], 0
	v_mfma_f32_16x16x32_bf16 v[68:71], v[8:11], v[32:35], 0
	v_mfma_f32_16x16x32_bf16 v[72:75], v[0:3], v[40:43], 0
	v_mfma_f32_16x16x32_bf16 v[76:79], v[8:11], v[40:43], 0
	v_mfma_f32_16x16x32_bf16 v[80:83], v[0:3], v[48:51], 0
	v_mfma_f32_16x16x32_bf16 v[84:87], v[8:11], v[48:51], 0
	v_mfma_f32_16x16x32_bf16 v[88:91], v[0:3], v[56:59], 0
	v_mfma_f32_16x16x32_bf16 v[92:95], v[8:11], v[56:59], 0
	v_mfma_f32_16x16x32_bf16 v[64:67], v[4:7], v[36:39], v[64:67]
	v_mfma_f32_16x16x32_bf16 v[68:71], v[12:15], v[36:39], v[68:71]
	v_mfma_f32_16x16x32_bf16 v[72:75], v[4:7], v[44:47], v[72:75]
	v_mfma_f32_16x16x32_bf16 v[76:79], v[12:15], v[44:47], v[76:79]
	v_mfma_f32_16x16x32_bf16 v[80:83], v[4:7], v[52:55], v[80:83]
	v_mfma_f32_16x16x32_bf16 v[84:87], v[12:15], v[52:55], v[84:87]
	v_mfma_f32_16x16x32_bf16 v[88:91], v[4:7], v[60:63], v[88:91]
	v_mfma_f32_16x16x32_bf16 v[92:95], v[12:15], v[60:63], v[92:95]
	v_mfma_f32_16x16x32_bf16 v[96:99], v[16:19], v[32:35], 0
	v_mfma_f32_16x16x32_bf16 v[32:35], v[24:27], v[32:35], 0
	v_mfma_f32_16x16x32_bf16 v[96:99], v[20:23], v[36:39], v[96:99]
	v_mfma_f32_16x16x32_bf16 v[32:35], v[28:31], v[36:39], v[32:35]
	v_mfma_f32_16x16x32_bf16 v[36:39], v[16:19], v[40:43], 0
	v_mfma_f32_16x16x32_bf16 v[40:43], v[24:27], v[40:43], 0
	v_mfma_f32_16x16x32_bf16 v[36:39], v[20:23], v[44:47], v[36:39]
	v_mfma_f32_16x16x32_bf16 v[40:43], v[28:31], v[44:47], v[40:43]
	v_mfma_f32_16x16x32_bf16 v[44:47], v[16:19], v[48:51], 0
	v_mfma_f32_16x16x32_bf16 v[48:51], v[24:27], v[48:51], 0
	v_mfma_f32_16x16x32_bf16 v[44:47], v[20:23], v[52:55], v[44:47]
	v_mfma_f32_16x16x32_bf16 v[48:51], v[28:31], v[52:55], v[48:51]
	v_mfma_f32_16x16x32_bf16 v[52:55], v[16:19], v[56:59], 0
	v_mfma_f32_16x16x32_bf16 v[56:59], v[24:27], v[56:59], 0
	v_mfma_f32_16x16x32_bf16 v[52:55], v[20:23], v[60:63], v[52:55]
	v_mfma_f32_16x16x32_bf16 v[56:59], v[28:31], v[60:63], v[56:59]
	s_barrier
	v_lshl_add_u64 v[204:205], s[48:49], 0, v[130:131]
	s_mov_b32 m0, s53
	v_lshl_add_u64 v[140:141], v[204:205], 0, s[26:27]
	v_lshl_add_u64 v[206:207], s[48:49], 0, v[128:129]
	s_add_u32 s64, s48, 0x10100
	ds_read_b128 v[60:63], v136 offset:16384
	ds_read_b128 v[100:103], v136 offset:17408
	ds_read_b128 v[104:107], v136 offset:18432
	ds_read_b128 v[108:111], v136 offset:19456
	ds_read_b128 v[112:115], v136 offset:20480
	ds_read_b128 v[116:119], v136 offset:21504
	ds_read_b128 v[120:123], v136 offset:22528
	ds_read_b128 v[124:127], v136 offset:23552
	global_load_lds_dwordx4 v[140:141], off
	v_lshl_add_u64 v[140:141], v[206:207], 0, s[26:27]
	s_mov_b32 m0, s54
	s_addc_u32 s65, s49, 0
	global_load_lds_dwordx4 v[140:141], off
	v_lshl_add_u64 v[140:141], s[64:65], 0, v[130:131]
	s_mov_b32 m0, s55
	v_lshl_add_u64 v[208:209], s[46:47], 0, v[130:131]
	global_load_lds_dwordx4 v[140:141], off
	v_lshl_add_u64 v[140:141], s[64:65], 0, v[128:129]
	s_mov_b32 m0, s56
	v_lshl_add_u64 v[210:211], s[46:47], 0, v[128:129]
	global_load_lds_dwordx4 v[140:141], off
	v_lshl_add_u64 v[140:141], v[208:209], 0, s[26:27]
	s_mov_b32 m0, s74
	s_nop 0
	global_load_lds_dwordx4 v[140:141], off
	v_lshl_add_u64 v[140:141], v[210:211], 0, s[26:27]
	s_mov_b32 m0, s43
	s_nop 0
	global_load_lds_dwordx4 v[140:141], off
	s_waitcnt vmcnt(8)
	s_waitcnt lgkmcnt(0)
	s_barrier
; #define PG8_STAGE(bufoff, gbase, voff) do { _Pragma("unroll") for (int _i = 0; _i < 2; ++_i) \
;         __builtin_amdgcn_global_load_lds((const unsigned*)((const char*)(gbase) + (voff)[_i]), (PG8_LAS unsigned*)(lds + (bufoff) + ldsw + _i * 8192), 16, 0, 0); } while (0)
; #define PG8_LDA(dst, b, h) do { _Pragma("unroll") for (int m = 0; m < 4; ++m) _Pragma("unroll") for (int k = 0; k < 2; ++k) dst[m][k] = *(const PG8_LAS bf16x8*)(lds + PG8_SA(b, h) + aoff + m * 2048 + k * 1024); } while (0)
; #define PG8_LDB(dst, b, h) do { _Pragma("unroll") for (int n = 0; n < 2; ++n) _Pragma("unroll") for (int k = 0; k < 2; ++k) dst[n][k] = *(const PG8_LAS bf16x8*)(lds + PG8_SB(b, h) + boff + n * 2048 + k * 1024); } while (0)
; #define PG8_MMA(ai, bj, At, Bt) do { __builtin_amdgcn_s_setprio(1); _Pragma("unroll") for (int m = 0; m < 4; ++m) _Pragma("unroll") for (int n = 0; n < 2; ++n) _Pragma("unroll") for (int k = 0; k < 2; ++k) \
;         acc[ai][bj][m][n] = mma16<F16>(Bt[n][k], At[m][k], acc[ai][bj][m][n]); __builtin_amdgcn_s_setprio(0); } while (0)
; #define PG8_WAIT_V(n) asm volatile("s_waitcnt vmcnt(" #n ")" ::: "memory")
; #define PG8_WAIT_L(n) asm volatile("s_waitcnt lgkmcnt(" #n ")" ::: "memory")
; #define PG8_BAR __builtin_amdgcn_s_barrier()
; #define PG8_SCHED __builtin_amdgcn_sched_barrier(0)
; template <class Epi, class Sched, bool ALIGN_EPI = false, bool SP2 = false, bool F16 = false>
; __device__ __forceinline__ void gemm_phase(PG8_LAS unsigned char* lds, const Gemm g, const Sched& S, const Epi& E, const int wid_in) {
;     ...
;             PG8_WAIT_V(8); PG8_WAIT_L(0); PG8_BAR; PG8_MMA(1, 0, At, B0); PG8_MMA(1, 1, At, B1); PG8_BAR; PG8_SCHED;
;             PG8_LDB(B0, 1, 0); PG8_LDB(B1, 1, 1); PG8_SCHED; PG8_LDA(At, 1, 0); PG8_STAGE(PG8_SA(0, 1), a2 + hstep, voffA);
;             PG8_WAIT_V(8); PG8_WAIT_L(0); PG8_BAR; PG8_MMA(0, 0, At, B0); PG8_MMA(0, 1, At, B1); PG8_BAR; PG8_SCHED;
	s_waitcnt lgkmcnt(0)
	v_mfma_f32_16x16x32_bf16 v[140:143], v[0:3], v[60:63], 0
	v_mfma_f32_16x16x32_bf16 v[148:151], v[0:3], v[104:107], 0
	v_mfma_f32_16x16x32_bf16 v[156:159], v[0:3], v[112:115], 0
	v_mfma_f32_16x16x32_bf16 v[0:3], v[0:3], v[120:123], 0
	v_mfma_f32_16x16x32_bf16 v[140:143], v[4:7], v[100:103], v[140:143]
	v_mfma_f32_16x16x32_bf16 v[148:151], v[4:7], v[108:111], v[148:151]
	v_mfma_f32_16x16x32_bf16 v[156:159], v[4:7], v[116:119], v[156:159]
	v_mfma_f32_16x16x32_bf16 v[0:3], v[4:7], v[124:127], v[0:3]
	v_mfma_f32_16x16x32_bf16 v[4:7], v[8:11], v[120:123], 0
	v_mfma_f32_16x16x32_bf16 v[144:147], v[8:11], v[60:63], 0
	v_mfma_f32_16x16x32_bf16 v[152:155], v[8:11], v[104:107], 0
	v_mfma_f32_16x16x32_bf16 v[160:163], v[8:11], v[112:115], 0
	v_mfma_f32_16x16x32_bf16 v[4:7], v[12:15], v[124:127], v[4:7]
	v_mfma_f32_16x16x32_bf16 v[144:147], v[12:15], v[100:103], v[144:147]
	v_mfma_f32_16x16x32_bf16 v[152:155], v[12:15], v[108:111], v[152:155]
	v_mfma_f32_16x16x32_bf16 v[160:163], v[12:15], v[116:119], v[160:163]
	v_mfma_f32_16x16x32_bf16 v[8:11], v[16:19], v[60:63], 0
	v_mfma_f32_16x16x32_bf16 v[12:15], v[24:27], v[60:63], 0
	v_mfma_f32_16x16x32_bf16 v[8:11], v[20:23], v[100:103], v[8:11]
	v_mfma_f32_16x16x32_bf16 v[12:15], v[28:31], v[100:103], v[12:15]
	v_mfma_f32_16x16x32_bf16 v[60:63], v[16:19], v[104:107], 0
	v_mfma_f32_16x16x32_bf16 v[100:103], v[24:27], v[104:107], 0
	v_mfma_f32_16x16x32_bf16 v[104:107], v[16:19], v[112:115], 0
	v_mfma_f32_16x16x32_bf16 v[16:19], v[16:19], v[120:123], 0
	v_mfma_f32_16x16x32_bf16 v[60:63], v[20:23], v[108:111], v[60:63]
	v_mfma_f32_16x16x32_bf16 v[100:103], v[28:31], v[108:111], v[100:103]
	v_mfma_f32_16x16x32_bf16 v[104:107], v[20:23], v[116:119], v[104:107]
	v_mfma_f32_16x16x32_bf16 v[108:111], v[24:27], v[112:115], 0
	v_mfma_f32_16x16x32_bf16 v[16:19], v[20:23], v[124:127], v[16:19]
	v_mfma_f32_16x16x32_bf16 v[20:23], v[24:27], v[120:123], 0
	v_mfma_f32_16x16x32_bf16 v[108:111], v[28:31], v[116:119], v[108:111]
	v_mfma_f32_16x16x32_bf16 v[20:23], v[28:31], v[124:127], v[20:23]
	s_barrier
	ds_read_b128 v[24:27], v137
	ds_read_b128 v[28:31], v137 offset:1024
	ds_read_b128 v[112:115], v137 offset:2048
	ds_read_b128 v[116:119], v137 offset:3072
	ds_read_b128 v[120:123], v138
	ds_read_b128 v[124:127], v138 offset:1024
	ds_read_b128 v[164:167], v138 offset:2048
	ds_read_b128 v[168:171], v138 offset:3072
	s_add_u32 s64, s46, 0x10100
	s_addc_u32 s65, s47, 0
	s_mov_b32 m0, s50
	v_lshl_add_u64 v[212:213], s[64:65], 0, v[130:131]
	ds_read_b128 v[172:175], v136 offset:32768
	ds_read_b128 v[176:179], v136 offset:33792
	ds_read_b128 v[180:183], v136 offset:34816
	ds_read_b128 v[184:187], v136 offset:35840
	ds_read_b128 v[188:191], v136 offset:36864
	ds_read_b128 v[192:195], v136 offset:37888
	ds_read_b128 v[196:199], v136 offset:38912
	ds_read_b128 v[200:203], v136 offset:39936
	global_load_lds_dwordx4 v[212:213], off
	v_lshl_add_u64 v[212:213], s[64:65], 0, v[128:129]
	s_mov_b32 m0, s51
	s_nop 0
	global_load_lds_dwordx4 v[212:213], off
	s_waitcnt vmcnt(8)
	s_waitcnt lgkmcnt(0)
	s_barrier
	s_waitcnt lgkmcnt(0)
	v_mfma_f32_16x16x32_bf16 v[64:67], v[24:27], v[172:175], v[64:67]
	v_mfma_f32_16x16x32_bf16 v[68:71], v[112:115], v[172:175], v[68:71]
	v_mfma_f32_16x16x32_bf16 v[72:75], v[24:27], v[180:183], v[72:75]
	v_mfma_f32_16x16x32_bf16 v[76:79], v[112:115], v[180:183], v[76:79]
	v_mfma_f32_16x16x32_bf16 v[80:83], v[24:27], v[188:191], v[80:83]
	v_mfma_f32_16x16x32_bf16 v[84:87], v[112:115], v[188:191], v[84:87]
	v_mfma_f32_16x16x32_bf16 v[88:91], v[24:27], v[196:199], v[88:91]
	v_mfma_f32_16x16x32_bf16 v[92:95], v[112:115], v[196:199], v[92:95]
	v_mfma_f32_16x16x32_bf16 v[64:67], v[28:31], v[176:179], v[64:67]
	v_mfma_f32_16x16x32_bf16 v[68:71], v[116:119], v[176:179], v[68:71]
	v_mfma_f32_16x16x32_bf16 v[72:75], v[28:31], v[184:187], v[72:75]
	v_mfma_f32_16x16x32_bf16 v[76:79], v[116:119], v[184:187], v[76:79]
	v_mfma_f32_16x16x32_bf16 v[80:83], v[28:31], v[192:195], v[80:83]
	v_mfma_f32_16x16x32_bf16 v[84:87], v[116:119], v[192:195], v[84:87]
	v_mfma_f32_16x16x32_bf16 v[88:91], v[28:31], v[200:203], v[88:91]
	v_mfma_f32_16x16x32_bf16 v[92:95], v[116:119], v[200:203], v[92:95]
	v_mfma_f32_16x16x32_bf16 v[96:99], v[120:123], v[172:175], v[96:99]
	v_mfma_f32_16x16x32_bf16 v[32:35], v[164:167], v[172:175], v[32:35]
	v_mfma_f32_16x16x32_bf16 v[36:39], v[120:123], v[180:183], v[36:39]
	v_mfma_f32_16x16x32_bf16 v[40:43], v[164:167], v[180:183], v[40:43]
	v_mfma_f32_16x16x32_bf16 v[44:47], v[120:123], v[188:191], v[44:47]
	v_mfma_f32_16x16x32_bf16 v[48:51], v[164:167], v[188:191], v[48:51]
	v_mfma_f32_16x16x32_bf16 v[52:55], v[120:123], v[196:199], v[52:55]
	v_mfma_f32_16x16x32_bf16 v[56:59], v[164:167], v[196:199], v[56:59]
	v_mfma_f32_16x16x32_bf16 v[96:99], v[124:127], v[176:179], v[96:99]
	v_mfma_f32_16x16x32_bf16 v[32:35], v[168:171], v[176:179], v[32:35]
	v_mfma_f32_16x16x32_bf16 v[36:39], v[124:127], v[184:187], v[36:39]
	v_mfma_f32_16x16x32_bf16 v[40:43], v[168:171], v[184:187], v[40:43]
	v_mfma_f32_16x16x32_bf16 v[44:47], v[124:127], v[192:195], v[44:47]
	v_mfma_f32_16x16x32_bf16 v[48:51], v[168:171], v[192:195], v[48:51]
	v_mfma_f32_16x16x32_bf16 v[52:55], v[124:127], v[200:203], v[52:55]
	v_mfma_f32_16x16x32_bf16 v[56:59], v[168:171], v[200:203], v[56:59]
	s_barrier
; #define PG8_STAGE(bufoff, gbase, voff) do { _Pragma("unroll") for (int _i = 0; _i < 2; ++_i) \
;         __builtin_amdgcn_global_load_lds((const unsigned*)((const char*)(gbase) + (voff)[_i]), (PG8_LAS unsigned*)(lds + (bufoff) + ldsw + _i * 8192), 16, 0, 0); } while (0)
; #define PG8_LDA(dst, b, h) do { _Pragma("unroll") for (int m = 0; m < 4; ++m) _Pragma("unroll") for (int k = 0; k < 2; ++k) dst[m][k] = *(const PG8_LAS bf16x8*)(lds + PG8_SA(b, h) + aoff + m * 2048 + k * 1024); } while (0)
; #define PG8_LDB(dst, b, h) do { _Pragma("unroll") for (int n = 0; n < 2; ++n) _Pragma("unroll") for (int k = 0; k < 2; ++k) dst[n][k] = *(const PG8_LAS bf16x8*)(lds + PG8_SB(b, h) + boff + n * 2048 + k * 1024); } while (0)
; #define PG8_MMA(ai, bj, At, Bt) do { __builtin_amdgcn_s_setprio(1); _Pragma("unroll") for (int m = 0; m < 4; ++m) _Pragma("unroll") for (int n = 0; n < 2; ++n) _Pragma("unroll") for (int k = 0; k < 2; ++k) \
;         acc[ai][bj][m][n] = mma16<F16>(Bt[n][k], At[m][k], acc[ai][bj][m][n]); __builtin_amdgcn_s_setprio(0); } while (0)
; #define PG8_WAIT_V(n) asm volatile("s_waitcnt vmcnt(" #n ")" ::: "memory")
; template <class Epi, class Sched, bool ALIGN_EPI = false, bool SP2 = false, bool F16 = false>
; __device__ __forceinline__ void gemm_phase(PG8_LAS unsigned char* lds, const Gemm g, const Sched& S, const Epi& E, const int wid_in) {
;     ...
;             PG8_LDB(B0, 0, 0); PG8_LDB(B1, 0, 1); PG8_SCHED; PG8_LDA(At, 0, 0); PG8_STAGE(PG8_SA(1, 1), a1 + hstep, voffA);
;             PG8_WAIT_V(8); PG8_WAIT_L(0); PG8_BAR; PG8_MMA(0, 0, At, B0); PG8_MMA(0, 1, At, B1); PG8_BAR; PG8_SCHED;
;             PG8_LDA(At, 0, 1); PG8_STAGE(PG8_SB(0, 0), b2, voffB); PG8_STAGE(PG8_SB(0, 1), b2 + hstep, voffB); PG8_STAGE(PG8_SA(0, 0), a2, voffA);
;             PG8_WAIT_V(8); PG8_WAIT_L(0); PG8_BAR; PG8_MMA(1, 0, At, B0); PG8_MMA(1, 1, At, B1); PG8_BAR; PG8_SCHED;
;             PG8_LDB(B0, 1, 0); PG8_LDB(B1, 1, 1); PG8_SCHED; PG8_LDA(At, 1, 0); PG8_STAGE(PG8_SA(0, 1), a2 + hstep, voffA);
;             PG8_WAIT_V(8); PG8_WAIT_L(0); PG8_BAR; PG8_MMA(0, 0, At, B0); PG8_MMA(0, 1, At, B1); PG8_BAR; PG8_SCHED;
;             PG8_LDA(At, 1, 1); PG8_STAGE(PG8_SB(1, 0), b3, voffB); PG8_STAGE(PG8_SB(1, 1), b3 + hstep, voffB); PG8_STAGE(PG8_SA(1, 0), a3, voffA);
;             PG8_WAIT_V(8); PG8_WAIT_L(0); PG8_BAR; PG8_MMA(1, 0, At, B0); PG8_MMA(1, 1, At, B1); PG8_BAR; PG8_SCHED;
	s_mov_b32 m0, s57
	v_lshl_add_u64 v[204:205], v[204:205], 0, s[28:29]
	s_add_u32 s48, s48, 0x10180
	ds_read_b128 v[172:175], v136 offset:49152
	ds_read_b128 v[176:179], v136 offset:50176
	ds_read_b128 v[180:183], v136 offset:51200
	ds_read_b128 v[184:187], v136 offset:52224
	ds_read_b128 v[188:191], v136 offset:53248
	ds_read_b128 v[192:195], v136 offset:54272
	ds_read_b128 v[196:199], v136 offset:55296
	ds_read_b128 v[200:203], v136 offset:56320
	global_load_lds_dwordx4 v[204:205], off
	v_lshl_add_u64 v[204:205], v[206:207], 0, s[28:29]
	s_mov_b32 m0, s58
	s_addc_u32 s49, s49, 0
	global_load_lds_dwordx4 v[204:205], off
	v_lshl_add_u64 v[204:205], s[48:49], 0, v[130:131]
	s_mov_b32 m0, s59
	s_nop 0
	global_load_lds_dwordx4 v[204:205], off
	v_lshl_add_u64 v[204:205], s[48:49], 0, v[128:129]
	s_mov_b32 m0, s60
	s_nop 0
	global_load_lds_dwordx4 v[204:205], off
	v_lshl_add_u64 v[204:205], v[208:209], 0, s[28:29]
	s_mov_b32 m0, s75
	s_nop 0
	global_load_lds_dwordx4 v[204:205], off
	v_lshl_add_u64 v[204:205], v[210:211], 0, s[28:29]
	s_mov_b32 m0, s14
	s_nop 0
	global_load_lds_dwordx4 v[204:205], off
	s_waitcnt vmcnt(8)
	s_waitcnt lgkmcnt(0)
	s_barrier
	s_waitcnt lgkmcnt(0)
	v_mfma_f32_16x16x32_bf16 v[0:3], v[24:27], v[196:199], v[0:3]
	v_mfma_f32_16x16x32_bf16 v[4:7], v[112:115], v[196:199], v[4:7]
	v_mfma_f32_16x16x32_bf16 v[140:143], v[24:27], v[172:175], v[140:143]
	v_mfma_f32_16x16x32_bf16 v[144:147], v[112:115], v[172:175], v[144:147]
	v_mfma_f32_16x16x32_bf16 v[148:151], v[24:27], v[180:183], v[148:151]
	v_mfma_f32_16x16x32_bf16 v[152:155], v[112:115], v[180:183], v[152:155]
	v_mfma_f32_16x16x32_bf16 v[156:159], v[24:27], v[188:191], v[156:159]
	v_mfma_f32_16x16x32_bf16 v[160:163], v[112:115], v[188:191], v[160:163]
	v_mfma_f32_16x16x32_bf16 v[0:3], v[28:31], v[200:203], v[0:3]
	v_mfma_f32_16x16x32_bf16 v[4:7], v[116:119], v[200:203], v[4:7]
	v_mfma_f32_16x16x32_bf16 v[140:143], v[28:31], v[176:179], v[140:143]
	v_mfma_f32_16x16x32_bf16 v[144:147], v[116:119], v[176:179], v[144:147]
	v_mfma_f32_16x16x32_bf16 v[148:151], v[28:31], v[184:187], v[148:151]
	v_mfma_f32_16x16x32_bf16 v[152:155], v[116:119], v[184:187], v[152:155]
	v_mfma_f32_16x16x32_bf16 v[156:159], v[28:31], v[192:195], v[156:159]
	v_mfma_f32_16x16x32_bf16 v[160:163], v[116:119], v[192:195], v[160:163]
	v_mfma_f32_16x16x32_bf16 v[8:11], v[120:123], v[172:175], v[8:11]
	v_mfma_f32_16x16x32_bf16 v[12:15], v[164:167], v[172:175], v[12:15]
	v_mfma_f32_16x16x32_bf16 v[24:27], v[120:123], v[180:183], v[60:63]
	v_mfma_f32_16x16x32_bf16 v[28:31], v[164:167], v[180:183], v[100:103]
	v_mfma_f32_16x16x32_bf16 v[60:63], v[120:123], v[188:191], v[104:107]
	v_mfma_f32_16x16x32_bf16 v[100:103], v[164:167], v[188:191], v[108:111]
	v_mfma_f32_16x16x32_bf16 v[16:19], v[120:123], v[196:199], v[16:19]
	v_mfma_f32_16x16x32_bf16 v[20:23], v[164:167], v[196:199], v[20:23]
	v_mfma_f32_16x16x32_bf16 v[8:11], v[124:127], v[176:179], v[8:11]
	v_mfma_f32_16x16x32_bf16 v[12:15], v[168:171], v[176:179], v[12:15]
	v_mfma_f32_16x16x32_bf16 v[24:27], v[124:127], v[184:187], v[24:27]
	v_mfma_f32_16x16x32_bf16 v[28:31], v[168:171], v[184:187], v[28:31]
	v_mfma_f32_16x16x32_bf16 v[60:63], v[124:127], v[192:195], v[60:63]
	v_mfma_f32_16x16x32_bf16 v[100:103], v[168:171], v[192:195], v[100:103]
	v_mfma_f32_16x16x32_bf16 v[16:19], v[124:127], v[200:203], v[16:19]
	v_mfma_f32_16x16x32_bf16 v[20:23], v[168:171], v[200:203], v[20:23]
	s_barrier
	ds_read_b128 v[104:107], v134
	ds_read_b128 v[108:111], v134 offset:1024
	ds_read_b128 v[112:115], v134 offset:2048
	ds_read_b128 v[116:119], v134 offset:3072
	ds_read_b128 v[120:123], v135
	ds_read_b128 v[124:127], v135 offset:1024
	ds_read_b128 v[164:167], v135 offset:2048
	ds_read_b128 v[168:171], v135 offset:3072
	s_add_u32 s46, s46, 0x10180
	s_addc_u32 s47, s47, 0
	s_mov_b32 m0, s15
	v_lshl_add_u64 v[204:205], s[46:47], 0, v[130:131]
	ds_read_b128 v[172:175], v136
	ds_read_b128 v[176:179], v136 offset:1024
	ds_read_b128 v[180:183], v136 offset:2048
	ds_read_b128 v[184:187], v136 offset:3072
	ds_read_b128 v[188:191], v136 offset:4096
	ds_read_b128 v[192:195], v136 offset:5120
	ds_read_b128 v[196:199], v136 offset:6144
	ds_read_b128 v[200:203], v136 offset:7168
	global_load_lds_dwordx4 v[204:205], off
	v_lshl_add_u64 v[204:205], s[46:47], 0, v[128:129]
	s_mov_b32 m0, s52
	s_nop 0
	global_load_lds_dwordx4 v[204:205], off
	s_waitcnt vmcnt(8)
	s_waitcnt lgkmcnt(0)
	s_barrier
	s_waitcnt lgkmcnt(0)
	v_mfma_f32_16x16x32_bf16 v[64:67], v[104:107], v[172:175], v[64:67]
	v_mfma_f32_16x16x32_bf16 v[68:71], v[112:115], v[172:175], v[68:71]
	v_mfma_f32_16x16x32_bf16 v[72:75], v[104:107], v[180:183], v[72:75]
	v_mfma_f32_16x16x32_bf16 v[76:79], v[112:115], v[180:183], v[76:79]
	v_mfma_f32_16x16x32_bf16 v[80:83], v[104:107], v[188:191], v[80:83]
	v_mfma_f32_16x16x32_bf16 v[84:87], v[112:115], v[188:191], v[84:87]
	v_mfma_f32_16x16x32_bf16 v[88:91], v[104:107], v[196:199], v[88:91]
	v_mfma_f32_16x16x32_bf16 v[92:95], v[112:115], v[196:199], v[92:95]
	v_mfma_f32_16x16x32_bf16 v[64:67], v[108:111], v[176:179], v[64:67]
	v_mfma_f32_16x16x32_bf16 v[68:71], v[116:119], v[176:179], v[68:71]
	v_mfma_f32_16x16x32_bf16 v[72:75], v[108:111], v[184:187], v[72:75]
	v_mfma_f32_16x16x32_bf16 v[76:79], v[116:119], v[184:187], v[76:79]
	v_mfma_f32_16x16x32_bf16 v[80:83], v[108:111], v[192:195], v[80:83]
	v_mfma_f32_16x16x32_bf16 v[84:87], v[116:119], v[192:195], v[84:87]
	v_mfma_f32_16x16x32_bf16 v[88:91], v[108:111], v[200:203], v[88:91]
	v_mfma_f32_16x16x32_bf16 v[92:95], v[116:119], v[200:203], v[92:95]
	v_mfma_f32_16x16x32_bf16 v[32:35], v[164:167], v[172:175], v[32:35]
	v_mfma_f32_16x16x32_bf16 v[96:99], v[120:123], v[172:175], v[96:99]
	v_mfma_f32_16x16x32_bf16 v[172:175], v[168:171], v[176:179], v[32:35]
	v_mfma_f32_16x16x32_bf16 v[32:35], v[120:123], v[180:183], v[36:39]
	v_mfma_f32_16x16x32_bf16 v[204:207], v[124:127], v[176:179], v[96:99]
	v_mfma_f32_16x16x32_bf16 v[176:179], v[124:127], v[184:187], v[32:35]
	v_mfma_f32_16x16x32_bf16 v[32:35], v[164:167], v[180:183], v[40:43]
	v_mfma_f32_16x16x32_bf16 v[40:43], v[168:171], v[184:187], v[32:35]
	v_mfma_f32_16x16x32_bf16 v[32:35], v[120:123], v[188:191], v[44:47]
	v_mfma_f32_16x16x32_bf16 v[44:47], v[124:127], v[192:195], v[32:35]
	v_mfma_f32_16x16x32_bf16 v[32:35], v[164:167], v[188:191], v[48:51]
	v_mfma_f32_16x16x32_bf16 v[48:51], v[168:171], v[192:195], v[32:35]
	v_mfma_f32_16x16x32_bf16 v[32:35], v[120:123], v[196:199], v[52:55]
	v_mfma_f32_16x16x32_bf16 v[52:55], v[124:127], v[200:203], v[32:35]
	v_mfma_f32_16x16x32_bf16 v[32:35], v[164:167], v[196:199], v[56:59]
	v_mfma_f32_16x16x32_bf16 v[56:59], v[168:171], v[200:203], v[32:35]
	s_barrier
; #define PG8_STAGE(bufoff, gbase, voff) do { _Pragma("unroll") for (int _i = 0; _i < 2; ++_i) \
;         __builtin_amdgcn_global_load_lds((const unsigned*)((const char*)(gbase) + (voff)[_i]), (PG8_LAS unsigned*)(lds + (bufoff) + ldsw + _i * 8192), 16, 0, 0); } while (0)
; #define PG8_LDA(dst, b, h) do { _Pragma("unroll") for (int m = 0; m < 4; ++m) _Pragma("unroll") for (int k = 0; k < 2; ++k) dst[m][k] = *(const PG8_LAS bf16x8*)(lds + PG8_SA(b, h) + aoff + m * 2048 + k * 1024); } while (0)
; #define PG8_LDB(dst, b, h) do { _Pragma("unroll") for (int n = 0; n < 2; ++n) _Pragma("unroll") for (int k = 0; k < 2; ++k) dst[n][k] = *(const PG8_LAS bf16x8*)(lds + PG8_SB(b, h) + boff + n * 2048 + k * 1024); } while (0)
; #define PG8_MMA(ai, bj, At, Bt) do { __builtin_amdgcn_s_setprio(1); _Pragma("unroll") for (int m = 0; m < 4; ++m) _Pragma("unroll") for (int n = 0; n < 2; ++n) _Pragma("unroll") for (int k = 0; k < 2; ++k) \
;         acc[ai][bj][m][n] = mma16<F16>(Bt[n][k], At[m][k], acc[ai][bj][m][n]); __builtin_amdgcn_s_setprio(0); } while (0)
; #define PG8_WAIT_V(n) asm volatile("s_waitcnt vmcnt(" #n ")" ::: "memory")
; #define PG8_WAIT_L(n) asm volatile("s_waitcnt lgkmcnt(" #n ")" ::: "memory")
; #define PG8_BAR __builtin_amdgcn_s_barrier()
; #define PG8_SCHED __builtin_amdgcn_sched_barrier(0)
; template <class Epi, class Sched, bool ALIGN_EPI = false, bool SP2 = false, bool F16 = false>
; __device__ __forceinline__ void gemm_phase(PG8_LAS unsigned char* lds, const Gemm g, const Sched& S, const Epi& E, const int wid_in) {
;     ...
;             PG8_LDA(At, 0, 1); PG8_STAGE(PG8_SB(0, 0), b2, voffB); PG8_STAGE(PG8_SB(0, 1), b2 + hstep, voffB); PG8_STAGE(PG8_SA(0, 0), a2, voffA);
;             PG8_WAIT_V(8); PG8_WAIT_L(0); PG8_BAR; PG8_MMA(1, 0, At, B0); PG8_MMA(1, 1, At, B1); PG8_BAR; PG8_SCHED;
;             PG8_LDB(B0, 1, 0); PG8_LDB(B1, 1, 1); PG8_SCHED; PG8_LDA(At, 1, 0); PG8_STAGE(PG8_SA(0, 1), a2 + hstep, voffA);
;             PG8_WAIT_V(8); PG8_WAIT_L(0); PG8_BAR; PG8_MMA(0, 0, At, B0); PG8_MMA(0, 1, At, B1); PG8_BAR; PG8_SCHED;
	s_mov_b32 m0, s53
	v_lshl_add_u64 v[240:241], s[36:37], 0, v[130:131]
	s_add_u32 s46, s36, 0x10000
	s_nop 1
	ds_read_b128 v[32:35], v136 offset:16384
	ds_read_b128 v[36:39], v136 offset:17408
	ds_read_b128 v[96:99], v136 offset:18432
	ds_read_b128 v[180:183], v136 offset:19456
	ds_read_b128 v[184:187], v136 offset:20480
	ds_read_b128 v[188:191], v136 offset:21504
	ds_read_b128 v[192:195], v136 offset:22528
	ds_read_b128 v[196:199], v136 offset:23552
	global_load_lds_dwordx4 v[240:241], off
	v_lshl_add_u64 v[242:243], s[36:37], 0, v[128:129]
	s_mov_b32 m0, s54
	s_addc_u32 s47, s37, 0
	global_load_lds_dwordx4 v[242:243], off
	v_lshl_add_u64 v[200:201], s[46:47], 0, v[130:131]
	s_mov_b32 m0, s55
	v_lshl_add_u64 v[244:245], s[44:45], 0, v[130:131]
	global_load_lds_dwordx4 v[200:201], off
	v_lshl_add_u64 v[200:201], s[46:47], 0, v[128:129]
	s_mov_b32 m0, s56
	v_lshl_add_u64 v[246:247], s[44:45], 0, v[128:129]
	global_load_lds_dwordx4 v[200:201], off
	s_mov_b32 m0, s74
	s_nop 0
	global_load_lds_dwordx4 v[244:245], off
	s_mov_b32 m0, s43
	s_nop 0
	global_load_lds_dwordx4 v[246:247], off
	s_waitcnt vmcnt(8)
	s_waitcnt lgkmcnt(0)
	s_barrier
	s_waitcnt lgkmcnt(0)
	v_mfma_f32_16x16x32_bf16 v[0:3], v[104:107], v[192:195], v[0:3]
	v_mfma_f32_16x16x32_bf16 v[140:143], v[104:107], v[32:35], v[140:143]
	v_mfma_f32_16x16x32_bf16 v[144:147], v[112:115], v[32:35], v[144:147]
	v_mfma_f32_16x16x32_bf16 v[148:151], v[104:107], v[96:99], v[148:151]
	v_mfma_f32_16x16x32_bf16 v[152:155], v[112:115], v[96:99], v[152:155]
	v_mfma_f32_16x16x32_bf16 v[156:159], v[104:107], v[184:187], v[156:159]
	v_mfma_f32_16x16x32_bf16 v[160:163], v[112:115], v[184:187], v[160:163]
	v_mfma_f32_16x16x32_bf16 v[0:3], v[108:111], v[196:199], v[0:3]
	v_mfma_f32_16x16x32_bf16 v[4:7], v[112:115], v[192:195], v[4:7]
	v_mfma_f32_16x16x32_bf16 v[140:143], v[108:111], v[36:39], v[140:143]
	v_mfma_f32_16x16x32_bf16 v[144:147], v[116:119], v[36:39], v[144:147]
	v_mfma_f32_16x16x32_bf16 v[148:151], v[108:111], v[180:183], v[148:151]
	v_mfma_f32_16x16x32_bf16 v[152:155], v[116:119], v[180:183], v[152:155]
	v_mfma_f32_16x16x32_bf16 v[156:159], v[108:111], v[188:191], v[156:159]
	v_mfma_f32_16x16x32_bf16 v[160:163], v[116:119], v[188:191], v[160:163]
	v_mfma_f32_16x16x32_bf16 v[200:203], v[116:119], v[196:199], v[4:7]
	v_mfma_f32_16x16x32_bf16 v[4:7], v[120:123], v[32:35], v[8:11]
	v_mfma_f32_16x16x32_bf16 v[8:11], v[124:127], v[36:39], v[4:7]
	v_mfma_f32_16x16x32_bf16 v[4:7], v[164:167], v[32:35], v[12:15]
	v_mfma_f32_16x16x32_bf16 v[12:15], v[168:171], v[36:39], v[4:7]
	v_mfma_f32_16x16x32_bf16 v[4:7], v[120:123], v[96:99], v[24:27]
	v_mfma_f32_16x16x32_bf16 v[24:27], v[124:127], v[180:183], v[4:7]
	v_mfma_f32_16x16x32_bf16 v[4:7], v[164:167], v[96:99], v[28:31]
	v_mfma_f32_16x16x32_bf16 v[28:31], v[168:171], v[180:183], v[4:7]
	v_mfma_f32_16x16x32_bf16 v[4:7], v[120:123], v[184:187], v[60:63]
	v_mfma_f32_16x16x32_bf16 v[180:183], v[124:127], v[188:191], v[4:7]
	v_mfma_f32_16x16x32_bf16 v[4:7], v[164:167], v[184:187], v[100:103]
	v_mfma_f32_16x16x32_bf16 v[184:187], v[168:171], v[188:191], v[4:7]
	v_mfma_f32_16x16x32_bf16 v[4:7], v[120:123], v[192:195], v[16:19]
	v_mfma_f32_16x16x32_bf16 v[188:191], v[124:127], v[196:199], v[4:7]
	v_mfma_f32_16x16x32_bf16 v[4:7], v[164:167], v[192:195], v[20:23]
	v_mfma_f32_16x16x32_bf16 v[164:167], v[168:171], v[196:199], v[4:7]
	s_barrier
	s_nop 4
	ds_read_b128 v[4:7], v137
	ds_read_b128 v[60:63], v137 offset:1024
	ds_read_b128 v[168:171], v137 offset:2048
	ds_read_b128 v[192:195], v137 offset:3072
	ds_read_b128 v[196:199], v138
	ds_read_b128 v[208:211], v138 offset:1024
	ds_read_b128 v[212:215], v138 offset:2048
	ds_read_b128 v[216:219], v138 offset:3072
	s_add_u32 s44, s44, 0x10000
	s_addc_u32 s45, s45, 0
	s_mov_b32 m0, s50
	v_lshl_add_u64 v[32:33], s[44:45], 0, v[130:131]
	ds_read_b128 v[16:19], v136 offset:32768
	ds_read_b128 v[20:23], v136 offset:33792
	ds_read_b128 v[104:107], v136 offset:34816
	ds_read_b128 v[220:223], v136 offset:35840
	ds_read_b128 v[224:227], v136 offset:36864
	ds_read_b128 v[228:231], v136 offset:37888
	ds_read_b128 v[232:235], v136 offset:38912
	ds_read_b128 v[236:239], v136 offset:39936
	global_load_lds_dwordx4 v[32:33], off
	v_lshl_add_u64 v[32:33], s[44:45], 0, v[128:129]
	s_mov_b32 m0, s51
	s_nop 0
	global_load_lds_dwordx4 v[32:33], off
	s_waitcnt vmcnt(8)
	s_waitcnt lgkmcnt(0)
	s_barrier
	s_waitcnt lgkmcnt(0)
	v_mfma_f32_16x16x32_bf16 v[32:35], v[4:7], v[16:19], v[64:67]
	v_mfma_f32_16x16x32_bf16 v[116:119], v[60:63], v[20:23], v[32:35]
	v_mfma_f32_16x16x32_bf16 v[32:35], v[168:171], v[16:19], v[68:71]
	v_mfma_f32_16x16x32_bf16 v[112:115], v[192:195], v[20:23], v[32:35]
	v_mfma_f32_16x16x32_bf16 v[32:35], v[4:7], v[104:107], v[72:75]
	v_mfma_f32_16x16x32_bf16 v[100:103], v[60:63], v[220:223], v[32:35]
	v_mfma_f32_16x16x32_bf16 v[32:35], v[168:171], v[104:107], v[76:79]
	v_mfma_f32_16x16x32_bf16 v[96:99], v[192:195], v[220:223], v[32:35]
	v_mfma_f32_16x16x32_bf16 v[32:35], v[4:7], v[224:227], v[80:83]
	v_mfma_f32_16x16x32_bf16 v[68:71], v[60:63], v[228:231], v[32:35]
	v_mfma_f32_16x16x32_bf16 v[32:35], v[168:171], v[224:227], v[84:87]
	v_mfma_f32_16x16x32_bf16 v[64:67], v[192:195], v[228:231], v[32:35]
	v_mfma_f32_16x16x32_bf16 v[32:35], v[4:7], v[232:235], v[88:91]
	v_mfma_f32_16x16x32_bf16 v[36:39], v[60:63], v[236:239], v[32:35]
	v_mfma_f32_16x16x32_bf16 v[32:35], v[168:171], v[232:235], v[92:95]
	v_mfma_f32_16x16x32_bf16 v[32:35], v[192:195], v[236:239], v[32:35]
	v_mfma_f32_16x16x32_bf16 v[72:75], v[196:199], v[16:19], v[204:207]
	v_mfma_f32_16x16x32_bf16 v[16:19], v[212:215], v[16:19], v[172:175]
	v_mfma_f32_16x16x32_bf16 v[120:123], v[216:219], v[20:23], v[16:19]
	v_mfma_f32_16x16x32_bf16 v[16:19], v[196:199], v[104:107], v[176:179]
	v_mfma_f32_16x16x32_bf16 v[108:111], v[208:211], v[220:223], v[16:19]
	v_mfma_f32_16x16x32_bf16 v[16:19], v[212:215], v[104:107], v[40:43]
	v_mfma_f32_16x16x32_bf16 v[104:107], v[216:219], v[220:223], v[16:19]
	v_mfma_f32_16x16x32_bf16 v[16:19], v[196:199], v[224:227], v[44:47]
	v_mfma_f32_16x16x32_bf16 v[80:83], v[208:211], v[228:231], v[16:19]
	v_mfma_f32_16x16x32_bf16 v[16:19], v[212:215], v[224:227], v[48:51]
	v_mfma_f32_16x16x32_bf16 v[124:127], v[208:211], v[20:23], v[72:75]
	v_mfma_f32_16x16x32_bf16 v[72:75], v[216:219], v[228:231], v[16:19]
	v_mfma_f32_16x16x32_bf16 v[16:19], v[196:199], v[232:235], v[52:55]
	v_mfma_f32_16x16x32_bf16 v[48:51], v[208:211], v[236:239], v[16:19]
	v_mfma_f32_16x16x32_bf16 v[16:19], v[212:215], v[232:235], v[56:59]
	v_mfma_f32_16x16x32_bf16 v[40:43], v[216:219], v[236:239], v[16:19]
	s_barrier
; #define PG8_STAGE(bufoff, gbase, voff) do { _Pragma("unroll") for (int _i = 0; _i < 2; ++_i) \
;         __builtin_amdgcn_global_load_lds((const unsigned*)((const char*)(gbase) + (voff)[_i]), (PG8_LAS unsigned*)(lds + (bufoff) + ldsw + _i * 8192), 16, 0, 0); } while (0)
; #define PG8_LDA(dst, b, h) do { _Pragma("unroll") for (int m = 0; m < 4; ++m) _Pragma("unroll") for (int k = 0; k < 2; ++k) dst[m][k] = *(const PG8_LAS bf16x8*)(lds + PG8_SA(b, h) + aoff + m * 2048 + k * 1024); } while (0)
; #define PG8_MMA(ai, bj, At, Bt) do { __builtin_amdgcn_s_setprio(1); _Pragma("unroll") for (int m = 0; m < 4; ++m) _Pragma("unroll") for (int n = 0; n < 2; ++n) _Pragma("unroll") for (int k = 0; k < 2; ++k) \
;         acc[ai][bj][m][n] = mma16<F16>(Bt[n][k], At[m][k], acc[ai][bj][m][n]); __builtin_amdgcn_s_setprio(0); } while (0)
; #define PG8_WAIT_V(n) asm volatile("s_waitcnt vmcnt(" #n ")" ::: "memory")
; #define PG8_WAIT_L(n) asm volatile("s_waitcnt lgkmcnt(" #n ")" ::: "memory")
; #define PG8_BAR __builtin_amdgcn_s_barrier()
; #define PG8_SCHED __builtin_amdgcn_sched_barrier(0)
; template <class Epi, class Sched, bool ALIGN_EPI = false, bool SP2 = false, bool F16 = false>
; __device__ __forceinline__ void gemm_phase(PG8_LAS unsigned char* lds, const Gemm g, const Sched& S, const Epi& E, const int wid_in) {
;     ...
;             PG8_LDA(At, 1, 1); PG8_STAGE(PG8_SB(1, 0), b3, voffB); PG8_STAGE(PG8_SB(1, 1), b3 + hstep, voffB); PG8_STAGE(PG8_SA(1, 0), a3, voffA);
;             PG8_WAIT_V(8); PG8_WAIT_L(0); PG8_BAR; PG8_MMA(1, 0, At, B0); PG8_MMA(1, 1, At, B1); PG8_BAR; PG8_SCHED;
;     ...
;         if constexpr (ALIGN_EPI) { if (wr == 0) PG8_BAR; }
	s_mov_b32 m0, s57
	s_nop 3
	v_lshl_add_u64 v[16:17], v[240:241], 0, s[24:25]
	s_add_u32 s36, s36, 0x10080
	ds_read_b128 v[56:59], v136 offset:49152
	ds_read_b128 v[88:91], v136 offset:50176
	ds_read_b128 v[172:175], v136 offset:51200
	ds_read_b128 v[176:179], v136 offset:52224
	ds_read_b128 v[204:207], v136 offset:53248
	ds_read_b128 v[220:223], v136 offset:54272
	ds_read_b128 v[224:227], v136 offset:55296
	ds_read_b128 v[228:231], v136 offset:56320
	global_load_lds_dwordx4 v[16:17], off
	v_lshl_add_u64 v[16:17], v[242:243], 0, s[24:25]
	s_mov_b32 m0, s58
	s_addc_u32 s37, s37, 0
	global_load_lds_dwordx4 v[16:17], off
	v_lshl_add_u64 v[16:17], s[36:37], 0, v[130:131]
	s_mov_b32 m0, s59
	s_nop 0
	global_load_lds_dwordx4 v[16:17], off
	v_lshl_add_u64 v[16:17], s[36:37], 0, v[128:129]
	s_mov_b32 m0, s60
	s_nop 0
	global_load_lds_dwordx4 v[16:17], off
	v_lshl_add_u64 v[16:17], v[244:245], 0, s[24:25]
	s_mov_b32 m0, s75
	s_nop 0
	global_load_lds_dwordx4 v[16:17], off
	v_lshl_add_u64 v[16:17], v[246:247], 0, s[24:25]
	s_mov_b32 m0, s14
	s_nop 0
	global_load_lds_dwordx4 v[16:17], off
	s_waitcnt vmcnt(8)
	s_waitcnt lgkmcnt(0)
	s_barrier
	s_waitcnt lgkmcnt(0)
	v_mfma_f32_16x16x32_bf16 v[16:19], v[4:7], v[56:59], v[140:143]
	v_mfma_f32_16x16x32_bf16 v[84:87], v[60:63], v[88:91], v[16:19]
	v_mfma_f32_16x16x32_bf16 v[16:19], v[168:171], v[56:59], v[144:147]
	v_mfma_f32_16x16x32_bf16 v[76:79], v[192:195], v[88:91], v[16:19]
	v_mfma_f32_16x16x32_bf16 v[16:19], v[4:7], v[172:175], v[148:151]
	v_mfma_f32_16x16x32_bf16 v[52:55], v[60:63], v[176:179], v[16:19]
	v_mfma_f32_16x16x32_bf16 v[16:19], v[168:171], v[172:175], v[152:155]
	v_mfma_f32_16x16x32_bf16 v[44:47], v[192:195], v[176:179], v[16:19]
	v_mfma_f32_16x16x32_bf16 v[16:19], v[4:7], v[204:207], v[156:159]
	v_mfma_f32_16x16x32_bf16 v[0:3], v[4:7], v[224:227], v[0:3]
	v_mfma_f32_16x16x32_bf16 v[20:23], v[60:63], v[220:223], v[16:19]
	v_mfma_f32_16x16x32_bf16 v[16:19], v[168:171], v[204:207], v[160:163]
	v_mfma_f32_16x16x32_bf16 v[4:7], v[60:63], v[228:231], v[0:3]
	v_mfma_f32_16x16x32_bf16 v[0:3], v[168:171], v[224:227], v[200:203]
	v_mfma_f32_16x16x32_bf16 v[16:19], v[192:195], v[220:223], v[16:19]
	v_mfma_f32_16x16x32_bf16 v[0:3], v[192:195], v[228:231], v[0:3]
	v_mfma_f32_16x16x32_bf16 v[8:11], v[196:199], v[56:59], v[8:11]
	v_mfma_f32_16x16x32_bf16 v[92:95], v[208:211], v[88:91], v[8:11]
	v_mfma_f32_16x16x32_bf16 v[8:11], v[212:215], v[56:59], v[12:15]
	v_mfma_f32_16x16x32_bf16 v[88:91], v[216:219], v[88:91], v[8:11]
	v_mfma_f32_16x16x32_bf16 v[8:11], v[196:199], v[172:175], v[24:27]
	v_mfma_f32_16x16x32_bf16 v[60:63], v[208:211], v[176:179], v[8:11]
	v_mfma_f32_16x16x32_bf16 v[8:11], v[212:215], v[172:175], v[28:31]
	v_mfma_f32_16x16x32_bf16 v[56:59], v[216:219], v[176:179], v[8:11]
	v_mfma_f32_16x16x32_bf16 v[8:11], v[196:199], v[204:207], v[180:183]
	v_mfma_f32_16x16x32_bf16 v[28:31], v[208:211], v[220:223], v[8:11]
	v_mfma_f32_16x16x32_bf16 v[8:11], v[212:215], v[204:207], v[184:187]
	v_mfma_f32_16x16x32_bf16 v[24:27], v[216:219], v[220:223], v[8:11]
	v_mfma_f32_16x16x32_bf16 v[8:11], v[196:199], v[224:227], v[188:191]
	v_mfma_f32_16x16x32_bf16 v[12:15], v[208:211], v[228:231], v[8:11]
	v_mfma_f32_16x16x32_bf16 v[8:11], v[212:215], v[224:227], v[164:167]
	v_mfma_f32_16x16x32_bf16 v[8:11], v[216:219], v[228:231], v[8:11]
	s_barrier
	s_and_b64 vcc, exec, s[8:9]
	s_cbranch_vccnz .LBB0_1279
	s_barrier
; __device__ __forceinline__ unsigned cvt_pk_bf16(float lo, float hi) { const f32x2cv v = {lo, hi}; const bf16x2cv b = __builtin_convertvector(v, bf16x2cv); return __builtin_bit_cast(unsigned, b); }
; #define PG8_WAIT_V(n) asm volatile("s_waitcnt vmcnt(" #n ")" ::: "memory")
; #define PG8_BAR __builtin_amdgcn_s_barrier()
;     __device__ __forceinline__ void operator()(const f32x4 (&acc)[2][2][4][2], const Unit& u, int wr, int wc, int fr, int fq) const {
;         asm volatile("" : "+v"(fr), "+v"(fq));
;         const int col0 = u.pn * BM + wc * 32 + 4 * fq;
; #pragma unroll
;         for (int ai = 0; ai < 2; ++ai)
; #pragma unroll
;             for (int m = 0; m < 4; ++m) { const int row = u.pm * BM + ai * HALF + wr * 64 + m * 16 + fr; const size_t off = (size_t)row * 1024 + col0;
; #pragma unroll
;                 for (int bj = 0; bj < 2; ++bj)
; #pragma unroll
;                     for (int n = 0; n < 2; ++n) { const f32x4 a = acc[ai][bj][m][n]; u32x2 w; w.x = cvt_pk_bf16(a[0], a[1]); w.y = cvt_pk_bf16(a[2], a[3]); *(u32x2*)(hb_ptr(off + bj * HALF + n * 16)) = w; } }
;     }
; template <class Epi, class Sched, bool ALIGN_EPI = false, bool SP2 = false, bool F16 = false>
; __device__ __forceinline__ void gemm_phase(PG8_LAS unsigned char* lds, const Gemm g, const Sched& S, const Epi& E, const int wid_in) {
;     ...
;         if (!has_next) break;
; #pragma unroll
;         for (int a = 0; a < 2; ++a)
; #pragma unroll
;             for (int b = 0; b < 2; ++b)
; #pragma unroll
;                 for (int m = 0; m < 4; ++m)
; #pragma unroll
;                     for (int n = 0; n < 2; ++n) acc[a][b][m][n] = (f32x4){0.f, 0.f, 0.f, 0.f};
;         cur = nxt; cA = nA; cB = nB; ++ui;
;         if constexpr (ALIGN_EPI) { if (wr == 1) PG8_BAR; }
;     }
;     PG8_WAIT_V(0);
;     if constexpr (!ALIGN_EPI) { if (wr == 0) PG8_BAR; }
.LBB0_1279:
	s_lshl_b32 s34, s34, 8
	v_mov_b32_e32 v139, v132
	v_mov_b32_e32 v140, v133
	s_lshl_b32 s35, s63, 8
	s_add_i32 s34, s34, s70
	s_or_b32 s35, s35, s82
	v_add_u32_e32 v142, s34, v139
	v_lshl_add_u32 v140, v140, 2, s35
	v_ashrrev_i32_e32 v143, 31, v142
	v_ashrrev_i32_e32 v141, 31, v140
	v_lshlrev_b64 v[144:145], 11, v[142:143]
	v_cvt_pk_bf16_f32 v116, v116, v117
	v_cvt_pk_bf16_f32 v117, v118, v119
	v_lshl_add_u64 v[118:119], s[22:23], 0, v[144:145]
	v_lshlrev_b64 v[140:141], 1, v[140:141]
	v_lshl_add_u64 v[118:119], v[118:119], 0, v[140:141]
	v_cvt_pk_bf16_f32 v112, v112, v113
	v_cvt_pk_bf16_f32 v113, v114, v115
	global_store_dwordx2 v[118:119], v[112:113], off offset:32
	v_cvt_pk_bf16_f32 v112, v124, v125
	v_cvt_pk_bf16_f32 v113, v126, v127
	global_store_dwordx2 v[118:119], v[112:113], off offset:256
	v_cvt_pk_bf16_f32 v112, v120, v121
	v_cvt_pk_bf16_f32 v113, v122, v123
	global_store_dwordx2 v[118:119], v[112:113], off offset:288
	v_add_u32_e32 v112, 16, v142
	v_ashrrev_i32_e32 v113, 31, v112
	v_lshlrev_b64 v[112:113], 11, v[112:113]
	v_cvt_pk_bf16_f32 v100, v100, v101
	v_cvt_pk_bf16_f32 v101, v102, v103
	v_lshl_add_u64 v[102:103], s[22:23], 0, v[112:113]
	v_lshl_add_u64 v[102:103], v[102:103], 0, v[140:141]
	v_cvt_pk_bf16_f32 v96, v96, v97
	v_cvt_pk_bf16_f32 v97, v98, v99
	global_store_dwordx2 v[102:103], v[96:97], off offset:32
	v_cvt_pk_bf16_f32 v96, v108, v109
	v_cvt_pk_bf16_f32 v97, v110, v111
	global_store_dwordx2 v[102:103], v[96:97], off offset:256
	v_cvt_pk_bf16_f32 v96, v104, v105
	v_cvt_pk_bf16_f32 v97, v106, v107
	global_store_dwordx2 v[102:103], v[96:97], off offset:288
	v_add_u32_e32 v96, 32, v142
	v_ashrrev_i32_e32 v97, 31, v96
	v_lshlrev_b64 v[96:97], 11, v[96:97]
	v_cvt_pk_bf16_f32 v68, v68, v69
	v_cvt_pk_bf16_f32 v69, v70, v71
	v_lshl_add_u64 v[70:71], s[22:23], 0, v[96:97]
	v_lshl_add_u64 v[70:71], v[70:71], 0, v[140:141]
	v_cvt_pk_bf16_f32 v64, v64, v65
	v_cvt_pk_bf16_f32 v65, v66, v67
	global_store_dwordx2 v[70:71], v[64:65], off offset:32
	v_cvt_pk_bf16_f32 v64, v80, v81
	v_cvt_pk_bf16_f32 v65, v82, v83
	global_store_dwordx2 v[70:71], v[64:65], off offset:256
	v_cvt_pk_bf16_f32 v64, v72, v73
	v_cvt_pk_bf16_f32 v65, v74, v75
	global_store_dwordx2 v[70:71], v[64:65], off offset:288
	v_add_u32_e32 v64, 48, v142
	v_ashrrev_i32_e32 v65, 31, v64
	v_lshlrev_b64 v[64:65], 11, v[64:65]
	v_cvt_pk_bf16_f32 v36, v36, v37
	v_cvt_pk_bf16_f32 v37, v38, v39
	v_lshl_add_u64 v[38:39], s[22:23], 0, v[64:65]
	v_lshl_add_u64 v[38:39], v[38:39], 0, v[140:141]
	v_cvt_pk_bf16_f32 v32, v32, v33
	v_cvt_pk_bf16_f32 v33, v34, v35
	global_store_dwordx2 v[38:39], v[32:33], off offset:32
	v_cvt_pk_bf16_f32 v32, v48, v49
	v_cvt_pk_bf16_f32 v33, v50, v51
	global_store_dwordx2 v[38:39], v[32:33], off offset:256
	v_cvt_pk_bf16_f32 v32, v40, v41
	v_cvt_pk_bf16_f32 v33, v42, v43
	global_store_dwordx2 v[38:39], v[32:33], off offset:288
	v_add_u32_e32 v32, 0x80, v142
	v_ashrrev_i32_e32 v33, 31, v32
	v_lshlrev_b64 v[32:33], 11, v[32:33]
	v_lshl_add_u64 v[32:33], s[22:23], 0, v[32:33]
	v_cvt_pk_bf16_f32 v34, v84, v85
	v_cvt_pk_bf16_f32 v35, v86, v87
	v_lshl_add_u64 v[32:33], v[32:33], 0, v[140:141]
	global_store_dwordx2 v[32:33], v[34:35], off
	v_cvt_pk_bf16_f32 v34, v76, v77
	v_cvt_pk_bf16_f32 v35, v78, v79
	global_store_dwordx2 v[32:33], v[34:35], off offset:32
	v_cvt_pk_bf16_f32 v34, v92, v93
	v_cvt_pk_bf16_f32 v35, v94, v95
	global_store_dwordx2 v[32:33], v[34:35], off offset:256
	v_cvt_pk_bf16_f32 v34, v88, v89
	v_cvt_pk_bf16_f32 v35, v90, v91
	global_store_dwordx2 v[32:33], v[34:35], off offset:288
	v_add_u32_e32 v32, 0x90, v142
	v_ashrrev_i32_e32 v33, 31, v32
	v_lshlrev_b64 v[32:33], 11, v[32:33]
	v_lshl_add_u64 v[32:33], s[22:23], 0, v[32:33]
	v_cvt_pk_bf16_f32 v34, v52, v53
	v_cvt_pk_bf16_f32 v35, v54, v55
	v_lshl_add_u64 v[32:33], v[32:33], 0, v[140:141]
	global_store_dwordx2 v[32:33], v[34:35], off
	v_cvt_pk_bf16_f32 v34, v44, v45
	v_cvt_pk_bf16_f32 v35, v46, v47
	global_store_dwordx2 v[32:33], v[34:35], off offset:32
	v_cvt_pk_bf16_f32 v34, v60, v61
	v_cvt_pk_bf16_f32 v35, v62, v63
	global_store_dwordx2 v[32:33], v[34:35], off offset:256
	v_cvt_pk_bf16_f32 v34, v56, v57
	v_cvt_pk_bf16_f32 v35, v58, v59
	global_store_dwordx2 v[32:33], v[34:35], off offset:288
	v_add_u32_e32 v32, 0xa0, v142
	v_ashrrev_i32_e32 v33, 31, v32
	v_lshlrev_b64 v[32:33], 11, v[32:33]
	v_cvt_pk_bf16_f32 v20, v20, v21
	v_cvt_pk_bf16_f32 v21, v22, v23
	v_lshl_add_u64 v[22:23], s[22:23], 0, v[32:33]
	v_lshl_add_u64 v[22:23], v[22:23], 0, v[140:141]
	v_cvt_pk_bf16_f32 v16, v16, v17
	v_cvt_pk_bf16_f32 v17, v18, v19
	global_store_dwordx2 v[22:23], v[16:17], off offset:32
	v_cvt_pk_bf16_f32 v16, v28, v29
	v_cvt_pk_bf16_f32 v17, v30, v31
	global_store_dwordx2 v[22:23], v[16:17], off offset:256
	v_cvt_pk_bf16_f32 v16, v24, v25
	v_cvt_pk_bf16_f32 v17, v26, v27
	global_store_dwordx2 v[22:23], v[16:17], off offset:288
	v_add_u32_e32 v16, 0xb0, v142
	v_ashrrev_i32_e32 v17, 31, v16
	v_lshlrev_b64 v[16:17], 11, v[16:17]
	v_cvt_pk_bf16_f32 v4, v4, v5
	v_cvt_pk_bf16_f32 v5, v6, v7
	v_lshl_add_u64 v[6:7], s[22:23], 0, v[16:17]
	v_lshl_add_u64 v[6:7], v[6:7], 0, v[140:141]
	v_cvt_pk_bf16_f32 v0, v0, v1
	v_cvt_pk_bf16_f32 v1, v2, v3
	global_store_dwordx2 v[6:7], v[0:1], off offset:32
	v_cvt_pk_bf16_f32 v0, v12, v13
	v_cvt_pk_bf16_f32 v1, v14, v15
	global_store_dwordx2 v[6:7], v[0:1], off offset:256
	v_cvt_pk_bf16_f32 v0, v8, v9
	v_cvt_pk_bf16_f32 v1, v10, v11
	s_andn2_b64 vcc, exec, s[30:31]
	s_mov_b64 s[34:35], -1
	global_store_dwordx2 v[118:119], v[116:117], off
	global_store_dwordx2 v[102:103], v[100:101], off
	global_store_dwordx2 v[70:71], v[68:69], off
	global_store_dwordx2 v[38:39], v[36:37], off
	global_store_dwordx2 v[22:23], v[20:21], off
	global_store_dwordx2 v[6:7], v[4:5], off
	global_store_dwordx2 v[6:7], v[0:1], off offset:288
	s_cbranch_vccnz .LBB0_1276
	s_setprio 0
	s_and_b64 vcc, exec, s[6:7]
	s_cbranch_vccnz .LBB0_1275
	s_barrier
	s_branch .LBB0_1275

; #define PG8_STAGE(bufoff, gbase, voff) do { _Pragma("unroll") for (int _i = 0; _i < 2; ++_i) \
;         __builtin_amdgcn_global_load_lds((const unsigned*)((const char*)(gbase) + (voff)[_i]), (PG8_LAS unsigned*)(lds + (bufoff) + ldsw + _i * 8192), 16, 0, 0); } while (0)
; #define PG8_LDA(dst, b, h) do { _Pragma("unroll") for (int m = 0; m < 4; ++m) _Pragma("unroll") for (int k = 0; k < 2; ++k) dst[m][k] = *(const PG8_LAS bf16x8*)(lds + PG8_SA(b, h) + aoff + m * 2048 + k * 1024); } while (0)
; #define PG8_LDB(dst, b, h) do { _Pragma("unroll") for (int n = 0; n < 2; ++n) _Pragma("unroll") for (int k = 0; k < 2; ++k) dst[n][k] = *(const PG8_LAS bf16x8*)(lds + PG8_SB(b, h) + boff + n * 2048 + k * 1024); } while (0)
; #define PG8_WAIT_V(n) asm volatile("s_waitcnt vmcnt(" #n ")" ::: "memory")
; #define PG8_WAIT_L(n) asm volatile("s_waitcnt lgkmcnt(" #n ")" ::: "memory")
; #define PG8_BAR __builtin_amdgcn_s_barrier()
; #define PG8_SCHED __builtin_amdgcn_sched_barrier(0)
; template <class Epi, class Sched, bool ALIGN_EPI = false, bool SP2 = false, bool F16 = false>
; __device__ __forceinline__ void gemm_phase(PG8_LAS unsigned char* lds, const Gemm g, const Sched& S, const Epi& E, const int wid_in) {
;     ...
;         const char* nA = has_next ? (const char*)g.A + (size_t)nxt.pm * tstep : cA; const char* nB = has_next ? (const char*)g.Bt + (size_t)nxt.pn * tstep : cB;
;         for (int t = 0; t < nt; t += 2) {
;             const bool last = (t == nt - 2);
;             const char* a1 = cA + (size_t)(t + 1) * kstep;
;             const char* a2 = last ? nA : cA + (size_t)(t + 2) * kstep; const char* b2 = last ? nB : cB + (size_t)(t + 2) * kstep;
;             const char* a3 = a2 + kstep; const char* b3 = b2 + kstep;
;             if (last && has_next) S.a_ready(nxt);
;             if constexpr (SP2) {
;             PG8_LDB(B0, 0, 0); PG8_LDB(B1, 0, 1); PG8_SCHED; PG8_LDA(At, 0, 0); PG8_STAGE(PG8_SA(1, 1), a1 + hstep, voffA);
;             PG8_WAIT_V(8); PG8_WAIT_L(0); PG8_BAR; PG8_MMA(0, 0, At, B0); PG8_MMA(0, 1, At, B1); PG8_BAR; PG8_SCHED;
;     ...
; #pragma unroll
;         for (int a = 0; a < 2; ++a)
; #pragma unroll
;             for (int b = 0; b < 2; ++b)
; #pragma unroll
;                 for (int m = 0; m < 4; ++m)
; #pragma unroll
;                     for (int n = 0; n < 2; ++n) acc[a][b][m][n] = (f32x4){0.f, 0.f, 0.f, 0.f};
.LBB0_1372:
	s_add_u32 s43, s44, 0x100
	v_mov_b32_e32 v0, 0
	s_addc_u32 s61, s45, 0
	s_mov_b32 s62, -2
	v_mov_b32_e32 v1, v0
	v_mov_b32_e32 v2, v0
	v_mov_b32_e32 v3, v0
	v_mov_b32_e32 v4, v0
	v_mov_b32_e32 v5, v0
	v_mov_b32_e32 v6, v0
	v_mov_b32_e32 v7, v0
	v_mov_b32_e32 v16, v0
	v_mov_b32_e32 v17, v0
	v_mov_b32_e32 v18, v0
	v_mov_b32_e32 v19, v0
	v_mov_b32_e32 v20, v0
	v_mov_b32_e32 v21, v0
	v_mov_b32_e32 v22, v0
	v_mov_b32_e32 v23, v0
	v_mov_b32_e32 v32, v0
	v_mov_b32_e32 v33, v0
	v_mov_b32_e32 v34, v0
	v_mov_b32_e32 v35, v0
	v_mov_b32_e32 v36, v0
	v_mov_b32_e32 v37, v0
	v_mov_b32_e32 v38, v0
	v_mov_b32_e32 v39, v0
	v_mov_b32_e32 v48, v0
	v_mov_b32_e32 v49, v0
	v_mov_b32_e32 v50, v0
	v_mov_b32_e32 v51, v0
	v_mov_b32_e32 v52, v0
	v_mov_b32_e32 v53, v0
	v_mov_b32_e32 v54, v0
	v_mov_b32_e32 v55, v0
	v_mov_b32_e32 v8, v0
	v_mov_b32_e32 v9, v0
	v_mov_b32_e32 v10, v0
	v_mov_b32_e32 v11, v0
	v_mov_b32_e32 v12, v0
	v_mov_b32_e32 v13, v0
	v_mov_b32_e32 v14, v0
	v_mov_b32_e32 v15, v0
	v_mov_b32_e32 v24, v0
	v_mov_b32_e32 v25, v0
	v_mov_b32_e32 v26, v0
	v_mov_b32_e32 v27, v0
	v_mov_b32_e32 v28, v0
	v_mov_b32_e32 v29, v0
	v_mov_b32_e32 v30, v0
	v_mov_b32_e32 v31, v0
	v_mov_b32_e32 v40, v0
	v_mov_b32_e32 v41, v0
	v_mov_b32_e32 v42, v0
	v_mov_b32_e32 v43, v0
	v_mov_b32_e32 v44, v0
	v_mov_b32_e32 v45, v0
	v_mov_b32_e32 v46, v0
	v_mov_b32_e32 v47, v0
	v_mov_b32_e32 v56, v0
	v_mov_b32_e32 v57, v0
	v_mov_b32_e32 v58, v0
	v_mov_b32_e32 v59, v0
	v_mov_b32_e32 v60, v0
	v_mov_b32_e32 v61, v0
	v_mov_b32_e32 v62, v0
	v_mov_b32_e32 v63, v0
	v_mov_b32_e32 v64, v0
	v_mov_b32_e32 v65, v0
	v_mov_b32_e32 v66, v0
	v_mov_b32_e32 v67, v0
	v_mov_b32_e32 v68, v0
	v_mov_b32_e32 v69, v0
	v_mov_b32_e32 v70, v0
	v_mov_b32_e32 v71, v0
	v_mov_b32_e32 v80, v0
	v_mov_b32_e32 v81, v0
	v_mov_b32_e32 v82, v0
	v_mov_b32_e32 v83, v0
	v_mov_b32_e32 v84, v0
	v_mov_b32_e32 v85, v0
	v_mov_b32_e32 v86, v0
	v_mov_b32_e32 v87, v0
	v_mov_b32_e32 v96, v0
	v_mov_b32_e32 v97, v0
	v_mov_b32_e32 v98, v0
	v_mov_b32_e32 v99, v0
	v_mov_b32_e32 v100, v0
	v_mov_b32_e32 v101, v0
	v_mov_b32_e32 v102, v0
	v_mov_b32_e32 v103, v0
	v_mov_b32_e32 v112, v0
	v_mov_b32_e32 v113, v0
	v_mov_b32_e32 v114, v0
	v_mov_b32_e32 v115, v0
	v_mov_b32_e32 v116, v0
	v_mov_b32_e32 v117, v0
	v_mov_b32_e32 v118, v0
	v_mov_b32_e32 v119, v0
	v_mov_b32_e32 v72, v0
	v_mov_b32_e32 v73, v0
	v_mov_b32_e32 v74, v0
	v_mov_b32_e32 v75, v0
	v_mov_b32_e32 v76, v0
	v_mov_b32_e32 v77, v0
	v_mov_b32_e32 v78, v0
	v_mov_b32_e32 v79, v0
	v_mov_b32_e32 v88, v0
	v_mov_b32_e32 v89, v0
	v_mov_b32_e32 v90, v0
	v_mov_b32_e32 v91, v0
	v_mov_b32_e32 v92, v0
	v_mov_b32_e32 v93, v0
	v_mov_b32_e32 v94, v0
	v_mov_b32_e32 v95, v0
	v_mov_b32_e32 v104, v0
	v_mov_b32_e32 v105, v0
	v_mov_b32_e32 v106, v0
	v_mov_b32_e32 v107, v0
	v_mov_b32_e32 v108, v0
	v_mov_b32_e32 v109, v0
	v_mov_b32_e32 v110, v0
	v_mov_b32_e32 v111, v0
	v_mov_b32_e32 v120, v0
	v_mov_b32_e32 v121, v0
	v_mov_b32_e32 v122, v0
	v_mov_b32_e32 v123, v0
	v_mov_b32_e32 v124, v0
	v_mov_b32_e32 v125, v0
	v_mov_b32_e32 v126, v0
	v_mov_b32_e32 v127, v0
	s_cmp_ge_u32 s3, 4
	s_cbranch_scc0 .Lgsp_10
	s_setprio 1
.Lgsp_10:
.LBB0_1373:
	ds_read_b128 v[128:131], v189
	ds_read_b128 v[132:135], v189 offset:1024
	ds_read_b128 v[136:139], v189 offset:2048
	ds_read_b128 v[140:143], v189 offset:3072
	ds_read_b128 v[144:147], v190
	ds_read_b128 v[148:151], v190 offset:1024
	ds_read_b128 v[168:171], v190 offset:2048
	ds_read_b128 v[172:175], v190 offset:3072
	s_add_u32 s44, s36, 0x100
	s_addc_u32 s45, s37, 0
	s_cmp_eq_u32 s62, 40
	s_cselect_b32 s49, s13, s45
	s_cselect_b32 s48, s12, s44
	s_cselect_b32 s47, s35, s61
	s_cselect_b32 s46, s34, s43
	v_lshl_add_u64 v[184:185], s[36:37], 0, v[160:161]
	s_add_i32 m0, s74, 0xc000
	ds_read_b128 v[176:179], v191
	ds_read_b128 v[180:183], v191 offset:1024
	ds_read_b128 v[192:195], v191 offset:2048
	ds_read_b128 v[196:199], v191 offset:3072
	ds_read_b128 v[200:203], v191 offset:4096
	ds_read_b128 v[204:207], v191 offset:5120
	ds_read_b128 v[208:211], v191 offset:6144
	ds_read_b128 v[212:215], v191 offset:7168
	global_load_lds_dwordx4 v[184:185], off
	v_lshl_add_u64 v[184:185], s[36:37], 0, v[162:163]
	s_add_i32 m0, s74, 0xe000
	s_nop 0
	global_load_lds_dwordx4 v[184:185], off
	s_waitcnt vmcnt(8)
	s_waitcnt lgkmcnt(0)
	s_barrier
	s_waitcnt lgkmcnt(0)
	v_mfma_f32_16x16x32_bf16 v[124:127], v[128:131], v[176:179], v[124:127]
	v_mfma_f32_16x16x32_bf16 v[120:123], v[136:139], v[176:179], v[120:123]
	v_mfma_f32_16x16x32_bf16 v[108:111], v[128:131], v[192:195], v[108:111]
	v_mfma_f32_16x16x32_bf16 v[104:107], v[136:139], v[192:195], v[104:107]
	v_mfma_f32_16x16x32_bf16 v[92:95], v[128:131], v[200:203], v[92:95]
	v_mfma_f32_16x16x32_bf16 v[88:91], v[136:139], v[200:203], v[88:91]
	v_mfma_f32_16x16x32_bf16 v[76:79], v[128:131], v[208:211], v[76:79]
	v_mfma_f32_16x16x32_bf16 v[72:75], v[136:139], v[208:211], v[72:75]
	v_mfma_f32_16x16x32_bf16 v[124:127], v[132:135], v[180:183], v[124:127]
	v_mfma_f32_16x16x32_bf16 v[120:123], v[140:143], v[180:183], v[120:123]
	v_mfma_f32_16x16x32_bf16 v[108:111], v[132:135], v[196:199], v[108:111]
	v_mfma_f32_16x16x32_bf16 v[104:107], v[140:143], v[196:199], v[104:107]
	v_mfma_f32_16x16x32_bf16 v[92:95], v[132:135], v[204:207], v[92:95]
	v_mfma_f32_16x16x32_bf16 v[88:91], v[140:143], v[204:207], v[88:91]
	v_mfma_f32_16x16x32_bf16 v[76:79], v[132:135], v[212:215], v[76:79]
	v_mfma_f32_16x16x32_bf16 v[72:75], v[140:143], v[212:215], v[72:75]
	v_mfma_f32_16x16x32_bf16 v[116:119], v[144:147], v[176:179], v[116:119]
	v_mfma_f32_16x16x32_bf16 v[112:115], v[168:171], v[176:179], v[112:115]
	v_mfma_f32_16x16x32_bf16 v[100:103], v[144:147], v[192:195], v[100:103]
	v_mfma_f32_16x16x32_bf16 v[96:99], v[168:171], v[192:195], v[96:99]
	v_mfma_f32_16x16x32_bf16 v[84:87], v[144:147], v[200:203], v[84:87]
	v_mfma_f32_16x16x32_bf16 v[80:83], v[168:171], v[200:203], v[80:83]
	v_mfma_f32_16x16x32_bf16 v[68:71], v[144:147], v[208:211], v[68:71]
	v_mfma_f32_16x16x32_bf16 v[64:67], v[168:171], v[208:211], v[64:67]
	v_mfma_f32_16x16x32_bf16 v[116:119], v[148:151], v[180:183], v[116:119]
	v_mfma_f32_16x16x32_bf16 v[112:115], v[172:175], v[180:183], v[112:115]
	v_mfma_f32_16x16x32_bf16 v[100:103], v[148:151], v[196:199], v[100:103]
	v_mfma_f32_16x16x32_bf16 v[96:99], v[172:175], v[196:199], v[96:99]
	v_mfma_f32_16x16x32_bf16 v[84:87], v[148:151], v[204:207], v[84:87]
	v_mfma_f32_16x16x32_bf16 v[80:83], v[172:175], v[204:207], v[80:83]
	v_mfma_f32_16x16x32_bf16 v[68:71], v[148:151], v[212:215], v[68:71]
	v_mfma_f32_16x16x32_bf16 v[64:67], v[172:175], v[212:215], v[64:67]
	s_barrier
; #define PG8_STAGE(bufoff, gbase, voff) do { _Pragma("unroll") for (int _i = 0; _i < 2; ++_i) \
;         __builtin_amdgcn_global_load_lds((const unsigned*)((const char*)(gbase) + (voff)[_i]), (PG8_LAS unsigned*)(lds + (bufoff) + ldsw + _i * 8192), 16, 0, 0); } while (0)
; #define PG8_LDA(dst, b, h) do { _Pragma("unroll") for (int m = 0; m < 4; ++m) _Pragma("unroll") for (int k = 0; k < 2; ++k) dst[m][k] = *(const PG8_LAS bf16x8*)(lds + PG8_SA(b, h) + aoff + m * 2048 + k * 1024); } while (0)
; #define PG8_LDB(dst, b, h) do { _Pragma("unroll") for (int n = 0; n < 2; ++n) _Pragma("unroll") for (int k = 0; k < 2; ++k) dst[n][k] = *(const PG8_LAS bf16x8*)(lds + PG8_SB(b, h) + boff + n * 2048 + k * 1024); } while (0)
; #define PG8_MMA(ai, bj, At, Bt) do { __builtin_amdgcn_s_setprio(1); _Pragma("unroll") for (int m = 0; m < 4; ++m) _Pragma("unroll") for (int n = 0; n < 2; ++n) _Pragma("unroll") for (int k = 0; k < 2; ++k) \
;         acc[ai][bj][m][n] = mma16<F16>(Bt[n][k], At[m][k], acc[ai][bj][m][n]); __builtin_amdgcn_s_setprio(0); } while (0)
; #define PG8_WAIT_V(n) asm volatile("s_waitcnt vmcnt(" #n ")" ::: "memory")
; #define PG8_WAIT_L(n) asm volatile("s_waitcnt lgkmcnt(" #n ")" ::: "memory")
; #define PG8_BAR __builtin_amdgcn_s_barrier()
; #define PG8_SCHED __builtin_amdgcn_sched_barrier(0)
; template <class Epi, class Sched, bool ALIGN_EPI = false, bool SP2 = false, bool F16 = false>
; __device__ __forceinline__ void gemm_phase(PG8_LAS unsigned char* lds, const Gemm g, const Sched& S, const Epi& E, const int wid_in) {
;     ...
;             PG8_LDA(At, 0, 1); PG8_STAGE(PG8_SB(0, 0), b2, voffB); PG8_STAGE(PG8_SB(0, 1), b2 + hstep, voffB); PG8_STAGE(PG8_SA(0, 0), a2, voffA);
;             PG8_WAIT_V(8); PG8_WAIT_L(0); PG8_BAR; PG8_MMA(1, 0, At, B0); PG8_MMA(1, 1, At, B1); PG8_BAR; PG8_SCHED;
;             PG8_LDB(B0, 1, 0); PG8_LDB(B1, 1, 1); PG8_SCHED; PG8_LDA(At, 1, 0); PG8_STAGE(PG8_SA(0, 1), a2 + hstep, voffA);
	s_add_i32 s36, s56, s68
	v_lshl_add_u64 v[184:185], s[46:47], 0, v[154:155]
	s_mov_b32 m0, s36
	ds_read_b128 v[176:179], v191 offset:16384
	ds_read_b128 v[180:183], v191 offset:17408
	ds_read_b128 v[192:195], v191 offset:18432
	ds_read_b128 v[196:199], v191 offset:19456
	ds_read_b128 v[200:203], v191 offset:20480
	ds_read_b128 v[204:207], v191 offset:21504
	ds_read_b128 v[208:211], v191 offset:22528
	ds_read_b128 v[212:215], v191 offset:23552
	global_load_lds_dwordx4 v[184:185], off
	s_add_i32 m0, s36, 0x2000
	s_add_u32 s36, s46, 0xb0000
	v_lshl_add_u64 v[216:217], s[46:47], 0, v[158:159]
	s_addc_u32 s37, s47, 0
	s_add_i32 s63, s57, s68
	global_load_lds_dwordx4 v[216:217], off
	v_lshl_add_u64 v[218:219], s[36:37], 0, v[154:155]
	s_mov_b32 m0, s63
	v_lshl_add_u64 v[220:221], s[48:49], 0, v[156:157]
	global_load_lds_dwordx4 v[218:219], off
	v_lshl_add_u64 v[218:219], s[36:37], 0, v[158:159]
	s_add_i32 m0, s63, 0x2000
	s_nop 0
	global_load_lds_dwordx4 v[218:219], off
	v_lshl_add_u64 v[218:219], s[48:49], 0, v[152:153]
	s_mov_b32 m0, s74
	s_nop 0
	global_load_lds_dwordx4 v[218:219], off
	s_mov_b32 m0, s41
	s_nop 0
	global_load_lds_dwordx4 v[220:221], off
	s_waitcnt vmcnt(8)
	s_waitcnt lgkmcnt(0)
	s_barrier
	s_waitcnt lgkmcnt(0)
	v_mfma_f32_16x16x32_bf16 v[60:63], v[128:131], v[176:179], v[60:63]
	v_mfma_f32_16x16x32_bf16 v[56:59], v[136:139], v[176:179], v[56:59]
	v_mfma_f32_16x16x32_bf16 v[44:47], v[128:131], v[192:195], v[44:47]
	v_mfma_f32_16x16x32_bf16 v[40:43], v[136:139], v[192:195], v[40:43]
	v_mfma_f32_16x16x32_bf16 v[28:31], v[128:131], v[200:203], v[28:31]
	v_mfma_f32_16x16x32_bf16 v[24:27], v[136:139], v[200:203], v[24:27]
	v_mfma_f32_16x16x32_bf16 v[12:15], v[128:131], v[208:211], v[12:15]
	v_mfma_f32_16x16x32_bf16 v[8:11], v[136:139], v[208:211], v[8:11]
	v_mfma_f32_16x16x32_bf16 v[60:63], v[132:135], v[180:183], v[60:63]
	v_mfma_f32_16x16x32_bf16 v[56:59], v[140:143], v[180:183], v[56:59]
	v_mfma_f32_16x16x32_bf16 v[44:47], v[132:135], v[196:199], v[44:47]
	v_mfma_f32_16x16x32_bf16 v[40:43], v[140:143], v[196:199], v[40:43]
	v_mfma_f32_16x16x32_bf16 v[28:31], v[132:135], v[204:207], v[28:31]
	v_mfma_f32_16x16x32_bf16 v[24:27], v[140:143], v[204:207], v[24:27]
	v_mfma_f32_16x16x32_bf16 v[12:15], v[132:135], v[212:215], v[12:15]
	v_mfma_f32_16x16x32_bf16 v[8:11], v[140:143], v[212:215], v[8:11]
	v_mfma_f32_16x16x32_bf16 v[52:55], v[144:147], v[176:179], v[52:55]
	v_mfma_f32_16x16x32_bf16 v[48:51], v[168:171], v[176:179], v[48:51]
	v_mfma_f32_16x16x32_bf16 v[36:39], v[144:147], v[192:195], v[36:39]
	v_mfma_f32_16x16x32_bf16 v[32:35], v[168:171], v[192:195], v[32:35]
	v_mfma_f32_16x16x32_bf16 v[20:23], v[144:147], v[200:203], v[20:23]
	v_mfma_f32_16x16x32_bf16 v[16:19], v[168:171], v[200:203], v[16:19]
	v_mfma_f32_16x16x32_bf16 v[4:7], v[144:147], v[208:211], v[4:7]
	v_mfma_f32_16x16x32_bf16 v[0:3], v[168:171], v[208:211], v[0:3]
	v_mfma_f32_16x16x32_bf16 v[52:55], v[148:151], v[180:183], v[52:55]
	v_mfma_f32_16x16x32_bf16 v[48:51], v[172:175], v[180:183], v[48:51]
	v_mfma_f32_16x16x32_bf16 v[36:39], v[148:151], v[196:199], v[36:39]
	v_mfma_f32_16x16x32_bf16 v[32:35], v[172:175], v[196:199], v[32:35]
	v_mfma_f32_16x16x32_bf16 v[20:23], v[148:151], v[204:207], v[20:23]
	v_mfma_f32_16x16x32_bf16 v[16:19], v[172:175], v[204:207], v[16:19]
	v_mfma_f32_16x16x32_bf16 v[4:7], v[148:151], v[212:215], v[4:7]
	v_mfma_f32_16x16x32_bf16 v[0:3], v[172:175], v[212:215], v[0:3]
	s_barrier
	s_add_i32 s63, 0, 0x18000
	s_add_i32 s64, 0, 0x1c000
	v_add_u32_e32 v140, s63, v188
	v_add_u32_e32 v172, s64, v188
	ds_read_b128 v[128:131], v140
	ds_read_b128 v[132:135], v140 offset:1024
	ds_read_b128 v[136:139], v140 offset:2048
	ds_read_b128 v[140:143], v140 offset:3072
	ds_read_b128 v[144:147], v172
	ds_read_b128 v[148:151], v172 offset:1024
	ds_read_b128 v[168:171], v172 offset:2048
	ds_read_b128 v[172:175], v172 offset:3072
	s_add_u32 s36, s48, 0xb0000
	s_addc_u32 s37, s49, 0
	s_mov_b32 m0, s50
	v_lshl_add_u64 v[222:223], s[36:37], 0, v[152:153]
	ds_read_b128 v[176:179], v191 offset:32768
	ds_read_b128 v[180:183], v191 offset:33792
	ds_read_b128 v[192:195], v191 offset:34816
	ds_read_b128 v[196:199], v191 offset:35840
	ds_read_b128 v[200:203], v191 offset:36864
	ds_read_b128 v[204:207], v191 offset:37888
	ds_read_b128 v[208:211], v191 offset:38912
	ds_read_b128 v[212:215], v191 offset:39936
	global_load_lds_dwordx4 v[222:223], off
	v_lshl_add_u64 v[222:223], s[36:37], 0, v[156:157]
	s_mov_b32 m0, s51
	s_nop 0
	global_load_lds_dwordx4 v[222:223], off
	s_waitcnt vmcnt(8)
	s_waitcnt lgkmcnt(0)
	s_barrier
; #define PG8_STAGE(bufoff, gbase, voff) do { _Pragma("unroll") for (int _i = 0; _i < 2; ++_i) \
;         __builtin_amdgcn_global_load_lds((const unsigned*)((const char*)(gbase) + (voff)[_i]), (PG8_LAS unsigned*)(lds + (bufoff) + ldsw + _i * 8192), 16, 0, 0); } while (0)
; #define PG8_LDA(dst, b, h) do { _Pragma("unroll") for (int m = 0; m < 4; ++m) _Pragma("unroll") for (int k = 0; k < 2; ++k) dst[m][k] = *(const PG8_LAS bf16x8*)(lds + PG8_SA(b, h) + aoff + m * 2048 + k * 1024); } while (0)
; #define PG8_MMA(ai, bj, At, Bt) do { __builtin_amdgcn_s_setprio(1); _Pragma("unroll") for (int m = 0; m < 4; ++m) _Pragma("unroll") for (int n = 0; n < 2; ++n) _Pragma("unroll") for (int k = 0; k < 2; ++k) \
;         acc[ai][bj][m][n] = mma16<F16>(Bt[n][k], At[m][k], acc[ai][bj][m][n]); __builtin_amdgcn_s_setprio(0); } while (0)
; #define PG8_WAIT_V(n) asm volatile("s_waitcnt vmcnt(" #n ")" ::: "memory")
; #define PG8_WAIT_L(n) asm volatile("s_waitcnt lgkmcnt(" #n ")" ::: "memory")
; #define PG8_BAR __builtin_amdgcn_s_barrier()
; #define PG8_SCHED __builtin_amdgcn_sched_barrier(0)
; template <class Epi, class Sched, bool ALIGN_EPI = false, bool SP2 = false, bool F16 = false>
; __device__ __forceinline__ void gemm_phase(PG8_LAS unsigned char* lds, const Gemm g, const Sched& S, const Epi& E, const int wid_in) {
;     ...
;             PG8_WAIT_V(8); PG8_WAIT_L(0); PG8_BAR; PG8_MMA(0, 0, At, B0); PG8_MMA(0, 1, At, B1); PG8_BAR; PG8_SCHED;
;             PG8_LDA(At, 1, 1); PG8_STAGE(PG8_SB(1, 0), b3, voffB); PG8_STAGE(PG8_SB(1, 1), b3 + hstep, voffB); PG8_STAGE(PG8_SA(1, 0), a3, voffA);
;             PG8_WAIT_V(8); PG8_WAIT_L(0); PG8_BAR; PG8_MMA(1, 0, At, B0); PG8_MMA(1, 1, At, B1); PG8_BAR; PG8_SCHED;
	s_waitcnt lgkmcnt(0)
	v_mfma_f32_16x16x32_bf16 v[124:127], v[128:131], v[176:179], v[124:127]
	v_mfma_f32_16x16x32_bf16 v[120:123], v[136:139], v[176:179], v[120:123]
	v_mfma_f32_16x16x32_bf16 v[108:111], v[128:131], v[192:195], v[108:111]
	v_mfma_f32_16x16x32_bf16 v[104:107], v[136:139], v[192:195], v[104:107]
	v_mfma_f32_16x16x32_bf16 v[92:95], v[128:131], v[200:203], v[92:95]
	v_mfma_f32_16x16x32_bf16 v[88:91], v[136:139], v[200:203], v[88:91]
	v_mfma_f32_16x16x32_bf16 v[76:79], v[128:131], v[208:211], v[76:79]
	v_mfma_f32_16x16x32_bf16 v[72:75], v[136:139], v[208:211], v[72:75]
	v_mfma_f32_16x16x32_bf16 v[124:127], v[132:135], v[180:183], v[124:127]
	v_mfma_f32_16x16x32_bf16 v[120:123], v[140:143], v[180:183], v[120:123]
	v_mfma_f32_16x16x32_bf16 v[108:111], v[132:135], v[196:199], v[108:111]
	v_mfma_f32_16x16x32_bf16 v[104:107], v[140:143], v[196:199], v[104:107]
	v_mfma_f32_16x16x32_bf16 v[92:95], v[132:135], v[204:207], v[92:95]
	v_mfma_f32_16x16x32_bf16 v[88:91], v[140:143], v[204:207], v[88:91]
	v_mfma_f32_16x16x32_bf16 v[76:79], v[132:135], v[212:215], v[76:79]
	v_mfma_f32_16x16x32_bf16 v[72:75], v[140:143], v[212:215], v[72:75]
	v_mfma_f32_16x16x32_bf16 v[116:119], v[144:147], v[176:179], v[116:119]
	v_mfma_f32_16x16x32_bf16 v[112:115], v[168:171], v[176:179], v[112:115]
	v_mfma_f32_16x16x32_bf16 v[100:103], v[144:147], v[192:195], v[100:103]
	v_mfma_f32_16x16x32_bf16 v[96:99], v[168:171], v[192:195], v[96:99]
	v_mfma_f32_16x16x32_bf16 v[84:87], v[144:147], v[200:203], v[84:87]
	v_mfma_f32_16x16x32_bf16 v[80:83], v[168:171], v[200:203], v[80:83]
	v_mfma_f32_16x16x32_bf16 v[68:71], v[144:147], v[208:211], v[68:71]
	v_mfma_f32_16x16x32_bf16 v[64:67], v[168:171], v[208:211], v[64:67]
	v_mfma_f32_16x16x32_bf16 v[116:119], v[148:151], v[180:183], v[116:119]
	v_mfma_f32_16x16x32_bf16 v[112:115], v[172:175], v[180:183], v[112:115]
	v_mfma_f32_16x16x32_bf16 v[100:103], v[148:151], v[196:199], v[100:103]
	v_mfma_f32_16x16x32_bf16 v[96:99], v[172:175], v[196:199], v[96:99]
	v_mfma_f32_16x16x32_bf16 v[84:87], v[148:151], v[204:207], v[84:87]
	v_mfma_f32_16x16x32_bf16 v[80:83], v[172:175], v[204:207], v[80:83]
	v_mfma_f32_16x16x32_bf16 v[68:71], v[148:151], v[212:215], v[68:71]
	v_mfma_f32_16x16x32_bf16 v[64:67], v[172:175], v[212:215], v[64:67]
	s_barrier
	s_add_i32 s36, s63, s68
	v_lshl_add_u64 v[184:185], v[184:185], 0, s[30:31]
	s_mov_b32 m0, s36
	ds_read_b128 v[176:179], v191 offset:49152
	ds_read_b128 v[180:183], v191 offset:50176
	ds_read_b128 v[192:195], v191 offset:51200
	ds_read_b128 v[196:199], v191 offset:52224
	ds_read_b128 v[200:203], v191 offset:53248
	ds_read_b128 v[204:207], v191 offset:54272
	ds_read_b128 v[208:211], v191 offset:55296
	ds_read_b128 v[212:215], v191 offset:56320
	global_load_lds_dwordx4 v[184:185], off
	s_add_i32 m0, s36, 0x2000
	s_add_u32 s36, s46, 0xb0080
	v_lshl_add_u64 v[184:185], v[216:217], 0, s[30:31]
	s_addc_u32 s37, s47, 0
	s_add_i32 s46, s64, s68
	global_load_lds_dwordx4 v[184:185], off
	v_lshl_add_u64 v[184:185], s[36:37], 0, v[154:155]
	s_mov_b32 m0, s46
	s_nop 0
	global_load_lds_dwordx4 v[184:185], off
	v_lshl_add_u64 v[184:185], s[36:37], 0, v[158:159]
	s_add_i32 m0, s46, 0x2000
	s_nop 0
	global_load_lds_dwordx4 v[184:185], off
	v_lshl_add_u64 v[184:185], v[218:219], 0, s[30:31]
	s_mov_b32 m0, s75
	s_nop 0
	global_load_lds_dwordx4 v[184:185], off
	v_lshl_add_u64 v[184:185], v[220:221], 0, s[30:31]
	s_mov_b32 m0, s52
	s_nop 0
	global_load_lds_dwordx4 v[184:185], off
	s_waitcnt vmcnt(8)
	s_waitcnt lgkmcnt(0)
	s_barrier
	s_waitcnt lgkmcnt(0)
	v_mfma_f32_16x16x32_bf16 v[60:63], v[128:131], v[176:179], v[60:63]
	v_mfma_f32_16x16x32_bf16 v[56:59], v[136:139], v[176:179], v[56:59]
	v_mfma_f32_16x16x32_bf16 v[44:47], v[128:131], v[192:195], v[44:47]
	v_mfma_f32_16x16x32_bf16 v[40:43], v[136:139], v[192:195], v[40:43]
	v_mfma_f32_16x16x32_bf16 v[28:31], v[128:131], v[200:203], v[28:31]
	v_mfma_f32_16x16x32_bf16 v[24:27], v[136:139], v[200:203], v[24:27]
	v_mfma_f32_16x16x32_bf16 v[12:15], v[128:131], v[208:211], v[12:15]
	v_mfma_f32_16x16x32_bf16 v[8:11], v[136:139], v[208:211], v[8:11]
	v_mfma_f32_16x16x32_bf16 v[60:63], v[132:135], v[180:183], v[60:63]
	v_mfma_f32_16x16x32_bf16 v[56:59], v[140:143], v[180:183], v[56:59]
	v_mfma_f32_16x16x32_bf16 v[44:47], v[132:135], v[196:199], v[44:47]
	v_mfma_f32_16x16x32_bf16 v[40:43], v[140:143], v[196:199], v[40:43]
	v_mfma_f32_16x16x32_bf16 v[28:31], v[132:135], v[204:207], v[28:31]
	v_mfma_f32_16x16x32_bf16 v[24:27], v[140:143], v[204:207], v[24:27]
	v_mfma_f32_16x16x32_bf16 v[12:15], v[132:135], v[212:215], v[12:15]
	v_mfma_f32_16x16x32_bf16 v[8:11], v[140:143], v[212:215], v[8:11]
	v_mfma_f32_16x16x32_bf16 v[52:55], v[144:147], v[176:179], v[52:55]
	v_mfma_f32_16x16x32_bf16 v[48:51], v[168:171], v[176:179], v[48:51]
	v_mfma_f32_16x16x32_bf16 v[36:39], v[144:147], v[192:195], v[36:39]
	v_mfma_f32_16x16x32_bf16 v[32:35], v[168:171], v[192:195], v[32:35]
	v_mfma_f32_16x16x32_bf16 v[20:23], v[144:147], v[200:203], v[20:23]
	v_mfma_f32_16x16x32_bf16 v[16:19], v[168:171], v[200:203], v[16:19]
	v_mfma_f32_16x16x32_bf16 v[4:7], v[144:147], v[208:211], v[4:7]
	v_mfma_f32_16x16x32_bf16 v[0:3], v[168:171], v[208:211], v[0:3]
	v_mfma_f32_16x16x32_bf16 v[52:55], v[148:151], v[180:183], v[52:55]
	v_mfma_f32_16x16x32_bf16 v[48:51], v[172:175], v[180:183], v[48:51]
	v_mfma_f32_16x16x32_bf16 v[36:39], v[148:151], v[196:199], v[36:39]
	v_mfma_f32_16x16x32_bf16 v[32:35], v[172:175], v[196:199], v[32:35]
	v_mfma_f32_16x16x32_bf16 v[20:23], v[148:151], v[204:207], v[20:23]
	v_mfma_f32_16x16x32_bf16 v[16:19], v[172:175], v[204:207], v[16:19]
	v_mfma_f32_16x16x32_bf16 v[4:7], v[148:151], v[212:215], v[4:7]
	v_mfma_f32_16x16x32_bf16 v[0:3], v[172:175], v[212:215], v[0:3]
	s_barrier
	s_add_i32 s62, s62, 2
	s_add_u32 s43, s43, 0x100
	s_addc_u32 s61, s61, 0
	s_cmp_gt_u32 s62, 41
	s_mov_b64 s[36:37], s[44:45]
	s_cbranch_scc0 .LBB0_1373
	s_setprio 0
	s_and_b64 vcc, exec, s[16:17]
	s_cbranch_vccz .LBB0_1376
	s_barrier

; #define PG8_STAGE(bufoff, gbase, voff) do { _Pragma("unroll") for (int _i = 0; _i < 2; ++_i) \
;         __builtin_amdgcn_global_load_lds((const unsigned*)((const char*)(gbase) + (voff)[_i]), (PG8_LAS unsigned*)(lds + (bufoff) + ldsw + _i * 8192), 16, 0, 0); } while (0)
; #define PG8_LDA(dst, b, h) do { _Pragma("unroll") for (int m = 0; m < 4; ++m) _Pragma("unroll") for (int k = 0; k < 2; ++k) dst[m][k] = *(const PG8_LAS bf16x8*)(lds + PG8_SA(b, h) + aoff + m * 2048 + k * 1024); } while (0)
; #define PG8_LDB(dst, b, h) do { _Pragma("unroll") for (int n = 0; n < 2; ++n) _Pragma("unroll") for (int k = 0; k < 2; ++k) dst[n][k] = *(const PG8_LAS bf16x8*)(lds + PG8_SB(b, h) + boff + n * 2048 + k * 1024); } while (0)
; #define PG8_WAIT_V(n) asm volatile("s_waitcnt vmcnt(" #n ")" ::: "memory")
; #define PG8_WAIT_L(n) asm volatile("s_waitcnt lgkmcnt(" #n ")" ::: "memory")
; #define PG8_BAR __builtin_amdgcn_s_barrier()
; #define PG8_SCHED __builtin_amdgcn_sched_barrier(0)
; template <class Epi, class Sched, bool ALIGN_EPI = false, bool SP2 = false, bool F16 = false>
; __device__ __forceinline__ void gemm_phase(PG8_LAS unsigned char* lds, const Gemm g, const Sched& S, const Epi& E, const int wid_in) {
;     ...
;         const char* nA = has_next ? (const char*)g.A + (size_t)nxt.pm * tstep : cA; const char* nB = has_next ? (const char*)g.Bt + (size_t)nxt.pn * tstep : cB;
;         for (int t = 0; t < nt; t += 2) {
;             const bool last = (t == nt - 2);
;             const char* a1 = cA + (size_t)(t + 1) * kstep;
;             const char* a2 = last ? nA : cA + (size_t)(t + 2) * kstep; const char* b2 = last ? nB : cB + (size_t)(t + 2) * kstep;
;             const char* a3 = a2 + kstep; const char* b3 = b2 + kstep;
;             if (last && has_next) S.a_ready(nxt);
;             if constexpr (SP2) {
;             PG8_LDB(B0, 0, 0); PG8_LDB(B1, 0, 1); PG8_SCHED; PG8_LDA(At, 0, 0); PG8_STAGE(PG8_SA(1, 1), a1 + hstep, voffA);
;             PG8_WAIT_V(8); PG8_WAIT_L(0); PG8_BAR; PG8_MMA(0, 0, At, B0); PG8_MMA(0, 1, At, B1); PG8_BAR; PG8_SCHED;
;     ...
; #pragma unroll
;         for (int a = 0; a < 2; ++a)
; #pragma unroll
;             for (int b = 0; b < 2; ++b)
; #pragma unroll
;                 for (int m = 0; m < 4; ++m)
; #pragma unroll
;                     for (int n = 0; n < 2; ++n) acc[a][b][m][n] = (f32x4){0.f, 0.f, 0.f, 0.f};
.LBB0_1468:
	s_ashr_i32 s45, s44, 31
	s_lshl_b64 s[14:15], s[44:45], 19
	s_add_u32 s46, s12, s14
	s_addc_u32 s47, s13, s15
	s_and_b64 s[14:15], s[10:11], exec
	s_cselect_b32 s14, s47, s53
	s_cselect_b32 s15, s46, s52
	s_ashr_i32 s37, s36, 31
	s_lshl_b64 s[40:41], s[36:37], 19
	s_add_u32 s48, s21, s40
	s_addc_u32 s49, s58, s41
	s_and_b64 s[40:41], s[10:11], exec
	s_cselect_b32 s37, s49, s55
	s_cselect_b32 s40, s48, s54
	s_add_u32 s52, s52, 0x40080
	s_addc_u32 s53, s53, 0
	s_add_u32 s41, s54, 0x100
	v_mov_b32_e32 v0, 0
	s_addc_u32 s42, s55, 0
	s_mov_b32 s43, -2
	v_mov_b32_e32 v1, v0
	v_mov_b32_e32 v2, v0
	v_mov_b32_e32 v3, v0
	v_mov_b32_e32 v4, v0
	v_mov_b32_e32 v5, v0
	v_mov_b32_e32 v6, v0
	v_mov_b32_e32 v7, v0
	v_mov_b32_e32 v16, v0
	v_mov_b32_e32 v17, v0
	v_mov_b32_e32 v18, v0
	v_mov_b32_e32 v19, v0
	v_mov_b32_e32 v20, v0
	v_mov_b32_e32 v21, v0
	v_mov_b32_e32 v22, v0
	v_mov_b32_e32 v23, v0
	v_mov_b32_e32 v32, v0
	v_mov_b32_e32 v33, v0
	v_mov_b32_e32 v34, v0
	v_mov_b32_e32 v35, v0
	v_mov_b32_e32 v36, v0
	v_mov_b32_e32 v37, v0
	v_mov_b32_e32 v38, v0
	v_mov_b32_e32 v39, v0
	v_mov_b32_e32 v48, v0
	v_mov_b32_e32 v49, v0
	v_mov_b32_e32 v50, v0
	v_mov_b32_e32 v51, v0
	v_mov_b32_e32 v52, v0
	v_mov_b32_e32 v53, v0
	v_mov_b32_e32 v54, v0
	v_mov_b32_e32 v55, v0
	v_mov_b32_e32 v8, v0
	v_mov_b32_e32 v9, v0
	v_mov_b32_e32 v10, v0
	v_mov_b32_e32 v11, v0
	v_mov_b32_e32 v12, v0
	v_mov_b32_e32 v13, v0
	v_mov_b32_e32 v14, v0
	v_mov_b32_e32 v15, v0
	v_mov_b32_e32 v24, v0
	v_mov_b32_e32 v25, v0
	v_mov_b32_e32 v26, v0
	v_mov_b32_e32 v27, v0
	v_mov_b32_e32 v28, v0
	v_mov_b32_e32 v29, v0
	v_mov_b32_e32 v30, v0
	v_mov_b32_e32 v31, v0
	v_mov_b32_e32 v40, v0
	v_mov_b32_e32 v41, v0
	v_mov_b32_e32 v42, v0
	v_mov_b32_e32 v43, v0
	v_mov_b32_e32 v44, v0
	v_mov_b32_e32 v45, v0
	v_mov_b32_e32 v46, v0
	v_mov_b32_e32 v47, v0
	v_mov_b32_e32 v56, v0
	v_mov_b32_e32 v57, v0
	v_mov_b32_e32 v58, v0
	v_mov_b32_e32 v59, v0
	v_mov_b32_e32 v60, v0
	v_mov_b32_e32 v61, v0
	v_mov_b32_e32 v62, v0
	v_mov_b32_e32 v63, v0
	v_mov_b32_e32 v64, v0
	v_mov_b32_e32 v65, v0
	v_mov_b32_e32 v66, v0
	v_mov_b32_e32 v67, v0
	v_mov_b32_e32 v68, v0
	v_mov_b32_e32 v69, v0
	v_mov_b32_e32 v70, v0
	v_mov_b32_e32 v71, v0
	v_mov_b32_e32 v80, v0
	v_mov_b32_e32 v81, v0
	v_mov_b32_e32 v82, v0
	v_mov_b32_e32 v83, v0
	v_mov_b32_e32 v84, v0
	v_mov_b32_e32 v85, v0
	v_mov_b32_e32 v86, v0
	v_mov_b32_e32 v87, v0
	v_mov_b32_e32 v96, v0
	v_mov_b32_e32 v97, v0
	v_mov_b32_e32 v98, v0
	v_mov_b32_e32 v99, v0
	v_mov_b32_e32 v100, v0
	v_mov_b32_e32 v101, v0
	v_mov_b32_e32 v102, v0
	v_mov_b32_e32 v103, v0
	v_mov_b32_e32 v120, v0
	v_mov_b32_e32 v121, v0
	v_mov_b32_e32 v122, v0
	v_mov_b32_e32 v123, v0
	v_mov_b32_e32 v124, v0
	v_mov_b32_e32 v125, v0
	v_mov_b32_e32 v126, v0
	v_mov_b32_e32 v127, v0
	v_mov_b32_e32 v72, v0
	v_mov_b32_e32 v73, v0
	v_mov_b32_e32 v74, v0
	v_mov_b32_e32 v75, v0
	v_mov_b32_e32 v76, v0
	v_mov_b32_e32 v77, v0
	v_mov_b32_e32 v78, v0
	v_mov_b32_e32 v79, v0
	v_mov_b32_e32 v88, v0
	v_mov_b32_e32 v89, v0
	v_mov_b32_e32 v90, v0
	v_mov_b32_e32 v91, v0
	v_mov_b32_e32 v92, v0
	v_mov_b32_e32 v93, v0
	v_mov_b32_e32 v94, v0
	v_mov_b32_e32 v95, v0
	v_mov_b32_e32 v104, v0
	v_mov_b32_e32 v105, v0
	v_mov_b32_e32 v106, v0
	v_mov_b32_e32 v107, v0
	v_mov_b32_e32 v108, v0
	v_mov_b32_e32 v109, v0
	v_mov_b32_e32 v110, v0
	v_mov_b32_e32 v111, v0
	v_mov_b32_e32 v136, v0
	v_mov_b32_e32 v137, v0
	v_mov_b32_e32 v138, v0
	v_mov_b32_e32 v139, v0
	v_mov_b32_e32 v140, v0
	v_mov_b32_e32 v141, v0
	v_mov_b32_e32 v142, v0
	v_mov_b32_e32 v143, v0
	s_cmp_ge_u32 s3, 4
	s_cbranch_scc0 .Lgsp_11
	s_setprio 1
.Lgsp_11:
.LBB0_1469:
	ds_read_b128 v[112:115], v235
	ds_read_b128 v[116:119], v235 offset:1024
	ds_read_b128 v[128:131], v235 offset:2048
	ds_read_b128 v[132:135], v235 offset:3072
	ds_read_b128 v[144:147], v236
	ds_read_b128 v[148:151], v236 offset:1024
	ds_read_b128 v[152:155], v236 offset:2048
	ds_read_b128 v[156:159], v236 offset:3072
	s_add_u32 s45, s52, 0xfffc0080
	s_addc_u32 s51, s53, -1
	s_cmp_eq_u32 s43, 12
	s_cselect_b32 s57, s14, s51
	s_cselect_b32 s56, s15, s45
	s_cselect_b32 s55, s37, s42
	s_cselect_b32 s54, s40, s41
	v_lshl_add_u64 v[192:193], s[52:53], 0, v[204:205]
	s_add_i32 m0, s74, 0xc000
	ds_read_b128 v[160:163], v237
	ds_read_b128 v[164:167], v237 offset:1024
	ds_read_b128 v[168:171], v237 offset:2048
	ds_read_b128 v[172:175], v237 offset:3072
	ds_read_b128 v[176:179], v237 offset:4096
	ds_read_b128 v[180:183], v237 offset:5120
	ds_read_b128 v[184:187], v237 offset:6144
	ds_read_b128 v[188:191], v237 offset:7168
	global_load_lds_dwordx4 v[192:193], off
	v_lshl_add_u64 v[192:193], s[52:53], 0, v[206:207]
	s_add_i32 m0, s74, 0xe000
	s_nop 0
	global_load_lds_dwordx4 v[192:193], off
	s_waitcnt vmcnt(8)
	s_waitcnt lgkmcnt(0)
	s_barrier
; #define PG8_STAGE(bufoff, gbase, voff) do { _Pragma("unroll") for (int _i = 0; _i < 2; ++_i) \
;         __builtin_amdgcn_global_load_lds((const unsigned*)((const char*)(gbase) + (voff)[_i]), (PG8_LAS unsigned*)(lds + (bufoff) + ldsw + _i * 8192), 16, 0, 0); } while (0)
; #define PG8_LDA(dst, b, h) do { _Pragma("unroll") for (int m = 0; m < 4; ++m) _Pragma("unroll") for (int k = 0; k < 2; ++k) dst[m][k] = *(const PG8_LAS bf16x8*)(lds + PG8_SA(b, h) + aoff + m * 2048 + k * 1024); } while (0)
; #define PG8_MMA(ai, bj, At, Bt) do { __builtin_amdgcn_s_setprio(1); _Pragma("unroll") for (int m = 0; m < 4; ++m) _Pragma("unroll") for (int n = 0; n < 2; ++n) _Pragma("unroll") for (int k = 0; k < 2; ++k) \
;         acc[ai][bj][m][n] = mma16<F16>(Bt[n][k], At[m][k], acc[ai][bj][m][n]); __builtin_amdgcn_s_setprio(0); } while (0)
; #define PG8_WAIT_V(n) asm volatile("s_waitcnt vmcnt(" #n ")" ::: "memory")
; #define PG8_WAIT_L(n) asm volatile("s_waitcnt lgkmcnt(" #n ")" ::: "memory")
; #define PG8_BAR __builtin_amdgcn_s_barrier()
; #define PG8_SCHED __builtin_amdgcn_sched_barrier(0)
; template <class Epi, class Sched, bool ALIGN_EPI = false, bool SP2 = false, bool F16 = false>
; __device__ __forceinline__ void gemm_phase(PG8_LAS unsigned char* lds, const Gemm g, const Sched& S, const Epi& E, const int wid_in) {
;     ...
;             PG8_WAIT_V(8); PG8_WAIT_L(0); PG8_BAR; PG8_MMA(0, 0, At, B0); PG8_MMA(0, 1, At, B1); PG8_BAR; PG8_SCHED;
;             PG8_LDA(At, 0, 1); PG8_STAGE(PG8_SB(0, 0), b2, voffB); PG8_STAGE(PG8_SB(0, 1), b2 + hstep, voffB); PG8_STAGE(PG8_SA(0, 0), a2, voffA);
;             PG8_WAIT_V(8); PG8_WAIT_L(0); PG8_BAR; PG8_MMA(1, 0, At, B0); PG8_MMA(1, 1, At, B1); PG8_BAR; PG8_SCHED;
	s_waitcnt lgkmcnt(0)
	v_mfma_f32_16x16x32_f16 v[140:143], v[112:115], v[160:163], v[140:143]
	v_mfma_f32_16x16x32_f16 v[136:139], v[128:131], v[160:163], v[136:139]
	v_mfma_f32_16x16x32_f16 v[108:111], v[112:115], v[168:171], v[108:111]
	v_mfma_f32_16x16x32_f16 v[104:107], v[128:131], v[168:171], v[104:107]
	v_mfma_f32_16x16x32_f16 v[92:95], v[112:115], v[176:179], v[92:95]
	v_mfma_f32_16x16x32_f16 v[88:91], v[128:131], v[176:179], v[88:91]
	v_mfma_f32_16x16x32_f16 v[76:79], v[112:115], v[184:187], v[76:79]
	v_mfma_f32_16x16x32_f16 v[72:75], v[128:131], v[184:187], v[72:75]
	v_mfma_f32_16x16x32_f16 v[140:143], v[116:119], v[164:167], v[140:143]
	v_mfma_f32_16x16x32_f16 v[136:139], v[132:135], v[164:167], v[136:139]
	v_mfma_f32_16x16x32_f16 v[108:111], v[116:119], v[172:175], v[108:111]
	v_mfma_f32_16x16x32_f16 v[104:107], v[132:135], v[172:175], v[104:107]
	v_mfma_f32_16x16x32_f16 v[92:95], v[116:119], v[180:183], v[92:95]
	v_mfma_f32_16x16x32_f16 v[88:91], v[132:135], v[180:183], v[88:91]
	v_mfma_f32_16x16x32_f16 v[76:79], v[116:119], v[188:191], v[76:79]
	v_mfma_f32_16x16x32_f16 v[72:75], v[132:135], v[188:191], v[72:75]
	v_mfma_f32_16x16x32_f16 v[124:127], v[144:147], v[160:163], v[124:127]
	v_mfma_f32_16x16x32_f16 v[120:123], v[152:155], v[160:163], v[120:123]
	v_mfma_f32_16x16x32_f16 v[100:103], v[144:147], v[168:171], v[100:103]
	v_mfma_f32_16x16x32_f16 v[96:99], v[152:155], v[168:171], v[96:99]
	v_mfma_f32_16x16x32_f16 v[84:87], v[144:147], v[176:179], v[84:87]
	v_mfma_f32_16x16x32_f16 v[80:83], v[152:155], v[176:179], v[80:83]
	v_mfma_f32_16x16x32_f16 v[68:71], v[144:147], v[184:187], v[68:71]
	v_mfma_f32_16x16x32_f16 v[64:67], v[152:155], v[184:187], v[64:67]
	v_mfma_f32_16x16x32_f16 v[124:127], v[148:151], v[164:167], v[124:127]
	v_mfma_f32_16x16x32_f16 v[120:123], v[156:159], v[164:167], v[120:123]
	v_mfma_f32_16x16x32_f16 v[100:103], v[148:151], v[172:175], v[100:103]
	v_mfma_f32_16x16x32_f16 v[96:99], v[156:159], v[172:175], v[96:99]
	v_mfma_f32_16x16x32_f16 v[84:87], v[148:151], v[180:183], v[84:87]
	v_mfma_f32_16x16x32_f16 v[80:83], v[156:159], v[180:183], v[80:83]
	v_mfma_f32_16x16x32_f16 v[68:71], v[148:151], v[188:191], v[68:71]
	v_mfma_f32_16x16x32_f16 v[64:67], v[156:159], v[188:191], v[64:67]
	s_barrier
	s_add_i32 s45, s66, s68
	v_lshl_add_u64 v[192:193], s[54:55], 0, v[198:199]
	s_mov_b32 m0, s45
	ds_read_b128 v[160:163], v237 offset:16384
	ds_read_b128 v[164:167], v237 offset:17408
	ds_read_b128 v[168:171], v237 offset:18432
	ds_read_b128 v[172:175], v237 offset:19456
	ds_read_b128 v[176:179], v237 offset:20480
	ds_read_b128 v[180:183], v237 offset:21504
	ds_read_b128 v[184:187], v237 offset:22528
	ds_read_b128 v[188:191], v237 offset:23552
	global_load_lds_dwordx4 v[192:193], off
	s_add_i32 m0, s45, 0x2000
	s_add_u32 s94, s54, 0x40000
	v_lshl_add_u64 v[194:195], s[54:55], 0, v[202:203]
	s_addc_u32 s95, s55, 0
	s_add_i32 s45, s67, s68
	global_load_lds_dwordx4 v[194:195], off
	v_lshl_add_u64 v[212:213], s[94:95], 0, v[198:199]
	s_mov_b32 m0, s45
	v_lshl_add_u64 v[214:215], s[56:57], 0, v[200:201]
	global_load_lds_dwordx4 v[212:213], off
	v_lshl_add_u64 v[212:213], s[94:95], 0, v[202:203]
	s_add_i32 m0, s45, 0x2000
	s_nop 0
	global_load_lds_dwordx4 v[212:213], off
	v_lshl_add_u64 v[212:213], s[56:57], 0, v[196:197]
	s_mov_b32 m0, s74
	s_nop 0
	global_load_lds_dwordx4 v[212:213], off
	s_mov_b32 m0, s59
	s_nop 0
	global_load_lds_dwordx4 v[214:215], off
	s_waitcnt vmcnt(8)
	s_waitcnt lgkmcnt(0)
	s_barrier
	s_waitcnt lgkmcnt(0)
	v_mfma_f32_16x16x32_f16 v[60:63], v[112:115], v[160:163], v[60:63]
	v_mfma_f32_16x16x32_f16 v[56:59], v[128:131], v[160:163], v[56:59]
	v_mfma_f32_16x16x32_f16 v[44:47], v[112:115], v[168:171], v[44:47]
	v_mfma_f32_16x16x32_f16 v[40:43], v[128:131], v[168:171], v[40:43]
	v_mfma_f32_16x16x32_f16 v[28:31], v[112:115], v[176:179], v[28:31]
	v_mfma_f32_16x16x32_f16 v[24:27], v[128:131], v[176:179], v[24:27]
	v_mfma_f32_16x16x32_f16 v[12:15], v[112:115], v[184:187], v[12:15]
	v_mfma_f32_16x16x32_f16 v[8:11], v[128:131], v[184:187], v[8:11]
	v_mfma_f32_16x16x32_f16 v[60:63], v[116:119], v[164:167], v[60:63]
	v_mfma_f32_16x16x32_f16 v[56:59], v[132:135], v[164:167], v[56:59]
	v_mfma_f32_16x16x32_f16 v[44:47], v[116:119], v[172:175], v[44:47]
	v_mfma_f32_16x16x32_f16 v[40:43], v[132:135], v[172:175], v[40:43]
	v_mfma_f32_16x16x32_f16 v[28:31], v[116:119], v[180:183], v[28:31]
	v_mfma_f32_16x16x32_f16 v[24:27], v[132:135], v[180:183], v[24:27]
	v_mfma_f32_16x16x32_f16 v[12:15], v[116:119], v[188:191], v[12:15]
	v_mfma_f32_16x16x32_f16 v[8:11], v[132:135], v[188:191], v[8:11]
	v_mfma_f32_16x16x32_f16 v[52:55], v[144:147], v[160:163], v[52:55]
	v_mfma_f32_16x16x32_f16 v[48:51], v[152:155], v[160:163], v[48:51]
	v_mfma_f32_16x16x32_f16 v[36:39], v[144:147], v[168:171], v[36:39]
	v_mfma_f32_16x16x32_f16 v[32:35], v[152:155], v[168:171], v[32:35]
	v_mfma_f32_16x16x32_f16 v[20:23], v[144:147], v[176:179], v[20:23]
	v_mfma_f32_16x16x32_f16 v[16:19], v[152:155], v[176:179], v[16:19]
	v_mfma_f32_16x16x32_f16 v[4:7], v[144:147], v[184:187], v[4:7]
	v_mfma_f32_16x16x32_f16 v[0:3], v[152:155], v[184:187], v[0:3]
	v_mfma_f32_16x16x32_f16 v[52:55], v[148:151], v[164:167], v[52:55]
	v_mfma_f32_16x16x32_f16 v[48:51], v[156:159], v[164:167], v[48:51]
	v_mfma_f32_16x16x32_f16 v[36:39], v[148:151], v[172:175], v[36:39]
	v_mfma_f32_16x16x32_f16 v[32:35], v[156:159], v[172:175], v[32:35]
	v_mfma_f32_16x16x32_f16 v[20:23], v[148:151], v[180:183], v[20:23]
	v_mfma_f32_16x16x32_f16 v[16:19], v[156:159], v[180:183], v[16:19]
	v_mfma_f32_16x16x32_f16 v[4:7], v[148:151], v[188:191], v[4:7]
	v_mfma_f32_16x16x32_f16 v[0:3], v[156:159], v[188:191], v[0:3]
	s_barrier
; #define PG8_STAGE(bufoff, gbase, voff) do { _Pragma("unroll") for (int _i = 0; _i < 2; ++_i) \
;         __builtin_amdgcn_global_load_lds((const unsigned*)((const char*)(gbase) + (voff)[_i]), (PG8_LAS unsigned*)(lds + (bufoff) + ldsw + _i * 8192), 16, 0, 0); } while (0)
; #define PG8_LDA(dst, b, h) do { _Pragma("unroll") for (int m = 0; m < 4; ++m) _Pragma("unroll") for (int k = 0; k < 2; ++k) dst[m][k] = *(const PG8_LAS bf16x8*)(lds + PG8_SA(b, h) + aoff + m * 2048 + k * 1024); } while (0)
; #define PG8_LDB(dst, b, h) do { _Pragma("unroll") for (int n = 0; n < 2; ++n) _Pragma("unroll") for (int k = 0; k < 2; ++k) dst[n][k] = *(const PG8_LAS bf16x8*)(lds + PG8_SB(b, h) + boff + n * 2048 + k * 1024); } while (0)
; #define PG8_MMA(ai, bj, At, Bt) do { __builtin_amdgcn_s_setprio(1); _Pragma("unroll") for (int m = 0; m < 4; ++m) _Pragma("unroll") for (int n = 0; n < 2; ++n) _Pragma("unroll") for (int k = 0; k < 2; ++k) \
;         acc[ai][bj][m][n] = mma16<F16>(Bt[n][k], At[m][k], acc[ai][bj][m][n]); __builtin_amdgcn_s_setprio(0); } while (0)
; #define PG8_WAIT_V(n) asm volatile("s_waitcnt vmcnt(" #n ")" ::: "memory")
; #define PG8_WAIT_L(n) asm volatile("s_waitcnt lgkmcnt(" #n ")" ::: "memory")
; #define PG8_BAR __builtin_amdgcn_s_barrier()
; #define PG8_SCHED __builtin_amdgcn_sched_barrier(0)
; template <class Epi, class Sched, bool ALIGN_EPI = false, bool SP2 = false, bool F16 = false>
; __device__ __forceinline__ void gemm_phase(PG8_LAS unsigned char* lds, const Gemm g, const Sched& S, const Epi& E, const int wid_in) {
;     ...
;             PG8_LDB(B0, 1, 0); PG8_LDB(B1, 1, 1); PG8_SCHED; PG8_LDA(At, 1, 0); PG8_STAGE(PG8_SA(0, 1), a2 + hstep, voffA);
;             PG8_WAIT_V(8); PG8_WAIT_L(0); PG8_BAR; PG8_MMA(0, 0, At, B0); PG8_MMA(0, 1, At, B1); PG8_BAR; PG8_SCHED;
	s_add_i32 s45, 0, 0x18000
	s_add_i32 s51, 0, 0x1c000
	v_add_u32_e32 v132, s45, v234
	v_add_u32_e32 v156, s51, v234
	ds_read_b128 v[112:115], v132
	ds_read_b128 v[116:119], v132 offset:1024
	ds_read_b128 v[128:131], v132 offset:2048
	ds_read_b128 v[132:135], v132 offset:3072
	ds_read_b128 v[144:147], v156
	ds_read_b128 v[148:151], v156 offset:1024
	ds_read_b128 v[152:155], v156 offset:2048
	ds_read_b128 v[156:159], v156 offset:3072
	s_add_u32 s56, s56, 0x40000
	s_addc_u32 s57, s57, 0
	s_mov_b32 m0, s60
	v_lshl_add_u64 v[216:217], s[56:57], 0, v[196:197]
	ds_read_b128 v[160:163], v237 offset:32768
	ds_read_b128 v[164:167], v237 offset:33792
	ds_read_b128 v[168:171], v237 offset:34816
	ds_read_b128 v[172:175], v237 offset:35840
	ds_read_b128 v[176:179], v237 offset:36864
	ds_read_b128 v[180:183], v237 offset:37888
	ds_read_b128 v[184:187], v237 offset:38912
	ds_read_b128 v[188:191], v237 offset:39936
	global_load_lds_dwordx4 v[216:217], off
	v_lshl_add_u64 v[216:217], s[56:57], 0, v[200:201]
	s_mov_b32 m0, s61
	s_nop 0
	global_load_lds_dwordx4 v[216:217], off
	s_waitcnt vmcnt(8)
	s_waitcnt lgkmcnt(0)
	s_barrier
	s_waitcnt lgkmcnt(0)
	v_mfma_f32_16x16x32_f16 v[140:143], v[112:115], v[160:163], v[140:143]
	v_mfma_f32_16x16x32_f16 v[136:139], v[128:131], v[160:163], v[136:139]
	v_mfma_f32_16x16x32_f16 v[108:111], v[112:115], v[168:171], v[108:111]
	v_mfma_f32_16x16x32_f16 v[104:107], v[128:131], v[168:171], v[104:107]
	v_mfma_f32_16x16x32_f16 v[92:95], v[112:115], v[176:179], v[92:95]
	v_mfma_f32_16x16x32_f16 v[88:91], v[128:131], v[176:179], v[88:91]
	v_mfma_f32_16x16x32_f16 v[76:79], v[112:115], v[184:187], v[76:79]
	v_mfma_f32_16x16x32_f16 v[72:75], v[128:131], v[184:187], v[72:75]
	v_mfma_f32_16x16x32_f16 v[140:143], v[116:119], v[164:167], v[140:143]
	v_mfma_f32_16x16x32_f16 v[136:139], v[132:135], v[164:167], v[136:139]
	v_mfma_f32_16x16x32_f16 v[108:111], v[116:119], v[172:175], v[108:111]
	v_mfma_f32_16x16x32_f16 v[104:107], v[132:135], v[172:175], v[104:107]
	v_mfma_f32_16x16x32_f16 v[92:95], v[116:119], v[180:183], v[92:95]
	v_mfma_f32_16x16x32_f16 v[88:91], v[132:135], v[180:183], v[88:91]
	v_mfma_f32_16x16x32_f16 v[76:79], v[116:119], v[188:191], v[76:79]
	v_mfma_f32_16x16x32_f16 v[72:75], v[132:135], v[188:191], v[72:75]
	v_mfma_f32_16x16x32_f16 v[124:127], v[144:147], v[160:163], v[124:127]
	v_mfma_f32_16x16x32_f16 v[120:123], v[152:155], v[160:163], v[120:123]
	v_mfma_f32_16x16x32_f16 v[100:103], v[144:147], v[168:171], v[100:103]
	v_mfma_f32_16x16x32_f16 v[96:99], v[152:155], v[168:171], v[96:99]
	v_mfma_f32_16x16x32_f16 v[84:87], v[144:147], v[176:179], v[84:87]
	v_mfma_f32_16x16x32_f16 v[80:83], v[152:155], v[176:179], v[80:83]
	v_mfma_f32_16x16x32_f16 v[68:71], v[144:147], v[184:187], v[68:71]
	v_mfma_f32_16x16x32_f16 v[64:67], v[152:155], v[184:187], v[64:67]
	v_mfma_f32_16x16x32_f16 v[124:127], v[148:151], v[164:167], v[124:127]
	v_mfma_f32_16x16x32_f16 v[120:123], v[156:159], v[164:167], v[120:123]
	v_mfma_f32_16x16x32_f16 v[100:103], v[148:151], v[172:175], v[100:103]
	v_mfma_f32_16x16x32_f16 v[96:99], v[156:159], v[172:175], v[96:99]
	v_mfma_f32_16x16x32_f16 v[84:87], v[148:151], v[180:183], v[84:87]
	v_mfma_f32_16x16x32_f16 v[80:83], v[156:159], v[180:183], v[80:83]
	v_mfma_f32_16x16x32_f16 v[68:71], v[148:151], v[188:191], v[68:71]
	v_mfma_f32_16x16x32_f16 v[64:67], v[156:159], v[188:191], v[64:67]
	s_barrier
; #define PG8_STAGE(bufoff, gbase, voff) do { _Pragma("unroll") for (int _i = 0; _i < 2; ++_i) \
;         __builtin_amdgcn_global_load_lds((const unsigned*)((const char*)(gbase) + (voff)[_i]), (PG8_LAS unsigned*)(lds + (bufoff) + ldsw + _i * 8192), 16, 0, 0); } while (0)
; #define PG8_LDA(dst, b, h) do { _Pragma("unroll") for (int m = 0; m < 4; ++m) _Pragma("unroll") for (int k = 0; k < 2; ++k) dst[m][k] = *(const PG8_LAS bf16x8*)(lds + PG8_SA(b, h) + aoff + m * 2048 + k * 1024); } while (0)
; #define PG8_MMA(ai, bj, At, Bt) do { __builtin_amdgcn_s_setprio(1); _Pragma("unroll") for (int m = 0; m < 4; ++m) _Pragma("unroll") for (int n = 0; n < 2; ++n) _Pragma("unroll") for (int k = 0; k < 2; ++k) \
;         acc[ai][bj][m][n] = mma16<F16>(Bt[n][k], At[m][k], acc[ai][bj][m][n]); __builtin_amdgcn_s_setprio(0); } while (0)
; #define PG8_WAIT_V(n) asm volatile("s_waitcnt vmcnt(" #n ")" ::: "memory")
; #define PG8_WAIT_L(n) asm volatile("s_waitcnt lgkmcnt(" #n ")" ::: "memory")
; #define PG8_BAR __builtin_amdgcn_s_barrier()
; #define PG8_SCHED __builtin_amdgcn_sched_barrier(0)
; template <class Epi, class Sched, bool ALIGN_EPI = false, bool SP2 = false, bool F16 = false>
; __device__ __forceinline__ void gemm_phase(PG8_LAS unsigned char* lds, const Gemm g, const Sched& S, const Epi& E, const int wid_in) {
;     ...
;             PG8_LDA(At, 1, 1); PG8_STAGE(PG8_SB(1, 0), b3, voffB); PG8_STAGE(PG8_SB(1, 1), b3 + hstep, voffB); PG8_STAGE(PG8_SA(1, 0), a3, voffA);
;             PG8_WAIT_V(8); PG8_WAIT_L(0); PG8_BAR; PG8_MMA(1, 0, At, B0); PG8_MMA(1, 1, At, B1); PG8_BAR; PG8_SCHED;
	s_add_i32 s45, s45, s68
	v_lshl_add_u64 v[192:193], v[192:193], 0, s[34:35]
	s_mov_b32 m0, s45
	ds_read_b128 v[160:163], v237 offset:49152
	ds_read_b128 v[164:167], v237 offset:50176
	ds_read_b128 v[168:171], v237 offset:51200
	ds_read_b128 v[172:175], v237 offset:52224
	ds_read_b128 v[176:179], v237 offset:53248
	ds_read_b128 v[180:183], v237 offset:54272
	ds_read_b128 v[184:187], v237 offset:55296
	ds_read_b128 v[188:191], v237 offset:56320
	global_load_lds_dwordx4 v[192:193], off
	s_add_i32 m0, s45, 0x2000
	s_add_u32 s54, s54, 0x40080
	v_lshl_add_u64 v[192:193], v[194:195], 0, s[34:35]
	s_addc_u32 s55, s55, 0
	s_add_i32 s45, s51, s68
	global_load_lds_dwordx4 v[192:193], off
	v_lshl_add_u64 v[192:193], s[54:55], 0, v[198:199]
	s_mov_b32 m0, s45
	s_nop 0
	global_load_lds_dwordx4 v[192:193], off
	v_lshl_add_u64 v[192:193], s[54:55], 0, v[202:203]
	s_add_i32 m0, s45, 0x2000
	s_nop 0
	global_load_lds_dwordx4 v[192:193], off
	v_lshl_add_u64 v[192:193], v[212:213], 0, s[34:35]
	s_mov_b32 m0, s75
	s_nop 0
	global_load_lds_dwordx4 v[192:193], off
	v_lshl_add_u64 v[192:193], v[214:215], 0, s[34:35]
	s_mov_b32 m0, s62
	s_nop 0
	global_load_lds_dwordx4 v[192:193], off
	s_waitcnt vmcnt(8)
	s_waitcnt lgkmcnt(0)
	s_barrier
	s_waitcnt lgkmcnt(0)
	v_mfma_f32_16x16x32_f16 v[60:63], v[112:115], v[160:163], v[60:63]
	v_mfma_f32_16x16x32_f16 v[56:59], v[128:131], v[160:163], v[56:59]
	v_mfma_f32_16x16x32_f16 v[44:47], v[112:115], v[168:171], v[44:47]
	v_mfma_f32_16x16x32_f16 v[40:43], v[128:131], v[168:171], v[40:43]
	v_mfma_f32_16x16x32_f16 v[28:31], v[112:115], v[176:179], v[28:31]
	v_mfma_f32_16x16x32_f16 v[24:27], v[128:131], v[176:179], v[24:27]
	v_mfma_f32_16x16x32_f16 v[12:15], v[112:115], v[184:187], v[12:15]
	v_mfma_f32_16x16x32_f16 v[8:11], v[128:131], v[184:187], v[8:11]
	v_mfma_f32_16x16x32_f16 v[60:63], v[116:119], v[164:167], v[60:63]
	v_mfma_f32_16x16x32_f16 v[56:59], v[132:135], v[164:167], v[56:59]
	v_mfma_f32_16x16x32_f16 v[44:47], v[116:119], v[172:175], v[44:47]
	v_mfma_f32_16x16x32_f16 v[40:43], v[132:135], v[172:175], v[40:43]
	v_mfma_f32_16x16x32_f16 v[28:31], v[116:119], v[180:183], v[28:31]
	v_mfma_f32_16x16x32_f16 v[24:27], v[132:135], v[180:183], v[24:27]
	v_mfma_f32_16x16x32_f16 v[12:15], v[116:119], v[188:191], v[12:15]
	v_mfma_f32_16x16x32_f16 v[8:11], v[132:135], v[188:191], v[8:11]
	v_mfma_f32_16x16x32_f16 v[52:55], v[144:147], v[160:163], v[52:55]
	v_mfma_f32_16x16x32_f16 v[48:51], v[152:155], v[160:163], v[48:51]
	v_mfma_f32_16x16x32_f16 v[36:39], v[144:147], v[168:171], v[36:39]
	v_mfma_f32_16x16x32_f16 v[32:35], v[152:155], v[168:171], v[32:35]
	v_mfma_f32_16x16x32_f16 v[20:23], v[144:147], v[176:179], v[20:23]
	v_mfma_f32_16x16x32_f16 v[16:19], v[152:155], v[176:179], v[16:19]
	v_mfma_f32_16x16x32_f16 v[4:7], v[144:147], v[184:187], v[4:7]
	v_mfma_f32_16x16x32_f16 v[0:3], v[152:155], v[184:187], v[0:3]
	v_mfma_f32_16x16x32_f16 v[52:55], v[148:151], v[164:167], v[52:55]
	v_mfma_f32_16x16x32_f16 v[48:51], v[156:159], v[164:167], v[48:51]
	v_mfma_f32_16x16x32_f16 v[36:39], v[148:151], v[172:175], v[36:39]
	v_mfma_f32_16x16x32_f16 v[32:35], v[156:159], v[172:175], v[32:35]
	v_mfma_f32_16x16x32_f16 v[20:23], v[148:151], v[180:183], v[20:23]
	v_mfma_f32_16x16x32_f16 v[16:19], v[156:159], v[180:183], v[16:19]
	v_mfma_f32_16x16x32_f16 v[4:7], v[148:151], v[188:191], v[4:7]
	v_mfma_f32_16x16x32_f16 v[0:3], v[156:159], v[188:191], v[0:3]
	s_barrier
	s_add_i32 s43, s43, 2
	s_add_u32 s52, s52, 0x100
	s_addc_u32 s53, s53, 0
	s_add_u32 s41, s41, 0x100
	s_addc_u32 s42, s42, 0
	s_cmp_gt_u32 s43, 13
	s_cbranch_scc0 .LBB0_1469
	s_setprio 0
	s_and_b64 vcc, exec, s[16:17]
	s_cbranch_vccz .LBB0_1472
	s_barrier

; #define PG8_STAGE(bufoff, gbase, voff) do { _Pragma("unroll") for (int _i = 0; _i < 2; ++_i) \
;         __builtin_amdgcn_global_load_lds((const unsigned*)((const char*)(gbase) + (voff)[_i]), (PG8_LAS unsigned*)(lds + (bufoff) + ldsw + _i * 8192), 16, 0, 0); } while (0)
; #define PG8_LDA(dst, b, h) do { _Pragma("unroll") for (int m = 0; m < 4; ++m) _Pragma("unroll") for (int k = 0; k < 2; ++k) dst[m][k] = *(const PG8_LAS bf16x8*)(lds + PG8_SA(b, h) + aoff + m * 2048 + k * 1024); } while (0)
; #define PG8_LDB(dst, b, h) do { _Pragma("unroll") for (int n = 0; n < 2; ++n) _Pragma("unroll") for (int k = 0; k < 2; ++k) dst[n][k] = *(const PG8_LAS bf16x8*)(lds + PG8_SB(b, h) + boff + n * 2048 + k * 1024); } while (0)
; #define PG8_WAIT_V(n) asm volatile("s_waitcnt vmcnt(" #n ")" ::: "memory")
; #define PG8_WAIT_L(n) asm volatile("s_waitcnt lgkmcnt(" #n ")" ::: "memory")
; #define PG8_BAR __builtin_amdgcn_s_barrier()
; #define PG8_SCHED __builtin_amdgcn_sched_barrier(0)
; template <class Epi, class Sched, bool ALIGN_EPI = false, bool SP2 = false, bool F16 = false>
; __device__ __forceinline__ void gemm_phase(PG8_LAS unsigned char* lds, const Gemm g, const Sched& S, const Epi& E, const int wid_in) {
;     ...
;         const char* nA = has_next ? (const char*)g.A + (size_t)nxt.pm * tstep : cA; const char* nB = has_next ? (const char*)g.Bt + (size_t)nxt.pn * tstep : cB;
;         for (int t = 0; t < nt; t += 2) {
;             const bool last = (t == nt - 2);
;             const char* a1 = cA + (size_t)(t + 1) * kstep;
;             const char* a2 = last ? nA : cA + (size_t)(t + 2) * kstep; const char* b2 = last ? nB : cB + (size_t)(t + 2) * kstep;
;             const char* a3 = a2 + kstep; const char* b3 = b2 + kstep;
;             if (last && has_next) S.a_ready(nxt);
;             if constexpr (SP2) {
;             PG8_LDB(B0, 0, 0); PG8_LDB(B1, 0, 1); PG8_SCHED; PG8_LDA(At, 0, 0); PG8_STAGE(PG8_SA(1, 1), a1 + hstep, voffA);
;             PG8_WAIT_V(8); PG8_WAIT_L(0); PG8_BAR; PG8_MMA(0, 0, At, B0); PG8_MMA(0, 1, At, B1); PG8_BAR; PG8_SCHED;
;     ...
; #pragma unroll
;         for (int a = 0; a < 2; ++a)
; #pragma unroll
;             for (int b = 0; b < 2; ++b)
; #pragma unroll
;                 for (int m = 0; m < 4; ++m)
; #pragma unroll
;                     for (int n = 0; n < 2; ++n) acc[a][b][m][n] = (f32x4){0.f, 0.f, 0.f, 0.f};
.LBB0_1547:
	s_ashr_i32 s45, s44, 31
	s_lshl_b64 s[40:41], s[44:45], 19
	s_add_u32 s46, s62, s40
	s_addc_u32 s47, s63, s41
	s_and_b64 s[40:41], s[10:11], exec
	s_cselect_b32 s13, s47, s51
	s_cselect_b32 s31, s46, s50
	s_ashr_i32 s37, s36, 31
	s_lshl_b64 s[40:41], s[36:37], 19
	s_add_u32 s48, s64, s40
	s_addc_u32 s49, s65, s41
	s_and_b64 s[40:41], s[10:11], exec
	s_cselect_b32 s37, s49, s53
	s_cselect_b32 s40, s48, s52
	s_add_u32 s50, s50, 0x40080
	s_addc_u32 s51, s51, 0
	s_add_u32 s41, s52, 0x100
	v_mov_b32_e32 v0, 0
	s_addc_u32 s42, s53, 0
	s_mov_b32 s43, -2
	s_waitcnt lgkmcnt(0)
	v_mov_b32_e32 v1, v0
	v_mov_b32_e32 v2, v0
	v_mov_b32_e32 v3, v0
	v_mov_b32_e32 v4, v0
	v_mov_b32_e32 v5, v0
	v_mov_b32_e32 v6, v0
	v_mov_b32_e32 v7, v0
	v_mov_b32_e32 v16, v0
	v_mov_b32_e32 v17, v0
	v_mov_b32_e32 v18, v0
	v_mov_b32_e32 v19, v0
	v_mov_b32_e32 v20, v0
	v_mov_b32_e32 v21, v0
	v_mov_b32_e32 v22, v0
	v_mov_b32_e32 v23, v0
	v_mov_b32_e32 v32, v0
	v_mov_b32_e32 v33, v0
	v_mov_b32_e32 v34, v0
	v_mov_b32_e32 v35, v0
	v_mov_b32_e32 v36, v0
	v_mov_b32_e32 v37, v0
	v_mov_b32_e32 v38, v0
	v_mov_b32_e32 v39, v0
	v_mov_b32_e32 v48, v0
	v_mov_b32_e32 v49, v0
	v_mov_b32_e32 v50, v0
	v_mov_b32_e32 v51, v0
	v_mov_b32_e32 v52, v0
	v_mov_b32_e32 v53, v0
	v_mov_b32_e32 v54, v0
	v_mov_b32_e32 v55, v0
	v_mov_b32_e32 v8, v0
	v_mov_b32_e32 v9, v0
	v_mov_b32_e32 v10, v0
	v_mov_b32_e32 v11, v0
	v_mov_b32_e32 v12, v0
	v_mov_b32_e32 v13, v0
	v_mov_b32_e32 v14, v0
	v_mov_b32_e32 v15, v0
	v_mov_b32_e32 v24, v0
	v_mov_b32_e32 v25, v0
	v_mov_b32_e32 v26, v0
	v_mov_b32_e32 v27, v0
	v_mov_b32_e32 v28, v0
	v_mov_b32_e32 v29, v0
	v_mov_b32_e32 v30, v0
	v_mov_b32_e32 v31, v0
	v_mov_b32_e32 v40, v0
	v_mov_b32_e32 v41, v0
	v_mov_b32_e32 v42, v0
	v_mov_b32_e32 v43, v0
	v_mov_b32_e32 v44, v0
	v_mov_b32_e32 v45, v0
	v_mov_b32_e32 v46, v0
	v_mov_b32_e32 v47, v0
	v_mov_b32_e32 v56, v0
	v_mov_b32_e32 v57, v0
	v_mov_b32_e32 v58, v0
	v_mov_b32_e32 v59, v0
	v_mov_b32_e32 v60, v0
	v_mov_b32_e32 v61, v0
	v_mov_b32_e32 v62, v0
	v_mov_b32_e32 v63, v0
	v_mov_b32_e32 v64, v0
	v_mov_b32_e32 v65, v0
	v_mov_b32_e32 v66, v0
	v_mov_b32_e32 v67, v0
	v_mov_b32_e32 v68, v0
	v_mov_b32_e32 v69, v0
	v_mov_b32_e32 v70, v0
	v_mov_b32_e32 v71, v0
	v_mov_b32_e32 v80, v0
	v_mov_b32_e32 v81, v0
	v_mov_b32_e32 v82, v0
	v_mov_b32_e32 v83, v0
	v_mov_b32_e32 v84, v0
	v_mov_b32_e32 v85, v0
	v_mov_b32_e32 v86, v0
	v_mov_b32_e32 v87, v0
	v_mov_b32_e32 v96, v0
	v_mov_b32_e32 v97, v0
	v_mov_b32_e32 v98, v0
	v_mov_b32_e32 v99, v0
	v_mov_b32_e32 v100, v0
	v_mov_b32_e32 v101, v0
	v_mov_b32_e32 v102, v0
	v_mov_b32_e32 v103, v0
	v_mov_b32_e32 v112, v0
	v_mov_b32_e32 v113, v0
	v_mov_b32_e32 v114, v0
	v_mov_b32_e32 v115, v0
	v_mov_b32_e32 v116, v0
	v_mov_b32_e32 v117, v0
	v_mov_b32_e32 v118, v0
	v_mov_b32_e32 v119, v0
	v_mov_b32_e32 v72, v0
	v_mov_b32_e32 v73, v0
	v_mov_b32_e32 v74, v0
	v_mov_b32_e32 v75, v0
	v_mov_b32_e32 v76, v0
	v_mov_b32_e32 v77, v0
	v_mov_b32_e32 v78, v0
	v_mov_b32_e32 v79, v0
	v_mov_b32_e32 v88, v0
	v_mov_b32_e32 v89, v0
	v_mov_b32_e32 v90, v0
	v_mov_b32_e32 v91, v0
	v_mov_b32_e32 v92, v0
	v_mov_b32_e32 v93, v0
	v_mov_b32_e32 v94, v0
	v_mov_b32_e32 v95, v0
	v_mov_b32_e32 v104, v0
	v_mov_b32_e32 v105, v0
	v_mov_b32_e32 v106, v0
	v_mov_b32_e32 v107, v0
	v_mov_b32_e32 v108, v0
	v_mov_b32_e32 v109, v0
	v_mov_b32_e32 v110, v0
	v_mov_b32_e32 v111, v0
	v_mov_b32_e32 v120, v0
	v_mov_b32_e32 v121, v0
	v_mov_b32_e32 v122, v0
	v_mov_b32_e32 v123, v0
	v_mov_b32_e32 v124, v0
	v_mov_b32_e32 v125, v0
	v_mov_b32_e32 v126, v0
	v_mov_b32_e32 v127, v0
	s_cmp_ge_u32 s3, 4
	s_cbranch_scc0 .Lgsp_12
	s_setprio 1
.Lgsp_12:
.LBB0_1548:
	ds_read_b128 v[128:131], v184
	ds_read_b128 v[132:135], v184 offset:1024
	ds_read_b128 v[136:139], v184 offset:2048
	ds_read_b128 v[140:143], v184 offset:3072
	ds_read_b128 v[144:147], v185
	ds_read_b128 v[148:151], v185 offset:1024
	ds_read_b128 v[152:155], v185 offset:2048
	ds_read_b128 v[174:177], v185 offset:3072
	s_add_u32 s45, s50, 0xfffc0080
	s_addc_u32 s52, s51, -1
	s_cmp_eq_u32 s43, 12
	s_cselect_b32 s55, s13, s52
	s_cselect_b32 s54, s31, s45
	s_cselect_b32 s53, s37, s42
	s_cselect_b32 s52, s40, s41
	v_lshl_add_u64 v[178:179], s[50:51], 0, v[166:167]
	s_add_i32 m0, s74, 0xc000
	ds_read_b128 v[190:193], v186
	ds_read_b128 v[194:197], v186 offset:1024
	ds_read_b128 v[198:201], v186 offset:2048
	ds_read_b128 v[202:205], v186 offset:3072
	ds_read_b128 v[206:209], v186 offset:4096
	ds_read_b128 v[210:213], v186 offset:5120
	ds_read_b128 v[214:217], v186 offset:6144
	ds_read_b128 v[218:221], v186 offset:7168
	global_load_lds_dwordx4 v[178:179], off
	v_lshl_add_u64 v[178:179], s[50:51], 0, v[168:169]
	s_add_i32 m0, s74, 0xe000
	s_nop 0
	global_load_lds_dwordx4 v[178:179], off
	s_waitcnt vmcnt(8)
	s_waitcnt lgkmcnt(0)
	s_barrier
; #define PG8_STAGE(bufoff, gbase, voff) do { _Pragma("unroll") for (int _i = 0; _i < 2; ++_i) \
;         __builtin_amdgcn_global_load_lds((const unsigned*)((const char*)(gbase) + (voff)[_i]), (PG8_LAS unsigned*)(lds + (bufoff) + ldsw + _i * 8192), 16, 0, 0); } while (0)
; #define PG8_LDA(dst, b, h) do { _Pragma("unroll") for (int m = 0; m < 4; ++m) _Pragma("unroll") for (int k = 0; k < 2; ++k) dst[m][k] = *(const PG8_LAS bf16x8*)(lds + PG8_SA(b, h) + aoff + m * 2048 + k * 1024); } while (0)
; #define PG8_MMA(ai, bj, At, Bt) do { __builtin_amdgcn_s_setprio(1); _Pragma("unroll") for (int m = 0; m < 4; ++m) _Pragma("unroll") for (int n = 0; n < 2; ++n) _Pragma("unroll") for (int k = 0; k < 2; ++k) \
;         acc[ai][bj][m][n] = mma16<F16>(Bt[n][k], At[m][k], acc[ai][bj][m][n]); __builtin_amdgcn_s_setprio(0); } while (0)
; #define PG8_WAIT_V(n) asm volatile("s_waitcnt vmcnt(" #n ")" ::: "memory")
; #define PG8_WAIT_L(n) asm volatile("s_waitcnt lgkmcnt(" #n ")" ::: "memory")
; #define PG8_BAR __builtin_amdgcn_s_barrier()
; #define PG8_SCHED __builtin_amdgcn_sched_barrier(0)
; template <class Epi, class Sched, bool ALIGN_EPI = false, bool SP2 = false, bool F16 = false>
; __device__ __forceinline__ void gemm_phase(PG8_LAS unsigned char* lds, const Gemm g, const Sched& S, const Epi& E, const int wid_in) {
;     ...
;             PG8_WAIT_V(8); PG8_WAIT_L(0); PG8_BAR; PG8_MMA(0, 0, At, B0); PG8_MMA(0, 1, At, B1); PG8_BAR; PG8_SCHED;
;             PG8_LDA(At, 0, 1); PG8_STAGE(PG8_SB(0, 0), b2, voffB); PG8_STAGE(PG8_SB(0, 1), b2 + hstep, voffB); PG8_STAGE(PG8_SA(0, 0), a2, voffA);
;             PG8_WAIT_V(8); PG8_WAIT_L(0); PG8_BAR; PG8_MMA(1, 0, At, B0); PG8_MMA(1, 1, At, B1); PG8_BAR; PG8_SCHED;
	s_waitcnt lgkmcnt(0)
	v_mfma_f32_16x16x32_f16 v[124:127], v[128:131], v[190:193], v[124:127]
	v_mfma_f32_16x16x32_f16 v[120:123], v[136:139], v[190:193], v[120:123]
	v_mfma_f32_16x16x32_f16 v[108:111], v[128:131], v[198:201], v[108:111]
	v_mfma_f32_16x16x32_f16 v[104:107], v[136:139], v[198:201], v[104:107]
	v_mfma_f32_16x16x32_f16 v[92:95], v[128:131], v[206:209], v[92:95]
	v_mfma_f32_16x16x32_f16 v[88:91], v[136:139], v[206:209], v[88:91]
	v_mfma_f32_16x16x32_f16 v[76:79], v[128:131], v[214:217], v[76:79]
	v_mfma_f32_16x16x32_f16 v[72:75], v[136:139], v[214:217], v[72:75]
	v_mfma_f32_16x16x32_f16 v[124:127], v[132:135], v[194:197], v[124:127]
	v_mfma_f32_16x16x32_f16 v[120:123], v[140:143], v[194:197], v[120:123]
	v_mfma_f32_16x16x32_f16 v[108:111], v[132:135], v[202:205], v[108:111]
	v_mfma_f32_16x16x32_f16 v[104:107], v[140:143], v[202:205], v[104:107]
	v_mfma_f32_16x16x32_f16 v[92:95], v[132:135], v[210:213], v[92:95]
	v_mfma_f32_16x16x32_f16 v[88:91], v[140:143], v[210:213], v[88:91]
	v_mfma_f32_16x16x32_f16 v[76:79], v[132:135], v[218:221], v[76:79]
	v_mfma_f32_16x16x32_f16 v[72:75], v[140:143], v[218:221], v[72:75]
	v_mfma_f32_16x16x32_f16 v[116:119], v[144:147], v[190:193], v[116:119]
	v_mfma_f32_16x16x32_f16 v[112:115], v[152:155], v[190:193], v[112:115]
	v_mfma_f32_16x16x32_f16 v[100:103], v[144:147], v[198:201], v[100:103]
	v_mfma_f32_16x16x32_f16 v[96:99], v[152:155], v[198:201], v[96:99]
	v_mfma_f32_16x16x32_f16 v[84:87], v[144:147], v[206:209], v[84:87]
	v_mfma_f32_16x16x32_f16 v[80:83], v[152:155], v[206:209], v[80:83]
	v_mfma_f32_16x16x32_f16 v[68:71], v[144:147], v[214:217], v[68:71]
	v_mfma_f32_16x16x32_f16 v[64:67], v[152:155], v[214:217], v[64:67]
	v_mfma_f32_16x16x32_f16 v[116:119], v[148:151], v[194:197], v[116:119]
	v_mfma_f32_16x16x32_f16 v[112:115], v[174:177], v[194:197], v[112:115]
	v_mfma_f32_16x16x32_f16 v[100:103], v[148:151], v[202:205], v[100:103]
	v_mfma_f32_16x16x32_f16 v[96:99], v[174:177], v[202:205], v[96:99]
	v_mfma_f32_16x16x32_f16 v[84:87], v[148:151], v[210:213], v[84:87]
	v_mfma_f32_16x16x32_f16 v[80:83], v[174:177], v[210:213], v[80:83]
	v_mfma_f32_16x16x32_f16 v[68:71], v[148:151], v[218:221], v[68:71]
	v_mfma_f32_16x16x32_f16 v[64:67], v[174:177], v[218:221], v[64:67]
	s_barrier
	s_add_i32 s45, s90, s68
	v_lshl_add_u64 v[178:179], s[52:53], 0, v[158:159]
	s_mov_b32 m0, s45
	ds_read_b128 v[190:193], v186 offset:16384
	ds_read_b128 v[194:197], v186 offset:17408
	ds_read_b128 v[198:201], v186 offset:18432
	ds_read_b128 v[202:205], v186 offset:19456
	ds_read_b128 v[206:209], v186 offset:20480
	ds_read_b128 v[210:213], v186 offset:21504
	ds_read_b128 v[214:217], v186 offset:22528
	ds_read_b128 v[218:221], v186 offset:23552
	global_load_lds_dwordx4 v[178:179], off
	s_add_i32 m0, s45, 0x2000
	s_add_u32 s56, s52, 0x40000
	v_lshl_add_u64 v[222:223], s[52:53], 0, v[162:163]
	s_addc_u32 s57, s53, 0
	s_add_i32 s45, s84, s68
	global_load_lds_dwordx4 v[222:223], off
	v_lshl_add_u64 v[224:225], s[56:57], 0, v[158:159]
	s_mov_b32 m0, s45
	v_lshl_add_u64 v[226:227], s[54:55], 0, v[160:161]
	global_load_lds_dwordx4 v[224:225], off
	v_lshl_add_u64 v[224:225], s[56:57], 0, v[162:163]
	s_add_i32 m0, s45, 0x2000
	s_nop 0
	global_load_lds_dwordx4 v[224:225], off
	v_lshl_add_u64 v[224:225], s[54:55], 0, v[156:157]
	s_mov_b32 m0, s74
	s_nop 0
	global_load_lds_dwordx4 v[224:225], off
	s_mov_b32 m0, s66
	s_nop 0
	global_load_lds_dwordx4 v[226:227], off
	s_waitcnt vmcnt(8)
	s_waitcnt lgkmcnt(0)
	s_barrier
	s_waitcnt lgkmcnt(0)
	v_mfma_f32_16x16x32_f16 v[60:63], v[128:131], v[190:193], v[60:63]
	v_mfma_f32_16x16x32_f16 v[56:59], v[136:139], v[190:193], v[56:59]
	v_mfma_f32_16x16x32_f16 v[44:47], v[128:131], v[198:201], v[44:47]
	v_mfma_f32_16x16x32_f16 v[40:43], v[136:139], v[198:201], v[40:43]
	v_mfma_f32_16x16x32_f16 v[28:31], v[128:131], v[206:209], v[28:31]
	v_mfma_f32_16x16x32_f16 v[24:27], v[136:139], v[206:209], v[24:27]
	v_mfma_f32_16x16x32_f16 v[12:15], v[128:131], v[214:217], v[12:15]
	v_mfma_f32_16x16x32_f16 v[8:11], v[136:139], v[214:217], v[8:11]
	v_mfma_f32_16x16x32_f16 v[60:63], v[132:135], v[194:197], v[60:63]
	v_mfma_f32_16x16x32_f16 v[56:59], v[140:143], v[194:197], v[56:59]
	v_mfma_f32_16x16x32_f16 v[44:47], v[132:135], v[202:205], v[44:47]
	v_mfma_f32_16x16x32_f16 v[40:43], v[140:143], v[202:205], v[40:43]
	v_mfma_f32_16x16x32_f16 v[28:31], v[132:135], v[210:213], v[28:31]
	v_mfma_f32_16x16x32_f16 v[24:27], v[140:143], v[210:213], v[24:27]
	v_mfma_f32_16x16x32_f16 v[12:15], v[132:135], v[218:221], v[12:15]
	v_mfma_f32_16x16x32_f16 v[8:11], v[140:143], v[218:221], v[8:11]
	v_mfma_f32_16x16x32_f16 v[52:55], v[144:147], v[190:193], v[52:55]
	v_mfma_f32_16x16x32_f16 v[48:51], v[152:155], v[190:193], v[48:51]
	v_mfma_f32_16x16x32_f16 v[36:39], v[144:147], v[198:201], v[36:39]
	v_mfma_f32_16x16x32_f16 v[32:35], v[152:155], v[198:201], v[32:35]
	v_mfma_f32_16x16x32_f16 v[20:23], v[144:147], v[206:209], v[20:23]
	v_mfma_f32_16x16x32_f16 v[16:19], v[152:155], v[206:209], v[16:19]
	v_mfma_f32_16x16x32_f16 v[4:7], v[144:147], v[214:217], v[4:7]
	v_mfma_f32_16x16x32_f16 v[0:3], v[152:155], v[214:217], v[0:3]
	v_mfma_f32_16x16x32_f16 v[52:55], v[148:151], v[194:197], v[52:55]
	v_mfma_f32_16x16x32_f16 v[48:51], v[174:177], v[194:197], v[48:51]
	v_mfma_f32_16x16x32_f16 v[36:39], v[148:151], v[202:205], v[36:39]
	v_mfma_f32_16x16x32_f16 v[32:35], v[174:177], v[202:205], v[32:35]
	v_mfma_f32_16x16x32_f16 v[20:23], v[148:151], v[210:213], v[20:23]
	v_mfma_f32_16x16x32_f16 v[16:19], v[174:177], v[210:213], v[16:19]
	v_mfma_f32_16x16x32_f16 v[4:7], v[148:151], v[218:221], v[4:7]
	v_mfma_f32_16x16x32_f16 v[0:3], v[174:177], v[218:221], v[0:3]
	s_barrier
; #define PG8_STAGE(bufoff, gbase, voff) do { _Pragma("unroll") for (int _i = 0; _i < 2; ++_i) \
;         __builtin_amdgcn_global_load_lds((const unsigned*)((const char*)(gbase) + (voff)[_i]), (PG8_LAS unsigned*)(lds + (bufoff) + ldsw + _i * 8192), 16, 0, 0); } while (0)
; #define PG8_LDA(dst, b, h) do { _Pragma("unroll") for (int m = 0; m < 4; ++m) _Pragma("unroll") for (int k = 0; k < 2; ++k) dst[m][k] = *(const PG8_LAS bf16x8*)(lds + PG8_SA(b, h) + aoff + m * 2048 + k * 1024); } while (0)
; #define PG8_LDB(dst, b, h) do { _Pragma("unroll") for (int n = 0; n < 2; ++n) _Pragma("unroll") for (int k = 0; k < 2; ++k) dst[n][k] = *(const PG8_LAS bf16x8*)(lds + PG8_SB(b, h) + boff + n * 2048 + k * 1024); } while (0)
; #define PG8_MMA(ai, bj, At, Bt) do { __builtin_amdgcn_s_setprio(1); _Pragma("unroll") for (int m = 0; m < 4; ++m) _Pragma("unroll") for (int n = 0; n < 2; ++n) _Pragma("unroll") for (int k = 0; k < 2; ++k) \
;         acc[ai][bj][m][n] = mma16<F16>(Bt[n][k], At[m][k], acc[ai][bj][m][n]); __builtin_amdgcn_s_setprio(0); } while (0)
; #define PG8_WAIT_V(n) asm volatile("s_waitcnt vmcnt(" #n ")" ::: "memory")
; #define PG8_WAIT_L(n) asm volatile("s_waitcnt lgkmcnt(" #n ")" ::: "memory")
; #define PG8_BAR __builtin_amdgcn_s_barrier()
; #define PG8_SCHED __builtin_amdgcn_sched_barrier(0)
; template <class Epi, class Sched, bool ALIGN_EPI = false, bool SP2 = false, bool F16 = false>
; __device__ __forceinline__ void gemm_phase(PG8_LAS unsigned char* lds, const Gemm g, const Sched& S, const Epi& E, const int wid_in) {
;     ...
;             PG8_LDB(B0, 1, 0); PG8_LDB(B1, 1, 1); PG8_SCHED; PG8_LDA(At, 1, 0); PG8_STAGE(PG8_SA(0, 1), a2 + hstep, voffA);
;             PG8_WAIT_V(8); PG8_WAIT_L(0); PG8_BAR; PG8_MMA(0, 0, At, B0); PG8_MMA(0, 1, At, B1); PG8_BAR; PG8_SCHED;
	s_add_i32 s45, 0, 0x18000
	s_add_i32 s56, 0, 0x1c000
	v_add_u32_e32 v140, s45, v183
	v_add_u32_e32 v165, s56, v183
	ds_read_b128 v[128:131], v140
	ds_read_b128 v[132:135], v140 offset:1024
	ds_read_b128 v[136:139], v140 offset:2048
	ds_read_b128 v[140:143], v140 offset:3072
	ds_read_b128 v[144:147], v165
	ds_read_b128 v[148:151], v165 offset:1024
	ds_read_b128 v[152:155], v165 offset:2048
	ds_read_b128 v[174:177], v165 offset:3072
	s_add_u32 s54, s54, 0x40000
	s_addc_u32 s55, s55, 0
	s_mov_b32 m0, s67
	v_lshl_add_u64 v[228:229], s[54:55], 0, v[156:157]
	ds_read_b128 v[190:193], v186 offset:32768
	ds_read_b128 v[194:197], v186 offset:33792
	ds_read_b128 v[198:201], v186 offset:34816
	ds_read_b128 v[202:205], v186 offset:35840
	ds_read_b128 v[206:209], v186 offset:36864
	ds_read_b128 v[210:213], v186 offset:37888
	ds_read_b128 v[214:217], v186 offset:38912
	ds_read_b128 v[218:221], v186 offset:39936
	global_load_lds_dwordx4 v[228:229], off
	v_lshl_add_u64 v[228:229], s[54:55], 0, v[160:161]
	s_mov_b32 m0, s91
	s_nop 0
	global_load_lds_dwordx4 v[228:229], off
	s_waitcnt vmcnt(8)
	s_waitcnt lgkmcnt(0)
	s_barrier
	s_waitcnt lgkmcnt(0)
	v_mfma_f32_16x16x32_f16 v[124:127], v[128:131], v[190:193], v[124:127]
	v_mfma_f32_16x16x32_f16 v[120:123], v[136:139], v[190:193], v[120:123]
	v_mfma_f32_16x16x32_f16 v[108:111], v[128:131], v[198:201], v[108:111]
	v_mfma_f32_16x16x32_f16 v[104:107], v[136:139], v[198:201], v[104:107]
	v_mfma_f32_16x16x32_f16 v[92:95], v[128:131], v[206:209], v[92:95]
	v_mfma_f32_16x16x32_f16 v[88:91], v[136:139], v[206:209], v[88:91]
	v_mfma_f32_16x16x32_f16 v[76:79], v[128:131], v[214:217], v[76:79]
	v_mfma_f32_16x16x32_f16 v[72:75], v[136:139], v[214:217], v[72:75]
	v_mfma_f32_16x16x32_f16 v[124:127], v[132:135], v[194:197], v[124:127]
	v_mfma_f32_16x16x32_f16 v[120:123], v[140:143], v[194:197], v[120:123]
	v_mfma_f32_16x16x32_f16 v[108:111], v[132:135], v[202:205], v[108:111]
	v_mfma_f32_16x16x32_f16 v[104:107], v[140:143], v[202:205], v[104:107]
	v_mfma_f32_16x16x32_f16 v[92:95], v[132:135], v[210:213], v[92:95]
	v_mfma_f32_16x16x32_f16 v[88:91], v[140:143], v[210:213], v[88:91]
	v_mfma_f32_16x16x32_f16 v[76:79], v[132:135], v[218:221], v[76:79]
	v_mfma_f32_16x16x32_f16 v[72:75], v[140:143], v[218:221], v[72:75]
	v_mfma_f32_16x16x32_f16 v[116:119], v[144:147], v[190:193], v[116:119]
	v_mfma_f32_16x16x32_f16 v[112:115], v[152:155], v[190:193], v[112:115]
	v_mfma_f32_16x16x32_f16 v[100:103], v[144:147], v[198:201], v[100:103]
	v_mfma_f32_16x16x32_f16 v[96:99], v[152:155], v[198:201], v[96:99]
	v_mfma_f32_16x16x32_f16 v[84:87], v[144:147], v[206:209], v[84:87]
	v_mfma_f32_16x16x32_f16 v[80:83], v[152:155], v[206:209], v[80:83]
	v_mfma_f32_16x16x32_f16 v[68:71], v[144:147], v[214:217], v[68:71]
	v_mfma_f32_16x16x32_f16 v[64:67], v[152:155], v[214:217], v[64:67]
	v_mfma_f32_16x16x32_f16 v[116:119], v[148:151], v[194:197], v[116:119]
	v_mfma_f32_16x16x32_f16 v[112:115], v[174:177], v[194:197], v[112:115]
	v_mfma_f32_16x16x32_f16 v[100:103], v[148:151], v[202:205], v[100:103]
	v_mfma_f32_16x16x32_f16 v[96:99], v[174:177], v[202:205], v[96:99]
	v_mfma_f32_16x16x32_f16 v[84:87], v[148:151], v[210:213], v[84:87]
	v_mfma_f32_16x16x32_f16 v[80:83], v[174:177], v[210:213], v[80:83]
	v_mfma_f32_16x16x32_f16 v[68:71], v[148:151], v[218:221], v[68:71]
	v_mfma_f32_16x16x32_f16 v[64:67], v[174:177], v[218:221], v[64:67]
	s_barrier
; #define PG8_STAGE(bufoff, gbase, voff) do { _Pragma("unroll") for (int _i = 0; _i < 2; ++_i) \
;         __builtin_amdgcn_global_load_lds((const unsigned*)((const char*)(gbase) + (voff)[_i]), (PG8_LAS unsigned*)(lds + (bufoff) + ldsw + _i * 8192), 16, 0, 0); } while (0)
; #define PG8_LDA(dst, b, h) do { _Pragma("unroll") for (int m = 0; m < 4; ++m) _Pragma("unroll") for (int k = 0; k < 2; ++k) dst[m][k] = *(const PG8_LAS bf16x8*)(lds + PG8_SA(b, h) + aoff + m * 2048 + k * 1024); } while (0)
; #define PG8_MMA(ai, bj, At, Bt) do { __builtin_amdgcn_s_setprio(1); _Pragma("unroll") for (int m = 0; m < 4; ++m) _Pragma("unroll") for (int n = 0; n < 2; ++n) _Pragma("unroll") for (int k = 0; k < 2; ++k) \
;         acc[ai][bj][m][n] = mma16<F16>(Bt[n][k], At[m][k], acc[ai][bj][m][n]); __builtin_amdgcn_s_setprio(0); } while (0)
; #define PG8_WAIT_V(n) asm volatile("s_waitcnt vmcnt(" #n ")" ::: "memory")
; #define PG8_WAIT_L(n) asm volatile("s_waitcnt lgkmcnt(" #n ")" ::: "memory")
; #define PG8_BAR __builtin_amdgcn_s_barrier()
; #define PG8_SCHED __builtin_amdgcn_sched_barrier(0)
; template <class Epi, class Sched, bool ALIGN_EPI = false, bool SP2 = false, bool F16 = false>
; __device__ __forceinline__ void gemm_phase(PG8_LAS unsigned char* lds, const Gemm g, const Sched& S, const Epi& E, const int wid_in) {
;     ...
;         for (int t = 0; t < nt; t += 2) {
;     ...
;             PG8_LDA(At, 1, 1); PG8_STAGE(PG8_SB(1, 0), b3, voffB); PG8_STAGE(PG8_SB(1, 1), b3 + hstep, voffB); PG8_STAGE(PG8_SA(1, 0), a3, voffA);
;             PG8_WAIT_V(8); PG8_WAIT_L(0); PG8_BAR; PG8_MMA(1, 0, At, B0); PG8_MMA(1, 1, At, B1); PG8_BAR; PG8_SCHED;
	s_add_i32 s45, s45, s68
	v_lshl_add_u64 v[178:179], v[178:179], 0, s[34:35]
	s_mov_b32 m0, s45
	ds_read_b128 v[190:193], v186 offset:49152
	ds_read_b128 v[194:197], v186 offset:50176
	ds_read_b128 v[198:201], v186 offset:51200
	ds_read_b128 v[202:205], v186 offset:52224
	ds_read_b128 v[206:209], v186 offset:53248
	ds_read_b128 v[210:213], v186 offset:54272
	ds_read_b128 v[214:217], v186 offset:55296
	ds_read_b128 v[218:221], v186 offset:56320
	global_load_lds_dwordx4 v[178:179], off
	s_add_i32 m0, s45, 0x2000
	s_add_u32 s52, s52, 0x40080
	v_lshl_add_u64 v[178:179], v[222:223], 0, s[34:35]
	s_addc_u32 s53, s53, 0
	s_add_i32 s45, s56, s68
	global_load_lds_dwordx4 v[178:179], off
	v_lshl_add_u64 v[178:179], s[52:53], 0, v[158:159]
	s_mov_b32 m0, s45
	s_nop 0
	global_load_lds_dwordx4 v[178:179], off
	v_lshl_add_u64 v[178:179], s[52:53], 0, v[162:163]
	s_add_i32 m0, s45, 0x2000
	s_nop 0
	global_load_lds_dwordx4 v[178:179], off
	v_lshl_add_u64 v[178:179], v[224:225], 0, s[34:35]
	s_mov_b32 m0, s75
	s_nop 0
	global_load_lds_dwordx4 v[178:179], off
	v_lshl_add_u64 v[178:179], v[226:227], 0, s[34:35]
	s_mov_b32 m0, s97
	s_nop 0
	global_load_lds_dwordx4 v[178:179], off
	s_waitcnt vmcnt(8)
	s_waitcnt lgkmcnt(0)
	s_barrier
	s_waitcnt lgkmcnt(0)
	v_mfma_f32_16x16x32_f16 v[60:63], v[128:131], v[190:193], v[60:63]
	v_mfma_f32_16x16x32_f16 v[56:59], v[136:139], v[190:193], v[56:59]
	v_mfma_f32_16x16x32_f16 v[44:47], v[128:131], v[198:201], v[44:47]
	v_mfma_f32_16x16x32_f16 v[40:43], v[136:139], v[198:201], v[40:43]
	v_mfma_f32_16x16x32_f16 v[28:31], v[128:131], v[206:209], v[28:31]
	v_mfma_f32_16x16x32_f16 v[24:27], v[136:139], v[206:209], v[24:27]
	v_mfma_f32_16x16x32_f16 v[12:15], v[128:131], v[214:217], v[12:15]
	v_mfma_f32_16x16x32_f16 v[8:11], v[136:139], v[214:217], v[8:11]
	v_mfma_f32_16x16x32_f16 v[60:63], v[132:135], v[194:197], v[60:63]
	v_mfma_f32_16x16x32_f16 v[56:59], v[140:143], v[194:197], v[56:59]
	v_mfma_f32_16x16x32_f16 v[44:47], v[132:135], v[202:205], v[44:47]
	v_mfma_f32_16x16x32_f16 v[40:43], v[140:143], v[202:205], v[40:43]
	v_mfma_f32_16x16x32_f16 v[28:31], v[132:135], v[210:213], v[28:31]
	v_mfma_f32_16x16x32_f16 v[24:27], v[140:143], v[210:213], v[24:27]
	v_mfma_f32_16x16x32_f16 v[12:15], v[132:135], v[218:221], v[12:15]
	v_mfma_f32_16x16x32_f16 v[8:11], v[140:143], v[218:221], v[8:11]
	v_mfma_f32_16x16x32_f16 v[52:55], v[144:147], v[190:193], v[52:55]
	v_mfma_f32_16x16x32_f16 v[48:51], v[152:155], v[190:193], v[48:51]
	v_mfma_f32_16x16x32_f16 v[36:39], v[144:147], v[198:201], v[36:39]
	v_mfma_f32_16x16x32_f16 v[32:35], v[152:155], v[198:201], v[32:35]
	v_mfma_f32_16x16x32_f16 v[20:23], v[144:147], v[206:209], v[20:23]
	v_mfma_f32_16x16x32_f16 v[16:19], v[152:155], v[206:209], v[16:19]
	v_mfma_f32_16x16x32_f16 v[4:7], v[144:147], v[214:217], v[4:7]
	v_mfma_f32_16x16x32_f16 v[0:3], v[152:155], v[214:217], v[0:3]
	v_mfma_f32_16x16x32_f16 v[52:55], v[148:151], v[194:197], v[52:55]
	v_mfma_f32_16x16x32_f16 v[48:51], v[174:177], v[194:197], v[48:51]
	v_mfma_f32_16x16x32_f16 v[36:39], v[148:151], v[202:205], v[36:39]
	v_mfma_f32_16x16x32_f16 v[32:35], v[174:177], v[202:205], v[32:35]
	v_mfma_f32_16x16x32_f16 v[20:23], v[148:151], v[210:213], v[20:23]
	v_mfma_f32_16x16x32_f16 v[16:19], v[174:177], v[210:213], v[16:19]
	v_mfma_f32_16x16x32_f16 v[4:7], v[148:151], v[218:221], v[4:7]
	v_mfma_f32_16x16x32_f16 v[0:3], v[174:177], v[218:221], v[0:3]
	s_barrier
	s_add_i32 s43, s43, 2
	s_add_u32 s50, s50, 0x100
	s_addc_u32 s51, s51, 0
	s_add_u32 s41, s41, 0x100
	s_addc_u32 s42, s42, 0
	s_cmp_gt_u32 s43, 13
	s_cbranch_scc0 .LBB0_1548
	s_setprio 0
	s_and_b64 vcc, exec, s[16:17]
	s_cbranch_vccz .LBB0_1551
	s_barrier

; #define PG8_STAGE(bufoff, gbase, voff) do { _Pragma("unroll") for (int _i = 0; _i < 2; ++_i) \
;         __builtin_amdgcn_global_load_lds((const unsigned*)((const char*)(gbase) + (voff)[_i]), (PG8_LAS unsigned*)(lds + (bufoff) + ldsw + _i * 8192), 16, 0, 0); } while (0)
; #define PG8_LDA(dst, b, h) do { _Pragma("unroll") for (int m = 0; m < 4; ++m) _Pragma("unroll") for (int k = 0; k < 2; ++k) dst[m][k] = *(const PG8_LAS bf16x8*)(lds + PG8_SA(b, h) + aoff + m * 2048 + k * 1024); } while (0)
; #define PG8_LDB(dst, b, h) do { _Pragma("unroll") for (int n = 0; n < 2; ++n) _Pragma("unroll") for (int k = 0; k < 2; ++k) dst[n][k] = *(const PG8_LAS bf16x8*)(lds + PG8_SB(b, h) + boff + n * 2048 + k * 1024); } while (0)
; #define PG8_WAIT_V(n) asm volatile("s_waitcnt vmcnt(" #n ")" ::: "memory")
; #define PG8_WAIT_L(n) asm volatile("s_waitcnt lgkmcnt(" #n ")" ::: "memory")
; #define PG8_BAR __builtin_amdgcn_s_barrier()
; template <class Epi, class Sched, bool ALIGN_EPI = false, bool SP2 = false, bool F16 = false>
; __device__ __forceinline__ void gemm_phase(PG8_LAS unsigned char* lds, const Gemm g, const Sched& S, const Epi& E, const int wid_in) {
;     ...
;         const bool has_next = S.next(ui + 1, nxt);
;         const char* nA = has_next ? (const char*)g.A + (size_t)nxt.pm * tstep : cA; const char* nB = has_next ? (const char*)g.Bt + (size_t)nxt.pn * tstep : cB;
;         for (int t = 0; t < nt; t += 2) {
;             const bool last = (t == nt - 2);
;             const char* a1 = cA + (size_t)(t + 1) * kstep;
;             const char* a2 = last ? nA : cA + (size_t)(t + 2) * kstep; const char* b2 = last ? nB : cB + (size_t)(t + 2) * kstep;
;             const char* a3 = a2 + kstep; const char* b3 = b2 + kstep;
;             if (last && has_next) S.a_ready(nxt);
;             if constexpr (SP2) {
;             PG8_LDB(B0, 0, 0); PG8_LDB(B1, 0, 1); PG8_SCHED; PG8_LDA(At, 0, 0); PG8_STAGE(PG8_SA(1, 1), a1 + hstep, voffA);
;             PG8_WAIT_V(8); PG8_WAIT_L(0); PG8_BAR; PG8_MMA(0, 0, At, B0); PG8_MMA(0, 1, At, B1); PG8_BAR; PG8_SCHED;
;     ...
; #pragma unroll
;         for (int a = 0; a < 2; ++a)
; #pragma unroll
;             for (int b = 0; b < 2; ++b)
; #pragma unroll
;                 for (int m = 0; m < 4; ++m)
; #pragma unroll
;                     for (int n = 0; n < 2; ++n) acc[a][b][m][n] = (f32x4){0.f, 0.f, 0.f, 0.f};
;         cur = nxt; cA = nA; cB = nB; ++ui;
.LBB0_1831:
	s_ashr_i32 s35, s34, 31
	s_lshl_b64 s[36:37], s[34:35], 19
	s_add_u32 s36, s15, s36
	s_addc_u32 s37, s19, s37
	s_and_b64 s[42:43], s[10:11], exec
	s_cselect_b32 s35, s37, s49
	s_cselect_b32 s42, s36, s48
	s_ashr_i32 s31, s30, 31
	s_lshl_b64 s[44:45], s[30:31], 19
	s_add_u32 s44, s21, s44
	s_addc_u32 s45, s40, s45
	s_and_b64 s[52:53], s[10:11], exec
	s_cselect_b32 s31, s45, s51
	s_cselect_b32 s43, s44, s50
	s_add_u32 s48, s48, 0x40080
	s_addc_u32 s49, s49, 0
	s_add_u32 s47, s50, 0x100
	v_mov_b32_e32 v0, 0
	s_addc_u32 s60, s51, 0
	s_mov_b32 s61, -2
	v_mov_b32_e32 v1, v0
	v_mov_b32_e32 v2, v0
	v_mov_b32_e32 v3, v0
	v_mov_b32_e32 v4, v0
	v_mov_b32_e32 v5, v0
	v_mov_b32_e32 v6, v0
	v_mov_b32_e32 v7, v0
	v_mov_b32_e32 v16, v0
	v_mov_b32_e32 v17, v0
	v_mov_b32_e32 v18, v0
	v_mov_b32_e32 v19, v0
	v_mov_b32_e32 v20, v0
	v_mov_b32_e32 v21, v0
	v_mov_b32_e32 v22, v0
	v_mov_b32_e32 v23, v0
	v_mov_b32_e32 v32, v0
	v_mov_b32_e32 v33, v0
	v_mov_b32_e32 v34, v0
	v_mov_b32_e32 v35, v0
	v_mov_b32_e32 v36, v0
	v_mov_b32_e32 v37, v0
	v_mov_b32_e32 v38, v0
	v_mov_b32_e32 v39, v0
	v_mov_b32_e32 v48, v0
	v_mov_b32_e32 v49, v0
	v_mov_b32_e32 v50, v0
	v_mov_b32_e32 v51, v0
	v_mov_b32_e32 v52, v0
	v_mov_b32_e32 v53, v0
	v_mov_b32_e32 v54, v0
	v_mov_b32_e32 v55, v0
	v_mov_b32_e32 v8, v0
	v_mov_b32_e32 v9, v0
	v_mov_b32_e32 v10, v0
	v_mov_b32_e32 v11, v0
	v_mov_b32_e32 v12, v0
	v_mov_b32_e32 v13, v0
	v_mov_b32_e32 v14, v0
	v_mov_b32_e32 v15, v0
	v_mov_b32_e32 v24, v0
	v_mov_b32_e32 v25, v0
	v_mov_b32_e32 v26, v0
	v_mov_b32_e32 v27, v0
	v_mov_b32_e32 v28, v0
	v_mov_b32_e32 v29, v0
	v_mov_b32_e32 v30, v0
	v_mov_b32_e32 v31, v0
	v_mov_b32_e32 v40, v0
	v_mov_b32_e32 v41, v0
	v_mov_b32_e32 v42, v0
	v_mov_b32_e32 v43, v0
	v_mov_b32_e32 v44, v0
	v_mov_b32_e32 v45, v0
	v_mov_b32_e32 v46, v0
	v_mov_b32_e32 v47, v0
	v_mov_b32_e32 v56, v0
	v_mov_b32_e32 v57, v0
	v_mov_b32_e32 v58, v0
	v_mov_b32_e32 v59, v0
	v_mov_b32_e32 v60, v0
	v_mov_b32_e32 v61, v0
	v_mov_b32_e32 v62, v0
	v_mov_b32_e32 v63, v0
	v_mov_b32_e32 v64, v0
	v_mov_b32_e32 v65, v0
	v_mov_b32_e32 v66, v0
	v_mov_b32_e32 v67, v0
	v_mov_b32_e32 v68, v0
	v_mov_b32_e32 v69, v0
	v_mov_b32_e32 v70, v0
	v_mov_b32_e32 v71, v0
	v_mov_b32_e32 v80, v0
	v_mov_b32_e32 v81, v0
	v_mov_b32_e32 v82, v0
	v_mov_b32_e32 v83, v0
	v_mov_b32_e32 v84, v0
	v_mov_b32_e32 v85, v0
	v_mov_b32_e32 v86, v0
	v_mov_b32_e32 v87, v0
	v_mov_b32_e32 v96, v0
	v_mov_b32_e32 v97, v0
	v_mov_b32_e32 v98, v0
	v_mov_b32_e32 v99, v0
	v_mov_b32_e32 v100, v0
	v_mov_b32_e32 v101, v0
	v_mov_b32_e32 v102, v0
	v_mov_b32_e32 v103, v0
	v_mov_b32_e32 v112, v0
	v_mov_b32_e32 v113, v0
	v_mov_b32_e32 v114, v0
	v_mov_b32_e32 v115, v0
	v_mov_b32_e32 v116, v0
	v_mov_b32_e32 v117, v0
	v_mov_b32_e32 v118, v0
	v_mov_b32_e32 v119, v0
	v_mov_b32_e32 v72, v0
	v_mov_b32_e32 v73, v0
	v_mov_b32_e32 v74, v0
	v_mov_b32_e32 v75, v0
	v_mov_b32_e32 v76, v0
	v_mov_b32_e32 v77, v0
	v_mov_b32_e32 v78, v0
	v_mov_b32_e32 v79, v0
	v_mov_b32_e32 v88, v0
	v_mov_b32_e32 v89, v0
	v_mov_b32_e32 v90, v0
	v_mov_b32_e32 v91, v0
	v_mov_b32_e32 v92, v0
	v_mov_b32_e32 v93, v0
	v_mov_b32_e32 v94, v0
	v_mov_b32_e32 v95, v0
	v_mov_b32_e32 v104, v0
	v_mov_b32_e32 v105, v0
	v_mov_b32_e32 v106, v0
	v_mov_b32_e32 v107, v0
	v_mov_b32_e32 v108, v0
	v_mov_b32_e32 v109, v0
	v_mov_b32_e32 v110, v0
	v_mov_b32_e32 v111, v0
	v_mov_b32_e32 v120, v0
	v_mov_b32_e32 v121, v0
	v_mov_b32_e32 v122, v0
	v_mov_b32_e32 v123, v0
	v_mov_b32_e32 v124, v0
	v_mov_b32_e32 v125, v0
	v_mov_b32_e32 v126, v0
	v_mov_b32_e32 v127, v0
	s_cmp_ge_u32 s3, 4
	s_cbranch_scc0 .Lgsp_13
	s_setprio 1
.Lgsp_13:
.LBB0_1832:
	ds_read_b128 v[128:131], v189
	ds_read_b128 v[132:135], v189 offset:1024
	ds_read_b128 v[136:139], v189 offset:2048
	ds_read_b128 v[140:143], v189 offset:3072
	ds_read_b128 v[144:147], v190
	ds_read_b128 v[148:151], v190 offset:1024
	ds_read_b128 v[168:171], v190 offset:2048
	ds_read_b128 v[172:175], v190 offset:3072
	s_add_u32 s50, s48, 0xfffc0080
	s_addc_u32 s51, s49, -1
	s_cmp_eq_u32 s61, 12
	s_cselect_b32 s53, s35, s51
	s_cselect_b32 s52, s42, s50
	s_cselect_b32 s51, s31, s60
	s_cselect_b32 s50, s43, s47
	s_mov_b32 m0, s91
	v_lshl_add_u64 v[184:185], s[48:49], 0, v[160:161]
	ds_read_b128 v[176:179], v191
	ds_read_b128 v[180:183], v191 offset:1024
	ds_read_b128 v[192:195], v191 offset:2048
	ds_read_b128 v[196:199], v191 offset:3072
	ds_read_b128 v[200:203], v191 offset:4096
	ds_read_b128 v[204:207], v191 offset:5120
	ds_read_b128 v[208:211], v191 offset:6144
	ds_read_b128 v[212:215], v191 offset:7168
	global_load_lds_dwordx4 v[184:185], off
	v_lshl_add_u64 v[184:185], s[48:49], 0, v[162:163]
	s_add_i32 m0, s74, 0xe000
	s_nop 0
	global_load_lds_dwordx4 v[184:185], off
	s_waitcnt vmcnt(8)
	s_waitcnt lgkmcnt(0)
	s_barrier
; #define PG8_STAGE(bufoff, gbase, voff) do { _Pragma("unroll") for (int _i = 0; _i < 2; ++_i) \
;         __builtin_amdgcn_global_load_lds((const unsigned*)((const char*)(gbase) + (voff)[_i]), (PG8_LAS unsigned*)(lds + (bufoff) + ldsw + _i * 8192), 16, 0, 0); } while (0)
; #define PG8_LDA(dst, b, h) do { _Pragma("unroll") for (int m = 0; m < 4; ++m) _Pragma("unroll") for (int k = 0; k < 2; ++k) dst[m][k] = *(const PG8_LAS bf16x8*)(lds + PG8_SA(b, h) + aoff + m * 2048 + k * 1024); } while (0)
; #define PG8_MMA(ai, bj, At, Bt) do { __builtin_amdgcn_s_setprio(1); _Pragma("unroll") for (int m = 0; m < 4; ++m) _Pragma("unroll") for (int n = 0; n < 2; ++n) _Pragma("unroll") for (int k = 0; k < 2; ++k) \
;         acc[ai][bj][m][n] = mma16<F16>(Bt[n][k], At[m][k], acc[ai][bj][m][n]); __builtin_amdgcn_s_setprio(0); } while (0)
; #define PG8_WAIT_V(n) asm volatile("s_waitcnt vmcnt(" #n ")" ::: "memory")
; #define PG8_WAIT_L(n) asm volatile("s_waitcnt lgkmcnt(" #n ")" ::: "memory")
; #define PG8_BAR __builtin_amdgcn_s_barrier()
; #define PG8_SCHED __builtin_amdgcn_sched_barrier(0)
; template <class Epi, class Sched, bool ALIGN_EPI = false, bool SP2 = false, bool F16 = false>
; __device__ __forceinline__ void gemm_phase(PG8_LAS unsigned char* lds, const Gemm g, const Sched& S, const Epi& E, const int wid_in) {
;     ...
;             PG8_WAIT_V(8); PG8_WAIT_L(0); PG8_BAR; PG8_MMA(0, 0, At, B0); PG8_MMA(0, 1, At, B1); PG8_BAR; PG8_SCHED;
;             PG8_LDA(At, 0, 1); PG8_STAGE(PG8_SB(0, 0), b2, voffB); PG8_STAGE(PG8_SB(0, 1), b2 + hstep, voffB); PG8_STAGE(PG8_SA(0, 0), a2, voffA);
;             PG8_WAIT_V(8); PG8_WAIT_L(0); PG8_BAR; PG8_MMA(1, 0, At, B0); PG8_MMA(1, 1, At, B1); PG8_BAR; PG8_SCHED;
	s_waitcnt lgkmcnt(0)
	v_mfma_f32_16x16x32_bf16 v[124:127], v[128:131], v[176:179], v[124:127]
	v_mfma_f32_16x16x32_bf16 v[120:123], v[136:139], v[176:179], v[120:123]
	v_mfma_f32_16x16x32_bf16 v[108:111], v[128:131], v[192:195], v[108:111]
	v_mfma_f32_16x16x32_bf16 v[104:107], v[136:139], v[192:195], v[104:107]
	v_mfma_f32_16x16x32_bf16 v[92:95], v[128:131], v[200:203], v[92:95]
	v_mfma_f32_16x16x32_bf16 v[88:91], v[136:139], v[200:203], v[88:91]
	v_mfma_f32_16x16x32_bf16 v[76:79], v[128:131], v[208:211], v[76:79]
	v_mfma_f32_16x16x32_bf16 v[72:75], v[136:139], v[208:211], v[72:75]
	v_mfma_f32_16x16x32_bf16 v[124:127], v[132:135], v[180:183], v[124:127]
	v_mfma_f32_16x16x32_bf16 v[120:123], v[140:143], v[180:183], v[120:123]
	v_mfma_f32_16x16x32_bf16 v[108:111], v[132:135], v[196:199], v[108:111]
	v_mfma_f32_16x16x32_bf16 v[104:107], v[140:143], v[196:199], v[104:107]
	v_mfma_f32_16x16x32_bf16 v[92:95], v[132:135], v[204:207], v[92:95]
	v_mfma_f32_16x16x32_bf16 v[88:91], v[140:143], v[204:207], v[88:91]
	v_mfma_f32_16x16x32_bf16 v[76:79], v[132:135], v[212:215], v[76:79]
	v_mfma_f32_16x16x32_bf16 v[72:75], v[140:143], v[212:215], v[72:75]
	v_mfma_f32_16x16x32_bf16 v[116:119], v[144:147], v[176:179], v[116:119]
	v_mfma_f32_16x16x32_bf16 v[112:115], v[168:171], v[176:179], v[112:115]
	v_mfma_f32_16x16x32_bf16 v[100:103], v[144:147], v[192:195], v[100:103]
	v_mfma_f32_16x16x32_bf16 v[96:99], v[168:171], v[192:195], v[96:99]
	v_mfma_f32_16x16x32_bf16 v[84:87], v[144:147], v[200:203], v[84:87]
	v_mfma_f32_16x16x32_bf16 v[80:83], v[168:171], v[200:203], v[80:83]
	v_mfma_f32_16x16x32_bf16 v[68:71], v[144:147], v[208:211], v[68:71]
	v_mfma_f32_16x16x32_bf16 v[64:67], v[168:171], v[208:211], v[64:67]
	v_mfma_f32_16x16x32_bf16 v[116:119], v[148:151], v[180:183], v[116:119]
	v_mfma_f32_16x16x32_bf16 v[112:115], v[172:175], v[180:183], v[112:115]
	v_mfma_f32_16x16x32_bf16 v[100:103], v[148:151], v[196:199], v[100:103]
	v_mfma_f32_16x16x32_bf16 v[96:99], v[172:175], v[196:199], v[96:99]
	v_mfma_f32_16x16x32_bf16 v[84:87], v[148:151], v[204:207], v[84:87]
	v_mfma_f32_16x16x32_bf16 v[80:83], v[172:175], v[204:207], v[80:83]
	v_mfma_f32_16x16x32_bf16 v[68:71], v[148:151], v[212:215], v[68:71]
	v_mfma_f32_16x16x32_bf16 v[64:67], v[172:175], v[212:215], v[64:67]
	s_barrier
	s_add_i32 s62, s57, s68
	v_lshl_add_u64 v[184:185], s[50:51], 0, v[154:155]
	s_mov_b32 m0, s62
	ds_read_b128 v[176:179], v191 offset:16384
	ds_read_b128 v[180:183], v191 offset:17408
	ds_read_b128 v[192:195], v191 offset:18432
	ds_read_b128 v[196:199], v191 offset:19456
	ds_read_b128 v[200:203], v191 offset:20480
	ds_read_b128 v[204:207], v191 offset:21504
	ds_read_b128 v[208:211], v191 offset:22528
	ds_read_b128 v[212:215], v191 offset:23552
	global_load_lds_dwordx4 v[184:185], off
	s_add_i32 m0, s62, 0x2000
	s_add_u32 s62, s50, 0x40000
	v_lshl_add_u64 v[216:217], s[50:51], 0, v[158:159]
	s_addc_u32 s63, s51, 0
	s_add_i32 s64, s58, s68
	global_load_lds_dwordx4 v[216:217], off
	v_lshl_add_u64 v[218:219], s[62:63], 0, v[154:155]
	s_mov_b32 m0, s64
	v_lshl_add_u64 v[220:221], s[52:53], 0, v[156:157]
	global_load_lds_dwordx4 v[218:219], off
	v_lshl_add_u64 v[218:219], s[62:63], 0, v[158:159]
	s_add_i32 m0, s64, 0x2000
	s_nop 0
	global_load_lds_dwordx4 v[218:219], off
	v_lshl_add_u64 v[218:219], s[52:53], 0, v[152:153]
	s_mov_b32 m0, s74
	s_nop 0
	global_load_lds_dwordx4 v[218:219], off
	s_mov_b32 m0, s66
	s_nop 0
	global_load_lds_dwordx4 v[220:221], off
	s_waitcnt vmcnt(8)
	s_waitcnt lgkmcnt(0)
	s_barrier
	s_waitcnt lgkmcnt(0)
	v_mfma_f32_16x16x32_bf16 v[60:63], v[128:131], v[176:179], v[60:63]
	v_mfma_f32_16x16x32_bf16 v[56:59], v[136:139], v[176:179], v[56:59]
	v_mfma_f32_16x16x32_bf16 v[44:47], v[128:131], v[192:195], v[44:47]
	v_mfma_f32_16x16x32_bf16 v[40:43], v[136:139], v[192:195], v[40:43]
	v_mfma_f32_16x16x32_bf16 v[28:31], v[128:131], v[200:203], v[28:31]
	v_mfma_f32_16x16x32_bf16 v[24:27], v[136:139], v[200:203], v[24:27]
	v_mfma_f32_16x16x32_bf16 v[12:15], v[128:131], v[208:211], v[12:15]
	v_mfma_f32_16x16x32_bf16 v[8:11], v[136:139], v[208:211], v[8:11]
	v_mfma_f32_16x16x32_bf16 v[60:63], v[132:135], v[180:183], v[60:63]
	v_mfma_f32_16x16x32_bf16 v[56:59], v[140:143], v[180:183], v[56:59]
	v_mfma_f32_16x16x32_bf16 v[44:47], v[132:135], v[196:199], v[44:47]
	v_mfma_f32_16x16x32_bf16 v[40:43], v[140:143], v[196:199], v[40:43]
	v_mfma_f32_16x16x32_bf16 v[28:31], v[132:135], v[204:207], v[28:31]
	v_mfma_f32_16x16x32_bf16 v[24:27], v[140:143], v[204:207], v[24:27]
	v_mfma_f32_16x16x32_bf16 v[12:15], v[132:135], v[212:215], v[12:15]
	v_mfma_f32_16x16x32_bf16 v[8:11], v[140:143], v[212:215], v[8:11]
	v_mfma_f32_16x16x32_bf16 v[52:55], v[144:147], v[176:179], v[52:55]
	v_mfma_f32_16x16x32_bf16 v[48:51], v[168:171], v[176:179], v[48:51]
	v_mfma_f32_16x16x32_bf16 v[36:39], v[144:147], v[192:195], v[36:39]
	v_mfma_f32_16x16x32_bf16 v[32:35], v[168:171], v[192:195], v[32:35]
	v_mfma_f32_16x16x32_bf16 v[20:23], v[144:147], v[200:203], v[20:23]
	v_mfma_f32_16x16x32_bf16 v[16:19], v[168:171], v[200:203], v[16:19]
	v_mfma_f32_16x16x32_bf16 v[4:7], v[144:147], v[208:211], v[4:7]
	v_mfma_f32_16x16x32_bf16 v[0:3], v[168:171], v[208:211], v[0:3]
	v_mfma_f32_16x16x32_bf16 v[52:55], v[148:151], v[180:183], v[52:55]
	v_mfma_f32_16x16x32_bf16 v[48:51], v[172:175], v[180:183], v[48:51]
	v_mfma_f32_16x16x32_bf16 v[36:39], v[148:151], v[196:199], v[36:39]
	v_mfma_f32_16x16x32_bf16 v[32:35], v[172:175], v[196:199], v[32:35]
	v_mfma_f32_16x16x32_bf16 v[20:23], v[148:151], v[204:207], v[20:23]
	v_mfma_f32_16x16x32_bf16 v[16:19], v[172:175], v[204:207], v[16:19]
	v_mfma_f32_16x16x32_bf16 v[4:7], v[148:151], v[212:215], v[4:7]
	v_mfma_f32_16x16x32_bf16 v[0:3], v[172:175], v[212:215], v[0:3]
	s_barrier
; #define PG8_STAGE(bufoff, gbase, voff) do { _Pragma("unroll") for (int _i = 0; _i < 2; ++_i) \
;         __builtin_amdgcn_global_load_lds((const unsigned*)((const char*)(gbase) + (voff)[_i]), (PG8_LAS unsigned*)(lds + (bufoff) + ldsw + _i * 8192), 16, 0, 0); } while (0)
; #define PG8_LDA(dst, b, h) do { _Pragma("unroll") for (int m = 0; m < 4; ++m) _Pragma("unroll") for (int k = 0; k < 2; ++k) dst[m][k] = *(const PG8_LAS bf16x8*)(lds + PG8_SA(b, h) + aoff + m * 2048 + k * 1024); } while (0)
; #define PG8_LDB(dst, b, h) do { _Pragma("unroll") for (int n = 0; n < 2; ++n) _Pragma("unroll") for (int k = 0; k < 2; ++k) dst[n][k] = *(const PG8_LAS bf16x8*)(lds + PG8_SB(b, h) + boff + n * 2048 + k * 1024); } while (0)
; #define PG8_MMA(ai, bj, At, Bt) do { __builtin_amdgcn_s_setprio(1); _Pragma("unroll") for (int m = 0; m < 4; ++m) _Pragma("unroll") for (int n = 0; n < 2; ++n) _Pragma("unroll") for (int k = 0; k < 2; ++k) \
;         acc[ai][bj][m][n] = mma16<F16>(Bt[n][k], At[m][k], acc[ai][bj][m][n]); __builtin_amdgcn_s_setprio(0); } while (0)
; #define PG8_WAIT_V(n) asm volatile("s_waitcnt vmcnt(" #n ")" ::: "memory")
; #define PG8_WAIT_L(n) asm volatile("s_waitcnt lgkmcnt(" #n ")" ::: "memory")
; #define PG8_BAR __builtin_amdgcn_s_barrier()
; #define PG8_SCHED __builtin_amdgcn_sched_barrier(0)
; template <class Epi, class Sched, bool ALIGN_EPI = false, bool SP2 = false, bool F16 = false>
; __device__ __forceinline__ void gemm_phase(PG8_LAS unsigned char* lds, const Gemm g, const Sched& S, const Epi& E, const int wid_in) {
;     ...
;             PG8_LDB(B0, 1, 0); PG8_LDB(B1, 1, 1); PG8_SCHED; PG8_LDA(At, 1, 0); PG8_STAGE(PG8_SA(0, 1), a2 + hstep, voffA);
;             PG8_WAIT_V(8); PG8_WAIT_L(0); PG8_BAR; PG8_MMA(0, 0, At, B0); PG8_MMA(0, 1, At, B1); PG8_BAR; PG8_SCHED;
	s_add_i32 s62, 0, 0x18000
	s_add_i32 s63, 0, 0x1c000
	v_add_u32_e32 v140, s62, v188
	v_add_u32_e32 v172, s63, v188
	ds_read_b128 v[128:131], v140
	ds_read_b128 v[132:135], v140 offset:1024
	ds_read_b128 v[136:139], v140 offset:2048
	ds_read_b128 v[140:143], v140 offset:3072
	ds_read_b128 v[144:147], v172
	ds_read_b128 v[148:151], v172 offset:1024
	ds_read_b128 v[168:171], v172 offset:2048
	ds_read_b128 v[172:175], v172 offset:3072
	s_add_u32 s52, s52, 0x40000
	s_addc_u32 s53, s53, 0
	s_mov_b32 m0, s90
	v_lshl_add_u64 v[222:223], s[52:53], 0, v[152:153]
	ds_read_b128 v[176:179], v191 offset:32768
	ds_read_b128 v[180:183], v191 offset:33792
	ds_read_b128 v[192:195], v191 offset:34816
	ds_read_b128 v[196:199], v191 offset:35840
	ds_read_b128 v[200:203], v191 offset:36864
	ds_read_b128 v[204:207], v191 offset:37888
	ds_read_b128 v[208:211], v191 offset:38912
	ds_read_b128 v[212:215], v191 offset:39936
	global_load_lds_dwordx4 v[222:223], off
	v_lshl_add_u64 v[222:223], s[52:53], 0, v[156:157]
	s_mov_b32 m0, s41
	s_nop 0
	global_load_lds_dwordx4 v[222:223], off
	s_waitcnt vmcnt(8)
	s_waitcnt lgkmcnt(0)
	s_barrier
	s_waitcnt lgkmcnt(0)
	v_mfma_f32_16x16x32_bf16 v[124:127], v[128:131], v[176:179], v[124:127]
	v_mfma_f32_16x16x32_bf16 v[120:123], v[136:139], v[176:179], v[120:123]
	v_mfma_f32_16x16x32_bf16 v[108:111], v[128:131], v[192:195], v[108:111]
	v_mfma_f32_16x16x32_bf16 v[104:107], v[136:139], v[192:195], v[104:107]
	v_mfma_f32_16x16x32_bf16 v[92:95], v[128:131], v[200:203], v[92:95]
	v_mfma_f32_16x16x32_bf16 v[88:91], v[136:139], v[200:203], v[88:91]
	v_mfma_f32_16x16x32_bf16 v[76:79], v[128:131], v[208:211], v[76:79]
	v_mfma_f32_16x16x32_bf16 v[72:75], v[136:139], v[208:211], v[72:75]
	v_mfma_f32_16x16x32_bf16 v[124:127], v[132:135], v[180:183], v[124:127]
	v_mfma_f32_16x16x32_bf16 v[120:123], v[140:143], v[180:183], v[120:123]
	v_mfma_f32_16x16x32_bf16 v[108:111], v[132:135], v[196:199], v[108:111]
	v_mfma_f32_16x16x32_bf16 v[104:107], v[140:143], v[196:199], v[104:107]
	v_mfma_f32_16x16x32_bf16 v[92:95], v[132:135], v[204:207], v[92:95]
	v_mfma_f32_16x16x32_bf16 v[88:91], v[140:143], v[204:207], v[88:91]
	v_mfma_f32_16x16x32_bf16 v[76:79], v[132:135], v[212:215], v[76:79]
	v_mfma_f32_16x16x32_bf16 v[72:75], v[140:143], v[212:215], v[72:75]
	v_mfma_f32_16x16x32_bf16 v[116:119], v[144:147], v[176:179], v[116:119]
	v_mfma_f32_16x16x32_bf16 v[112:115], v[168:171], v[176:179], v[112:115]
	v_mfma_f32_16x16x32_bf16 v[100:103], v[144:147], v[192:195], v[100:103]
	v_mfma_f32_16x16x32_bf16 v[96:99], v[168:171], v[192:195], v[96:99]
	v_mfma_f32_16x16x32_bf16 v[84:87], v[144:147], v[200:203], v[84:87]
	v_mfma_f32_16x16x32_bf16 v[80:83], v[168:171], v[200:203], v[80:83]
	v_mfma_f32_16x16x32_bf16 v[68:71], v[144:147], v[208:211], v[68:71]
	v_mfma_f32_16x16x32_bf16 v[64:67], v[168:171], v[208:211], v[64:67]
	v_mfma_f32_16x16x32_bf16 v[116:119], v[148:151], v[180:183], v[116:119]
	v_mfma_f32_16x16x32_bf16 v[112:115], v[172:175], v[180:183], v[112:115]
	v_mfma_f32_16x16x32_bf16 v[100:103], v[148:151], v[196:199], v[100:103]
	v_mfma_f32_16x16x32_bf16 v[96:99], v[172:175], v[196:199], v[96:99]
	v_mfma_f32_16x16x32_bf16 v[84:87], v[148:151], v[204:207], v[84:87]
	v_mfma_f32_16x16x32_bf16 v[80:83], v[172:175], v[204:207], v[80:83]
	v_mfma_f32_16x16x32_bf16 v[68:71], v[148:151], v[212:215], v[68:71]
	v_mfma_f32_16x16x32_bf16 v[64:67], v[172:175], v[212:215], v[64:67]
	s_barrier
; #define PG8_STAGE(bufoff, gbase, voff) do { _Pragma("unroll") for (int _i = 0; _i < 2; ++_i) \
;         __builtin_amdgcn_global_load_lds((const unsigned*)((const char*)(gbase) + (voff)[_i]), (PG8_LAS unsigned*)(lds + (bufoff) + ldsw + _i * 8192), 16, 0, 0); } while (0)
; #define PG8_LDA(dst, b, h) do { _Pragma("unroll") for (int m = 0; m < 4; ++m) _Pragma("unroll") for (int k = 0; k < 2; ++k) dst[m][k] = *(const PG8_LAS bf16x8*)(lds + PG8_SA(b, h) + aoff + m * 2048 + k * 1024); } while (0)
; #define PG8_MMA(ai, bj, At, Bt) do { __builtin_amdgcn_s_setprio(1); _Pragma("unroll") for (int m = 0; m < 4; ++m) _Pragma("unroll") for (int n = 0; n < 2; ++n) _Pragma("unroll") for (int k = 0; k < 2; ++k) \
;         acc[ai][bj][m][n] = mma16<F16>(Bt[n][k], At[m][k], acc[ai][bj][m][n]); __builtin_amdgcn_s_setprio(0); } while (0)
; #define PG8_WAIT_V(n) asm volatile("s_waitcnt vmcnt(" #n ")" ::: "memory")
; #define PG8_WAIT_L(n) asm volatile("s_waitcnt lgkmcnt(" #n ")" ::: "memory")
; #define PG8_BAR __builtin_amdgcn_s_barrier()
; #define PG8_SCHED __builtin_amdgcn_sched_barrier(0)
; template <class Epi, class Sched, bool ALIGN_EPI = false, bool SP2 = false, bool F16 = false>
; __device__ __forceinline__ void gemm_phase(PG8_LAS unsigned char* lds, const Gemm g, const Sched& S, const Epi& E, const int wid_in) {
;     ...
;         for (int t = 0; t < nt; t += 2) {
;     ...
;             PG8_LDA(At, 1, 1); PG8_STAGE(PG8_SB(1, 0), b3, voffB); PG8_STAGE(PG8_SB(1, 1), b3 + hstep, voffB); PG8_STAGE(PG8_SA(1, 0), a3, voffA);
;             PG8_WAIT_V(8); PG8_WAIT_L(0); PG8_BAR; PG8_MMA(1, 0, At, B0); PG8_MMA(1, 1, At, B1); PG8_BAR; PG8_SCHED;
	s_add_i32 s52, s62, s68
	v_lshl_add_u64 v[184:185], v[184:185], 0, s[28:29]
	s_mov_b32 m0, s52
	ds_read_b128 v[176:179], v191 offset:49152
	ds_read_b128 v[180:183], v191 offset:50176
	ds_read_b128 v[192:195], v191 offset:51200
	ds_read_b128 v[196:199], v191 offset:52224
	ds_read_b128 v[200:203], v191 offset:53248
	ds_read_b128 v[204:207], v191 offset:54272
	ds_read_b128 v[208:211], v191 offset:55296
	ds_read_b128 v[212:215], v191 offset:56320
	global_load_lds_dwordx4 v[184:185], off
	s_add_i32 m0, s52, 0x2000
	s_add_u32 s50, s50, 0x40080
	v_lshl_add_u64 v[184:185], v[216:217], 0, s[28:29]
	s_addc_u32 s51, s51, 0
	s_add_i32 s52, s63, s68
	global_load_lds_dwordx4 v[184:185], off
	v_lshl_add_u64 v[184:185], s[50:51], 0, v[154:155]
	s_mov_b32 m0, s52
	s_nop 0
	global_load_lds_dwordx4 v[184:185], off
	v_lshl_add_u64 v[184:185], s[50:51], 0, v[158:159]
	s_add_i32 m0, s52, 0x2000
	s_nop 0
	global_load_lds_dwordx4 v[184:185], off
	v_lshl_add_u64 v[184:185], v[218:219], 0, s[28:29]
	s_mov_b32 m0, s75
	s_nop 0
	global_load_lds_dwordx4 v[184:185], off
	v_lshl_add_u64 v[184:185], v[220:221], 0, s[28:29]
	s_mov_b32 m0, s67
	s_nop 0
	global_load_lds_dwordx4 v[184:185], off
	s_waitcnt vmcnt(8)
	s_waitcnt lgkmcnt(0)
	s_barrier
	s_waitcnt lgkmcnt(0)
	v_mfma_f32_16x16x32_bf16 v[60:63], v[128:131], v[176:179], v[60:63]
	v_mfma_f32_16x16x32_bf16 v[56:59], v[136:139], v[176:179], v[56:59]
	v_mfma_f32_16x16x32_bf16 v[44:47], v[128:131], v[192:195], v[44:47]
	v_mfma_f32_16x16x32_bf16 v[40:43], v[136:139], v[192:195], v[40:43]
	v_mfma_f32_16x16x32_bf16 v[28:31], v[128:131], v[200:203], v[28:31]
	v_mfma_f32_16x16x32_bf16 v[24:27], v[136:139], v[200:203], v[24:27]
	v_mfma_f32_16x16x32_bf16 v[12:15], v[128:131], v[208:211], v[12:15]
	v_mfma_f32_16x16x32_bf16 v[8:11], v[136:139], v[208:211], v[8:11]
	v_mfma_f32_16x16x32_bf16 v[60:63], v[132:135], v[180:183], v[60:63]
	v_mfma_f32_16x16x32_bf16 v[56:59], v[140:143], v[180:183], v[56:59]
	v_mfma_f32_16x16x32_bf16 v[44:47], v[132:135], v[196:199], v[44:47]
	v_mfma_f32_16x16x32_bf16 v[40:43], v[140:143], v[196:199], v[40:43]
	v_mfma_f32_16x16x32_bf16 v[28:31], v[132:135], v[204:207], v[28:31]
	v_mfma_f32_16x16x32_bf16 v[24:27], v[140:143], v[204:207], v[24:27]
	v_mfma_f32_16x16x32_bf16 v[12:15], v[132:135], v[212:215], v[12:15]
	v_mfma_f32_16x16x32_bf16 v[8:11], v[140:143], v[212:215], v[8:11]
	v_mfma_f32_16x16x32_bf16 v[52:55], v[144:147], v[176:179], v[52:55]
	v_mfma_f32_16x16x32_bf16 v[48:51], v[168:171], v[176:179], v[48:51]
	v_mfma_f32_16x16x32_bf16 v[36:39], v[144:147], v[192:195], v[36:39]
	v_mfma_f32_16x16x32_bf16 v[32:35], v[168:171], v[192:195], v[32:35]
	v_mfma_f32_16x16x32_bf16 v[20:23], v[144:147], v[200:203], v[20:23]
	v_mfma_f32_16x16x32_bf16 v[16:19], v[168:171], v[200:203], v[16:19]
	v_mfma_f32_16x16x32_bf16 v[4:7], v[144:147], v[208:211], v[4:7]
	v_mfma_f32_16x16x32_bf16 v[0:3], v[168:171], v[208:211], v[0:3]
	v_mfma_f32_16x16x32_bf16 v[52:55], v[148:151], v[180:183], v[52:55]
	v_mfma_f32_16x16x32_bf16 v[48:51], v[172:175], v[180:183], v[48:51]
	v_mfma_f32_16x16x32_bf16 v[36:39], v[148:151], v[196:199], v[36:39]
	v_mfma_f32_16x16x32_bf16 v[32:35], v[172:175], v[196:199], v[32:35]
	v_mfma_f32_16x16x32_bf16 v[20:23], v[148:151], v[204:207], v[20:23]
	v_mfma_f32_16x16x32_bf16 v[16:19], v[172:175], v[204:207], v[16:19]
	v_mfma_f32_16x16x32_bf16 v[4:7], v[148:151], v[212:215], v[4:7]
	v_mfma_f32_16x16x32_bf16 v[0:3], v[172:175], v[212:215], v[0:3]
	s_barrier
	s_add_i32 s61, s61, 2
	s_add_u32 s48, s48, 0x100
	s_addc_u32 s49, s49, 0
	s_add_u32 s47, s47, 0x100
	s_addc_u32 s60, s60, 0
	s_cmp_gt_u32 s61, 13
	s_cbranch_scc0 .LBB0_1832
	s_setprio 0
	s_and_b64 vcc, exec, s[16:17]
	s_cbranch_vccz .LBB0_1835
	s_barrier

; #define PG8_STAGE(bufoff, gbase, voff) do { _Pragma("unroll") for (int _i = 0; _i < 2; ++_i) \
;         __builtin_amdgcn_global_load_lds((const unsigned*)((const char*)(gbase) + (voff)[_i]), (PG8_LAS unsigned*)(lds + (bufoff) + ldsw + _i * 8192), 16, 0, 0); } while (0)
; #define PG8_LDA(dst, b, h) do { _Pragma("unroll") for (int m = 0; m < 4; ++m) _Pragma("unroll") for (int k = 0; k < 2; ++k) dst[m][k] = *(const PG8_LAS bf16x8*)(lds + PG8_SA(b, h) + aoff + m * 2048 + k * 1024); } while (0)
; #define PG8_LDB(dst, b, h) do { _Pragma("unroll") for (int n = 0; n < 2; ++n) _Pragma("unroll") for (int k = 0; k < 2; ++k) dst[n][k] = *(const PG8_LAS bf16x8*)(lds + PG8_SB(b, h) + boff + n * 2048 + k * 1024); } while (0)
; #define PG8_WAIT_V(n) asm volatile("s_waitcnt vmcnt(" #n ")" ::: "memory")
; #define PG8_WAIT_L(n) asm volatile("s_waitcnt lgkmcnt(" #n ")" ::: "memory")
; #define PG8_BAR __builtin_amdgcn_s_barrier()
; template <class Epi, class Sched, bool ALIGN_EPI = false, bool SP2 = false, bool F16 = false>
; __device__ __forceinline__ void gemm_phase(PG8_LAS unsigned char* lds, const Gemm g, const Sched& S, const Epi& E, const int wid_in) {
;     ...
;         const bool has_next = S.next(ui + 1, nxt);
;         const char* nA = has_next ? (const char*)g.A + (size_t)nxt.pm * tstep : cA; const char* nB = has_next ? (const char*)g.Bt + (size_t)nxt.pn * tstep : cB;
;         for (int t = 0; t < nt; t += 2) {
;             const bool last = (t == nt - 2);
;             const char* a1 = cA + (size_t)(t + 1) * kstep;
;             const char* a2 = last ? nA : cA + (size_t)(t + 2) * kstep; const char* b2 = last ? nB : cB + (size_t)(t + 2) * kstep;
;             const char* a3 = a2 + kstep; const char* b3 = b2 + kstep;
;             if (last && has_next) S.a_ready(nxt);
;             if constexpr (SP2) {
;             PG8_LDB(B0, 0, 0); PG8_LDB(B1, 0, 1); PG8_SCHED; PG8_LDA(At, 0, 0); PG8_STAGE(PG8_SA(1, 1), a1 + hstep, voffA);
;             PG8_WAIT_V(8); PG8_WAIT_L(0); PG8_BAR; PG8_MMA(0, 0, At, B0); PG8_MMA(0, 1, At, B1); PG8_BAR; PG8_SCHED;
;     ...
; #pragma unroll
;         for (int a = 0; a < 2; ++a)
; #pragma unroll
;             for (int b = 0; b < 2; ++b)
; #pragma unroll
;                 for (int m = 0; m < 4; ++m)
; #pragma unroll
;                     for (int n = 0; n < 2; ++n) acc[a][b][m][n] = (f32x4){0.f, 0.f, 0.f, 0.f};
;         cur = nxt; cA = nA; cB = nB; ++ui;
.LBB0_1908:
	s_ashr_i32 s29, s28, 31
	s_lshl_b64 s[30:31], s[28:29], 19
	s_add_u32 s30, s21, s30
	s_addc_u32 s31, s40, s31
	s_and_b64 s[34:35], s[10:11], exec
	s_cselect_b32 s29, s31, s47
	s_cselect_b32 s42, s30, s46
	s_ashr_i32 s27, s26, 31
	s_lshl_b64 s[34:35], s[26:27], 19
	s_add_u32 s34, s41, s34
	s_addc_u32 s35, s52, s35
	s_and_b64 s[50:51], s[10:11], exec
	s_cselect_b32 s27, s35, s49
	s_cselect_b32 s43, s34, s48
	s_add_u32 s46, s46, 0x40080
	s_addc_u32 s47, s47, 0
	s_add_u32 s45, s48, 0x100
	v_mov_b32_e32 v8, 0
	s_addc_u32 s63, s49, 0
	s_mov_b32 s64, -2
	v_mov_b32_e32 v9, v8
	v_mov_b32_e32 v10, v8
	v_mov_b32_e32 v11, v8
	v_mov_b32_e32 v12, v8
	v_mov_b32_e32 v13, v8
	v_mov_b32_e32 v14, v8
	v_mov_b32_e32 v15, v8
	v_mov_b32_e32 v24, v8
	v_mov_b32_e32 v25, v8
	v_mov_b32_e32 v26, v8
	v_mov_b32_e32 v27, v8
	v_mov_b32_e32 v28, v8
	v_mov_b32_e32 v29, v8
	v_mov_b32_e32 v30, v8
	v_mov_b32_e32 v31, v8
	v_mov_b32_e32 v40, v8
	v_mov_b32_e32 v41, v8
	v_mov_b32_e32 v42, v8
	v_mov_b32_e32 v43, v8
	v_mov_b32_e32 v44, v8
	v_mov_b32_e32 v45, v8
	v_mov_b32_e32 v46, v8
	v_mov_b32_e32 v47, v8
	v_mov_b32_e32 v56, v8
	v_mov_b32_e32 v57, v8
	v_mov_b32_e32 v58, v8
	v_mov_b32_e32 v59, v8
	v_mov_b32_e32 v60, v8
	v_mov_b32_e32 v61, v8
	v_mov_b32_e32 v62, v8
	v_mov_b32_e32 v63, v8
	v_mov_b32_e32 v16, v8
	v_mov_b32_e32 v17, v8
	v_mov_b32_e32 v18, v8
	v_mov_b32_e32 v19, v8
	v_mov_b32_e32 v20, v8
	v_mov_b32_e32 v21, v8
	v_mov_b32_e32 v22, v8
	v_mov_b32_e32 v23, v8
	v_mov_b32_e32 v32, v8
	v_mov_b32_e32 v33, v8
	v_mov_b32_e32 v34, v8
	v_mov_b32_e32 v35, v8
	v_mov_b32_e32 v36, v8
	v_mov_b32_e32 v37, v8
	v_mov_b32_e32 v38, v8
	v_mov_b32_e32 v39, v8
	v_mov_b32_e32 v48, v8
	v_mov_b32_e32 v49, v8
	v_mov_b32_e32 v50, v8
	v_mov_b32_e32 v51, v8
	v_mov_b32_e32 v52, v8
	v_mov_b32_e32 v53, v8
	v_mov_b32_e32 v54, v8
	v_mov_b32_e32 v55, v8
	v_mov_b32_e32 v64, v8
	v_mov_b32_e32 v65, v8
	v_mov_b32_e32 v66, v8
	v_mov_b32_e32 v67, v8
	v_mov_b32_e32 v68, v8
	v_mov_b32_e32 v69, v8
	v_mov_b32_e32 v70, v8
	v_mov_b32_e32 v71, v8
	v_mov_b32_e32 v72, v8
	v_mov_b32_e32 v73, v8
	v_mov_b32_e32 v74, v8
	v_mov_b32_e32 v75, v8
	v_mov_b32_e32 v76, v8
	v_mov_b32_e32 v77, v8
	v_mov_b32_e32 v78, v8
	v_mov_b32_e32 v79, v8
	v_mov_b32_e32 v88, v8
	v_mov_b32_e32 v89, v8
	v_mov_b32_e32 v90, v8
	v_mov_b32_e32 v91, v8
	v_mov_b32_e32 v92, v8
	v_mov_b32_e32 v93, v8
	v_mov_b32_e32 v94, v8
	v_mov_b32_e32 v95, v8
	v_mov_b32_e32 v104, v8
	v_mov_b32_e32 v105, v8
	v_mov_b32_e32 v106, v8
	v_mov_b32_e32 v107, v8
	v_mov_b32_e32 v108, v8
	v_mov_b32_e32 v109, v8
	v_mov_b32_e32 v110, v8
	v_mov_b32_e32 v111, v8
	v_mov_b32_e32 v120, v8
	v_mov_b32_e32 v121, v8
	v_mov_b32_e32 v122, v8
	v_mov_b32_e32 v123, v8
	v_mov_b32_e32 v124, v8
	v_mov_b32_e32 v125, v8
	v_mov_b32_e32 v126, v8
	v_mov_b32_e32 v127, v8
	v_mov_b32_e32 v80, v8
	v_mov_b32_e32 v81, v8
	v_mov_b32_e32 v82, v8
	v_mov_b32_e32 v83, v8
	v_mov_b32_e32 v84, v8
	v_mov_b32_e32 v85, v8
	v_mov_b32_e32 v86, v8
	v_mov_b32_e32 v87, v8
	v_mov_b32_e32 v96, v8
	v_mov_b32_e32 v97, v8
	v_mov_b32_e32 v98, v8
	v_mov_b32_e32 v99, v8
	v_mov_b32_e32 v100, v8
	v_mov_b32_e32 v101, v8
	v_mov_b32_e32 v102, v8
	v_mov_b32_e32 v103, v8
	v_mov_b32_e32 v112, v8
	v_mov_b32_e32 v113, v8
	v_mov_b32_e32 v114, v8
	v_mov_b32_e32 v115, v8
	v_mov_b32_e32 v116, v8
	v_mov_b32_e32 v117, v8
	v_mov_b32_e32 v118, v8
	v_mov_b32_e32 v119, v8
	v_mov_b32_e32 v128, v8
	v_mov_b32_e32 v129, v8
	v_mov_b32_e32 v130, v8
	v_mov_b32_e32 v131, v8
	v_mov_b32_e32 v132, v8
	v_mov_b32_e32 v133, v8
	v_mov_b32_e32 v134, v8
	v_mov_b32_e32 v135, v8
	s_cmp_ge_u32 s3, 4
	s_cbranch_scc0 .Lgsp_14
	s_setprio 1
.Lgsp_14:
.LBB0_1909:
	ds_read_b128 v[0:3], v193
	ds_read_b128 v[4:7], v193 offset:1024
	ds_read_b128 v[136:139], v193 offset:2048
	ds_read_b128 v[140:143], v193 offset:3072
	ds_read_b128 v[144:147], v194
	ds_read_b128 v[148:151], v194 offset:1024
	ds_read_b128 v[152:155], v194 offset:2048
	ds_read_b128 v[156:159], v194 offset:3072
	s_add_u32 s48, s46, 0xfffc0080
	s_addc_u32 s49, s47, -1
	s_cmp_eq_u32 s64, 12
	s_cselect_b32 s51, s29, s49
	s_cselect_b32 s50, s42, s48
	s_cselect_b32 s49, s27, s63
	s_cselect_b32 s48, s43, s45
	s_mov_b32 m0, s91
	v_lshl_add_u64 v[188:189], s[46:47], 0, v[168:169]
	ds_read_b128 v[176:179], v195
	ds_read_b128 v[180:183], v195 offset:1024
	ds_read_b128 v[184:187], v195 offset:2048
	ds_read_b128 v[198:201], v195 offset:3072
	ds_read_b128 v[202:205], v195 offset:4096
	ds_read_b128 v[206:209], v195 offset:5120
	ds_read_b128 v[210:213], v195 offset:6144
	ds_read_b128 v[214:217], v195 offset:7168
	global_load_lds_dwordx4 v[188:189], off
	v_lshl_add_u64 v[188:189], s[46:47], 0, v[170:171]
	s_add_i32 m0, s74, 0xe000
	s_nop 0
	global_load_lds_dwordx4 v[188:189], off
	s_waitcnt vmcnt(8)
	s_waitcnt lgkmcnt(0)
	s_barrier
; #define PG8_STAGE(bufoff, gbase, voff) do { _Pragma("unroll") for (int _i = 0; _i < 2; ++_i) \
;         __builtin_amdgcn_global_load_lds((const unsigned*)((const char*)(gbase) + (voff)[_i]), (PG8_LAS unsigned*)(lds + (bufoff) + ldsw + _i * 8192), 16, 0, 0); } while (0)
; #define PG8_LDA(dst, b, h) do { _Pragma("unroll") for (int m = 0; m < 4; ++m) _Pragma("unroll") for (int k = 0; k < 2; ++k) dst[m][k] = *(const PG8_LAS bf16x8*)(lds + PG8_SA(b, h) + aoff + m * 2048 + k * 1024); } while (0)
; #define PG8_MMA(ai, bj, At, Bt) do { __builtin_amdgcn_s_setprio(1); _Pragma("unroll") for (int m = 0; m < 4; ++m) _Pragma("unroll") for (int n = 0; n < 2; ++n) _Pragma("unroll") for (int k = 0; k < 2; ++k) \
;         acc[ai][bj][m][n] = mma16<F16>(Bt[n][k], At[m][k], acc[ai][bj][m][n]); __builtin_amdgcn_s_setprio(0); } while (0)
; #define PG8_WAIT_V(n) asm volatile("s_waitcnt vmcnt(" #n ")" ::: "memory")
; #define PG8_WAIT_L(n) asm volatile("s_waitcnt lgkmcnt(" #n ")" ::: "memory")
; #define PG8_BAR __builtin_amdgcn_s_barrier()
; #define PG8_SCHED __builtin_amdgcn_sched_barrier(0)
; template <class Epi, class Sched, bool ALIGN_EPI = false, bool SP2 = false, bool F16 = false>
; __device__ __forceinline__ void gemm_phase(PG8_LAS unsigned char* lds, const Gemm g, const Sched& S, const Epi& E, const int wid_in) {
;     ...
;             PG8_WAIT_V(8); PG8_WAIT_L(0); PG8_BAR; PG8_MMA(0, 0, At, B0); PG8_MMA(0, 1, At, B1); PG8_BAR; PG8_SCHED;
;             PG8_LDA(At, 0, 1); PG8_STAGE(PG8_SB(0, 0), b2, voffB); PG8_STAGE(PG8_SB(0, 1), b2 + hstep, voffB); PG8_STAGE(PG8_SA(0, 0), a2, voffA);
;             PG8_WAIT_V(8); PG8_WAIT_L(0); PG8_BAR; PG8_MMA(1, 0, At, B0); PG8_MMA(1, 1, At, B1); PG8_BAR; PG8_SCHED;
	s_waitcnt lgkmcnt(0)
	v_mfma_f32_16x16x32_f16 v[132:135], v[0:3], v[176:179], v[132:135]
	v_mfma_f32_16x16x32_f16 v[128:131], v[136:139], v[176:179], v[128:131]
	v_mfma_f32_16x16x32_f16 v[116:119], v[0:3], v[184:187], v[116:119]
	v_mfma_f32_16x16x32_f16 v[112:115], v[136:139], v[184:187], v[112:115]
	v_mfma_f32_16x16x32_f16 v[100:103], v[0:3], v[202:205], v[100:103]
	v_mfma_f32_16x16x32_f16 v[96:99], v[136:139], v[202:205], v[96:99]
	v_mfma_f32_16x16x32_f16 v[84:87], v[0:3], v[210:213], v[84:87]
	v_mfma_f32_16x16x32_f16 v[80:83], v[136:139], v[210:213], v[80:83]
	v_mfma_f32_16x16x32_f16 v[132:135], v[4:7], v[180:183], v[132:135]
	v_mfma_f32_16x16x32_f16 v[128:131], v[140:143], v[180:183], v[128:131]
	v_mfma_f32_16x16x32_f16 v[116:119], v[4:7], v[198:201], v[116:119]
	v_mfma_f32_16x16x32_f16 v[112:115], v[140:143], v[198:201], v[112:115]
	v_mfma_f32_16x16x32_f16 v[100:103], v[4:7], v[206:209], v[100:103]
	v_mfma_f32_16x16x32_f16 v[96:99], v[140:143], v[206:209], v[96:99]
	v_mfma_f32_16x16x32_f16 v[84:87], v[4:7], v[214:217], v[84:87]
	v_mfma_f32_16x16x32_f16 v[80:83], v[140:143], v[214:217], v[80:83]
	v_mfma_f32_16x16x32_f16 v[124:127], v[144:147], v[176:179], v[124:127]
	v_mfma_f32_16x16x32_f16 v[120:123], v[152:155], v[176:179], v[120:123]
	v_mfma_f32_16x16x32_f16 v[108:111], v[144:147], v[184:187], v[108:111]
	v_mfma_f32_16x16x32_f16 v[104:107], v[152:155], v[184:187], v[104:107]
	v_mfma_f32_16x16x32_f16 v[92:95], v[144:147], v[202:205], v[92:95]
	v_mfma_f32_16x16x32_f16 v[88:91], v[152:155], v[202:205], v[88:91]
	v_mfma_f32_16x16x32_f16 v[76:79], v[144:147], v[210:213], v[76:79]
	v_mfma_f32_16x16x32_f16 v[72:75], v[152:155], v[210:213], v[72:75]
	v_mfma_f32_16x16x32_f16 v[124:127], v[148:151], v[180:183], v[124:127]
	v_mfma_f32_16x16x32_f16 v[120:123], v[156:159], v[180:183], v[120:123]
	v_mfma_f32_16x16x32_f16 v[108:111], v[148:151], v[198:201], v[108:111]
	v_mfma_f32_16x16x32_f16 v[104:107], v[156:159], v[198:201], v[104:107]
	v_mfma_f32_16x16x32_f16 v[92:95], v[148:151], v[206:209], v[92:95]
	v_mfma_f32_16x16x32_f16 v[88:91], v[156:159], v[206:209], v[88:91]
	v_mfma_f32_16x16x32_f16 v[76:79], v[148:151], v[214:217], v[76:79]
	v_mfma_f32_16x16x32_f16 v[72:75], v[156:159], v[214:217], v[72:75]
	s_barrier
	s_add_i32 s65, s60, s68
	v_lshl_add_u64 v[188:189], s[48:49], 0, v[162:163]
	s_mov_b32 m0, s65
	ds_read_b128 v[176:179], v195 offset:16384
	ds_read_b128 v[180:183], v195 offset:17408
	ds_read_b128 v[184:187], v195 offset:18432
	ds_read_b128 v[198:201], v195 offset:19456
	ds_read_b128 v[202:205], v195 offset:20480
	ds_read_b128 v[206:209], v195 offset:21504
	ds_read_b128 v[210:213], v195 offset:22528
	ds_read_b128 v[214:217], v195 offset:23552
	global_load_lds_dwordx4 v[188:189], off
	s_add_i32 m0, s65, 0x2000
	s_add_u32 s84, s48, 0x40000
	v_lshl_add_u64 v[218:219], s[48:49], 0, v[166:167]
	s_addc_u32 s85, s49, 0
	s_add_i32 s65, s61, s68
	global_load_lds_dwordx4 v[218:219], off
	v_lshl_add_u64 v[220:221], s[84:85], 0, v[162:163]
	s_mov_b32 m0, s65
	v_lshl_add_u64 v[222:223], s[50:51], 0, v[164:165]
	global_load_lds_dwordx4 v[220:221], off
	v_lshl_add_u64 v[220:221], s[84:85], 0, v[166:167]
	s_add_i32 m0, s65, 0x2000
	s_nop 0
	global_load_lds_dwordx4 v[220:221], off
	v_lshl_add_u64 v[220:221], s[50:51], 0, v[160:161]
	s_mov_b32 m0, s74
	s_nop 0
	global_load_lds_dwordx4 v[220:221], off
	s_mov_b32 m0, s66
	s_nop 0
	global_load_lds_dwordx4 v[222:223], off
	s_waitcnt vmcnt(8)
	s_waitcnt lgkmcnt(0)
	s_barrier
	s_waitcnt lgkmcnt(0)
	v_mfma_f32_16x16x32_f16 v[68:71], v[0:3], v[176:179], v[68:71]
	v_mfma_f32_16x16x32_f16 v[64:67], v[136:139], v[176:179], v[64:67]
	v_mfma_f32_16x16x32_f16 v[52:55], v[0:3], v[184:187], v[52:55]
	v_mfma_f32_16x16x32_f16 v[48:51], v[136:139], v[184:187], v[48:51]
	v_mfma_f32_16x16x32_f16 v[36:39], v[0:3], v[202:205], v[36:39]
	v_mfma_f32_16x16x32_f16 v[32:35], v[136:139], v[202:205], v[32:35]
	v_mfma_f32_16x16x32_f16 v[0:3], v[0:3], v[210:213], v[20:23]
	v_mfma_f32_16x16x32_f16 v[68:71], v[4:7], v[180:183], v[68:71]
	v_mfma_f32_16x16x32_f16 v[64:67], v[140:143], v[180:183], v[64:67]
	v_mfma_f32_16x16x32_f16 v[52:55], v[4:7], v[198:201], v[52:55]
	v_mfma_f32_16x16x32_f16 v[48:51], v[140:143], v[198:201], v[48:51]
	v_mfma_f32_16x16x32_f16 v[36:39], v[4:7], v[206:209], v[36:39]
	v_mfma_f32_16x16x32_f16 v[32:35], v[140:143], v[206:209], v[32:35]
	v_mfma_f32_16x16x32_f16 v[0:3], v[4:7], v[214:217], v[0:3]
	v_mfma_f32_16x16x32_f16 v[4:7], v[136:139], v[210:213], v[16:19]
	v_mfma_f32_16x16x32_f16 v[4:7], v[140:143], v[214:217], v[4:7]
	v_mfma_f32_16x16x32_f16 v[16:19], v[144:147], v[176:179], v[60:63]
	v_mfma_f32_16x16x32_f16 v[60:63], v[148:151], v[180:183], v[16:19]
	v_mfma_f32_16x16x32_f16 v[16:19], v[152:155], v[176:179], v[56:59]
	v_mfma_f32_16x16x32_f16 v[56:59], v[156:159], v[180:183], v[16:19]
	v_mfma_f32_16x16x32_f16 v[16:19], v[144:147], v[184:187], v[44:47]
	v_mfma_f32_16x16x32_f16 v[44:47], v[148:151], v[198:201], v[16:19]
	v_mfma_f32_16x16x32_f16 v[16:19], v[152:155], v[184:187], v[40:43]
	v_mfma_f32_16x16x32_f16 v[40:43], v[156:159], v[198:201], v[16:19]
	v_mfma_f32_16x16x32_f16 v[16:19], v[144:147], v[202:205], v[28:31]
	v_mfma_f32_16x16x32_f16 v[28:31], v[148:151], v[206:209], v[16:19]
	v_mfma_f32_16x16x32_f16 v[16:19], v[152:155], v[202:205], v[24:27]
	v_mfma_f32_16x16x32_f16 v[12:15], v[144:147], v[210:213], v[12:15]
	v_mfma_f32_16x16x32_f16 v[8:11], v[152:155], v[210:213], v[8:11]
	v_mfma_f32_16x16x32_f16 v[24:27], v[156:159], v[206:209], v[16:19]
	v_mfma_f32_16x16x32_f16 v[12:15], v[148:151], v[214:217], v[12:15]
	v_mfma_f32_16x16x32_f16 v[8:11], v[156:159], v[214:217], v[8:11]
	s_barrier
; #define PG8_STAGE(bufoff, gbase, voff) do { _Pragma("unroll") for (int _i = 0; _i < 2; ++_i) \
;         __builtin_amdgcn_global_load_lds((const unsigned*)((const char*)(gbase) + (voff)[_i]), (PG8_LAS unsigned*)(lds + (bufoff) + ldsw + _i * 8192), 16, 0, 0); } while (0)
; #define PG8_LDA(dst, b, h) do { _Pragma("unroll") for (int m = 0; m < 4; ++m) _Pragma("unroll") for (int k = 0; k < 2; ++k) dst[m][k] = *(const PG8_LAS bf16x8*)(lds + PG8_SA(b, h) + aoff + m * 2048 + k * 1024); } while (0)
; #define PG8_LDB(dst, b, h) do { _Pragma("unroll") for (int n = 0; n < 2; ++n) _Pragma("unroll") for (int k = 0; k < 2; ++k) dst[n][k] = *(const PG8_LAS bf16x8*)(lds + PG8_SB(b, h) + boff + n * 2048 + k * 1024); } while (0)
; #define PG8_MMA(ai, bj, At, Bt) do { __builtin_amdgcn_s_setprio(1); _Pragma("unroll") for (int m = 0; m < 4; ++m) _Pragma("unroll") for (int n = 0; n < 2; ++n) _Pragma("unroll") for (int k = 0; k < 2; ++k) \
;         acc[ai][bj][m][n] = mma16<F16>(Bt[n][k], At[m][k], acc[ai][bj][m][n]); __builtin_amdgcn_s_setprio(0); } while (0)
; #define PG8_WAIT_V(n) asm volatile("s_waitcnt vmcnt(" #n ")" ::: "memory")
; #define PG8_WAIT_L(n) asm volatile("s_waitcnt lgkmcnt(" #n ")" ::: "memory")
; #define PG8_BAR __builtin_amdgcn_s_barrier()
; #define PG8_SCHED __builtin_amdgcn_sched_barrier(0)
; template <class Epi, class Sched, bool ALIGN_EPI = false, bool SP2 = false, bool F16 = false>
; __device__ __forceinline__ void gemm_phase(PG8_LAS unsigned char* lds, const Gemm g, const Sched& S, const Epi& E, const int wid_in) {
;     ...
;             PG8_LDB(B0, 1, 0); PG8_LDB(B1, 1, 1); PG8_SCHED; PG8_LDA(At, 1, 0); PG8_STAGE(PG8_SA(0, 1), a2 + hstep, voffA);
;             PG8_WAIT_V(8); PG8_WAIT_L(0); PG8_BAR; PG8_MMA(0, 0, At, B0); PG8_MMA(0, 1, At, B1); PG8_BAR; PG8_SCHED;
;             PG8_LDA(At, 1, 1); PG8_STAGE(PG8_SB(1, 0), b3, voffB); PG8_STAGE(PG8_SB(1, 1), b3 + hstep, voffB); PG8_STAGE(PG8_SA(1, 0), a3, voffA);
;             PG8_WAIT_V(8); PG8_WAIT_L(0); PG8_BAR; PG8_MMA(1, 0, At, B0); PG8_MMA(1, 1, At, B1); PG8_BAR; PG8_SCHED;
	s_add_i32 s65, 0, 0x18000
	s_add_i32 s76, 0, 0x1c000
	v_add_u32_e32 v140, s65, v192
	v_add_u32_e32 v156, s76, v192
	ds_read_b128 v[16:19], v140
	ds_read_b128 v[20:23], v140 offset:1024
	ds_read_b128 v[136:139], v140 offset:2048
	ds_read_b128 v[140:143], v140 offset:3072
	ds_read_b128 v[144:147], v156
	ds_read_b128 v[148:151], v156 offset:1024
	ds_read_b128 v[152:155], v156 offset:2048
	ds_read_b128 v[156:159], v156 offset:3072
	s_add_u32 s50, s50, 0x40000
	s_addc_u32 s51, s51, 0
	s_mov_b32 m0, s90
	v_lshl_add_u64 v[224:225], s[50:51], 0, v[160:161]
	ds_read_b128 v[176:179], v195 offset:32768
	ds_read_b128 v[180:183], v195 offset:33792
	ds_read_b128 v[184:187], v195 offset:34816
	ds_read_b128 v[198:201], v195 offset:35840
	ds_read_b128 v[202:205], v195 offset:36864
	ds_read_b128 v[206:209], v195 offset:37888
	ds_read_b128 v[210:213], v195 offset:38912
	ds_read_b128 v[214:217], v195 offset:39936
	global_load_lds_dwordx4 v[224:225], off
	v_lshl_add_u64 v[224:225], s[50:51], 0, v[164:165]
	s_mov_b32 m0, s37
	s_nop 0
	global_load_lds_dwordx4 v[224:225], off
	s_waitcnt vmcnt(8)
	s_waitcnt lgkmcnt(0)
	s_barrier
	s_waitcnt lgkmcnt(0)
	v_mfma_f32_16x16x32_f16 v[132:135], v[16:19], v[176:179], v[132:135]
	v_mfma_f32_16x16x32_f16 v[128:131], v[136:139], v[176:179], v[128:131]
	v_mfma_f32_16x16x32_f16 v[116:119], v[16:19], v[184:187], v[116:119]
	v_mfma_f32_16x16x32_f16 v[112:115], v[136:139], v[184:187], v[112:115]
	v_mfma_f32_16x16x32_f16 v[100:103], v[16:19], v[202:205], v[100:103]
	v_mfma_f32_16x16x32_f16 v[96:99], v[136:139], v[202:205], v[96:99]
	v_mfma_f32_16x16x32_f16 v[84:87], v[16:19], v[210:213], v[84:87]
	v_mfma_f32_16x16x32_f16 v[80:83], v[136:139], v[210:213], v[80:83]
	v_mfma_f32_16x16x32_f16 v[132:135], v[20:23], v[180:183], v[132:135]
	v_mfma_f32_16x16x32_f16 v[128:131], v[140:143], v[180:183], v[128:131]
	v_mfma_f32_16x16x32_f16 v[116:119], v[20:23], v[198:201], v[116:119]
	v_mfma_f32_16x16x32_f16 v[112:115], v[140:143], v[198:201], v[112:115]
	v_mfma_f32_16x16x32_f16 v[100:103], v[20:23], v[206:209], v[100:103]
	v_mfma_f32_16x16x32_f16 v[96:99], v[140:143], v[206:209], v[96:99]
	v_mfma_f32_16x16x32_f16 v[84:87], v[20:23], v[214:217], v[84:87]
	v_mfma_f32_16x16x32_f16 v[80:83], v[140:143], v[214:217], v[80:83]
	v_mfma_f32_16x16x32_f16 v[124:127], v[144:147], v[176:179], v[124:127]
	v_mfma_f32_16x16x32_f16 v[120:123], v[152:155], v[176:179], v[120:123]
	v_mfma_f32_16x16x32_f16 v[108:111], v[144:147], v[184:187], v[108:111]
	v_mfma_f32_16x16x32_f16 v[104:107], v[152:155], v[184:187], v[104:107]
	v_mfma_f32_16x16x32_f16 v[92:95], v[144:147], v[202:205], v[92:95]
	v_mfma_f32_16x16x32_f16 v[88:91], v[152:155], v[202:205], v[88:91]
	v_mfma_f32_16x16x32_f16 v[76:79], v[144:147], v[210:213], v[76:79]
	v_mfma_f32_16x16x32_f16 v[72:75], v[152:155], v[210:213], v[72:75]
	v_mfma_f32_16x16x32_f16 v[124:127], v[148:151], v[180:183], v[124:127]
	v_mfma_f32_16x16x32_f16 v[120:123], v[156:159], v[180:183], v[120:123]
	v_mfma_f32_16x16x32_f16 v[108:111], v[148:151], v[198:201], v[108:111]
	v_mfma_f32_16x16x32_f16 v[104:107], v[156:159], v[198:201], v[104:107]
	v_mfma_f32_16x16x32_f16 v[92:95], v[148:151], v[206:209], v[92:95]
	v_mfma_f32_16x16x32_f16 v[88:91], v[156:159], v[206:209], v[88:91]
	v_mfma_f32_16x16x32_f16 v[76:79], v[148:151], v[214:217], v[76:79]
	v_mfma_f32_16x16x32_f16 v[72:75], v[156:159], v[214:217], v[72:75]
	s_barrier
	s_add_i32 s50, s65, s68
	v_lshl_add_u64 v[188:189], v[188:189], 0, s[24:25]
	s_mov_b32 m0, s50
	ds_read_b128 v[176:179], v195 offset:49152
	ds_read_b128 v[180:183], v195 offset:50176
	ds_read_b128 v[184:187], v195 offset:51200
	ds_read_b128 v[198:201], v195 offset:52224
	ds_read_b128 v[202:205], v195 offset:53248
	ds_read_b128 v[206:209], v195 offset:54272
	ds_read_b128 v[210:213], v195 offset:55296
	ds_read_b128 v[214:217], v195 offset:56320
	global_load_lds_dwordx4 v[188:189], off
	s_add_i32 m0, s50, 0x2000
	s_add_u32 s48, s48, 0x40080
	v_lshl_add_u64 v[188:189], v[218:219], 0, s[24:25]
	s_addc_u32 s49, s49, 0
	s_add_i32 s50, s76, s68
	global_load_lds_dwordx4 v[188:189], off
	v_lshl_add_u64 v[188:189], s[48:49], 0, v[162:163]
	s_mov_b32 m0, s50
	s_nop 0
	global_load_lds_dwordx4 v[188:189], off
	v_lshl_add_u64 v[188:189], s[48:49], 0, v[166:167]
	s_add_i32 m0, s50, 0x2000
	s_nop 0
	global_load_lds_dwordx4 v[188:189], off
	v_lshl_add_u64 v[188:189], v[220:221], 0, s[24:25]
	s_mov_b32 m0, s75
	s_nop 0
	global_load_lds_dwordx4 v[188:189], off
	v_lshl_add_u64 v[188:189], v[222:223], 0, s[24:25]
	s_mov_b32 m0, s67
	s_nop 0
	global_load_lds_dwordx4 v[188:189], off
	s_waitcnt vmcnt(8)
	s_waitcnt lgkmcnt(0)
	s_barrier
	s_waitcnt lgkmcnt(0)
	v_mfma_f32_16x16x32_f16 v[68:71], v[16:19], v[176:179], v[68:71]
	v_mfma_f32_16x16x32_f16 v[52:55], v[16:19], v[184:187], v[52:55]
	v_mfma_f32_16x16x32_f16 v[36:39], v[16:19], v[202:205], v[36:39]
	v_mfma_f32_16x16x32_f16 v[0:3], v[16:19], v[210:213], v[0:3]
	v_mfma_f32_16x16x32_f16 v[68:71], v[20:23], v[180:183], v[68:71]
	v_mfma_f32_16x16x32_f16 v[64:67], v[136:139], v[176:179], v[64:67]
	v_mfma_f32_16x16x32_f16 v[52:55], v[20:23], v[198:201], v[52:55]
	v_mfma_f32_16x16x32_f16 v[48:51], v[136:139], v[184:187], v[48:51]
	v_mfma_f32_16x16x32_f16 v[36:39], v[20:23], v[206:209], v[36:39]
	v_mfma_f32_16x16x32_f16 v[32:35], v[136:139], v[202:205], v[32:35]
	v_mfma_f32_16x16x32_f16 v[20:23], v[20:23], v[214:217], v[0:3]
	v_mfma_f32_16x16x32_f16 v[0:3], v[136:139], v[210:213], v[4:7]
	v_mfma_f32_16x16x32_f16 v[64:67], v[140:143], v[180:183], v[64:67]
	v_mfma_f32_16x16x32_f16 v[48:51], v[140:143], v[198:201], v[48:51]
	v_mfma_f32_16x16x32_f16 v[32:35], v[140:143], v[206:209], v[32:35]
	v_mfma_f32_16x16x32_f16 v[16:19], v[140:143], v[214:217], v[0:3]
	v_mfma_f32_16x16x32_f16 v[0:3], v[144:147], v[176:179], v[60:63]
	v_mfma_f32_16x16x32_f16 v[60:63], v[148:151], v[180:183], v[0:3]
	v_mfma_f32_16x16x32_f16 v[0:3], v[152:155], v[176:179], v[56:59]
	v_mfma_f32_16x16x32_f16 v[56:59], v[156:159], v[180:183], v[0:3]
	v_mfma_f32_16x16x32_f16 v[0:3], v[144:147], v[184:187], v[44:47]
	v_mfma_f32_16x16x32_f16 v[44:47], v[148:151], v[198:201], v[0:3]
	v_mfma_f32_16x16x32_f16 v[0:3], v[152:155], v[184:187], v[40:43]
	v_mfma_f32_16x16x32_f16 v[40:43], v[156:159], v[198:201], v[0:3]
	v_mfma_f32_16x16x32_f16 v[0:3], v[144:147], v[202:205], v[28:31]
	v_mfma_f32_16x16x32_f16 v[28:31], v[148:151], v[206:209], v[0:3]
	v_mfma_f32_16x16x32_f16 v[0:3], v[152:155], v[202:205], v[24:27]
	v_mfma_f32_16x16x32_f16 v[24:27], v[156:159], v[206:209], v[0:3]
	v_mfma_f32_16x16x32_f16 v[0:3], v[144:147], v[210:213], v[12:15]
	v_mfma_f32_16x16x32_f16 v[12:15], v[148:151], v[214:217], v[0:3]
	v_mfma_f32_16x16x32_f16 v[0:3], v[152:155], v[210:213], v[8:11]
	v_mfma_f32_16x16x32_f16 v[8:11], v[156:159], v[214:217], v[0:3]
	s_barrier
	s_add_i32 s64, s64, 2
	s_add_u32 s46, s46, 0x100
	s_addc_u32 s47, s47, 0
	s_add_u32 s45, s45, 0x100
	s_addc_u32 s63, s63, 0
	s_cmp_gt_u32 s64, 13
	s_cbranch_scc0 .LBB0_1909
	s_setprio 0
	s_and_b64 vcc, exec, s[16:17]
	s_cbranch_vccz .LBB0_1912
	s_barrier

; #define PG8_STAGE(bufoff, gbase, voff) do { _Pragma("unroll") for (int _i = 0; _i < 2; ++_i) \
;         __builtin_amdgcn_global_load_lds((const unsigned*)((const char*)(gbase) + (voff)[_i]), (PG8_LAS unsigned*)(lds + (bufoff) + ldsw + _i * 8192), 16, 0, 0); } while (0)
; #define PG8_LDA(dst, b, h) do { _Pragma("unroll") for (int m = 0; m < 4; ++m) _Pragma("unroll") for (int k = 0; k < 2; ++k) dst[m][k] = *(const PG8_LAS bf16x8*)(lds + PG8_SA(b, h) + aoff + m * 2048 + k * 1024); } while (0)
; #define PG8_LDB(dst, b, h) do { _Pragma("unroll") for (int n = 0; n < 2; ++n) _Pragma("unroll") for (int k = 0; k < 2; ++k) dst[n][k] = *(const PG8_LAS bf16x8*)(lds + PG8_SB(b, h) + boff + n * 2048 + k * 1024); } while (0)
; #define PG8_MMA(ai, bj, At, Bt) do { __builtin_amdgcn_s_setprio(1); _Pragma("unroll") for (int m = 0; m < 4; ++m) _Pragma("unroll") for (int n = 0; n < 2; ++n) _Pragma("unroll") for (int k = 0; k < 2; ++k) \
;         acc[ai][bj][m][n] = mma16<F16>(Bt[n][k], At[m][k], acc[ai][bj][m][n]); __builtin_amdgcn_s_setprio(0); } while (0)
; #define PG8_WAIT_V(n) asm volatile("s_waitcnt vmcnt(" #n ")" ::: "memory")
; #define PG8_WAIT_L(n) asm volatile("s_waitcnt lgkmcnt(" #n ")" ::: "memory")
; #define PG8_BAR __builtin_amdgcn_s_barrier()
; template <class Epi, class Sched, bool ALIGN_EPI = false, bool SP2 = false, bool F16 = false>
; __device__ __forceinline__ void gemm_phase(PG8_LAS unsigned char* lds, const Gemm g, const Sched& S, const Epi& E, const int wid_in) {
;     ...
;         const bool has_next = S.next(ui + 1, nxt);
;         const char* nA = has_next ? (const char*)g.A + (size_t)nxt.pm * tstep : cA; const char* nB = has_next ? (const char*)g.Bt + (size_t)nxt.pn * tstep : cB;
;         for (int t = 0; t < nt; t += 2) {
;             const bool last = (t == nt - 2);
;             const char* a1 = cA + (size_t)(t + 1) * kstep;
;             const char* a2 = last ? nA : cA + (size_t)(t + 2) * kstep; const char* b2 = last ? nB : cB + (size_t)(t + 2) * kstep;
;             const char* a3 = a2 + kstep; const char* b3 = b2 + kstep;
;             if (last && has_next) S.a_ready(nxt);
;             if constexpr (SP2) {
;             PG8_LDB(B0, 0, 0); PG8_LDB(B1, 0, 1); PG8_SCHED; PG8_LDA(At, 0, 0); PG8_STAGE(PG8_SA(1, 1), a1 + hstep, voffA);
;             PG8_WAIT_V(8); PG8_WAIT_L(0); PG8_BAR; PG8_MMA(0, 0, At, B0); PG8_MMA(0, 1, At, B1); PG8_BAR; PG8_SCHED;
.Lgsp_15:
.LBB0_1943:
	s_mov_b32 s36, 2
	s_mov_b64 s[30:31], 0
	s_andn2_b64 vcc, exec, s[34:35]
	s_mov_b32 s59, s57
	s_mov_b32 s34, s58
	s_cbranch_vccz .LBB0_1949
.LBB0_1944:
	s_mov_b64 s[48:49], s[10:11]
	s_add_i32 s10, s36, s19
	s_mov_b64 s[46:47], s[12:13]
	s_mov_b32 s12, s58
	s_mov_b32 s13, s57
	s_and_b32 s57, s10, 3
	s_ashr_i32 s58, s10, 2
	s_and_b64 s[10:11], s[30:31], exec
	s_cselect_b32 s12, s58, s12
	ds_read_b128 v[0:3], v134
	ds_read_b128 v[4:7], v134 offset:1024
	ds_read_b128 v[8:11], v134 offset:2048
	ds_read_b128 v[12:15], v134 offset:3072
	ds_read_b128 v[16:19], v135
	ds_read_b128 v[20:23], v135 offset:1024
	ds_read_b128 v[24:27], v135 offset:2048
	ds_read_b128 v[28:31], v135 offset:3072
	s_cselect_b32 s10, s57, s13
	s_ashr_i32 s13, s12, 31
	s_lshl_b64 s[12:13], s[12:13], 17
	s_add_u32 s12, s21, s12
	s_addc_u32 s13, s40, s13
	s_and_b64 s[36:37], s[30:31], exec
	s_cselect_b32 s45, s13, s47
	s_cselect_b32 s44, s12, s46
	s_ashr_i32 s11, s10, 31
	s_lshl_b64 s[10:11], s[10:11], 17
	s_add_u32 s10, s41, s10
	s_addc_u32 s11, s42, s11
	s_and_b64 s[36:37], s[30:31], exec
	s_cselect_b32 s37, s11, s49
	s_cselect_b32 s36, s10, s48
	s_add_u32 s60, s46, 0x10080
	s_addc_u32 s61, s47, 0
	s_mov_b32 m0, s91
	v_lshl_add_u64 v[64:65], s[60:61], 0, v[130:131]
	ds_read_b128 v[32:35], v136
	ds_read_b128 v[36:39], v136 offset:1024
	ds_read_b128 v[40:43], v136 offset:2048
	ds_read_b128 v[44:47], v136 offset:3072
	ds_read_b128 v[48:51], v136 offset:4096
	ds_read_b128 v[52:55], v136 offset:5120
	ds_read_b128 v[56:59], v136 offset:6144
	ds_read_b128 v[60:63], v136 offset:7168
	global_load_lds_dwordx4 v[64:65], off
	v_lshl_add_u64 v[64:65], s[60:61], 0, v[128:129]
	s_mov_b32 m0, s14
	s_nop 0
	global_load_lds_dwordx4 v[64:65], off
	s_waitcnt vmcnt(8)
	s_waitcnt lgkmcnt(0)
	s_barrier
	s_waitcnt lgkmcnt(0)
	v_mfma_f32_16x16x32_bf16 v[64:67], v[0:3], v[32:35], 0
	v_mfma_f32_16x16x32_bf16 v[68:71], v[8:11], v[32:35], 0
	v_mfma_f32_16x16x32_bf16 v[72:75], v[0:3], v[40:43], 0
	v_mfma_f32_16x16x32_bf16 v[76:79], v[8:11], v[40:43], 0
	v_mfma_f32_16x16x32_bf16 v[80:83], v[0:3], v[48:51], 0
	v_mfma_f32_16x16x32_bf16 v[84:87], v[8:11], v[48:51], 0
	v_mfma_f32_16x16x32_bf16 v[88:91], v[0:3], v[56:59], 0
	v_mfma_f32_16x16x32_bf16 v[92:95], v[8:11], v[56:59], 0
	v_mfma_f32_16x16x32_bf16 v[64:67], v[4:7], v[36:39], v[64:67]
	v_mfma_f32_16x16x32_bf16 v[68:71], v[12:15], v[36:39], v[68:71]
	v_mfma_f32_16x16x32_bf16 v[72:75], v[4:7], v[44:47], v[72:75]
	v_mfma_f32_16x16x32_bf16 v[76:79], v[12:15], v[44:47], v[76:79]
	v_mfma_f32_16x16x32_bf16 v[80:83], v[4:7], v[52:55], v[80:83]
	v_mfma_f32_16x16x32_bf16 v[84:87], v[12:15], v[52:55], v[84:87]
	v_mfma_f32_16x16x32_bf16 v[88:91], v[4:7], v[60:63], v[88:91]
	v_mfma_f32_16x16x32_bf16 v[92:95], v[12:15], v[60:63], v[92:95]
	v_mfma_f32_16x16x32_bf16 v[96:99], v[16:19], v[32:35], 0
	v_mfma_f32_16x16x32_bf16 v[32:35], v[24:27], v[32:35], 0
	v_mfma_f32_16x16x32_bf16 v[96:99], v[20:23], v[36:39], v[96:99]
	v_mfma_f32_16x16x32_bf16 v[32:35], v[28:31], v[36:39], v[32:35]
	v_mfma_f32_16x16x32_bf16 v[36:39], v[16:19], v[40:43], 0
	v_mfma_f32_16x16x32_bf16 v[40:43], v[24:27], v[40:43], 0
	v_mfma_f32_16x16x32_bf16 v[36:39], v[20:23], v[44:47], v[36:39]
	v_mfma_f32_16x16x32_bf16 v[40:43], v[28:31], v[44:47], v[40:43]
	v_mfma_f32_16x16x32_bf16 v[44:47], v[16:19], v[48:51], 0
	v_mfma_f32_16x16x32_bf16 v[48:51], v[24:27], v[48:51], 0
	v_mfma_f32_16x16x32_bf16 v[44:47], v[20:23], v[52:55], v[44:47]
	v_mfma_f32_16x16x32_bf16 v[48:51], v[28:31], v[52:55], v[48:51]
	v_mfma_f32_16x16x32_bf16 v[52:55], v[16:19], v[56:59], 0
	v_mfma_f32_16x16x32_bf16 v[56:59], v[24:27], v[56:59], 0
	v_mfma_f32_16x16x32_bf16 v[52:55], v[20:23], v[60:63], v[52:55]
	v_mfma_f32_16x16x32_bf16 v[56:59], v[28:31], v[60:63], v[56:59]
	s_barrier
	v_lshl_add_u64 v[204:205], s[48:49], 0, v[130:131]
	s_mov_b32 m0, s15
	v_lshl_add_u64 v[140:141], v[204:205], 0, s[26:27]
	v_lshl_add_u64 v[206:207], s[48:49], 0, v[128:129]
	s_add_u32 s60, s48, 0x10100
	ds_read_b128 v[60:63], v136 offset:16384
	ds_read_b128 v[100:103], v136 offset:17408
	ds_read_b128 v[104:107], v136 offset:18432
	ds_read_b128 v[108:111], v136 offset:19456
	ds_read_b128 v[112:115], v136 offset:20480
	ds_read_b128 v[116:119], v136 offset:21504
	ds_read_b128 v[120:123], v136 offset:22528
	ds_read_b128 v[124:127], v136 offset:23552
	global_load_lds_dwordx4 v[140:141], off
	v_lshl_add_u64 v[140:141], v[206:207], 0, s[26:27]
	s_mov_b32 m0, s50
	s_addc_u32 s61, s49, 0
	global_load_lds_dwordx4 v[140:141], off
	v_lshl_add_u64 v[140:141], s[60:61], 0, v[130:131]
	s_mov_b32 m0, s51
	v_lshl_add_u64 v[208:209], s[46:47], 0, v[130:131]
	global_load_lds_dwordx4 v[140:141], off
	v_lshl_add_u64 v[140:141], s[60:61], 0, v[128:129]
	s_mov_b32 m0, s52
	v_lshl_add_u64 v[210:211], s[46:47], 0, v[128:129]
	global_load_lds_dwordx4 v[140:141], off
	v_lshl_add_u64 v[140:141], v[208:209], 0, s[26:27]
	s_mov_b32 m0, s74
	s_nop 0
	global_load_lds_dwordx4 v[140:141], off
	v_lshl_add_u64 v[140:141], v[210:211], 0, s[26:27]
	s_mov_b32 m0, s66
	s_nop 0
	global_load_lds_dwordx4 v[140:141], off
	s_waitcnt vmcnt(8)
	s_waitcnt lgkmcnt(0)
	s_barrier
; #define PG8_STAGE(bufoff, gbase, voff) do { _Pragma("unroll") for (int _i = 0; _i < 2; ++_i) \
;         __builtin_amdgcn_global_load_lds((const unsigned*)((const char*)(gbase) + (voff)[_i]), (PG8_LAS unsigned*)(lds + (bufoff) + ldsw + _i * 8192), 16, 0, 0); } while (0)
; #define PG8_LDA(dst, b, h) do { _Pragma("unroll") for (int m = 0; m < 4; ++m) _Pragma("unroll") for (int k = 0; k < 2; ++k) dst[m][k] = *(const PG8_LAS bf16x8*)(lds + PG8_SA(b, h) + aoff + m * 2048 + k * 1024); } while (0)
; #define PG8_LDB(dst, b, h) do { _Pragma("unroll") for (int n = 0; n < 2; ++n) _Pragma("unroll") for (int k = 0; k < 2; ++k) dst[n][k] = *(const PG8_LAS bf16x8*)(lds + PG8_SB(b, h) + boff + n * 2048 + k * 1024); } while (0)
; #define PG8_MMA(ai, bj, At, Bt) do { __builtin_amdgcn_s_setprio(1); _Pragma("unroll") for (int m = 0; m < 4; ++m) _Pragma("unroll") for (int n = 0; n < 2; ++n) _Pragma("unroll") for (int k = 0; k < 2; ++k) \
;         acc[ai][bj][m][n] = mma16<F16>(Bt[n][k], At[m][k], acc[ai][bj][m][n]); __builtin_amdgcn_s_setprio(0); } while (0)
; #define PG8_WAIT_V(n) asm volatile("s_waitcnt vmcnt(" #n ")" ::: "memory")
; #define PG8_WAIT_L(n) asm volatile("s_waitcnt lgkmcnt(" #n ")" ::: "memory")
; #define PG8_BAR __builtin_amdgcn_s_barrier()
; #define PG8_SCHED __builtin_amdgcn_sched_barrier(0)
; template <class Epi, class Sched, bool ALIGN_EPI = false, bool SP2 = false, bool F16 = false>
; __device__ __forceinline__ void gemm_phase(PG8_LAS unsigned char* lds, const Gemm g, const Sched& S, const Epi& E, const int wid_in) {
;     ...
;             PG8_WAIT_V(8); PG8_WAIT_L(0); PG8_BAR; PG8_MMA(1, 0, At, B0); PG8_MMA(1, 1, At, B1); PG8_BAR; PG8_SCHED;
;             PG8_LDB(B0, 1, 0); PG8_LDB(B1, 1, 1); PG8_SCHED; PG8_LDA(At, 1, 0); PG8_STAGE(PG8_SA(0, 1), a2 + hstep, voffA);
;             PG8_WAIT_V(8); PG8_WAIT_L(0); PG8_BAR; PG8_MMA(0, 0, At, B0); PG8_MMA(0, 1, At, B1); PG8_BAR; PG8_SCHED;
	s_waitcnt lgkmcnt(0)
	v_mfma_f32_16x16x32_bf16 v[140:143], v[0:3], v[60:63], 0
	v_mfma_f32_16x16x32_bf16 v[148:151], v[0:3], v[104:107], 0
	v_mfma_f32_16x16x32_bf16 v[156:159], v[0:3], v[112:115], 0
	v_mfma_f32_16x16x32_bf16 v[0:3], v[0:3], v[120:123], 0
	v_mfma_f32_16x16x32_bf16 v[140:143], v[4:7], v[100:103], v[140:143]
	v_mfma_f32_16x16x32_bf16 v[148:151], v[4:7], v[108:111], v[148:151]
	v_mfma_f32_16x16x32_bf16 v[156:159], v[4:7], v[116:119], v[156:159]
	v_mfma_f32_16x16x32_bf16 v[0:3], v[4:7], v[124:127], v[0:3]
	v_mfma_f32_16x16x32_bf16 v[4:7], v[8:11], v[120:123], 0
	v_mfma_f32_16x16x32_bf16 v[144:147], v[8:11], v[60:63], 0
	v_mfma_f32_16x16x32_bf16 v[152:155], v[8:11], v[104:107], 0
	v_mfma_f32_16x16x32_bf16 v[160:163], v[8:11], v[112:115], 0
	v_mfma_f32_16x16x32_bf16 v[4:7], v[12:15], v[124:127], v[4:7]
	v_mfma_f32_16x16x32_bf16 v[144:147], v[12:15], v[100:103], v[144:147]
	v_mfma_f32_16x16x32_bf16 v[152:155], v[12:15], v[108:111], v[152:155]
	v_mfma_f32_16x16x32_bf16 v[160:163], v[12:15], v[116:119], v[160:163]
	v_mfma_f32_16x16x32_bf16 v[8:11], v[16:19], v[60:63], 0
	v_mfma_f32_16x16x32_bf16 v[12:15], v[24:27], v[60:63], 0
	v_mfma_f32_16x16x32_bf16 v[8:11], v[20:23], v[100:103], v[8:11]
	v_mfma_f32_16x16x32_bf16 v[12:15], v[28:31], v[100:103], v[12:15]
	v_mfma_f32_16x16x32_bf16 v[60:63], v[16:19], v[104:107], 0
	v_mfma_f32_16x16x32_bf16 v[100:103], v[24:27], v[104:107], 0
	v_mfma_f32_16x16x32_bf16 v[104:107], v[16:19], v[112:115], 0
	v_mfma_f32_16x16x32_bf16 v[16:19], v[16:19], v[120:123], 0
	v_mfma_f32_16x16x32_bf16 v[60:63], v[20:23], v[108:111], v[60:63]
	v_mfma_f32_16x16x32_bf16 v[100:103], v[28:31], v[108:111], v[100:103]
	v_mfma_f32_16x16x32_bf16 v[104:107], v[20:23], v[116:119], v[104:107]
	v_mfma_f32_16x16x32_bf16 v[108:111], v[24:27], v[112:115], 0
	v_mfma_f32_16x16x32_bf16 v[16:19], v[20:23], v[124:127], v[16:19]
	v_mfma_f32_16x16x32_bf16 v[20:23], v[24:27], v[120:123], 0
	v_mfma_f32_16x16x32_bf16 v[108:111], v[28:31], v[116:119], v[108:111]
	v_mfma_f32_16x16x32_bf16 v[20:23], v[28:31], v[124:127], v[20:23]
	s_barrier
	ds_read_b128 v[24:27], v137
	ds_read_b128 v[28:31], v137 offset:1024
	ds_read_b128 v[112:115], v137 offset:2048
	ds_read_b128 v[116:119], v137 offset:3072
	ds_read_b128 v[120:123], v138
	ds_read_b128 v[124:127], v138 offset:1024
	ds_read_b128 v[164:167], v138 offset:2048
	ds_read_b128 v[168:171], v138 offset:3072
	s_add_u32 s60, s46, 0x10100
	s_addc_u32 s61, s47, 0
	s_mov_b32 m0, s90
	v_lshl_add_u64 v[212:213], s[60:61], 0, v[130:131]
	ds_read_b128 v[172:175], v136 offset:32768
	ds_read_b128 v[176:179], v136 offset:33792
	ds_read_b128 v[180:183], v136 offset:34816
	ds_read_b128 v[184:187], v136 offset:35840
	ds_read_b128 v[188:191], v136 offset:36864
	ds_read_b128 v[192:195], v136 offset:37888
	ds_read_b128 v[196:199], v136 offset:38912
	ds_read_b128 v[200:203], v136 offset:39936
	global_load_lds_dwordx4 v[212:213], off
	v_lshl_add_u64 v[212:213], s[60:61], 0, v[128:129]
	s_mov_b32 m0, s43
	s_nop 0
	global_load_lds_dwordx4 v[212:213], off
	s_waitcnt vmcnt(8)
	s_waitcnt lgkmcnt(0)
	s_barrier
	s_waitcnt lgkmcnt(0)
	v_mfma_f32_16x16x32_bf16 v[64:67], v[24:27], v[172:175], v[64:67]
	v_mfma_f32_16x16x32_bf16 v[68:71], v[112:115], v[172:175], v[68:71]
	v_mfma_f32_16x16x32_bf16 v[72:75], v[24:27], v[180:183], v[72:75]
	v_mfma_f32_16x16x32_bf16 v[76:79], v[112:115], v[180:183], v[76:79]
	v_mfma_f32_16x16x32_bf16 v[80:83], v[24:27], v[188:191], v[80:83]
	v_mfma_f32_16x16x32_bf16 v[84:87], v[112:115], v[188:191], v[84:87]
	v_mfma_f32_16x16x32_bf16 v[88:91], v[24:27], v[196:199], v[88:91]
	v_mfma_f32_16x16x32_bf16 v[92:95], v[112:115], v[196:199], v[92:95]
	v_mfma_f32_16x16x32_bf16 v[64:67], v[28:31], v[176:179], v[64:67]
	v_mfma_f32_16x16x32_bf16 v[68:71], v[116:119], v[176:179], v[68:71]
	v_mfma_f32_16x16x32_bf16 v[72:75], v[28:31], v[184:187], v[72:75]
	v_mfma_f32_16x16x32_bf16 v[76:79], v[116:119], v[184:187], v[76:79]
	v_mfma_f32_16x16x32_bf16 v[80:83], v[28:31], v[192:195], v[80:83]
	v_mfma_f32_16x16x32_bf16 v[84:87], v[116:119], v[192:195], v[84:87]
	v_mfma_f32_16x16x32_bf16 v[88:91], v[28:31], v[200:203], v[88:91]
	v_mfma_f32_16x16x32_bf16 v[92:95], v[116:119], v[200:203], v[92:95]
	v_mfma_f32_16x16x32_bf16 v[96:99], v[120:123], v[172:175], v[96:99]
	v_mfma_f32_16x16x32_bf16 v[32:35], v[164:167], v[172:175], v[32:35]
	v_mfma_f32_16x16x32_bf16 v[36:39], v[120:123], v[180:183], v[36:39]
	v_mfma_f32_16x16x32_bf16 v[40:43], v[164:167], v[180:183], v[40:43]
	v_mfma_f32_16x16x32_bf16 v[44:47], v[120:123], v[188:191], v[44:47]
	v_mfma_f32_16x16x32_bf16 v[48:51], v[164:167], v[188:191], v[48:51]
	v_mfma_f32_16x16x32_bf16 v[52:55], v[120:123], v[196:199], v[52:55]
	v_mfma_f32_16x16x32_bf16 v[56:59], v[164:167], v[196:199], v[56:59]
	v_mfma_f32_16x16x32_bf16 v[96:99], v[124:127], v[176:179], v[96:99]
	v_mfma_f32_16x16x32_bf16 v[32:35], v[168:171], v[176:179], v[32:35]
	v_mfma_f32_16x16x32_bf16 v[36:39], v[124:127], v[184:187], v[36:39]
	v_mfma_f32_16x16x32_bf16 v[40:43], v[168:171], v[184:187], v[40:43]
	v_mfma_f32_16x16x32_bf16 v[44:47], v[124:127], v[192:195], v[44:47]
	v_mfma_f32_16x16x32_bf16 v[48:51], v[168:171], v[192:195], v[48:51]
	v_mfma_f32_16x16x32_bf16 v[52:55], v[124:127], v[200:203], v[52:55]
	v_mfma_f32_16x16x32_bf16 v[56:59], v[168:171], v[200:203], v[56:59]
	s_barrier
; #define PG8_STAGE(bufoff, gbase, voff) do { _Pragma("unroll") for (int _i = 0; _i < 2; ++_i) \
;         __builtin_amdgcn_global_load_lds((const unsigned*)((const char*)(gbase) + (voff)[_i]), (PG8_LAS unsigned*)(lds + (bufoff) + ldsw + _i * 8192), 16, 0, 0); } while (0)
; #define PG8_LDA(dst, b, h) do { _Pragma("unroll") for (int m = 0; m < 4; ++m) _Pragma("unroll") for (int k = 0; k < 2; ++k) dst[m][k] = *(const PG8_LAS bf16x8*)(lds + PG8_SA(b, h) + aoff + m * 2048 + k * 1024); } while (0)
; #define PG8_LDB(dst, b, h) do { _Pragma("unroll") for (int n = 0; n < 2; ++n) _Pragma("unroll") for (int k = 0; k < 2; ++k) dst[n][k] = *(const PG8_LAS bf16x8*)(lds + PG8_SB(b, h) + boff + n * 2048 + k * 1024); } while (0)
; #define PG8_MMA(ai, bj, At, Bt) do { __builtin_amdgcn_s_setprio(1); _Pragma("unroll") for (int m = 0; m < 4; ++m) _Pragma("unroll") for (int n = 0; n < 2; ++n) _Pragma("unroll") for (int k = 0; k < 2; ++k) \
;         acc[ai][bj][m][n] = mma16<F16>(Bt[n][k], At[m][k], acc[ai][bj][m][n]); __builtin_amdgcn_s_setprio(0); } while (0)
; #define PG8_WAIT_V(n) asm volatile("s_waitcnt vmcnt(" #n ")" ::: "memory")
; #define PG8_WAIT_L(n) asm volatile("s_waitcnt lgkmcnt(" #n ")" ::: "memory")
; #define PG8_BAR __builtin_amdgcn_s_barrier()
; #define PG8_SCHED __builtin_amdgcn_sched_barrier(0)
; template <class Epi, class Sched, bool ALIGN_EPI = false, bool SP2 = false, bool F16 = false>
; __device__ __forceinline__ void gemm_phase(PG8_LAS unsigned char* lds, const Gemm g, const Sched& S, const Epi& E, const int wid_in) {
;     ...
;             PG8_LDB(B0, 0, 0); PG8_LDB(B1, 0, 1); PG8_SCHED; PG8_LDA(At, 0, 0); PG8_STAGE(PG8_SA(1, 1), a1 + hstep, voffA);
;             PG8_WAIT_V(8); PG8_WAIT_L(0); PG8_BAR; PG8_MMA(0, 0, At, B0); PG8_MMA(0, 1, At, B1); PG8_BAR; PG8_SCHED;
;     ...
;             PG8_LDA(At, 1, 1); PG8_STAGE(PG8_SB(1, 0), b3, voffB); PG8_STAGE(PG8_SB(1, 1), b3 + hstep, voffB); PG8_STAGE(PG8_SA(1, 0), a3, voffA);
;             PG8_WAIT_V(8); PG8_WAIT_L(0); PG8_BAR; PG8_MMA(1, 0, At, B0); PG8_MMA(1, 1, At, B1); PG8_BAR; PG8_SCHED;
	s_mov_b32 m0, s53
	v_lshl_add_u64 v[204:205], v[204:205], 0, s[28:29]
	s_add_u32 s48, s48, 0x10180
	ds_read_b128 v[172:175], v136 offset:49152
	ds_read_b128 v[176:179], v136 offset:50176
	ds_read_b128 v[180:183], v136 offset:51200
	ds_read_b128 v[184:187], v136 offset:52224
	ds_read_b128 v[188:191], v136 offset:53248
	ds_read_b128 v[192:195], v136 offset:54272
	ds_read_b128 v[196:199], v136 offset:55296
	ds_read_b128 v[200:203], v136 offset:56320
	global_load_lds_dwordx4 v[204:205], off
	v_lshl_add_u64 v[204:205], v[206:207], 0, s[28:29]
	s_mov_b32 m0, s54
	s_addc_u32 s49, s49, 0
	global_load_lds_dwordx4 v[204:205], off
	v_lshl_add_u64 v[204:205], s[48:49], 0, v[130:131]
	s_mov_b32 m0, s55
	s_nop 0
	global_load_lds_dwordx4 v[204:205], off
	v_lshl_add_u64 v[204:205], s[48:49], 0, v[128:129]
	s_mov_b32 m0, s56
	s_nop 0
	global_load_lds_dwordx4 v[204:205], off
	v_lshl_add_u64 v[204:205], v[208:209], 0, s[28:29]
	s_mov_b32 m0, s75
	s_nop 0
	global_load_lds_dwordx4 v[204:205], off
	v_lshl_add_u64 v[204:205], v[210:211], 0, s[28:29]
	s_mov_b32 m0, s67
	s_nop 0
	global_load_lds_dwordx4 v[204:205], off
	s_waitcnt vmcnt(8)
	s_waitcnt lgkmcnt(0)
	s_barrier
	s_waitcnt lgkmcnt(0)
	v_mfma_f32_16x16x32_bf16 v[0:3], v[24:27], v[196:199], v[0:3]
	v_mfma_f32_16x16x32_bf16 v[4:7], v[112:115], v[196:199], v[4:7]
	v_mfma_f32_16x16x32_bf16 v[140:143], v[24:27], v[172:175], v[140:143]
	v_mfma_f32_16x16x32_bf16 v[144:147], v[112:115], v[172:175], v[144:147]
	v_mfma_f32_16x16x32_bf16 v[148:151], v[24:27], v[180:183], v[148:151]
	v_mfma_f32_16x16x32_bf16 v[152:155], v[112:115], v[180:183], v[152:155]
	v_mfma_f32_16x16x32_bf16 v[156:159], v[24:27], v[188:191], v[156:159]
	v_mfma_f32_16x16x32_bf16 v[160:163], v[112:115], v[188:191], v[160:163]
	v_mfma_f32_16x16x32_bf16 v[0:3], v[28:31], v[200:203], v[0:3]
	v_mfma_f32_16x16x32_bf16 v[4:7], v[116:119], v[200:203], v[4:7]
	v_mfma_f32_16x16x32_bf16 v[140:143], v[28:31], v[176:179], v[140:143]
	v_mfma_f32_16x16x32_bf16 v[144:147], v[116:119], v[176:179], v[144:147]
	v_mfma_f32_16x16x32_bf16 v[148:151], v[28:31], v[184:187], v[148:151]
	v_mfma_f32_16x16x32_bf16 v[152:155], v[116:119], v[184:187], v[152:155]
	v_mfma_f32_16x16x32_bf16 v[156:159], v[28:31], v[192:195], v[156:159]
	v_mfma_f32_16x16x32_bf16 v[160:163], v[116:119], v[192:195], v[160:163]
	v_mfma_f32_16x16x32_bf16 v[8:11], v[120:123], v[172:175], v[8:11]
	v_mfma_f32_16x16x32_bf16 v[12:15], v[164:167], v[172:175], v[12:15]
	v_mfma_f32_16x16x32_bf16 v[24:27], v[120:123], v[180:183], v[60:63]
	v_mfma_f32_16x16x32_bf16 v[28:31], v[164:167], v[180:183], v[100:103]
	v_mfma_f32_16x16x32_bf16 v[60:63], v[120:123], v[188:191], v[104:107]
	v_mfma_f32_16x16x32_bf16 v[100:103], v[164:167], v[188:191], v[108:111]
	v_mfma_f32_16x16x32_bf16 v[16:19], v[120:123], v[196:199], v[16:19]
	v_mfma_f32_16x16x32_bf16 v[20:23], v[164:167], v[196:199], v[20:23]
	v_mfma_f32_16x16x32_bf16 v[8:11], v[124:127], v[176:179], v[8:11]
	v_mfma_f32_16x16x32_bf16 v[12:15], v[168:171], v[176:179], v[12:15]
	v_mfma_f32_16x16x32_bf16 v[24:27], v[124:127], v[184:187], v[24:27]
	v_mfma_f32_16x16x32_bf16 v[28:31], v[168:171], v[184:187], v[28:31]
	v_mfma_f32_16x16x32_bf16 v[60:63], v[124:127], v[192:195], v[60:63]
	v_mfma_f32_16x16x32_bf16 v[100:103], v[168:171], v[192:195], v[100:103]
	v_mfma_f32_16x16x32_bf16 v[16:19], v[124:127], v[200:203], v[16:19]
	v_mfma_f32_16x16x32_bf16 v[20:23], v[168:171], v[200:203], v[20:23]
	s_barrier
	ds_read_b128 v[104:107], v134
	ds_read_b128 v[108:111], v134 offset:1024
	ds_read_b128 v[112:115], v134 offset:2048
	ds_read_b128 v[116:119], v134 offset:3072
	ds_read_b128 v[120:123], v135
	ds_read_b128 v[124:127], v135 offset:1024
	ds_read_b128 v[164:167], v135 offset:2048
	ds_read_b128 v[168:171], v135 offset:3072
	s_add_u32 s46, s46, 0x10180
	s_addc_u32 s47, s47, 0
	s_mov_b32 m0, s91
	v_lshl_add_u64 v[204:205], s[46:47], 0, v[130:131]
	ds_read_b128 v[172:175], v136
	ds_read_b128 v[176:179], v136 offset:1024
	ds_read_b128 v[180:183], v136 offset:2048
	ds_read_b128 v[184:187], v136 offset:3072
	ds_read_b128 v[188:191], v136 offset:4096
	ds_read_b128 v[192:195], v136 offset:5120
	ds_read_b128 v[196:199], v136 offset:6144
	ds_read_b128 v[200:203], v136 offset:7168
	global_load_lds_dwordx4 v[204:205], off
	v_lshl_add_u64 v[204:205], s[46:47], 0, v[128:129]
	s_mov_b32 m0, s14
	s_nop 0
	global_load_lds_dwordx4 v[204:205], off
	s_waitcnt vmcnt(8)
	s_waitcnt lgkmcnt(0)
	s_barrier
	s_waitcnt lgkmcnt(0)
	v_mfma_f32_16x16x32_bf16 v[64:67], v[104:107], v[172:175], v[64:67]
	v_mfma_f32_16x16x32_bf16 v[68:71], v[112:115], v[172:175], v[68:71]
	v_mfma_f32_16x16x32_bf16 v[72:75], v[104:107], v[180:183], v[72:75]
	v_mfma_f32_16x16x32_bf16 v[76:79], v[112:115], v[180:183], v[76:79]
	v_mfma_f32_16x16x32_bf16 v[80:83], v[104:107], v[188:191], v[80:83]
	v_mfma_f32_16x16x32_bf16 v[84:87], v[112:115], v[188:191], v[84:87]
	v_mfma_f32_16x16x32_bf16 v[88:91], v[104:107], v[196:199], v[88:91]
	v_mfma_f32_16x16x32_bf16 v[92:95], v[112:115], v[196:199], v[92:95]
	v_mfma_f32_16x16x32_bf16 v[64:67], v[108:111], v[176:179], v[64:67]
	v_mfma_f32_16x16x32_bf16 v[68:71], v[116:119], v[176:179], v[68:71]
	v_mfma_f32_16x16x32_bf16 v[72:75], v[108:111], v[184:187], v[72:75]
	v_mfma_f32_16x16x32_bf16 v[76:79], v[116:119], v[184:187], v[76:79]
	v_mfma_f32_16x16x32_bf16 v[80:83], v[108:111], v[192:195], v[80:83]
	v_mfma_f32_16x16x32_bf16 v[84:87], v[116:119], v[192:195], v[84:87]
	v_mfma_f32_16x16x32_bf16 v[88:91], v[108:111], v[200:203], v[88:91]
	v_mfma_f32_16x16x32_bf16 v[92:95], v[116:119], v[200:203], v[92:95]
	v_mfma_f32_16x16x32_bf16 v[32:35], v[164:167], v[172:175], v[32:35]
	v_mfma_f32_16x16x32_bf16 v[96:99], v[120:123], v[172:175], v[96:99]
	v_mfma_f32_16x16x32_bf16 v[172:175], v[168:171], v[176:179], v[32:35]
	v_mfma_f32_16x16x32_bf16 v[32:35], v[120:123], v[180:183], v[36:39]
	v_mfma_f32_16x16x32_bf16 v[204:207], v[124:127], v[176:179], v[96:99]
	v_mfma_f32_16x16x32_bf16 v[176:179], v[124:127], v[184:187], v[32:35]
	v_mfma_f32_16x16x32_bf16 v[32:35], v[164:167], v[180:183], v[40:43]
	v_mfma_f32_16x16x32_bf16 v[40:43], v[168:171], v[184:187], v[32:35]
	v_mfma_f32_16x16x32_bf16 v[32:35], v[120:123], v[188:191], v[44:47]
	v_mfma_f32_16x16x32_bf16 v[44:47], v[124:127], v[192:195], v[32:35]
	v_mfma_f32_16x16x32_bf16 v[32:35], v[164:167], v[188:191], v[48:51]
	v_mfma_f32_16x16x32_bf16 v[48:51], v[168:171], v[192:195], v[32:35]
	v_mfma_f32_16x16x32_bf16 v[32:35], v[120:123], v[196:199], v[52:55]
	v_mfma_f32_16x16x32_bf16 v[52:55], v[124:127], v[200:203], v[32:35]
	v_mfma_f32_16x16x32_bf16 v[32:35], v[164:167], v[196:199], v[56:59]
	v_mfma_f32_16x16x32_bf16 v[56:59], v[168:171], v[200:203], v[32:35]
	s_barrier
; #define PG8_STAGE(bufoff, gbase, voff) do { _Pragma("unroll") for (int _i = 0; _i < 2; ++_i) \
;         __builtin_amdgcn_global_load_lds((const unsigned*)((const char*)(gbase) + (voff)[_i]), (PG8_LAS unsigned*)(lds + (bufoff) + ldsw + _i * 8192), 16, 0, 0); } while (0)
; #define PG8_LDA(dst, b, h) do { _Pragma("unroll") for (int m = 0; m < 4; ++m) _Pragma("unroll") for (int k = 0; k < 2; ++k) dst[m][k] = *(const PG8_LAS bf16x8*)(lds + PG8_SA(b, h) + aoff + m * 2048 + k * 1024); } while (0)
; #define PG8_LDB(dst, b, h) do { _Pragma("unroll") for (int n = 0; n < 2; ++n) _Pragma("unroll") for (int k = 0; k < 2; ++k) dst[n][k] = *(const PG8_LAS bf16x8*)(lds + PG8_SB(b, h) + boff + n * 2048 + k * 1024); } while (0)
; #define PG8_MMA(ai, bj, At, Bt) do { __builtin_amdgcn_s_setprio(1); _Pragma("unroll") for (int m = 0; m < 4; ++m) _Pragma("unroll") for (int n = 0; n < 2; ++n) _Pragma("unroll") for (int k = 0; k < 2; ++k) \
;         acc[ai][bj][m][n] = mma16<F16>(Bt[n][k], At[m][k], acc[ai][bj][m][n]); __builtin_amdgcn_s_setprio(0); } while (0)
; #define PG8_WAIT_V(n) asm volatile("s_waitcnt vmcnt(" #n ")" ::: "memory")
; #define PG8_WAIT_L(n) asm volatile("s_waitcnt lgkmcnt(" #n ")" ::: "memory")
; #define PG8_BAR __builtin_amdgcn_s_barrier()
; #define PG8_SCHED __builtin_amdgcn_sched_barrier(0)
; template <class Epi, class Sched, bool ALIGN_EPI = false, bool SP2 = false, bool F16 = false>
; __device__ __forceinline__ void gemm_phase(PG8_LAS unsigned char* lds, const Gemm g, const Sched& S, const Epi& E, const int wid_in) {
;     ...
;             PG8_LDA(At, 0, 1); PG8_STAGE(PG8_SB(0, 0), b2, voffB); PG8_STAGE(PG8_SB(0, 1), b2 + hstep, voffB); PG8_STAGE(PG8_SA(0, 0), a2, voffA);
;             PG8_WAIT_V(8); PG8_WAIT_L(0); PG8_BAR; PG8_MMA(1, 0, At, B0); PG8_MMA(1, 1, At, B1); PG8_BAR; PG8_SCHED;
;             PG8_LDB(B0, 1, 0); PG8_LDB(B1, 1, 1); PG8_SCHED; PG8_LDA(At, 1, 0); PG8_STAGE(PG8_SA(0, 1), a2 + hstep, voffA);
;             PG8_WAIT_V(8); PG8_WAIT_L(0); PG8_BAR; PG8_MMA(0, 0, At, B0); PG8_MMA(0, 1, At, B1); PG8_BAR; PG8_SCHED;
	s_mov_b32 m0, s15
	v_lshl_add_u64 v[240:241], s[36:37], 0, v[130:131]
	s_add_u32 s46, s36, 0x10000
	s_nop 1
	ds_read_b128 v[32:35], v136 offset:16384
	ds_read_b128 v[36:39], v136 offset:17408
	ds_read_b128 v[96:99], v136 offset:18432
	ds_read_b128 v[180:183], v136 offset:19456
	ds_read_b128 v[184:187], v136 offset:20480
	ds_read_b128 v[188:191], v136 offset:21504
	ds_read_b128 v[192:195], v136 offset:22528
	ds_read_b128 v[196:199], v136 offset:23552
	global_load_lds_dwordx4 v[240:241], off
	v_lshl_add_u64 v[242:243], s[36:37], 0, v[128:129]
	s_mov_b32 m0, s50
	s_addc_u32 s47, s37, 0
	global_load_lds_dwordx4 v[242:243], off
	v_lshl_add_u64 v[200:201], s[46:47], 0, v[130:131]
	s_mov_b32 m0, s51
	v_lshl_add_u64 v[244:245], s[44:45], 0, v[130:131]
	global_load_lds_dwordx4 v[200:201], off
	v_lshl_add_u64 v[200:201], s[46:47], 0, v[128:129]
	s_mov_b32 m0, s52
	v_lshl_add_u64 v[246:247], s[44:45], 0, v[128:129]
	global_load_lds_dwordx4 v[200:201], off
	s_mov_b32 m0, s74
	s_nop 0
	global_load_lds_dwordx4 v[244:245], off
	s_mov_b32 m0, s66
	s_nop 0
	global_load_lds_dwordx4 v[246:247], off
	s_waitcnt vmcnt(8)
	s_waitcnt lgkmcnt(0)
	s_barrier
	s_waitcnt lgkmcnt(0)
	v_mfma_f32_16x16x32_bf16 v[0:3], v[104:107], v[192:195], v[0:3]
	v_mfma_f32_16x16x32_bf16 v[140:143], v[104:107], v[32:35], v[140:143]
	v_mfma_f32_16x16x32_bf16 v[144:147], v[112:115], v[32:35], v[144:147]
	v_mfma_f32_16x16x32_bf16 v[148:151], v[104:107], v[96:99], v[148:151]
	v_mfma_f32_16x16x32_bf16 v[152:155], v[112:115], v[96:99], v[152:155]
	v_mfma_f32_16x16x32_bf16 v[156:159], v[104:107], v[184:187], v[156:159]
	v_mfma_f32_16x16x32_bf16 v[160:163], v[112:115], v[184:187], v[160:163]
	v_mfma_f32_16x16x32_bf16 v[0:3], v[108:111], v[196:199], v[0:3]
	v_mfma_f32_16x16x32_bf16 v[4:7], v[112:115], v[192:195], v[4:7]
	v_mfma_f32_16x16x32_bf16 v[140:143], v[108:111], v[36:39], v[140:143]
	v_mfma_f32_16x16x32_bf16 v[144:147], v[116:119], v[36:39], v[144:147]
	v_mfma_f32_16x16x32_bf16 v[148:151], v[108:111], v[180:183], v[148:151]
	v_mfma_f32_16x16x32_bf16 v[152:155], v[116:119], v[180:183], v[152:155]
	v_mfma_f32_16x16x32_bf16 v[156:159], v[108:111], v[188:191], v[156:159]
	v_mfma_f32_16x16x32_bf16 v[160:163], v[116:119], v[188:191], v[160:163]
	v_mfma_f32_16x16x32_bf16 v[200:203], v[116:119], v[196:199], v[4:7]
	v_mfma_f32_16x16x32_bf16 v[4:7], v[120:123], v[32:35], v[8:11]
	v_mfma_f32_16x16x32_bf16 v[8:11], v[124:127], v[36:39], v[4:7]
	v_mfma_f32_16x16x32_bf16 v[4:7], v[164:167], v[32:35], v[12:15]
	v_mfma_f32_16x16x32_bf16 v[12:15], v[168:171], v[36:39], v[4:7]
	v_mfma_f32_16x16x32_bf16 v[4:7], v[120:123], v[96:99], v[24:27]
	v_mfma_f32_16x16x32_bf16 v[24:27], v[124:127], v[180:183], v[4:7]
	v_mfma_f32_16x16x32_bf16 v[4:7], v[164:167], v[96:99], v[28:31]
	v_mfma_f32_16x16x32_bf16 v[28:31], v[168:171], v[180:183], v[4:7]
	v_mfma_f32_16x16x32_bf16 v[4:7], v[120:123], v[184:187], v[60:63]
	v_mfma_f32_16x16x32_bf16 v[180:183], v[124:127], v[188:191], v[4:7]
	v_mfma_f32_16x16x32_bf16 v[4:7], v[164:167], v[184:187], v[100:103]
	v_mfma_f32_16x16x32_bf16 v[184:187], v[168:171], v[188:191], v[4:7]
	v_mfma_f32_16x16x32_bf16 v[4:7], v[120:123], v[192:195], v[16:19]
	v_mfma_f32_16x16x32_bf16 v[188:191], v[124:127], v[196:199], v[4:7]
	v_mfma_f32_16x16x32_bf16 v[4:7], v[164:167], v[192:195], v[20:23]
	v_mfma_f32_16x16x32_bf16 v[164:167], v[168:171], v[196:199], v[4:7]
	s_barrier
	s_nop 4
	ds_read_b128 v[4:7], v137
	ds_read_b128 v[60:63], v137 offset:1024
	ds_read_b128 v[168:171], v137 offset:2048
	ds_read_b128 v[192:195], v137 offset:3072
	ds_read_b128 v[196:199], v138
	ds_read_b128 v[208:211], v138 offset:1024
	ds_read_b128 v[212:215], v138 offset:2048
	ds_read_b128 v[216:219], v138 offset:3072
	s_add_u32 s44, s44, 0x10000
	s_addc_u32 s45, s45, 0
	s_mov_b32 m0, s90
	v_lshl_add_u64 v[32:33], s[44:45], 0, v[130:131]
	ds_read_b128 v[16:19], v136 offset:32768
	ds_read_b128 v[20:23], v136 offset:33792
	ds_read_b128 v[104:107], v136 offset:34816
	ds_read_b128 v[220:223], v136 offset:35840
	ds_read_b128 v[224:227], v136 offset:36864
	ds_read_b128 v[228:231], v136 offset:37888
	ds_read_b128 v[232:235], v136 offset:38912
	ds_read_b128 v[236:239], v136 offset:39936
	global_load_lds_dwordx4 v[32:33], off
	v_lshl_add_u64 v[32:33], s[44:45], 0, v[128:129]
	s_mov_b32 m0, s43
	s_nop 0
	global_load_lds_dwordx4 v[32:33], off
	s_waitcnt vmcnt(8)
	s_waitcnt lgkmcnt(0)
	s_barrier
	s_waitcnt lgkmcnt(0)
	v_mfma_f32_16x16x32_bf16 v[32:35], v[4:7], v[16:19], v[64:67]
	v_mfma_f32_16x16x32_bf16 v[116:119], v[60:63], v[20:23], v[32:35]
	v_mfma_f32_16x16x32_bf16 v[32:35], v[168:171], v[16:19], v[68:71]
	v_mfma_f32_16x16x32_bf16 v[112:115], v[192:195], v[20:23], v[32:35]
	v_mfma_f32_16x16x32_bf16 v[32:35], v[4:7], v[104:107], v[72:75]
	v_mfma_f32_16x16x32_bf16 v[100:103], v[60:63], v[220:223], v[32:35]
	v_mfma_f32_16x16x32_bf16 v[32:35], v[168:171], v[104:107], v[76:79]
	v_mfma_f32_16x16x32_bf16 v[96:99], v[192:195], v[220:223], v[32:35]
	v_mfma_f32_16x16x32_bf16 v[32:35], v[4:7], v[224:227], v[80:83]
	v_mfma_f32_16x16x32_bf16 v[68:71], v[60:63], v[228:231], v[32:35]
	v_mfma_f32_16x16x32_bf16 v[32:35], v[168:171], v[224:227], v[84:87]
	v_mfma_f32_16x16x32_bf16 v[64:67], v[192:195], v[228:231], v[32:35]
	v_mfma_f32_16x16x32_bf16 v[32:35], v[4:7], v[232:235], v[88:91]
	v_mfma_f32_16x16x32_bf16 v[36:39], v[60:63], v[236:239], v[32:35]
	v_mfma_f32_16x16x32_bf16 v[32:35], v[168:171], v[232:235], v[92:95]
	v_mfma_f32_16x16x32_bf16 v[32:35], v[192:195], v[236:239], v[32:35]
	v_mfma_f32_16x16x32_bf16 v[72:75], v[196:199], v[16:19], v[204:207]
	v_mfma_f32_16x16x32_bf16 v[16:19], v[212:215], v[16:19], v[172:175]
	v_mfma_f32_16x16x32_bf16 v[120:123], v[216:219], v[20:23], v[16:19]
	v_mfma_f32_16x16x32_bf16 v[16:19], v[196:199], v[104:107], v[176:179]
	v_mfma_f32_16x16x32_bf16 v[108:111], v[208:211], v[220:223], v[16:19]
	v_mfma_f32_16x16x32_bf16 v[16:19], v[212:215], v[104:107], v[40:43]
	v_mfma_f32_16x16x32_bf16 v[104:107], v[216:219], v[220:223], v[16:19]
	v_mfma_f32_16x16x32_bf16 v[16:19], v[196:199], v[224:227], v[44:47]
	v_mfma_f32_16x16x32_bf16 v[80:83], v[208:211], v[228:231], v[16:19]
	v_mfma_f32_16x16x32_bf16 v[16:19], v[212:215], v[224:227], v[48:51]
	v_mfma_f32_16x16x32_bf16 v[124:127], v[208:211], v[20:23], v[72:75]
	v_mfma_f32_16x16x32_bf16 v[72:75], v[216:219], v[228:231], v[16:19]
	v_mfma_f32_16x16x32_bf16 v[16:19], v[196:199], v[232:235], v[52:55]
	v_mfma_f32_16x16x32_bf16 v[48:51], v[208:211], v[236:239], v[16:19]
	v_mfma_f32_16x16x32_bf16 v[16:19], v[212:215], v[232:235], v[56:59]
	v_mfma_f32_16x16x32_bf16 v[40:43], v[216:219], v[236:239], v[16:19]
	s_barrier
; #define PG8_STAGE(bufoff, gbase, voff) do { _Pragma("unroll") for (int _i = 0; _i < 2; ++_i) \
;         __builtin_amdgcn_global_load_lds((const unsigned*)((const char*)(gbase) + (voff)[_i]), (PG8_LAS unsigned*)(lds + (bufoff) + ldsw + _i * 8192), 16, 0, 0); } while (0)
; #define PG8_LDA(dst, b, h) do { _Pragma("unroll") for (int m = 0; m < 4; ++m) _Pragma("unroll") for (int k = 0; k < 2; ++k) dst[m][k] = *(const PG8_LAS bf16x8*)(lds + PG8_SA(b, h) + aoff + m * 2048 + k * 1024); } while (0)
; #define PG8_MMA(ai, bj, At, Bt) do { __builtin_amdgcn_s_setprio(1); _Pragma("unroll") for (int m = 0; m < 4; ++m) _Pragma("unroll") for (int n = 0; n < 2; ++n) _Pragma("unroll") for (int k = 0; k < 2; ++k) \
;         acc[ai][bj][m][n] = mma16<F16>(Bt[n][k], At[m][k], acc[ai][bj][m][n]); __builtin_amdgcn_s_setprio(0); } while (0)
; #define PG8_WAIT_V(n) asm volatile("s_waitcnt vmcnt(" #n ")" ::: "memory")
; #define PG8_WAIT_L(n) asm volatile("s_waitcnt lgkmcnt(" #n ")" ::: "memory")
; #define PG8_BAR __builtin_amdgcn_s_barrier()
; #define PG8_SCHED __builtin_amdgcn_sched_barrier(0)
; template <class Epi, class Sched, bool ALIGN_EPI = false, bool SP2 = false, bool F16 = false>
; __device__ __forceinline__ void gemm_phase(PG8_LAS unsigned char* lds, const Gemm g, const Sched& S, const Epi& E, const int wid_in) {
;     ...
;             PG8_LDA(At, 1, 1); PG8_STAGE(PG8_SB(1, 0), b3, voffB); PG8_STAGE(PG8_SB(1, 1), b3 + hstep, voffB); PG8_STAGE(PG8_SA(1, 0), a3, voffA);
;             PG8_WAIT_V(8); PG8_WAIT_L(0); PG8_BAR; PG8_MMA(1, 0, At, B0); PG8_MMA(1, 1, At, B1); PG8_BAR; PG8_SCHED;
;     ...
;         if constexpr (ALIGN_EPI) { if (wr == 0) PG8_BAR; }
	s_mov_b32 m0, s53
	s_nop 3
	v_lshl_add_u64 v[16:17], v[240:241], 0, s[24:25]
	s_add_u32 s36, s36, 0x10080
	ds_read_b128 v[56:59], v136 offset:49152
	ds_read_b128 v[88:91], v136 offset:50176
	ds_read_b128 v[172:175], v136 offset:51200
	ds_read_b128 v[176:179], v136 offset:52224
	ds_read_b128 v[204:207], v136 offset:53248
	ds_read_b128 v[220:223], v136 offset:54272
	ds_read_b128 v[224:227], v136 offset:55296
	ds_read_b128 v[228:231], v136 offset:56320
	global_load_lds_dwordx4 v[16:17], off
	v_lshl_add_u64 v[16:17], v[242:243], 0, s[24:25]
	s_mov_b32 m0, s54
	s_addc_u32 s37, s37, 0
	global_load_lds_dwordx4 v[16:17], off
	v_lshl_add_u64 v[16:17], s[36:37], 0, v[130:131]
	s_mov_b32 m0, s55
	s_nop 0
	global_load_lds_dwordx4 v[16:17], off
	v_lshl_add_u64 v[16:17], s[36:37], 0, v[128:129]
	s_mov_b32 m0, s56
	s_nop 0
	global_load_lds_dwordx4 v[16:17], off
	v_lshl_add_u64 v[16:17], v[244:245], 0, s[24:25]
	s_mov_b32 m0, s75
	s_nop 0
	global_load_lds_dwordx4 v[16:17], off
	v_lshl_add_u64 v[16:17], v[246:247], 0, s[24:25]
	s_mov_b32 m0, s67
	s_nop 0
	global_load_lds_dwordx4 v[16:17], off
	s_waitcnt vmcnt(8)
	s_waitcnt lgkmcnt(0)
	s_barrier
	s_waitcnt lgkmcnt(0)
	v_mfma_f32_16x16x32_bf16 v[16:19], v[4:7], v[56:59], v[140:143]
	v_mfma_f32_16x16x32_bf16 v[84:87], v[60:63], v[88:91], v[16:19]
	v_mfma_f32_16x16x32_bf16 v[16:19], v[168:171], v[56:59], v[144:147]
	v_mfma_f32_16x16x32_bf16 v[76:79], v[192:195], v[88:91], v[16:19]
	v_mfma_f32_16x16x32_bf16 v[16:19], v[4:7], v[172:175], v[148:151]
	v_mfma_f32_16x16x32_bf16 v[52:55], v[60:63], v[176:179], v[16:19]
	v_mfma_f32_16x16x32_bf16 v[16:19], v[168:171], v[172:175], v[152:155]
	v_mfma_f32_16x16x32_bf16 v[44:47], v[192:195], v[176:179], v[16:19]
	v_mfma_f32_16x16x32_bf16 v[16:19], v[4:7], v[204:207], v[156:159]
	v_mfma_f32_16x16x32_bf16 v[0:3], v[4:7], v[224:227], v[0:3]
	v_mfma_f32_16x16x32_bf16 v[20:23], v[60:63], v[220:223], v[16:19]
	v_mfma_f32_16x16x32_bf16 v[16:19], v[168:171], v[204:207], v[160:163]
	v_mfma_f32_16x16x32_bf16 v[4:7], v[60:63], v[228:231], v[0:3]
	v_mfma_f32_16x16x32_bf16 v[0:3], v[168:171], v[224:227], v[200:203]
	v_mfma_f32_16x16x32_bf16 v[16:19], v[192:195], v[220:223], v[16:19]
	v_mfma_f32_16x16x32_bf16 v[0:3], v[192:195], v[228:231], v[0:3]
	v_mfma_f32_16x16x32_bf16 v[8:11], v[196:199], v[56:59], v[8:11]
	v_mfma_f32_16x16x32_bf16 v[92:95], v[208:211], v[88:91], v[8:11]
	v_mfma_f32_16x16x32_bf16 v[8:11], v[212:215], v[56:59], v[12:15]
	v_mfma_f32_16x16x32_bf16 v[88:91], v[216:219], v[88:91], v[8:11]
	v_mfma_f32_16x16x32_bf16 v[8:11], v[196:199], v[172:175], v[24:27]
	v_mfma_f32_16x16x32_bf16 v[60:63], v[208:211], v[176:179], v[8:11]
	v_mfma_f32_16x16x32_bf16 v[8:11], v[212:215], v[172:175], v[28:31]
	v_mfma_f32_16x16x32_bf16 v[56:59], v[216:219], v[176:179], v[8:11]
	v_mfma_f32_16x16x32_bf16 v[8:11], v[196:199], v[204:207], v[180:183]
	v_mfma_f32_16x16x32_bf16 v[28:31], v[208:211], v[220:223], v[8:11]
	v_mfma_f32_16x16x32_bf16 v[8:11], v[212:215], v[204:207], v[184:187]
	v_mfma_f32_16x16x32_bf16 v[24:27], v[216:219], v[220:223], v[8:11]
	v_mfma_f32_16x16x32_bf16 v[8:11], v[196:199], v[224:227], v[188:191]
	v_mfma_f32_16x16x32_bf16 v[12:15], v[208:211], v[228:231], v[8:11]
	v_mfma_f32_16x16x32_bf16 v[8:11], v[212:215], v[224:227], v[164:167]
	v_mfma_f32_16x16x32_bf16 v[8:11], v[216:219], v[228:231], v[8:11]
	s_barrier
	s_and_b64 vcc, exec, s[8:9]
	s_cbranch_vccnz .LBB0_1946
	s_barrier
; __device__ __forceinline__ unsigned cvt_pk_bf16(float lo, float hi) { const f32x2cv v = {lo, hi}; const bf16x2cv b = __builtin_convertvector(v, bf16x2cv); return __builtin_bit_cast(unsigned, b); }
; #define PG8_BAR __builtin_amdgcn_s_barrier()
;     __device__ __forceinline__ void operator()(const f32x4 (&acc)[2][2][4][2], const Unit& u, int wr, int wc, int fr, int fq) const {
;     ...
;         const int col0 = u.pn * BM + wc * 32 + 4 * fq;
; #pragma unroll
;         for (int ai = 0; ai < 2; ++ai)
; #pragma unroll
;             for (int m = 0; m < 4; ++m) { const int row = u.pm * BM + ai * HALF + wr * 64 + m * 16 + fr; const size_t off = (size_t)row * 1024 + col0;
; #pragma unroll
;                 for (int bj = 0; bj < 2; ++bj)
; #pragma unroll
;                     for (int n = 0; n < 2; ++n) { const f32x4 a = acc[ai][bj][m][n]; u32x2 w; w.x = cvt_pk_bf16(a[0], a[1]); w.y = cvt_pk_bf16(a[2], a[3]); *(u32x2*)(hb_ptr(off + bj * HALF + n * 16)) = w; } }
; template <class Epi, class Sched, bool ALIGN_EPI = false, bool SP2 = false, bool F16 = false>
; __device__ __forceinline__ void gemm_phase(PG8_LAS unsigned char* lds, const Gemm g, const Sched& S, const Epi& E, const int wid_in) {
;     ...
;         if constexpr (!Epi::AFTER_DRAIN) { E(acc, cur, wr, wc, fr, fq); S.done(cur); }
;         if (!has_next) break;
; #pragma unroll
;         for (int a = 0; a < 2; ++a)
; #pragma unroll
;             for (int b = 0; b < 2; ++b)
; #pragma unroll
;                 for (int m = 0; m < 4; ++m)
; #pragma unroll
;                     for (int n = 0; n < 2; ++n) acc[a][b][m][n] = (f32x4){0.f, 0.f, 0.f, 0.f};
;         cur = nxt; cA = nA; cB = nB; ++ui;
;         if constexpr (ALIGN_EPI) { if (wr == 1) PG8_BAR; }
;     }
.LBB0_1946:
	s_lshl_b32 s34, s34, 8
	v_mov_b32_e32 v139, v132
	v_mov_b32_e32 v140, v133
	s_lshl_b32 s35, s59, 8
	s_add_i32 s34, s34, s70
	s_or_b32 s35, s35, s82
	v_add_u32_e32 v142, s34, v139
	v_lshl_add_u32 v140, v140, 2, s35
	v_ashrrev_i32_e32 v143, 31, v142
	v_ashrrev_i32_e32 v141, 31, v140
	v_lshlrev_b64 v[144:145], 11, v[142:143]
	v_cvt_pk_bf16_f32 v116, v116, v117
	v_cvt_pk_bf16_f32 v117, v118, v119
	v_lshl_add_u64 v[118:119], s[22:23], 0, v[144:145]
	v_lshlrev_b64 v[140:141], 1, v[140:141]
	v_lshl_add_u64 v[118:119], v[118:119], 0, v[140:141]
	v_cvt_pk_bf16_f32 v112, v112, v113
	v_cvt_pk_bf16_f32 v113, v114, v115
	global_store_dwordx2 v[118:119], v[112:113], off offset:32
	v_cvt_pk_bf16_f32 v112, v124, v125
	v_cvt_pk_bf16_f32 v113, v126, v127
	global_store_dwordx2 v[118:119], v[112:113], off offset:256
	v_cvt_pk_bf16_f32 v112, v120, v121
	v_cvt_pk_bf16_f32 v113, v122, v123
	global_store_dwordx2 v[118:119], v[112:113], off offset:288
	v_add_u32_e32 v112, 16, v142
	v_ashrrev_i32_e32 v113, 31, v112
	v_lshlrev_b64 v[112:113], 11, v[112:113]
	v_cvt_pk_bf16_f32 v100, v100, v101
	v_cvt_pk_bf16_f32 v101, v102, v103
	v_lshl_add_u64 v[102:103], s[22:23], 0, v[112:113]
	v_lshl_add_u64 v[102:103], v[102:103], 0, v[140:141]
	v_cvt_pk_bf16_f32 v96, v96, v97
	v_cvt_pk_bf16_f32 v97, v98, v99
	global_store_dwordx2 v[102:103], v[96:97], off offset:32
	v_cvt_pk_bf16_f32 v96, v108, v109
	v_cvt_pk_bf16_f32 v97, v110, v111
	global_store_dwordx2 v[102:103], v[96:97], off offset:256
	v_cvt_pk_bf16_f32 v96, v104, v105
	v_cvt_pk_bf16_f32 v97, v106, v107
	global_store_dwordx2 v[102:103], v[96:97], off offset:288
	v_add_u32_e32 v96, 32, v142
	v_ashrrev_i32_e32 v97, 31, v96
	v_lshlrev_b64 v[96:97], 11, v[96:97]
	v_cvt_pk_bf16_f32 v68, v68, v69
	v_cvt_pk_bf16_f32 v69, v70, v71
	v_lshl_add_u64 v[70:71], s[22:23], 0, v[96:97]
	v_lshl_add_u64 v[70:71], v[70:71], 0, v[140:141]
	v_cvt_pk_bf16_f32 v64, v64, v65
	v_cvt_pk_bf16_f32 v65, v66, v67
	global_store_dwordx2 v[70:71], v[64:65], off offset:32
	v_cvt_pk_bf16_f32 v64, v80, v81
	v_cvt_pk_bf16_f32 v65, v82, v83
	global_store_dwordx2 v[70:71], v[64:65], off offset:256
	v_cvt_pk_bf16_f32 v64, v72, v73
	v_cvt_pk_bf16_f32 v65, v74, v75
	global_store_dwordx2 v[70:71], v[64:65], off offset:288
	v_add_u32_e32 v64, 48, v142
	v_ashrrev_i32_e32 v65, 31, v64
	v_lshlrev_b64 v[64:65], 11, v[64:65]
	v_cvt_pk_bf16_f32 v36, v36, v37
	v_cvt_pk_bf16_f32 v37, v38, v39
	v_lshl_add_u64 v[38:39], s[22:23], 0, v[64:65]
	v_lshl_add_u64 v[38:39], v[38:39], 0, v[140:141]
	v_cvt_pk_bf16_f32 v32, v32, v33
	v_cvt_pk_bf16_f32 v33, v34, v35
	global_store_dwordx2 v[38:39], v[32:33], off offset:32
	v_cvt_pk_bf16_f32 v32, v48, v49
	v_cvt_pk_bf16_f32 v33, v50, v51
	global_store_dwordx2 v[38:39], v[32:33], off offset:256
	v_cvt_pk_bf16_f32 v32, v40, v41
	v_cvt_pk_bf16_f32 v33, v42, v43
	global_store_dwordx2 v[38:39], v[32:33], off offset:288
	v_add_u32_e32 v32, 0x80, v142
	v_ashrrev_i32_e32 v33, 31, v32
	v_lshlrev_b64 v[32:33], 11, v[32:33]
	v_lshl_add_u64 v[32:33], s[22:23], 0, v[32:33]
	v_cvt_pk_bf16_f32 v34, v84, v85
	v_cvt_pk_bf16_f32 v35, v86, v87
	v_lshl_add_u64 v[32:33], v[32:33], 0, v[140:141]
	global_store_dwordx2 v[32:33], v[34:35], off
	v_cvt_pk_bf16_f32 v34, v76, v77
	v_cvt_pk_bf16_f32 v35, v78, v79
	global_store_dwordx2 v[32:33], v[34:35], off offset:32
	v_cvt_pk_bf16_f32 v34, v92, v93
	v_cvt_pk_bf16_f32 v35, v94, v95
	global_store_dwordx2 v[32:33], v[34:35], off offset:256
	v_cvt_pk_bf16_f32 v34, v88, v89
	v_cvt_pk_bf16_f32 v35, v90, v91
	global_store_dwordx2 v[32:33], v[34:35], off offset:288
	v_add_u32_e32 v32, 0x90, v142
	v_ashrrev_i32_e32 v33, 31, v32
	v_lshlrev_b64 v[32:33], 11, v[32:33]
	v_lshl_add_u64 v[32:33], s[22:23], 0, v[32:33]
	v_cvt_pk_bf16_f32 v34, v52, v53
	v_cvt_pk_bf16_f32 v35, v54, v55
	v_lshl_add_u64 v[32:33], v[32:33], 0, v[140:141]
	global_store_dwordx2 v[32:33], v[34:35], off
	v_cvt_pk_bf16_f32 v34, v44, v45
	v_cvt_pk_bf16_f32 v35, v46, v47
	global_store_dwordx2 v[32:33], v[34:35], off offset:32
	v_cvt_pk_bf16_f32 v34, v60, v61
	v_cvt_pk_bf16_f32 v35, v62, v63
	global_store_dwordx2 v[32:33], v[34:35], off offset:256
	v_cvt_pk_bf16_f32 v34, v56, v57
	v_cvt_pk_bf16_f32 v35, v58, v59
	global_store_dwordx2 v[32:33], v[34:35], off offset:288
	v_add_u32_e32 v32, 0xa0, v142
	v_ashrrev_i32_e32 v33, 31, v32
	v_lshlrev_b64 v[32:33], 11, v[32:33]
	v_cvt_pk_bf16_f32 v20, v20, v21
	v_cvt_pk_bf16_f32 v21, v22, v23
	v_lshl_add_u64 v[22:23], s[22:23], 0, v[32:33]
	v_lshl_add_u64 v[22:23], v[22:23], 0, v[140:141]
	v_cvt_pk_bf16_f32 v16, v16, v17
	v_cvt_pk_bf16_f32 v17, v18, v19
	global_store_dwordx2 v[22:23], v[16:17], off offset:32
	v_cvt_pk_bf16_f32 v16, v28, v29
	v_cvt_pk_bf16_f32 v17, v30, v31
	global_store_dwordx2 v[22:23], v[16:17], off offset:256
	v_cvt_pk_bf16_f32 v16, v24, v25
	v_cvt_pk_bf16_f32 v17, v26, v27
	global_store_dwordx2 v[22:23], v[16:17], off offset:288
	v_add_u32_e32 v16, 0xb0, v142
	v_ashrrev_i32_e32 v17, 31, v16
	v_lshlrev_b64 v[16:17], 11, v[16:17]
	v_cvt_pk_bf16_f32 v4, v4, v5
	v_cvt_pk_bf16_f32 v5, v6, v7
	v_lshl_add_u64 v[6:7], s[22:23], 0, v[16:17]
	v_lshl_add_u64 v[6:7], v[6:7], 0, v[140:141]
	v_cvt_pk_bf16_f32 v0, v0, v1
	v_cvt_pk_bf16_f32 v1, v2, v3
	global_store_dwordx2 v[6:7], v[0:1], off offset:32
	v_cvt_pk_bf16_f32 v0, v12, v13
	v_cvt_pk_bf16_f32 v1, v14, v15
	global_store_dwordx2 v[6:7], v[0:1], off offset:256
	v_cvt_pk_bf16_f32 v0, v8, v9
	v_cvt_pk_bf16_f32 v1, v10, v11
	s_andn2_b64 vcc, exec, s[30:31]
	s_mov_b64 s[34:35], -1
	global_store_dwordx2 v[118:119], v[116:117], off
	global_store_dwordx2 v[102:103], v[100:101], off
	global_store_dwordx2 v[70:71], v[68:69], off
	global_store_dwordx2 v[38:39], v[36:37], off
	global_store_dwordx2 v[22:23], v[20:21], off
	global_store_dwordx2 v[6:7], v[4:5], off
	global_store_dwordx2 v[6:7], v[0:1], off offset:288
	s_cbranch_vccnz .LBB0_1943
	s_setprio 0
	s_and_b64 vcc, exec, s[6:7]
	s_cbranch_vccnz .LBB0_1942
	s_barrier
	s_branch .LBB0_1942

; #define PG8_STAGE(bufoff, gbase, voff) do { _Pragma("unroll") for (int _i = 0; _i < 2; ++_i) \
;         __builtin_amdgcn_global_load_lds((const unsigned*)((const char*)(gbase) + (voff)[_i]), (PG8_LAS unsigned*)(lds + (bufoff) + ldsw + _i * 8192), 16, 0, 0); } while (0)
; #define PG8_LDA(dst, b, h) do { _Pragma("unroll") for (int m = 0; m < 4; ++m) _Pragma("unroll") for (int k = 0; k < 2; ++k) dst[m][k] = *(const PG8_LAS bf16x8*)(lds + PG8_SA(b, h) + aoff + m * 2048 + k * 1024); } while (0)
; #define PG8_LDB(dst, b, h) do { _Pragma("unroll") for (int n = 0; n < 2; ++n) _Pragma("unroll") for (int k = 0; k < 2; ++k) dst[n][k] = *(const PG8_LAS bf16x8*)(lds + PG8_SB(b, h) + boff + n * 2048 + k * 1024); } while (0)
; #define PG8_WAIT_V(n) asm volatile("s_waitcnt vmcnt(" #n ")" ::: "memory")
; #define PG8_WAIT_L(n) asm volatile("s_waitcnt lgkmcnt(" #n ")" ::: "memory")
; #define PG8_BAR __builtin_amdgcn_s_barrier()
; template <class Epi, class Sched, bool ALIGN_EPI = false, bool SP2 = false, bool F16 = false>
; __device__ __forceinline__ void gemm_phase(PG8_LAS unsigned char* lds, const Gemm g, const Sched& S, const Epi& E, const int wid_in) {
;     ...
;         const bool has_next = S.next(ui + 1, nxt);
;         const char* nA = has_next ? (const char*)g.A + (size_t)nxt.pm * tstep : cA; const char* nB = has_next ? (const char*)g.Bt + (size_t)nxt.pn * tstep : cB;
;         for (int t = 0; t < nt; t += 2) {
;             const bool last = (t == nt - 2);
;             const char* a1 = cA + (size_t)(t + 1) * kstep;
;             const char* a2 = last ? nA : cA + (size_t)(t + 2) * kstep; const char* b2 = last ? nB : cB + (size_t)(t + 2) * kstep;
;             const char* a3 = a2 + kstep; const char* b3 = b2 + kstep;
;             if (last && has_next) S.a_ready(nxt);
;             if constexpr (SP2) {
;             PG8_LDB(B0, 0, 0); PG8_LDB(B1, 0, 1); PG8_SCHED; PG8_LDA(At, 0, 0); PG8_STAGE(PG8_SA(1, 1), a1 + hstep, voffA);
;             PG8_WAIT_V(8); PG8_WAIT_L(0); PG8_BAR; PG8_MMA(0, 0, At, B0); PG8_MMA(0, 1, At, B1); PG8_BAR; PG8_SCHED;
;     ...
; #pragma unroll
;         for (int a = 0; a < 2; ++a)
; #pragma unroll
;             for (int b = 0; b < 2; ++b)
; #pragma unroll
;                 for (int m = 0; m < 4; ++m)
; #pragma unroll
;                     for (int n = 0; n < 2; ++n) acc[a][b][m][n] = (f32x4){0.f, 0.f, 0.f, 0.f};
.LBB0_2039:
	s_add_u32 s43, s44, 0x100
	v_mov_b32_e32 v0, 0
	s_addc_u32 s58, s45, 0
	s_mov_b32 s59, -2
	v_mov_b32_e32 v1, v0
	v_mov_b32_e32 v2, v0
	v_mov_b32_e32 v3, v0
	v_mov_b32_e32 v4, v0
	v_mov_b32_e32 v5, v0
	v_mov_b32_e32 v6, v0
	v_mov_b32_e32 v7, v0
	v_mov_b32_e32 v16, v0
	v_mov_b32_e32 v17, v0
	v_mov_b32_e32 v18, v0
	v_mov_b32_e32 v19, v0
	v_mov_b32_e32 v20, v0
	v_mov_b32_e32 v21, v0
	v_mov_b32_e32 v22, v0
	v_mov_b32_e32 v23, v0
	v_mov_b32_e32 v32, v0
	v_mov_b32_e32 v33, v0
	v_mov_b32_e32 v34, v0
	v_mov_b32_e32 v35, v0
	v_mov_b32_e32 v36, v0
	v_mov_b32_e32 v37, v0
	v_mov_b32_e32 v38, v0
	v_mov_b32_e32 v39, v0
	v_mov_b32_e32 v48, v0
	v_mov_b32_e32 v49, v0
	v_mov_b32_e32 v50, v0
	v_mov_b32_e32 v51, v0
	v_mov_b32_e32 v52, v0
	v_mov_b32_e32 v53, v0
	v_mov_b32_e32 v54, v0
	v_mov_b32_e32 v55, v0
	v_mov_b32_e32 v8, v0
	v_mov_b32_e32 v9, v0
	v_mov_b32_e32 v10, v0
	v_mov_b32_e32 v11, v0
	v_mov_b32_e32 v12, v0
	v_mov_b32_e32 v13, v0
	v_mov_b32_e32 v14, v0
	v_mov_b32_e32 v15, v0
	v_mov_b32_e32 v24, v0
	v_mov_b32_e32 v25, v0
	v_mov_b32_e32 v26, v0
	v_mov_b32_e32 v27, v0
	v_mov_b32_e32 v28, v0
	v_mov_b32_e32 v29, v0
	v_mov_b32_e32 v30, v0
	v_mov_b32_e32 v31, v0
	v_mov_b32_e32 v40, v0
	v_mov_b32_e32 v41, v0
	v_mov_b32_e32 v42, v0
	v_mov_b32_e32 v43, v0
	v_mov_b32_e32 v44, v0
	v_mov_b32_e32 v45, v0
	v_mov_b32_e32 v46, v0
	v_mov_b32_e32 v47, v0
	v_mov_b32_e32 v56, v0
	v_mov_b32_e32 v57, v0
	v_mov_b32_e32 v58, v0
	v_mov_b32_e32 v59, v0
	v_mov_b32_e32 v60, v0
	v_mov_b32_e32 v61, v0
	v_mov_b32_e32 v62, v0
	v_mov_b32_e32 v63, v0
	v_mov_b32_e32 v64, v0
	v_mov_b32_e32 v65, v0
	v_mov_b32_e32 v66, v0
	v_mov_b32_e32 v67, v0
	v_mov_b32_e32 v68, v0
	v_mov_b32_e32 v69, v0
	v_mov_b32_e32 v70, v0
	v_mov_b32_e32 v71, v0
	v_mov_b32_e32 v80, v0
	v_mov_b32_e32 v81, v0
	v_mov_b32_e32 v82, v0
	v_mov_b32_e32 v83, v0
	v_mov_b32_e32 v84, v0
	v_mov_b32_e32 v85, v0
	v_mov_b32_e32 v86, v0
	v_mov_b32_e32 v87, v0
	v_mov_b32_e32 v96, v0
	v_mov_b32_e32 v97, v0
	v_mov_b32_e32 v98, v0
	v_mov_b32_e32 v99, v0
	v_mov_b32_e32 v100, v0
	v_mov_b32_e32 v101, v0
	v_mov_b32_e32 v102, v0
	v_mov_b32_e32 v103, v0
	v_mov_b32_e32 v112, v0
	v_mov_b32_e32 v113, v0
	v_mov_b32_e32 v114, v0
	v_mov_b32_e32 v115, v0
	v_mov_b32_e32 v116, v0
	v_mov_b32_e32 v117, v0
	v_mov_b32_e32 v118, v0
	v_mov_b32_e32 v119, v0
	v_mov_b32_e32 v72, v0
	v_mov_b32_e32 v73, v0
	v_mov_b32_e32 v74, v0
	v_mov_b32_e32 v75, v0
	v_mov_b32_e32 v76, v0
	v_mov_b32_e32 v77, v0
	v_mov_b32_e32 v78, v0
	v_mov_b32_e32 v79, v0
	v_mov_b32_e32 v88, v0
	v_mov_b32_e32 v89, v0
	v_mov_b32_e32 v90, v0
	v_mov_b32_e32 v91, v0
	v_mov_b32_e32 v92, v0
	v_mov_b32_e32 v93, v0
	v_mov_b32_e32 v94, v0
	v_mov_b32_e32 v95, v0
	v_mov_b32_e32 v104, v0
	v_mov_b32_e32 v105, v0
	v_mov_b32_e32 v106, v0
	v_mov_b32_e32 v107, v0
	v_mov_b32_e32 v108, v0
	v_mov_b32_e32 v109, v0
	v_mov_b32_e32 v110, v0
	v_mov_b32_e32 v111, v0
	v_mov_b32_e32 v120, v0
	v_mov_b32_e32 v121, v0
	v_mov_b32_e32 v122, v0
	v_mov_b32_e32 v123, v0
	v_mov_b32_e32 v124, v0
	v_mov_b32_e32 v125, v0
	v_mov_b32_e32 v126, v0
	v_mov_b32_e32 v127, v0
	s_cmp_ge_u32 s3, 4
	s_cbranch_scc0 .Lgsp_16
	s_setprio 1
.Lgsp_16:
.LBB0_2040:
	ds_read_b128 v[128:131], v189
	ds_read_b128 v[132:135], v189 offset:1024
	ds_read_b128 v[136:139], v189 offset:2048
	ds_read_b128 v[140:143], v189 offset:3072
	ds_read_b128 v[144:147], v190
	ds_read_b128 v[148:151], v190 offset:1024
	ds_read_b128 v[168:171], v190 offset:2048
	ds_read_b128 v[172:175], v190 offset:3072
	s_add_u32 s44, s36, 0x100
	s_addc_u32 s45, s37, 0
	s_cmp_eq_u32 s59, 40
	s_cselect_b32 s49, s13, s45
	s_cselect_b32 s48, s12, s44
	s_cselect_b32 s47, s35, s58
	s_cselect_b32 s46, s34, s43
	s_mov_b32 m0, s91
	v_lshl_add_u64 v[184:185], s[36:37], 0, v[160:161]
	ds_read_b128 v[176:179], v191
	ds_read_b128 v[180:183], v191 offset:1024
	ds_read_b128 v[192:195], v191 offset:2048
	ds_read_b128 v[196:199], v191 offset:3072
	ds_read_b128 v[200:203], v191 offset:4096
	ds_read_b128 v[204:207], v191 offset:5120
	ds_read_b128 v[208:211], v191 offset:6144
	ds_read_b128 v[212:215], v191 offset:7168
	global_load_lds_dwordx4 v[184:185], off
	v_lshl_add_u64 v[184:185], s[36:37], 0, v[162:163]
	s_add_i32 m0, s74, 0xe000
	s_nop 0
	global_load_lds_dwordx4 v[184:185], off
	s_waitcnt vmcnt(8)
	s_waitcnt lgkmcnt(0)
	s_barrier
	s_waitcnt lgkmcnt(0)
	v_mfma_f32_16x16x32_bf16 v[124:127], v[128:131], v[176:179], v[124:127]
	v_mfma_f32_16x16x32_bf16 v[120:123], v[136:139], v[176:179], v[120:123]
	v_mfma_f32_16x16x32_bf16 v[108:111], v[128:131], v[192:195], v[108:111]
	v_mfma_f32_16x16x32_bf16 v[104:107], v[136:139], v[192:195], v[104:107]
	v_mfma_f32_16x16x32_bf16 v[92:95], v[128:131], v[200:203], v[92:95]
	v_mfma_f32_16x16x32_bf16 v[88:91], v[136:139], v[200:203], v[88:91]
	v_mfma_f32_16x16x32_bf16 v[76:79], v[128:131], v[208:211], v[76:79]
	v_mfma_f32_16x16x32_bf16 v[72:75], v[136:139], v[208:211], v[72:75]
	v_mfma_f32_16x16x32_bf16 v[124:127], v[132:135], v[180:183], v[124:127]
	v_mfma_f32_16x16x32_bf16 v[120:123], v[140:143], v[180:183], v[120:123]
	v_mfma_f32_16x16x32_bf16 v[108:111], v[132:135], v[196:199], v[108:111]
	v_mfma_f32_16x16x32_bf16 v[104:107], v[140:143], v[196:199], v[104:107]
	v_mfma_f32_16x16x32_bf16 v[92:95], v[132:135], v[204:207], v[92:95]
	v_mfma_f32_16x16x32_bf16 v[88:91], v[140:143], v[204:207], v[88:91]
	v_mfma_f32_16x16x32_bf16 v[76:79], v[132:135], v[212:215], v[76:79]
	v_mfma_f32_16x16x32_bf16 v[72:75], v[140:143], v[212:215], v[72:75]
	v_mfma_f32_16x16x32_bf16 v[116:119], v[144:147], v[176:179], v[116:119]
	v_mfma_f32_16x16x32_bf16 v[112:115], v[168:171], v[176:179], v[112:115]
	v_mfma_f32_16x16x32_bf16 v[100:103], v[144:147], v[192:195], v[100:103]
	v_mfma_f32_16x16x32_bf16 v[96:99], v[168:171], v[192:195], v[96:99]
	v_mfma_f32_16x16x32_bf16 v[84:87], v[144:147], v[200:203], v[84:87]
	v_mfma_f32_16x16x32_bf16 v[80:83], v[168:171], v[200:203], v[80:83]
	v_mfma_f32_16x16x32_bf16 v[68:71], v[144:147], v[208:211], v[68:71]
	v_mfma_f32_16x16x32_bf16 v[64:67], v[168:171], v[208:211], v[64:67]
	v_mfma_f32_16x16x32_bf16 v[116:119], v[148:151], v[180:183], v[116:119]
	v_mfma_f32_16x16x32_bf16 v[112:115], v[172:175], v[180:183], v[112:115]
	v_mfma_f32_16x16x32_bf16 v[100:103], v[148:151], v[196:199], v[100:103]
	v_mfma_f32_16x16x32_bf16 v[96:99], v[172:175], v[196:199], v[96:99]
	v_mfma_f32_16x16x32_bf16 v[84:87], v[148:151], v[204:207], v[84:87]
	v_mfma_f32_16x16x32_bf16 v[80:83], v[172:175], v[204:207], v[80:83]
	v_mfma_f32_16x16x32_bf16 v[68:71], v[148:151], v[212:215], v[68:71]
	v_mfma_f32_16x16x32_bf16 v[64:67], v[172:175], v[212:215], v[64:67]
	s_barrier
; #define PG8_STAGE(bufoff, gbase, voff) do { _Pragma("unroll") for (int _i = 0; _i < 2; ++_i) \
;         __builtin_amdgcn_global_load_lds((const unsigned*)((const char*)(gbase) + (voff)[_i]), (PG8_LAS unsigned*)(lds + (bufoff) + ldsw + _i * 8192), 16, 0, 0); } while (0)
; #define PG8_LDA(dst, b, h) do { _Pragma("unroll") for (int m = 0; m < 4; ++m) _Pragma("unroll") for (int k = 0; k < 2; ++k) dst[m][k] = *(const PG8_LAS bf16x8*)(lds + PG8_SA(b, h) + aoff + m * 2048 + k * 1024); } while (0)
; #define PG8_LDB(dst, b, h) do { _Pragma("unroll") for (int n = 0; n < 2; ++n) _Pragma("unroll") for (int k = 0; k < 2; ++k) dst[n][k] = *(const PG8_LAS bf16x8*)(lds + PG8_SB(b, h) + boff + n * 2048 + k * 1024); } while (0)
; #define PG8_MMA(ai, bj, At, Bt) do { __builtin_amdgcn_s_setprio(1); _Pragma("unroll") for (int m = 0; m < 4; ++m) _Pragma("unroll") for (int n = 0; n < 2; ++n) _Pragma("unroll") for (int k = 0; k < 2; ++k) \
;         acc[ai][bj][m][n] = mma16<F16>(Bt[n][k], At[m][k], acc[ai][bj][m][n]); __builtin_amdgcn_s_setprio(0); } while (0)
; #define PG8_WAIT_V(n) asm volatile("s_waitcnt vmcnt(" #n ")" ::: "memory")
; #define PG8_WAIT_L(n) asm volatile("s_waitcnt lgkmcnt(" #n ")" ::: "memory")
; #define PG8_BAR __builtin_amdgcn_s_barrier()
; #define PG8_SCHED __builtin_amdgcn_sched_barrier(0)
; template <class Epi, class Sched, bool ALIGN_EPI = false, bool SP2 = false, bool F16 = false>
; __device__ __forceinline__ void gemm_phase(PG8_LAS unsigned char* lds, const Gemm g, const Sched& S, const Epi& E, const int wid_in) {
;     ...
;             PG8_LDA(At, 0, 1); PG8_STAGE(PG8_SB(0, 0), b2, voffB); PG8_STAGE(PG8_SB(0, 1), b2 + hstep, voffB); PG8_STAGE(PG8_SA(0, 0), a2, voffA);
;             PG8_WAIT_V(8); PG8_WAIT_L(0); PG8_BAR; PG8_MMA(1, 0, At, B0); PG8_MMA(1, 1, At, B1); PG8_BAR; PG8_SCHED;
;             PG8_LDB(B0, 1, 0); PG8_LDB(B1, 1, 1); PG8_SCHED; PG8_LDA(At, 1, 0); PG8_STAGE(PG8_SA(0, 1), a2 + hstep, voffA);
	s_add_i32 s36, s53, s68
	v_lshl_add_u64 v[184:185], s[46:47], 0, v[154:155]
	s_mov_b32 m0, s36
	ds_read_b128 v[176:179], v191 offset:16384
	ds_read_b128 v[180:183], v191 offset:17408
	ds_read_b128 v[192:195], v191 offset:18432
	ds_read_b128 v[196:199], v191 offset:19456
	ds_read_b128 v[200:203], v191 offset:20480
	ds_read_b128 v[204:207], v191 offset:21504
	ds_read_b128 v[208:211], v191 offset:22528
	ds_read_b128 v[212:215], v191 offset:23552
	global_load_lds_dwordx4 v[184:185], off
	s_add_i32 m0, s36, 0x2000
	s_add_u32 s36, s46, 0xb0000
	v_lshl_add_u64 v[216:217], s[46:47], 0, v[158:159]
	s_addc_u32 s37, s47, 0
	s_add_i32 s60, s54, s68
	global_load_lds_dwordx4 v[216:217], off
	v_lshl_add_u64 v[218:219], s[36:37], 0, v[154:155]
	s_mov_b32 m0, s60
	v_lshl_add_u64 v[220:221], s[48:49], 0, v[156:157]
	global_load_lds_dwordx4 v[218:219], off
	v_lshl_add_u64 v[218:219], s[36:37], 0, v[158:159]
	s_add_i32 m0, s60, 0x2000
	s_nop 0
	global_load_lds_dwordx4 v[218:219], off
	v_lshl_add_u64 v[218:219], s[48:49], 0, v[152:153]
	s_mov_b32 m0, s74
	s_nop 0
	global_load_lds_dwordx4 v[218:219], off
	s_mov_b32 m0, s66
	s_nop 0
	global_load_lds_dwordx4 v[220:221], off
	s_waitcnt vmcnt(8)
	s_waitcnt lgkmcnt(0)
	s_barrier
	s_waitcnt lgkmcnt(0)
	v_mfma_f32_16x16x32_bf16 v[60:63], v[128:131], v[176:179], v[60:63]
	v_mfma_f32_16x16x32_bf16 v[56:59], v[136:139], v[176:179], v[56:59]
	v_mfma_f32_16x16x32_bf16 v[44:47], v[128:131], v[192:195], v[44:47]
	v_mfma_f32_16x16x32_bf16 v[40:43], v[136:139], v[192:195], v[40:43]
	v_mfma_f32_16x16x32_bf16 v[28:31], v[128:131], v[200:203], v[28:31]
	v_mfma_f32_16x16x32_bf16 v[24:27], v[136:139], v[200:203], v[24:27]
	v_mfma_f32_16x16x32_bf16 v[12:15], v[128:131], v[208:211], v[12:15]
	v_mfma_f32_16x16x32_bf16 v[8:11], v[136:139], v[208:211], v[8:11]
	v_mfma_f32_16x16x32_bf16 v[60:63], v[132:135], v[180:183], v[60:63]
	v_mfma_f32_16x16x32_bf16 v[56:59], v[140:143], v[180:183], v[56:59]
	v_mfma_f32_16x16x32_bf16 v[44:47], v[132:135], v[196:199], v[44:47]
	v_mfma_f32_16x16x32_bf16 v[40:43], v[140:143], v[196:199], v[40:43]
	v_mfma_f32_16x16x32_bf16 v[28:31], v[132:135], v[204:207], v[28:31]
	v_mfma_f32_16x16x32_bf16 v[24:27], v[140:143], v[204:207], v[24:27]
	v_mfma_f32_16x16x32_bf16 v[12:15], v[132:135], v[212:215], v[12:15]
	v_mfma_f32_16x16x32_bf16 v[8:11], v[140:143], v[212:215], v[8:11]
	v_mfma_f32_16x16x32_bf16 v[52:55], v[144:147], v[176:179], v[52:55]
	v_mfma_f32_16x16x32_bf16 v[48:51], v[168:171], v[176:179], v[48:51]
	v_mfma_f32_16x16x32_bf16 v[36:39], v[144:147], v[192:195], v[36:39]
	v_mfma_f32_16x16x32_bf16 v[32:35], v[168:171], v[192:195], v[32:35]
	v_mfma_f32_16x16x32_bf16 v[20:23], v[144:147], v[200:203], v[20:23]
	v_mfma_f32_16x16x32_bf16 v[16:19], v[168:171], v[200:203], v[16:19]
	v_mfma_f32_16x16x32_bf16 v[4:7], v[144:147], v[208:211], v[4:7]
	v_mfma_f32_16x16x32_bf16 v[0:3], v[168:171], v[208:211], v[0:3]
	v_mfma_f32_16x16x32_bf16 v[52:55], v[148:151], v[180:183], v[52:55]
	v_mfma_f32_16x16x32_bf16 v[48:51], v[172:175], v[180:183], v[48:51]
	v_mfma_f32_16x16x32_bf16 v[36:39], v[148:151], v[196:199], v[36:39]
	v_mfma_f32_16x16x32_bf16 v[32:35], v[172:175], v[196:199], v[32:35]
	v_mfma_f32_16x16x32_bf16 v[20:23], v[148:151], v[204:207], v[20:23]
	v_mfma_f32_16x16x32_bf16 v[16:19], v[172:175], v[204:207], v[16:19]
	v_mfma_f32_16x16x32_bf16 v[4:7], v[148:151], v[212:215], v[4:7]
	v_mfma_f32_16x16x32_bf16 v[0:3], v[172:175], v[212:215], v[0:3]
	s_barrier
	s_add_i32 s60, 0, 0x18000
	s_add_i32 s61, 0, 0x1c000
	v_add_u32_e32 v140, s60, v188
	v_add_u32_e32 v172, s61, v188
	ds_read_b128 v[128:131], v140
	ds_read_b128 v[132:135], v140 offset:1024
	ds_read_b128 v[136:139], v140 offset:2048
	ds_read_b128 v[140:143], v140 offset:3072
	ds_read_b128 v[144:147], v172
	ds_read_b128 v[148:151], v172 offset:1024
	ds_read_b128 v[168:171], v172 offset:2048
	ds_read_b128 v[172:175], v172 offset:3072
	s_add_u32 s36, s48, 0xb0000
	s_addc_u32 s37, s49, 0
	s_mov_b32 m0, s90
	v_lshl_add_u64 v[222:223], s[36:37], 0, v[152:153]
	ds_read_b128 v[176:179], v191 offset:32768
	ds_read_b128 v[180:183], v191 offset:33792
	ds_read_b128 v[192:195], v191 offset:34816
	ds_read_b128 v[196:199], v191 offset:35840
	ds_read_b128 v[200:203], v191 offset:36864
	ds_read_b128 v[204:207], v191 offset:37888
	ds_read_b128 v[208:211], v191 offset:38912
	ds_read_b128 v[212:215], v191 offset:39936
	global_load_lds_dwordx4 v[222:223], off
	v_lshl_add_u64 v[222:223], s[36:37], 0, v[156:157]
	s_mov_b32 m0, s41
	s_nop 0
	global_load_lds_dwordx4 v[222:223], off
	s_waitcnt vmcnt(8)
	s_waitcnt lgkmcnt(0)
	s_barrier
; #define PG8_STAGE(bufoff, gbase, voff) do { _Pragma("unroll") for (int _i = 0; _i < 2; ++_i) \
;         __builtin_amdgcn_global_load_lds((const unsigned*)((const char*)(gbase) + (voff)[_i]), (PG8_LAS unsigned*)(lds + (bufoff) + ldsw + _i * 8192), 16, 0, 0); } while (0)
; #define PG8_LDA(dst, b, h) do { _Pragma("unroll") for (int m = 0; m < 4; ++m) _Pragma("unroll") for (int k = 0; k < 2; ++k) dst[m][k] = *(const PG8_LAS bf16x8*)(lds + PG8_SA(b, h) + aoff + m * 2048 + k * 1024); } while (0)
; #define PG8_MMA(ai, bj, At, Bt) do { __builtin_amdgcn_s_setprio(1); _Pragma("unroll") for (int m = 0; m < 4; ++m) _Pragma("unroll") for (int n = 0; n < 2; ++n) _Pragma("unroll") for (int k = 0; k < 2; ++k) \
;         acc[ai][bj][m][n] = mma16<F16>(Bt[n][k], At[m][k], acc[ai][bj][m][n]); __builtin_amdgcn_s_setprio(0); } while (0)
; #define PG8_WAIT_V(n) asm volatile("s_waitcnt vmcnt(" #n ")" ::: "memory")
; #define PG8_WAIT_L(n) asm volatile("s_waitcnt lgkmcnt(" #n ")" ::: "memory")
; #define PG8_BAR __builtin_amdgcn_s_barrier()
; #define PG8_SCHED __builtin_amdgcn_sched_barrier(0)
; template <class Epi, class Sched, bool ALIGN_EPI = false, bool SP2 = false, bool F16 = false>
; __device__ __forceinline__ void gemm_phase(PG8_LAS unsigned char* lds, const Gemm g, const Sched& S, const Epi& E, const int wid_in) {
;     ...
;         for (int t = 0; t < nt; t += 2) {
;     ...
;             PG8_WAIT_V(8); PG8_WAIT_L(0); PG8_BAR; PG8_MMA(0, 0, At, B0); PG8_MMA(0, 1, At, B1); PG8_BAR; PG8_SCHED;
;             PG8_LDA(At, 1, 1); PG8_STAGE(PG8_SB(1, 0), b3, voffB); PG8_STAGE(PG8_SB(1, 1), b3 + hstep, voffB); PG8_STAGE(PG8_SA(1, 0), a3, voffA);
;             PG8_WAIT_V(8); PG8_WAIT_L(0); PG8_BAR; PG8_MMA(1, 0, At, B0); PG8_MMA(1, 1, At, B1); PG8_BAR; PG8_SCHED;
	s_waitcnt lgkmcnt(0)
	v_mfma_f32_16x16x32_bf16 v[124:127], v[128:131], v[176:179], v[124:127]
	v_mfma_f32_16x16x32_bf16 v[120:123], v[136:139], v[176:179], v[120:123]
	v_mfma_f32_16x16x32_bf16 v[108:111], v[128:131], v[192:195], v[108:111]
	v_mfma_f32_16x16x32_bf16 v[104:107], v[136:139], v[192:195], v[104:107]
	v_mfma_f32_16x16x32_bf16 v[92:95], v[128:131], v[200:203], v[92:95]
	v_mfma_f32_16x16x32_bf16 v[88:91], v[136:139], v[200:203], v[88:91]
	v_mfma_f32_16x16x32_bf16 v[76:79], v[128:131], v[208:211], v[76:79]
	v_mfma_f32_16x16x32_bf16 v[72:75], v[136:139], v[208:211], v[72:75]
	v_mfma_f32_16x16x32_bf16 v[124:127], v[132:135], v[180:183], v[124:127]
	v_mfma_f32_16x16x32_bf16 v[120:123], v[140:143], v[180:183], v[120:123]
	v_mfma_f32_16x16x32_bf16 v[108:111], v[132:135], v[196:199], v[108:111]
	v_mfma_f32_16x16x32_bf16 v[104:107], v[140:143], v[196:199], v[104:107]
	v_mfma_f32_16x16x32_bf16 v[92:95], v[132:135], v[204:207], v[92:95]
	v_mfma_f32_16x16x32_bf16 v[88:91], v[140:143], v[204:207], v[88:91]
	v_mfma_f32_16x16x32_bf16 v[76:79], v[132:135], v[212:215], v[76:79]
	v_mfma_f32_16x16x32_bf16 v[72:75], v[140:143], v[212:215], v[72:75]
	v_mfma_f32_16x16x32_bf16 v[116:119], v[144:147], v[176:179], v[116:119]
	v_mfma_f32_16x16x32_bf16 v[112:115], v[168:171], v[176:179], v[112:115]
	v_mfma_f32_16x16x32_bf16 v[100:103], v[144:147], v[192:195], v[100:103]
	v_mfma_f32_16x16x32_bf16 v[96:99], v[168:171], v[192:195], v[96:99]
	v_mfma_f32_16x16x32_bf16 v[84:87], v[144:147], v[200:203], v[84:87]
	v_mfma_f32_16x16x32_bf16 v[80:83], v[168:171], v[200:203], v[80:83]
	v_mfma_f32_16x16x32_bf16 v[68:71], v[144:147], v[208:211], v[68:71]
	v_mfma_f32_16x16x32_bf16 v[64:67], v[168:171], v[208:211], v[64:67]
	v_mfma_f32_16x16x32_bf16 v[116:119], v[148:151], v[180:183], v[116:119]
	v_mfma_f32_16x16x32_bf16 v[112:115], v[172:175], v[180:183], v[112:115]
	v_mfma_f32_16x16x32_bf16 v[100:103], v[148:151], v[196:199], v[100:103]
	v_mfma_f32_16x16x32_bf16 v[96:99], v[172:175], v[196:199], v[96:99]
	v_mfma_f32_16x16x32_bf16 v[84:87], v[148:151], v[204:207], v[84:87]
	v_mfma_f32_16x16x32_bf16 v[80:83], v[172:175], v[204:207], v[80:83]
	v_mfma_f32_16x16x32_bf16 v[68:71], v[148:151], v[212:215], v[68:71]
	v_mfma_f32_16x16x32_bf16 v[64:67], v[172:175], v[212:215], v[64:67]
	s_barrier
	s_add_i32 s36, s60, s68
	v_lshl_add_u64 v[184:185], v[184:185], 0, s[30:31]
	s_mov_b32 m0, s36
	ds_read_b128 v[176:179], v191 offset:49152
	ds_read_b128 v[180:183], v191 offset:50176
	ds_read_b128 v[192:195], v191 offset:51200
	ds_read_b128 v[196:199], v191 offset:52224
	ds_read_b128 v[200:203], v191 offset:53248
	ds_read_b128 v[204:207], v191 offset:54272
	ds_read_b128 v[208:211], v191 offset:55296
	ds_read_b128 v[212:215], v191 offset:56320
	global_load_lds_dwordx4 v[184:185], off
	s_add_i32 m0, s36, 0x2000
	s_add_u32 s36, s46, 0xb0080
	v_lshl_add_u64 v[184:185], v[216:217], 0, s[30:31]
	s_addc_u32 s37, s47, 0
	s_add_i32 s46, s61, s68
	global_load_lds_dwordx4 v[184:185], off
	v_lshl_add_u64 v[184:185], s[36:37], 0, v[154:155]
	s_mov_b32 m0, s46
	s_nop 0
	global_load_lds_dwordx4 v[184:185], off
	v_lshl_add_u64 v[184:185], s[36:37], 0, v[158:159]
	s_add_i32 m0, s46, 0x2000
	s_nop 0
	global_load_lds_dwordx4 v[184:185], off
	v_lshl_add_u64 v[184:185], v[218:219], 0, s[30:31]
	s_mov_b32 m0, s75
	s_nop 0
	global_load_lds_dwordx4 v[184:185], off
	v_lshl_add_u64 v[184:185], v[220:221], 0, s[30:31]
	s_mov_b32 m0, s67
	s_nop 0
	global_load_lds_dwordx4 v[184:185], off
	s_waitcnt vmcnt(8)
	s_waitcnt lgkmcnt(0)
	s_barrier
	s_waitcnt lgkmcnt(0)
	v_mfma_f32_16x16x32_bf16 v[60:63], v[128:131], v[176:179], v[60:63]
	v_mfma_f32_16x16x32_bf16 v[56:59], v[136:139], v[176:179], v[56:59]
	v_mfma_f32_16x16x32_bf16 v[44:47], v[128:131], v[192:195], v[44:47]
	v_mfma_f32_16x16x32_bf16 v[40:43], v[136:139], v[192:195], v[40:43]
	v_mfma_f32_16x16x32_bf16 v[28:31], v[128:131], v[200:203], v[28:31]
	v_mfma_f32_16x16x32_bf16 v[24:27], v[136:139], v[200:203], v[24:27]
	v_mfma_f32_16x16x32_bf16 v[12:15], v[128:131], v[208:211], v[12:15]
	v_mfma_f32_16x16x32_bf16 v[8:11], v[136:139], v[208:211], v[8:11]
	v_mfma_f32_16x16x32_bf16 v[60:63], v[132:135], v[180:183], v[60:63]
	v_mfma_f32_16x16x32_bf16 v[56:59], v[140:143], v[180:183], v[56:59]
	v_mfma_f32_16x16x32_bf16 v[44:47], v[132:135], v[196:199], v[44:47]
	v_mfma_f32_16x16x32_bf16 v[40:43], v[140:143], v[196:199], v[40:43]
	v_mfma_f32_16x16x32_bf16 v[28:31], v[132:135], v[204:207], v[28:31]
	v_mfma_f32_16x16x32_bf16 v[24:27], v[140:143], v[204:207], v[24:27]
	v_mfma_f32_16x16x32_bf16 v[12:15], v[132:135], v[212:215], v[12:15]
	v_mfma_f32_16x16x32_bf16 v[8:11], v[140:143], v[212:215], v[8:11]
	v_mfma_f32_16x16x32_bf16 v[52:55], v[144:147], v[176:179], v[52:55]
	v_mfma_f32_16x16x32_bf16 v[48:51], v[168:171], v[176:179], v[48:51]
	v_mfma_f32_16x16x32_bf16 v[36:39], v[144:147], v[192:195], v[36:39]
	v_mfma_f32_16x16x32_bf16 v[32:35], v[168:171], v[192:195], v[32:35]
	v_mfma_f32_16x16x32_bf16 v[20:23], v[144:147], v[200:203], v[20:23]
	v_mfma_f32_16x16x32_bf16 v[16:19], v[168:171], v[200:203], v[16:19]
	v_mfma_f32_16x16x32_bf16 v[4:7], v[144:147], v[208:211], v[4:7]
	v_mfma_f32_16x16x32_bf16 v[0:3], v[168:171], v[208:211], v[0:3]
	v_mfma_f32_16x16x32_bf16 v[52:55], v[148:151], v[180:183], v[52:55]
	v_mfma_f32_16x16x32_bf16 v[48:51], v[172:175], v[180:183], v[48:51]
	v_mfma_f32_16x16x32_bf16 v[36:39], v[148:151], v[196:199], v[36:39]
	v_mfma_f32_16x16x32_bf16 v[32:35], v[172:175], v[196:199], v[32:35]
	v_mfma_f32_16x16x32_bf16 v[20:23], v[148:151], v[204:207], v[20:23]
	v_mfma_f32_16x16x32_bf16 v[16:19], v[172:175], v[204:207], v[16:19]
	v_mfma_f32_16x16x32_bf16 v[4:7], v[148:151], v[212:215], v[4:7]
	v_mfma_f32_16x16x32_bf16 v[0:3], v[172:175], v[212:215], v[0:3]
	s_barrier
	s_add_i32 s59, s59, 2
	s_add_u32 s43, s43, 0x100
	s_addc_u32 s58, s58, 0
	s_cmp_gt_u32 s59, 41
	s_mov_b64 s[36:37], s[44:45]
	s_cbranch_scc0 .LBB0_2040
	s_setprio 0
	s_and_b64 vcc, exec, s[16:17]
	s_cbranch_vccz .LBB0_2043
	s_barrier

; #define PG8_STAGE(bufoff, gbase, voff) do { _Pragma("unroll") for (int _i = 0; _i < 2; ++_i) \
;         __builtin_amdgcn_global_load_lds((const unsigned*)((const char*)(gbase) + (voff)[_i]), (PG8_LAS unsigned*)(lds + (bufoff) + ldsw + _i * 8192), 16, 0, 0); } while (0)
; #define PG8_LDA(dst, b, h) do { _Pragma("unroll") for (int m = 0; m < 4; ++m) _Pragma("unroll") for (int k = 0; k < 2; ++k) dst[m][k] = *(const PG8_LAS bf16x8*)(lds + PG8_SA(b, h) + aoff + m * 2048 + k * 1024); } while (0)
; #define PG8_LDB(dst, b, h) do { _Pragma("unroll") for (int n = 0; n < 2; ++n) _Pragma("unroll") for (int k = 0; k < 2; ++k) dst[n][k] = *(const PG8_LAS bf16x8*)(lds + PG8_SB(b, h) + boff + n * 2048 + k * 1024); } while (0)
; #define PG8_MMA(ai, bj, At, Bt) do { __builtin_amdgcn_s_setprio(1); _Pragma("unroll") for (int m = 0; m < 4; ++m) _Pragma("unroll") for (int n = 0; n < 2; ++n) _Pragma("unroll") for (int k = 0; k < 2; ++k) \
;         acc[ai][bj][m][n] = mma16<F16>(Bt[n][k], At[m][k], acc[ai][bj][m][n]); __builtin_amdgcn_s_setprio(0); } while (0)
; #define PG8_WAIT_V(n) asm volatile("s_waitcnt vmcnt(" #n ")" ::: "memory")
; #define PG8_WAIT_L(n) asm volatile("s_waitcnt lgkmcnt(" #n ")" ::: "memory")
; #define PG8_BAR __builtin_amdgcn_s_barrier()
; #define PG8_SCHED __builtin_amdgcn_sched_barrier(0)
; template <class Epi, class Sched, bool ALIGN_EPI = false, bool SP2 = false, bool F16 = false>
; __device__ __forceinline__ void gemm_phase(PG8_LAS unsigned char* lds, const Gemm g, const Sched& S, const Epi& E, const int wid_in) {
;     ...
;             PG8_LDB(B0, 0, 0); PG8_LDB(B1, 0, 1); PG8_SCHED; PG8_LDA(At, 0, 0); PG8_STAGE(PG8_SA(1, 1), a1 + hstep, voffA);
;             PG8_WAIT_V(8); PG8_WAIT_L(0); PG8_BAR; PG8_MMA(0, 0, At, B0); PG8_MMA(0, 1, At, B1); PG8_BAR; PG8_SCHED;
;             PG8_LDA(At, 0, 1); PG8_STAGE(PG8_SB(0, 0), b2, voffB); PG8_STAGE(PG8_SB(0, 1), b2 + hstep, voffB); PG8_STAGE(PG8_SA(0, 0), a2, voffA);
.Lgsp_17:
.LBB0_2136:
	ds_read_b128 v[112:115], v235
	ds_read_b128 v[116:119], v235 offset:1024
	ds_read_b128 v[128:131], v235 offset:2048
	ds_read_b128 v[132:135], v235 offset:3072
	ds_read_b128 v[144:147], v236
	ds_read_b128 v[148:151], v236 offset:1024
	ds_read_b128 v[152:155], v236 offset:2048
	ds_read_b128 v[156:159], v236 offset:3072
	s_add_u32 s45, s52, 0xfffc0080
	s_addc_u32 s51, s53, -1
	s_cmp_eq_u32 s43, 12
	s_cselect_b32 s57, s14, s51
	s_cselect_b32 s56, s15, s45
	s_cselect_b32 s55, s37, s42
	s_cselect_b32 s54, s40, s41
	s_mov_b32 m0, s91
	v_lshl_add_u64 v[192:193], s[52:53], 0, v[204:205]
	ds_read_b128 v[160:163], v237
	ds_read_b128 v[164:167], v237 offset:1024
	ds_read_b128 v[168:171], v237 offset:2048
	ds_read_b128 v[172:175], v237 offset:3072
	ds_read_b128 v[176:179], v237 offset:4096
	ds_read_b128 v[180:183], v237 offset:5120
	ds_read_b128 v[184:187], v237 offset:6144
	ds_read_b128 v[188:191], v237 offset:7168
	global_load_lds_dwordx4 v[192:193], off
	v_lshl_add_u64 v[192:193], s[52:53], 0, v[206:207]
	s_add_i32 m0, s74, 0xe000
	s_nop 0
	global_load_lds_dwordx4 v[192:193], off
	s_waitcnt vmcnt(8)
	s_waitcnt lgkmcnt(0)
	s_barrier
	s_waitcnt lgkmcnt(0)
	v_mfma_f32_16x16x32_f16 v[140:143], v[112:115], v[160:163], v[140:143]
	v_mfma_f32_16x16x32_f16 v[136:139], v[128:131], v[160:163], v[136:139]
	v_mfma_f32_16x16x32_f16 v[108:111], v[112:115], v[168:171], v[108:111]
	v_mfma_f32_16x16x32_f16 v[104:107], v[128:131], v[168:171], v[104:107]
	v_mfma_f32_16x16x32_f16 v[92:95], v[112:115], v[176:179], v[92:95]
	v_mfma_f32_16x16x32_f16 v[88:91], v[128:131], v[176:179], v[88:91]
	v_mfma_f32_16x16x32_f16 v[76:79], v[112:115], v[184:187], v[76:79]
	v_mfma_f32_16x16x32_f16 v[72:75], v[128:131], v[184:187], v[72:75]
	v_mfma_f32_16x16x32_f16 v[140:143], v[116:119], v[164:167], v[140:143]
	v_mfma_f32_16x16x32_f16 v[136:139], v[132:135], v[164:167], v[136:139]
	v_mfma_f32_16x16x32_f16 v[108:111], v[116:119], v[172:175], v[108:111]
	v_mfma_f32_16x16x32_f16 v[104:107], v[132:135], v[172:175], v[104:107]
	v_mfma_f32_16x16x32_f16 v[92:95], v[116:119], v[180:183], v[92:95]
	v_mfma_f32_16x16x32_f16 v[88:91], v[132:135], v[180:183], v[88:91]
	v_mfma_f32_16x16x32_f16 v[76:79], v[116:119], v[188:191], v[76:79]
	v_mfma_f32_16x16x32_f16 v[72:75], v[132:135], v[188:191], v[72:75]
	v_mfma_f32_16x16x32_f16 v[124:127], v[144:147], v[160:163], v[124:127]
	v_mfma_f32_16x16x32_f16 v[120:123], v[152:155], v[160:163], v[120:123]
	v_mfma_f32_16x16x32_f16 v[100:103], v[144:147], v[168:171], v[100:103]
	v_mfma_f32_16x16x32_f16 v[96:99], v[152:155], v[168:171], v[96:99]
	v_mfma_f32_16x16x32_f16 v[84:87], v[144:147], v[176:179], v[84:87]
	v_mfma_f32_16x16x32_f16 v[80:83], v[152:155], v[176:179], v[80:83]
	v_mfma_f32_16x16x32_f16 v[68:71], v[144:147], v[184:187], v[68:71]
	v_mfma_f32_16x16x32_f16 v[64:67], v[152:155], v[184:187], v[64:67]
	v_mfma_f32_16x16x32_f16 v[124:127], v[148:151], v[164:167], v[124:127]
	v_mfma_f32_16x16x32_f16 v[120:123], v[156:159], v[164:167], v[120:123]
	v_mfma_f32_16x16x32_f16 v[100:103], v[148:151], v[172:175], v[100:103]
	v_mfma_f32_16x16x32_f16 v[96:99], v[156:159], v[172:175], v[96:99]
	v_mfma_f32_16x16x32_f16 v[84:87], v[148:151], v[180:183], v[84:87]
	v_mfma_f32_16x16x32_f16 v[80:83], v[156:159], v[180:183], v[80:83]
	v_mfma_f32_16x16x32_f16 v[68:71], v[148:151], v[188:191], v[68:71]
	v_mfma_f32_16x16x32_f16 v[64:67], v[156:159], v[188:191], v[64:67]
	s_barrier
	s_add_i32 s45, s63, s68
	v_lshl_add_u64 v[192:193], s[54:55], 0, v[198:199]
	s_mov_b32 m0, s45
	ds_read_b128 v[160:163], v237 offset:16384
	ds_read_b128 v[164:167], v237 offset:17408
	ds_read_b128 v[168:171], v237 offset:18432
	ds_read_b128 v[172:175], v237 offset:19456
	ds_read_b128 v[176:179], v237 offset:20480
	ds_read_b128 v[180:183], v237 offset:21504
	ds_read_b128 v[184:187], v237 offset:22528
	ds_read_b128 v[188:191], v237 offset:23552
	global_load_lds_dwordx4 v[192:193], off
	s_add_i32 m0, s45, 0x2000
	s_add_u32 s84, s54, 0x40000
	v_lshl_add_u64 v[194:195], s[54:55], 0, v[202:203]
	s_addc_u32 s85, s55, 0
	s_add_i32 s45, s64, s68
	global_load_lds_dwordx4 v[194:195], off
	v_lshl_add_u64 v[212:213], s[84:85], 0, v[198:199]
	s_mov_b32 m0, s45
	v_lshl_add_u64 v[214:215], s[56:57], 0, v[200:201]
	global_load_lds_dwordx4 v[212:213], off
	v_lshl_add_u64 v[212:213], s[84:85], 0, v[202:203]
	s_add_i32 m0, s45, 0x2000
	s_nop 0
	global_load_lds_dwordx4 v[212:213], off
	v_lshl_add_u64 v[212:213], s[56:57], 0, v[196:197]
	s_mov_b32 m0, s74
	s_nop 0
	global_load_lds_dwordx4 v[212:213], off
	s_mov_b32 m0, s66
	s_nop 0
	global_load_lds_dwordx4 v[214:215], off
	s_waitcnt vmcnt(8)
	s_waitcnt lgkmcnt(0)
	s_barrier
; #define PG8_STAGE(bufoff, gbase, voff) do { _Pragma("unroll") for (int _i = 0; _i < 2; ++_i) \
;         __builtin_amdgcn_global_load_lds((const unsigned*)((const char*)(gbase) + (voff)[_i]), (PG8_LAS unsigned*)(lds + (bufoff) + ldsw + _i * 8192), 16, 0, 0); } while (0)
; #define PG8_LDA(dst, b, h) do { _Pragma("unroll") for (int m = 0; m < 4; ++m) _Pragma("unroll") for (int k = 0; k < 2; ++k) dst[m][k] = *(const PG8_LAS bf16x8*)(lds + PG8_SA(b, h) + aoff + m * 2048 + k * 1024); } while (0)
; #define PG8_LDB(dst, b, h) do { _Pragma("unroll") for (int n = 0; n < 2; ++n) _Pragma("unroll") for (int k = 0; k < 2; ++k) dst[n][k] = *(const PG8_LAS bf16x8*)(lds + PG8_SB(b, h) + boff + n * 2048 + k * 1024); } while (0)
; #define PG8_MMA(ai, bj, At, Bt) do { __builtin_amdgcn_s_setprio(1); _Pragma("unroll") for (int m = 0; m < 4; ++m) _Pragma("unroll") for (int n = 0; n < 2; ++n) _Pragma("unroll") for (int k = 0; k < 2; ++k) \
;         acc[ai][bj][m][n] = mma16<F16>(Bt[n][k], At[m][k], acc[ai][bj][m][n]); __builtin_amdgcn_s_setprio(0); } while (0)
; #define PG8_WAIT_V(n) asm volatile("s_waitcnt vmcnt(" #n ")" ::: "memory")
; #define PG8_WAIT_L(n) asm volatile("s_waitcnt lgkmcnt(" #n ")" ::: "memory")
; #define PG8_BAR __builtin_amdgcn_s_barrier()
; #define PG8_SCHED __builtin_amdgcn_sched_barrier(0)
; template <class Epi, class Sched, bool ALIGN_EPI = false, bool SP2 = false, bool F16 = false>
; __device__ __forceinline__ void gemm_phase(PG8_LAS unsigned char* lds, const Gemm g, const Sched& S, const Epi& E, const int wid_in) {
;     ...
;             PG8_WAIT_V(8); PG8_WAIT_L(0); PG8_BAR; PG8_MMA(1, 0, At, B0); PG8_MMA(1, 1, At, B1); PG8_BAR; PG8_SCHED;
;             PG8_LDB(B0, 1, 0); PG8_LDB(B1, 1, 1); PG8_SCHED; PG8_LDA(At, 1, 0); PG8_STAGE(PG8_SA(0, 1), a2 + hstep, voffA);
;             PG8_WAIT_V(8); PG8_WAIT_L(0); PG8_BAR; PG8_MMA(0, 0, At, B0); PG8_MMA(0, 1, At, B1); PG8_BAR; PG8_SCHED;
	s_waitcnt lgkmcnt(0)
	v_mfma_f32_16x16x32_f16 v[60:63], v[112:115], v[160:163], v[60:63]
	v_mfma_f32_16x16x32_f16 v[56:59], v[128:131], v[160:163], v[56:59]
	v_mfma_f32_16x16x32_f16 v[44:47], v[112:115], v[168:171], v[44:47]
	v_mfma_f32_16x16x32_f16 v[40:43], v[128:131], v[168:171], v[40:43]
	v_mfma_f32_16x16x32_f16 v[28:31], v[112:115], v[176:179], v[28:31]
	v_mfma_f32_16x16x32_f16 v[24:27], v[128:131], v[176:179], v[24:27]
	v_mfma_f32_16x16x32_f16 v[12:15], v[112:115], v[184:187], v[12:15]
	v_mfma_f32_16x16x32_f16 v[8:11], v[128:131], v[184:187], v[8:11]
	v_mfma_f32_16x16x32_f16 v[60:63], v[116:119], v[164:167], v[60:63]
	v_mfma_f32_16x16x32_f16 v[56:59], v[132:135], v[164:167], v[56:59]
	v_mfma_f32_16x16x32_f16 v[44:47], v[116:119], v[172:175], v[44:47]
	v_mfma_f32_16x16x32_f16 v[40:43], v[132:135], v[172:175], v[40:43]
	v_mfma_f32_16x16x32_f16 v[28:31], v[116:119], v[180:183], v[28:31]
	v_mfma_f32_16x16x32_f16 v[24:27], v[132:135], v[180:183], v[24:27]
	v_mfma_f32_16x16x32_f16 v[12:15], v[116:119], v[188:191], v[12:15]
	v_mfma_f32_16x16x32_f16 v[8:11], v[132:135], v[188:191], v[8:11]
	v_mfma_f32_16x16x32_f16 v[52:55], v[144:147], v[160:163], v[52:55]
	v_mfma_f32_16x16x32_f16 v[48:51], v[152:155], v[160:163], v[48:51]
	v_mfma_f32_16x16x32_f16 v[36:39], v[144:147], v[168:171], v[36:39]
	v_mfma_f32_16x16x32_f16 v[32:35], v[152:155], v[168:171], v[32:35]
	v_mfma_f32_16x16x32_f16 v[20:23], v[144:147], v[176:179], v[20:23]
	v_mfma_f32_16x16x32_f16 v[16:19], v[152:155], v[176:179], v[16:19]
	v_mfma_f32_16x16x32_f16 v[4:7], v[144:147], v[184:187], v[4:7]
	v_mfma_f32_16x16x32_f16 v[0:3], v[152:155], v[184:187], v[0:3]
	v_mfma_f32_16x16x32_f16 v[52:55], v[148:151], v[164:167], v[52:55]
	v_mfma_f32_16x16x32_f16 v[48:51], v[156:159], v[164:167], v[48:51]
	v_mfma_f32_16x16x32_f16 v[36:39], v[148:151], v[172:175], v[36:39]
	v_mfma_f32_16x16x32_f16 v[32:35], v[156:159], v[172:175], v[32:35]
	v_mfma_f32_16x16x32_f16 v[20:23], v[148:151], v[180:183], v[20:23]
	v_mfma_f32_16x16x32_f16 v[16:19], v[156:159], v[180:183], v[16:19]
	v_mfma_f32_16x16x32_f16 v[4:7], v[148:151], v[188:191], v[4:7]
	v_mfma_f32_16x16x32_f16 v[0:3], v[156:159], v[188:191], v[0:3]
	s_barrier
	s_add_i32 s45, 0, 0x18000
	s_add_i32 s51, 0, 0x1c000
	v_add_u32_e32 v132, s45, v234
	v_add_u32_e32 v156, s51, v234
	ds_read_b128 v[112:115], v132
	ds_read_b128 v[116:119], v132 offset:1024
	ds_read_b128 v[128:131], v132 offset:2048
	ds_read_b128 v[132:135], v132 offset:3072
	ds_read_b128 v[144:147], v156
	ds_read_b128 v[148:151], v156 offset:1024
	ds_read_b128 v[152:155], v156 offset:2048
	ds_read_b128 v[156:159], v156 offset:3072
	s_add_u32 s56, s56, 0x40000
	s_addc_u32 s57, s57, 0
	s_mov_b32 m0, s90
	v_lshl_add_u64 v[216:217], s[56:57], 0, v[196:197]
	ds_read_b128 v[160:163], v237 offset:32768
	ds_read_b128 v[164:167], v237 offset:33792
	ds_read_b128 v[168:171], v237 offset:34816
	ds_read_b128 v[172:175], v237 offset:35840
	ds_read_b128 v[176:179], v237 offset:36864
	ds_read_b128 v[180:183], v237 offset:37888
	ds_read_b128 v[184:187], v237 offset:38912
	ds_read_b128 v[188:191], v237 offset:39936
	global_load_lds_dwordx4 v[216:217], off
	v_lshl_add_u64 v[216:217], s[56:57], 0, v[200:201]
	s_mov_b32 m0, s59
	s_nop 0
	global_load_lds_dwordx4 v[216:217], off
	s_waitcnt vmcnt(8)
	s_waitcnt lgkmcnt(0)
	s_barrier
	s_waitcnt lgkmcnt(0)
	v_mfma_f32_16x16x32_f16 v[140:143], v[112:115], v[160:163], v[140:143]
	v_mfma_f32_16x16x32_f16 v[136:139], v[128:131], v[160:163], v[136:139]
	v_mfma_f32_16x16x32_f16 v[108:111], v[112:115], v[168:171], v[108:111]
	v_mfma_f32_16x16x32_f16 v[104:107], v[128:131], v[168:171], v[104:107]
	v_mfma_f32_16x16x32_f16 v[92:95], v[112:115], v[176:179], v[92:95]
	v_mfma_f32_16x16x32_f16 v[88:91], v[128:131], v[176:179], v[88:91]
	v_mfma_f32_16x16x32_f16 v[76:79], v[112:115], v[184:187], v[76:79]
	v_mfma_f32_16x16x32_f16 v[72:75], v[128:131], v[184:187], v[72:75]
	v_mfma_f32_16x16x32_f16 v[140:143], v[116:119], v[164:167], v[140:143]
	v_mfma_f32_16x16x32_f16 v[136:139], v[132:135], v[164:167], v[136:139]
	v_mfma_f32_16x16x32_f16 v[108:111], v[116:119], v[172:175], v[108:111]
	v_mfma_f32_16x16x32_f16 v[104:107], v[132:135], v[172:175], v[104:107]
	v_mfma_f32_16x16x32_f16 v[92:95], v[116:119], v[180:183], v[92:95]
	v_mfma_f32_16x16x32_f16 v[88:91], v[132:135], v[180:183], v[88:91]
	v_mfma_f32_16x16x32_f16 v[76:79], v[116:119], v[188:191], v[76:79]
	v_mfma_f32_16x16x32_f16 v[72:75], v[132:135], v[188:191], v[72:75]
	v_mfma_f32_16x16x32_f16 v[124:127], v[144:147], v[160:163], v[124:127]
	v_mfma_f32_16x16x32_f16 v[120:123], v[152:155], v[160:163], v[120:123]
	v_mfma_f32_16x16x32_f16 v[100:103], v[144:147], v[168:171], v[100:103]
	v_mfma_f32_16x16x32_f16 v[96:99], v[152:155], v[168:171], v[96:99]
	v_mfma_f32_16x16x32_f16 v[84:87], v[144:147], v[176:179], v[84:87]
	v_mfma_f32_16x16x32_f16 v[80:83], v[152:155], v[176:179], v[80:83]
	v_mfma_f32_16x16x32_f16 v[68:71], v[144:147], v[184:187], v[68:71]
	v_mfma_f32_16x16x32_f16 v[64:67], v[152:155], v[184:187], v[64:67]
	v_mfma_f32_16x16x32_f16 v[124:127], v[148:151], v[164:167], v[124:127]
	v_mfma_f32_16x16x32_f16 v[120:123], v[156:159], v[164:167], v[120:123]
	v_mfma_f32_16x16x32_f16 v[100:103], v[148:151], v[172:175], v[100:103]
	v_mfma_f32_16x16x32_f16 v[96:99], v[156:159], v[172:175], v[96:99]
	v_mfma_f32_16x16x32_f16 v[84:87], v[148:151], v[180:183], v[84:87]
	v_mfma_f32_16x16x32_f16 v[80:83], v[156:159], v[180:183], v[80:83]
	v_mfma_f32_16x16x32_f16 v[68:71], v[148:151], v[188:191], v[68:71]
	v_mfma_f32_16x16x32_f16 v[64:67], v[156:159], v[188:191], v[64:67]
	s_barrier
; #define PG8_STAGE(bufoff, gbase, voff) do { _Pragma("unroll") for (int _i = 0; _i < 2; ++_i) \
;         __builtin_amdgcn_global_load_lds((const unsigned*)((const char*)(gbase) + (voff)[_i]), (PG8_LAS unsigned*)(lds + (bufoff) + ldsw + _i * 8192), 16, 0, 0); } while (0)
; #define PG8_LDA(dst, b, h) do { _Pragma("unroll") for (int m = 0; m < 4; ++m) _Pragma("unroll") for (int k = 0; k < 2; ++k) dst[m][k] = *(const PG8_LAS bf16x8*)(lds + PG8_SA(b, h) + aoff + m * 2048 + k * 1024); } while (0)
; #define PG8_MMA(ai, bj, At, Bt) do { __builtin_amdgcn_s_setprio(1); _Pragma("unroll") for (int m = 0; m < 4; ++m) _Pragma("unroll") for (int n = 0; n < 2; ++n) _Pragma("unroll") for (int k = 0; k < 2; ++k) \
;         acc[ai][bj][m][n] = mma16<F16>(Bt[n][k], At[m][k], acc[ai][bj][m][n]); __builtin_amdgcn_s_setprio(0); } while (0)
; #define PG8_WAIT_V(n) asm volatile("s_waitcnt vmcnt(" #n ")" ::: "memory")
; #define PG8_WAIT_L(n) asm volatile("s_waitcnt lgkmcnt(" #n ")" ::: "memory")
; #define PG8_BAR __builtin_amdgcn_s_barrier()
; #define PG8_SCHED __builtin_amdgcn_sched_barrier(0)
; template <class Epi, class Sched, bool ALIGN_EPI = false, bool SP2 = false, bool F16 = false>
; __device__ __forceinline__ void gemm_phase(PG8_LAS unsigned char* lds, const Gemm g, const Sched& S, const Epi& E, const int wid_in) {
;     ...
;         for (int t = 0; t < nt; t += 2) {
;     ...
;             PG8_LDA(At, 1, 1); PG8_STAGE(PG8_SB(1, 0), b3, voffB); PG8_STAGE(PG8_SB(1, 1), b3 + hstep, voffB); PG8_STAGE(PG8_SA(1, 0), a3, voffA);
;             PG8_WAIT_V(8); PG8_WAIT_L(0); PG8_BAR; PG8_MMA(1, 0, At, B0); PG8_MMA(1, 1, At, B1); PG8_BAR; PG8_SCHED;
	s_add_i32 s45, s45, s68
	v_lshl_add_u64 v[192:193], v[192:193], 0, s[34:35]
	s_mov_b32 m0, s45
	ds_read_b128 v[160:163], v237 offset:49152
	ds_read_b128 v[164:167], v237 offset:50176
	ds_read_b128 v[168:171], v237 offset:51200
	ds_read_b128 v[172:175], v237 offset:52224
	ds_read_b128 v[176:179], v237 offset:53248
	ds_read_b128 v[180:183], v237 offset:54272
	ds_read_b128 v[184:187], v237 offset:55296
	ds_read_b128 v[188:191], v237 offset:56320
	global_load_lds_dwordx4 v[192:193], off
	s_add_i32 m0, s45, 0x2000
	s_add_u32 s54, s54, 0x40080
	v_lshl_add_u64 v[192:193], v[194:195], 0, s[34:35]
	s_addc_u32 s55, s55, 0
	s_add_i32 s45, s51, s68
	global_load_lds_dwordx4 v[192:193], off
	v_lshl_add_u64 v[192:193], s[54:55], 0, v[198:199]
	s_mov_b32 m0, s45
	s_nop 0
	global_load_lds_dwordx4 v[192:193], off
	v_lshl_add_u64 v[192:193], s[54:55], 0, v[202:203]
	s_add_i32 m0, s45, 0x2000
	s_nop 0
	global_load_lds_dwordx4 v[192:193], off
	v_lshl_add_u64 v[192:193], v[212:213], 0, s[34:35]
	s_mov_b32 m0, s75
	s_nop 0
	global_load_lds_dwordx4 v[192:193], off
	v_lshl_add_u64 v[192:193], v[214:215], 0, s[34:35]
	s_mov_b32 m0, s67
	s_nop 0
	global_load_lds_dwordx4 v[192:193], off
	s_waitcnt vmcnt(8)
	s_waitcnt lgkmcnt(0)
	s_barrier
	s_waitcnt lgkmcnt(0)
	v_mfma_f32_16x16x32_f16 v[60:63], v[112:115], v[160:163], v[60:63]
	v_mfma_f32_16x16x32_f16 v[56:59], v[128:131], v[160:163], v[56:59]
	v_mfma_f32_16x16x32_f16 v[44:47], v[112:115], v[168:171], v[44:47]
	v_mfma_f32_16x16x32_f16 v[40:43], v[128:131], v[168:171], v[40:43]
	v_mfma_f32_16x16x32_f16 v[28:31], v[112:115], v[176:179], v[28:31]
	v_mfma_f32_16x16x32_f16 v[24:27], v[128:131], v[176:179], v[24:27]
	v_mfma_f32_16x16x32_f16 v[12:15], v[112:115], v[184:187], v[12:15]
	v_mfma_f32_16x16x32_f16 v[8:11], v[128:131], v[184:187], v[8:11]
	v_mfma_f32_16x16x32_f16 v[60:63], v[116:119], v[164:167], v[60:63]
	v_mfma_f32_16x16x32_f16 v[56:59], v[132:135], v[164:167], v[56:59]
	v_mfma_f32_16x16x32_f16 v[44:47], v[116:119], v[172:175], v[44:47]
	v_mfma_f32_16x16x32_f16 v[40:43], v[132:135], v[172:175], v[40:43]
	v_mfma_f32_16x16x32_f16 v[28:31], v[116:119], v[180:183], v[28:31]
	v_mfma_f32_16x16x32_f16 v[24:27], v[132:135], v[180:183], v[24:27]
	v_mfma_f32_16x16x32_f16 v[12:15], v[116:119], v[188:191], v[12:15]
	v_mfma_f32_16x16x32_f16 v[8:11], v[132:135], v[188:191], v[8:11]
	v_mfma_f32_16x16x32_f16 v[52:55], v[144:147], v[160:163], v[52:55]
	v_mfma_f32_16x16x32_f16 v[48:51], v[152:155], v[160:163], v[48:51]
	v_mfma_f32_16x16x32_f16 v[36:39], v[144:147], v[168:171], v[36:39]
	v_mfma_f32_16x16x32_f16 v[32:35], v[152:155], v[168:171], v[32:35]
	v_mfma_f32_16x16x32_f16 v[20:23], v[144:147], v[176:179], v[20:23]
	v_mfma_f32_16x16x32_f16 v[16:19], v[152:155], v[176:179], v[16:19]
	v_mfma_f32_16x16x32_f16 v[4:7], v[144:147], v[184:187], v[4:7]
	v_mfma_f32_16x16x32_f16 v[0:3], v[152:155], v[184:187], v[0:3]
	v_mfma_f32_16x16x32_f16 v[52:55], v[148:151], v[164:167], v[52:55]
	v_mfma_f32_16x16x32_f16 v[48:51], v[156:159], v[164:167], v[48:51]
	v_mfma_f32_16x16x32_f16 v[36:39], v[148:151], v[172:175], v[36:39]
	v_mfma_f32_16x16x32_f16 v[32:35], v[156:159], v[172:175], v[32:35]
	v_mfma_f32_16x16x32_f16 v[20:23], v[148:151], v[180:183], v[20:23]
	v_mfma_f32_16x16x32_f16 v[16:19], v[156:159], v[180:183], v[16:19]
	v_mfma_f32_16x16x32_f16 v[4:7], v[148:151], v[188:191], v[4:7]
	v_mfma_f32_16x16x32_f16 v[0:3], v[156:159], v[188:191], v[0:3]
	s_barrier
	s_add_i32 s43, s43, 2
	s_add_u32 s52, s52, 0x100
	s_addc_u32 s53, s53, 0
	s_add_u32 s41, s41, 0x100
	s_addc_u32 s42, s42, 0
	s_cmp_gt_u32 s43, 13
	s_cbranch_scc0 .LBB0_2136
	s_setprio 0
	s_and_b64 vcc, exec, s[16:17]
	s_cbranch_vccz .LBB0_2139
	s_barrier

; #define PG8_STAGE(bufoff, gbase, voff) do { _Pragma("unroll") for (int _i = 0; _i < 2; ++_i) \
;         __builtin_amdgcn_global_load_lds((const unsigned*)((const char*)(gbase) + (voff)[_i]), (PG8_LAS unsigned*)(lds + (bufoff) + ldsw + _i * 8192), 16, 0, 0); } while (0)
; #define PG8_LDA(dst, b, h) do { _Pragma("unroll") for (int m = 0; m < 4; ++m) _Pragma("unroll") for (int k = 0; k < 2; ++k) dst[m][k] = *(const PG8_LAS bf16x8*)(lds + PG8_SA(b, h) + aoff + m * 2048 + k * 1024); } while (0)
; #define PG8_LDB(dst, b, h) do { _Pragma("unroll") for (int n = 0; n < 2; ++n) _Pragma("unroll") for (int k = 0; k < 2; ++k) dst[n][k] = *(const PG8_LAS bf16x8*)(lds + PG8_SB(b, h) + boff + n * 2048 + k * 1024); } while (0)
; #define PG8_WAIT_V(n) asm volatile("s_waitcnt vmcnt(" #n ")" ::: "memory")
; #define PG8_WAIT_L(n) asm volatile("s_waitcnt lgkmcnt(" #n ")" ::: "memory")
; #define PG8_BAR __builtin_amdgcn_s_barrier()
; template <class Epi, class Sched, bool ALIGN_EPI = false, bool SP2 = false, bool F16 = false>
; __device__ __forceinline__ void gemm_phase(PG8_LAS unsigned char* lds, const Gemm g, const Sched& S, const Epi& E, const int wid_in) {
;     ...
;         const bool has_next = S.next(ui + 1, nxt);
;         const char* nA = has_next ? (const char*)g.A + (size_t)nxt.pm * tstep : cA; const char* nB = has_next ? (const char*)g.Bt + (size_t)nxt.pn * tstep : cB;
;         for (int t = 0; t < nt; t += 2) {
;             const bool last = (t == nt - 2);
;             const char* a1 = cA + (size_t)(t + 1) * kstep;
;             const char* a2 = last ? nA : cA + (size_t)(t + 2) * kstep; const char* b2 = last ? nB : cB + (size_t)(t + 2) * kstep;
;             const char* a3 = a2 + kstep; const char* b3 = b2 + kstep;
;             if (last && has_next) S.a_ready(nxt);
;             if constexpr (SP2) {
;             PG8_LDB(B0, 0, 0); PG8_LDB(B1, 0, 1); PG8_SCHED; PG8_LDA(At, 0, 0); PG8_STAGE(PG8_SA(1, 1), a1 + hstep, voffA);
;             PG8_WAIT_V(8); PG8_WAIT_L(0); PG8_BAR; PG8_MMA(0, 0, At, B0); PG8_MMA(0, 1, At, B1); PG8_BAR; PG8_SCHED;
;     ...
; #pragma unroll
;         for (int a = 0; a < 2; ++a)
; #pragma unroll
;             for (int b = 0; b < 2; ++b)
; #pragma unroll
;                 for (int m = 0; m < 4; ++m)
; #pragma unroll
;                     for (int n = 0; n < 2; ++n) acc[a][b][m][n] = (f32x4){0.f, 0.f, 0.f, 0.f};
.LBB0_2225:
	s_ashr_i32 s37, s36, 31
	s_lshl_b64 s[40:41], s[36:37], 19
	s_add_u32 s44, s59, s40
	s_addc_u32 s45, s60, s41
	s_and_b64 s[40:41], s[10:11], exec
	s_cselect_b32 s13, s45, s49
	s_cselect_b32 s23, s44, s48
	s_ashr_i32 s35, s34, 31
	s_lshl_b64 s[40:41], s[34:35], 19
	s_add_u32 s46, s61, s40
	s_addc_u32 s47, s62, s41
	s_and_b64 s[40:41], s[10:11], exec
	s_cselect_b32 s35, s47, s51
	s_cselect_b32 s37, s46, s50
	s_add_u32 s48, s48, 0x40080
	s_addc_u32 s49, s49, 0
	s_add_u32 s40, s50, 0x100
	v_mov_b32_e32 v0, 0
	s_addc_u32 s41, s51, 0
	s_mov_b32 s42, -2
	s_waitcnt lgkmcnt(0)
	v_mov_b32_e32 v1, v0
	v_mov_b32_e32 v2, v0
	v_mov_b32_e32 v3, v0
	v_mov_b32_e32 v4, v0
	v_mov_b32_e32 v5, v0
	v_mov_b32_e32 v6, v0
	v_mov_b32_e32 v7, v0
	v_mov_b32_e32 v16, v0
	v_mov_b32_e32 v17, v0
	v_mov_b32_e32 v18, v0
	v_mov_b32_e32 v19, v0
	v_mov_b32_e32 v20, v0
	v_mov_b32_e32 v21, v0
	v_mov_b32_e32 v22, v0
	v_mov_b32_e32 v23, v0
	v_mov_b32_e32 v32, v0
	v_mov_b32_e32 v33, v0
	v_mov_b32_e32 v34, v0
	v_mov_b32_e32 v35, v0
	v_mov_b32_e32 v36, v0
	v_mov_b32_e32 v37, v0
	v_mov_b32_e32 v38, v0
	v_mov_b32_e32 v39, v0
	v_mov_b32_e32 v48, v0
	v_mov_b32_e32 v49, v0
	v_mov_b32_e32 v50, v0
	v_mov_b32_e32 v51, v0
	v_mov_b32_e32 v52, v0
	v_mov_b32_e32 v53, v0
	v_mov_b32_e32 v54, v0
	v_mov_b32_e32 v55, v0
	v_mov_b32_e32 v8, v0
	v_mov_b32_e32 v9, v0
	v_mov_b32_e32 v10, v0
	v_mov_b32_e32 v11, v0
	v_mov_b32_e32 v12, v0
	v_mov_b32_e32 v13, v0
	v_mov_b32_e32 v14, v0
	v_mov_b32_e32 v15, v0
	v_mov_b32_e32 v24, v0
	v_mov_b32_e32 v25, v0
	v_mov_b32_e32 v26, v0
	v_mov_b32_e32 v27, v0
	v_mov_b32_e32 v28, v0
	v_mov_b32_e32 v29, v0
	v_mov_b32_e32 v30, v0
	v_mov_b32_e32 v31, v0
	v_mov_b32_e32 v40, v0
	v_mov_b32_e32 v41, v0
	v_mov_b32_e32 v42, v0
	v_mov_b32_e32 v43, v0
	v_mov_b32_e32 v44, v0
	v_mov_b32_e32 v45, v0
	v_mov_b32_e32 v46, v0
	v_mov_b32_e32 v47, v0
	v_mov_b32_e32 v56, v0
	v_mov_b32_e32 v57, v0
	v_mov_b32_e32 v58, v0
	v_mov_b32_e32 v59, v0
	v_mov_b32_e32 v60, v0
	v_mov_b32_e32 v61, v0
	v_mov_b32_e32 v62, v0
	v_mov_b32_e32 v63, v0
	v_mov_b32_e32 v64, v0
	v_mov_b32_e32 v65, v0
	v_mov_b32_e32 v66, v0
	v_mov_b32_e32 v67, v0
	v_mov_b32_e32 v68, v0
	v_mov_b32_e32 v69, v0
	v_mov_b32_e32 v70, v0
	v_mov_b32_e32 v71, v0
	v_mov_b32_e32 v80, v0
	v_mov_b32_e32 v81, v0
	v_mov_b32_e32 v82, v0
	v_mov_b32_e32 v83, v0
	v_mov_b32_e32 v84, v0
	v_mov_b32_e32 v85, v0
	v_mov_b32_e32 v86, v0
	v_mov_b32_e32 v87, v0
	v_mov_b32_e32 v96, v0
	v_mov_b32_e32 v97, v0
	v_mov_b32_e32 v98, v0
	v_mov_b32_e32 v99, v0
	v_mov_b32_e32 v100, v0
	v_mov_b32_e32 v101, v0
	v_mov_b32_e32 v102, v0
	v_mov_b32_e32 v103, v0
	v_mov_b32_e32 v112, v0
	v_mov_b32_e32 v113, v0
	v_mov_b32_e32 v114, v0
	v_mov_b32_e32 v115, v0
	v_mov_b32_e32 v116, v0
	v_mov_b32_e32 v117, v0
	v_mov_b32_e32 v118, v0
	v_mov_b32_e32 v119, v0
	v_mov_b32_e32 v72, v0
	v_mov_b32_e32 v73, v0
	v_mov_b32_e32 v74, v0
	v_mov_b32_e32 v75, v0
	v_mov_b32_e32 v76, v0
	v_mov_b32_e32 v77, v0
	v_mov_b32_e32 v78, v0
	v_mov_b32_e32 v79, v0
	v_mov_b32_e32 v88, v0
	v_mov_b32_e32 v89, v0
	v_mov_b32_e32 v90, v0
	v_mov_b32_e32 v91, v0
	v_mov_b32_e32 v92, v0
	v_mov_b32_e32 v93, v0
	v_mov_b32_e32 v94, v0
	v_mov_b32_e32 v95, v0
	v_mov_b32_e32 v104, v0
	v_mov_b32_e32 v105, v0
	v_mov_b32_e32 v106, v0
	v_mov_b32_e32 v107, v0
	v_mov_b32_e32 v108, v0
	v_mov_b32_e32 v109, v0
	v_mov_b32_e32 v110, v0
	v_mov_b32_e32 v111, v0
	v_mov_b32_e32 v120, v0
	v_mov_b32_e32 v121, v0
	v_mov_b32_e32 v122, v0
	v_mov_b32_e32 v123, v0
	v_mov_b32_e32 v124, v0
	v_mov_b32_e32 v125, v0
	v_mov_b32_e32 v126, v0
	v_mov_b32_e32 v127, v0
	s_cmp_ge_u32 s3, 4
	s_cbranch_scc0 .Lgsp_18
	s_setprio 1
.Lgsp_18:
.LBB0_2226:
	ds_read_b128 v[128:131], v183
	ds_read_b128 v[132:135], v183 offset:1024
	ds_read_b128 v[136:139], v183 offset:2048
	ds_read_b128 v[140:143], v183 offset:3072
	ds_read_b128 v[144:147], v184
	ds_read_b128 v[148:151], v184 offset:1024
	ds_read_b128 v[152:155], v184 offset:2048
	ds_read_b128 v[174:177], v184 offset:3072
	s_add_u32 s43, s48, 0xfffc0080
	s_addc_u32 s50, s49, -1
	s_cmp_eq_u32 s42, 12
	s_cselect_b32 s53, s13, s50
	s_cselect_b32 s52, s23, s43
	s_cselect_b32 s51, s35, s41
	s_cselect_b32 s50, s37, s40
	s_mov_b32 m0, s91
	v_lshl_add_u64 v[178:179], s[48:49], 0, v[166:167]
	ds_read_b128 v[188:191], v185
	ds_read_b128 v[192:195], v185 offset:1024
	ds_read_b128 v[196:199], v185 offset:2048
	ds_read_b128 v[200:203], v185 offset:3072
	ds_read_b128 v[204:207], v185 offset:4096
	ds_read_b128 v[208:211], v185 offset:5120
	ds_read_b128 v[212:215], v185 offset:6144
	ds_read_b128 v[216:219], v185 offset:7168
	global_load_lds_dwordx4 v[178:179], off
	v_lshl_add_u64 v[178:179], s[48:49], 0, v[168:169]
	s_add_i32 m0, s74, 0xe000
	s_nop 0
	global_load_lds_dwordx4 v[178:179], off
	s_waitcnt vmcnt(8)
	s_waitcnt lgkmcnt(0)
	s_barrier
; #define PG8_STAGE(bufoff, gbase, voff) do { _Pragma("unroll") for (int _i = 0; _i < 2; ++_i) \
;         __builtin_amdgcn_global_load_lds((const unsigned*)((const char*)(gbase) + (voff)[_i]), (PG8_LAS unsigned*)(lds + (bufoff) + ldsw + _i * 8192), 16, 0, 0); } while (0)
; #define PG8_LDA(dst, b, h) do { _Pragma("unroll") for (int m = 0; m < 4; ++m) _Pragma("unroll") for (int k = 0; k < 2; ++k) dst[m][k] = *(const PG8_LAS bf16x8*)(lds + PG8_SA(b, h) + aoff + m * 2048 + k * 1024); } while (0)
; #define PG8_MMA(ai, bj, At, Bt) do { __builtin_amdgcn_s_setprio(1); _Pragma("unroll") for (int m = 0; m < 4; ++m) _Pragma("unroll") for (int n = 0; n < 2; ++n) _Pragma("unroll") for (int k = 0; k < 2; ++k) \
;         acc[ai][bj][m][n] = mma16<F16>(Bt[n][k], At[m][k], acc[ai][bj][m][n]); __builtin_amdgcn_s_setprio(0); } while (0)
; #define PG8_WAIT_V(n) asm volatile("s_waitcnt vmcnt(" #n ")" ::: "memory")
; #define PG8_WAIT_L(n) asm volatile("s_waitcnt lgkmcnt(" #n ")" ::: "memory")
; #define PG8_BAR __builtin_amdgcn_s_barrier()
; #define PG8_SCHED __builtin_amdgcn_sched_barrier(0)
; template <class Epi, class Sched, bool ALIGN_EPI = false, bool SP2 = false, bool F16 = false>
; __device__ __forceinline__ void gemm_phase(PG8_LAS unsigned char* lds, const Gemm g, const Sched& S, const Epi& E, const int wid_in) {
;     ...
;             PG8_WAIT_V(8); PG8_WAIT_L(0); PG8_BAR; PG8_MMA(0, 0, At, B0); PG8_MMA(0, 1, At, B1); PG8_BAR; PG8_SCHED;
;             PG8_LDA(At, 0, 1); PG8_STAGE(PG8_SB(0, 0), b2, voffB); PG8_STAGE(PG8_SB(0, 1), b2 + hstep, voffB); PG8_STAGE(PG8_SA(0, 0), a2, voffA);
;             PG8_WAIT_V(8); PG8_WAIT_L(0); PG8_BAR; PG8_MMA(1, 0, At, B0); PG8_MMA(1, 1, At, B1); PG8_BAR; PG8_SCHED;
	s_waitcnt lgkmcnt(0)
	v_mfma_f32_16x16x32_f16 v[124:127], v[128:131], v[188:191], v[124:127]
	v_mfma_f32_16x16x32_f16 v[120:123], v[136:139], v[188:191], v[120:123]
	v_mfma_f32_16x16x32_f16 v[108:111], v[128:131], v[196:199], v[108:111]
	v_mfma_f32_16x16x32_f16 v[104:107], v[136:139], v[196:199], v[104:107]
	v_mfma_f32_16x16x32_f16 v[92:95], v[128:131], v[204:207], v[92:95]
	v_mfma_f32_16x16x32_f16 v[88:91], v[136:139], v[204:207], v[88:91]
	v_mfma_f32_16x16x32_f16 v[76:79], v[128:131], v[212:215], v[76:79]
	v_mfma_f32_16x16x32_f16 v[72:75], v[136:139], v[212:215], v[72:75]
	v_mfma_f32_16x16x32_f16 v[124:127], v[132:135], v[192:195], v[124:127]
	v_mfma_f32_16x16x32_f16 v[120:123], v[140:143], v[192:195], v[120:123]
	v_mfma_f32_16x16x32_f16 v[108:111], v[132:135], v[200:203], v[108:111]
	v_mfma_f32_16x16x32_f16 v[104:107], v[140:143], v[200:203], v[104:107]
	v_mfma_f32_16x16x32_f16 v[92:95], v[132:135], v[208:211], v[92:95]
	v_mfma_f32_16x16x32_f16 v[88:91], v[140:143], v[208:211], v[88:91]
	v_mfma_f32_16x16x32_f16 v[76:79], v[132:135], v[216:219], v[76:79]
	v_mfma_f32_16x16x32_f16 v[72:75], v[140:143], v[216:219], v[72:75]
	v_mfma_f32_16x16x32_f16 v[116:119], v[144:147], v[188:191], v[116:119]
	v_mfma_f32_16x16x32_f16 v[112:115], v[152:155], v[188:191], v[112:115]
	v_mfma_f32_16x16x32_f16 v[100:103], v[144:147], v[196:199], v[100:103]
	v_mfma_f32_16x16x32_f16 v[96:99], v[152:155], v[196:199], v[96:99]
	v_mfma_f32_16x16x32_f16 v[84:87], v[144:147], v[204:207], v[84:87]
	v_mfma_f32_16x16x32_f16 v[80:83], v[152:155], v[204:207], v[80:83]
	v_mfma_f32_16x16x32_f16 v[68:71], v[144:147], v[212:215], v[68:71]
	v_mfma_f32_16x16x32_f16 v[64:67], v[152:155], v[212:215], v[64:67]
	v_mfma_f32_16x16x32_f16 v[116:119], v[148:151], v[192:195], v[116:119]
	v_mfma_f32_16x16x32_f16 v[112:115], v[174:177], v[192:195], v[112:115]
	v_mfma_f32_16x16x32_f16 v[100:103], v[148:151], v[200:203], v[100:103]
	v_mfma_f32_16x16x32_f16 v[96:99], v[174:177], v[200:203], v[96:99]
	v_mfma_f32_16x16x32_f16 v[84:87], v[148:151], v[208:211], v[84:87]
	v_mfma_f32_16x16x32_f16 v[80:83], v[174:177], v[208:211], v[80:83]
	v_mfma_f32_16x16x32_f16 v[68:71], v[148:151], v[216:219], v[68:71]
	v_mfma_f32_16x16x32_f16 v[64:67], v[174:177], v[216:219], v[64:67]
	s_barrier
	s_add_i32 s43, s84, s68
	v_lshl_add_u64 v[178:179], s[50:51], 0, v[158:159]
	s_mov_b32 m0, s43
	ds_read_b128 v[188:191], v185 offset:16384
	ds_read_b128 v[192:195], v185 offset:17408
	ds_read_b128 v[196:199], v185 offset:18432
	ds_read_b128 v[200:203], v185 offset:19456
	ds_read_b128 v[204:207], v185 offset:20480
	ds_read_b128 v[208:211], v185 offset:21504
	ds_read_b128 v[212:215], v185 offset:22528
	ds_read_b128 v[216:219], v185 offset:23552
	global_load_lds_dwordx4 v[178:179], off
	s_add_i32 m0, s43, 0x2000
	s_add_u32 s54, s50, 0x40000
	v_lshl_add_u64 v[220:221], s[50:51], 0, v[162:163]
	s_addc_u32 s55, s51, 0
	s_add_i32 s43, s93, s68
	global_load_lds_dwordx4 v[220:221], off
	v_lshl_add_u64 v[222:223], s[54:55], 0, v[158:159]
	s_mov_b32 m0, s43
	v_lshl_add_u64 v[224:225], s[52:53], 0, v[160:161]
	global_load_lds_dwordx4 v[222:223], off
	v_lshl_add_u64 v[222:223], s[54:55], 0, v[162:163]
	s_add_i32 m0, s43, 0x2000
	s_nop 0
	global_load_lds_dwordx4 v[222:223], off
	v_lshl_add_u64 v[222:223], s[52:53], 0, v[156:157]
	s_mov_b32 m0, s74
	s_nop 0
	global_load_lds_dwordx4 v[222:223], off
	s_mov_b32 m0, s66
	s_nop 0
	global_load_lds_dwordx4 v[224:225], off
	s_waitcnt vmcnt(8)
	s_waitcnt lgkmcnt(0)
	s_barrier
	s_waitcnt lgkmcnt(0)
	v_mfma_f32_16x16x32_f16 v[60:63], v[128:131], v[188:191], v[60:63]
	v_mfma_f32_16x16x32_f16 v[56:59], v[136:139], v[188:191], v[56:59]
	v_mfma_f32_16x16x32_f16 v[44:47], v[128:131], v[196:199], v[44:47]
	v_mfma_f32_16x16x32_f16 v[40:43], v[136:139], v[196:199], v[40:43]
	v_mfma_f32_16x16x32_f16 v[28:31], v[128:131], v[204:207], v[28:31]
	v_mfma_f32_16x16x32_f16 v[24:27], v[136:139], v[204:207], v[24:27]
	v_mfma_f32_16x16x32_f16 v[12:15], v[128:131], v[212:215], v[12:15]
	v_mfma_f32_16x16x32_f16 v[8:11], v[136:139], v[212:215], v[8:11]
	v_mfma_f32_16x16x32_f16 v[60:63], v[132:135], v[192:195], v[60:63]
	v_mfma_f32_16x16x32_f16 v[56:59], v[140:143], v[192:195], v[56:59]
	v_mfma_f32_16x16x32_f16 v[44:47], v[132:135], v[200:203], v[44:47]
	v_mfma_f32_16x16x32_f16 v[40:43], v[140:143], v[200:203], v[40:43]
	v_mfma_f32_16x16x32_f16 v[28:31], v[132:135], v[208:211], v[28:31]
	v_mfma_f32_16x16x32_f16 v[24:27], v[140:143], v[208:211], v[24:27]
	v_mfma_f32_16x16x32_f16 v[12:15], v[132:135], v[216:219], v[12:15]
	v_mfma_f32_16x16x32_f16 v[8:11], v[140:143], v[216:219], v[8:11]
	v_mfma_f32_16x16x32_f16 v[52:55], v[144:147], v[188:191], v[52:55]
	v_mfma_f32_16x16x32_f16 v[48:51], v[152:155], v[188:191], v[48:51]
	v_mfma_f32_16x16x32_f16 v[36:39], v[144:147], v[196:199], v[36:39]
	v_mfma_f32_16x16x32_f16 v[32:35], v[152:155], v[196:199], v[32:35]
	v_mfma_f32_16x16x32_f16 v[20:23], v[144:147], v[204:207], v[20:23]
	v_mfma_f32_16x16x32_f16 v[16:19], v[152:155], v[204:207], v[16:19]
	v_mfma_f32_16x16x32_f16 v[4:7], v[144:147], v[212:215], v[4:7]
	v_mfma_f32_16x16x32_f16 v[0:3], v[152:155], v[212:215], v[0:3]
	v_mfma_f32_16x16x32_f16 v[52:55], v[148:151], v[192:195], v[52:55]
	v_mfma_f32_16x16x32_f16 v[48:51], v[174:177], v[192:195], v[48:51]
	v_mfma_f32_16x16x32_f16 v[36:39], v[148:151], v[200:203], v[36:39]
	v_mfma_f32_16x16x32_f16 v[32:35], v[174:177], v[200:203], v[32:35]
	v_mfma_f32_16x16x32_f16 v[20:23], v[148:151], v[208:211], v[20:23]
	v_mfma_f32_16x16x32_f16 v[16:19], v[174:177], v[208:211], v[16:19]
	v_mfma_f32_16x16x32_f16 v[4:7], v[148:151], v[216:219], v[4:7]
	v_mfma_f32_16x16x32_f16 v[0:3], v[174:177], v[216:219], v[0:3]
	s_barrier
; #define PG8_STAGE(bufoff, gbase, voff) do { _Pragma("unroll") for (int _i = 0; _i < 2; ++_i) \
;         __builtin_amdgcn_global_load_lds((const unsigned*)((const char*)(gbase) + (voff)[_i]), (PG8_LAS unsigned*)(lds + (bufoff) + ldsw + _i * 8192), 16, 0, 0); } while (0)
; #define PG8_LDA(dst, b, h) do { _Pragma("unroll") for (int m = 0; m < 4; ++m) _Pragma("unroll") for (int k = 0; k < 2; ++k) dst[m][k] = *(const PG8_LAS bf16x8*)(lds + PG8_SA(b, h) + aoff + m * 2048 + k * 1024); } while (0)
; #define PG8_LDB(dst, b, h) do { _Pragma("unroll") for (int n = 0; n < 2; ++n) _Pragma("unroll") for (int k = 0; k < 2; ++k) dst[n][k] = *(const PG8_LAS bf16x8*)(lds + PG8_SB(b, h) + boff + n * 2048 + k * 1024); } while (0)
; #define PG8_MMA(ai, bj, At, Bt) do { __builtin_amdgcn_s_setprio(1); _Pragma("unroll") for (int m = 0; m < 4; ++m) _Pragma("unroll") for (int n = 0; n < 2; ++n) _Pragma("unroll") for (int k = 0; k < 2; ++k) \
;         acc[ai][bj][m][n] = mma16<F16>(Bt[n][k], At[m][k], acc[ai][bj][m][n]); __builtin_amdgcn_s_setprio(0); } while (0)
; #define PG8_WAIT_V(n) asm volatile("s_waitcnt vmcnt(" #n ")" ::: "memory")
; #define PG8_WAIT_L(n) asm volatile("s_waitcnt lgkmcnt(" #n ")" ::: "memory")
; #define PG8_BAR __builtin_amdgcn_s_barrier()
; #define PG8_SCHED __builtin_amdgcn_sched_barrier(0)
; template <class Epi, class Sched, bool ALIGN_EPI = false, bool SP2 = false, bool F16 = false>
; __device__ __forceinline__ void gemm_phase(PG8_LAS unsigned char* lds, const Gemm g, const Sched& S, const Epi& E, const int wid_in) {
;     ...
;             PG8_LDB(B0, 1, 0); PG8_LDB(B1, 1, 1); PG8_SCHED; PG8_LDA(At, 1, 0); PG8_STAGE(PG8_SA(0, 1), a2 + hstep, voffA);
;             PG8_WAIT_V(8); PG8_WAIT_L(0); PG8_BAR; PG8_MMA(0, 0, At, B0); PG8_MMA(0, 1, At, B1); PG8_BAR; PG8_SCHED;
	s_add_i32 s43, 0, 0x18000
	s_add_i32 s54, 0, 0x1c000
	v_add_u32_e32 v140, s43, v182
	v_add_u32_e32 v165, s54, v182
	ds_read_b128 v[128:131], v140
	ds_read_b128 v[132:135], v140 offset:1024
	ds_read_b128 v[136:139], v140 offset:2048
	ds_read_b128 v[140:143], v140 offset:3072
	ds_read_b128 v[144:147], v165
	ds_read_b128 v[148:151], v165 offset:1024
	ds_read_b128 v[152:155], v165 offset:2048
	ds_read_b128 v[174:177], v165 offset:3072
	s_add_u32 s52, s52, 0x40000
	s_addc_u32 s53, s53, 0
	s_mov_b32 m0, s90
	v_lshl_add_u64 v[226:227], s[52:53], 0, v[156:157]
	ds_read_b128 v[188:191], v185 offset:32768
	ds_read_b128 v[192:195], v185 offset:33792
	ds_read_b128 v[196:199], v185 offset:34816
	ds_read_b128 v[200:203], v185 offset:35840
	ds_read_b128 v[204:207], v185 offset:36864
	ds_read_b128 v[208:211], v185 offset:37888
	ds_read_b128 v[212:215], v185 offset:38912
	ds_read_b128 v[216:219], v185 offset:39936
	global_load_lds_dwordx4 v[226:227], off
	v_lshl_add_u64 v[226:227], s[52:53], 0, v[160:161]
	s_mov_b32 m0, s63
	s_nop 0
	global_load_lds_dwordx4 v[226:227], off
	s_waitcnt vmcnt(8)
	s_waitcnt lgkmcnt(0)
	s_barrier
	s_waitcnt lgkmcnt(0)
	v_mfma_f32_16x16x32_f16 v[124:127], v[128:131], v[188:191], v[124:127]
	v_mfma_f32_16x16x32_f16 v[120:123], v[136:139], v[188:191], v[120:123]
	v_mfma_f32_16x16x32_f16 v[108:111], v[128:131], v[196:199], v[108:111]
	v_mfma_f32_16x16x32_f16 v[104:107], v[136:139], v[196:199], v[104:107]
	v_mfma_f32_16x16x32_f16 v[92:95], v[128:131], v[204:207], v[92:95]
	v_mfma_f32_16x16x32_f16 v[88:91], v[136:139], v[204:207], v[88:91]
	v_mfma_f32_16x16x32_f16 v[76:79], v[128:131], v[212:215], v[76:79]
	v_mfma_f32_16x16x32_f16 v[72:75], v[136:139], v[212:215], v[72:75]
	v_mfma_f32_16x16x32_f16 v[124:127], v[132:135], v[192:195], v[124:127]
	v_mfma_f32_16x16x32_f16 v[120:123], v[140:143], v[192:195], v[120:123]
	v_mfma_f32_16x16x32_f16 v[108:111], v[132:135], v[200:203], v[108:111]
	v_mfma_f32_16x16x32_f16 v[104:107], v[140:143], v[200:203], v[104:107]
	v_mfma_f32_16x16x32_f16 v[92:95], v[132:135], v[208:211], v[92:95]
	v_mfma_f32_16x16x32_f16 v[88:91], v[140:143], v[208:211], v[88:91]
	v_mfma_f32_16x16x32_f16 v[76:79], v[132:135], v[216:219], v[76:79]
	v_mfma_f32_16x16x32_f16 v[72:75], v[140:143], v[216:219], v[72:75]
	v_mfma_f32_16x16x32_f16 v[116:119], v[144:147], v[188:191], v[116:119]
	v_mfma_f32_16x16x32_f16 v[112:115], v[152:155], v[188:191], v[112:115]
	v_mfma_f32_16x16x32_f16 v[100:103], v[144:147], v[196:199], v[100:103]
	v_mfma_f32_16x16x32_f16 v[96:99], v[152:155], v[196:199], v[96:99]
	v_mfma_f32_16x16x32_f16 v[84:87], v[144:147], v[204:207], v[84:87]
	v_mfma_f32_16x16x32_f16 v[80:83], v[152:155], v[204:207], v[80:83]
	v_mfma_f32_16x16x32_f16 v[68:71], v[144:147], v[212:215], v[68:71]
	v_mfma_f32_16x16x32_f16 v[64:67], v[152:155], v[212:215], v[64:67]
	v_mfma_f32_16x16x32_f16 v[116:119], v[148:151], v[192:195], v[116:119]
	v_mfma_f32_16x16x32_f16 v[112:115], v[174:177], v[192:195], v[112:115]
	v_mfma_f32_16x16x32_f16 v[100:103], v[148:151], v[200:203], v[100:103]
	v_mfma_f32_16x16x32_f16 v[96:99], v[174:177], v[200:203], v[96:99]
	v_mfma_f32_16x16x32_f16 v[84:87], v[148:151], v[208:211], v[84:87]
	v_mfma_f32_16x16x32_f16 v[80:83], v[174:177], v[208:211], v[80:83]
	v_mfma_f32_16x16x32_f16 v[68:71], v[148:151], v[216:219], v[68:71]
	v_mfma_f32_16x16x32_f16 v[64:67], v[174:177], v[216:219], v[64:67]
	s_barrier
; #define PG8_STAGE(bufoff, gbase, voff) do { _Pragma("unroll") for (int _i = 0; _i < 2; ++_i) \
;         __builtin_amdgcn_global_load_lds((const unsigned*)((const char*)(gbase) + (voff)[_i]), (PG8_LAS unsigned*)(lds + (bufoff) + ldsw + _i * 8192), 16, 0, 0); } while (0)
; #define PG8_LDA(dst, b, h) do { _Pragma("unroll") for (int m = 0; m < 4; ++m) _Pragma("unroll") for (int k = 0; k < 2; ++k) dst[m][k] = *(const PG8_LAS bf16x8*)(lds + PG8_SA(b, h) + aoff + m * 2048 + k * 1024); } while (0)
; #define PG8_MMA(ai, bj, At, Bt) do { __builtin_amdgcn_s_setprio(1); _Pragma("unroll") for (int m = 0; m < 4; ++m) _Pragma("unroll") for (int n = 0; n < 2; ++n) _Pragma("unroll") for (int k = 0; k < 2; ++k) \
;         acc[ai][bj][m][n] = mma16<F16>(Bt[n][k], At[m][k], acc[ai][bj][m][n]); __builtin_amdgcn_s_setprio(0); } while (0)
; #define PG8_WAIT_V(n) asm volatile("s_waitcnt vmcnt(" #n ")" ::: "memory")
; #define PG8_WAIT_L(n) asm volatile("s_waitcnt lgkmcnt(" #n ")" ::: "memory")
; #define PG8_BAR __builtin_amdgcn_s_barrier()
; #define PG8_SCHED __builtin_amdgcn_sched_barrier(0)
; template <class Epi, class Sched, bool ALIGN_EPI = false, bool SP2 = false, bool F16 = false>
; __device__ __forceinline__ void gemm_phase(PG8_LAS unsigned char* lds, const Gemm g, const Sched& S, const Epi& E, const int wid_in) {
;     ...
;             PG8_LDA(At, 1, 1); PG8_STAGE(PG8_SB(1, 0), b3, voffB); PG8_STAGE(PG8_SB(1, 1), b3 + hstep, voffB); PG8_STAGE(PG8_SA(1, 0), a3, voffA);
;             PG8_WAIT_V(8); PG8_WAIT_L(0); PG8_BAR; PG8_MMA(1, 0, At, B0); PG8_MMA(1, 1, At, B1); PG8_BAR; PG8_SCHED;
;     ...
;         if constexpr (ALIGN_EPI) { if (wr == 0) PG8_BAR; }
	s_add_i32 s43, s43, s68
	v_lshl_add_u64 v[178:179], v[178:179], 0, s[26:27]
	s_mov_b32 m0, s43
	ds_read_b128 v[188:191], v185 offset:49152
	ds_read_b128 v[192:195], v185 offset:50176
	ds_read_b128 v[196:199], v185 offset:51200
	ds_read_b128 v[200:203], v185 offset:52224
	ds_read_b128 v[204:207], v185 offset:53248
	ds_read_b128 v[208:211], v185 offset:54272
	ds_read_b128 v[212:215], v185 offset:55296
	ds_read_b128 v[216:219], v185 offset:56320
	global_load_lds_dwordx4 v[178:179], off
	s_add_i32 m0, s43, 0x2000
	s_add_u32 s50, s50, 0x40080
	v_lshl_add_u64 v[178:179], v[220:221], 0, s[26:27]
	s_addc_u32 s51, s51, 0
	s_add_i32 s43, s54, s68
	global_load_lds_dwordx4 v[178:179], off
	v_lshl_add_u64 v[178:179], s[50:51], 0, v[158:159]
	s_mov_b32 m0, s43
	s_nop 0
	global_load_lds_dwordx4 v[178:179], off
	v_lshl_add_u64 v[178:179], s[50:51], 0, v[162:163]
	s_add_i32 m0, s43, 0x2000
	s_nop 0
	global_load_lds_dwordx4 v[178:179], off
	v_lshl_add_u64 v[178:179], v[222:223], 0, s[26:27]
	s_mov_b32 m0, s75
	s_nop 0
	global_load_lds_dwordx4 v[178:179], off
	v_lshl_add_u64 v[178:179], v[224:225], 0, s[26:27]
	s_mov_b32 m0, s67
	s_nop 0
	global_load_lds_dwordx4 v[178:179], off
	s_waitcnt vmcnt(8)
	s_waitcnt lgkmcnt(0)
	s_barrier
	s_waitcnt lgkmcnt(0)
	v_mfma_f32_16x16x32_f16 v[60:63], v[128:131], v[188:191], v[60:63]
	v_mfma_f32_16x16x32_f16 v[56:59], v[136:139], v[188:191], v[56:59]
	v_mfma_f32_16x16x32_f16 v[44:47], v[128:131], v[196:199], v[44:47]
	v_mfma_f32_16x16x32_f16 v[40:43], v[136:139], v[196:199], v[40:43]
	v_mfma_f32_16x16x32_f16 v[28:31], v[128:131], v[204:207], v[28:31]
	v_mfma_f32_16x16x32_f16 v[24:27], v[136:139], v[204:207], v[24:27]
	v_mfma_f32_16x16x32_f16 v[12:15], v[128:131], v[212:215], v[12:15]
	v_mfma_f32_16x16x32_f16 v[8:11], v[136:139], v[212:215], v[8:11]
	v_mfma_f32_16x16x32_f16 v[60:63], v[132:135], v[192:195], v[60:63]
	v_mfma_f32_16x16x32_f16 v[56:59], v[140:143], v[192:195], v[56:59]
	v_mfma_f32_16x16x32_f16 v[44:47], v[132:135], v[200:203], v[44:47]
	v_mfma_f32_16x16x32_f16 v[40:43], v[140:143], v[200:203], v[40:43]
	v_mfma_f32_16x16x32_f16 v[28:31], v[132:135], v[208:211], v[28:31]
	v_mfma_f32_16x16x32_f16 v[24:27], v[140:143], v[208:211], v[24:27]
	v_mfma_f32_16x16x32_f16 v[12:15], v[132:135], v[216:219], v[12:15]
	v_mfma_f32_16x16x32_f16 v[8:11], v[140:143], v[216:219], v[8:11]
	v_mfma_f32_16x16x32_f16 v[52:55], v[144:147], v[188:191], v[52:55]
	v_mfma_f32_16x16x32_f16 v[48:51], v[152:155], v[188:191], v[48:51]
	v_mfma_f32_16x16x32_f16 v[36:39], v[144:147], v[196:199], v[36:39]
	v_mfma_f32_16x16x32_f16 v[32:35], v[152:155], v[196:199], v[32:35]
	v_mfma_f32_16x16x32_f16 v[20:23], v[144:147], v[204:207], v[20:23]
	v_mfma_f32_16x16x32_f16 v[16:19], v[152:155], v[204:207], v[16:19]
	v_mfma_f32_16x16x32_f16 v[4:7], v[144:147], v[212:215], v[4:7]
	v_mfma_f32_16x16x32_f16 v[0:3], v[152:155], v[212:215], v[0:3]
	v_mfma_f32_16x16x32_f16 v[52:55], v[148:151], v[192:195], v[52:55]
	v_mfma_f32_16x16x32_f16 v[48:51], v[174:177], v[192:195], v[48:51]
	v_mfma_f32_16x16x32_f16 v[36:39], v[148:151], v[200:203], v[36:39]
	v_mfma_f32_16x16x32_f16 v[32:35], v[174:177], v[200:203], v[32:35]
	v_mfma_f32_16x16x32_f16 v[20:23], v[148:151], v[208:211], v[20:23]
	v_mfma_f32_16x16x32_f16 v[16:19], v[174:177], v[208:211], v[16:19]
	v_mfma_f32_16x16x32_f16 v[4:7], v[148:151], v[216:219], v[4:7]
	v_mfma_f32_16x16x32_f16 v[0:3], v[174:177], v[216:219], v[0:3]
	s_barrier
	s_add_i32 s42, s42, 2
	s_add_u32 s48, s48, 0x100
	s_addc_u32 s49, s49, 0
	s_add_u32 s40, s40, 0x100
	s_addc_u32 s41, s41, 0
	s_cmp_gt_u32 s42, 13
	s_cbranch_scc0 .LBB0_2226
	s_setprio 0
	s_and_b64 vcc, exec, s[16:17]
	s_cbranch_vccz .LBB0_2229
	s_barrier

; #define PG8_STAGE(bufoff, gbase, voff) do { _Pragma("unroll") for (int _i = 0; _i < 2; ++_i) \
;         __builtin_amdgcn_global_load_lds((const unsigned*)((const char*)(gbase) + (voff)[_i]), (PG8_LAS unsigned*)(lds + (bufoff) + ldsw + _i * 8192), 16, 0, 0); } while (0)
; #define PG8_LDA(dst, b, h) do { _Pragma("unroll") for (int m = 0; m < 4; ++m) _Pragma("unroll") for (int k = 0; k < 2; ++k) dst[m][k] = *(const PG8_LAS bf16x8*)(lds + PG8_SA(b, h) + aoff + m * 2048 + k * 1024); } while (0)
; #define PG8_LDB(dst, b, h) do { _Pragma("unroll") for (int n = 0; n < 2; ++n) _Pragma("unroll") for (int k = 0; k < 2; ++k) dst[n][k] = *(const PG8_LAS bf16x8*)(lds + PG8_SB(b, h) + boff + n * 2048 + k * 1024); } while (0)
; #define PG8_SCHED __builtin_amdgcn_sched_barrier(0)
; template <class Epi, class Sched, bool ALIGN_EPI = false, bool SP2 = false, bool F16 = false>
; __device__ __forceinline__ void gemm_phase(PG8_LAS unsigned char* lds, const Gemm g, const Sched& S, const Epi& E, const int wid_in) {
;     ...
;         const char* nA = has_next ? (const char*)g.A + (size_t)nxt.pm * tstep : cA; const char* nB = has_next ? (const char*)g.Bt + (size_t)nxt.pn * tstep : cB;
;         for (int t = 0; t < nt; t += 2) {
;             const bool last = (t == nt - 2);
;             const char* a1 = cA + (size_t)(t + 1) * kstep;
;             const char* a2 = last ? nA : cA + (size_t)(t + 2) * kstep; const char* b2 = last ? nB : cB + (size_t)(t + 2) * kstep;
;             const char* a3 = a2 + kstep; const char* b3 = b2 + kstep;
;             if (last && has_next) S.a_ready(nxt);
;             if constexpr (SP2) {
;             PG8_LDB(B0, 0, 0); PG8_LDB(B1, 0, 1); PG8_SCHED; PG8_LDA(At, 0, 0); PG8_STAGE(PG8_SA(1, 1), a1 + hstep, voffA);
;     ...
;         for (int a = 0; a < 2; ++a)
; #pragma unroll
;             for (int b = 0; b < 2; ++b)
; #pragma unroll
;                 for (int m = 0; m < 4; ++m)
; #pragma unroll
;                     for (int n = 0; n < 2; ++n) acc[a][b][m][n] = (f32x4){0.f, 0.f, 0.f, 0.f};
.LBB0_2488:
	s_ashr_i32 s29, s28, 31
	s_lshl_b64 s[30:31], s[28:29], 19
	s_add_u32 s30, s15, s30
	s_addc_u32 s31, s40, s31
	s_and_b64 s[34:35], s[10:11], exec
	s_cselect_b32 s29, s31, s43
	s_cselect_b32 s37, s30, s42
	s_ashr_i32 s27, s26, 31
	s_lshl_b64 s[34:35], s[26:27], 19
	s_add_u32 s34, s41, s34
	s_addc_u32 s35, s48, s35
	s_and_b64 s[46:47], s[10:11], exec
	s_cselect_b32 s27, s35, s45
	s_cselect_b32 s56, s34, s44
	s_add_u32 s42, s42, 0x40080
	s_addc_u32 s43, s43, 0
	s_add_u32 s57, s44, 0x100
	v_mov_b32_e32 v0, 0
	s_addc_u32 s58, s45, 0
	s_mov_b32 s59, -2
	v_mov_b32_e32 v1, v0
	v_mov_b32_e32 v2, v0
	v_mov_b32_e32 v3, v0
	v_mov_b32_e32 v4, v0
	v_mov_b32_e32 v5, v0
	v_mov_b32_e32 v6, v0
	v_mov_b32_e32 v7, v0
	v_mov_b32_e32 v16, v0
	v_mov_b32_e32 v17, v0
	v_mov_b32_e32 v18, v0
	v_mov_b32_e32 v19, v0
	v_mov_b32_e32 v20, v0
	v_mov_b32_e32 v21, v0
	v_mov_b32_e32 v22, v0
	v_mov_b32_e32 v23, v0
	v_mov_b32_e32 v32, v0
	v_mov_b32_e32 v33, v0
	v_mov_b32_e32 v34, v0
	v_mov_b32_e32 v35, v0
	v_mov_b32_e32 v36, v0
	v_mov_b32_e32 v37, v0
	v_mov_b32_e32 v38, v0
	v_mov_b32_e32 v39, v0
	v_mov_b32_e32 v48, v0
	v_mov_b32_e32 v49, v0
	v_mov_b32_e32 v50, v0
	v_mov_b32_e32 v51, v0
	v_mov_b32_e32 v52, v0
	v_mov_b32_e32 v53, v0
	v_mov_b32_e32 v54, v0
	v_mov_b32_e32 v55, v0
	v_mov_b32_e32 v8, v0
	v_mov_b32_e32 v9, v0
	v_mov_b32_e32 v10, v0
	v_mov_b32_e32 v11, v0
	v_mov_b32_e32 v12, v0
	v_mov_b32_e32 v13, v0
	v_mov_b32_e32 v14, v0
	v_mov_b32_e32 v15, v0
	v_mov_b32_e32 v24, v0
	v_mov_b32_e32 v25, v0
	v_mov_b32_e32 v26, v0
	v_mov_b32_e32 v27, v0
	v_mov_b32_e32 v28, v0
	v_mov_b32_e32 v29, v0
	v_mov_b32_e32 v30, v0
	v_mov_b32_e32 v31, v0
	v_mov_b32_e32 v40, v0
	v_mov_b32_e32 v41, v0
	v_mov_b32_e32 v42, v0
	v_mov_b32_e32 v43, v0
	v_mov_b32_e32 v44, v0
	v_mov_b32_e32 v45, v0
	v_mov_b32_e32 v46, v0
	v_mov_b32_e32 v47, v0
	v_mov_b32_e32 v56, v0
	v_mov_b32_e32 v57, v0
	v_mov_b32_e32 v58, v0
	v_mov_b32_e32 v59, v0
	v_mov_b32_e32 v60, v0
	v_mov_b32_e32 v61, v0
	v_mov_b32_e32 v62, v0
	v_mov_b32_e32 v63, v0
	v_mov_b32_e32 v64, v0
	v_mov_b32_e32 v65, v0
	v_mov_b32_e32 v66, v0
	v_mov_b32_e32 v67, v0
	v_mov_b32_e32 v68, v0
	v_mov_b32_e32 v69, v0
	v_mov_b32_e32 v70, v0
	v_mov_b32_e32 v71, v0
	v_mov_b32_e32 v80, v0
	v_mov_b32_e32 v81, v0
	v_mov_b32_e32 v82, v0
	v_mov_b32_e32 v83, v0
	v_mov_b32_e32 v84, v0
	v_mov_b32_e32 v85, v0
	v_mov_b32_e32 v86, v0
	v_mov_b32_e32 v87, v0
	v_mov_b32_e32 v96, v0
	v_mov_b32_e32 v97, v0
	v_mov_b32_e32 v98, v0
	v_mov_b32_e32 v99, v0
	v_mov_b32_e32 v100, v0
	v_mov_b32_e32 v101, v0
	v_mov_b32_e32 v102, v0
	v_mov_b32_e32 v103, v0
	v_mov_b32_e32 v112, v0
	v_mov_b32_e32 v113, v0
	v_mov_b32_e32 v114, v0
	v_mov_b32_e32 v115, v0
	v_mov_b32_e32 v116, v0
	v_mov_b32_e32 v117, v0
	v_mov_b32_e32 v118, v0
	v_mov_b32_e32 v119, v0
	v_mov_b32_e32 v72, v0
	v_mov_b32_e32 v73, v0
	v_mov_b32_e32 v74, v0
	v_mov_b32_e32 v75, v0
	v_mov_b32_e32 v76, v0
	v_mov_b32_e32 v77, v0
	v_mov_b32_e32 v78, v0
	v_mov_b32_e32 v79, v0
	v_mov_b32_e32 v88, v0
	v_mov_b32_e32 v89, v0
	v_mov_b32_e32 v90, v0
	v_mov_b32_e32 v91, v0
	v_mov_b32_e32 v92, v0
	v_mov_b32_e32 v93, v0
	v_mov_b32_e32 v94, v0
	v_mov_b32_e32 v95, v0
	v_mov_b32_e32 v104, v0
	v_mov_b32_e32 v105, v0
	v_mov_b32_e32 v106, v0
	v_mov_b32_e32 v107, v0
	v_mov_b32_e32 v108, v0
	v_mov_b32_e32 v109, v0
	v_mov_b32_e32 v110, v0
	v_mov_b32_e32 v111, v0
	v_mov_b32_e32 v120, v0
	v_mov_b32_e32 v121, v0
	v_mov_b32_e32 v122, v0
	v_mov_b32_e32 v123, v0
	v_mov_b32_e32 v124, v0
	v_mov_b32_e32 v125, v0
	v_mov_b32_e32 v126, v0
	v_mov_b32_e32 v127, v0
	s_cmp_ge_u32 s3, 4
	s_cbranch_scc0 .Lgsp_19
	s_setprio 1
.Lgsp_19:
.LBB0_2489:
	ds_read_b128 v[128:131], v189
	ds_read_b128 v[132:135], v189 offset:1024
	ds_read_b128 v[136:139], v189 offset:2048
	ds_read_b128 v[140:143], v189 offset:3072
	ds_read_b128 v[144:147], v190
	ds_read_b128 v[148:151], v190 offset:1024
	ds_read_b128 v[168:171], v190 offset:2048
	ds_read_b128 v[172:175], v190 offset:3072
	s_add_u32 s44, s42, 0xfffc0080
	s_addc_u32 s45, s43, -1
	s_cmp_eq_u32 s59, 12
	s_cselect_b32 s47, s29, s45
	s_cselect_b32 s46, s37, s44
	s_cselect_b32 s45, s27, s58
	s_cselect_b32 s44, s56, s57
	s_mov_b32 m0, s91
	v_lshl_add_u64 v[184:185], s[42:43], 0, v[160:161]
	ds_read_b128 v[176:179], v191
	ds_read_b128 v[180:183], v191 offset:1024
	ds_read_b128 v[192:195], v191 offset:2048
	ds_read_b128 v[196:199], v191 offset:3072
	ds_read_b128 v[200:203], v191 offset:4096
	ds_read_b128 v[204:207], v191 offset:5120
	ds_read_b128 v[208:211], v191 offset:6144
	ds_read_b128 v[212:215], v191 offset:7168
	global_load_lds_dwordx4 v[184:185], off
	v_lshl_add_u64 v[184:185], s[42:43], 0, v[162:163]
	s_add_i32 m0, s74, 0xe000
	s_nop 0
	global_load_lds_dwordx4 v[184:185], off
	s_waitcnt vmcnt(8)
	s_waitcnt lgkmcnt(0)
	s_barrier
; #define PG8_STAGE(bufoff, gbase, voff) do { _Pragma("unroll") for (int _i = 0; _i < 2; ++_i) \
;         __builtin_amdgcn_global_load_lds((const unsigned*)((const char*)(gbase) + (voff)[_i]), (PG8_LAS unsigned*)(lds + (bufoff) + ldsw + _i * 8192), 16, 0, 0); } while (0)
; #define PG8_LDA(dst, b, h) do { _Pragma("unroll") for (int m = 0; m < 4; ++m) _Pragma("unroll") for (int k = 0; k < 2; ++k) dst[m][k] = *(const PG8_LAS bf16x8*)(lds + PG8_SA(b, h) + aoff + m * 2048 + k * 1024); } while (0)
; #define PG8_MMA(ai, bj, At, Bt) do { __builtin_amdgcn_s_setprio(1); _Pragma("unroll") for (int m = 0; m < 4; ++m) _Pragma("unroll") for (int n = 0; n < 2; ++n) _Pragma("unroll") for (int k = 0; k < 2; ++k) \
;         acc[ai][bj][m][n] = mma16<F16>(Bt[n][k], At[m][k], acc[ai][bj][m][n]); __builtin_amdgcn_s_setprio(0); } while (0)
; #define PG8_WAIT_V(n) asm volatile("s_waitcnt vmcnt(" #n ")" ::: "memory")
; #define PG8_WAIT_L(n) asm volatile("s_waitcnt lgkmcnt(" #n ")" ::: "memory")
; #define PG8_BAR __builtin_amdgcn_s_barrier()
; #define PG8_SCHED __builtin_amdgcn_sched_barrier(0)
; template <class Epi, class Sched, bool ALIGN_EPI = false, bool SP2 = false, bool F16 = false>
; __device__ __forceinline__ void gemm_phase(PG8_LAS unsigned char* lds, const Gemm g, const Sched& S, const Epi& E, const int wid_in) {
;     ...
;             PG8_WAIT_V(8); PG8_WAIT_L(0); PG8_BAR; PG8_MMA(0, 0, At, B0); PG8_MMA(0, 1, At, B1); PG8_BAR; PG8_SCHED;
;             PG8_LDA(At, 0, 1); PG8_STAGE(PG8_SB(0, 0), b2, voffB); PG8_STAGE(PG8_SB(0, 1), b2 + hstep, voffB); PG8_STAGE(PG8_SA(0, 0), a2, voffA);
;             PG8_WAIT_V(8); PG8_WAIT_L(0); PG8_BAR; PG8_MMA(1, 0, At, B0); PG8_MMA(1, 1, At, B1); PG8_BAR; PG8_SCHED;
	s_waitcnt lgkmcnt(0)
	v_mfma_f32_16x16x32_bf16 v[124:127], v[128:131], v[176:179], v[124:127]
	v_mfma_f32_16x16x32_bf16 v[120:123], v[136:139], v[176:179], v[120:123]
	v_mfma_f32_16x16x32_bf16 v[108:111], v[128:131], v[192:195], v[108:111]
	v_mfma_f32_16x16x32_bf16 v[104:107], v[136:139], v[192:195], v[104:107]
	v_mfma_f32_16x16x32_bf16 v[92:95], v[128:131], v[200:203], v[92:95]
	v_mfma_f32_16x16x32_bf16 v[88:91], v[136:139], v[200:203], v[88:91]
	v_mfma_f32_16x16x32_bf16 v[76:79], v[128:131], v[208:211], v[76:79]
	v_mfma_f32_16x16x32_bf16 v[72:75], v[136:139], v[208:211], v[72:75]
	v_mfma_f32_16x16x32_bf16 v[124:127], v[132:135], v[180:183], v[124:127]
	v_mfma_f32_16x16x32_bf16 v[120:123], v[140:143], v[180:183], v[120:123]
	v_mfma_f32_16x16x32_bf16 v[108:111], v[132:135], v[196:199], v[108:111]
	v_mfma_f32_16x16x32_bf16 v[104:107], v[140:143], v[196:199], v[104:107]
	v_mfma_f32_16x16x32_bf16 v[92:95], v[132:135], v[204:207], v[92:95]
	v_mfma_f32_16x16x32_bf16 v[88:91], v[140:143], v[204:207], v[88:91]
	v_mfma_f32_16x16x32_bf16 v[76:79], v[132:135], v[212:215], v[76:79]
	v_mfma_f32_16x16x32_bf16 v[72:75], v[140:143], v[212:215], v[72:75]
	v_mfma_f32_16x16x32_bf16 v[116:119], v[144:147], v[176:179], v[116:119]
	v_mfma_f32_16x16x32_bf16 v[112:115], v[168:171], v[176:179], v[112:115]
	v_mfma_f32_16x16x32_bf16 v[100:103], v[144:147], v[192:195], v[100:103]
	v_mfma_f32_16x16x32_bf16 v[96:99], v[168:171], v[192:195], v[96:99]
	v_mfma_f32_16x16x32_bf16 v[84:87], v[144:147], v[200:203], v[84:87]
	v_mfma_f32_16x16x32_bf16 v[80:83], v[168:171], v[200:203], v[80:83]
	v_mfma_f32_16x16x32_bf16 v[68:71], v[144:147], v[208:211], v[68:71]
	v_mfma_f32_16x16x32_bf16 v[64:67], v[168:171], v[208:211], v[64:67]
	v_mfma_f32_16x16x32_bf16 v[116:119], v[148:151], v[180:183], v[116:119]
	v_mfma_f32_16x16x32_bf16 v[112:115], v[172:175], v[180:183], v[112:115]
	v_mfma_f32_16x16x32_bf16 v[100:103], v[148:151], v[196:199], v[100:103]
	v_mfma_f32_16x16x32_bf16 v[96:99], v[172:175], v[196:199], v[96:99]
	v_mfma_f32_16x16x32_bf16 v[84:87], v[148:151], v[204:207], v[84:87]
	v_mfma_f32_16x16x32_bf16 v[80:83], v[172:175], v[204:207], v[80:83]
	v_mfma_f32_16x16x32_bf16 v[68:71], v[148:151], v[212:215], v[68:71]
	v_mfma_f32_16x16x32_bf16 v[64:67], v[172:175], v[212:215], v[64:67]
	s_barrier
	s_add_i32 s60, s53, s68
	v_lshl_add_u64 v[184:185], s[44:45], 0, v[154:155]
	s_mov_b32 m0, s60
	ds_read_b128 v[176:179], v191 offset:16384
	ds_read_b128 v[180:183], v191 offset:17408
	ds_read_b128 v[192:195], v191 offset:18432
	ds_read_b128 v[196:199], v191 offset:19456
	ds_read_b128 v[200:203], v191 offset:20480
	ds_read_b128 v[204:207], v191 offset:21504
	ds_read_b128 v[208:211], v191 offset:22528
	ds_read_b128 v[212:215], v191 offset:23552
	global_load_lds_dwordx4 v[184:185], off
	s_add_i32 m0, s60, 0x2000
	s_add_u32 s60, s44, 0x40000
	v_lshl_add_u64 v[216:217], s[44:45], 0, v[158:159]
	s_addc_u32 s61, s45, 0
	s_add_i32 s62, s54, s68
	global_load_lds_dwordx4 v[216:217], off
	v_lshl_add_u64 v[218:219], s[60:61], 0, v[154:155]
	s_mov_b32 m0, s62
	v_lshl_add_u64 v[220:221], s[46:47], 0, v[156:157]
	global_load_lds_dwordx4 v[218:219], off
	v_lshl_add_u64 v[218:219], s[60:61], 0, v[158:159]
	s_add_i32 m0, s62, 0x2000
	s_nop 0
	global_load_lds_dwordx4 v[218:219], off
	v_lshl_add_u64 v[218:219], s[46:47], 0, v[152:153]
	s_mov_b32 m0, s74
	s_nop 0
	global_load_lds_dwordx4 v[218:219], off
	s_mov_b32 m0, s66
	s_nop 0
	global_load_lds_dwordx4 v[220:221], off
	s_waitcnt vmcnt(8)
	s_waitcnt lgkmcnt(0)
	s_barrier
	s_waitcnt lgkmcnt(0)
	v_mfma_f32_16x16x32_bf16 v[60:63], v[128:131], v[176:179], v[60:63]
	v_mfma_f32_16x16x32_bf16 v[56:59], v[136:139], v[176:179], v[56:59]
	v_mfma_f32_16x16x32_bf16 v[44:47], v[128:131], v[192:195], v[44:47]
	v_mfma_f32_16x16x32_bf16 v[40:43], v[136:139], v[192:195], v[40:43]
	v_mfma_f32_16x16x32_bf16 v[28:31], v[128:131], v[200:203], v[28:31]
	v_mfma_f32_16x16x32_bf16 v[24:27], v[136:139], v[200:203], v[24:27]
	v_mfma_f32_16x16x32_bf16 v[12:15], v[128:131], v[208:211], v[12:15]
	v_mfma_f32_16x16x32_bf16 v[8:11], v[136:139], v[208:211], v[8:11]
	v_mfma_f32_16x16x32_bf16 v[60:63], v[132:135], v[180:183], v[60:63]
	v_mfma_f32_16x16x32_bf16 v[56:59], v[140:143], v[180:183], v[56:59]
	v_mfma_f32_16x16x32_bf16 v[44:47], v[132:135], v[196:199], v[44:47]
	v_mfma_f32_16x16x32_bf16 v[40:43], v[140:143], v[196:199], v[40:43]
	v_mfma_f32_16x16x32_bf16 v[28:31], v[132:135], v[204:207], v[28:31]
	v_mfma_f32_16x16x32_bf16 v[24:27], v[140:143], v[204:207], v[24:27]
	v_mfma_f32_16x16x32_bf16 v[12:15], v[132:135], v[212:215], v[12:15]
	v_mfma_f32_16x16x32_bf16 v[8:11], v[140:143], v[212:215], v[8:11]
	v_mfma_f32_16x16x32_bf16 v[52:55], v[144:147], v[176:179], v[52:55]
	v_mfma_f32_16x16x32_bf16 v[48:51], v[168:171], v[176:179], v[48:51]
	v_mfma_f32_16x16x32_bf16 v[36:39], v[144:147], v[192:195], v[36:39]
	v_mfma_f32_16x16x32_bf16 v[32:35], v[168:171], v[192:195], v[32:35]
	v_mfma_f32_16x16x32_bf16 v[20:23], v[144:147], v[200:203], v[20:23]
	v_mfma_f32_16x16x32_bf16 v[16:19], v[168:171], v[200:203], v[16:19]
	v_mfma_f32_16x16x32_bf16 v[4:7], v[144:147], v[208:211], v[4:7]
	v_mfma_f32_16x16x32_bf16 v[0:3], v[168:171], v[208:211], v[0:3]
	v_mfma_f32_16x16x32_bf16 v[52:55], v[148:151], v[180:183], v[52:55]
	v_mfma_f32_16x16x32_bf16 v[48:51], v[172:175], v[180:183], v[48:51]
	v_mfma_f32_16x16x32_bf16 v[36:39], v[148:151], v[196:199], v[36:39]
	v_mfma_f32_16x16x32_bf16 v[32:35], v[172:175], v[196:199], v[32:35]
	v_mfma_f32_16x16x32_bf16 v[20:23], v[148:151], v[204:207], v[20:23]
	v_mfma_f32_16x16x32_bf16 v[16:19], v[172:175], v[204:207], v[16:19]
	v_mfma_f32_16x16x32_bf16 v[4:7], v[148:151], v[212:215], v[4:7]
	v_mfma_f32_16x16x32_bf16 v[0:3], v[172:175], v[212:215], v[0:3]
	s_barrier
; #define PG8_STAGE(bufoff, gbase, voff) do { _Pragma("unroll") for (int _i = 0; _i < 2; ++_i) \
;         __builtin_amdgcn_global_load_lds((const unsigned*)((const char*)(gbase) + (voff)[_i]), (PG8_LAS unsigned*)(lds + (bufoff) + ldsw + _i * 8192), 16, 0, 0); } while (0)
; #define PG8_LDA(dst, b, h) do { _Pragma("unroll") for (int m = 0; m < 4; ++m) _Pragma("unroll") for (int k = 0; k < 2; ++k) dst[m][k] = *(const PG8_LAS bf16x8*)(lds + PG8_SA(b, h) + aoff + m * 2048 + k * 1024); } while (0)
; #define PG8_LDB(dst, b, h) do { _Pragma("unroll") for (int n = 0; n < 2; ++n) _Pragma("unroll") for (int k = 0; k < 2; ++k) dst[n][k] = *(const PG8_LAS bf16x8*)(lds + PG8_SB(b, h) + boff + n * 2048 + k * 1024); } while (0)
; #define PG8_MMA(ai, bj, At, Bt) do { __builtin_amdgcn_s_setprio(1); _Pragma("unroll") for (int m = 0; m < 4; ++m) _Pragma("unroll") for (int n = 0; n < 2; ++n) _Pragma("unroll") for (int k = 0; k < 2; ++k) \
;         acc[ai][bj][m][n] = mma16<F16>(Bt[n][k], At[m][k], acc[ai][bj][m][n]); __builtin_amdgcn_s_setprio(0); } while (0)
; #define PG8_WAIT_V(n) asm volatile("s_waitcnt vmcnt(" #n ")" ::: "memory")
; #define PG8_WAIT_L(n) asm volatile("s_waitcnt lgkmcnt(" #n ")" ::: "memory")
; #define PG8_BAR __builtin_amdgcn_s_barrier()
; #define PG8_SCHED __builtin_amdgcn_sched_barrier(0)
; template <class Epi, class Sched, bool ALIGN_EPI = false, bool SP2 = false, bool F16 = false>
; __device__ __forceinline__ void gemm_phase(PG8_LAS unsigned char* lds, const Gemm g, const Sched& S, const Epi& E, const int wid_in) {
;     ...
;             PG8_LDB(B0, 1, 0); PG8_LDB(B1, 1, 1); PG8_SCHED; PG8_LDA(At, 1, 0); PG8_STAGE(PG8_SA(0, 1), a2 + hstep, voffA);
;             PG8_WAIT_V(8); PG8_WAIT_L(0); PG8_BAR; PG8_MMA(0, 0, At, B0); PG8_MMA(0, 1, At, B1); PG8_BAR; PG8_SCHED;
	s_add_i32 s60, 0, 0x18000
	s_add_i32 s61, 0, 0x1c000
	v_add_u32_e32 v140, s60, v188
	v_add_u32_e32 v172, s61, v188
	ds_read_b128 v[128:131], v140
	ds_read_b128 v[132:135], v140 offset:1024
	ds_read_b128 v[136:139], v140 offset:2048
	ds_read_b128 v[140:143], v140 offset:3072
	ds_read_b128 v[144:147], v172
	ds_read_b128 v[148:151], v172 offset:1024
	ds_read_b128 v[168:171], v172 offset:2048
	ds_read_b128 v[172:175], v172 offset:3072
	s_add_u32 s46, s46, 0x40000
	s_addc_u32 s47, s47, 0
	s_mov_b32 m0, s90
	v_lshl_add_u64 v[222:223], s[46:47], 0, v[152:153]
	ds_read_b128 v[176:179], v191 offset:32768
	ds_read_b128 v[180:183], v191 offset:33792
	ds_read_b128 v[192:195], v191 offset:34816
	ds_read_b128 v[196:199], v191 offset:35840
	ds_read_b128 v[200:203], v191 offset:36864
	ds_read_b128 v[204:207], v191 offset:37888
	ds_read_b128 v[208:211], v191 offset:38912
	ds_read_b128 v[212:215], v191 offset:39936
	global_load_lds_dwordx4 v[222:223], off
	v_lshl_add_u64 v[222:223], s[46:47], 0, v[156:157]
	s_mov_b32 m0, s49
	s_nop 0
	global_load_lds_dwordx4 v[222:223], off
	s_waitcnt vmcnt(8)
	s_waitcnt lgkmcnt(0)
	s_barrier
	s_waitcnt lgkmcnt(0)
	v_mfma_f32_16x16x32_bf16 v[124:127], v[128:131], v[176:179], v[124:127]
	v_mfma_f32_16x16x32_bf16 v[120:123], v[136:139], v[176:179], v[120:123]
	v_mfma_f32_16x16x32_bf16 v[108:111], v[128:131], v[192:195], v[108:111]
	v_mfma_f32_16x16x32_bf16 v[104:107], v[136:139], v[192:195], v[104:107]
	v_mfma_f32_16x16x32_bf16 v[92:95], v[128:131], v[200:203], v[92:95]
	v_mfma_f32_16x16x32_bf16 v[88:91], v[136:139], v[200:203], v[88:91]
	v_mfma_f32_16x16x32_bf16 v[76:79], v[128:131], v[208:211], v[76:79]
	v_mfma_f32_16x16x32_bf16 v[72:75], v[136:139], v[208:211], v[72:75]
	v_mfma_f32_16x16x32_bf16 v[124:127], v[132:135], v[180:183], v[124:127]
	v_mfma_f32_16x16x32_bf16 v[120:123], v[140:143], v[180:183], v[120:123]
	v_mfma_f32_16x16x32_bf16 v[108:111], v[132:135], v[196:199], v[108:111]
	v_mfma_f32_16x16x32_bf16 v[104:107], v[140:143], v[196:199], v[104:107]
	v_mfma_f32_16x16x32_bf16 v[92:95], v[132:135], v[204:207], v[92:95]
	v_mfma_f32_16x16x32_bf16 v[88:91], v[140:143], v[204:207], v[88:91]
	v_mfma_f32_16x16x32_bf16 v[76:79], v[132:135], v[212:215], v[76:79]
	v_mfma_f32_16x16x32_bf16 v[72:75], v[140:143], v[212:215], v[72:75]
	v_mfma_f32_16x16x32_bf16 v[116:119], v[144:147], v[176:179], v[116:119]
	v_mfma_f32_16x16x32_bf16 v[112:115], v[168:171], v[176:179], v[112:115]
	v_mfma_f32_16x16x32_bf16 v[100:103], v[144:147], v[192:195], v[100:103]
	v_mfma_f32_16x16x32_bf16 v[96:99], v[168:171], v[192:195], v[96:99]
	v_mfma_f32_16x16x32_bf16 v[84:87], v[144:147], v[200:203], v[84:87]
	v_mfma_f32_16x16x32_bf16 v[80:83], v[168:171], v[200:203], v[80:83]
	v_mfma_f32_16x16x32_bf16 v[68:71], v[144:147], v[208:211], v[68:71]
	v_mfma_f32_16x16x32_bf16 v[64:67], v[168:171], v[208:211], v[64:67]
	v_mfma_f32_16x16x32_bf16 v[116:119], v[148:151], v[180:183], v[116:119]
	v_mfma_f32_16x16x32_bf16 v[112:115], v[172:175], v[180:183], v[112:115]
	v_mfma_f32_16x16x32_bf16 v[100:103], v[148:151], v[196:199], v[100:103]
	v_mfma_f32_16x16x32_bf16 v[96:99], v[172:175], v[196:199], v[96:99]
	v_mfma_f32_16x16x32_bf16 v[84:87], v[148:151], v[204:207], v[84:87]
	v_mfma_f32_16x16x32_bf16 v[80:83], v[172:175], v[204:207], v[80:83]
	v_mfma_f32_16x16x32_bf16 v[68:71], v[148:151], v[212:215], v[68:71]
	v_mfma_f32_16x16x32_bf16 v[64:67], v[172:175], v[212:215], v[64:67]
	s_barrier
; #define PG8_STAGE(bufoff, gbase, voff) do { _Pragma("unroll") for (int _i = 0; _i < 2; ++_i) \
;         __builtin_amdgcn_global_load_lds((const unsigned*)((const char*)(gbase) + (voff)[_i]), (PG8_LAS unsigned*)(lds + (bufoff) + ldsw + _i * 8192), 16, 0, 0); } while (0)
; #define PG8_LDA(dst, b, h) do { _Pragma("unroll") for (int m = 0; m < 4; ++m) _Pragma("unroll") for (int k = 0; k < 2; ++k) dst[m][k] = *(const PG8_LAS bf16x8*)(lds + PG8_SA(b, h) + aoff + m * 2048 + k * 1024); } while (0)
; #define PG8_MMA(ai, bj, At, Bt) do { __builtin_amdgcn_s_setprio(1); _Pragma("unroll") for (int m = 0; m < 4; ++m) _Pragma("unroll") for (int n = 0; n < 2; ++n) _Pragma("unroll") for (int k = 0; k < 2; ++k) \
;         acc[ai][bj][m][n] = mma16<F16>(Bt[n][k], At[m][k], acc[ai][bj][m][n]); __builtin_amdgcn_s_setprio(0); } while (0)
; #define PG8_WAIT_V(n) asm volatile("s_waitcnt vmcnt(" #n ")" ::: "memory")
; #define PG8_WAIT_L(n) asm volatile("s_waitcnt lgkmcnt(" #n ")" ::: "memory")
; #define PG8_BAR __builtin_amdgcn_s_barrier()
; #define PG8_SCHED __builtin_amdgcn_sched_barrier(0)
; template <class Epi, class Sched, bool ALIGN_EPI = false, bool SP2 = false, bool F16 = false>
; __device__ __forceinline__ void gemm_phase(PG8_LAS unsigned char* lds, const Gemm g, const Sched& S, const Epi& E, const int wid_in) {
;     ...
;             PG8_LDA(At, 1, 1); PG8_STAGE(PG8_SB(1, 0), b3, voffB); PG8_STAGE(PG8_SB(1, 1), b3 + hstep, voffB); PG8_STAGE(PG8_SA(1, 0), a3, voffA);
;             PG8_WAIT_V(8); PG8_WAIT_L(0); PG8_BAR; PG8_MMA(1, 0, At, B0); PG8_MMA(1, 1, At, B1); PG8_BAR; PG8_SCHED;
;     ...
;         if constexpr (ALIGN_EPI) { if (wr == 0) PG8_BAR; }
	s_add_i32 s46, s60, s68
	v_lshl_add_u64 v[184:185], v[184:185], 0, s[24:25]
	s_mov_b32 m0, s46
	ds_read_b128 v[176:179], v191 offset:49152
	ds_read_b128 v[180:183], v191 offset:50176
	ds_read_b128 v[192:195], v191 offset:51200
	ds_read_b128 v[196:199], v191 offset:52224
	ds_read_b128 v[200:203], v191 offset:53248
	ds_read_b128 v[204:207], v191 offset:54272
	ds_read_b128 v[208:211], v191 offset:55296
	ds_read_b128 v[212:215], v191 offset:56320
	global_load_lds_dwordx4 v[184:185], off
	s_add_i32 m0, s46, 0x2000
	s_add_u32 s44, s44, 0x40080
	v_lshl_add_u64 v[184:185], v[216:217], 0, s[24:25]
	s_addc_u32 s45, s45, 0
	s_add_i32 s46, s61, s68
	global_load_lds_dwordx4 v[184:185], off
	v_lshl_add_u64 v[184:185], s[44:45], 0, v[154:155]
	s_mov_b32 m0, s46
	s_nop 0
	global_load_lds_dwordx4 v[184:185], off
	v_lshl_add_u64 v[184:185], s[44:45], 0, v[158:159]
	s_add_i32 m0, s46, 0x2000
	s_nop 0
	global_load_lds_dwordx4 v[184:185], off
	v_lshl_add_u64 v[184:185], v[218:219], 0, s[24:25]
	s_mov_b32 m0, s75
	s_nop 0
	global_load_lds_dwordx4 v[184:185], off
	v_lshl_add_u64 v[184:185], v[220:221], 0, s[24:25]
	s_mov_b32 m0, s67
	s_nop 0
	global_load_lds_dwordx4 v[184:185], off
	s_waitcnt vmcnt(8)
	s_waitcnt lgkmcnt(0)
	s_barrier
	s_waitcnt lgkmcnt(0)
	v_mfma_f32_16x16x32_bf16 v[60:63], v[128:131], v[176:179], v[60:63]
	v_mfma_f32_16x16x32_bf16 v[56:59], v[136:139], v[176:179], v[56:59]
	v_mfma_f32_16x16x32_bf16 v[44:47], v[128:131], v[192:195], v[44:47]
	v_mfma_f32_16x16x32_bf16 v[40:43], v[136:139], v[192:195], v[40:43]
	v_mfma_f32_16x16x32_bf16 v[28:31], v[128:131], v[200:203], v[28:31]
	v_mfma_f32_16x16x32_bf16 v[24:27], v[136:139], v[200:203], v[24:27]
	v_mfma_f32_16x16x32_bf16 v[12:15], v[128:131], v[208:211], v[12:15]
	v_mfma_f32_16x16x32_bf16 v[8:11], v[136:139], v[208:211], v[8:11]
	v_mfma_f32_16x16x32_bf16 v[60:63], v[132:135], v[180:183], v[60:63]
	v_mfma_f32_16x16x32_bf16 v[56:59], v[140:143], v[180:183], v[56:59]
	v_mfma_f32_16x16x32_bf16 v[44:47], v[132:135], v[196:199], v[44:47]
	v_mfma_f32_16x16x32_bf16 v[40:43], v[140:143], v[196:199], v[40:43]
	v_mfma_f32_16x16x32_bf16 v[28:31], v[132:135], v[204:207], v[28:31]
	v_mfma_f32_16x16x32_bf16 v[24:27], v[140:143], v[204:207], v[24:27]
	v_mfma_f32_16x16x32_bf16 v[12:15], v[132:135], v[212:215], v[12:15]
	v_mfma_f32_16x16x32_bf16 v[8:11], v[140:143], v[212:215], v[8:11]
	v_mfma_f32_16x16x32_bf16 v[52:55], v[144:147], v[176:179], v[52:55]
	v_mfma_f32_16x16x32_bf16 v[48:51], v[168:171], v[176:179], v[48:51]
	v_mfma_f32_16x16x32_bf16 v[36:39], v[144:147], v[192:195], v[36:39]
	v_mfma_f32_16x16x32_bf16 v[32:35], v[168:171], v[192:195], v[32:35]
	v_mfma_f32_16x16x32_bf16 v[20:23], v[144:147], v[200:203], v[20:23]
	v_mfma_f32_16x16x32_bf16 v[16:19], v[168:171], v[200:203], v[16:19]
	v_mfma_f32_16x16x32_bf16 v[4:7], v[144:147], v[208:211], v[4:7]
	v_mfma_f32_16x16x32_bf16 v[0:3], v[168:171], v[208:211], v[0:3]
	v_mfma_f32_16x16x32_bf16 v[52:55], v[148:151], v[180:183], v[52:55]
	v_mfma_f32_16x16x32_bf16 v[48:51], v[172:175], v[180:183], v[48:51]
	v_mfma_f32_16x16x32_bf16 v[36:39], v[148:151], v[196:199], v[36:39]
	v_mfma_f32_16x16x32_bf16 v[32:35], v[172:175], v[196:199], v[32:35]
	v_mfma_f32_16x16x32_bf16 v[20:23], v[148:151], v[204:207], v[20:23]
	v_mfma_f32_16x16x32_bf16 v[16:19], v[172:175], v[204:207], v[16:19]
	v_mfma_f32_16x16x32_bf16 v[4:7], v[148:151], v[212:215], v[4:7]
	v_mfma_f32_16x16x32_bf16 v[0:3], v[172:175], v[212:215], v[0:3]
	s_barrier
	s_add_i32 s59, s59, 2
	s_add_u32 s42, s42, 0x100
	s_addc_u32 s43, s43, 0
	s_add_u32 s57, s57, 0x100
	s_addc_u32 s58, s58, 0
	s_cmp_gt_u32 s59, 13
	s_cbranch_scc0 .LBB0_2489
	s_setprio 0
	s_and_b64 vcc, exec, s[16:17]
	s_cbranch_vccz .LBB0_2492
	s_barrier

; #define PG8_STAGE(bufoff, gbase, voff) do { _Pragma("unroll") for (int _i = 0; _i < 2; ++_i) \
;         __builtin_amdgcn_global_load_lds((const unsigned*)((const char*)(gbase) + (voff)[_i]), (PG8_LAS unsigned*)(lds + (bufoff) + ldsw + _i * 8192), 16, 0, 0); } while (0)
; #define PG8_LDA(dst, b, h) do { _Pragma("unroll") for (int m = 0; m < 4; ++m) _Pragma("unroll") for (int k = 0; k < 2; ++k) dst[m][k] = *(const PG8_LAS bf16x8*)(lds + PG8_SA(b, h) + aoff + m * 2048 + k * 1024); } while (0)
; #define PG8_LDB(dst, b, h) do { _Pragma("unroll") for (int n = 0; n < 2; ++n) _Pragma("unroll") for (int k = 0; k < 2; ++k) dst[n][k] = *(const PG8_LAS bf16x8*)(lds + PG8_SB(b, h) + boff + n * 2048 + k * 1024); } while (0)
; #define PG8_SCHED __builtin_amdgcn_sched_barrier(0)
; template <class Epi, class Sched, bool ALIGN_EPI = false, bool SP2 = false, bool F16 = false>
; __device__ __forceinline__ void gemm_phase(PG8_LAS unsigned char* lds, const Gemm g, const Sched& S, const Epi& E, const int wid_in) {
;     ...
;         const char* nA = has_next ? (const char*)g.A + (size_t)nxt.pm * tstep : cA; const char* nB = has_next ? (const char*)g.Bt + (size_t)nxt.pn * tstep : cB;
;         for (int t = 0; t < nt; t += 2) {
;             const bool last = (t == nt - 2);
;             const char* a1 = cA + (size_t)(t + 1) * kstep;
;             const char* a2 = last ? nA : cA + (size_t)(t + 2) * kstep; const char* b2 = last ? nB : cB + (size_t)(t + 2) * kstep;
;             const char* a3 = a2 + kstep; const char* b3 = b2 + kstep;
;             if (last && has_next) S.a_ready(nxt);
;             if constexpr (SP2) {
;             PG8_LDB(B0, 0, 0); PG8_LDB(B1, 0, 1); PG8_SCHED; PG8_LDA(At, 0, 0); PG8_STAGE(PG8_SA(1, 1), a1 + hstep, voffA);
;     ...
;         for (int a = 0; a < 2; ++a)
; #pragma unroll
;             for (int b = 0; b < 2; ++b)
; #pragma unroll
;                 for (int m = 0; m < 4; ++m)
; #pragma unroll
;                     for (int n = 0; n < 2; ++n) acc[a][b][m][n] = (f32x4){0.f, 0.f, 0.f, 0.f};
.LBB0_2565:
	s_ashr_i32 s25, s24, 31
	s_lshl_b64 s[26:27], s[24:25], 19
	s_add_u32 s26, s41, s26
	s_addc_u32 s27, s46, s27
	s_and_b64 s[28:29], s[10:11], exec
	s_cselect_b32 s25, s27, s37
	s_cselect_b32 s35, s26, s36
	s_ashr_i32 s23, s22, 31
	s_lshl_b64 s[28:29], s[22:23], 19
	s_add_u32 s28, s47, s28
	s_addc_u32 s29, s48, s29
	s_and_b64 s[44:45], s[10:11], exec
	s_cselect_b32 s23, s29, s43
	s_cselect_b32 s59, s28, s42
	s_add_u32 s36, s36, 0x40080
	s_addc_u32 s37, s37, 0
	s_add_u32 s60, s42, 0x100
	v_mov_b32_e32 v8, 0
	s_addc_u32 s61, s43, 0
	s_mov_b32 s62, -2
	v_mov_b32_e32 v9, v8
	v_mov_b32_e32 v10, v8
	v_mov_b32_e32 v11, v8
	v_mov_b32_e32 v12, v8
	v_mov_b32_e32 v13, v8
	v_mov_b32_e32 v14, v8
	v_mov_b32_e32 v15, v8
	v_mov_b32_e32 v24, v8
	v_mov_b32_e32 v25, v8
	v_mov_b32_e32 v26, v8
	v_mov_b32_e32 v27, v8
	v_mov_b32_e32 v28, v8
	v_mov_b32_e32 v29, v8
	v_mov_b32_e32 v30, v8
	v_mov_b32_e32 v31, v8
	v_mov_b32_e32 v40, v8
	v_mov_b32_e32 v41, v8
	v_mov_b32_e32 v42, v8
	v_mov_b32_e32 v43, v8
	v_mov_b32_e32 v44, v8
	v_mov_b32_e32 v45, v8
	v_mov_b32_e32 v46, v8
	v_mov_b32_e32 v47, v8
	v_mov_b32_e32 v56, v8
	v_mov_b32_e32 v57, v8
	v_mov_b32_e32 v58, v8
	v_mov_b32_e32 v59, v8
	v_mov_b32_e32 v60, v8
	v_mov_b32_e32 v61, v8
	v_mov_b32_e32 v62, v8
	v_mov_b32_e32 v63, v8
	v_mov_b32_e32 v16, v8
	v_mov_b32_e32 v17, v8
	v_mov_b32_e32 v18, v8
	v_mov_b32_e32 v19, v8
	v_mov_b32_e32 v20, v8
	v_mov_b32_e32 v21, v8
	v_mov_b32_e32 v22, v8
	v_mov_b32_e32 v23, v8
	v_mov_b32_e32 v32, v8
	v_mov_b32_e32 v33, v8
	v_mov_b32_e32 v34, v8
	v_mov_b32_e32 v35, v8
	v_mov_b32_e32 v36, v8
	v_mov_b32_e32 v37, v8
	v_mov_b32_e32 v38, v8
	v_mov_b32_e32 v39, v8
	v_mov_b32_e32 v48, v8
	v_mov_b32_e32 v49, v8
	v_mov_b32_e32 v50, v8
	v_mov_b32_e32 v51, v8
	v_mov_b32_e32 v52, v8
	v_mov_b32_e32 v53, v8
	v_mov_b32_e32 v54, v8
	v_mov_b32_e32 v55, v8
	v_mov_b32_e32 v64, v8
	v_mov_b32_e32 v65, v8
	v_mov_b32_e32 v66, v8
	v_mov_b32_e32 v67, v8
	v_mov_b32_e32 v68, v8
	v_mov_b32_e32 v69, v8
	v_mov_b32_e32 v70, v8
	v_mov_b32_e32 v71, v8
	v_mov_b32_e32 v72, v8
	v_mov_b32_e32 v73, v8
	v_mov_b32_e32 v74, v8
	v_mov_b32_e32 v75, v8
	v_mov_b32_e32 v76, v8
	v_mov_b32_e32 v77, v8
	v_mov_b32_e32 v78, v8
	v_mov_b32_e32 v79, v8
	v_mov_b32_e32 v88, v8
	v_mov_b32_e32 v89, v8
	v_mov_b32_e32 v90, v8
	v_mov_b32_e32 v91, v8
	v_mov_b32_e32 v92, v8
	v_mov_b32_e32 v93, v8
	v_mov_b32_e32 v94, v8
	v_mov_b32_e32 v95, v8
	v_mov_b32_e32 v104, v8
	v_mov_b32_e32 v105, v8
	v_mov_b32_e32 v106, v8
	v_mov_b32_e32 v107, v8
	v_mov_b32_e32 v108, v8
	v_mov_b32_e32 v109, v8
	v_mov_b32_e32 v110, v8
	v_mov_b32_e32 v111, v8
	v_mov_b32_e32 v120, v8
	v_mov_b32_e32 v121, v8
	v_mov_b32_e32 v122, v8
	v_mov_b32_e32 v123, v8
	v_mov_b32_e32 v124, v8
	v_mov_b32_e32 v125, v8
	v_mov_b32_e32 v126, v8
	v_mov_b32_e32 v127, v8
	v_mov_b32_e32 v80, v8
	v_mov_b32_e32 v81, v8
	v_mov_b32_e32 v82, v8
	v_mov_b32_e32 v83, v8
	v_mov_b32_e32 v84, v8
	v_mov_b32_e32 v85, v8
	v_mov_b32_e32 v86, v8
	v_mov_b32_e32 v87, v8
	v_mov_b32_e32 v96, v8
	v_mov_b32_e32 v97, v8
	v_mov_b32_e32 v98, v8
	v_mov_b32_e32 v99, v8
	v_mov_b32_e32 v100, v8
	v_mov_b32_e32 v101, v8
	v_mov_b32_e32 v102, v8
	v_mov_b32_e32 v103, v8
	v_mov_b32_e32 v112, v8
	v_mov_b32_e32 v113, v8
	v_mov_b32_e32 v114, v8
	v_mov_b32_e32 v115, v8
	v_mov_b32_e32 v116, v8
	v_mov_b32_e32 v117, v8
	v_mov_b32_e32 v118, v8
	v_mov_b32_e32 v119, v8
	v_mov_b32_e32 v128, v8
	v_mov_b32_e32 v129, v8
	v_mov_b32_e32 v130, v8
	v_mov_b32_e32 v131, v8
	v_mov_b32_e32 v132, v8
	v_mov_b32_e32 v133, v8
	v_mov_b32_e32 v134, v8
	v_mov_b32_e32 v135, v8
	s_cmp_ge_u32 s3, 4
	s_cbranch_scc0 .Lgsp_20
	s_setprio 1
.Lgsp_20:
.LBB0_2566:
	ds_read_b128 v[0:3], v193
	ds_read_b128 v[4:7], v193 offset:1024
	ds_read_b128 v[136:139], v193 offset:2048
	ds_read_b128 v[140:143], v193 offset:3072
	ds_read_b128 v[144:147], v194
	ds_read_b128 v[148:151], v194 offset:1024
	ds_read_b128 v[152:155], v194 offset:2048
	ds_read_b128 v[156:159], v194 offset:3072
	s_add_u32 s42, s36, 0xfffc0080
	s_addc_u32 s43, s37, -1
	s_cmp_eq_u32 s62, 12
	s_cselect_b32 s45, s25, s43
	s_cselect_b32 s44, s35, s42
	s_cselect_b32 s43, s23, s61
	s_cselect_b32 s42, s59, s60
	s_mov_b32 m0, s91
	v_lshl_add_u64 v[188:189], s[36:37], 0, v[168:169]
	ds_read_b128 v[176:179], v195
	ds_read_b128 v[180:183], v195 offset:1024
	ds_read_b128 v[184:187], v195 offset:2048
	ds_read_b128 v[198:201], v195 offset:3072
	ds_read_b128 v[202:205], v195 offset:4096
	ds_read_b128 v[206:209], v195 offset:5120
	ds_read_b128 v[210:213], v195 offset:6144
	ds_read_b128 v[214:217], v195 offset:7168
	global_load_lds_dwordx4 v[188:189], off
	v_lshl_add_u64 v[188:189], s[36:37], 0, v[170:171]
	s_add_i32 m0, s74, 0xe000
	s_nop 0
	global_load_lds_dwordx4 v[188:189], off
	s_waitcnt vmcnt(8)
	s_waitcnt lgkmcnt(0)
	s_barrier
; #define PG8_STAGE(bufoff, gbase, voff) do { _Pragma("unroll") for (int _i = 0; _i < 2; ++_i) \
;         __builtin_amdgcn_global_load_lds((const unsigned*)((const char*)(gbase) + (voff)[_i]), (PG8_LAS unsigned*)(lds + (bufoff) + ldsw + _i * 8192), 16, 0, 0); } while (0)
; #define PG8_LDA(dst, b, h) do { _Pragma("unroll") for (int m = 0; m < 4; ++m) _Pragma("unroll") for (int k = 0; k < 2; ++k) dst[m][k] = *(const PG8_LAS bf16x8*)(lds + PG8_SA(b, h) + aoff + m * 2048 + k * 1024); } while (0)
; #define PG8_MMA(ai, bj, At, Bt) do { __builtin_amdgcn_s_setprio(1); _Pragma("unroll") for (int m = 0; m < 4; ++m) _Pragma("unroll") for (int n = 0; n < 2; ++n) _Pragma("unroll") for (int k = 0; k < 2; ++k) \
;         acc[ai][bj][m][n] = mma16<F16>(Bt[n][k], At[m][k], acc[ai][bj][m][n]); __builtin_amdgcn_s_setprio(0); } while (0)
; #define PG8_WAIT_V(n) asm volatile("s_waitcnt vmcnt(" #n ")" ::: "memory")
; #define PG8_WAIT_L(n) asm volatile("s_waitcnt lgkmcnt(" #n ")" ::: "memory")
; #define PG8_BAR __builtin_amdgcn_s_barrier()
; #define PG8_SCHED __builtin_amdgcn_sched_barrier(0)
; template <class Epi, class Sched, bool ALIGN_EPI = false, bool SP2 = false, bool F16 = false>
; __device__ __forceinline__ void gemm_phase(PG8_LAS unsigned char* lds, const Gemm g, const Sched& S, const Epi& E, const int wid_in) {
;     ...
;             PG8_WAIT_V(8); PG8_WAIT_L(0); PG8_BAR; PG8_MMA(0, 0, At, B0); PG8_MMA(0, 1, At, B1); PG8_BAR; PG8_SCHED;
;             PG8_LDA(At, 0, 1); PG8_STAGE(PG8_SB(0, 0), b2, voffB); PG8_STAGE(PG8_SB(0, 1), b2 + hstep, voffB); PG8_STAGE(PG8_SA(0, 0), a2, voffA);
;             PG8_WAIT_V(8); PG8_WAIT_L(0); PG8_BAR; PG8_MMA(1, 0, At, B0); PG8_MMA(1, 1, At, B1); PG8_BAR; PG8_SCHED;
	s_waitcnt lgkmcnt(0)
	v_mfma_f32_16x16x32_f16 v[132:135], v[0:3], v[176:179], v[132:135]
	v_mfma_f32_16x16x32_f16 v[128:131], v[136:139], v[176:179], v[128:131]
	v_mfma_f32_16x16x32_f16 v[116:119], v[0:3], v[184:187], v[116:119]
	v_mfma_f32_16x16x32_f16 v[112:115], v[136:139], v[184:187], v[112:115]
	v_mfma_f32_16x16x32_f16 v[100:103], v[0:3], v[202:205], v[100:103]
	v_mfma_f32_16x16x32_f16 v[96:99], v[136:139], v[202:205], v[96:99]
	v_mfma_f32_16x16x32_f16 v[84:87], v[0:3], v[210:213], v[84:87]
	v_mfma_f32_16x16x32_f16 v[80:83], v[136:139], v[210:213], v[80:83]
	v_mfma_f32_16x16x32_f16 v[132:135], v[4:7], v[180:183], v[132:135]
	v_mfma_f32_16x16x32_f16 v[128:131], v[140:143], v[180:183], v[128:131]
	v_mfma_f32_16x16x32_f16 v[116:119], v[4:7], v[198:201], v[116:119]
	v_mfma_f32_16x16x32_f16 v[112:115], v[140:143], v[198:201], v[112:115]
	v_mfma_f32_16x16x32_f16 v[100:103], v[4:7], v[206:209], v[100:103]
	v_mfma_f32_16x16x32_f16 v[96:99], v[140:143], v[206:209], v[96:99]
	v_mfma_f32_16x16x32_f16 v[84:87], v[4:7], v[214:217], v[84:87]
	v_mfma_f32_16x16x32_f16 v[80:83], v[140:143], v[214:217], v[80:83]
	v_mfma_f32_16x16x32_f16 v[124:127], v[144:147], v[176:179], v[124:127]
	v_mfma_f32_16x16x32_f16 v[120:123], v[152:155], v[176:179], v[120:123]
	v_mfma_f32_16x16x32_f16 v[108:111], v[144:147], v[184:187], v[108:111]
	v_mfma_f32_16x16x32_f16 v[104:107], v[152:155], v[184:187], v[104:107]
	v_mfma_f32_16x16x32_f16 v[92:95], v[144:147], v[202:205], v[92:95]
	v_mfma_f32_16x16x32_f16 v[88:91], v[152:155], v[202:205], v[88:91]
	v_mfma_f32_16x16x32_f16 v[76:79], v[144:147], v[210:213], v[76:79]
	v_mfma_f32_16x16x32_f16 v[72:75], v[152:155], v[210:213], v[72:75]
	v_mfma_f32_16x16x32_f16 v[124:127], v[148:151], v[180:183], v[124:127]
	v_mfma_f32_16x16x32_f16 v[120:123], v[156:159], v[180:183], v[120:123]
	v_mfma_f32_16x16x32_f16 v[108:111], v[148:151], v[198:201], v[108:111]
	v_mfma_f32_16x16x32_f16 v[104:107], v[156:159], v[198:201], v[104:107]
	v_mfma_f32_16x16x32_f16 v[92:95], v[148:151], v[206:209], v[92:95]
	v_mfma_f32_16x16x32_f16 v[88:91], v[156:159], v[206:209], v[88:91]
	v_mfma_f32_16x16x32_f16 v[76:79], v[148:151], v[214:217], v[76:79]
	v_mfma_f32_16x16x32_f16 v[72:75], v[156:159], v[214:217], v[72:75]
	s_barrier
	s_add_i32 s63, s56, s68
	v_lshl_add_u64 v[188:189], s[42:43], 0, v[162:163]
	s_mov_b32 m0, s63
	ds_read_b128 v[176:179], v195 offset:16384
	ds_read_b128 v[180:183], v195 offset:17408
	ds_read_b128 v[184:187], v195 offset:18432
	ds_read_b128 v[198:201], v195 offset:19456
	ds_read_b128 v[202:205], v195 offset:20480
	ds_read_b128 v[206:209], v195 offset:21504
	ds_read_b128 v[210:213], v195 offset:22528
	ds_read_b128 v[214:217], v195 offset:23552
	global_load_lds_dwordx4 v[188:189], off
	s_add_i32 m0, s63, 0x2000
	s_add_u32 s64, s42, 0x40000
	v_lshl_add_u64 v[218:219], s[42:43], 0, v[166:167]
	s_addc_u32 s65, s43, 0
	s_add_i32 s63, s57, s68
	global_load_lds_dwordx4 v[218:219], off
	v_lshl_add_u64 v[220:221], s[64:65], 0, v[162:163]
	s_mov_b32 m0, s63
	v_lshl_add_u64 v[222:223], s[44:45], 0, v[164:165]
	global_load_lds_dwordx4 v[220:221], off
	v_lshl_add_u64 v[220:221], s[64:65], 0, v[166:167]
	s_add_i32 m0, s63, 0x2000
	s_nop 0
	global_load_lds_dwordx4 v[220:221], off
	v_lshl_add_u64 v[220:221], s[44:45], 0, v[160:161]
	s_mov_b32 m0, s74
	s_nop 0
	global_load_lds_dwordx4 v[220:221], off
	s_mov_b32 m0, s66
	s_nop 0
	global_load_lds_dwordx4 v[222:223], off
	s_waitcnt vmcnt(8)
	s_waitcnt lgkmcnt(0)
	s_barrier
	s_waitcnt lgkmcnt(0)
	v_mfma_f32_16x16x32_f16 v[68:71], v[0:3], v[176:179], v[68:71]
	v_mfma_f32_16x16x32_f16 v[64:67], v[136:139], v[176:179], v[64:67]
	v_mfma_f32_16x16x32_f16 v[52:55], v[0:3], v[184:187], v[52:55]
	v_mfma_f32_16x16x32_f16 v[48:51], v[136:139], v[184:187], v[48:51]
	v_mfma_f32_16x16x32_f16 v[36:39], v[0:3], v[202:205], v[36:39]
	v_mfma_f32_16x16x32_f16 v[32:35], v[136:139], v[202:205], v[32:35]
	v_mfma_f32_16x16x32_f16 v[0:3], v[0:3], v[210:213], v[20:23]
	v_mfma_f32_16x16x32_f16 v[68:71], v[4:7], v[180:183], v[68:71]
	v_mfma_f32_16x16x32_f16 v[64:67], v[140:143], v[180:183], v[64:67]
	v_mfma_f32_16x16x32_f16 v[52:55], v[4:7], v[198:201], v[52:55]
	v_mfma_f32_16x16x32_f16 v[48:51], v[140:143], v[198:201], v[48:51]
	v_mfma_f32_16x16x32_f16 v[36:39], v[4:7], v[206:209], v[36:39]
	v_mfma_f32_16x16x32_f16 v[32:35], v[140:143], v[206:209], v[32:35]
	v_mfma_f32_16x16x32_f16 v[0:3], v[4:7], v[214:217], v[0:3]
	v_mfma_f32_16x16x32_f16 v[4:7], v[136:139], v[210:213], v[16:19]
	v_mfma_f32_16x16x32_f16 v[4:7], v[140:143], v[214:217], v[4:7]
	v_mfma_f32_16x16x32_f16 v[16:19], v[144:147], v[176:179], v[60:63]
	v_mfma_f32_16x16x32_f16 v[60:63], v[148:151], v[180:183], v[16:19]
	v_mfma_f32_16x16x32_f16 v[16:19], v[152:155], v[176:179], v[56:59]
	v_mfma_f32_16x16x32_f16 v[56:59], v[156:159], v[180:183], v[16:19]
	v_mfma_f32_16x16x32_f16 v[16:19], v[144:147], v[184:187], v[44:47]
	v_mfma_f32_16x16x32_f16 v[44:47], v[148:151], v[198:201], v[16:19]
	v_mfma_f32_16x16x32_f16 v[16:19], v[152:155], v[184:187], v[40:43]
	v_mfma_f32_16x16x32_f16 v[40:43], v[156:159], v[198:201], v[16:19]
	v_mfma_f32_16x16x32_f16 v[16:19], v[144:147], v[202:205], v[28:31]
	v_mfma_f32_16x16x32_f16 v[28:31], v[148:151], v[206:209], v[16:19]
	v_mfma_f32_16x16x32_f16 v[16:19], v[152:155], v[202:205], v[24:27]
	v_mfma_f32_16x16x32_f16 v[12:15], v[144:147], v[210:213], v[12:15]
	v_mfma_f32_16x16x32_f16 v[8:11], v[152:155], v[210:213], v[8:11]
	v_mfma_f32_16x16x32_f16 v[24:27], v[156:159], v[206:209], v[16:19]
	v_mfma_f32_16x16x32_f16 v[12:15], v[148:151], v[214:217], v[12:15]
	v_mfma_f32_16x16x32_f16 v[8:11], v[156:159], v[214:217], v[8:11]
	s_barrier
; #define PG8_STAGE(bufoff, gbase, voff) do { _Pragma("unroll") for (int _i = 0; _i < 2; ++_i) \
;         __builtin_amdgcn_global_load_lds((const unsigned*)((const char*)(gbase) + (voff)[_i]), (PG8_LAS unsigned*)(lds + (bufoff) + ldsw + _i * 8192), 16, 0, 0); } while (0)
; #define PG8_LDA(dst, b, h) do { _Pragma("unroll") for (int m = 0; m < 4; ++m) _Pragma("unroll") for (int k = 0; k < 2; ++k) dst[m][k] = *(const PG8_LAS bf16x8*)(lds + PG8_SA(b, h) + aoff + m * 2048 + k * 1024); } while (0)
; #define PG8_LDB(dst, b, h) do { _Pragma("unroll") for (int n = 0; n < 2; ++n) _Pragma("unroll") for (int k = 0; k < 2; ++k) dst[n][k] = *(const PG8_LAS bf16x8*)(lds + PG8_SB(b, h) + boff + n * 2048 + k * 1024); } while (0)
; #define PG8_MMA(ai, bj, At, Bt) do { __builtin_amdgcn_s_setprio(1); _Pragma("unroll") for (int m = 0; m < 4; ++m) _Pragma("unroll") for (int n = 0; n < 2; ++n) _Pragma("unroll") for (int k = 0; k < 2; ++k) \
;         acc[ai][bj][m][n] = mma16<F16>(Bt[n][k], At[m][k], acc[ai][bj][m][n]); __builtin_amdgcn_s_setprio(0); } while (0)
; #define PG8_WAIT_V(n) asm volatile("s_waitcnt vmcnt(" #n ")" ::: "memory")
; #define PG8_WAIT_L(n) asm volatile("s_waitcnt lgkmcnt(" #n ")" ::: "memory")
; #define PG8_BAR __builtin_amdgcn_s_barrier()
; #define PG8_SCHED __builtin_amdgcn_sched_barrier(0)
; template <class Epi, class Sched, bool ALIGN_EPI = false, bool SP2 = false, bool F16 = false>
; __device__ __forceinline__ void gemm_phase(PG8_LAS unsigned char* lds, const Gemm g, const Sched& S, const Epi& E, const int wid_in) {
;     ...
;             PG8_LDB(B0, 1, 0); PG8_LDB(B1, 1, 1); PG8_SCHED; PG8_LDA(At, 1, 0); PG8_STAGE(PG8_SA(0, 1), a2 + hstep, voffA);
;             PG8_WAIT_V(8); PG8_WAIT_L(0); PG8_BAR; PG8_MMA(0, 0, At, B0); PG8_MMA(0, 1, At, B1); PG8_BAR; PG8_SCHED;
;             PG8_LDA(At, 1, 1); PG8_STAGE(PG8_SB(1, 0), b3, voffB); PG8_STAGE(PG8_SB(1, 1), b3 + hstep, voffB); PG8_STAGE(PG8_SA(1, 0), a3, voffA);
;             PG8_WAIT_V(8); PG8_WAIT_L(0); PG8_BAR; PG8_MMA(1, 0, At, B0); PG8_MMA(1, 1, At, B1); PG8_BAR; PG8_SCHED;
;     ...
;         if constexpr (ALIGN_EPI) { if (wr == 0) PG8_BAR; }
	s_add_i32 s63, 0, 0x18000
	s_add_i32 s64, 0, 0x1c000
	v_add_u32_e32 v140, s63, v192
	v_add_u32_e32 v156, s64, v192
	ds_read_b128 v[16:19], v140
	ds_read_b128 v[20:23], v140 offset:1024
	ds_read_b128 v[136:139], v140 offset:2048
	ds_read_b128 v[140:143], v140 offset:3072
	ds_read_b128 v[144:147], v156
	ds_read_b128 v[148:151], v156 offset:1024
	ds_read_b128 v[152:155], v156 offset:2048
	ds_read_b128 v[156:159], v156 offset:3072
	s_add_u32 s44, s44, 0x40000
	s_addc_u32 s45, s45, 0
	s_mov_b32 m0, s90
	v_lshl_add_u64 v[224:225], s[44:45], 0, v[160:161]
	ds_read_b128 v[176:179], v195 offset:32768
	ds_read_b128 v[180:183], v195 offset:33792
	ds_read_b128 v[184:187], v195 offset:34816
	ds_read_b128 v[198:201], v195 offset:35840
	ds_read_b128 v[202:205], v195 offset:36864
	ds_read_b128 v[206:209], v195 offset:37888
	ds_read_b128 v[210:213], v195 offset:38912
	ds_read_b128 v[214:217], v195 offset:39936
	global_load_lds_dwordx4 v[224:225], off
	v_lshl_add_u64 v[224:225], s[44:45], 0, v[164:165]
	s_mov_b32 m0, s31
	s_nop 0
	global_load_lds_dwordx4 v[224:225], off
	s_waitcnt vmcnt(8)
	s_waitcnt lgkmcnt(0)
	s_barrier
	s_waitcnt lgkmcnt(0)
	v_mfma_f32_16x16x32_f16 v[132:135], v[16:19], v[176:179], v[132:135]
	v_mfma_f32_16x16x32_f16 v[128:131], v[136:139], v[176:179], v[128:131]
	v_mfma_f32_16x16x32_f16 v[116:119], v[16:19], v[184:187], v[116:119]
	v_mfma_f32_16x16x32_f16 v[112:115], v[136:139], v[184:187], v[112:115]
	v_mfma_f32_16x16x32_f16 v[100:103], v[16:19], v[202:205], v[100:103]
	v_mfma_f32_16x16x32_f16 v[96:99], v[136:139], v[202:205], v[96:99]
	v_mfma_f32_16x16x32_f16 v[84:87], v[16:19], v[210:213], v[84:87]
	v_mfma_f32_16x16x32_f16 v[80:83], v[136:139], v[210:213], v[80:83]
	v_mfma_f32_16x16x32_f16 v[132:135], v[20:23], v[180:183], v[132:135]
	v_mfma_f32_16x16x32_f16 v[128:131], v[140:143], v[180:183], v[128:131]
	v_mfma_f32_16x16x32_f16 v[116:119], v[20:23], v[198:201], v[116:119]
	v_mfma_f32_16x16x32_f16 v[112:115], v[140:143], v[198:201], v[112:115]
	v_mfma_f32_16x16x32_f16 v[100:103], v[20:23], v[206:209], v[100:103]
	v_mfma_f32_16x16x32_f16 v[96:99], v[140:143], v[206:209], v[96:99]
	v_mfma_f32_16x16x32_f16 v[84:87], v[20:23], v[214:217], v[84:87]
	v_mfma_f32_16x16x32_f16 v[80:83], v[140:143], v[214:217], v[80:83]
	v_mfma_f32_16x16x32_f16 v[124:127], v[144:147], v[176:179], v[124:127]
	v_mfma_f32_16x16x32_f16 v[120:123], v[152:155], v[176:179], v[120:123]
	v_mfma_f32_16x16x32_f16 v[108:111], v[144:147], v[184:187], v[108:111]
	v_mfma_f32_16x16x32_f16 v[104:107], v[152:155], v[184:187], v[104:107]
	v_mfma_f32_16x16x32_f16 v[92:95], v[144:147], v[202:205], v[92:95]
	v_mfma_f32_16x16x32_f16 v[88:91], v[152:155], v[202:205], v[88:91]
	v_mfma_f32_16x16x32_f16 v[76:79], v[144:147], v[210:213], v[76:79]
	v_mfma_f32_16x16x32_f16 v[72:75], v[152:155], v[210:213], v[72:75]
	v_mfma_f32_16x16x32_f16 v[124:127], v[148:151], v[180:183], v[124:127]
	v_mfma_f32_16x16x32_f16 v[120:123], v[156:159], v[180:183], v[120:123]
	v_mfma_f32_16x16x32_f16 v[108:111], v[148:151], v[198:201], v[108:111]
	v_mfma_f32_16x16x32_f16 v[104:107], v[156:159], v[198:201], v[104:107]
	v_mfma_f32_16x16x32_f16 v[92:95], v[148:151], v[206:209], v[92:95]
	v_mfma_f32_16x16x32_f16 v[88:91], v[156:159], v[206:209], v[88:91]
	v_mfma_f32_16x16x32_f16 v[76:79], v[148:151], v[214:217], v[76:79]
	v_mfma_f32_16x16x32_f16 v[72:75], v[156:159], v[214:217], v[72:75]
	s_barrier
	s_add_i32 s44, s63, s68
	v_lshl_add_u64 v[188:189], v[188:189], 0, s[20:21]
	s_mov_b32 m0, s44
	ds_read_b128 v[176:179], v195 offset:49152
	ds_read_b128 v[180:183], v195 offset:50176
	ds_read_b128 v[184:187], v195 offset:51200
	ds_read_b128 v[198:201], v195 offset:52224
	ds_read_b128 v[202:205], v195 offset:53248
	ds_read_b128 v[206:209], v195 offset:54272
	ds_read_b128 v[210:213], v195 offset:55296
	ds_read_b128 v[214:217], v195 offset:56320
	global_load_lds_dwordx4 v[188:189], off
	s_add_i32 m0, s44, 0x2000
	s_add_u32 s42, s42, 0x40080
	v_lshl_add_u64 v[188:189], v[218:219], 0, s[20:21]
	s_addc_u32 s43, s43, 0
	s_add_i32 s44, s64, s68
	global_load_lds_dwordx4 v[188:189], off
	v_lshl_add_u64 v[188:189], s[42:43], 0, v[162:163]
	s_mov_b32 m0, s44
	s_nop 0
	global_load_lds_dwordx4 v[188:189], off
	v_lshl_add_u64 v[188:189], s[42:43], 0, v[166:167]
	s_add_i32 m0, s44, 0x2000
	s_nop 0
	global_load_lds_dwordx4 v[188:189], off
	v_lshl_add_u64 v[188:189], v[220:221], 0, s[20:21]
	s_mov_b32 m0, s75
	s_nop 0
	global_load_lds_dwordx4 v[188:189], off
	v_lshl_add_u64 v[188:189], v[222:223], 0, s[20:21]
	s_mov_b32 m0, s67
	s_nop 0
	global_load_lds_dwordx4 v[188:189], off
	s_waitcnt vmcnt(8)
	s_waitcnt lgkmcnt(0)
	s_barrier
	s_waitcnt lgkmcnt(0)
	v_mfma_f32_16x16x32_f16 v[68:71], v[16:19], v[176:179], v[68:71]
	v_mfma_f32_16x16x32_f16 v[52:55], v[16:19], v[184:187], v[52:55]
	v_mfma_f32_16x16x32_f16 v[36:39], v[16:19], v[202:205], v[36:39]
	v_mfma_f32_16x16x32_f16 v[0:3], v[16:19], v[210:213], v[0:3]
	v_mfma_f32_16x16x32_f16 v[68:71], v[20:23], v[180:183], v[68:71]
	v_mfma_f32_16x16x32_f16 v[64:67], v[136:139], v[176:179], v[64:67]
	v_mfma_f32_16x16x32_f16 v[52:55], v[20:23], v[198:201], v[52:55]
	v_mfma_f32_16x16x32_f16 v[48:51], v[136:139], v[184:187], v[48:51]
	v_mfma_f32_16x16x32_f16 v[36:39], v[20:23], v[206:209], v[36:39]
	v_mfma_f32_16x16x32_f16 v[32:35], v[136:139], v[202:205], v[32:35]
	v_mfma_f32_16x16x32_f16 v[20:23], v[20:23], v[214:217], v[0:3]
	v_mfma_f32_16x16x32_f16 v[0:3], v[136:139], v[210:213], v[4:7]
	v_mfma_f32_16x16x32_f16 v[64:67], v[140:143], v[180:183], v[64:67]
	v_mfma_f32_16x16x32_f16 v[48:51], v[140:143], v[198:201], v[48:51]
	v_mfma_f32_16x16x32_f16 v[32:35], v[140:143], v[206:209], v[32:35]
	v_mfma_f32_16x16x32_f16 v[16:19], v[140:143], v[214:217], v[0:3]
	v_mfma_f32_16x16x32_f16 v[0:3], v[144:147], v[176:179], v[60:63]
	v_mfma_f32_16x16x32_f16 v[60:63], v[148:151], v[180:183], v[0:3]
	v_mfma_f32_16x16x32_f16 v[0:3], v[152:155], v[176:179], v[56:59]
	v_mfma_f32_16x16x32_f16 v[56:59], v[156:159], v[180:183], v[0:3]
	v_mfma_f32_16x16x32_f16 v[0:3], v[144:147], v[184:187], v[44:47]
	v_mfma_f32_16x16x32_f16 v[44:47], v[148:151], v[198:201], v[0:3]
	v_mfma_f32_16x16x32_f16 v[0:3], v[152:155], v[184:187], v[40:43]
	v_mfma_f32_16x16x32_f16 v[40:43], v[156:159], v[198:201], v[0:3]
	v_mfma_f32_16x16x32_f16 v[0:3], v[144:147], v[202:205], v[28:31]
	v_mfma_f32_16x16x32_f16 v[28:31], v[148:151], v[206:209], v[0:3]
	v_mfma_f32_16x16x32_f16 v[0:3], v[152:155], v[202:205], v[24:27]
	v_mfma_f32_16x16x32_f16 v[24:27], v[156:159], v[206:209], v[0:3]
	v_mfma_f32_16x16x32_f16 v[0:3], v[144:147], v[210:213], v[12:15]
	v_mfma_f32_16x16x32_f16 v[12:15], v[148:151], v[214:217], v[0:3]
	v_mfma_f32_16x16x32_f16 v[0:3], v[152:155], v[210:213], v[8:11]
	v_mfma_f32_16x16x32_f16 v[8:11], v[156:159], v[214:217], v[0:3]
	s_barrier
	s_add_i32 s62, s62, 2
	s_add_u32 s36, s36, 0x100
	s_addc_u32 s37, s37, 0
	s_add_u32 s60, s60, 0x100
	s_addc_u32 s61, s61, 0
	s_cmp_gt_u32 s62, 13
	s_cbranch_scc0 .LBB0_2566
	s_setprio 0
	s_and_b64 vcc, exec, s[16:17]
	s_cbranch_vccz .LBB0_2569
	s_barrier

; #define PG8_STAGE(bufoff, gbase, voff) do { _Pragma("unroll") for (int _i = 0; _i < 2; ++_i) \
;         __builtin_amdgcn_global_load_lds((const unsigned*)((const char*)(gbase) + (voff)[_i]), (PG8_LAS unsigned*)(lds + (bufoff) + ldsw + _i * 8192), 16, 0, 0); } while (0)
; #define PG8_LDA(dst, b, h) do { _Pragma("unroll") for (int m = 0; m < 4; ++m) _Pragma("unroll") for (int k = 0; k < 2; ++k) dst[m][k] = *(const PG8_LAS bf16x8*)(lds + PG8_SA(b, h) + aoff + m * 2048 + k * 1024); } while (0)
; #define PG8_LDB(dst, b, h) do { _Pragma("unroll") for (int n = 0; n < 2; ++n) _Pragma("unroll") for (int k = 0; k < 2; ++k) dst[n][k] = *(const PG8_LAS bf16x8*)(lds + PG8_SB(b, h) + boff + n * 2048 + k * 1024); } while (0)
; #define PG8_MMA(ai, bj, At, Bt) do { __builtin_amdgcn_s_setprio(1); _Pragma("unroll") for (int m = 0; m < 4; ++m) _Pragma("unroll") for (int n = 0; n < 2; ++n) _Pragma("unroll") for (int k = 0; k < 2; ++k) \
;         acc[ai][bj][m][n] = mma16<F16>(Bt[n][k], At[m][k], acc[ai][bj][m][n]); __builtin_amdgcn_s_setprio(0); } while (0)
; #define PG8_WAIT_V(n) asm volatile("s_waitcnt vmcnt(" #n ")" ::: "memory")
; #define PG8_BAR __builtin_amdgcn_s_barrier()
; template <class Epi, class Sched, bool ALIGN_EPI = false, bool SP2 = false, bool F16 = false>
; __device__ __forceinline__ void gemm_phase(PG8_LAS unsigned char* lds, const Gemm g, const Sched& S, const Epi& E, const int wid_in) {
;     ...
;         for (int t = 0; t < nt; t += 2) {
;             const bool last = (t == nt - 2);
;             const char* a1 = cA + (size_t)(t + 1) * kstep;
;             const char* a2 = last ? nA : cA + (size_t)(t + 2) * kstep; const char* b2 = last ? nB : cB + (size_t)(t + 2) * kstep;
;             const char* a3 = a2 + kstep; const char* b3 = b2 + kstep;
;             if (last && has_next) S.a_ready(nxt);
;             if constexpr (SP2) {
;             PG8_LDB(B0, 0, 0); PG8_LDB(B1, 0, 1); PG8_SCHED; PG8_LDA(At, 0, 0); PG8_STAGE(PG8_SA(1, 1), a1 + hstep, voffA);
;             PG8_WAIT_V(8); PG8_WAIT_L(0); PG8_BAR; PG8_MMA(0, 0, At, B0); PG8_MMA(0, 1, At, B1); PG8_BAR; PG8_SCHED;
;             PG8_LDA(At, 0, 1); PG8_STAGE(PG8_SB(0, 0), b2, voffB); PG8_STAGE(PG8_SB(0, 1), b2 + hstep, voffB); PG8_STAGE(PG8_SA(0, 0), a2, voffA);
;             PG8_WAIT_V(8); PG8_WAIT_L(0); PG8_BAR; PG8_MMA(1, 0, At, B0); PG8_MMA(1, 1, At, B1); PG8_BAR; PG8_SCHED;
.Lgsp_21:
.LBB0_2600:
	s_mov_b32 s30, 2
	s_mov_b64 s[26:27], 0
	s_andn2_b64 vcc, exec, s[28:29]
	s_mov_b32 s57, s55
	s_mov_b32 s28, s56
	s_cbranch_vccz .LBB0_2606
.LBB0_2601:
	s_mov_b64 s[42:43], s[10:11]
	s_add_i32 s10, s30, s40
	s_mov_b64 s[36:37], s[12:13]
	s_mov_b32 s12, s56
	s_mov_b32 s13, s55
	s_and_b32 s55, s10, 3
	s_ashr_i32 s56, s10, 2
	s_and_b64 s[10:11], s[26:27], exec
	s_cselect_b32 s12, s56, s12
	ds_read_b128 v[0:3], v134
	ds_read_b128 v[4:7], v134 offset:1024
	ds_read_b128 v[8:11], v134 offset:2048
	ds_read_b128 v[12:15], v134 offset:3072
	ds_read_b128 v[16:19], v135
	ds_read_b128 v[20:23], v135 offset:1024
	ds_read_b128 v[24:27], v135 offset:2048
	ds_read_b128 v[28:31], v135 offset:3072
	s_cselect_b32 s10, s55, s13
	s_ashr_i32 s13, s12, 31
	s_lshl_b64 s[12:13], s[12:13], 17
	s_add_u32 s12, s41, s12
	s_addc_u32 s13, s44, s13
	s_and_b64 s[30:31], s[26:27], exec
	s_cselect_b32 s35, s13, s37
	s_cselect_b32 s34, s12, s36
	s_ashr_i32 s11, s10, 31
	s_lshl_b64 s[10:11], s[10:11], 17
	s_add_u32 s10, s45, s10
	s_addc_u32 s11, s46, s11
	s_and_b64 s[30:31], s[26:27], exec
	s_cselect_b32 s31, s11, s43
	s_cselect_b32 s30, s10, s42
	s_add_u32 s58, s36, 0x10080
	s_addc_u32 s59, s37, 0
	s_mov_b32 m0, s91
	v_lshl_add_u64 v[64:65], s[58:59], 0, v[130:131]
	ds_read_b128 v[32:35], v136
	ds_read_b128 v[36:39], v136 offset:1024
	ds_read_b128 v[40:43], v136 offset:2048
	ds_read_b128 v[44:47], v136 offset:3072
	ds_read_b128 v[48:51], v136 offset:4096
	ds_read_b128 v[52:55], v136 offset:5120
	ds_read_b128 v[56:59], v136 offset:6144
	ds_read_b128 v[60:63], v136 offset:7168
	global_load_lds_dwordx4 v[64:65], off
	v_lshl_add_u64 v[64:65], s[58:59], 0, v[128:129]
	s_mov_b32 m0, s14
	s_nop 0
	global_load_lds_dwordx4 v[64:65], off
	s_waitcnt vmcnt(8)
	s_waitcnt lgkmcnt(0)
	s_barrier
	s_waitcnt lgkmcnt(0)
	v_mfma_f32_16x16x32_bf16 v[64:67], v[0:3], v[32:35], 0
	v_mfma_f32_16x16x32_bf16 v[68:71], v[8:11], v[32:35], 0
	v_mfma_f32_16x16x32_bf16 v[72:75], v[0:3], v[40:43], 0
	v_mfma_f32_16x16x32_bf16 v[76:79], v[8:11], v[40:43], 0
	v_mfma_f32_16x16x32_bf16 v[80:83], v[0:3], v[48:51], 0
	v_mfma_f32_16x16x32_bf16 v[84:87], v[8:11], v[48:51], 0
	v_mfma_f32_16x16x32_bf16 v[88:91], v[0:3], v[56:59], 0
	v_mfma_f32_16x16x32_bf16 v[92:95], v[8:11], v[56:59], 0
	v_mfma_f32_16x16x32_bf16 v[64:67], v[4:7], v[36:39], v[64:67]
	v_mfma_f32_16x16x32_bf16 v[68:71], v[12:15], v[36:39], v[68:71]
	v_mfma_f32_16x16x32_bf16 v[72:75], v[4:7], v[44:47], v[72:75]
	v_mfma_f32_16x16x32_bf16 v[76:79], v[12:15], v[44:47], v[76:79]
	v_mfma_f32_16x16x32_bf16 v[80:83], v[4:7], v[52:55], v[80:83]
	v_mfma_f32_16x16x32_bf16 v[84:87], v[12:15], v[52:55], v[84:87]
	v_mfma_f32_16x16x32_bf16 v[88:91], v[4:7], v[60:63], v[88:91]
	v_mfma_f32_16x16x32_bf16 v[92:95], v[12:15], v[60:63], v[92:95]
	v_mfma_f32_16x16x32_bf16 v[96:99], v[16:19], v[32:35], 0
	v_mfma_f32_16x16x32_bf16 v[32:35], v[24:27], v[32:35], 0
	v_mfma_f32_16x16x32_bf16 v[96:99], v[20:23], v[36:39], v[96:99]
	v_mfma_f32_16x16x32_bf16 v[32:35], v[28:31], v[36:39], v[32:35]
	v_mfma_f32_16x16x32_bf16 v[36:39], v[16:19], v[40:43], 0
	v_mfma_f32_16x16x32_bf16 v[40:43], v[24:27], v[40:43], 0
	v_mfma_f32_16x16x32_bf16 v[36:39], v[20:23], v[44:47], v[36:39]
	v_mfma_f32_16x16x32_bf16 v[40:43], v[28:31], v[44:47], v[40:43]
	v_mfma_f32_16x16x32_bf16 v[44:47], v[16:19], v[48:51], 0
	v_mfma_f32_16x16x32_bf16 v[48:51], v[24:27], v[48:51], 0
	v_mfma_f32_16x16x32_bf16 v[44:47], v[20:23], v[52:55], v[44:47]
	v_mfma_f32_16x16x32_bf16 v[48:51], v[28:31], v[52:55], v[48:51]
	v_mfma_f32_16x16x32_bf16 v[52:55], v[16:19], v[56:59], 0
	v_mfma_f32_16x16x32_bf16 v[56:59], v[24:27], v[56:59], 0
	v_mfma_f32_16x16x32_bf16 v[52:55], v[20:23], v[60:63], v[52:55]
	v_mfma_f32_16x16x32_bf16 v[56:59], v[28:31], v[60:63], v[56:59]
	s_barrier
	v_lshl_add_u64 v[204:205], s[42:43], 0, v[130:131]
	s_mov_b32 m0, s15
	v_lshl_add_u64 v[140:141], v[204:205], 0, s[22:23]
	v_lshl_add_u64 v[206:207], s[42:43], 0, v[128:129]
	s_add_u32 s58, s42, 0x10100
	ds_read_b128 v[60:63], v136 offset:16384
	ds_read_b128 v[100:103], v136 offset:17408
	ds_read_b128 v[104:107], v136 offset:18432
	ds_read_b128 v[108:111], v136 offset:19456
	ds_read_b128 v[112:115], v136 offset:20480
	ds_read_b128 v[116:119], v136 offset:21504
	ds_read_b128 v[120:123], v136 offset:22528
	ds_read_b128 v[124:127], v136 offset:23552
	global_load_lds_dwordx4 v[140:141], off
	v_lshl_add_u64 v[140:141], v[206:207], 0, s[22:23]
	s_mov_b32 m0, s48
	s_addc_u32 s59, s43, 0
	global_load_lds_dwordx4 v[140:141], off
	v_lshl_add_u64 v[140:141], s[58:59], 0, v[130:131]
	s_mov_b32 m0, s49
	v_lshl_add_u64 v[208:209], s[36:37], 0, v[130:131]
	global_load_lds_dwordx4 v[140:141], off
	v_lshl_add_u64 v[140:141], s[58:59], 0, v[128:129]
	s_mov_b32 m0, s50
	v_lshl_add_u64 v[210:211], s[36:37], 0, v[128:129]
	global_load_lds_dwordx4 v[140:141], off
	v_lshl_add_u64 v[140:141], v[208:209], 0, s[22:23]
	s_mov_b32 m0, s74
	s_nop 0
	global_load_lds_dwordx4 v[140:141], off
	v_lshl_add_u64 v[140:141], v[210:211], 0, s[22:23]
	s_mov_b32 m0, s66
	s_nop 0
	global_load_lds_dwordx4 v[140:141], off
	s_waitcnt vmcnt(8)
	s_waitcnt lgkmcnt(0)
	s_barrier
; #define PG8_STAGE(bufoff, gbase, voff) do { _Pragma("unroll") for (int _i = 0; _i < 2; ++_i) \
;         __builtin_amdgcn_global_load_lds((const unsigned*)((const char*)(gbase) + (voff)[_i]), (PG8_LAS unsigned*)(lds + (bufoff) + ldsw + _i * 8192), 16, 0, 0); } while (0)
; #define PG8_LDA(dst, b, h) do { _Pragma("unroll") for (int m = 0; m < 4; ++m) _Pragma("unroll") for (int k = 0; k < 2; ++k) dst[m][k] = *(const PG8_LAS bf16x8*)(lds + PG8_SA(b, h) + aoff + m * 2048 + k * 1024); } while (0)
; #define PG8_LDB(dst, b, h) do { _Pragma("unroll") for (int n = 0; n < 2; ++n) _Pragma("unroll") for (int k = 0; k < 2; ++k) dst[n][k] = *(const PG8_LAS bf16x8*)(lds + PG8_SB(b, h) + boff + n * 2048 + k * 1024); } while (0)
; #define PG8_MMA(ai, bj, At, Bt) do { __builtin_amdgcn_s_setprio(1); _Pragma("unroll") for (int m = 0; m < 4; ++m) _Pragma("unroll") for (int n = 0; n < 2; ++n) _Pragma("unroll") for (int k = 0; k < 2; ++k) \
;         acc[ai][bj][m][n] = mma16<F16>(Bt[n][k], At[m][k], acc[ai][bj][m][n]); __builtin_amdgcn_s_setprio(0); } while (0)
; #define PG8_WAIT_V(n) asm volatile("s_waitcnt vmcnt(" #n ")" ::: "memory")
; #define PG8_WAIT_L(n) asm volatile("s_waitcnt lgkmcnt(" #n ")" ::: "memory")
; #define PG8_BAR __builtin_amdgcn_s_barrier()
; #define PG8_SCHED __builtin_amdgcn_sched_barrier(0)
; template <class Epi, class Sched, bool ALIGN_EPI = false, bool SP2 = false, bool F16 = false>
; __device__ __forceinline__ void gemm_phase(PG8_LAS unsigned char* lds, const Gemm g, const Sched& S, const Epi& E, const int wid_in) {
;     ...
;             PG8_LDA(At, 0, 1); PG8_STAGE(PG8_SB(0, 0), b2, voffB); PG8_STAGE(PG8_SB(0, 1), b2 + hstep, voffB); PG8_STAGE(PG8_SA(0, 0), a2, voffA);
;             PG8_WAIT_V(8); PG8_WAIT_L(0); PG8_BAR; PG8_MMA(1, 0, At, B0); PG8_MMA(1, 1, At, B1); PG8_BAR; PG8_SCHED;
;             PG8_LDB(B0, 1, 0); PG8_LDB(B1, 1, 1); PG8_SCHED; PG8_LDA(At, 1, 0); PG8_STAGE(PG8_SA(0, 1), a2 + hstep, voffA);
;             PG8_WAIT_V(8); PG8_WAIT_L(0); PG8_BAR; PG8_MMA(0, 0, At, B0); PG8_MMA(0, 1, At, B1); PG8_BAR; PG8_SCHED;
	s_waitcnt lgkmcnt(0)
	v_mfma_f32_16x16x32_bf16 v[140:143], v[0:3], v[60:63], 0
	v_mfma_f32_16x16x32_bf16 v[148:151], v[0:3], v[104:107], 0
	v_mfma_f32_16x16x32_bf16 v[156:159], v[0:3], v[112:115], 0
	v_mfma_f32_16x16x32_bf16 v[0:3], v[0:3], v[120:123], 0
	v_mfma_f32_16x16x32_bf16 v[140:143], v[4:7], v[100:103], v[140:143]
	v_mfma_f32_16x16x32_bf16 v[148:151], v[4:7], v[108:111], v[148:151]
	v_mfma_f32_16x16x32_bf16 v[156:159], v[4:7], v[116:119], v[156:159]
	v_mfma_f32_16x16x32_bf16 v[0:3], v[4:7], v[124:127], v[0:3]
	v_mfma_f32_16x16x32_bf16 v[4:7], v[8:11], v[120:123], 0
	v_mfma_f32_16x16x32_bf16 v[144:147], v[8:11], v[60:63], 0
	v_mfma_f32_16x16x32_bf16 v[152:155], v[8:11], v[104:107], 0
	v_mfma_f32_16x16x32_bf16 v[160:163], v[8:11], v[112:115], 0
	v_mfma_f32_16x16x32_bf16 v[4:7], v[12:15], v[124:127], v[4:7]
	v_mfma_f32_16x16x32_bf16 v[144:147], v[12:15], v[100:103], v[144:147]
	v_mfma_f32_16x16x32_bf16 v[152:155], v[12:15], v[108:111], v[152:155]
	v_mfma_f32_16x16x32_bf16 v[160:163], v[12:15], v[116:119], v[160:163]
	v_mfma_f32_16x16x32_bf16 v[8:11], v[16:19], v[60:63], 0
	v_mfma_f32_16x16x32_bf16 v[12:15], v[24:27], v[60:63], 0
	v_mfma_f32_16x16x32_bf16 v[8:11], v[20:23], v[100:103], v[8:11]
	v_mfma_f32_16x16x32_bf16 v[12:15], v[28:31], v[100:103], v[12:15]
	v_mfma_f32_16x16x32_bf16 v[60:63], v[16:19], v[104:107], 0
	v_mfma_f32_16x16x32_bf16 v[100:103], v[24:27], v[104:107], 0
	v_mfma_f32_16x16x32_bf16 v[104:107], v[16:19], v[112:115], 0
	v_mfma_f32_16x16x32_bf16 v[16:19], v[16:19], v[120:123], 0
	v_mfma_f32_16x16x32_bf16 v[60:63], v[20:23], v[108:111], v[60:63]
	v_mfma_f32_16x16x32_bf16 v[100:103], v[28:31], v[108:111], v[100:103]
	v_mfma_f32_16x16x32_bf16 v[104:107], v[20:23], v[116:119], v[104:107]
	v_mfma_f32_16x16x32_bf16 v[108:111], v[24:27], v[112:115], 0
	v_mfma_f32_16x16x32_bf16 v[16:19], v[20:23], v[124:127], v[16:19]
	v_mfma_f32_16x16x32_bf16 v[20:23], v[24:27], v[120:123], 0
	v_mfma_f32_16x16x32_bf16 v[108:111], v[28:31], v[116:119], v[108:111]
	v_mfma_f32_16x16x32_bf16 v[20:23], v[28:31], v[124:127], v[20:23]
	s_barrier
	ds_read_b128 v[24:27], v137
	ds_read_b128 v[28:31], v137 offset:1024
	ds_read_b128 v[112:115], v137 offset:2048
	ds_read_b128 v[116:119], v137 offset:3072
	ds_read_b128 v[120:123], v138
	ds_read_b128 v[124:127], v138 offset:1024
	ds_read_b128 v[164:167], v138 offset:2048
	ds_read_b128 v[168:171], v138 offset:3072
	s_add_u32 s58, s36, 0x10100
	s_addc_u32 s59, s37, 0
	s_mov_b32 m0, s90
	v_lshl_add_u64 v[212:213], s[58:59], 0, v[130:131]
	ds_read_b128 v[172:175], v136 offset:32768
	ds_read_b128 v[176:179], v136 offset:33792
	ds_read_b128 v[180:183], v136 offset:34816
	ds_read_b128 v[184:187], v136 offset:35840
	ds_read_b128 v[188:191], v136 offset:36864
	ds_read_b128 v[192:195], v136 offset:37888
	ds_read_b128 v[196:199], v136 offset:38912
	ds_read_b128 v[200:203], v136 offset:39936
	global_load_lds_dwordx4 v[212:213], off
	v_lshl_add_u64 v[212:213], s[58:59], 0, v[128:129]
	s_mov_b32 m0, s47
	s_nop 0
	global_load_lds_dwordx4 v[212:213], off
	s_waitcnt vmcnt(8)
	s_waitcnt lgkmcnt(0)
	s_barrier
	s_waitcnt lgkmcnt(0)
	v_mfma_f32_16x16x32_bf16 v[64:67], v[24:27], v[172:175], v[64:67]
	v_mfma_f32_16x16x32_bf16 v[68:71], v[112:115], v[172:175], v[68:71]
	v_mfma_f32_16x16x32_bf16 v[72:75], v[24:27], v[180:183], v[72:75]
	v_mfma_f32_16x16x32_bf16 v[76:79], v[112:115], v[180:183], v[76:79]
	v_mfma_f32_16x16x32_bf16 v[80:83], v[24:27], v[188:191], v[80:83]
	v_mfma_f32_16x16x32_bf16 v[84:87], v[112:115], v[188:191], v[84:87]
	v_mfma_f32_16x16x32_bf16 v[88:91], v[24:27], v[196:199], v[88:91]
	v_mfma_f32_16x16x32_bf16 v[92:95], v[112:115], v[196:199], v[92:95]
	v_mfma_f32_16x16x32_bf16 v[64:67], v[28:31], v[176:179], v[64:67]
	v_mfma_f32_16x16x32_bf16 v[68:71], v[116:119], v[176:179], v[68:71]
	v_mfma_f32_16x16x32_bf16 v[72:75], v[28:31], v[184:187], v[72:75]
	v_mfma_f32_16x16x32_bf16 v[76:79], v[116:119], v[184:187], v[76:79]
	v_mfma_f32_16x16x32_bf16 v[80:83], v[28:31], v[192:195], v[80:83]
	v_mfma_f32_16x16x32_bf16 v[84:87], v[116:119], v[192:195], v[84:87]
	v_mfma_f32_16x16x32_bf16 v[88:91], v[28:31], v[200:203], v[88:91]
	v_mfma_f32_16x16x32_bf16 v[92:95], v[116:119], v[200:203], v[92:95]
	v_mfma_f32_16x16x32_bf16 v[96:99], v[120:123], v[172:175], v[96:99]
	v_mfma_f32_16x16x32_bf16 v[32:35], v[164:167], v[172:175], v[32:35]
	v_mfma_f32_16x16x32_bf16 v[36:39], v[120:123], v[180:183], v[36:39]
	v_mfma_f32_16x16x32_bf16 v[40:43], v[164:167], v[180:183], v[40:43]
	v_mfma_f32_16x16x32_bf16 v[44:47], v[120:123], v[188:191], v[44:47]
	v_mfma_f32_16x16x32_bf16 v[48:51], v[164:167], v[188:191], v[48:51]
	v_mfma_f32_16x16x32_bf16 v[52:55], v[120:123], v[196:199], v[52:55]
	v_mfma_f32_16x16x32_bf16 v[56:59], v[164:167], v[196:199], v[56:59]
	v_mfma_f32_16x16x32_bf16 v[96:99], v[124:127], v[176:179], v[96:99]
	v_mfma_f32_16x16x32_bf16 v[32:35], v[168:171], v[176:179], v[32:35]
	v_mfma_f32_16x16x32_bf16 v[36:39], v[124:127], v[184:187], v[36:39]
	v_mfma_f32_16x16x32_bf16 v[40:43], v[168:171], v[184:187], v[40:43]
	v_mfma_f32_16x16x32_bf16 v[44:47], v[124:127], v[192:195], v[44:47]
	v_mfma_f32_16x16x32_bf16 v[48:51], v[168:171], v[192:195], v[48:51]
	v_mfma_f32_16x16x32_bf16 v[52:55], v[124:127], v[200:203], v[52:55]
	v_mfma_f32_16x16x32_bf16 v[56:59], v[168:171], v[200:203], v[56:59]
	s_barrier
; #define PG8_STAGE(bufoff, gbase, voff) do { _Pragma("unroll") for (int _i = 0; _i < 2; ++_i) \
;         __builtin_amdgcn_global_load_lds((const unsigned*)((const char*)(gbase) + (voff)[_i]), (PG8_LAS unsigned*)(lds + (bufoff) + ldsw + _i * 8192), 16, 0, 0); } while (0)
; #define PG8_LDA(dst, b, h) do { _Pragma("unroll") for (int m = 0; m < 4; ++m) _Pragma("unroll") for (int k = 0; k < 2; ++k) dst[m][k] = *(const PG8_LAS bf16x8*)(lds + PG8_SA(b, h) + aoff + m * 2048 + k * 1024); } while (0)
; #define PG8_LDB(dst, b, h) do { _Pragma("unroll") for (int n = 0; n < 2; ++n) _Pragma("unroll") for (int k = 0; k < 2; ++k) dst[n][k] = *(const PG8_LAS bf16x8*)(lds + PG8_SB(b, h) + boff + n * 2048 + k * 1024); } while (0)
; #define PG8_MMA(ai, bj, At, Bt) do { __builtin_amdgcn_s_setprio(1); _Pragma("unroll") for (int m = 0; m < 4; ++m) _Pragma("unroll") for (int n = 0; n < 2; ++n) _Pragma("unroll") for (int k = 0; k < 2; ++k) \
;         acc[ai][bj][m][n] = mma16<F16>(Bt[n][k], At[m][k], acc[ai][bj][m][n]); __builtin_amdgcn_s_setprio(0); } while (0)
; #define PG8_WAIT_V(n) asm volatile("s_waitcnt vmcnt(" #n ")" ::: "memory")
; template <class Epi, class Sched, bool ALIGN_EPI = false, bool SP2 = false, bool F16 = false>
; __device__ __forceinline__ void gemm_phase(PG8_LAS unsigned char* lds, const Gemm g, const Sched& S, const Epi& E, const int wid_in) {
;     ...
;             PG8_LDB(B0, 0, 0); PG8_LDB(B1, 0, 1); PG8_SCHED; PG8_LDA(At, 0, 0); PG8_STAGE(PG8_SA(1, 1), a1 + hstep, voffA);
;             PG8_WAIT_V(8); PG8_WAIT_L(0); PG8_BAR; PG8_MMA(0, 0, At, B0); PG8_MMA(0, 1, At, B1); PG8_BAR; PG8_SCHED;
;             PG8_LDA(At, 0, 1); PG8_STAGE(PG8_SB(0, 0), b2, voffB); PG8_STAGE(PG8_SB(0, 1), b2 + hstep, voffB); PG8_STAGE(PG8_SA(0, 0), a2, voffA);
;             PG8_WAIT_V(8); PG8_WAIT_L(0); PG8_BAR; PG8_MMA(1, 0, At, B0); PG8_MMA(1, 1, At, B1); PG8_BAR; PG8_SCHED;
;             PG8_LDB(B0, 1, 0); PG8_LDB(B1, 1, 1); PG8_SCHED; PG8_LDA(At, 1, 0); PG8_STAGE(PG8_SA(0, 1), a2 + hstep, voffA);
;             PG8_WAIT_V(8); PG8_WAIT_L(0); PG8_BAR; PG8_MMA(0, 0, At, B0); PG8_MMA(0, 1, At, B1); PG8_BAR; PG8_SCHED;
;             PG8_LDA(At, 1, 1); PG8_STAGE(PG8_SB(1, 0), b3, voffB); PG8_STAGE(PG8_SB(1, 1), b3 + hstep, voffB); PG8_STAGE(PG8_SA(1, 0), a3, voffA);
;             PG8_WAIT_V(8); PG8_WAIT_L(0); PG8_BAR; PG8_MMA(1, 0, At, B0); PG8_MMA(1, 1, At, B1); PG8_BAR; PG8_SCHED;
	s_mov_b32 m0, s51
	v_lshl_add_u64 v[204:205], v[204:205], 0, s[24:25]
	s_add_u32 s42, s42, 0x10180
	ds_read_b128 v[172:175], v136 offset:49152
	ds_read_b128 v[176:179], v136 offset:50176
	ds_read_b128 v[180:183], v136 offset:51200
	ds_read_b128 v[184:187], v136 offset:52224
	ds_read_b128 v[188:191], v136 offset:53248
	ds_read_b128 v[192:195], v136 offset:54272
	ds_read_b128 v[196:199], v136 offset:55296
	ds_read_b128 v[200:203], v136 offset:56320
	global_load_lds_dwordx4 v[204:205], off
	v_lshl_add_u64 v[204:205], v[206:207], 0, s[24:25]
	s_mov_b32 m0, s52
	s_addc_u32 s43, s43, 0
	global_load_lds_dwordx4 v[204:205], off
	v_lshl_add_u64 v[204:205], s[42:43], 0, v[130:131]
	s_mov_b32 m0, s53
	s_nop 0
	global_load_lds_dwordx4 v[204:205], off
	v_lshl_add_u64 v[204:205], s[42:43], 0, v[128:129]
	s_mov_b32 m0, s54
	s_nop 0
	global_load_lds_dwordx4 v[204:205], off
	v_lshl_add_u64 v[204:205], v[208:209], 0, s[24:25]
	s_mov_b32 m0, s75
	s_nop 0
	global_load_lds_dwordx4 v[204:205], off
	v_lshl_add_u64 v[204:205], v[210:211], 0, s[24:25]
	s_mov_b32 m0, s67
	s_nop 0
	global_load_lds_dwordx4 v[204:205], off
	s_waitcnt vmcnt(8)
	s_waitcnt lgkmcnt(0)
	s_barrier
	s_waitcnt lgkmcnt(0)
	v_mfma_f32_16x16x32_bf16 v[0:3], v[24:27], v[196:199], v[0:3]
	v_mfma_f32_16x16x32_bf16 v[4:7], v[112:115], v[196:199], v[4:7]
	v_mfma_f32_16x16x32_bf16 v[140:143], v[24:27], v[172:175], v[140:143]
	v_mfma_f32_16x16x32_bf16 v[144:147], v[112:115], v[172:175], v[144:147]
	v_mfma_f32_16x16x32_bf16 v[148:151], v[24:27], v[180:183], v[148:151]
	v_mfma_f32_16x16x32_bf16 v[152:155], v[112:115], v[180:183], v[152:155]
	v_mfma_f32_16x16x32_bf16 v[156:159], v[24:27], v[188:191], v[156:159]
	v_mfma_f32_16x16x32_bf16 v[160:163], v[112:115], v[188:191], v[160:163]
	v_mfma_f32_16x16x32_bf16 v[0:3], v[28:31], v[200:203], v[0:3]
	v_mfma_f32_16x16x32_bf16 v[4:7], v[116:119], v[200:203], v[4:7]
	v_mfma_f32_16x16x32_bf16 v[140:143], v[28:31], v[176:179], v[140:143]
	v_mfma_f32_16x16x32_bf16 v[144:147], v[116:119], v[176:179], v[144:147]
	v_mfma_f32_16x16x32_bf16 v[148:151], v[28:31], v[184:187], v[148:151]
	v_mfma_f32_16x16x32_bf16 v[152:155], v[116:119], v[184:187], v[152:155]
	v_mfma_f32_16x16x32_bf16 v[156:159], v[28:31], v[192:195], v[156:159]
	v_mfma_f32_16x16x32_bf16 v[160:163], v[116:119], v[192:195], v[160:163]
	v_mfma_f32_16x16x32_bf16 v[8:11], v[120:123], v[172:175], v[8:11]
	v_mfma_f32_16x16x32_bf16 v[12:15], v[164:167], v[172:175], v[12:15]
	v_mfma_f32_16x16x32_bf16 v[24:27], v[120:123], v[180:183], v[60:63]
	v_mfma_f32_16x16x32_bf16 v[28:31], v[164:167], v[180:183], v[100:103]
	v_mfma_f32_16x16x32_bf16 v[60:63], v[120:123], v[188:191], v[104:107]
	v_mfma_f32_16x16x32_bf16 v[100:103], v[164:167], v[188:191], v[108:111]
	v_mfma_f32_16x16x32_bf16 v[16:19], v[120:123], v[196:199], v[16:19]
	v_mfma_f32_16x16x32_bf16 v[20:23], v[164:167], v[196:199], v[20:23]
	v_mfma_f32_16x16x32_bf16 v[8:11], v[124:127], v[176:179], v[8:11]
	v_mfma_f32_16x16x32_bf16 v[12:15], v[168:171], v[176:179], v[12:15]
	v_mfma_f32_16x16x32_bf16 v[24:27], v[124:127], v[184:187], v[24:27]
	v_mfma_f32_16x16x32_bf16 v[28:31], v[168:171], v[184:187], v[28:31]
	v_mfma_f32_16x16x32_bf16 v[60:63], v[124:127], v[192:195], v[60:63]
	v_mfma_f32_16x16x32_bf16 v[100:103], v[168:171], v[192:195], v[100:103]
	v_mfma_f32_16x16x32_bf16 v[16:19], v[124:127], v[200:203], v[16:19]
	v_mfma_f32_16x16x32_bf16 v[20:23], v[168:171], v[200:203], v[20:23]
	s_barrier
	ds_read_b128 v[104:107], v134
	ds_read_b128 v[108:111], v134 offset:1024
	ds_read_b128 v[112:115], v134 offset:2048
	ds_read_b128 v[116:119], v134 offset:3072
	ds_read_b128 v[120:123], v135
	ds_read_b128 v[124:127], v135 offset:1024
	ds_read_b128 v[164:167], v135 offset:2048
	ds_read_b128 v[168:171], v135 offset:3072
	s_add_u32 s36, s36, 0x10180
	s_addc_u32 s37, s37, 0
	s_mov_b32 m0, s91
	v_lshl_add_u64 v[204:205], s[36:37], 0, v[130:131]
	ds_read_b128 v[172:175], v136
	ds_read_b128 v[176:179], v136 offset:1024
	ds_read_b128 v[180:183], v136 offset:2048
	ds_read_b128 v[184:187], v136 offset:3072
	ds_read_b128 v[188:191], v136 offset:4096
	ds_read_b128 v[192:195], v136 offset:5120
	ds_read_b128 v[196:199], v136 offset:6144
	ds_read_b128 v[200:203], v136 offset:7168
	global_load_lds_dwordx4 v[204:205], off
	v_lshl_add_u64 v[204:205], s[36:37], 0, v[128:129]
	s_mov_b32 m0, s14
	s_nop 0
	global_load_lds_dwordx4 v[204:205], off
	s_waitcnt vmcnt(8)
	s_waitcnt lgkmcnt(0)
	s_barrier
	s_waitcnt lgkmcnt(0)
	v_mfma_f32_16x16x32_bf16 v[64:67], v[104:107], v[172:175], v[64:67]
	v_mfma_f32_16x16x32_bf16 v[68:71], v[112:115], v[172:175], v[68:71]
	v_mfma_f32_16x16x32_bf16 v[72:75], v[104:107], v[180:183], v[72:75]
	v_mfma_f32_16x16x32_bf16 v[76:79], v[112:115], v[180:183], v[76:79]
	v_mfma_f32_16x16x32_bf16 v[80:83], v[104:107], v[188:191], v[80:83]
	v_mfma_f32_16x16x32_bf16 v[84:87], v[112:115], v[188:191], v[84:87]
	v_mfma_f32_16x16x32_bf16 v[88:91], v[104:107], v[196:199], v[88:91]
	v_mfma_f32_16x16x32_bf16 v[92:95], v[112:115], v[196:199], v[92:95]
	v_mfma_f32_16x16x32_bf16 v[64:67], v[108:111], v[176:179], v[64:67]
	v_mfma_f32_16x16x32_bf16 v[68:71], v[116:119], v[176:179], v[68:71]
	v_mfma_f32_16x16x32_bf16 v[72:75], v[108:111], v[184:187], v[72:75]
	v_mfma_f32_16x16x32_bf16 v[76:79], v[116:119], v[184:187], v[76:79]
	v_mfma_f32_16x16x32_bf16 v[80:83], v[108:111], v[192:195], v[80:83]
	v_mfma_f32_16x16x32_bf16 v[84:87], v[116:119], v[192:195], v[84:87]
	v_mfma_f32_16x16x32_bf16 v[88:91], v[108:111], v[200:203], v[88:91]
	v_mfma_f32_16x16x32_bf16 v[92:95], v[116:119], v[200:203], v[92:95]
	v_mfma_f32_16x16x32_bf16 v[32:35], v[164:167], v[172:175], v[32:35]
	v_mfma_f32_16x16x32_bf16 v[96:99], v[120:123], v[172:175], v[96:99]
	v_mfma_f32_16x16x32_bf16 v[172:175], v[168:171], v[176:179], v[32:35]
	v_mfma_f32_16x16x32_bf16 v[32:35], v[120:123], v[180:183], v[36:39]
	v_mfma_f32_16x16x32_bf16 v[204:207], v[124:127], v[176:179], v[96:99]
	v_mfma_f32_16x16x32_bf16 v[176:179], v[124:127], v[184:187], v[32:35]
	v_mfma_f32_16x16x32_bf16 v[32:35], v[164:167], v[180:183], v[40:43]
	v_mfma_f32_16x16x32_bf16 v[40:43], v[168:171], v[184:187], v[32:35]
	v_mfma_f32_16x16x32_bf16 v[32:35], v[120:123], v[188:191], v[44:47]
	v_mfma_f32_16x16x32_bf16 v[44:47], v[124:127], v[192:195], v[32:35]
	v_mfma_f32_16x16x32_bf16 v[32:35], v[164:167], v[188:191], v[48:51]
	v_mfma_f32_16x16x32_bf16 v[48:51], v[168:171], v[192:195], v[32:35]
	v_mfma_f32_16x16x32_bf16 v[32:35], v[120:123], v[196:199], v[52:55]
	v_mfma_f32_16x16x32_bf16 v[52:55], v[124:127], v[200:203], v[32:35]
	v_mfma_f32_16x16x32_bf16 v[32:35], v[164:167], v[196:199], v[56:59]
	v_mfma_f32_16x16x32_bf16 v[56:59], v[168:171], v[200:203], v[32:35]
	s_barrier
; #define PG8_STAGE(bufoff, gbase, voff) do { _Pragma("unroll") for (int _i = 0; _i < 2; ++_i) \
;         __builtin_amdgcn_global_load_lds((const unsigned*)((const char*)(gbase) + (voff)[_i]), (PG8_LAS unsigned*)(lds + (bufoff) + ldsw + _i * 8192), 16, 0, 0); } while (0)
; #define PG8_LDA(dst, b, h) do { _Pragma("unroll") for (int m = 0; m < 4; ++m) _Pragma("unroll") for (int k = 0; k < 2; ++k) dst[m][k] = *(const PG8_LAS bf16x8*)(lds + PG8_SA(b, h) + aoff + m * 2048 + k * 1024); } while (0)
; #define PG8_LDB(dst, b, h) do { _Pragma("unroll") for (int n = 0; n < 2; ++n) _Pragma("unroll") for (int k = 0; k < 2; ++k) dst[n][k] = *(const PG8_LAS bf16x8*)(lds + PG8_SB(b, h) + boff + n * 2048 + k * 1024); } while (0)
; #define PG8_MMA(ai, bj, At, Bt) do { __builtin_amdgcn_s_setprio(1); _Pragma("unroll") for (int m = 0; m < 4; ++m) _Pragma("unroll") for (int n = 0; n < 2; ++n) _Pragma("unroll") for (int k = 0; k < 2; ++k) \
;         acc[ai][bj][m][n] = mma16<F16>(Bt[n][k], At[m][k], acc[ai][bj][m][n]); __builtin_amdgcn_s_setprio(0); } while (0)
; #define PG8_WAIT_V(n) asm volatile("s_waitcnt vmcnt(" #n ")" ::: "memory")
; #define PG8_WAIT_L(n) asm volatile("s_waitcnt lgkmcnt(" #n ")" ::: "memory")
; #define PG8_BAR __builtin_amdgcn_s_barrier()
; #define PG8_SCHED __builtin_amdgcn_sched_barrier(0)
; template <class Epi, class Sched, bool ALIGN_EPI = false, bool SP2 = false, bool F16 = false>
; __device__ __forceinline__ void gemm_phase(PG8_LAS unsigned char* lds, const Gemm g, const Sched& S, const Epi& E, const int wid_in) {
;     ...
;             PG8_LDA(At, 0, 1); PG8_STAGE(PG8_SB(0, 0), b2, voffB); PG8_STAGE(PG8_SB(0, 1), b2 + hstep, voffB); PG8_STAGE(PG8_SA(0, 0), a2, voffA);
;             PG8_WAIT_V(8); PG8_WAIT_L(0); PG8_BAR; PG8_MMA(1, 0, At, B0); PG8_MMA(1, 1, At, B1); PG8_BAR; PG8_SCHED;
;             PG8_LDB(B0, 1, 0); PG8_LDB(B1, 1, 1); PG8_SCHED; PG8_LDA(At, 1, 0); PG8_STAGE(PG8_SA(0, 1), a2 + hstep, voffA);
;             PG8_WAIT_V(8); PG8_WAIT_L(0); PG8_BAR; PG8_MMA(0, 0, At, B0); PG8_MMA(0, 1, At, B1); PG8_BAR; PG8_SCHED;
	s_mov_b32 m0, s15
	v_lshl_add_u64 v[240:241], s[30:31], 0, v[130:131]
	s_add_u32 s36, s30, 0x10000
	s_nop 1
	ds_read_b128 v[32:35], v136 offset:16384
	ds_read_b128 v[36:39], v136 offset:17408
	ds_read_b128 v[96:99], v136 offset:18432
	ds_read_b128 v[180:183], v136 offset:19456
	ds_read_b128 v[184:187], v136 offset:20480
	ds_read_b128 v[188:191], v136 offset:21504
	ds_read_b128 v[192:195], v136 offset:22528
	ds_read_b128 v[196:199], v136 offset:23552
	global_load_lds_dwordx4 v[240:241], off
	v_lshl_add_u64 v[242:243], s[30:31], 0, v[128:129]
	s_mov_b32 m0, s48
	s_addc_u32 s37, s31, 0
	global_load_lds_dwordx4 v[242:243], off
	v_lshl_add_u64 v[200:201], s[36:37], 0, v[130:131]
	s_mov_b32 m0, s49
	v_lshl_add_u64 v[244:245], s[34:35], 0, v[130:131]
	global_load_lds_dwordx4 v[200:201], off
	v_lshl_add_u64 v[200:201], s[36:37], 0, v[128:129]
	s_mov_b32 m0, s50
	v_lshl_add_u64 v[246:247], s[34:35], 0, v[128:129]
	global_load_lds_dwordx4 v[200:201], off
	s_mov_b32 m0, s74
	s_nop 0
	global_load_lds_dwordx4 v[244:245], off
	s_mov_b32 m0, s66
	s_nop 0
	global_load_lds_dwordx4 v[246:247], off
	s_waitcnt vmcnt(8)
	s_waitcnt lgkmcnt(0)
	s_barrier
	s_waitcnt lgkmcnt(0)
	v_mfma_f32_16x16x32_bf16 v[0:3], v[104:107], v[192:195], v[0:3]
	v_mfma_f32_16x16x32_bf16 v[140:143], v[104:107], v[32:35], v[140:143]
	v_mfma_f32_16x16x32_bf16 v[144:147], v[112:115], v[32:35], v[144:147]
	v_mfma_f32_16x16x32_bf16 v[148:151], v[104:107], v[96:99], v[148:151]
	v_mfma_f32_16x16x32_bf16 v[152:155], v[112:115], v[96:99], v[152:155]
	v_mfma_f32_16x16x32_bf16 v[156:159], v[104:107], v[184:187], v[156:159]
	v_mfma_f32_16x16x32_bf16 v[160:163], v[112:115], v[184:187], v[160:163]
	v_mfma_f32_16x16x32_bf16 v[0:3], v[108:111], v[196:199], v[0:3]
	v_mfma_f32_16x16x32_bf16 v[4:7], v[112:115], v[192:195], v[4:7]
	v_mfma_f32_16x16x32_bf16 v[140:143], v[108:111], v[36:39], v[140:143]
	v_mfma_f32_16x16x32_bf16 v[144:147], v[116:119], v[36:39], v[144:147]
	v_mfma_f32_16x16x32_bf16 v[148:151], v[108:111], v[180:183], v[148:151]
	v_mfma_f32_16x16x32_bf16 v[152:155], v[116:119], v[180:183], v[152:155]
	v_mfma_f32_16x16x32_bf16 v[156:159], v[108:111], v[188:191], v[156:159]
	v_mfma_f32_16x16x32_bf16 v[160:163], v[116:119], v[188:191], v[160:163]
	v_mfma_f32_16x16x32_bf16 v[200:203], v[116:119], v[196:199], v[4:7]
	v_mfma_f32_16x16x32_bf16 v[4:7], v[120:123], v[32:35], v[8:11]
	v_mfma_f32_16x16x32_bf16 v[8:11], v[124:127], v[36:39], v[4:7]
	v_mfma_f32_16x16x32_bf16 v[4:7], v[164:167], v[32:35], v[12:15]
	v_mfma_f32_16x16x32_bf16 v[12:15], v[168:171], v[36:39], v[4:7]
	v_mfma_f32_16x16x32_bf16 v[4:7], v[120:123], v[96:99], v[24:27]
	v_mfma_f32_16x16x32_bf16 v[24:27], v[124:127], v[180:183], v[4:7]
	v_mfma_f32_16x16x32_bf16 v[4:7], v[164:167], v[96:99], v[28:31]
	v_mfma_f32_16x16x32_bf16 v[28:31], v[168:171], v[180:183], v[4:7]
	v_mfma_f32_16x16x32_bf16 v[4:7], v[120:123], v[184:187], v[60:63]
	v_mfma_f32_16x16x32_bf16 v[180:183], v[124:127], v[188:191], v[4:7]
	v_mfma_f32_16x16x32_bf16 v[4:7], v[164:167], v[184:187], v[100:103]
	v_mfma_f32_16x16x32_bf16 v[184:187], v[168:171], v[188:191], v[4:7]
	v_mfma_f32_16x16x32_bf16 v[4:7], v[120:123], v[192:195], v[16:19]
	v_mfma_f32_16x16x32_bf16 v[188:191], v[124:127], v[196:199], v[4:7]
	v_mfma_f32_16x16x32_bf16 v[4:7], v[164:167], v[192:195], v[20:23]
	v_mfma_f32_16x16x32_bf16 v[164:167], v[168:171], v[196:199], v[4:7]
	s_barrier
	s_nop 4
	ds_read_b128 v[4:7], v137
	ds_read_b128 v[60:63], v137 offset:1024
	ds_read_b128 v[168:171], v137 offset:2048
	ds_read_b128 v[192:195], v137 offset:3072
	ds_read_b128 v[196:199], v138
	ds_read_b128 v[208:211], v138 offset:1024
	ds_read_b128 v[212:215], v138 offset:2048
	ds_read_b128 v[216:219], v138 offset:3072
	s_add_u32 s34, s34, 0x10000
	s_addc_u32 s35, s35, 0
	s_mov_b32 m0, s90
	v_lshl_add_u64 v[32:33], s[34:35], 0, v[130:131]
	ds_read_b128 v[16:19], v136 offset:32768
	ds_read_b128 v[20:23], v136 offset:33792
	ds_read_b128 v[104:107], v136 offset:34816
	ds_read_b128 v[220:223], v136 offset:35840
	ds_read_b128 v[224:227], v136 offset:36864
	ds_read_b128 v[228:231], v136 offset:37888
	ds_read_b128 v[232:235], v136 offset:38912
	ds_read_b128 v[236:239], v136 offset:39936
	global_load_lds_dwordx4 v[32:33], off
	v_lshl_add_u64 v[32:33], s[34:35], 0, v[128:129]
	s_mov_b32 m0, s47
	s_nop 0
	global_load_lds_dwordx4 v[32:33], off
	s_waitcnt vmcnt(8)
	s_waitcnt lgkmcnt(0)
	s_barrier
	s_waitcnt lgkmcnt(0)
	v_mfma_f32_16x16x32_bf16 v[32:35], v[4:7], v[16:19], v[64:67]
	v_mfma_f32_16x16x32_bf16 v[116:119], v[60:63], v[20:23], v[32:35]
	v_mfma_f32_16x16x32_bf16 v[32:35], v[168:171], v[16:19], v[68:71]
	v_mfma_f32_16x16x32_bf16 v[112:115], v[192:195], v[20:23], v[32:35]
	v_mfma_f32_16x16x32_bf16 v[32:35], v[4:7], v[104:107], v[72:75]
	v_mfma_f32_16x16x32_bf16 v[100:103], v[60:63], v[220:223], v[32:35]
	v_mfma_f32_16x16x32_bf16 v[32:35], v[168:171], v[104:107], v[76:79]
	v_mfma_f32_16x16x32_bf16 v[96:99], v[192:195], v[220:223], v[32:35]
	v_mfma_f32_16x16x32_bf16 v[32:35], v[4:7], v[224:227], v[80:83]
	v_mfma_f32_16x16x32_bf16 v[68:71], v[60:63], v[228:231], v[32:35]
	v_mfma_f32_16x16x32_bf16 v[32:35], v[168:171], v[224:227], v[84:87]
	v_mfma_f32_16x16x32_bf16 v[64:67], v[192:195], v[228:231], v[32:35]
	v_mfma_f32_16x16x32_bf16 v[32:35], v[4:7], v[232:235], v[88:91]
	v_mfma_f32_16x16x32_bf16 v[36:39], v[60:63], v[236:239], v[32:35]
	v_mfma_f32_16x16x32_bf16 v[32:35], v[168:171], v[232:235], v[92:95]
	v_mfma_f32_16x16x32_bf16 v[32:35], v[192:195], v[236:239], v[32:35]
	v_mfma_f32_16x16x32_bf16 v[72:75], v[196:199], v[16:19], v[204:207]
	v_mfma_f32_16x16x32_bf16 v[16:19], v[212:215], v[16:19], v[172:175]
	v_mfma_f32_16x16x32_bf16 v[120:123], v[216:219], v[20:23], v[16:19]
	v_mfma_f32_16x16x32_bf16 v[16:19], v[196:199], v[104:107], v[176:179]
	v_mfma_f32_16x16x32_bf16 v[108:111], v[208:211], v[220:223], v[16:19]
	v_mfma_f32_16x16x32_bf16 v[16:19], v[212:215], v[104:107], v[40:43]
	v_mfma_f32_16x16x32_bf16 v[104:107], v[216:219], v[220:223], v[16:19]
	v_mfma_f32_16x16x32_bf16 v[16:19], v[196:199], v[224:227], v[44:47]
	v_mfma_f32_16x16x32_bf16 v[80:83], v[208:211], v[228:231], v[16:19]
	v_mfma_f32_16x16x32_bf16 v[16:19], v[212:215], v[224:227], v[48:51]
	v_mfma_f32_16x16x32_bf16 v[124:127], v[208:211], v[20:23], v[72:75]
	v_mfma_f32_16x16x32_bf16 v[72:75], v[216:219], v[228:231], v[16:19]
	v_mfma_f32_16x16x32_bf16 v[16:19], v[196:199], v[232:235], v[52:55]
	v_mfma_f32_16x16x32_bf16 v[48:51], v[208:211], v[236:239], v[16:19]
	v_mfma_f32_16x16x32_bf16 v[16:19], v[212:215], v[232:235], v[56:59]
	v_mfma_f32_16x16x32_bf16 v[40:43], v[216:219], v[236:239], v[16:19]
	s_barrier
; #define PG8_STAGE(bufoff, gbase, voff) do { _Pragma("unroll") for (int _i = 0; _i < 2; ++_i) \
;         __builtin_amdgcn_global_load_lds((const unsigned*)((const char*)(gbase) + (voff)[_i]), (PG8_LAS unsigned*)(lds + (bufoff) + ldsw + _i * 8192), 16, 0, 0); } while (0)
; #define PG8_LDA(dst, b, h) do { _Pragma("unroll") for (int m = 0; m < 4; ++m) _Pragma("unroll") for (int k = 0; k < 2; ++k) dst[m][k] = *(const PG8_LAS bf16x8*)(lds + PG8_SA(b, h) + aoff + m * 2048 + k * 1024); } while (0)
; #define PG8_MMA(ai, bj, At, Bt) do { __builtin_amdgcn_s_setprio(1); _Pragma("unroll") for (int m = 0; m < 4; ++m) _Pragma("unroll") for (int n = 0; n < 2; ++n) _Pragma("unroll") for (int k = 0; k < 2; ++k) \
;         acc[ai][bj][m][n] = mma16<F16>(Bt[n][k], At[m][k], acc[ai][bj][m][n]); __builtin_amdgcn_s_setprio(0); } while (0)
; #define PG8_WAIT_V(n) asm volatile("s_waitcnt vmcnt(" #n ")" ::: "memory")
; #define PG8_WAIT_L(n) asm volatile("s_waitcnt lgkmcnt(" #n ")" ::: "memory")
; #define PG8_BAR __builtin_amdgcn_s_barrier()
; #define PG8_SCHED __builtin_amdgcn_sched_barrier(0)
; template <class Epi, class Sched, bool ALIGN_EPI = false, bool SP2 = false, bool F16 = false>
; __device__ __forceinline__ void gemm_phase(PG8_LAS unsigned char* lds, const Gemm g, const Sched& S, const Epi& E, const int wid_in) {
;     ...
;             PG8_LDA(At, 1, 1); PG8_STAGE(PG8_SB(1, 0), b3, voffB); PG8_STAGE(PG8_SB(1, 1), b3 + hstep, voffB); PG8_STAGE(PG8_SA(1, 0), a3, voffA);
;             PG8_WAIT_V(8); PG8_WAIT_L(0); PG8_BAR; PG8_MMA(1, 0, At, B0); PG8_MMA(1, 1, At, B1); PG8_BAR; PG8_SCHED;
;     ...
;         if constexpr (ALIGN_EPI) { if (wr == 0) PG8_BAR; }
	s_mov_b32 m0, s51
	s_nop 3
	v_lshl_add_u64 v[16:17], v[240:241], 0, s[20:21]
	s_add_u32 s30, s30, 0x10080
	ds_read_b128 v[56:59], v136 offset:49152
	ds_read_b128 v[88:91], v136 offset:50176
	ds_read_b128 v[172:175], v136 offset:51200
	ds_read_b128 v[176:179], v136 offset:52224
	ds_read_b128 v[204:207], v136 offset:53248
	ds_read_b128 v[220:223], v136 offset:54272
	ds_read_b128 v[224:227], v136 offset:55296
	ds_read_b128 v[228:231], v136 offset:56320
	global_load_lds_dwordx4 v[16:17], off
	v_lshl_add_u64 v[16:17], v[242:243], 0, s[20:21]
	s_mov_b32 m0, s52
	s_addc_u32 s31, s31, 0
	global_load_lds_dwordx4 v[16:17], off
	v_lshl_add_u64 v[16:17], s[30:31], 0, v[130:131]
	s_mov_b32 m0, s53
	s_nop 0
	global_load_lds_dwordx4 v[16:17], off
	v_lshl_add_u64 v[16:17], s[30:31], 0, v[128:129]
	s_mov_b32 m0, s54
	s_nop 0
	global_load_lds_dwordx4 v[16:17], off
	v_lshl_add_u64 v[16:17], v[244:245], 0, s[20:21]
	s_mov_b32 m0, s75
	s_nop 0
	global_load_lds_dwordx4 v[16:17], off
	v_lshl_add_u64 v[16:17], v[246:247], 0, s[20:21]
	s_mov_b32 m0, s67
	s_nop 0
	global_load_lds_dwordx4 v[16:17], off
	s_waitcnt vmcnt(8)
	s_waitcnt lgkmcnt(0)
	s_barrier
	s_waitcnt lgkmcnt(0)
	v_mfma_f32_16x16x32_bf16 v[16:19], v[4:7], v[56:59], v[140:143]
	v_mfma_f32_16x16x32_bf16 v[84:87], v[60:63], v[88:91], v[16:19]
	v_mfma_f32_16x16x32_bf16 v[16:19], v[168:171], v[56:59], v[144:147]
	v_mfma_f32_16x16x32_bf16 v[76:79], v[192:195], v[88:91], v[16:19]
	v_mfma_f32_16x16x32_bf16 v[16:19], v[4:7], v[172:175], v[148:151]
	v_mfma_f32_16x16x32_bf16 v[52:55], v[60:63], v[176:179], v[16:19]
	v_mfma_f32_16x16x32_bf16 v[16:19], v[168:171], v[172:175], v[152:155]
	v_mfma_f32_16x16x32_bf16 v[44:47], v[192:195], v[176:179], v[16:19]
	v_mfma_f32_16x16x32_bf16 v[16:19], v[4:7], v[204:207], v[156:159]
	v_mfma_f32_16x16x32_bf16 v[0:3], v[4:7], v[224:227], v[0:3]
	v_mfma_f32_16x16x32_bf16 v[20:23], v[60:63], v[220:223], v[16:19]
	v_mfma_f32_16x16x32_bf16 v[16:19], v[168:171], v[204:207], v[160:163]
	v_mfma_f32_16x16x32_bf16 v[4:7], v[60:63], v[228:231], v[0:3]
	v_mfma_f32_16x16x32_bf16 v[0:3], v[168:171], v[224:227], v[200:203]
	v_mfma_f32_16x16x32_bf16 v[16:19], v[192:195], v[220:223], v[16:19]
	v_mfma_f32_16x16x32_bf16 v[0:3], v[192:195], v[228:231], v[0:3]
	v_mfma_f32_16x16x32_bf16 v[8:11], v[196:199], v[56:59], v[8:11]
	v_mfma_f32_16x16x32_bf16 v[92:95], v[208:211], v[88:91], v[8:11]
	v_mfma_f32_16x16x32_bf16 v[8:11], v[212:215], v[56:59], v[12:15]
	v_mfma_f32_16x16x32_bf16 v[88:91], v[216:219], v[88:91], v[8:11]
	v_mfma_f32_16x16x32_bf16 v[8:11], v[196:199], v[172:175], v[24:27]
	v_mfma_f32_16x16x32_bf16 v[60:63], v[208:211], v[176:179], v[8:11]
	v_mfma_f32_16x16x32_bf16 v[8:11], v[212:215], v[172:175], v[28:31]
	v_mfma_f32_16x16x32_bf16 v[56:59], v[216:219], v[176:179], v[8:11]
	v_mfma_f32_16x16x32_bf16 v[8:11], v[196:199], v[204:207], v[180:183]
	v_mfma_f32_16x16x32_bf16 v[28:31], v[208:211], v[220:223], v[8:11]
	v_mfma_f32_16x16x32_bf16 v[8:11], v[212:215], v[204:207], v[184:187]
	v_mfma_f32_16x16x32_bf16 v[24:27], v[216:219], v[220:223], v[8:11]
	v_mfma_f32_16x16x32_bf16 v[8:11], v[196:199], v[224:227], v[188:191]
	v_mfma_f32_16x16x32_bf16 v[12:15], v[208:211], v[228:231], v[8:11]
	v_mfma_f32_16x16x32_bf16 v[8:11], v[212:215], v[224:227], v[164:167]
	v_mfma_f32_16x16x32_bf16 v[8:11], v[216:219], v[228:231], v[8:11]
	s_barrier
	s_and_b64 vcc, exec, s[8:9]
	s_cbranch_vccnz .LBB0_2603
	s_barrier
; __device__ __forceinline__ unsigned cvt_pk_bf16(float lo, float hi) { const f32x2cv v = {lo, hi}; const bf16x2cv b = __builtin_convertvector(v, bf16x2cv); return __builtin_bit_cast(unsigned, b); }
;     __device__ __forceinline__ void operator()(const f32x4 (&acc)[2][2][4][2], const Unit& u, int wr, int wc, int fr, int fq) const {
;     ...
;         const int col0 = u.pn * BM + wc * 32 + 4 * fq;
; #pragma unroll
;         for (int ai = 0; ai < 2; ++ai)
; #pragma unroll
;             for (int m = 0; m < 4; ++m) { const int row = u.pm * BM + ai * HALF + wr * 64 + m * 16 + fr; const size_t off = (size_t)row * 1024 + col0;
; #pragma unroll
;                 for (int bj = 0; bj < 2; ++bj)
; #pragma unroll
;                     for (int n = 0; n < 2; ++n) { const f32x4 a = acc[ai][bj][m][n]; u32x2 w; w.x = cvt_pk_bf16(a[0], a[1]); w.y = cvt_pk_bf16(a[2], a[3]); *(u32x2*)(hb_ptr(off + bj * HALF + n * 16)) = w; } }
; template <class Epi, class Sched, bool ALIGN_EPI = false, bool SP2 = false, bool F16 = false>
; __device__ __forceinline__ void gemm_phase(PG8_LAS unsigned char* lds, const Gemm g, const Sched& S, const Epi& E, const int wid_in) {
;     ...
;         if (!has_next) break;
.LBB0_2603:
	s_lshl_b32 s28, s28, 8
	v_mov_b32_e32 v139, v132
	v_mov_b32_e32 v140, v133
	s_lshl_b32 s29, s57, 8
	s_add_i32 s28, s28, s70
	s_or_b32 s29, s29, s82
	v_add_u32_e32 v142, s28, v139
	v_lshl_add_u32 v140, v140, 2, s29
	v_ashrrev_i32_e32 v143, 31, v142
	v_ashrrev_i32_e32 v141, 31, v140
	v_lshlrev_b64 v[144:145], 11, v[142:143]
	v_cvt_pk_bf16_f32 v116, v116, v117
	v_cvt_pk_bf16_f32 v117, v118, v119
	v_lshl_add_u64 v[118:119], s[18:19], 0, v[144:145]
	v_lshlrev_b64 v[140:141], 1, v[140:141]
	v_lshl_add_u64 v[118:119], v[118:119], 0, v[140:141]
	v_cvt_pk_bf16_f32 v112, v112, v113
	v_cvt_pk_bf16_f32 v113, v114, v115
	global_store_dwordx2 v[118:119], v[112:113], off offset:32
	v_cvt_pk_bf16_f32 v112, v124, v125
	v_cvt_pk_bf16_f32 v113, v126, v127
	global_store_dwordx2 v[118:119], v[112:113], off offset:256
	v_cvt_pk_bf16_f32 v112, v120, v121
	v_cvt_pk_bf16_f32 v113, v122, v123
	global_store_dwordx2 v[118:119], v[112:113], off offset:288
	v_add_u32_e32 v112, 16, v142
	v_ashrrev_i32_e32 v113, 31, v112
	v_lshlrev_b64 v[112:113], 11, v[112:113]
	v_cvt_pk_bf16_f32 v100, v100, v101
	v_cvt_pk_bf16_f32 v101, v102, v103
	v_lshl_add_u64 v[102:103], s[18:19], 0, v[112:113]
	v_lshl_add_u64 v[102:103], v[102:103], 0, v[140:141]
	v_cvt_pk_bf16_f32 v96, v96, v97
	v_cvt_pk_bf16_f32 v97, v98, v99
	global_store_dwordx2 v[102:103], v[96:97], off offset:32
	v_cvt_pk_bf16_f32 v96, v108, v109
	v_cvt_pk_bf16_f32 v97, v110, v111
	global_store_dwordx2 v[102:103], v[96:97], off offset:256
	v_cvt_pk_bf16_f32 v96, v104, v105
	v_cvt_pk_bf16_f32 v97, v106, v107
	global_store_dwordx2 v[102:103], v[96:97], off offset:288
	v_add_u32_e32 v96, 32, v142
	v_ashrrev_i32_e32 v97, 31, v96
	v_lshlrev_b64 v[96:97], 11, v[96:97]
	v_cvt_pk_bf16_f32 v68, v68, v69
	v_cvt_pk_bf16_f32 v69, v70, v71
	v_lshl_add_u64 v[70:71], s[18:19], 0, v[96:97]
	v_lshl_add_u64 v[70:71], v[70:71], 0, v[140:141]
	v_cvt_pk_bf16_f32 v64, v64, v65
	v_cvt_pk_bf16_f32 v65, v66, v67
	global_store_dwordx2 v[70:71], v[64:65], off offset:32
	v_cvt_pk_bf16_f32 v64, v80, v81
	v_cvt_pk_bf16_f32 v65, v82, v83
	global_store_dwordx2 v[70:71], v[64:65], off offset:256
	v_cvt_pk_bf16_f32 v64, v72, v73
	v_cvt_pk_bf16_f32 v65, v74, v75
	global_store_dwordx2 v[70:71], v[64:65], off offset:288
	v_add_u32_e32 v64, 48, v142
	v_ashrrev_i32_e32 v65, 31, v64
	v_lshlrev_b64 v[64:65], 11, v[64:65]
	v_cvt_pk_bf16_f32 v36, v36, v37
	v_cvt_pk_bf16_f32 v37, v38, v39
	v_lshl_add_u64 v[38:39], s[18:19], 0, v[64:65]
	v_lshl_add_u64 v[38:39], v[38:39], 0, v[140:141]
	v_cvt_pk_bf16_f32 v32, v32, v33
	v_cvt_pk_bf16_f32 v33, v34, v35
	global_store_dwordx2 v[38:39], v[32:33], off offset:32
	v_cvt_pk_bf16_f32 v32, v48, v49
	v_cvt_pk_bf16_f32 v33, v50, v51
	global_store_dwordx2 v[38:39], v[32:33], off offset:256
	v_cvt_pk_bf16_f32 v32, v40, v41
	v_cvt_pk_bf16_f32 v33, v42, v43
	global_store_dwordx2 v[38:39], v[32:33], off offset:288
	v_add_u32_e32 v32, 0x80, v142
	v_ashrrev_i32_e32 v33, 31, v32
	v_lshlrev_b64 v[32:33], 11, v[32:33]
	v_lshl_add_u64 v[32:33], s[18:19], 0, v[32:33]
	v_cvt_pk_bf16_f32 v34, v84, v85
	v_cvt_pk_bf16_f32 v35, v86, v87
	v_lshl_add_u64 v[32:33], v[32:33], 0, v[140:141]
	global_store_dwordx2 v[32:33], v[34:35], off
	v_cvt_pk_bf16_f32 v34, v76, v77
	v_cvt_pk_bf16_f32 v35, v78, v79
	global_store_dwordx2 v[32:33], v[34:35], off offset:32
	v_cvt_pk_bf16_f32 v34, v92, v93
	v_cvt_pk_bf16_f32 v35, v94, v95
	global_store_dwordx2 v[32:33], v[34:35], off offset:256
	v_cvt_pk_bf16_f32 v34, v88, v89
	v_cvt_pk_bf16_f32 v35, v90, v91
	global_store_dwordx2 v[32:33], v[34:35], off offset:288
	v_add_u32_e32 v32, 0x90, v142
	v_ashrrev_i32_e32 v33, 31, v32
	v_lshlrev_b64 v[32:33], 11, v[32:33]
	v_lshl_add_u64 v[32:33], s[18:19], 0, v[32:33]
	v_cvt_pk_bf16_f32 v34, v52, v53
	v_cvt_pk_bf16_f32 v35, v54, v55
	v_lshl_add_u64 v[32:33], v[32:33], 0, v[140:141]
	global_store_dwordx2 v[32:33], v[34:35], off
	v_cvt_pk_bf16_f32 v34, v44, v45
	v_cvt_pk_bf16_f32 v35, v46, v47
	global_store_dwordx2 v[32:33], v[34:35], off offset:32
	v_cvt_pk_bf16_f32 v34, v60, v61
	v_cvt_pk_bf16_f32 v35, v62, v63
	global_store_dwordx2 v[32:33], v[34:35], off offset:256
	v_cvt_pk_bf16_f32 v34, v56, v57
	v_cvt_pk_bf16_f32 v35, v58, v59
	global_store_dwordx2 v[32:33], v[34:35], off offset:288
	v_add_u32_e32 v32, 0xa0, v142
	v_ashrrev_i32_e32 v33, 31, v32
	v_lshlrev_b64 v[32:33], 11, v[32:33]
	v_cvt_pk_bf16_f32 v20, v20, v21
	v_cvt_pk_bf16_f32 v21, v22, v23
	v_lshl_add_u64 v[22:23], s[18:19], 0, v[32:33]
	v_lshl_add_u64 v[22:23], v[22:23], 0, v[140:141]
	v_cvt_pk_bf16_f32 v16, v16, v17
	v_cvt_pk_bf16_f32 v17, v18, v19
	global_store_dwordx2 v[22:23], v[16:17], off offset:32
	v_cvt_pk_bf16_f32 v16, v28, v29
	v_cvt_pk_bf16_f32 v17, v30, v31
	global_store_dwordx2 v[22:23], v[16:17], off offset:256
	v_cvt_pk_bf16_f32 v16, v24, v25
	v_cvt_pk_bf16_f32 v17, v26, v27
	global_store_dwordx2 v[22:23], v[16:17], off offset:288
	v_add_u32_e32 v16, 0xb0, v142
	v_ashrrev_i32_e32 v17, 31, v16
	v_lshlrev_b64 v[16:17], 11, v[16:17]
	v_cvt_pk_bf16_f32 v4, v4, v5
	v_cvt_pk_bf16_f32 v5, v6, v7
	v_lshl_add_u64 v[6:7], s[18:19], 0, v[16:17]
	v_lshl_add_u64 v[6:7], v[6:7], 0, v[140:141]
	v_cvt_pk_bf16_f32 v0, v0, v1
	v_cvt_pk_bf16_f32 v1, v2, v3
	global_store_dwordx2 v[6:7], v[0:1], off offset:32
	v_cvt_pk_bf16_f32 v0, v12, v13
	v_cvt_pk_bf16_f32 v1, v14, v15
	global_store_dwordx2 v[6:7], v[0:1], off offset:256
	v_cvt_pk_bf16_f32 v0, v8, v9
	v_cvt_pk_bf16_f32 v1, v10, v11
	s_andn2_b64 vcc, exec, s[26:27]
	s_mov_b64 s[28:29], -1
	global_store_dwordx2 v[118:119], v[116:117], off
	global_store_dwordx2 v[102:103], v[100:101], off
	global_store_dwordx2 v[70:71], v[68:69], off
	global_store_dwordx2 v[38:39], v[36:37], off
	global_store_dwordx2 v[22:23], v[20:21], off
	global_store_dwordx2 v[6:7], v[4:5], off
	global_store_dwordx2 v[6:7], v[0:1], off offset:288
	s_cbranch_vccnz .LBB0_2600
	s_setprio 0
	s_and_b64 vcc, exec, s[6:7]
	s_cbranch_vccnz .LBB0_2599
	s_barrier
	s_branch .LBB0_2599

; #define PG8_STAGE(bufoff, gbase, voff) do { _Pragma("unroll") for (int _i = 0; _i < 2; ++_i) \
;         __builtin_amdgcn_global_load_lds((const unsigned*)((const char*)(gbase) + (voff)[_i]), (PG8_LAS unsigned*)(lds + (bufoff) + ldsw + _i * 8192), 16, 0, 0); } while (0)
; #define PG8_LDA(dst, b, h) do { _Pragma("unroll") for (int m = 0; m < 4; ++m) _Pragma("unroll") for (int k = 0; k < 2; ++k) dst[m][k] = *(const PG8_LAS bf16x8*)(lds + PG8_SA(b, h) + aoff + m * 2048 + k * 1024); } while (0)
; #define PG8_LDB(dst, b, h) do { _Pragma("unroll") for (int n = 0; n < 2; ++n) _Pragma("unroll") for (int k = 0; k < 2; ++k) dst[n][k] = *(const PG8_LAS bf16x8*)(lds + PG8_SB(b, h) + boff + n * 2048 + k * 1024); } while (0)
; #define PG8_MMA(ai, bj, At, Bt) do { __builtin_amdgcn_s_setprio(1); _Pragma("unroll") for (int m = 0; m < 4; ++m) _Pragma("unroll") for (int n = 0; n < 2; ++n) _Pragma("unroll") for (int k = 0; k < 2; ++k) \
;         acc[ai][bj][m][n] = mma16<F16>(Bt[n][k], At[m][k], acc[ai][bj][m][n]); __builtin_amdgcn_s_setprio(0); } while (0)
; #define PG8_WAIT_V(n) asm volatile("s_waitcnt vmcnt(" #n ")" ::: "memory")
; #define PG8_BAR __builtin_amdgcn_s_barrier()
; template <class Epi, class Sched, bool ALIGN_EPI = false, bool SP2 = false, bool F16 = false>
; __device__ __forceinline__ void gemm_phase(PG8_LAS unsigned char* lds, const Gemm g, const Sched& S, const Epi& E, const int wid_in) {
;     ...
;         for (int t = 0; t < nt; t += 2) {
;             const bool last = (t == nt - 2);
;             const char* a1 = cA + (size_t)(t + 1) * kstep;
;             const char* a2 = last ? nA : cA + (size_t)(t + 2) * kstep; const char* b2 = last ? nB : cB + (size_t)(t + 2) * kstep;
;             const char* a3 = a2 + kstep; const char* b3 = b2 + kstep;
;             if (last && has_next) S.a_ready(nxt);
;             if constexpr (SP2) {
;             PG8_LDB(B0, 0, 0); PG8_LDB(B1, 0, 1); PG8_SCHED; PG8_LDA(At, 0, 0); PG8_STAGE(PG8_SA(1, 1), a1 + hstep, voffA);
;             PG8_WAIT_V(8); PG8_WAIT_L(0); PG8_BAR; PG8_MMA(0, 0, At, B0); PG8_MMA(0, 1, At, B1); PG8_BAR; PG8_SCHED;
;     ...
;         for (int a = 0; a < 2; ++a)
; #pragma unroll
;             for (int b = 0; b < 2; ++b)
; #pragma unroll
;                 for (int m = 0; m < 4; ++m)
; #pragma unroll
;                     for (int n = 0; n < 2; ++n) acc[a][b][m][n] = (f32x4){0.f, 0.f, 0.f, 0.f};
.LBB0_2696:
	s_add_u32 s53, s30, 0x100
	v_mov_b32_e32 v0, 0
	s_addc_u32 s54, s31, 0
	s_mov_b32 s55, -2
	v_mov_b32_e32 v1, v0
	v_mov_b32_e32 v2, v0
	v_mov_b32_e32 v3, v0
	v_mov_b32_e32 v4, v0
	v_mov_b32_e32 v5, v0
	v_mov_b32_e32 v6, v0
	v_mov_b32_e32 v7, v0
	v_mov_b32_e32 v16, v0
	v_mov_b32_e32 v17, v0
	v_mov_b32_e32 v18, v0
	v_mov_b32_e32 v19, v0
	v_mov_b32_e32 v20, v0
	v_mov_b32_e32 v21, v0
	v_mov_b32_e32 v22, v0
	v_mov_b32_e32 v23, v0
	v_mov_b32_e32 v32, v0
	v_mov_b32_e32 v33, v0
	v_mov_b32_e32 v34, v0
	v_mov_b32_e32 v35, v0
	v_mov_b32_e32 v36, v0
	v_mov_b32_e32 v37, v0
	v_mov_b32_e32 v38, v0
	v_mov_b32_e32 v39, v0
	v_mov_b32_e32 v48, v0
	v_mov_b32_e32 v49, v0
	v_mov_b32_e32 v50, v0
	v_mov_b32_e32 v51, v0
	v_mov_b32_e32 v52, v0
	v_mov_b32_e32 v53, v0
	v_mov_b32_e32 v54, v0
	v_mov_b32_e32 v55, v0
	v_mov_b32_e32 v8, v0
	v_mov_b32_e32 v9, v0
	v_mov_b32_e32 v10, v0
	v_mov_b32_e32 v11, v0
	v_mov_b32_e32 v12, v0
	v_mov_b32_e32 v13, v0
	v_mov_b32_e32 v14, v0
	v_mov_b32_e32 v15, v0
	v_mov_b32_e32 v24, v0
	v_mov_b32_e32 v25, v0
	v_mov_b32_e32 v26, v0
	v_mov_b32_e32 v27, v0
	v_mov_b32_e32 v28, v0
	v_mov_b32_e32 v29, v0
	v_mov_b32_e32 v30, v0
	v_mov_b32_e32 v31, v0
	v_mov_b32_e32 v40, v0
	v_mov_b32_e32 v41, v0
	v_mov_b32_e32 v42, v0
	v_mov_b32_e32 v43, v0
	v_mov_b32_e32 v44, v0
	v_mov_b32_e32 v45, v0
	v_mov_b32_e32 v46, v0
	v_mov_b32_e32 v47, v0
	v_mov_b32_e32 v56, v0
	v_mov_b32_e32 v57, v0
	v_mov_b32_e32 v58, v0
	v_mov_b32_e32 v59, v0
	v_mov_b32_e32 v60, v0
	v_mov_b32_e32 v61, v0
	v_mov_b32_e32 v62, v0
	v_mov_b32_e32 v63, v0
	v_mov_b32_e32 v64, v0
	v_mov_b32_e32 v65, v0
	v_mov_b32_e32 v66, v0
	v_mov_b32_e32 v67, v0
	v_mov_b32_e32 v68, v0
	v_mov_b32_e32 v69, v0
	v_mov_b32_e32 v70, v0
	v_mov_b32_e32 v71, v0
	v_mov_b32_e32 v80, v0
	v_mov_b32_e32 v81, v0
	v_mov_b32_e32 v82, v0
	v_mov_b32_e32 v83, v0
	v_mov_b32_e32 v84, v0
	v_mov_b32_e32 v85, v0
	v_mov_b32_e32 v86, v0
	v_mov_b32_e32 v87, v0
	v_mov_b32_e32 v96, v0
	v_mov_b32_e32 v97, v0
	v_mov_b32_e32 v98, v0
	v_mov_b32_e32 v99, v0
	v_mov_b32_e32 v100, v0
	v_mov_b32_e32 v101, v0
	v_mov_b32_e32 v102, v0
	v_mov_b32_e32 v103, v0
	v_mov_b32_e32 v112, v0
	v_mov_b32_e32 v113, v0
	v_mov_b32_e32 v114, v0
	v_mov_b32_e32 v115, v0
	v_mov_b32_e32 v116, v0
	v_mov_b32_e32 v117, v0
	v_mov_b32_e32 v118, v0
	v_mov_b32_e32 v119, v0
	v_mov_b32_e32 v72, v0
	v_mov_b32_e32 v73, v0
	v_mov_b32_e32 v74, v0
	v_mov_b32_e32 v75, v0
	v_mov_b32_e32 v76, v0
	v_mov_b32_e32 v77, v0
	v_mov_b32_e32 v78, v0
	v_mov_b32_e32 v79, v0
	v_mov_b32_e32 v88, v0
	v_mov_b32_e32 v89, v0
	v_mov_b32_e32 v90, v0
	v_mov_b32_e32 v91, v0
	v_mov_b32_e32 v92, v0
	v_mov_b32_e32 v93, v0
	v_mov_b32_e32 v94, v0
	v_mov_b32_e32 v95, v0
	v_mov_b32_e32 v104, v0
	v_mov_b32_e32 v105, v0
	v_mov_b32_e32 v106, v0
	v_mov_b32_e32 v107, v0
	v_mov_b32_e32 v108, v0
	v_mov_b32_e32 v109, v0
	v_mov_b32_e32 v110, v0
	v_mov_b32_e32 v111, v0
	v_mov_b32_e32 v120, v0
	v_mov_b32_e32 v121, v0
	v_mov_b32_e32 v122, v0
	v_mov_b32_e32 v123, v0
	v_mov_b32_e32 v124, v0
	v_mov_b32_e32 v125, v0
	v_mov_b32_e32 v126, v0
	v_mov_b32_e32 v127, v0
	s_cmp_ge_u32 s3, 4
	s_cbranch_scc0 .Lgsp_22
	s_setprio 1
.Lgsp_22:
.LBB0_2697:
	ds_read_b128 v[128:131], v189
	ds_read_b128 v[132:135], v189 offset:1024
	ds_read_b128 v[136:139], v189 offset:2048
	ds_read_b128 v[140:143], v189 offset:3072
	ds_read_b128 v[144:147], v190
	ds_read_b128 v[148:151], v190 offset:1024
	ds_read_b128 v[168:171], v190 offset:2048
	ds_read_b128 v[172:175], v190 offset:3072
	s_add_u32 s30, s28, 0x100
	s_addc_u32 s31, s29, 0
	s_cmp_eq_u32 s55, 40
	s_cselect_b32 s37, s11, s31
	s_cselect_b32 s36, s10, s30
	s_cselect_b32 s35, s27, s54
	s_cselect_b32 s34, s26, s53
	s_mov_b32 m0, s91
	v_lshl_add_u64 v[184:185], s[28:29], 0, v[160:161]
	ds_read_b128 v[176:179], v191
	ds_read_b128 v[180:183], v191 offset:1024
	ds_read_b128 v[192:195], v191 offset:2048
	ds_read_b128 v[196:199], v191 offset:3072
	ds_read_b128 v[200:203], v191 offset:4096
	ds_read_b128 v[204:207], v191 offset:5120
	ds_read_b128 v[208:211], v191 offset:6144
	ds_read_b128 v[212:215], v191 offset:7168
	global_load_lds_dwordx4 v[184:185], off
	v_lshl_add_u64 v[184:185], s[28:29], 0, v[162:163]
	s_add_i32 m0, s74, 0xe000
	s_nop 0
	global_load_lds_dwordx4 v[184:185], off
	s_waitcnt vmcnt(8)
	s_waitcnt lgkmcnt(0)
	s_barrier
	s_waitcnt lgkmcnt(0)
	v_mfma_f32_16x16x32_bf16 v[124:127], v[128:131], v[176:179], v[124:127]
	v_mfma_f32_16x16x32_bf16 v[120:123], v[136:139], v[176:179], v[120:123]
	v_mfma_f32_16x16x32_bf16 v[108:111], v[128:131], v[192:195], v[108:111]
	v_mfma_f32_16x16x32_bf16 v[104:107], v[136:139], v[192:195], v[104:107]
	v_mfma_f32_16x16x32_bf16 v[92:95], v[128:131], v[200:203], v[92:95]
	v_mfma_f32_16x16x32_bf16 v[88:91], v[136:139], v[200:203], v[88:91]
	v_mfma_f32_16x16x32_bf16 v[76:79], v[128:131], v[208:211], v[76:79]
	v_mfma_f32_16x16x32_bf16 v[72:75], v[136:139], v[208:211], v[72:75]
	v_mfma_f32_16x16x32_bf16 v[124:127], v[132:135], v[180:183], v[124:127]
	v_mfma_f32_16x16x32_bf16 v[120:123], v[140:143], v[180:183], v[120:123]
	v_mfma_f32_16x16x32_bf16 v[108:111], v[132:135], v[196:199], v[108:111]
	v_mfma_f32_16x16x32_bf16 v[104:107], v[140:143], v[196:199], v[104:107]
	v_mfma_f32_16x16x32_bf16 v[92:95], v[132:135], v[204:207], v[92:95]
	v_mfma_f32_16x16x32_bf16 v[88:91], v[140:143], v[204:207], v[88:91]
	v_mfma_f32_16x16x32_bf16 v[76:79], v[132:135], v[212:215], v[76:79]
	v_mfma_f32_16x16x32_bf16 v[72:75], v[140:143], v[212:215], v[72:75]
	v_mfma_f32_16x16x32_bf16 v[116:119], v[144:147], v[176:179], v[116:119]
	v_mfma_f32_16x16x32_bf16 v[112:115], v[168:171], v[176:179], v[112:115]
	v_mfma_f32_16x16x32_bf16 v[100:103], v[144:147], v[192:195], v[100:103]
	v_mfma_f32_16x16x32_bf16 v[96:99], v[168:171], v[192:195], v[96:99]
	v_mfma_f32_16x16x32_bf16 v[84:87], v[144:147], v[200:203], v[84:87]
	v_mfma_f32_16x16x32_bf16 v[80:83], v[168:171], v[200:203], v[80:83]
	v_mfma_f32_16x16x32_bf16 v[68:71], v[144:147], v[208:211], v[68:71]
	v_mfma_f32_16x16x32_bf16 v[64:67], v[168:171], v[208:211], v[64:67]
	v_mfma_f32_16x16x32_bf16 v[116:119], v[148:151], v[180:183], v[116:119]
	v_mfma_f32_16x16x32_bf16 v[112:115], v[172:175], v[180:183], v[112:115]
	v_mfma_f32_16x16x32_bf16 v[100:103], v[148:151], v[196:199], v[100:103]
	v_mfma_f32_16x16x32_bf16 v[96:99], v[172:175], v[196:199], v[96:99]
	v_mfma_f32_16x16x32_bf16 v[84:87], v[148:151], v[204:207], v[84:87]
	v_mfma_f32_16x16x32_bf16 v[80:83], v[172:175], v[204:207], v[80:83]
	v_mfma_f32_16x16x32_bf16 v[68:71], v[148:151], v[212:215], v[68:71]
	v_mfma_f32_16x16x32_bf16 v[64:67], v[172:175], v[212:215], v[64:67]
	s_barrier
; #define PG8_STAGE(bufoff, gbase, voff) do { _Pragma("unroll") for (int _i = 0; _i < 2; ++_i) \
;         __builtin_amdgcn_global_load_lds((const unsigned*)((const char*)(gbase) + (voff)[_i]), (PG8_LAS unsigned*)(lds + (bufoff) + ldsw + _i * 8192), 16, 0, 0); } while (0)
; #define PG8_LDA(dst, b, h) do { _Pragma("unroll") for (int m = 0; m < 4; ++m) _Pragma("unroll") for (int k = 0; k < 2; ++k) dst[m][k] = *(const PG8_LAS bf16x8*)(lds + PG8_SA(b, h) + aoff + m * 2048 + k * 1024); } while (0)
; #define PG8_LDB(dst, b, h) do { _Pragma("unroll") for (int n = 0; n < 2; ++n) _Pragma("unroll") for (int k = 0; k < 2; ++k) dst[n][k] = *(const PG8_LAS bf16x8*)(lds + PG8_SB(b, h) + boff + n * 2048 + k * 1024); } while (0)
; #define PG8_MMA(ai, bj, At, Bt) do { __builtin_amdgcn_s_setprio(1); _Pragma("unroll") for (int m = 0; m < 4; ++m) _Pragma("unroll") for (int n = 0; n < 2; ++n) _Pragma("unroll") for (int k = 0; k < 2; ++k) \
;         acc[ai][bj][m][n] = mma16<F16>(Bt[n][k], At[m][k], acc[ai][bj][m][n]); __builtin_amdgcn_s_setprio(0); } while (0)
; #define PG8_WAIT_V(n) asm volatile("s_waitcnt vmcnt(" #n ")" ::: "memory")
; #define PG8_WAIT_L(n) asm volatile("s_waitcnt lgkmcnt(" #n ")" ::: "memory")
; #define PG8_BAR __builtin_amdgcn_s_barrier()
; #define PG8_SCHED __builtin_amdgcn_sched_barrier(0)
; template <class Epi, class Sched, bool ALIGN_EPI = false, bool SP2 = false, bool F16 = false>
; __device__ __forceinline__ void gemm_phase(PG8_LAS unsigned char* lds, const Gemm g, const Sched& S, const Epi& E, const int wid_in) {
;     ...
;             PG8_WAIT_V(8); PG8_WAIT_L(0); PG8_BAR; PG8_MMA(0, 0, At, B0); PG8_MMA(0, 1, At, B1); PG8_BAR; PG8_SCHED;
;             PG8_LDA(At, 0, 1); PG8_STAGE(PG8_SB(0, 0), b2, voffB); PG8_STAGE(PG8_SB(0, 1), b2 + hstep, voffB); PG8_STAGE(PG8_SA(0, 0), a2, voffA);
;             PG8_WAIT_V(8); PG8_WAIT_L(0); PG8_BAR; PG8_MMA(1, 0, At, B0); PG8_MMA(1, 1, At, B1); PG8_BAR; PG8_SCHED;
;             PG8_LDB(B0, 1, 0); PG8_LDB(B1, 1, 1); PG8_SCHED; PG8_LDA(At, 1, 0); PG8_STAGE(PG8_SA(0, 1), a2 + hstep, voffA);
	s_add_i32 s28, s47, s68
	v_lshl_add_u64 v[184:185], s[34:35], 0, v[154:155]
	s_mov_b32 m0, s28
	ds_read_b128 v[176:179], v191 offset:16384
	ds_read_b128 v[180:183], v191 offset:17408
	ds_read_b128 v[192:195], v191 offset:18432
	ds_read_b128 v[196:199], v191 offset:19456
	ds_read_b128 v[200:203], v191 offset:20480
	ds_read_b128 v[204:207], v191 offset:21504
	ds_read_b128 v[208:211], v191 offset:22528
	ds_read_b128 v[212:215], v191 offset:23552
	global_load_lds_dwordx4 v[184:185], off
	s_add_i32 m0, s28, 0x2000
	s_add_u32 s28, s34, 0xb0000
	v_lshl_add_u64 v[216:217], s[34:35], 0, v[158:159]
	s_addc_u32 s29, s35, 0
	s_add_i32 s56, s48, s68
	global_load_lds_dwordx4 v[216:217], off
	v_lshl_add_u64 v[218:219], s[28:29], 0, v[154:155]
	s_mov_b32 m0, s56
	v_lshl_add_u64 v[220:221], s[36:37], 0, v[156:157]
	global_load_lds_dwordx4 v[218:219], off
	v_lshl_add_u64 v[218:219], s[28:29], 0, v[158:159]
	s_add_i32 m0, s56, 0x2000
	s_nop 0
	global_load_lds_dwordx4 v[218:219], off
	v_lshl_add_u64 v[218:219], s[36:37], 0, v[152:153]
	s_mov_b32 m0, s74
	s_nop 0
	global_load_lds_dwordx4 v[218:219], off
	s_mov_b32 m0, s66
	s_nop 0
	global_load_lds_dwordx4 v[220:221], off
	s_waitcnt vmcnt(8)
	s_waitcnt lgkmcnt(0)
	s_barrier
	s_waitcnt lgkmcnt(0)
	v_mfma_f32_16x16x32_bf16 v[60:63], v[128:131], v[176:179], v[60:63]
	v_mfma_f32_16x16x32_bf16 v[56:59], v[136:139], v[176:179], v[56:59]
	v_mfma_f32_16x16x32_bf16 v[44:47], v[128:131], v[192:195], v[44:47]
	v_mfma_f32_16x16x32_bf16 v[40:43], v[136:139], v[192:195], v[40:43]
	v_mfma_f32_16x16x32_bf16 v[28:31], v[128:131], v[200:203], v[28:31]
	v_mfma_f32_16x16x32_bf16 v[24:27], v[136:139], v[200:203], v[24:27]
	v_mfma_f32_16x16x32_bf16 v[12:15], v[128:131], v[208:211], v[12:15]
	v_mfma_f32_16x16x32_bf16 v[8:11], v[136:139], v[208:211], v[8:11]
	v_mfma_f32_16x16x32_bf16 v[60:63], v[132:135], v[180:183], v[60:63]
	v_mfma_f32_16x16x32_bf16 v[56:59], v[140:143], v[180:183], v[56:59]
	v_mfma_f32_16x16x32_bf16 v[44:47], v[132:135], v[196:199], v[44:47]
	v_mfma_f32_16x16x32_bf16 v[40:43], v[140:143], v[196:199], v[40:43]
	v_mfma_f32_16x16x32_bf16 v[28:31], v[132:135], v[204:207], v[28:31]
	v_mfma_f32_16x16x32_bf16 v[24:27], v[140:143], v[204:207], v[24:27]
	v_mfma_f32_16x16x32_bf16 v[12:15], v[132:135], v[212:215], v[12:15]
	v_mfma_f32_16x16x32_bf16 v[8:11], v[140:143], v[212:215], v[8:11]
	v_mfma_f32_16x16x32_bf16 v[52:55], v[144:147], v[176:179], v[52:55]
	v_mfma_f32_16x16x32_bf16 v[48:51], v[168:171], v[176:179], v[48:51]
	v_mfma_f32_16x16x32_bf16 v[36:39], v[144:147], v[192:195], v[36:39]
	v_mfma_f32_16x16x32_bf16 v[32:35], v[168:171], v[192:195], v[32:35]
	v_mfma_f32_16x16x32_bf16 v[20:23], v[144:147], v[200:203], v[20:23]
	v_mfma_f32_16x16x32_bf16 v[16:19], v[168:171], v[200:203], v[16:19]
	v_mfma_f32_16x16x32_bf16 v[4:7], v[144:147], v[208:211], v[4:7]
	v_mfma_f32_16x16x32_bf16 v[0:3], v[168:171], v[208:211], v[0:3]
	v_mfma_f32_16x16x32_bf16 v[52:55], v[148:151], v[180:183], v[52:55]
	v_mfma_f32_16x16x32_bf16 v[48:51], v[172:175], v[180:183], v[48:51]
	v_mfma_f32_16x16x32_bf16 v[36:39], v[148:151], v[196:199], v[36:39]
	v_mfma_f32_16x16x32_bf16 v[32:35], v[172:175], v[196:199], v[32:35]
	v_mfma_f32_16x16x32_bf16 v[20:23], v[148:151], v[204:207], v[20:23]
	v_mfma_f32_16x16x32_bf16 v[16:19], v[172:175], v[204:207], v[16:19]
	v_mfma_f32_16x16x32_bf16 v[4:7], v[148:151], v[212:215], v[4:7]
	v_mfma_f32_16x16x32_bf16 v[0:3], v[172:175], v[212:215], v[0:3]
	s_barrier
	s_add_i32 s56, 0, 0x18000
	s_add_i32 s57, 0, 0x1c000
	v_add_u32_e32 v140, s56, v188
	v_add_u32_e32 v172, s57, v188
	ds_read_b128 v[128:131], v140
	ds_read_b128 v[132:135], v140 offset:1024
	ds_read_b128 v[136:139], v140 offset:2048
	ds_read_b128 v[140:143], v140 offset:3072
	ds_read_b128 v[144:147], v172
	ds_read_b128 v[148:151], v172 offset:1024
	ds_read_b128 v[168:171], v172 offset:2048
	ds_read_b128 v[172:175], v172 offset:3072
	s_add_u32 s28, s36, 0xb0000
	s_addc_u32 s29, s37, 0
	s_mov_b32 m0, s90
	v_lshl_add_u64 v[222:223], s[28:29], 0, v[152:153]
	ds_read_b128 v[176:179], v191 offset:32768
	ds_read_b128 v[180:183], v191 offset:33792
	ds_read_b128 v[192:195], v191 offset:34816
	ds_read_b128 v[196:199], v191 offset:35840
	ds_read_b128 v[200:203], v191 offset:36864
	ds_read_b128 v[204:207], v191 offset:37888
	ds_read_b128 v[208:211], v191 offset:38912
	ds_read_b128 v[212:215], v191 offset:39936
	global_load_lds_dwordx4 v[222:223], off
	v_lshl_add_u64 v[222:223], s[28:29], 0, v[156:157]
	s_mov_b32 m0, s43
	s_nop 0
	global_load_lds_dwordx4 v[222:223], off
	s_waitcnt vmcnt(8)
	s_waitcnt lgkmcnt(0)
	s_barrier
; #define PG8_STAGE(bufoff, gbase, voff) do { _Pragma("unroll") for (int _i = 0; _i < 2; ++_i) \
;         __builtin_amdgcn_global_load_lds((const unsigned*)((const char*)(gbase) + (voff)[_i]), (PG8_LAS unsigned*)(lds + (bufoff) + ldsw + _i * 8192), 16, 0, 0); } while (0)
; #define PG8_LDA(dst, b, h) do { _Pragma("unroll") for (int m = 0; m < 4; ++m) _Pragma("unroll") for (int k = 0; k < 2; ++k) dst[m][k] = *(const PG8_LAS bf16x8*)(lds + PG8_SA(b, h) + aoff + m * 2048 + k * 1024); } while (0)
; #define PG8_MMA(ai, bj, At, Bt) do { __builtin_amdgcn_s_setprio(1); _Pragma("unroll") for (int m = 0; m < 4; ++m) _Pragma("unroll") for (int n = 0; n < 2; ++n) _Pragma("unroll") for (int k = 0; k < 2; ++k) \
;         acc[ai][bj][m][n] = mma16<F16>(Bt[n][k], At[m][k], acc[ai][bj][m][n]); __builtin_amdgcn_s_setprio(0); } while (0)
; #define PG8_WAIT_V(n) asm volatile("s_waitcnt vmcnt(" #n ")" ::: "memory")
; #define PG8_WAIT_L(n) asm volatile("s_waitcnt lgkmcnt(" #n ")" ::: "memory")
; #define PG8_BAR __builtin_amdgcn_s_barrier()
; #define PG8_SCHED __builtin_amdgcn_sched_barrier(0)
; template <class Epi, class Sched, bool ALIGN_EPI = false, bool SP2 = false, bool F16 = false>
; __device__ __forceinline__ void gemm_phase(PG8_LAS unsigned char* lds, const Gemm g, const Sched& S, const Epi& E, const int wid_in) {
;     ...
;             PG8_WAIT_V(8); PG8_WAIT_L(0); PG8_BAR; PG8_MMA(0, 0, At, B0); PG8_MMA(0, 1, At, B1); PG8_BAR; PG8_SCHED;
;             PG8_LDA(At, 1, 1); PG8_STAGE(PG8_SB(1, 0), b3, voffB); PG8_STAGE(PG8_SB(1, 1), b3 + hstep, voffB); PG8_STAGE(PG8_SA(1, 0), a3, voffA);
;             PG8_WAIT_V(8); PG8_WAIT_L(0); PG8_BAR; PG8_MMA(1, 0, At, B0); PG8_MMA(1, 1, At, B1); PG8_BAR; PG8_SCHED;
;     ...
;         if constexpr (ALIGN_EPI) { if (wr == 0) PG8_BAR; }
	s_waitcnt lgkmcnt(0)
	v_mfma_f32_16x16x32_bf16 v[124:127], v[128:131], v[176:179], v[124:127]
	v_mfma_f32_16x16x32_bf16 v[120:123], v[136:139], v[176:179], v[120:123]
	v_mfma_f32_16x16x32_bf16 v[108:111], v[128:131], v[192:195], v[108:111]
	v_mfma_f32_16x16x32_bf16 v[104:107], v[136:139], v[192:195], v[104:107]
	v_mfma_f32_16x16x32_bf16 v[92:95], v[128:131], v[200:203], v[92:95]
	v_mfma_f32_16x16x32_bf16 v[88:91], v[136:139], v[200:203], v[88:91]
	v_mfma_f32_16x16x32_bf16 v[76:79], v[128:131], v[208:211], v[76:79]
	v_mfma_f32_16x16x32_bf16 v[72:75], v[136:139], v[208:211], v[72:75]
	v_mfma_f32_16x16x32_bf16 v[124:127], v[132:135], v[180:183], v[124:127]
	v_mfma_f32_16x16x32_bf16 v[120:123], v[140:143], v[180:183], v[120:123]
	v_mfma_f32_16x16x32_bf16 v[108:111], v[132:135], v[196:199], v[108:111]
	v_mfma_f32_16x16x32_bf16 v[104:107], v[140:143], v[196:199], v[104:107]
	v_mfma_f32_16x16x32_bf16 v[92:95], v[132:135], v[204:207], v[92:95]
	v_mfma_f32_16x16x32_bf16 v[88:91], v[140:143], v[204:207], v[88:91]
	v_mfma_f32_16x16x32_bf16 v[76:79], v[132:135], v[212:215], v[76:79]
	v_mfma_f32_16x16x32_bf16 v[72:75], v[140:143], v[212:215], v[72:75]
	v_mfma_f32_16x16x32_bf16 v[116:119], v[144:147], v[176:179], v[116:119]
	v_mfma_f32_16x16x32_bf16 v[112:115], v[168:171], v[176:179], v[112:115]
	v_mfma_f32_16x16x32_bf16 v[100:103], v[144:147], v[192:195], v[100:103]
	v_mfma_f32_16x16x32_bf16 v[96:99], v[168:171], v[192:195], v[96:99]
	v_mfma_f32_16x16x32_bf16 v[84:87], v[144:147], v[200:203], v[84:87]
	v_mfma_f32_16x16x32_bf16 v[80:83], v[168:171], v[200:203], v[80:83]
	v_mfma_f32_16x16x32_bf16 v[68:71], v[144:147], v[208:211], v[68:71]
	v_mfma_f32_16x16x32_bf16 v[64:67], v[168:171], v[208:211], v[64:67]
	v_mfma_f32_16x16x32_bf16 v[116:119], v[148:151], v[180:183], v[116:119]
	v_mfma_f32_16x16x32_bf16 v[112:115], v[172:175], v[180:183], v[112:115]
	v_mfma_f32_16x16x32_bf16 v[100:103], v[148:151], v[196:199], v[100:103]
	v_mfma_f32_16x16x32_bf16 v[96:99], v[172:175], v[196:199], v[96:99]
	v_mfma_f32_16x16x32_bf16 v[84:87], v[148:151], v[204:207], v[84:87]
	v_mfma_f32_16x16x32_bf16 v[80:83], v[172:175], v[204:207], v[80:83]
	v_mfma_f32_16x16x32_bf16 v[68:71], v[148:151], v[212:215], v[68:71]
	v_mfma_f32_16x16x32_bf16 v[64:67], v[172:175], v[212:215], v[64:67]
	s_barrier
	s_add_i32 s28, s56, s68
	v_lshl_add_u64 v[184:185], v[184:185], 0, s[24:25]
	s_mov_b32 m0, s28
	ds_read_b128 v[176:179], v191 offset:49152
	ds_read_b128 v[180:183], v191 offset:50176
	ds_read_b128 v[192:195], v191 offset:51200
	ds_read_b128 v[196:199], v191 offset:52224
	ds_read_b128 v[200:203], v191 offset:53248
	ds_read_b128 v[204:207], v191 offset:54272
	ds_read_b128 v[208:211], v191 offset:55296
	ds_read_b128 v[212:215], v191 offset:56320
	global_load_lds_dwordx4 v[184:185], off
	s_add_i32 m0, s28, 0x2000
	s_add_u32 s28, s34, 0xb0080
	v_lshl_add_u64 v[184:185], v[216:217], 0, s[24:25]
	s_addc_u32 s29, s35, 0
	s_add_i32 s34, s57, s68
	global_load_lds_dwordx4 v[184:185], off
	v_lshl_add_u64 v[184:185], s[28:29], 0, v[154:155]
	s_mov_b32 m0, s34
	s_nop 0
	global_load_lds_dwordx4 v[184:185], off
	v_lshl_add_u64 v[184:185], s[28:29], 0, v[158:159]
	s_add_i32 m0, s34, 0x2000
	s_nop 0
	global_load_lds_dwordx4 v[184:185], off
	v_lshl_add_u64 v[184:185], v[218:219], 0, s[24:25]
	s_mov_b32 m0, s75
	s_nop 0
	global_load_lds_dwordx4 v[184:185], off
	v_lshl_add_u64 v[184:185], v[220:221], 0, s[24:25]
	s_mov_b32 m0, s67
	s_nop 0
	global_load_lds_dwordx4 v[184:185], off
	s_waitcnt vmcnt(8)
	s_waitcnt lgkmcnt(0)
	s_barrier
	s_waitcnt lgkmcnt(0)
	v_mfma_f32_16x16x32_bf16 v[60:63], v[128:131], v[176:179], v[60:63]
	v_mfma_f32_16x16x32_bf16 v[56:59], v[136:139], v[176:179], v[56:59]
	v_mfma_f32_16x16x32_bf16 v[44:47], v[128:131], v[192:195], v[44:47]
	v_mfma_f32_16x16x32_bf16 v[40:43], v[136:139], v[192:195], v[40:43]
	v_mfma_f32_16x16x32_bf16 v[28:31], v[128:131], v[200:203], v[28:31]
	v_mfma_f32_16x16x32_bf16 v[24:27], v[136:139], v[200:203], v[24:27]
	v_mfma_f32_16x16x32_bf16 v[12:15], v[128:131], v[208:211], v[12:15]
	v_mfma_f32_16x16x32_bf16 v[8:11], v[136:139], v[208:211], v[8:11]
	v_mfma_f32_16x16x32_bf16 v[60:63], v[132:135], v[180:183], v[60:63]
	v_mfma_f32_16x16x32_bf16 v[56:59], v[140:143], v[180:183], v[56:59]
	v_mfma_f32_16x16x32_bf16 v[44:47], v[132:135], v[196:199], v[44:47]
	v_mfma_f32_16x16x32_bf16 v[40:43], v[140:143], v[196:199], v[40:43]
	v_mfma_f32_16x16x32_bf16 v[28:31], v[132:135], v[204:207], v[28:31]
	v_mfma_f32_16x16x32_bf16 v[24:27], v[140:143], v[204:207], v[24:27]
	v_mfma_f32_16x16x32_bf16 v[12:15], v[132:135], v[212:215], v[12:15]
	v_mfma_f32_16x16x32_bf16 v[8:11], v[140:143], v[212:215], v[8:11]
	v_mfma_f32_16x16x32_bf16 v[52:55], v[144:147], v[176:179], v[52:55]
	v_mfma_f32_16x16x32_bf16 v[48:51], v[168:171], v[176:179], v[48:51]
	v_mfma_f32_16x16x32_bf16 v[36:39], v[144:147], v[192:195], v[36:39]
	v_mfma_f32_16x16x32_bf16 v[32:35], v[168:171], v[192:195], v[32:35]
	v_mfma_f32_16x16x32_bf16 v[20:23], v[144:147], v[200:203], v[20:23]
	v_mfma_f32_16x16x32_bf16 v[16:19], v[168:171], v[200:203], v[16:19]
	v_mfma_f32_16x16x32_bf16 v[4:7], v[144:147], v[208:211], v[4:7]
	v_mfma_f32_16x16x32_bf16 v[0:3], v[168:171], v[208:211], v[0:3]
	v_mfma_f32_16x16x32_bf16 v[52:55], v[148:151], v[180:183], v[52:55]
	v_mfma_f32_16x16x32_bf16 v[48:51], v[172:175], v[180:183], v[48:51]
	v_mfma_f32_16x16x32_bf16 v[36:39], v[148:151], v[196:199], v[36:39]
	v_mfma_f32_16x16x32_bf16 v[32:35], v[172:175], v[196:199], v[32:35]
	v_mfma_f32_16x16x32_bf16 v[20:23], v[148:151], v[204:207], v[20:23]
	v_mfma_f32_16x16x32_bf16 v[16:19], v[172:175], v[204:207], v[16:19]
	v_mfma_f32_16x16x32_bf16 v[4:7], v[148:151], v[212:215], v[4:7]
	v_mfma_f32_16x16x32_bf16 v[0:3], v[172:175], v[212:215], v[0:3]
	s_barrier
	s_add_i32 s55, s55, 2
	s_add_u32 s53, s53, 0x100
	s_addc_u32 s54, s54, 0
	s_cmp_gt_u32 s55, 41
	s_mov_b64 s[28:29], s[30:31]
	s_cbranch_scc0 .LBB0_2697
	s_setprio 0
	s_and_b64 vcc, exec, s[16:17]
	s_cbranch_vccz .LBB0_2700
	s_barrier

; #define PG8_STAGE(bufoff, gbase, voff) do { _Pragma("unroll") for (int _i = 0; _i < 2; ++_i) \
;         __builtin_amdgcn_global_load_lds((const unsigned*)((const char*)(gbase) + (voff)[_i]), (PG8_LAS unsigned*)(lds + (bufoff) + ldsw + _i * 8192), 16, 0, 0); } while (0)
; #define PG8_LDA(dst, b, h) do { _Pragma("unroll") for (int m = 0; m < 4; ++m) _Pragma("unroll") for (int k = 0; k < 2; ++k) dst[m][k] = *(const PG8_LAS bf16x8*)(lds + PG8_SA(b, h) + aoff + m * 2048 + k * 1024); } while (0)
; #define PG8_LDB(dst, b, h) do { _Pragma("unroll") for (int n = 0; n < 2; ++n) _Pragma("unroll") for (int k = 0; k < 2; ++k) dst[n][k] = *(const PG8_LAS bf16x8*)(lds + PG8_SB(b, h) + boff + n * 2048 + k * 1024); } while (0)
; #define PG8_SCHED __builtin_amdgcn_sched_barrier(0)
; template <class Epi, class Sched, bool ALIGN_EPI = false, bool SP2 = false, bool F16 = false>
; __device__ __forceinline__ void gemm_phase(PG8_LAS unsigned char* lds, const Gemm g, const Sched& S, const Epi& E, const int wid_in) {
;     ...
;         const char* nA = has_next ? (const char*)g.A + (size_t)nxt.pm * tstep : cA; const char* nB = has_next ? (const char*)g.Bt + (size_t)nxt.pn * tstep : cB;
;         for (int t = 0; t < nt; t += 2) {
;             const bool last = (t == nt - 2);
;             const char* a1 = cA + (size_t)(t + 1) * kstep;
;             const char* a2 = last ? nA : cA + (size_t)(t + 2) * kstep; const char* b2 = last ? nB : cB + (size_t)(t + 2) * kstep;
;             const char* a3 = a2 + kstep; const char* b3 = b2 + kstep;
;             if (last && has_next) S.a_ready(nxt);
;             if constexpr (SP2) {
;             PG8_LDB(B0, 0, 0); PG8_LDB(B1, 0, 1); PG8_SCHED; PG8_LDA(At, 0, 0); PG8_STAGE(PG8_SA(1, 1), a1 + hstep, voffA);
;     ...
;         for (int a = 0; a < 2; ++a)
; #pragma unroll
;             for (int b = 0; b < 2; ++b)
; #pragma unroll
;                 for (int m = 0; m < 4; ++m)
; #pragma unroll
;                     for (int n = 0; n < 2; ++n) acc[a][b][m][n] = (f32x4){0.f, 0.f, 0.f, 0.f};
.LBB0_2792:
	s_ashr_i32 s31, s30, 31
	s_lshl_b64 s[14:15], s[30:31], 19
	s_add_u32 s34, s10, s14
	s_addc_u32 s35, s11, s15
	s_and_b64 s[14:15], s[8:9], exec
	s_cselect_b32 s14, s35, s43
	s_cselect_b32 s15, s34, s42
	s_ashr_i32 s29, s28, 31
	s_lshl_b64 s[36:37], s[28:29], 19
	s_add_u32 s36, s49, s36
	s_addc_u32 s37, s50, s37
	s_and_b64 s[46:47], s[8:9], exec
	s_cselect_b32 s29, s37, s45
	s_cselect_b32 s31, s36, s44
	s_add_u32 s42, s42, 0x40080
	s_addc_u32 s43, s43, 0
	s_add_u32 s41, s44, 0x100
	v_mov_b32_e32 v0, 0
	s_addc_u32 s58, s45, 0
	s_mov_b32 s59, -2
	v_mov_b32_e32 v1, v0
	v_mov_b32_e32 v2, v0
	v_mov_b32_e32 v3, v0
	v_mov_b32_e32 v4, v0
	v_mov_b32_e32 v5, v0
	v_mov_b32_e32 v6, v0
	v_mov_b32_e32 v7, v0
	v_mov_b32_e32 v16, v0
	v_mov_b32_e32 v17, v0
	v_mov_b32_e32 v18, v0
	v_mov_b32_e32 v19, v0
	v_mov_b32_e32 v20, v0
	v_mov_b32_e32 v21, v0
	v_mov_b32_e32 v22, v0
	v_mov_b32_e32 v23, v0
	v_mov_b32_e32 v32, v0
	v_mov_b32_e32 v33, v0
	v_mov_b32_e32 v34, v0
	v_mov_b32_e32 v35, v0
	v_mov_b32_e32 v36, v0
	v_mov_b32_e32 v37, v0
	v_mov_b32_e32 v38, v0
	v_mov_b32_e32 v39, v0
	v_mov_b32_e32 v48, v0
	v_mov_b32_e32 v49, v0
	v_mov_b32_e32 v50, v0
	v_mov_b32_e32 v51, v0
	v_mov_b32_e32 v52, v0
	v_mov_b32_e32 v53, v0
	v_mov_b32_e32 v54, v0
	v_mov_b32_e32 v55, v0
	v_mov_b32_e32 v8, v0
	v_mov_b32_e32 v9, v0
	v_mov_b32_e32 v10, v0
	v_mov_b32_e32 v11, v0
	v_mov_b32_e32 v12, v0
	v_mov_b32_e32 v13, v0
	v_mov_b32_e32 v14, v0
	v_mov_b32_e32 v15, v0
	v_mov_b32_e32 v24, v0
	v_mov_b32_e32 v25, v0
	v_mov_b32_e32 v26, v0
	v_mov_b32_e32 v27, v0
	v_mov_b32_e32 v28, v0
	v_mov_b32_e32 v29, v0
	v_mov_b32_e32 v30, v0
	v_mov_b32_e32 v31, v0
	v_mov_b32_e32 v40, v0
	v_mov_b32_e32 v41, v0
	v_mov_b32_e32 v42, v0
	v_mov_b32_e32 v43, v0
	v_mov_b32_e32 v44, v0
	v_mov_b32_e32 v45, v0
	v_mov_b32_e32 v46, v0
	v_mov_b32_e32 v47, v0
	v_mov_b32_e32 v56, v0
	v_mov_b32_e32 v57, v0
	v_mov_b32_e32 v58, v0
	v_mov_b32_e32 v59, v0
	v_mov_b32_e32 v60, v0
	v_mov_b32_e32 v61, v0
	v_mov_b32_e32 v62, v0
	v_mov_b32_e32 v63, v0
	v_mov_b32_e32 v64, v0
	v_mov_b32_e32 v65, v0
	v_mov_b32_e32 v66, v0
	v_mov_b32_e32 v67, v0
	v_mov_b32_e32 v68, v0
	v_mov_b32_e32 v69, v0
	v_mov_b32_e32 v70, v0
	v_mov_b32_e32 v71, v0
	v_mov_b32_e32 v80, v0
	v_mov_b32_e32 v81, v0
	v_mov_b32_e32 v82, v0
	v_mov_b32_e32 v83, v0
	v_mov_b32_e32 v84, v0
	v_mov_b32_e32 v85, v0
	v_mov_b32_e32 v86, v0
	v_mov_b32_e32 v87, v0
	v_mov_b32_e32 v96, v0
	v_mov_b32_e32 v97, v0
	v_mov_b32_e32 v98, v0
	v_mov_b32_e32 v99, v0
	v_mov_b32_e32 v100, v0
	v_mov_b32_e32 v101, v0
	v_mov_b32_e32 v102, v0
	v_mov_b32_e32 v103, v0
	v_mov_b32_e32 v120, v0
	v_mov_b32_e32 v121, v0
	v_mov_b32_e32 v122, v0
	v_mov_b32_e32 v123, v0
	v_mov_b32_e32 v124, v0
	v_mov_b32_e32 v125, v0
	v_mov_b32_e32 v126, v0
	v_mov_b32_e32 v127, v0
	v_mov_b32_e32 v72, v0
	v_mov_b32_e32 v73, v0
	v_mov_b32_e32 v74, v0
	v_mov_b32_e32 v75, v0
	v_mov_b32_e32 v76, v0
	v_mov_b32_e32 v77, v0
	v_mov_b32_e32 v78, v0
	v_mov_b32_e32 v79, v0
	v_mov_b32_e32 v88, v0
	v_mov_b32_e32 v89, v0
	v_mov_b32_e32 v90, v0
	v_mov_b32_e32 v91, v0
	v_mov_b32_e32 v92, v0
	v_mov_b32_e32 v93, v0
	v_mov_b32_e32 v94, v0
	v_mov_b32_e32 v95, v0
	v_mov_b32_e32 v104, v0
	v_mov_b32_e32 v105, v0
	v_mov_b32_e32 v106, v0
	v_mov_b32_e32 v107, v0
	v_mov_b32_e32 v108, v0
	v_mov_b32_e32 v109, v0
	v_mov_b32_e32 v110, v0
	v_mov_b32_e32 v111, v0
	v_mov_b32_e32 v136, v0
	v_mov_b32_e32 v137, v0
	v_mov_b32_e32 v138, v0
	v_mov_b32_e32 v139, v0
	v_mov_b32_e32 v140, v0
	v_mov_b32_e32 v141, v0
	v_mov_b32_e32 v142, v0
	v_mov_b32_e32 v143, v0
	s_cmp_ge_u32 s3, 4
	s_cbranch_scc0 .Lgsp_23
	s_setprio 1
.Lgsp_23:
.LBB0_2793:
	ds_read_b128 v[112:115], v235
	ds_read_b128 v[116:119], v235 offset:1024
	ds_read_b128 v[128:131], v235 offset:2048
	ds_read_b128 v[132:135], v235 offset:3072
	ds_read_b128 v[144:147], v236
	ds_read_b128 v[148:151], v236 offset:1024
	ds_read_b128 v[152:155], v236 offset:2048
	ds_read_b128 v[156:159], v236 offset:3072
	s_add_u32 s44, s42, 0xfffc0080
	s_addc_u32 s45, s43, -1
	s_cmp_eq_u32 s59, 12
	s_cselect_b32 s47, s14, s45
	s_cselect_b32 s46, s15, s44
	s_cselect_b32 s45, s29, s58
	s_cselect_b32 s44, s31, s41
	s_mov_b32 m0, s91
	v_lshl_add_u64 v[192:193], s[42:43], 0, v[204:205]
	ds_read_b128 v[160:163], v237
	ds_read_b128 v[164:167], v237 offset:1024
	ds_read_b128 v[168:171], v237 offset:2048
	ds_read_b128 v[172:175], v237 offset:3072
	ds_read_b128 v[176:179], v237 offset:4096
	ds_read_b128 v[180:183], v237 offset:5120
	ds_read_b128 v[184:187], v237 offset:6144
	ds_read_b128 v[188:191], v237 offset:7168
	global_load_lds_dwordx4 v[192:193], off
	v_lshl_add_u64 v[192:193], s[42:43], 0, v[206:207]
	s_add_i32 m0, s74, 0xe000
	s_nop 0
	global_load_lds_dwordx4 v[192:193], off
	s_waitcnt vmcnt(8)
	s_waitcnt lgkmcnt(0)
	s_barrier
; #define PG8_STAGE(bufoff, gbase, voff) do { _Pragma("unroll") for (int _i = 0; _i < 2; ++_i) \
;         __builtin_amdgcn_global_load_lds((const unsigned*)((const char*)(gbase) + (voff)[_i]), (PG8_LAS unsigned*)(lds + (bufoff) + ldsw + _i * 8192), 16, 0, 0); } while (0)
; #define PG8_LDA(dst, b, h) do { _Pragma("unroll") for (int m = 0; m < 4; ++m) _Pragma("unroll") for (int k = 0; k < 2; ++k) dst[m][k] = *(const PG8_LAS bf16x8*)(lds + PG8_SA(b, h) + aoff + m * 2048 + k * 1024); } while (0)
; #define PG8_MMA(ai, bj, At, Bt) do { __builtin_amdgcn_s_setprio(1); _Pragma("unroll") for (int m = 0; m < 4; ++m) _Pragma("unroll") for (int n = 0; n < 2; ++n) _Pragma("unroll") for (int k = 0; k < 2; ++k) \
;         acc[ai][bj][m][n] = mma16<F16>(Bt[n][k], At[m][k], acc[ai][bj][m][n]); __builtin_amdgcn_s_setprio(0); } while (0)
; #define PG8_WAIT_V(n) asm volatile("s_waitcnt vmcnt(" #n ")" ::: "memory")
; #define PG8_WAIT_L(n) asm volatile("s_waitcnt lgkmcnt(" #n ")" ::: "memory")
; #define PG8_BAR __builtin_amdgcn_s_barrier()
; #define PG8_SCHED __builtin_amdgcn_sched_barrier(0)
; template <class Epi, class Sched, bool ALIGN_EPI = false, bool SP2 = false, bool F16 = false>
; __device__ __forceinline__ void gemm_phase(PG8_LAS unsigned char* lds, const Gemm g, const Sched& S, const Epi& E, const int wid_in) {
;     ...
;             PG8_WAIT_V(8); PG8_WAIT_L(0); PG8_BAR; PG8_MMA(0, 0, At, B0); PG8_MMA(0, 1, At, B1); PG8_BAR; PG8_SCHED;
;             PG8_LDA(At, 0, 1); PG8_STAGE(PG8_SB(0, 0), b2, voffB); PG8_STAGE(PG8_SB(0, 1), b2 + hstep, voffB); PG8_STAGE(PG8_SA(0, 0), a2, voffA);
;             PG8_WAIT_V(8); PG8_WAIT_L(0); PG8_BAR; PG8_MMA(1, 0, At, B0); PG8_MMA(1, 1, At, B1); PG8_BAR; PG8_SCHED;
	s_waitcnt lgkmcnt(0)
	v_mfma_f32_16x16x32_f16 v[140:143], v[112:115], v[160:163], v[140:143]
	v_mfma_f32_16x16x32_f16 v[136:139], v[128:131], v[160:163], v[136:139]
	v_mfma_f32_16x16x32_f16 v[108:111], v[112:115], v[168:171], v[108:111]
	v_mfma_f32_16x16x32_f16 v[104:107], v[128:131], v[168:171], v[104:107]
	v_mfma_f32_16x16x32_f16 v[92:95], v[112:115], v[176:179], v[92:95]
	v_mfma_f32_16x16x32_f16 v[88:91], v[128:131], v[176:179], v[88:91]
	v_mfma_f32_16x16x32_f16 v[76:79], v[112:115], v[184:187], v[76:79]
	v_mfma_f32_16x16x32_f16 v[72:75], v[128:131], v[184:187], v[72:75]
	v_mfma_f32_16x16x32_f16 v[140:143], v[116:119], v[164:167], v[140:143]
	v_mfma_f32_16x16x32_f16 v[136:139], v[132:135], v[164:167], v[136:139]
	v_mfma_f32_16x16x32_f16 v[108:111], v[116:119], v[172:175], v[108:111]
	v_mfma_f32_16x16x32_f16 v[104:107], v[132:135], v[172:175], v[104:107]
	v_mfma_f32_16x16x32_f16 v[92:95], v[116:119], v[180:183], v[92:95]
	v_mfma_f32_16x16x32_f16 v[88:91], v[132:135], v[180:183], v[88:91]
	v_mfma_f32_16x16x32_f16 v[76:79], v[116:119], v[188:191], v[76:79]
	v_mfma_f32_16x16x32_f16 v[72:75], v[132:135], v[188:191], v[72:75]
	v_mfma_f32_16x16x32_f16 v[124:127], v[144:147], v[160:163], v[124:127]
	v_mfma_f32_16x16x32_f16 v[120:123], v[152:155], v[160:163], v[120:123]
	v_mfma_f32_16x16x32_f16 v[100:103], v[144:147], v[168:171], v[100:103]
	v_mfma_f32_16x16x32_f16 v[96:99], v[152:155], v[168:171], v[96:99]
	v_mfma_f32_16x16x32_f16 v[84:87], v[144:147], v[176:179], v[84:87]
	v_mfma_f32_16x16x32_f16 v[80:83], v[152:155], v[176:179], v[80:83]
	v_mfma_f32_16x16x32_f16 v[68:71], v[144:147], v[184:187], v[68:71]
	v_mfma_f32_16x16x32_f16 v[64:67], v[152:155], v[184:187], v[64:67]
	v_mfma_f32_16x16x32_f16 v[124:127], v[148:151], v[164:167], v[124:127]
	v_mfma_f32_16x16x32_f16 v[120:123], v[156:159], v[164:167], v[120:123]
	v_mfma_f32_16x16x32_f16 v[100:103], v[148:151], v[172:175], v[100:103]
	v_mfma_f32_16x16x32_f16 v[96:99], v[156:159], v[172:175], v[96:99]
	v_mfma_f32_16x16x32_f16 v[84:87], v[148:151], v[180:183], v[84:87]
	v_mfma_f32_16x16x32_f16 v[80:83], v[156:159], v[180:183], v[80:83]
	v_mfma_f32_16x16x32_f16 v[68:71], v[148:151], v[188:191], v[68:71]
	v_mfma_f32_16x16x32_f16 v[64:67], v[156:159], v[188:191], v[64:67]
	s_barrier
	s_add_i32 s60, s55, s68
	v_lshl_add_u64 v[192:193], s[44:45], 0, v[198:199]
	s_mov_b32 m0, s60
	ds_read_b128 v[160:163], v237 offset:16384
	ds_read_b128 v[164:167], v237 offset:17408
	ds_read_b128 v[168:171], v237 offset:18432
	ds_read_b128 v[172:175], v237 offset:19456
	ds_read_b128 v[176:179], v237 offset:20480
	ds_read_b128 v[180:183], v237 offset:21504
	ds_read_b128 v[184:187], v237 offset:22528
	ds_read_b128 v[188:191], v237 offset:23552
	global_load_lds_dwordx4 v[192:193], off
	s_add_i32 m0, s60, 0x2000
	s_add_u32 s60, s44, 0x40000
	v_lshl_add_u64 v[194:195], s[44:45], 0, v[202:203]
	s_addc_u32 s61, s45, 0
	s_add_i32 s62, s56, s68
	global_load_lds_dwordx4 v[194:195], off
	v_lshl_add_u64 v[212:213], s[60:61], 0, v[198:199]
	s_mov_b32 m0, s62
	v_lshl_add_u64 v[214:215], s[46:47], 0, v[200:201]
	global_load_lds_dwordx4 v[212:213], off
	v_lshl_add_u64 v[212:213], s[60:61], 0, v[202:203]
	s_add_i32 m0, s62, 0x2000
	s_nop 0
	global_load_lds_dwordx4 v[212:213], off
	v_lshl_add_u64 v[212:213], s[46:47], 0, v[196:197]
	s_mov_b32 m0, s74
	s_nop 0
	global_load_lds_dwordx4 v[212:213], off
	s_mov_b32 m0, s66
	s_nop 0
	global_load_lds_dwordx4 v[214:215], off
	s_waitcnt vmcnt(8)
	s_waitcnt lgkmcnt(0)
	s_barrier
	s_waitcnt lgkmcnt(0)
	v_mfma_f32_16x16x32_f16 v[60:63], v[112:115], v[160:163], v[60:63]
	v_mfma_f32_16x16x32_f16 v[56:59], v[128:131], v[160:163], v[56:59]
	v_mfma_f32_16x16x32_f16 v[44:47], v[112:115], v[168:171], v[44:47]
	v_mfma_f32_16x16x32_f16 v[40:43], v[128:131], v[168:171], v[40:43]
	v_mfma_f32_16x16x32_f16 v[28:31], v[112:115], v[176:179], v[28:31]
	v_mfma_f32_16x16x32_f16 v[24:27], v[128:131], v[176:179], v[24:27]
	v_mfma_f32_16x16x32_f16 v[12:15], v[112:115], v[184:187], v[12:15]
	v_mfma_f32_16x16x32_f16 v[8:11], v[128:131], v[184:187], v[8:11]
	v_mfma_f32_16x16x32_f16 v[60:63], v[116:119], v[164:167], v[60:63]
	v_mfma_f32_16x16x32_f16 v[56:59], v[132:135], v[164:167], v[56:59]
	v_mfma_f32_16x16x32_f16 v[44:47], v[116:119], v[172:175], v[44:47]
	v_mfma_f32_16x16x32_f16 v[40:43], v[132:135], v[172:175], v[40:43]
	v_mfma_f32_16x16x32_f16 v[28:31], v[116:119], v[180:183], v[28:31]
	v_mfma_f32_16x16x32_f16 v[24:27], v[132:135], v[180:183], v[24:27]
	v_mfma_f32_16x16x32_f16 v[12:15], v[116:119], v[188:191], v[12:15]
	v_mfma_f32_16x16x32_f16 v[8:11], v[132:135], v[188:191], v[8:11]
	v_mfma_f32_16x16x32_f16 v[52:55], v[144:147], v[160:163], v[52:55]
	v_mfma_f32_16x16x32_f16 v[48:51], v[152:155], v[160:163], v[48:51]
	v_mfma_f32_16x16x32_f16 v[36:39], v[144:147], v[168:171], v[36:39]
	v_mfma_f32_16x16x32_f16 v[32:35], v[152:155], v[168:171], v[32:35]
	v_mfma_f32_16x16x32_f16 v[20:23], v[144:147], v[176:179], v[20:23]
	v_mfma_f32_16x16x32_f16 v[16:19], v[152:155], v[176:179], v[16:19]
	v_mfma_f32_16x16x32_f16 v[4:7], v[144:147], v[184:187], v[4:7]
	v_mfma_f32_16x16x32_f16 v[0:3], v[152:155], v[184:187], v[0:3]
	v_mfma_f32_16x16x32_f16 v[52:55], v[148:151], v[164:167], v[52:55]
	v_mfma_f32_16x16x32_f16 v[48:51], v[156:159], v[164:167], v[48:51]
	v_mfma_f32_16x16x32_f16 v[36:39], v[148:151], v[172:175], v[36:39]
	v_mfma_f32_16x16x32_f16 v[32:35], v[156:159], v[172:175], v[32:35]
	v_mfma_f32_16x16x32_f16 v[20:23], v[148:151], v[180:183], v[20:23]
	v_mfma_f32_16x16x32_f16 v[16:19], v[156:159], v[180:183], v[16:19]
	v_mfma_f32_16x16x32_f16 v[4:7], v[148:151], v[188:191], v[4:7]
	v_mfma_f32_16x16x32_f16 v[0:3], v[156:159], v[188:191], v[0:3]
	s_barrier
; #define PG8_STAGE(bufoff, gbase, voff) do { _Pragma("unroll") for (int _i = 0; _i < 2; ++_i) \
;         __builtin_amdgcn_global_load_lds((const unsigned*)((const char*)(gbase) + (voff)[_i]), (PG8_LAS unsigned*)(lds + (bufoff) + ldsw + _i * 8192), 16, 0, 0); } while (0)
; #define PG8_LDA(dst, b, h) do { _Pragma("unroll") for (int m = 0; m < 4; ++m) _Pragma("unroll") for (int k = 0; k < 2; ++k) dst[m][k] = *(const PG8_LAS bf16x8*)(lds + PG8_SA(b, h) + aoff + m * 2048 + k * 1024); } while (0)
; #define PG8_LDB(dst, b, h) do { _Pragma("unroll") for (int n = 0; n < 2; ++n) _Pragma("unroll") for (int k = 0; k < 2; ++k) dst[n][k] = *(const PG8_LAS bf16x8*)(lds + PG8_SB(b, h) + boff + n * 2048 + k * 1024); } while (0)
; #define PG8_MMA(ai, bj, At, Bt) do { __builtin_amdgcn_s_setprio(1); _Pragma("unroll") for (int m = 0; m < 4; ++m) _Pragma("unroll") for (int n = 0; n < 2; ++n) _Pragma("unroll") for (int k = 0; k < 2; ++k) \
;         acc[ai][bj][m][n] = mma16<F16>(Bt[n][k], At[m][k], acc[ai][bj][m][n]); __builtin_amdgcn_s_setprio(0); } while (0)
; #define PG8_WAIT_V(n) asm volatile("s_waitcnt vmcnt(" #n ")" ::: "memory")
; #define PG8_WAIT_L(n) asm volatile("s_waitcnt lgkmcnt(" #n ")" ::: "memory")
; #define PG8_BAR __builtin_amdgcn_s_barrier()
; #define PG8_SCHED __builtin_amdgcn_sched_barrier(0)
; template <class Epi, class Sched, bool ALIGN_EPI = false, bool SP2 = false, bool F16 = false>
; __device__ __forceinline__ void gemm_phase(PG8_LAS unsigned char* lds, const Gemm g, const Sched& S, const Epi& E, const int wid_in) {
;     ...
;             PG8_LDB(B0, 1, 0); PG8_LDB(B1, 1, 1); PG8_SCHED; PG8_LDA(At, 1, 0); PG8_STAGE(PG8_SA(0, 1), a2 + hstep, voffA);
;             PG8_WAIT_V(8); PG8_WAIT_L(0); PG8_BAR; PG8_MMA(0, 0, At, B0); PG8_MMA(0, 1, At, B1); PG8_BAR; PG8_SCHED;
	s_add_i32 s60, 0, 0x18000
	s_add_i32 s61, 0, 0x1c000
	v_add_u32_e32 v132, s60, v234
	v_add_u32_e32 v156, s61, v234
	ds_read_b128 v[112:115], v132
	ds_read_b128 v[116:119], v132 offset:1024
	ds_read_b128 v[128:131], v132 offset:2048
	ds_read_b128 v[132:135], v132 offset:3072
	ds_read_b128 v[144:147], v156
	ds_read_b128 v[148:151], v156 offset:1024
	ds_read_b128 v[152:155], v156 offset:2048
	ds_read_b128 v[156:159], v156 offset:3072
	s_add_u32 s46, s46, 0x40000
	s_addc_u32 s47, s47, 0
	s_mov_b32 m0, s90
	v_lshl_add_u64 v[216:217], s[46:47], 0, v[196:197]
	ds_read_b128 v[160:163], v237 offset:32768
	ds_read_b128 v[164:167], v237 offset:33792
	ds_read_b128 v[168:171], v237 offset:34816
	ds_read_b128 v[172:175], v237 offset:35840
	ds_read_b128 v[176:179], v237 offset:36864
	ds_read_b128 v[180:183], v237 offset:37888
	ds_read_b128 v[184:187], v237 offset:38912
	ds_read_b128 v[188:191], v237 offset:39936
	global_load_lds_dwordx4 v[216:217], off
	v_lshl_add_u64 v[216:217], s[46:47], 0, v[200:201]
	s_mov_b32 m0, s51
	s_nop 0
	global_load_lds_dwordx4 v[216:217], off
	s_waitcnt vmcnt(8)
	s_waitcnt lgkmcnt(0)
	s_barrier
	s_waitcnt lgkmcnt(0)
	v_mfma_f32_16x16x32_f16 v[140:143], v[112:115], v[160:163], v[140:143]
	v_mfma_f32_16x16x32_f16 v[136:139], v[128:131], v[160:163], v[136:139]
	v_mfma_f32_16x16x32_f16 v[108:111], v[112:115], v[168:171], v[108:111]
	v_mfma_f32_16x16x32_f16 v[104:107], v[128:131], v[168:171], v[104:107]
	v_mfma_f32_16x16x32_f16 v[92:95], v[112:115], v[176:179], v[92:95]
	v_mfma_f32_16x16x32_f16 v[88:91], v[128:131], v[176:179], v[88:91]
	v_mfma_f32_16x16x32_f16 v[76:79], v[112:115], v[184:187], v[76:79]
	v_mfma_f32_16x16x32_f16 v[72:75], v[128:131], v[184:187], v[72:75]
	v_mfma_f32_16x16x32_f16 v[140:143], v[116:119], v[164:167], v[140:143]
	v_mfma_f32_16x16x32_f16 v[136:139], v[132:135], v[164:167], v[136:139]
	v_mfma_f32_16x16x32_f16 v[108:111], v[116:119], v[172:175], v[108:111]
	v_mfma_f32_16x16x32_f16 v[104:107], v[132:135], v[172:175], v[104:107]
	v_mfma_f32_16x16x32_f16 v[92:95], v[116:119], v[180:183], v[92:95]
	v_mfma_f32_16x16x32_f16 v[88:91], v[132:135], v[180:183], v[88:91]
	v_mfma_f32_16x16x32_f16 v[76:79], v[116:119], v[188:191], v[76:79]
	v_mfma_f32_16x16x32_f16 v[72:75], v[132:135], v[188:191], v[72:75]
	v_mfma_f32_16x16x32_f16 v[124:127], v[144:147], v[160:163], v[124:127]
	v_mfma_f32_16x16x32_f16 v[120:123], v[152:155], v[160:163], v[120:123]
	v_mfma_f32_16x16x32_f16 v[100:103], v[144:147], v[168:171], v[100:103]
	v_mfma_f32_16x16x32_f16 v[96:99], v[152:155], v[168:171], v[96:99]
	v_mfma_f32_16x16x32_f16 v[84:87], v[144:147], v[176:179], v[84:87]
	v_mfma_f32_16x16x32_f16 v[80:83], v[152:155], v[176:179], v[80:83]
	v_mfma_f32_16x16x32_f16 v[68:71], v[144:147], v[184:187], v[68:71]
	v_mfma_f32_16x16x32_f16 v[64:67], v[152:155], v[184:187], v[64:67]
	v_mfma_f32_16x16x32_f16 v[124:127], v[148:151], v[164:167], v[124:127]
	v_mfma_f32_16x16x32_f16 v[120:123], v[156:159], v[164:167], v[120:123]
	v_mfma_f32_16x16x32_f16 v[100:103], v[148:151], v[172:175], v[100:103]
	v_mfma_f32_16x16x32_f16 v[96:99], v[156:159], v[172:175], v[96:99]
	v_mfma_f32_16x16x32_f16 v[84:87], v[148:151], v[180:183], v[84:87]
	v_mfma_f32_16x16x32_f16 v[80:83], v[156:159], v[180:183], v[80:83]
	v_mfma_f32_16x16x32_f16 v[68:71], v[148:151], v[188:191], v[68:71]
	v_mfma_f32_16x16x32_f16 v[64:67], v[156:159], v[188:191], v[64:67]
	s_barrier
; #define PG8_STAGE(bufoff, gbase, voff) do { _Pragma("unroll") for (int _i = 0; _i < 2; ++_i) \
;         __builtin_amdgcn_global_load_lds((const unsigned*)((const char*)(gbase) + (voff)[_i]), (PG8_LAS unsigned*)(lds + (bufoff) + ldsw + _i * 8192), 16, 0, 0); } while (0)
; #define PG8_LDA(dst, b, h) do { _Pragma("unroll") for (int m = 0; m < 4; ++m) _Pragma("unroll") for (int k = 0; k < 2; ++k) dst[m][k] = *(const PG8_LAS bf16x8*)(lds + PG8_SA(b, h) + aoff + m * 2048 + k * 1024); } while (0)
; #define PG8_MMA(ai, bj, At, Bt) do { __builtin_amdgcn_s_setprio(1); _Pragma("unroll") for (int m = 0; m < 4; ++m) _Pragma("unroll") for (int n = 0; n < 2; ++n) _Pragma("unroll") for (int k = 0; k < 2; ++k) \
;         acc[ai][bj][m][n] = mma16<F16>(Bt[n][k], At[m][k], acc[ai][bj][m][n]); __builtin_amdgcn_s_setprio(0); } while (0)
; #define PG8_WAIT_V(n) asm volatile("s_waitcnt vmcnt(" #n ")" ::: "memory")
; #define PG8_WAIT_L(n) asm volatile("s_waitcnt lgkmcnt(" #n ")" ::: "memory")
; #define PG8_BAR __builtin_amdgcn_s_barrier()
; #define PG8_SCHED __builtin_amdgcn_sched_barrier(0)
; template <class Epi, class Sched, bool ALIGN_EPI = false, bool SP2 = false, bool F16 = false>
; __device__ __forceinline__ void gemm_phase(PG8_LAS unsigned char* lds, const Gemm g, const Sched& S, const Epi& E, const int wid_in) {
;     ...
;             PG8_LDA(At, 1, 1); PG8_STAGE(PG8_SB(1, 0), b3, voffB); PG8_STAGE(PG8_SB(1, 1), b3 + hstep, voffB); PG8_STAGE(PG8_SA(1, 0), a3, voffA);
;             PG8_WAIT_V(8); PG8_WAIT_L(0); PG8_BAR; PG8_MMA(1, 0, At, B0); PG8_MMA(1, 1, At, B1); PG8_BAR; PG8_SCHED;
;     ...
;         if constexpr (ALIGN_EPI) { if (wr == 0) PG8_BAR; }
	s_add_i32 s46, s60, s68
	v_lshl_add_u64 v[192:193], v[192:193], 0, s[26:27]
	s_mov_b32 m0, s46
	ds_read_b128 v[160:163], v237 offset:49152
	ds_read_b128 v[164:167], v237 offset:50176
	ds_read_b128 v[168:171], v237 offset:51200
	ds_read_b128 v[172:175], v237 offset:52224
	ds_read_b128 v[176:179], v237 offset:53248
	ds_read_b128 v[180:183], v237 offset:54272
	ds_read_b128 v[184:187], v237 offset:55296
	ds_read_b128 v[188:191], v237 offset:56320
	global_load_lds_dwordx4 v[192:193], off
	s_add_i32 m0, s46, 0x2000
	s_add_u32 s44, s44, 0x40080
	v_lshl_add_u64 v[192:193], v[194:195], 0, s[26:27]
	s_addc_u32 s45, s45, 0
	s_add_i32 s46, s61, s68
	global_load_lds_dwordx4 v[192:193], off
	v_lshl_add_u64 v[192:193], s[44:45], 0, v[198:199]
	s_mov_b32 m0, s46
	s_nop 0
	global_load_lds_dwordx4 v[192:193], off
	v_lshl_add_u64 v[192:193], s[44:45], 0, v[202:203]
	s_add_i32 m0, s46, 0x2000
	s_nop 0
	global_load_lds_dwordx4 v[192:193], off
	v_lshl_add_u64 v[192:193], v[212:213], 0, s[26:27]
	s_mov_b32 m0, s75
	s_nop 0
	global_load_lds_dwordx4 v[192:193], off
	v_lshl_add_u64 v[192:193], v[214:215], 0, s[26:27]
	s_mov_b32 m0, s67
	s_nop 0
	global_load_lds_dwordx4 v[192:193], off
	s_waitcnt vmcnt(8)
	s_waitcnt lgkmcnt(0)
	s_barrier
	s_waitcnt lgkmcnt(0)
	v_mfma_f32_16x16x32_f16 v[60:63], v[112:115], v[160:163], v[60:63]
	v_mfma_f32_16x16x32_f16 v[56:59], v[128:131], v[160:163], v[56:59]
	v_mfma_f32_16x16x32_f16 v[44:47], v[112:115], v[168:171], v[44:47]
	v_mfma_f32_16x16x32_f16 v[40:43], v[128:131], v[168:171], v[40:43]
	v_mfma_f32_16x16x32_f16 v[28:31], v[112:115], v[176:179], v[28:31]
	v_mfma_f32_16x16x32_f16 v[24:27], v[128:131], v[176:179], v[24:27]
	v_mfma_f32_16x16x32_f16 v[12:15], v[112:115], v[184:187], v[12:15]
	v_mfma_f32_16x16x32_f16 v[8:11], v[128:131], v[184:187], v[8:11]
	v_mfma_f32_16x16x32_f16 v[60:63], v[116:119], v[164:167], v[60:63]
	v_mfma_f32_16x16x32_f16 v[56:59], v[132:135], v[164:167], v[56:59]
	v_mfma_f32_16x16x32_f16 v[44:47], v[116:119], v[172:175], v[44:47]
	v_mfma_f32_16x16x32_f16 v[40:43], v[132:135], v[172:175], v[40:43]
	v_mfma_f32_16x16x32_f16 v[28:31], v[116:119], v[180:183], v[28:31]
	v_mfma_f32_16x16x32_f16 v[24:27], v[132:135], v[180:183], v[24:27]
	v_mfma_f32_16x16x32_f16 v[12:15], v[116:119], v[188:191], v[12:15]
	v_mfma_f32_16x16x32_f16 v[8:11], v[132:135], v[188:191], v[8:11]
	v_mfma_f32_16x16x32_f16 v[52:55], v[144:147], v[160:163], v[52:55]
	v_mfma_f32_16x16x32_f16 v[48:51], v[152:155], v[160:163], v[48:51]
	v_mfma_f32_16x16x32_f16 v[36:39], v[144:147], v[168:171], v[36:39]
	v_mfma_f32_16x16x32_f16 v[32:35], v[152:155], v[168:171], v[32:35]
	v_mfma_f32_16x16x32_f16 v[20:23], v[144:147], v[176:179], v[20:23]
	v_mfma_f32_16x16x32_f16 v[16:19], v[152:155], v[176:179], v[16:19]
	v_mfma_f32_16x16x32_f16 v[4:7], v[144:147], v[184:187], v[4:7]
	v_mfma_f32_16x16x32_f16 v[0:3], v[152:155], v[184:187], v[0:3]
	v_mfma_f32_16x16x32_f16 v[52:55], v[148:151], v[164:167], v[52:55]
	v_mfma_f32_16x16x32_f16 v[48:51], v[156:159], v[164:167], v[48:51]
	v_mfma_f32_16x16x32_f16 v[36:39], v[148:151], v[172:175], v[36:39]
	v_mfma_f32_16x16x32_f16 v[32:35], v[156:159], v[172:175], v[32:35]
	v_mfma_f32_16x16x32_f16 v[20:23], v[148:151], v[180:183], v[20:23]
	v_mfma_f32_16x16x32_f16 v[16:19], v[156:159], v[180:183], v[16:19]
	v_mfma_f32_16x16x32_f16 v[4:7], v[148:151], v[188:191], v[4:7]
	v_mfma_f32_16x16x32_f16 v[0:3], v[156:159], v[188:191], v[0:3]
	s_barrier
	s_add_i32 s59, s59, 2
	s_add_u32 s42, s42, 0x100
	s_addc_u32 s43, s43, 0
	s_add_u32 s41, s41, 0x100
	s_addc_u32 s58, s58, 0
	s_cmp_gt_u32 s59, 13
	s_cbranch_scc0 .LBB0_2793
	s_setprio 0
	s_and_b64 vcc, exec, s[16:17]
	s_cbranch_vccz .LBB0_2796
	s_barrier
